# skip redundant cg grid.sync (xcd barrier follows), flat->global memory ops, drop 28 redundant lgkmcnt(0) after GEMM barriers
# speedup vs baseline: 1.0014x; 1.0014x over previous
; __device__ __forceinline__ unsigned short f2bf(float f) { return (unsigned short)(cvt_pk_bf16(f, 0.f) & 0xffffu); }
; __global__ void __launch_bounds__(512, 2) mega_fwd(Params P) {
;     ...
;                 for (size_t i = gtid; i < (size_t)1024 * 512; i += GT) { const int row = (int)(i >> 9), k = (int)(i & 511);
;                     const int pn = row >> 8, gsel = (row >> 7) & 1, ch = pn * 128 + (row & 127);
;                     float v = 0.f; if ((k >> 6) == (ch >> 6)) v = gwt[(((size_t)gsel * 8 + (ch >> 6)) * 64 + (k & 63)) * 64 + (ch & 63)];
;                     dst[i] = f2bf(v); }
.LBB0_318:
	s_or_b64 exec, exec, s[54:55]
	v_lshl_add_u64 v[42:43], v[42:43], 0, s[72:73]
	s_mov_b64 s[36:37], 0x7ffff
	v_cmp_lt_u64_e32 vcc, s[36:37], v[42:43]
	s_waitcnt vmcnt(0)
	v_cvt_pk_bf16_f32 v14, v44, v15
	global_store_short v[4:5], v14, off
	v_lshl_add_u64 v[4:5], v[4:5], 0, s[76:77]
	s_or_b64 s[52:53], vcc, s[52:53]
	v_lshl_add_u64 v[2:3], v[2:3], 0, s[78:79]
	s_andn2_b64 exec, exec, s[52:53]
	s_cbranch_execz .LBB0_6

; __device__ __forceinline__ float xsum32(float v) { auto rr = __builtin_amdgcn_permlane32_swap(__float_as_uint(v), __float_as_uint(v), false, false); return __uint_as_float(rr[0]) + __uint_as_float(rr[1]); }
; __global__ void __launch_bounds__(512, 2) mega_fwd(Params P) {
;     ...
;                 s1 = xsum32(s1); s2 = xsum32(s2);
;                 if (kseg == 0) { float* cv = (float*)(ws + WS_CVEC) + (size_t)k * CVEC_STRIDE; cv[drow] = s1; cv[5632 + drow] = s2; }
.LBB0_349:
	s_or_b64 exec, exec, s[48:49]
	v_mov_b32_e32 v7, v20
	v_mov_b32_e32 v8, v21
	s_nop 0
	v_permlane32_swap_b32_e32 v20, v7
	v_permlane32_swap_b32_e32 v21, v8
	s_and_b64 exec, exec, s[2:3]
	s_cbranch_execz .LBB0_323
	v_mov_b64_e32 v[16:17], s[6:7]
	s_mov_b32 s34, 0xb000
	v_mad_u64_u32 v[16:17], s[34:35], v5, s34, v[16:17]
	v_mov_b32_e32 v15, v9
	v_add_f32_e32 v7, v20, v7
	v_lshl_add_u64 v[14:15], v[14:15], 2, v[16:17]
	global_store_dword v[14:15], v7, off
	v_add_co_u32_e32 v14, vcc, 0x5000, v14
	v_add_f32_e32 v8, v21, v8
	s_nop 0
	v_addc_co_u32_e32 v15, vcc, 0, v15, vcc
	global_store_dword v[14:15], v8, off offset:2048
	s_branch .LBB0_323

; __global__ void __launch_bounds__(512, 2) mega_fwd(Params P) {
;     ...
;         for (size_t i = gtid; i < 1024; i += GT) { ((float*)(ws + WS_ONES))[i] = 1.0f; ((float*)(ws + WS_ZEROS))[i] = 0.0f; }
.LBB0_353:
	v_add_co_u32_e32 v8, vcc, 0xfffff000, v2
	v_lshl_add_u64 v[4:5], v[4:5], 0, s[72:73]
	s_nop 0
	v_addc_co_u32_e32 v9, vcc, -1, v3, vcc
	v_cmp_lt_u64_e32 vcc, s[28:29], v[4:5]
	global_store_dword v[2:3], v6, off
	v_lshl_add_u64 v[2:3], v[2:3], 0, s[6:7]
	s_or_b64 s[26:27], vcc, s[26:27]
	global_store_dword v[8:9], v1, off
	s_andn2_b64 exec, exec, s[26:27]
	s_cbranch_execnz .LBB0_353

; __global__ void __launch_bounds__(512, 2) mega_fwd(Params P) {
;     ...
;         for (size_t i = gtid; i < (size_t)T_TOK * 4; i += GT) { ((f32x2*)(ws + WS_STATS))[i] = (f32x2){0.f, (i & 3) ? 0.f : 1024.0f * (1.0f - 1e-5f)}; }
.LBB0_356:
	v_lshl_add_u64 v[6:7], v[6:7], 0, s[72:73]
	v_cmp_lt_u64_e32 vcc, s[28:29], v[6:7]
	global_store_dwordx2 v[4:5], v[2:3], off
	s_or_b64 s[26:27], vcc, s[26:27]
	v_lshl_add_u64 v[4:5], v[4:5], 0, s[6:7]
	s_andn2_b64 exec, exec, s[26:27]
	s_cbranch_execnz .LBB0_356

; __global__ void __launch_bounds__(512, 2) mega_fwd(Params P) {
;     ...
;         for (size_t i = gtid; i < 1024; i += GT) { const float L = P.in[18][i]; ((float*)(ws + WS_SPL))[i] = -8.0f * (fmaxf(-L, 0.f) + log1pf(expf(-fabsf(L)))); }
.LBB0_359:
	v_lshl_add_u64 v[10:11], s[56:57], 0, v[2:3]
	global_load_dword v5, v[10:11], off
	v_lshl_add_u64 v[6:7], v[6:7], 0, s[72:73]
	v_cmp_lt_u64_e32 vcc, s[28:29], v[6:7]
	s_or_b64 s[26:27], vcc, s[26:27]
	v_lshl_add_u64 v[10:11], s[2:3], 0, v[2:3]
	v_lshl_add_u64 v[2:3], v[2:3], 0, s[6:7]
	s_waitcnt vmcnt(0)
	v_mul_f32_e64 v12, |v5|, s0
	v_fma_f32 v13, |v5|, s0, -v12
	v_rndne_f32_e32 v14, v12
	v_fma_f32 v13, |v5|, s1, v13
	v_sub_f32_e32 v12, v12, v14
	v_add_f32_e32 v12, v12, v13
	v_cvt_i32_f32_e32 v14, v14
	v_exp_f32_e32 v12, v12
	v_cmp_ngt_f32_e64 vcc, |v5|, s30
	v_max_f32_e64 v9, -v5, -v5
	v_max_f32_e32 v9, 0, v9
	v_ldexp_f32 v12, v12, v14
	v_cndmask_b32_e32 v12, 0, v12, vcc
	v_cmp_nlt_f32_e64 vcc, |v5|, s31
	s_nop 1
	v_cndmask_b32_e32 v28, v1, v12, vcc
	v_add_f32_e32 v5, 1.0, v28
	v_add_f32_e32 v14, -1.0, v5
	v_frexp_mant_f32_e32 v15, v5
	v_cvt_f64_f32_e32 v[12:13], v5
	v_sub_f32_e32 v16, v14, v5
	v_frexp_exp_i32_f64_e32 v12, v[12:13]
	v_cmp_gt_f32_e32 vcc, s34, v15
	v_sub_f32_e32 v14, v28, v14
	v_add_f32_e32 v13, 1.0, v16
	v_subbrev_co_u32_e32 v12, vcc, 0, v12, vcc
	v_add_f32_e32 v13, v14, v13
	v_sub_u32_e32 v14, 0, v12
	v_ldexp_f32 v5, v5, v14
	v_ldexp_f32 v13, v13, v14
	v_add_f32_e32 v14, -1.0, v5
	v_add_f32_e32 v16, 1.0, v5
	v_add_f32_e32 v15, 1.0, v14
	v_add_f32_e32 v17, -1.0, v16
	v_sub_f32_e32 v15, v5, v15
	v_sub_f32_e32 v5, v5, v17
	v_add_f32_e32 v5, v13, v5
	v_add_f32_e32 v17, v13, v15
	v_add_f32_e32 v13, v16, v5
	v_rcp_f32_e32 v22, v13
	v_add_f32_e32 v15, v14, v17
	v_sub_f32_e32 v16, v16, v13
	v_add_f32_e32 v5, v5, v16
	v_mul_f32_e32 v24, v15, v22
	v_mul_f32_e32 v16, v13, v24
	v_fma_f32 v20, v24, v13, -v16
	v_sub_f32_e32 v14, v14, v15
	v_fmac_f32_e32 v20, v24, v5
	v_add_f32_e32 v23, v17, v14
	v_add_f32_e32 v14, v16, v20
	v_sub_f32_e32 v17, v15, v14
	v_mov_b32_e32 v21, v14
	v_pk_add_f32 v[14:15], v[14:15], v[16:17] neg_lo:[0,1] neg_hi:[0,1]
	v_cvt_f32_i32_e32 v12, v12
	v_pk_add_f32 v[14:15], v[14:15], v[20:21] neg_lo:[0,1] neg_hi:[0,1]
	v_cmp_neq_f32_e32 vcc, s33, v28
	v_add_f32_e32 v15, v23, v15
	v_add_f32_e32 v14, v14, v15
	v_add_f32_e32 v15, v17, v14
	v_mul_f32_e32 v21, v22, v15
	v_mul_f32_e32 v16, v13, v21
	v_fma_f32 v20, v21, v13, -v16
	v_sub_f32_e32 v17, v17, v15
	v_fmac_f32_e32 v20, v21, v5
	v_add_f32_e32 v23, v14, v17
	v_add_f32_e32 v25, v24, v21
	v_add_f32_e32 v14, v16, v20
	v_sub_f32_e32 v13, v25, v24
	v_sub_f32_e32 v17, v15, v14
	v_sub_f32_e32 v5, v21, v13
	v_mov_b32_e32 v21, v14
	v_pk_add_f32 v[14:15], v[14:15], v[16:17] neg_lo:[0,1] neg_hi:[0,1]
	s_nop 0
	v_pk_add_f32 v[14:15], v[14:15], v[20:21] neg_lo:[0,1] neg_hi:[0,1]
	s_nop 0
	v_add_f32_e32 v13, v23, v15
	v_add_f32_e32 v13, v14, v13
	v_add_f32_e32 v13, v17, v13
	v_mul_f32_e32 v13, v22, v13
	v_add_f32_e32 v5, v5, v13
	v_add_f32_e32 v13, v25, v5
	v_mul_f32_e32 v14, v13, v13
	v_sub_f32_e32 v16, v13, v25
	v_fmamk_f32 v17, v14, 0x3e9b6dac, v8
	v_ldexp_f32 v15, v13, 1
	v_sub_f32_e32 v16, v5, v16
	v_mul_f32_e32 v13, v13, v14
	v_fmaak_f32 v5, v14, v17, 0x3f2aaada
	v_ldexp_f32 v21, v16, 1
	v_pk_mul_f32 v[16:17], v[12:13], v[4:5]
	s_nop 0
	v_fma_f32 v14, v12, s35, -v16
	v_fmac_f32_e32 v14, 0xb102e308, v12
	v_pk_add_f32 v[12:13], v[16:17], v[14:15]
	v_mov_b32_e32 v20, v16
	v_sub_f32_e32 v5, v13, v15
	v_sub_f32_e32 v5, v17, v5
	v_add_f32_e32 v21, v21, v5
	v_pk_add_f32 v[22:23], v[12:13], v[16:17] neg_lo:[0,1] neg_hi:[0,1]
	v_pk_add_f32 v[16:17], v[12:13], v[20:21]
	v_mov_b32_e32 v15, v12
	v_mov_b32_e32 v23, v17
	v_pk_add_f32 v[26:27], v[14:15], v[22:23] neg_lo:[0,1] neg_hi:[0,1]
	v_pk_add_f32 v[14:15], v[14:15], v[22:23]
	v_mov_b32_e32 v25, v12
	v_pk_add_f32 v[22:23], v[14:15], v[12:13] op_sel:[1,0] op_sel_hi:[0,1] neg_lo:[0,1] neg_hi:[0,1]
	v_mov_b32_e32 v24, v21
	v_mov_b32_e32 v20, v17
	v_mov_b32_e32 v21, v15
	v_pk_mov_b32 v[12:13], v[12:13], v[22:23] op_sel:[1,0]
	v_pk_add_f32 v[16:17], v[16:17], v[22:23] op_sel_hi:[1,0] neg_lo:[0,1] neg_hi:[0,1]
	v_pk_add_f32 v[12:13], v[20:21], v[12:13] neg_lo:[0,1] neg_hi:[0,1]
	v_mov_b32_e32 v16, v26
	v_pk_add_f32 v[12:13], v[24:25], v[12:13] neg_lo:[0,1] neg_hi:[0,1]
	v_mov_b32_e32 v27, v15
	v_pk_add_f32 v[16:17], v[16:17], v[12:13]
	s_nop 0
	v_pk_add_f32 v[20:21], v[16:17], v[16:17] op_sel:[0,1] op_sel_hi:[1,0]
	s_nop 0
	v_pk_add_f32 v[14:15], v[14:15], v[20:21] op_sel:[1,0] op_sel_hi:[0,1]
	v_mov_b32_e32 v17, v14
	v_mov_b32_e32 v13, v20
	v_pk_add_f32 v[20:21], v[16:17], v[26:27] neg_lo:[0,1] neg_hi:[0,1]
	s_nop 0
	v_sub_f32_e32 v5, v16, v20
	v_pk_add_f32 v[12:13], v[12:13], v[20:21] neg_lo:[0,1] neg_hi:[0,1]
	v_sub_f32_e32 v5, v26, v5
	v_add_f32_e32 v5, v12, v5
	v_add_f32_e32 v5, v5, v13
	v_add_f32_e32 v5, v14, v5
	v_cndmask_b32_e32 v5, v1, v5, vcc
	v_cmp_lt_f32_e64 vcc, |v28|, s36
	s_nop 1
	v_cndmask_b32_e32 v5, v5, v28, vcc
	v_add_f32_e32 v5, v9, v5
	v_mul_f32_e32 v5, 0xc1000000, v5
	global_store_dword v[10:11], v5, off
	s_andn2_b64 exec, exec, s[26:27]
	s_cbranch_execnz .LBB0_359

; __device__ __forceinline__ unsigned cvt_pk_bf16(float lo, float hi) { unsigned r; asm volatile("v_cvt_pk_bf16_f32 %0, %1, %2" : "=v"(r) : "v"(lo), "v"(hi)); return r; }
; __global__ void __launch_bounds__(512, 2) mega_fwd(Params P) {
;     ...
;             for (int q = 0; q < 4; ++q) { const size_t i = i0 + (size_t)q * GT; vv[q] = (i < (size_t)MEMT * DM / 4) ? ((const f32x4*)P.in[1])[i] : (f32x4){0.f, 0.f, 0.f, 0.f}; }
; #pragma unroll
;             for (int q = 0; q < 4; ++q) { const size_t i = i0 + (size_t)q * GT; if (i < (size_t)MEMT * DM / 4) { const f32x4 v = vv[q];
;                 ((unsigned long long*)MEMB)[i] = (unsigned long long)cvt_pk_bf16(v[0], v[1]) | ((unsigned long long)cvt_pk_bf16(v[2], v[3]) << 32); } }
.LBB0_369:
	s_or_b64 exec, exec, s[50:51]
	s_waitcnt vmcnt(0)
	v_cvt_pk_bf16_f32 v10, v10, v11
	v_cvt_pk_bf16_f32 v11, v12, v13
	v_lshl_add_u64 v[12:13], s[74:75], 0, v[26:27]
	global_store_dwordx2 v[12:13], v[10:11], off
	s_and_saveexec_b64 s[50:51], vcc
	s_cbranch_execnz .LBB0_372
	s_or_b64 exec, exec, s[50:51]
	s_and_saveexec_b64 s[50:51], s[2:3]
	s_cbranch_execnz .LBB0_373

; __device__ __forceinline__ unsigned cvt_pk_bf16(float lo, float hi) { unsigned r; asm volatile("v_cvt_pk_bf16_f32 %0, %1, %2" : "=v"(r) : "v"(lo), "v"(hi)); return r; }
; __global__ void __launch_bounds__(512, 2) mega_fwd(Params P) {
;     ...
;             for (int q = 0; q < 4; ++q) { const size_t i = i0 + (size_t)q * GT; if (i < (size_t)MEMT * DM / 4) { const f32x4 v = vv[q];
;                 ((unsigned long long*)MEMB)[i] = (unsigned long long)cvt_pk_bf16(v[0], v[1]) | ((unsigned long long)cvt_pk_bf16(v[2], v[3]) << 32); } }
.LBB0_372:
	v_cvt_pk_bf16_f32 v6, v6, v7
	v_cvt_pk_bf16_f32 v7, v8, v9
	v_lshl_add_u64 v[8:9], s[74:75], 0, v[24:25]
	global_store_dwordx2 v[8:9], v[6:7], off
	s_or_b64 exec, exec, s[50:51]
	s_and_saveexec_b64 s[50:51], s[2:3]
	s_cbranch_execz .LBB0_371
.LBB0_373:
	v_cvt_pk_bf16_f32 v2, v2, v3
	v_cvt_pk_bf16_f32 v3, v4, v5
	v_lshl_add_u64 v[4:5], s[74:75], 0, v[38:39]
	global_store_dwordx2 v[4:5], v[2:3], off
	s_or_b64 exec, exec, s[50:51]
	s_and_saveexec_b64 s[2:3], s[4:5]
	s_cbranch_execz .LBB0_362
.LBB0_374:
	v_lshl_add_u64 v[4:5], s[74:75], 0, v[42:43]
	v_cvt_pk_bf16_f32 v2, v14, v15
	v_cvt_pk_bf16_f32 v3, v16, v17
	global_store_dwordx2 v[4:5], v[2:3], off
	s_branch .LBB0_362

; __device__ __forceinline__ unsigned cvt_pk_bf16(float lo, float hi) { unsigned r; asm volatile("v_cvt_pk_bf16_f32 %0, %1, %2" : "=v"(r) : "v"(lo), "v"(hi)); return r; }
; __device__ __forceinline__ float bflo(unsigned w) { return __uint_as_float(w << 16); }
; __device__ __forceinline__ float bfhi(unsigned w) { return __uint_as_float(w & 0xffff0000u); }
; __global__ void __launch_bounds__(512, 2) mega_fwd(Params P) {
;     ...
;             for (int q = 0; q < 8; ++q) { const size_t i = i0 + (size_t)q * GT; if (i < (size_t)T_TOK * DM / 4) { const f32x4 v = vv[q];
;                 const unsigned h0 = cvt_pk_bf16(v[0], v[1]), h1 = cvt_pk_bf16(v[2], v[3]);
;                 const unsigned l0 = cvt_pk_bf16(v[0] - bflo(h0), v[1] - bfhi(h0)), l1 = cvt_pk_bf16(v[2] - bflo(h1), v[3] - bfhi(h1));
;                 ((unsigned long long*)XB)[i] = (unsigned long long)h0 | ((unsigned long long)h1 << 32);
;                 const size_t row = i >> 8, c4 = i & 255;
;                 ((unsigned long long*)X)[row * 512 + 256 + c4] = (unsigned long long)l0 | ((unsigned long long)l1 << 32); } }
.LBB0_392:
	s_or_b64 exec, exec, s[50:51]
	s_waitcnt vmcnt(0)
	v_cvt_pk_bf16_f32 v78, v30, v31
	v_cvt_pk_bf16_f32 v79, v32, v33
	s_nop 0
	v_lshlrev_b32_e32 v1, 16, v78
	v_sub_f32_e32 v1, v30, v1
	v_and_b32_e32 v30, 0xffff0000, v78
	v_sub_f32_e32 v30, v31, v30
	v_cvt_pk_bf16_f32 v30, v1, v30
	v_lshlrev_b32_e32 v1, 16, v79
	v_and_b32_e32 v31, 0xffff0000, v79
	v_sub_f32_e32 v1, v32, v1
	v_sub_f32_e32 v31, v33, v31
	v_cvt_pk_bf16_f32 v31, v1, v31
	v_and_b32_e32 v1, 0x1fffe00, v36
	v_lshl_add_u64 v[32:33], s[74:75], 0, v[44:45]
	v_lshlrev_b32_e32 v38, 3, v1
	global_store_dwordx2 v[32:33], v[78:79], off
	v_lshl_add_u64 v[32:33], v[40:41], 0, v[38:39]
	global_store_dwordx2 v[32:33], v[30:31], off offset:2048
	s_and_saveexec_b64 s[50:51], s[12:13]
	s_cbranch_execnz .LBB0_399
	s_or_b64 exec, exec, s[50:51]
	s_and_saveexec_b64 s[12:13], s[10:11]
	s_cbranch_execnz .LBB0_400

; __device__ __forceinline__ unsigned cvt_pk_bf16(float lo, float hi) { unsigned r; asm volatile("v_cvt_pk_bf16_f32 %0, %1, %2" : "=v"(r) : "v"(lo), "v"(hi)); return r; }
; __device__ __forceinline__ float bflo(unsigned w) { return __uint_as_float(w << 16); }
; __device__ __forceinline__ float bfhi(unsigned w) { return __uint_as_float(w & 0xffff0000u); }
; __global__ void __launch_bounds__(512, 2) mega_fwd(Params P) {
;     ...
;             for (int q = 0; q < 8; ++q) { const size_t i = i0 + (size_t)q * GT; if (i < (size_t)T_TOK * DM / 4) { const f32x4 v = vv[q];
;                 const unsigned h0 = cvt_pk_bf16(v[0], v[1]), h1 = cvt_pk_bf16(v[2], v[3]);
;                 const unsigned l0 = cvt_pk_bf16(v[0] - bflo(h0), v[1] - bfhi(h0)), l1 = cvt_pk_bf16(v[2] - bflo(h1), v[3] - bfhi(h1));
;                 ((unsigned long long*)XB)[i] = (unsigned long long)h0 | ((unsigned long long)h1 << 32);
;                 const size_t row = i >> 8, c4 = i & 255;
;                 ((unsigned long long*)X)[row * 512 + 256 + c4] = (unsigned long long)l0 | ((unsigned long long)l1 << 32); } }
.LBB0_399:
	v_cvt_pk_bf16_f32 v30, v26, v27
	v_cvt_pk_bf16_f32 v31, v28, v29
	s_nop 0
	v_lshlrev_b32_e32 v1, 16, v30
	v_sub_f32_e32 v1, v26, v1
	v_and_b32_e32 v26, 0xffff0000, v30
	v_sub_f32_e32 v26, v27, v26
	v_cvt_pk_bf16_f32 v26, v1, v26
	v_lshlrev_b32_e32 v1, 16, v31
	v_and_b32_e32 v27, 0xffff0000, v31
	v_sub_f32_e32 v1, v28, v1
	v_sub_f32_e32 v27, v29, v27
	v_cvt_pk_bf16_f32 v27, v1, v27
	v_add_u32_e32 v1, s76, v36
	v_and_b32_e32 v1, 0x1fffe00, v1
	v_lshl_add_u64 v[28:29], s[74:75], 0, v[42:43]
	v_lshlrev_b32_e32 v38, 3, v1
	global_store_dwordx2 v[28:29], v[30:31], off
	v_lshl_add_u64 v[28:29], v[40:41], 0, v[38:39]
	global_store_dwordx2 v[28:29], v[26:27], off offset:2048
	s_or_b64 exec, exec, s[50:51]
	s_and_saveexec_b64 s[12:13], s[10:11]
	s_cbranch_execz .LBB0_394
.LBB0_400:
	v_cvt_pk_bf16_f32 v26, v22, v23
	v_cvt_pk_bf16_f32 v27, v24, v25
	s_nop 0
	v_lshlrev_b32_e32 v1, 16, v26
	v_sub_f32_e32 v1, v22, v1
	v_and_b32_e32 v22, 0xffff0000, v26
	v_sub_f32_e32 v22, v23, v22
	v_cvt_pk_bf16_f32 v22, v1, v22
	v_lshlrev_b32_e32 v1, 16, v27
	v_and_b32_e32 v23, 0xffff0000, v27
	v_sub_f32_e32 v1, v24, v1
	v_sub_f32_e32 v23, v25, v23
	v_cvt_pk_bf16_f32 v23, v1, v23
	v_add_u32_e32 v1, s44, v36
	v_and_b32_e32 v1, 0x1fffe00, v1
	v_lshl_add_u64 v[24:25], s[74:75], 0, v[52:53]
	v_lshlrev_b32_e32 v38, 3, v1
	global_store_dwordx2 v[24:25], v[26:27], off
	v_lshl_add_u64 v[24:25], v[40:41], 0, v[38:39]
	global_store_dwordx2 v[24:25], v[22:23], off offset:2048
	s_or_b64 exec, exec, s[12:13]
	s_and_saveexec_b64 s[10:11], s[8:9]
	s_cbranch_execz .LBB0_395
.LBB0_401:
	v_cvt_pk_bf16_f32 v22, v10, v11
	v_cvt_pk_bf16_f32 v23, v12, v13
	s_nop 0
	v_lshlrev_b32_e32 v1, 16, v22
	v_sub_f32_e32 v1, v10, v1
	v_and_b32_e32 v10, 0xffff0000, v22
	v_sub_f32_e32 v10, v11, v10
	v_cvt_pk_bf16_f32 v10, v1, v10
	v_lshlrev_b32_e32 v1, 16, v23
	v_and_b32_e32 v11, 0xffff0000, v23
	v_sub_f32_e32 v1, v12, v1
	v_sub_f32_e32 v11, v13, v11
	v_cvt_pk_bf16_f32 v11, v1, v11
	v_add_u32_e32 v1, s0, v36
	v_and_b32_e32 v1, 0x1fffe00, v1
	v_lshl_add_u64 v[12:13], s[74:75], 0, v[56:57]
	v_lshlrev_b32_e32 v38, 3, v1
	global_store_dwordx2 v[12:13], v[22:23], off
	v_lshl_add_u64 v[12:13], v[40:41], 0, v[38:39]
	global_store_dwordx2 v[12:13], v[10:11], off offset:2048
	s_or_b64 exec, exec, s[10:11]
	s_and_saveexec_b64 s[8:9], s[6:7]
	s_cbranch_execz .LBB0_396
.LBB0_402:
	v_cvt_pk_bf16_f32 v10, v18, v19
	v_cvt_pk_bf16_f32 v11, v20, v21
	s_nop 0
	v_lshlrev_b32_e32 v1, 16, v10
	v_and_b32_e32 v12, 0xffff0000, v10
	v_sub_f32_e32 v1, v18, v1
	v_sub_f32_e32 v12, v19, v12
	v_cvt_pk_bf16_f32 v12, v1, v12
	v_lshlrev_b32_e32 v1, 16, v11
	v_and_b32_e32 v13, 0xffff0000, v11
	v_sub_f32_e32 v1, v20, v1
	v_sub_f32_e32 v13, v21, v13
	v_cvt_pk_bf16_f32 v13, v1, v13
	v_add_u32_e32 v1, s24, v36
	v_and_b32_e32 v1, 0x1fffe00, v1
	v_lshl_add_u64 v[18:19], s[74:75], 0, v[60:61]
	v_lshlrev_b32_e32 v38, 3, v1
	global_store_dwordx2 v[18:19], v[10:11], off
	v_lshl_add_u64 v[10:11], v[40:41], 0, v[38:39]
	global_store_dwordx2 v[10:11], v[12:13], off offset:2048
	s_or_b64 exec, exec, s[8:9]
	s_and_saveexec_b64 s[6:7], s[4:5]
	s_cbranch_execz .LBB0_397
.LBB0_403:
	v_cvt_pk_bf16_f32 v10, v6, v7
	v_cvt_pk_bf16_f32 v11, v8, v9
	s_nop 0
	v_lshlrev_b32_e32 v1, 16, v10
	v_sub_f32_e32 v1, v6, v1
	v_and_b32_e32 v6, 0xffff0000, v10
	v_sub_f32_e32 v6, v7, v6
	v_cvt_pk_bf16_f32 v6, v1, v6
	v_lshlrev_b32_e32 v1, 16, v11
	v_and_b32_e32 v7, 0xffff0000, v11
	v_sub_f32_e32 v1, v8, v1
	v_sub_f32_e32 v7, v9, v7
	v_cvt_pk_bf16_f32 v7, v1, v7
	v_add_u32_e32 v1, s1, v36
	v_and_b32_e32 v1, 0x1fffe00, v1
	v_lshl_add_u64 v[8:9], s[74:75], 0, v[64:65]
	v_lshlrev_b32_e32 v38, 3, v1
	global_store_dwordx2 v[8:9], v[10:11], off
	v_lshl_add_u64 v[8:9], v[40:41], 0, v[38:39]
	global_store_dwordx2 v[8:9], v[6:7], off offset:2048
	s_or_b64 exec, exec, s[6:7]
	s_and_saveexec_b64 s[4:5], s[2:3]
	s_cbranch_execz .LBB0_398
.LBB0_404:
	v_cvt_pk_bf16_f32 v6, v14, v15
	v_cvt_pk_bf16_f32 v7, v16, v17
	v_lshl_add_u64 v[10:11], s[74:75], 0, v[68:69]
	v_lshlrev_b32_e32 v1, 16, v6
	v_and_b32_e32 v8, 0xffff0000, v6
	v_sub_f32_e32 v1, v14, v1
	v_sub_f32_e32 v8, v15, v8
	v_cvt_pk_bf16_f32 v8, v1, v8
	v_lshlrev_b32_e32 v1, 16, v7
	v_and_b32_e32 v9, 0xffff0000, v7
	v_sub_f32_e32 v1, v16, v1
	v_sub_f32_e32 v9, v17, v9
	v_cvt_pk_bf16_f32 v9, v1, v9
	v_add_u32_e32 v1, s21, v36
	v_and_b32_e32 v1, 0x1fffe00, v1
	v_lshlrev_b32_e32 v38, 3, v1
	global_store_dwordx2 v[10:11], v[6:7], off
	v_lshl_add_u64 v[6:7], v[40:41], 0, v[38:39]
	global_store_dwordx2 v[6:7], v[8:9], off offset:2048
	s_or_b64 exec, exec, s[4:5]
	s_and_saveexec_b64 s[2:3], vcc
	s_cbranch_execz .LBB0_377
.LBB0_405:
	v_cvt_pk_bf16_f32 v6, v2, v3
	v_cvt_pk_bf16_f32 v7, v4, v5
	s_nop 0
	v_lshlrev_b32_e32 v1, 16, v6
	v_sub_f32_e32 v1, v2, v1
	v_and_b32_e32 v2, 0xffff0000, v6
	v_sub_f32_e32 v2, v3, v2
	v_cvt_pk_bf16_f32 v2, v1, v2
	v_lshlrev_b32_e32 v1, 16, v7
	v_and_b32_e32 v3, 0xffff0000, v7
	v_sub_f32_e32 v1, v4, v1
	v_sub_f32_e32 v3, v5, v3
	v_cvt_pk_bf16_f32 v3, v1, v3
	v_add_u32_e32 v1, s33, v36
	v_and_b32_e32 v1, 0x1fffe00, v1
	v_lshl_add_u64 v[4:5], s[74:75], 0, v[72:73]
	v_lshlrev_b32_e32 v38, 3, v1
	global_store_dwordx2 v[4:5], v[6:7], off
	v_lshl_add_u64 v[4:5], v[40:41], 0, v[38:39]
	global_store_dwordx2 v[4:5], v[2:3], off offset:2048
	s_branch .LBB0_377

; __device__ __forceinline__ void sincos_acc(float angf, float& s, float& c) {
;     const double x = (double)angf; const double k = rint(x * 0.15915494309189535); const double r = fma(-k, 6.283185307179586, x);
;     const double r2 = r * r; double ts = r, tc = 1.0, ss = r, cc = 1.0;
; #pragma unroll
;     for (int n = 1; n <= 14; ++n) { tc *= -r2 * (1.0 / (double)((2 * n - 1) * (2 * n))); cc += tc; ts *= -r2 * (1.0 / (double)((2 * n) * (2 * n + 1))); ss += ts; }
;     s = (float)ss; c = (float)cc;
; __global__ void __launch_bounds__(512, 2) mega_fwd(Params P) {
;     ...
;         for (size_t i = gtid; i < (size_t)SEQ * 40; i += GT) { const int pos = (int)(i / 40), e = (int)(i % 40);
;             float inv; if (e < 8) inv = (float)exp2(-((double)e * 2.0 / 16.0) * 18.931568569324174);
;             else inv = (float)exp2(-((double)(e - 8) * 2.0 / 64.0) * 13.287712379549449);
;             const float ang = (float)pos * inv; float s, c; sincos_acc(ang, s, c);
;             if (e < 8) ROPE_DA[pos * 8 + e] = (f32x2){c, s}; else ROPE_RET[pos * 32 + (e - 8)] = (f32x2){c, s}; }
;     }
;     __syncthreads();
;     grid.sync();
.LBB0_409:
	s_mov_b32 s0, 0xcccccccd
	v_mul_hi_u32 v2, v34, s0
	v_lshrrev_b32_e32 v22, 5, v2
	v_mul_lo_u32 v2, v22, 40
	v_sub_u32_e32 v2, v34, v2
	v_cmp_lt_u32_e32 vcc, 7, v2
	s_and_saveexec_b64 s[0:1], vcc
	s_xor_b64 s[2:3], exec, s[0:1]
	v_add_u32_e32 v23, -8, v2
	v_cvt_f64_u32_e32 v[24:25], v23
	v_add_f64 v[24:25], v[24:25], v[24:25]
	v_ldexp_f64 v[24:25], -v[24:25], -6
	v_mul_f64 v[24:25], v[24:25], s[18:19]
	s_andn2_saveexec_b64 s[2:3], s[2:3]
	v_lshlrev_b32_e32 v23, 1, v2
	v_cvt_f64_u32_e32 v[24:25], v23
	v_ldexp_f64 v[24:25], -v[24:25], -4
	v_mul_f64 v[24:25], v[24:25], s[20:21]
	s_or_b64 exec, exec, s[2:3]
	v_rndne_f64_e32 v[26:27], v[24:25]
	v_add_f64 v[28:29], v[24:25], -v[26:27]
	v_mul_f64 v[30:31], v[28:29], s[22:23]
	v_fmac_f64_e32 v[30:31], s[24:25], v[28:29]
	v_fma_f64 v[28:29], s[26:27], v[30:31], v[4:5]
	v_fma_f64 v[28:29], v[30:31], v[28:29], v[6:7]
	v_fma_f64 v[28:29], v[30:31], v[28:29], v[8:9]
	v_fma_f64 v[28:29], v[30:31], v[28:29], v[10:11]
	v_fma_f64 v[28:29], v[30:31], v[28:29], v[12:13]
	v_fma_f64 v[28:29], v[30:31], v[28:29], v[14:15]
	v_fma_f64 v[28:29], v[30:31], v[28:29], v[16:17]
	v_fma_f64 v[28:29], v[30:31], v[28:29], v[18:19]
	v_fma_f64 v[28:29], v[30:31], v[28:29], v[20:21]
	s_mov_b32 s0, 0
	v_fma_f64 v[28:29], v[30:31], v[28:29], 1.0
	s_mov_b32 s1, 0x40900000
	v_fma_f64 v[28:29], v[30:31], v[28:29], 1.0
	v_cvt_i32_f64_e32 v26, v[26:27]
	v_cmp_nlt_f64_e64 s[2:3], s[0:1], v[24:25]
	s_mov_b32 s0, 0
	v_ldexp_f64 v[26:27], v[28:29], v26
	s_mov_b32 s1, 0xc090cc00
	v_cndmask_b32_e64 v27, v1, v27, s[2:3]
	v_cmp_ngt_f64_e64 s[4:5], s[0:1], v[24:25]
	s_and_b64 s[2:3], s[4:5], s[2:3]
	v_cndmask_b32_e64 v24, 0, v26, s[2:3]
	v_cndmask_b32_e64 v25, 0, v27, s[4:5]
	v_cvt_f32_u32_e32 v27, v22
	v_cvt_f32_f64_e32 v24, v[24:25]
	s_mov_b32 s76, s66
	v_mov_b32_e32 v23, v3
	v_mul_f32_e32 v24, v27, v24
	v_cvt_f64_f32_e32 v[24:25], v24
	v_mul_f64 v[26:27], v[24:25], s[30:31]
	v_rndne_f64_e32 v[26:27], v[26:27]
	v_fmac_f64_e32 v[24:25], s[36:37], v[26:27]
	v_mul_f64 v[26:27], v[24:25], -v[24:25]
	v_mul_f64 v[32:33], v[26:27], s[28:29]
	v_mul_f64 v[28:29], v[26:27], 0.5
	v_fma_f64 v[30:31], v[26:27], 0.5, 1.0
	v_mul_f64 v[36:37], v[24:25], v[32:33]
	v_fmac_f64_e32 v[24:25], v[24:25], v[32:33]
	v_mul_f64 v[32:33], v[26:27], s[38:39]
	v_mul_f64 v[38:39], v[28:29], v[32:33]
	v_fmac_f64_e32 v[30:31], v[28:29], v[32:33]
	v_mul_f64 v[28:29], v[26:27], s[44:45]
	v_mul_f64 v[32:33], v[28:29], v[36:37]
	v_fmac_f64_e32 v[24:25], v[28:29], v[36:37]
	v_mul_f64 v[28:29], v[26:27], s[46:47]
	v_mul_f64 v[36:37], v[28:29], v[38:39]
	v_fmac_f64_e32 v[30:31], v[28:29], v[38:39]
	v_mul_f64 v[28:29], v[26:27], s[50:51]
	v_mul_f64 v[38:39], v[28:29], v[32:33]
	v_fmac_f64_e32 v[24:25], v[28:29], v[32:33]
	v_mul_f64 v[28:29], v[26:27], s[52:53]
	v_mul_f64 v[32:33], v[28:29], v[36:37]
	v_fmac_f64_e32 v[30:31], v[28:29], v[36:37]
	v_mul_f64 v[28:29], v[26:27], s[54:55]
	v_mul_f64 v[36:37], v[28:29], v[38:39]
	v_fmac_f64_e32 v[24:25], v[28:29], v[38:39]
	v_mul_f64 v[28:29], v[26:27], s[56:57]
	v_mul_f64 v[38:39], v[28:29], v[32:33]
	v_fmac_f64_e32 v[30:31], v[28:29], v[32:33]
	v_mul_f64 v[28:29], v[26:27], s[58:59]
	v_mul_f64 v[32:33], v[28:29], v[36:37]
	v_fmac_f64_e32 v[24:25], v[28:29], v[36:37]
	v_mul_f64 v[28:29], v[26:27], s[60:61]
	v_mul_f64 v[36:37], v[28:29], v[38:39]
	v_fmac_f64_e32 v[30:31], v[28:29], v[38:39]
	v_mul_f64 v[28:29], v[26:27], s[62:63]
	v_mul_f64 v[38:39], v[28:29], v[32:33]
	v_fmac_f64_e32 v[24:25], v[28:29], v[32:33]
	v_mul_f64 v[28:29], v[26:27], s[64:65]
	v_mul_f64 v[32:33], v[28:29], v[36:37]
	v_fmac_f64_e32 v[30:31], v[28:29], v[36:37]
	v_mul_f64 v[28:29], v[26:27], s[66:67]
	v_mul_f64 v[36:37], v[28:29], v[38:39]
	v_fmac_f64_e32 v[24:25], v[28:29], v[38:39]
	v_mul_f64 v[28:29], v[26:27], s[48:49]
	v_mul_f64 v[38:39], v[28:29], v[32:33]
	v_fmac_f64_e32 v[30:31], v[28:29], v[32:33]
	v_mul_f64 v[28:29], v[26:27], s[68:69]
	v_mul_f64 v[32:33], v[28:29], v[36:37]
	v_fmac_f64_e32 v[24:25], v[28:29], v[36:37]
	v_mul_f64 v[28:29], v[26:27], s[70:71]
	v_mul_f64 v[36:37], v[28:29], v[38:39]
	v_fmac_f64_e32 v[30:31], v[28:29], v[38:39]
	v_mul_f64 v[28:29], v[26:27], s[14:15]
	v_mul_f64 v[38:39], v[28:29], v[32:33]
	v_fmac_f64_e32 v[24:25], v[28:29], v[32:33]
	v_mul_f64 v[28:29], v[26:27], s[74:75]
	v_mul_f64 v[32:33], v[28:29], v[36:37]
	v_fmac_f64_e32 v[30:31], v[28:29], v[36:37]
	v_mul_f64 v[28:29], v[26:27], s[76:77]
	v_mul_f64 v[36:37], v[28:29], v[38:39]
	v_fmac_f64_e32 v[24:25], v[28:29], v[38:39]
	v_mul_f64 v[28:29], v[26:27], s[78:79]
	v_mul_f64 v[38:39], v[28:29], v[32:33]
	v_fmac_f64_e32 v[30:31], v[28:29], v[32:33]
	v_mul_f64 v[28:29], v[26:27], s[80:81]
	v_mul_f64 v[32:33], v[28:29], v[36:37]
	v_fmac_f64_e32 v[24:25], v[28:29], v[36:37]
	v_mul_f64 v[28:29], v[26:27], s[82:83]
	v_mul_f64 v[36:37], v[28:29], v[38:39]
	v_fmac_f64_e32 v[30:31], v[28:29], v[38:39]
	v_mul_f64 v[28:29], v[26:27], s[88:89]
	v_mul_f64 v[38:39], v[28:29], v[32:33]
	v_fmac_f64_e32 v[24:25], v[28:29], v[32:33]
	v_mul_f64 v[28:29], v[26:27], s[90:91]
	v_mul_f64 v[32:33], v[28:29], v[36:37]
	v_fmac_f64_e32 v[30:31], v[28:29], v[36:37]
	v_mul_f64 v[28:29], v[26:27], s[92:93]
	v_mul_f64 v[36:37], v[28:29], v[38:39]
	v_fmac_f64_e32 v[24:25], v[28:29], v[38:39]
	v_mul_f64 v[28:29], v[26:27], s[94:95]
	v_mul_f64 v[26:27], v[26:27], s[96:97]
	v_fmac_f64_e32 v[30:31], v[28:29], v[32:33]
	v_fmac_f64_e32 v[24:25], v[26:27], v[36:37]
	v_cvt_f32_f64_e32 v25, v[24:25]
	v_cvt_f32_f64_e32 v24, v[30:31]
	s_and_saveexec_b64 s[0:1], vcc
	s_xor_b64 s[2:3], exec, s[0:1]
	s_cbranch_execz .LBB0_415
	v_lshlrev_b32_e32 v22, 5, v22
	v_add3_u32 v2, v2, v22, -8
	v_lshl_add_u64 v[22:23], v[2:3], 3, s[8:9]
	global_store_dwordx2 v[22:23], v[24:25], off
.LBB0_415:
	s_andn2_saveexec_b64 s[2:3], s[2:3]
	s_cbranch_execz .LBB0_408
	v_lshlrev_b64 v[22:23], 6, v[22:23]
	v_lshl_add_u64 v[22:23], s[10:11], 0, v[22:23]
	v_lshl_add_u64 v[22:23], v[2:3], 3, v[22:23]
	global_store_dwordx2 v[22:23], v[24:25], off
	s_branch .LBB0_408
.LBB0_417:
	s_or_b64 exec, exec, s[6:7]
	v_lshrrev_b32_e32 v1, 20, v0
	v_lshrrev_b32_e32 v0, 10, v0
	v_or_b32_e32 v0, v0, v1
	s_movk_i32 s0, 0x3ff
	v_and_or_b32 v0, v0, s0, v211
	v_cmp_eq_u32_e32 vcc, 0, v0
	s_waitcnt lgkmcnt(0)
	s_barrier
	s_barrier
	s_and_saveexec_b64 s[2:3], vcc
	s_branch .LBB0_427
	buffer_wbl2 sc1
	s_waitcnt vmcnt(0)
	s_load_dwordx2 s[4:5], s[86:87], 0x58
	v_mov_b32_e32 v2, 0
	s_mov_b64 s[6:7], exec
	v_mbcnt_lo_u32_b32 v1, s6, 0
	v_mbcnt_hi_u32_b32 v1, s7, v1
	s_waitcnt lgkmcnt(0)
	global_load_dword v0, v2, s[4:5] offset:40
	v_cmp_eq_u32_e32 vcc, 0, v1
	s_and_saveexec_b64 s[8:9], vcc
	s_cbranch_execz .LBB0_420
	s_bcnt1_i32_b64 s0, s[6:7]
	v_mov_b32_e32 v3, s0
	global_atomic_add v3, v2, v3, s[4:5] offset:32 sc0

; __device__ __forceinline__ unsigned cvt_pk_bf16(float lo, float hi) { unsigned r; asm volatile("v_cvt_pk_bf16_f32 %0, %1, %2" : "=v"(r) : "v"(lo), "v"(hi)); return r; }
; #define LAS __attribute__((address_space(3)))
; __global__ void __launch_bounds__(512, 2) mega_fwd(Params P) {
;     ...
;                   { LAS unsigned* CV = (LAS unsigned*)(lds + 131072); for (int i = tid; i < 1024; i += 512) CV[i] = (cvt_pk_bf16(cvk[i], 0.f) & 0xffffu) | (cvt_pk_bf16(cvk[5632 + i], 0.f) << 16);
.LBB0_492:
	v_add_co_u32_e32 v6, vcc, 0xffffa800, v4
	v_add_u32_e32 v0, 0x200, v0
	s_nop 0
	v_addc_co_u32_e32 v7, vcc, -1, v5, vcc
	global_load_dword v6, v[6:7], off
	s_waitcnt vmcnt(0) lgkmcnt(0)
	v_cvt_pk_bf16_f32 v6, v6, v1
	global_load_dword v7, v[4:5], off
	v_and_b32_e32 v6, 0xffff, v6
	v_cmp_lt_i32_e32 vcc, s69, v0
	s_waitcnt vmcnt(0) lgkmcnt(0)
	v_cvt_pk_bf16_f32 v7, v7, v1
	s_or_b64 s[6:7], vcc, s[6:7]
	v_lshl_or_b32 v6, v7, 16, v6
	v_lshl_add_u64 v[4:5], v[4:5], 0, s[42:43]
	ds_write_b32 v3, v6
	v_add_u32_e32 v3, 0x800, v3
	s_andn2_b64 exec, exec, s[6:7]
	s_cbranch_execnz .LBB0_492

; #define PG8_STAGE(bufoff, gbase, voff) do { _Pragma("unroll") for (int _i = 0; _i < 2; ++_i) \
;         __builtin_amdgcn_global_load_lds((const unsigned*)((const char*)(gbase) + (voff)[_i]), (PG8_LAS unsigned*)(lds + (bufoff) + ldsw + _i * 8192), 16, 0, 0); } while (0)
; #define PG8_LDA(dst, b, h) do { _Pragma("unroll") for (int m = 0; m < 4; ++m) _Pragma("unroll") for (int k = 0; k < 2; ++k) dst[m][k] = *(const PG8_LAS bf16x8*)(lds + PG8_SA(b, h) + aoff + m * 2048 + k * 1024); } while (0)
; #define PG8_LDB(dst, b, h) do { _Pragma("unroll") for (int n = 0; n < 2; ++n) _Pragma("unroll") for (int k = 0; k < 2; ++k) dst[n][k] = *(const PG8_LAS bf16x8*)(lds + PG8_SB(b, h) + boff + n * 2048 + k * 1024); } while (0)
; #define PG8_MMA(ai, bj, At, Bt) do { __builtin_amdgcn_s_setprio(1); _Pragma("unroll") for (int m = 0; m < 4; ++m) _Pragma("unroll") for (int n = 0; n < 2; ++n) _Pragma("unroll") for (int k = 0; k < 2; ++k) \
;         acc[ai][bj][m][n] = __builtin_amdgcn_mfma_f32_16x16x32_bf16(Bt[n][k], At[m][k], acc[ai][bj][m][n], 0, 0, 0); __builtin_amdgcn_s_setprio(0); } while (0)
; #define PG8_WAIT_V(n) asm volatile("s_waitcnt vmcnt(" #n ")" ::: "memory")
; #define PG8_WAIT_L(n) asm volatile("s_waitcnt lgkmcnt(" #n ")" ::: "memory")
; template <class Epi, class Sched, bool ALIGN_EPI = false, bool SP2 = false>
; __device__ __forceinline__ void gemm_phase(PG8_LAS unsigned char* lds, const Gemm g, const Sched& S, const Epi& E) {
;     ...
;             const bool last = (t == nt - 2);
;             const char* a1 = cA + (size_t)(t + 1) * kstep;
;             const char* a2 = last ? nA : cA + (size_t)(t + 2) * kstep; const char* b2 = last ? nB : cB + (size_t)(t + 2) * kstep;
;             const char* a3 = a2 + kstep; const char* b3 = b2 + kstep;
;             if (last && has_next) S.a_ready(nxt);
;             if constexpr (SP2) {
;             PG8_LDB(B0, 0, 0); PG8_LDB(B1, 0, 1); PG8_SCHED; PG8_LDA(At, 0, 0); PG8_STAGE(PG8_SA(1, 1), a1 + hstep, voffA);
;             PG8_WAIT_V(8); PG8_WAIT_L(0); PG8_BAR; PG8_MMA(0, 0, At, B0); PG8_MMA(0, 1, At, B1); PG8_BAR; PG8_SCHED;
;             PG8_LDA(At, 0, 1); PG8_STAGE(PG8_SB(0, 0), b2, voffB); PG8_STAGE(PG8_SB(0, 1), b2 + hstep, voffB); PG8_STAGE(PG8_SA(0, 0), a2, voffA);
;             PG8_WAIT_V(8); PG8_WAIT_L(0); PG8_BAR; PG8_MMA(1, 0, At, B0); PG8_MMA(1, 1, At, B1); PG8_BAR; PG8_SCHED;
.LBB0_517:
	s_add_i32 s62, s28, 2
	s_add_u32 s63, s26, 0x80
	s_addc_u32 s29, s27, 0
	s_add_i32 s67, 0, 0x10000
	s_cmp_eq_u32 s46, s28
	s_cselect_b32 s29, s5, s29
	s_cselect_b32 s28, s4, s63
	v_add_u32_e32 v0, s67, v205
	s_cselect_b32 s75, s25, s61
	s_cselect_b32 s74, s24, s56
	s_add_i32 s63, 0, 0x14000
	ds_read_b128 v[130:133], v0
	ds_read_b128 v[134:137], v0 offset:1024
	ds_read_b128 v[138:141], v0 offset:2048
	ds_read_b128 v[142:145], v0 offset:3072
	v_add_u32_e32 v0, s63, v205
	ds_read_b128 v[162:165], v0
	ds_read_b128 v[166:169], v0 offset:1024
	ds_read_b128 v[170:173], v0 offset:2048
	ds_read_b128 v[174:177], v0 offset:3072
	v_lshl_add_u64 v[158:159], s[26:27], 0, v[156:157]
	s_add_i32 m0, s34, 0xc000
	ds_read_b128 v[178:181], v231
	ds_read_b128 v[182:185], v231 offset:1024
	ds_read_b128 v[194:197], v231 offset:2048
	ds_read_b128 v[198:201], v231 offset:3072
	ds_read_b128 v[232:235], v231 offset:4096
	ds_read_b128 v[236:239], v231 offset:5120
	ds_read_b128 v[240:243], v231 offset:6144
	ds_read_b128 v[244:247], v231 offset:7168
	global_load_lds_dwordx4 v[158:159], off
	v_lshl_add_u64 v[158:159], s[26:27], 0, v[154:155]
	s_add_i32 m0, s34, 0xe000
	s_nop 0
	global_load_lds_dwordx4 v[158:159], off
	s_waitcnt vmcnt(8)
	s_waitcnt lgkmcnt(0)
	s_barrier
	s_setprio 1
	v_mfma_f32_16x16x32_bf16 v[126:129], v[130:133], v[178:181], v[126:129]
	v_mfma_f32_16x16x32_bf16 v[122:125], v[138:141], v[178:181], v[122:125]
	v_mfma_f32_16x16x32_bf16 v[110:113], v[130:133], v[194:197], v[110:113]
	v_mfma_f32_16x16x32_bf16 v[106:109], v[138:141], v[194:197], v[106:109]
	v_mfma_f32_16x16x32_bf16 v[94:97], v[130:133], v[232:235], v[94:97]
	v_mfma_f32_16x16x32_bf16 v[90:93], v[138:141], v[232:235], v[90:93]
	v_mfma_f32_16x16x32_bf16 v[78:81], v[130:133], v[240:243], v[78:81]
	v_mfma_f32_16x16x32_bf16 v[74:77], v[138:141], v[240:243], v[74:77]
	v_mfma_f32_16x16x32_bf16 v[126:129], v[134:137], v[182:185], v[126:129]
	v_mfma_f32_16x16x32_bf16 v[122:125], v[142:145], v[182:185], v[122:125]
	v_mfma_f32_16x16x32_bf16 v[110:113], v[134:137], v[198:201], v[110:113]
	v_mfma_f32_16x16x32_bf16 v[106:109], v[142:145], v[198:201], v[106:109]
	v_mfma_f32_16x16x32_bf16 v[94:97], v[134:137], v[236:239], v[94:97]
	v_mfma_f32_16x16x32_bf16 v[90:93], v[142:145], v[236:239], v[90:93]
	v_mfma_f32_16x16x32_bf16 v[78:81], v[134:137], v[244:247], v[78:81]
	v_mfma_f32_16x16x32_bf16 v[74:77], v[142:145], v[244:247], v[74:77]
	s_setprio 0
	s_setprio 1
	v_mfma_f32_16x16x32_bf16 v[118:121], v[162:165], v[178:181], v[118:121]
	v_mfma_f32_16x16x32_bf16 v[114:117], v[170:173], v[178:181], v[114:117]
	v_mfma_f32_16x16x32_bf16 v[102:105], v[162:165], v[194:197], v[102:105]
	v_mfma_f32_16x16x32_bf16 v[98:101], v[170:173], v[194:197], v[98:101]
	v_mfma_f32_16x16x32_bf16 v[86:89], v[162:165], v[232:235], v[86:89]
	v_mfma_f32_16x16x32_bf16 v[82:85], v[170:173], v[232:235], v[82:85]
	v_mfma_f32_16x16x32_bf16 v[70:73], v[162:165], v[240:243], v[70:73]
	v_mfma_f32_16x16x32_bf16 v[66:69], v[170:173], v[240:243], v[66:69]
	v_mfma_f32_16x16x32_bf16 v[118:121], v[166:169], v[182:185], v[118:121]
	v_mfma_f32_16x16x32_bf16 v[114:117], v[174:177], v[182:185], v[114:117]
	v_mfma_f32_16x16x32_bf16 v[102:105], v[166:169], v[198:201], v[102:105]
	v_mfma_f32_16x16x32_bf16 v[98:101], v[174:177], v[198:201], v[98:101]
	v_mfma_f32_16x16x32_bf16 v[86:89], v[166:169], v[236:239], v[86:89]
	v_mfma_f32_16x16x32_bf16 v[82:85], v[174:177], v[236:239], v[82:85]
	v_mfma_f32_16x16x32_bf16 v[70:73], v[166:169], v[244:247], v[70:73]
	v_mfma_f32_16x16x32_bf16 v[66:69], v[174:177], v[244:247], v[66:69]
	s_setprio 0
	s_barrier
	s_add_i32 s67, s67, s33
	v_lshl_add_u64 v[158:159], s[74:75], 0, v[148:149]
	s_mov_b32 m0, s67
	ds_read_b128 v[178:181], v231 offset:16384
	ds_read_b128 v[182:185], v231 offset:17408
	ds_read_b128 v[194:197], v231 offset:18432
	ds_read_b128 v[198:201], v231 offset:19456
	ds_read_b128 v[232:235], v231 offset:20480
	ds_read_b128 v[236:239], v231 offset:21504
	ds_read_b128 v[240:243], v231 offset:22528
	ds_read_b128 v[244:247], v231 offset:23552
	global_load_lds_dwordx4 v[158:159], off
	s_add_i32 m0, s67, 0x2000
	v_lshl_add_u64 v[202:203], s[74:75], 0, v[152:153]
	s_add_u32 s74, s74, s10
	s_addc_u32 s75, s75, s11
	s_add_i32 s63, s63, s33
	global_load_lds_dwordx4 v[202:203], off
	v_lshl_add_u64 v[212:213], s[74:75], 0, v[148:149]
	s_mov_b32 m0, s63
	v_lshl_add_u64 v[214:215], s[74:75], 0, v[152:153]
	global_load_lds_dwordx4 v[212:213], off
	s_add_i32 m0, s63, 0x2000
	v_lshl_add_u64 v[216:217], s[28:29], 0, v[146:147]
	global_load_lds_dwordx4 v[214:215], off
	s_mov_b32 m0, s34
	v_lshl_add_u64 v[248:249], s[28:29], 0, v[150:151]
	global_load_lds_dwordx4 v[216:217], off
	s_mov_b32 m0, s40
	s_nop 0
	global_load_lds_dwordx4 v[248:249], off
	s_waitcnt vmcnt(8)
	s_waitcnt lgkmcnt(0)
	s_barrier
; #define PG8_STAGE(bufoff, gbase, voff) do { _Pragma("unroll") for (int _i = 0; _i < 2; ++_i) \
;         __builtin_amdgcn_global_load_lds((const unsigned*)((const char*)(gbase) + (voff)[_i]), (PG8_LAS unsigned*)(lds + (bufoff) + ldsw + _i * 8192), 16, 0, 0); } while (0)
; #define PG8_LDA(dst, b, h) do { _Pragma("unroll") for (int m = 0; m < 4; ++m) _Pragma("unroll") for (int k = 0; k < 2; ++k) dst[m][k] = *(const PG8_LAS bf16x8*)(lds + PG8_SA(b, h) + aoff + m * 2048 + k * 1024); } while (0)
; #define PG8_LDB(dst, b, h) do { _Pragma("unroll") for (int n = 0; n < 2; ++n) _Pragma("unroll") for (int k = 0; k < 2; ++k) dst[n][k] = *(const PG8_LAS bf16x8*)(lds + PG8_SB(b, h) + boff + n * 2048 + k * 1024); } while (0)
; #define PG8_MMA(ai, bj, At, Bt) do { __builtin_amdgcn_s_setprio(1); _Pragma("unroll") for (int m = 0; m < 4; ++m) _Pragma("unroll") for (int n = 0; n < 2; ++n) _Pragma("unroll") for (int k = 0; k < 2; ++k) \
;         acc[ai][bj][m][n] = __builtin_amdgcn_mfma_f32_16x16x32_bf16(Bt[n][k], At[m][k], acc[ai][bj][m][n], 0, 0, 0); __builtin_amdgcn_s_setprio(0); } while (0)
; #define PG8_WAIT_V(n) asm volatile("s_waitcnt vmcnt(" #n ")" ::: "memory")
; #define PG8_WAIT_L(n) asm volatile("s_waitcnt lgkmcnt(" #n ")" ::: "memory")
; #define PG8_BAR __builtin_amdgcn_s_barrier()
; #define PG8_SCHED __builtin_amdgcn_sched_barrier(0)
; template <class Epi, class Sched, bool ALIGN_EPI = false, bool SP2 = false>
; __device__ __forceinline__ void gemm_phase(PG8_LAS unsigned char* lds, const Gemm g, const Sched& S, const Epi& E) {
;     ...
;             PG8_WAIT_V(8); PG8_WAIT_L(0); PG8_BAR; PG8_MMA(1, 0, At, B0); PG8_MMA(1, 1, At, B1); PG8_BAR; PG8_SCHED;
;             PG8_LDB(B0, 1, 0); PG8_LDB(B1, 1, 1); PG8_SCHED; PG8_LDA(At, 1, 0); PG8_STAGE(PG8_SA(0, 1), a2 + hstep, voffA);
;             PG8_WAIT_V(8); PG8_WAIT_L(0); PG8_BAR; PG8_MMA(0, 0, At, B0); PG8_MMA(0, 1, At, B1); PG8_BAR; PG8_SCHED;
	s_setprio 1
	v_mfma_f32_16x16x32_bf16 v[62:65], v[130:133], v[178:181], v[62:65]
	v_mfma_f32_16x16x32_bf16 v[58:61], v[138:141], v[178:181], v[58:61]
	v_mfma_f32_16x16x32_bf16 v[46:49], v[130:133], v[194:197], v[46:49]
	v_mfma_f32_16x16x32_bf16 v[42:45], v[138:141], v[194:197], v[42:45]
	v_mfma_f32_16x16x32_bf16 v[30:33], v[130:133], v[232:235], v[30:33]
	v_mfma_f32_16x16x32_bf16 v[26:29], v[138:141], v[232:235], v[26:29]
	v_mfma_f32_16x16x32_bf16 v[14:17], v[130:133], v[240:243], v[14:17]
	v_mfma_f32_16x16x32_bf16 v[10:13], v[138:141], v[240:243], v[10:13]
	v_mfma_f32_16x16x32_bf16 v[62:65], v[134:137], v[182:185], v[62:65]
	v_mfma_f32_16x16x32_bf16 v[58:61], v[142:145], v[182:185], v[58:61]
	v_mfma_f32_16x16x32_bf16 v[46:49], v[134:137], v[198:201], v[46:49]
	v_mfma_f32_16x16x32_bf16 v[42:45], v[142:145], v[198:201], v[42:45]
	v_mfma_f32_16x16x32_bf16 v[30:33], v[134:137], v[236:239], v[30:33]
	v_mfma_f32_16x16x32_bf16 v[26:29], v[142:145], v[236:239], v[26:29]
	v_mfma_f32_16x16x32_bf16 v[14:17], v[134:137], v[244:247], v[14:17]
	v_mfma_f32_16x16x32_bf16 v[10:13], v[142:145], v[244:247], v[10:13]
	s_setprio 0
	s_setprio 1
	v_mfma_f32_16x16x32_bf16 v[54:57], v[162:165], v[178:181], v[54:57]
	v_mfma_f32_16x16x32_bf16 v[50:53], v[170:173], v[178:181], v[50:53]
	v_mfma_f32_16x16x32_bf16 v[38:41], v[162:165], v[194:197], v[38:41]
	v_mfma_f32_16x16x32_bf16 v[34:37], v[170:173], v[194:197], v[34:37]
	v_mfma_f32_16x16x32_bf16 v[22:25], v[162:165], v[232:235], v[22:25]
	v_mfma_f32_16x16x32_bf16 v[18:21], v[170:173], v[232:235], v[18:21]
	v_mfma_f32_16x16x32_bf16 v[6:9], v[162:165], v[240:243], v[6:9]
	v_mfma_f32_16x16x32_bf16 v[2:5], v[170:173], v[240:243], v[2:5]
	v_mfma_f32_16x16x32_bf16 v[54:57], v[166:169], v[182:185], v[54:57]
	v_mfma_f32_16x16x32_bf16 v[50:53], v[174:177], v[182:185], v[50:53]
	v_mfma_f32_16x16x32_bf16 v[38:41], v[166:169], v[198:201], v[38:41]
	v_mfma_f32_16x16x32_bf16 v[34:37], v[174:177], v[198:201], v[34:37]
	v_mfma_f32_16x16x32_bf16 v[22:25], v[166:169], v[236:239], v[22:25]
	v_mfma_f32_16x16x32_bf16 v[18:21], v[174:177], v[236:239], v[18:21]
	v_mfma_f32_16x16x32_bf16 v[6:9], v[166:169], v[244:247], v[6:9]
	v_mfma_f32_16x16x32_bf16 v[2:5], v[174:177], v[244:247], v[2:5]
	s_setprio 0
	s_barrier
	s_add_i32 s63, 0, 0x18000
	v_add_u32_e32 v0, s63, v205
	s_add_i32 s67, 0, 0x1c000
	ds_read_b128 v[130:133], v0
	ds_read_b128 v[134:137], v0 offset:1024
	ds_read_b128 v[138:141], v0 offset:2048
	ds_read_b128 v[142:145], v0 offset:3072
	v_add_u32_e32 v0, s67, v205
	ds_read_b128 v[162:165], v0
	ds_read_b128 v[166:169], v0 offset:1024
	ds_read_b128 v[170:173], v0 offset:2048
	ds_read_b128 v[174:177], v0 offset:3072
	s_add_u32 s28, s28, s10
	s_addc_u32 s29, s29, s11
	s_mov_b32 m0, s41
	v_lshl_add_u64 v[250:251], s[28:29], 0, v[146:147]
	ds_read_b128 v[178:181], v231 offset:32768
	ds_read_b128 v[182:185], v231 offset:33792
	ds_read_b128 v[194:197], v231 offset:34816
	ds_read_b128 v[198:201], v231 offset:35840
	ds_read_b128 v[232:235], v231 offset:36864
	ds_read_b128 v[236:239], v231 offset:37888
	ds_read_b128 v[240:243], v231 offset:38912
	ds_read_b128 v[244:247], v231 offset:39936
	global_load_lds_dwordx4 v[250:251], off
	v_lshl_add_u64 v[250:251], s[28:29], 0, v[150:151]
	s_mov_b32 m0, s42
	s_nop 0
	global_load_lds_dwordx4 v[250:251], off
	s_waitcnt vmcnt(8)
	s_waitcnt lgkmcnt(0)
	s_barrier
	s_setprio 1
	v_mfma_f32_16x16x32_bf16 v[126:129], v[130:133], v[178:181], v[126:129]
	v_mfma_f32_16x16x32_bf16 v[122:125], v[138:141], v[178:181], v[122:125]
	v_mfma_f32_16x16x32_bf16 v[110:113], v[130:133], v[194:197], v[110:113]
	v_mfma_f32_16x16x32_bf16 v[106:109], v[138:141], v[194:197], v[106:109]
	v_mfma_f32_16x16x32_bf16 v[94:97], v[130:133], v[232:235], v[94:97]
	v_mfma_f32_16x16x32_bf16 v[90:93], v[138:141], v[232:235], v[90:93]
	v_mfma_f32_16x16x32_bf16 v[78:81], v[130:133], v[240:243], v[78:81]
	v_mfma_f32_16x16x32_bf16 v[74:77], v[138:141], v[240:243], v[74:77]
	v_mfma_f32_16x16x32_bf16 v[126:129], v[134:137], v[182:185], v[126:129]
	v_mfma_f32_16x16x32_bf16 v[122:125], v[142:145], v[182:185], v[122:125]
	v_mfma_f32_16x16x32_bf16 v[110:113], v[134:137], v[198:201], v[110:113]
	v_mfma_f32_16x16x32_bf16 v[106:109], v[142:145], v[198:201], v[106:109]
	v_mfma_f32_16x16x32_bf16 v[94:97], v[134:137], v[236:239], v[94:97]
	v_mfma_f32_16x16x32_bf16 v[90:93], v[142:145], v[236:239], v[90:93]
	v_mfma_f32_16x16x32_bf16 v[78:81], v[134:137], v[244:247], v[78:81]
	v_mfma_f32_16x16x32_bf16 v[74:77], v[142:145], v[244:247], v[74:77]
	s_setprio 0
	s_setprio 1
	v_mfma_f32_16x16x32_bf16 v[118:121], v[162:165], v[178:181], v[118:121]
	v_mfma_f32_16x16x32_bf16 v[114:117], v[170:173], v[178:181], v[114:117]
	v_mfma_f32_16x16x32_bf16 v[102:105], v[162:165], v[194:197], v[102:105]
	v_mfma_f32_16x16x32_bf16 v[98:101], v[170:173], v[194:197], v[98:101]
	v_mfma_f32_16x16x32_bf16 v[86:89], v[162:165], v[232:235], v[86:89]
	v_mfma_f32_16x16x32_bf16 v[82:85], v[170:173], v[232:235], v[82:85]
	v_mfma_f32_16x16x32_bf16 v[70:73], v[162:165], v[240:243], v[70:73]
	v_mfma_f32_16x16x32_bf16 v[66:69], v[170:173], v[240:243], v[66:69]
	v_mfma_f32_16x16x32_bf16 v[118:121], v[166:169], v[182:185], v[118:121]
	v_mfma_f32_16x16x32_bf16 v[114:117], v[174:177], v[182:185], v[114:117]
	v_mfma_f32_16x16x32_bf16 v[102:105], v[166:169], v[198:201], v[102:105]
	v_mfma_f32_16x16x32_bf16 v[98:101], v[174:177], v[198:201], v[98:101]
	v_mfma_f32_16x16x32_bf16 v[86:89], v[166:169], v[236:239], v[86:89]
	v_mfma_f32_16x16x32_bf16 v[82:85], v[174:177], v[236:239], v[82:85]
	v_mfma_f32_16x16x32_bf16 v[70:73], v[166:169], v[244:247], v[70:73]
	v_mfma_f32_16x16x32_bf16 v[66:69], v[174:177], v[244:247], v[66:69]
	s_setprio 0
	s_barrier
; #define PG8_STAGE(bufoff, gbase, voff) do { _Pragma("unroll") for (int _i = 0; _i < 2; ++_i) \
;         __builtin_amdgcn_global_load_lds((const unsigned*)((const char*)(gbase) + (voff)[_i]), (PG8_LAS unsigned*)(lds + (bufoff) + ldsw + _i * 8192), 16, 0, 0); } while (0)
; #define PG8_LDA(dst, b, h) do { _Pragma("unroll") for (int m = 0; m < 4; ++m) _Pragma("unroll") for (int k = 0; k < 2; ++k) dst[m][k] = *(const PG8_LAS bf16x8*)(lds + PG8_SA(b, h) + aoff + m * 2048 + k * 1024); } while (0)
; #define PG8_MMA(ai, bj, At, Bt) do { __builtin_amdgcn_s_setprio(1); _Pragma("unroll") for (int m = 0; m < 4; ++m) _Pragma("unroll") for (int n = 0; n < 2; ++n) _Pragma("unroll") for (int k = 0; k < 2; ++k) \
;         acc[ai][bj][m][n] = __builtin_amdgcn_mfma_f32_16x16x32_bf16(Bt[n][k], At[m][k], acc[ai][bj][m][n], 0, 0, 0); __builtin_amdgcn_s_setprio(0); } while (0)
; #define PG8_WAIT_V(n) asm volatile("s_waitcnt vmcnt(" #n ")" ::: "memory")
; #define PG8_WAIT_L(n) asm volatile("s_waitcnt lgkmcnt(" #n ")" ::: "memory")
; #define PG8_BAR __builtin_amdgcn_s_barrier()
; #define PG8_SCHED __builtin_amdgcn_sched_barrier(0)
; template <class Epi, class Sched, bool ALIGN_EPI = false, bool SP2 = false>
; __device__ __forceinline__ void gemm_phase(PG8_LAS unsigned char* lds, const Gemm g, const Sched& S, const Epi& E) {
;     ...
;         for (int t = 0; t < nt; t += 2) {
;     ...
;             PG8_WAIT_V(8); PG8_WAIT_L(0); PG8_BAR; PG8_MMA(0, 0, At, B0); PG8_MMA(0, 1, At, B1); PG8_BAR; PG8_SCHED;
;             PG8_LDA(At, 1, 1); PG8_STAGE(PG8_SB(1, 0), b3, voffB); PG8_STAGE(PG8_SB(1, 1), b3 + hstep, voffB); PG8_STAGE(PG8_SA(1, 0), a3, voffA);
;             PG8_WAIT_V(8); PG8_WAIT_L(0); PG8_BAR; PG8_MMA(1, 0, At, B0); PG8_MMA(1, 1, At, B1); PG8_BAR; PG8_SCHED;
	s_add_i32 s28, s63, s33
	v_lshl_add_u64 v[158:159], v[158:159], 0, s[38:39]
	s_mov_b32 m0, s28
	ds_read_b128 v[178:181], v231 offset:49152
	ds_read_b128 v[182:185], v231 offset:50176
	ds_read_b128 v[194:197], v231 offset:51200
	ds_read_b128 v[198:201], v231 offset:52224
	ds_read_b128 v[232:235], v231 offset:53248
	ds_read_b128 v[236:239], v231 offset:54272
	ds_read_b128 v[240:243], v231 offset:55296
	ds_read_b128 v[244:247], v231 offset:56320
	global_load_lds_dwordx4 v[158:159], off
	v_lshl_add_u64 v[158:159], v[202:203], 0, s[38:39]
	s_add_i32 m0, s28, 0x2000
	s_add_i32 s28, s67, s33
	global_load_lds_dwordx4 v[158:159], off
	v_lshl_add_u64 v[158:159], v[212:213], 0, s[38:39]
	s_mov_b32 m0, s28
	s_nop 0
	global_load_lds_dwordx4 v[158:159], off
	v_lshl_add_u64 v[158:159], v[214:215], 0, s[38:39]
	s_add_i32 m0, s28, 0x2000
	s_nop 0
	global_load_lds_dwordx4 v[158:159], off
	v_lshl_add_u64 v[158:159], v[216:217], 0, s[38:39]
	s_mov_b32 m0, s44
	s_nop 0
	global_load_lds_dwordx4 v[158:159], off
	v_lshl_add_u64 v[158:159], v[248:249], 0, s[38:39]
	s_mov_b32 m0, s45
	s_nop 0
	global_load_lds_dwordx4 v[158:159], off
	s_waitcnt vmcnt(8)
	s_waitcnt lgkmcnt(0)
	s_barrier
	s_setprio 1
	v_mfma_f32_16x16x32_bf16 v[62:65], v[130:133], v[178:181], v[62:65]
	v_mfma_f32_16x16x32_bf16 v[58:61], v[138:141], v[178:181], v[58:61]
	v_mfma_f32_16x16x32_bf16 v[46:49], v[130:133], v[194:197], v[46:49]
	v_mfma_f32_16x16x32_bf16 v[42:45], v[138:141], v[194:197], v[42:45]
	v_mfma_f32_16x16x32_bf16 v[30:33], v[130:133], v[232:235], v[30:33]
	v_mfma_f32_16x16x32_bf16 v[26:29], v[138:141], v[232:235], v[26:29]
	v_mfma_f32_16x16x32_bf16 v[14:17], v[130:133], v[240:243], v[14:17]
	v_mfma_f32_16x16x32_bf16 v[10:13], v[138:141], v[240:243], v[10:13]
	v_mfma_f32_16x16x32_bf16 v[62:65], v[134:137], v[182:185], v[62:65]
	v_mfma_f32_16x16x32_bf16 v[58:61], v[142:145], v[182:185], v[58:61]
	v_mfma_f32_16x16x32_bf16 v[46:49], v[134:137], v[198:201], v[46:49]
	v_mfma_f32_16x16x32_bf16 v[42:45], v[142:145], v[198:201], v[42:45]
	v_mfma_f32_16x16x32_bf16 v[30:33], v[134:137], v[236:239], v[30:33]
	v_mfma_f32_16x16x32_bf16 v[26:29], v[142:145], v[236:239], v[26:29]
	v_mfma_f32_16x16x32_bf16 v[14:17], v[134:137], v[244:247], v[14:17]
	v_mfma_f32_16x16x32_bf16 v[10:13], v[142:145], v[244:247], v[10:13]
	s_setprio 0
	s_setprio 1
	v_mfma_f32_16x16x32_bf16 v[54:57], v[162:165], v[178:181], v[54:57]
	v_mfma_f32_16x16x32_bf16 v[50:53], v[170:173], v[178:181], v[50:53]
	v_mfma_f32_16x16x32_bf16 v[38:41], v[162:165], v[194:197], v[38:41]
	v_mfma_f32_16x16x32_bf16 v[34:37], v[170:173], v[194:197], v[34:37]
	v_mfma_f32_16x16x32_bf16 v[22:25], v[162:165], v[232:235], v[22:25]
	v_mfma_f32_16x16x32_bf16 v[18:21], v[170:173], v[232:235], v[18:21]
	v_mfma_f32_16x16x32_bf16 v[6:9], v[162:165], v[240:243], v[6:9]
	v_mfma_f32_16x16x32_bf16 v[2:5], v[170:173], v[240:243], v[2:5]
	v_mfma_f32_16x16x32_bf16 v[54:57], v[166:169], v[182:185], v[54:57]
	v_mfma_f32_16x16x32_bf16 v[50:53], v[174:177], v[182:185], v[50:53]
	v_mfma_f32_16x16x32_bf16 v[38:41], v[166:169], v[198:201], v[38:41]
	v_mfma_f32_16x16x32_bf16 v[34:37], v[174:177], v[198:201], v[34:37]
	v_mfma_f32_16x16x32_bf16 v[22:25], v[166:169], v[236:239], v[22:25]
	v_mfma_f32_16x16x32_bf16 v[18:21], v[174:177], v[236:239], v[18:21]
	v_mfma_f32_16x16x32_bf16 v[6:9], v[166:169], v[244:247], v[6:9]
	v_mfma_f32_16x16x32_bf16 v[2:5], v[174:177], v[244:247], v[2:5]
	s_setprio 0
	s_barrier
	s_add_u32 s56, s56, 0x100
	s_addc_u32 s61, s61, 0
	s_add_u32 s26, s26, 0x100
	s_addc_u32 s27, s27, 0
	s_cmp_ge_i32 s62, s43
	s_mov_b32 s28, s62
	s_cbranch_scc0 .LBB0_517

; __device__ __forceinline__ float xsum_rows(float v) { return xsum32(xsum16(v)); }
; __device__ __forceinline__ void ln_row(const float* st, int row, int fq, float& rs, float& ms) {
;     f32x2 v = *(const f32x2*)(st + (unsigned)(8 * row + 2 * fq));
;     v.x = xsum_rows(v.x); v.y = xsum_rows(v.y);
;     const float mean = v.x * (1.0f / 1024.0f); const float var = v.y * (1.0f / 1024.0f) - mean * mean;
;     rs = __builtin_amdgcn_rsqf(var + 1e-5f); ms = rs * mean;
; }
;     __device__ __forceinline__ void operator()(const f32x4 (&acc)[2][2][4][2], const Unit& u, int wr, int wc, int fr, int fq, PG8_LAS unsigned char* ldsb) const {
;     ...
;             if (TAG[wr] != u.pm) {
; #pragma unroll
;                 for (int ai = 0; ai < 2; ++ai)
; #pragma unroll
;                     for (int m = 0; m < 4; ++m) { ln_row(ln.st, row0 + ai * HALF + m * 16, fq, rsv[ai][m], msv[ai][m]);
;                         f32x2 pr; pr.x = rsv[ai][m]; pr.y = msv[ai][m]; ST[ai * HALF + wr * 64 + m * 16 + fr] = pr; }
;                 asm volatile("s_waitcnt lgkmcnt(0)" ::: "memory");
;                 TAG[wr] = u.pm;
.LBB0_520:
	v_mov_b32_e32 v0, s47
	ds_read_b32 v0, v0
	v_lshl_add_u32 v158, s52, 8, v161
	s_mov_b64 s[26:27], -1
	s_waitcnt lgkmcnt(0)
	v_cmp_eq_u32_e32 vcc, s52, v0
	s_cbranch_vccnz .LBB0_522
	v_lshlrev_b32_e32 v159, 3, v158
	v_or_b32_e32 v0, v159, v207
	v_lshl_add_u64 v[130:131], v[0:1], 2, s[18:19]
	global_load_dwordx2 v[132:133], v[130:131], off
	s_mov_b64 s[26:27], 0
	s_waitcnt vmcnt(0) lgkmcnt(0)
	v_mov_b32_e32 v0, v132
	s_nop 1
	v_permlane16_swap_b32_e32 v132, v0
	v_add_f32_e32 v135, v132, v0
	v_mov_b32_e32 v0, v133
	s_nop 1
	v_permlane16_swap_b32_e32 v133, v0
	v_add_f32_e32 v134, v133, v0
	v_mov_b32_e32 v137, v135
	v_mov_b32_e32 v136, v134
	s_nop 0
	v_permlane32_swap_b32_e32 v135, v137
	v_permlane32_swap_b32_e32 v134, v136
	v_pk_add_f32 v[132:133], v[134:135], v[136:137]
	s_nop 0
	v_pk_mul_f32 v[132:133], v[132:133], s[68:69] op_sel_hi:[1,0]
	s_nop 0
	v_fma_f32 v0, -v133, v133, v132
	v_add_f32_e32 v0, 0x3727c5ac, v0
	v_rsq_f32_e32 v142, v0
	s_nop 0
	v_mul_f32_e32 v143, v133, v142
	ds_write_b64 v209, v[142:143]
	global_load_dwordx2 v[132:133], v[130:131], off offset:512
	v_mov_b32_e32 v214, v143
	s_waitcnt vmcnt(0) lgkmcnt(0)
	v_mov_b32_e32 v0, v132
	s_nop 1
	v_permlane16_swap_b32_e32 v132, v0
	v_add_f32_e32 v135, v132, v0
	v_mov_b32_e32 v0, v133
	s_nop 1
	v_permlane16_swap_b32_e32 v133, v0
	v_add_f32_e32 v134, v133, v0
	v_mov_b32_e32 v137, v135
	v_mov_b32_e32 v136, v134
	s_nop 0
	v_permlane32_swap_b32_e32 v135, v137
	v_permlane32_swap_b32_e32 v134, v136
	v_pk_add_f32 v[132:133], v[134:135], v[136:137]
	s_nop 0
	v_pk_mul_f32 v[132:133], v[132:133], s[68:69] op_sel_hi:[1,0]
	s_nop 0
	v_fma_f32 v0, -v133, v133, v132
	v_add_f32_e32 v0, 0x3727c5ac, v0
	v_rsq_f32_e32 v144, v0
	s_nop 0
	v_mul_f32_e32 v145, v133, v144
	ds_write_b64 v209, v[144:145] offset:128
	global_load_dwordx2 v[132:133], v[130:131], off offset:1024
	v_mov_b32_e32 v212, v145
	s_waitcnt vmcnt(0) lgkmcnt(0)
	v_mov_b32_e32 v0, v132
	s_nop 1
	v_permlane16_swap_b32_e32 v132, v0
	v_add_f32_e32 v135, v132, v0
	v_mov_b32_e32 v0, v133
	s_nop 1
	v_permlane16_swap_b32_e32 v133, v0
	v_add_f32_e32 v134, v133, v0
	v_mov_b32_e32 v137, v135
	v_mov_b32_e32 v136, v134
	s_nop 0
	v_permlane32_swap_b32_e32 v135, v137
	v_permlane32_swap_b32_e32 v134, v136
	v_pk_add_f32 v[132:133], v[134:135], v[136:137]
	s_nop 0
	v_pk_mul_f32 v[132:133], v[132:133], s[68:69] op_sel_hi:[1,0]
	s_nop 0
	v_fma_f32 v0, -v133, v133, v132
	v_add_f32_e32 v0, 0x3727c5ac, v0
	v_rsq_f32_e32 v138, v0
	s_nop 0
	v_mul_f32_e32 v139, v133, v138
	ds_write_b64 v209, v[138:139] offset:256
	global_load_dwordx2 v[130:131], v[130:131], off offset:1536
	v_mov_b32_e32 v210, v139
	s_waitcnt vmcnt(0) lgkmcnt(0)
	v_mov_b32_e32 v0, v130
	s_nop 1
	v_permlane16_swap_b32_e32 v130, v0
	v_add_f32_e32 v133, v130, v0
	v_mov_b32_e32 v0, v131
	s_nop 1
	v_permlane16_swap_b32_e32 v131, v0
	v_add_f32_e32 v132, v131, v0
	v_mov_b32_e32 v135, v133
	v_mov_b32_e32 v134, v132
	s_nop 0
	v_permlane32_swap_b32_e32 v133, v135
	v_permlane32_swap_b32_e32 v132, v134
	v_pk_add_f32 v[130:131], v[132:133], v[134:135]
	s_nop 0
	v_pk_mul_f32 v[130:131], v[130:131], s[68:69] op_sel_hi:[1,0]
	s_nop 0
	v_fma_f32 v0, -v131, v131, v130
	v_add_f32_e32 v0, 0x3727c5ac, v0
	v_rsq_f32_e32 v140, v0
	v_add_u32_e32 v0, v226, v159
	v_mul_f32_e32 v141, v131, v140
	ds_write_b64 v209, v[140:141] offset:384
	v_lshl_add_u64 v[130:131], v[0:1], 2, s[18:19]
	global_load_dwordx2 v[130:131], v[130:131], off
	v_mov_b32_e32 v208, v141
	s_waitcnt vmcnt(0) lgkmcnt(0)
	v_mov_b32_e32 v0, v130
	s_nop 1
	v_permlane16_swap_b32_e32 v130, v0
	v_add_f32_e32 v133, v130, v0
	v_mov_b32_e32 v0, v131
	s_nop 1
	v_permlane16_swap_b32_e32 v131, v0
	v_add_f32_e32 v132, v131, v0
	v_mov_b32_e32 v135, v133
	v_mov_b32_e32 v134, v132
	s_nop 0
	v_permlane32_swap_b32_e32 v133, v135
	v_permlane32_swap_b32_e32 v132, v134
	v_pk_add_f32 v[130:131], v[132:133], v[134:135]
	s_nop 0
	v_pk_mul_f32 v[130:131], v[130:131], s[68:69] op_sel_hi:[1,0]
	s_nop 0
	v_fma_f32 v0, -v131, v131, v130
	v_add_f32_e32 v0, 0x3727c5ac, v0
	v_rsq_f32_e32 v134, v0
	v_add_u32_e32 v0, v227, v159
	v_mul_f32_e32 v135, v131, v134
	ds_write_b64 v209, v[134:135] offset:1024
	v_lshl_add_u64 v[130:131], v[0:1], 2, s[18:19]
	global_load_dwordx2 v[130:131], v[130:131], off
	v_mov_b32_e32 v206, v135
	s_waitcnt vmcnt(0) lgkmcnt(0)
	v_mov_b32_e32 v0, v130
	s_nop 1
	v_permlane16_swap_b32_e32 v130, v0
	v_add_f32_e32 v133, v130, v0
	v_mov_b32_e32 v0, v131
	s_nop 1
	v_permlane16_swap_b32_e32 v131, v0
	v_add_f32_e32 v132, v131, v0
	v_mov_b32_e32 v137, v133
	v_mov_b32_e32 v136, v132
	s_nop 0
	v_permlane32_swap_b32_e32 v133, v137
	v_permlane32_swap_b32_e32 v132, v136
	v_pk_add_f32 v[130:131], v[132:133], v[136:137]
	s_nop 0
	v_pk_mul_f32 v[130:131], v[130:131], s[68:69] op_sel_hi:[1,0]
	s_nop 0
	v_fma_f32 v0, -v131, v131, v130
	v_add_f32_e32 v0, 0x3727c5ac, v0
	v_rsq_f32_e32 v136, v0
	v_add_u32_e32 v0, v228, v159
	v_mul_f32_e32 v137, v131, v136
	ds_write_b64 v209, v[136:137] offset:1152
	v_lshl_add_u64 v[130:131], v[0:1], 2, s[18:19]
	global_load_dwordx2 v[130:131], v[130:131], off
	v_mov_b32_e32 v204, v137
	s_waitcnt vmcnt(0) lgkmcnt(0)
	v_mov_b32_e32 v0, v130
	s_nop 1
	v_permlane16_swap_b32_e32 v130, v0
	v_add_f32_e32 v133, v130, v0
	v_mov_b32_e32 v0, v131
	s_nop 1
	v_permlane16_swap_b32_e32 v131, v0
	v_add_f32_e32 v132, v131, v0
	v_mov_b32_e32 v163, v133
	v_mov_b32_e32 v162, v132
	s_nop 0
	v_permlane32_swap_b32_e32 v133, v163
	v_permlane32_swap_b32_e32 v132, v162
	v_pk_add_f32 v[130:131], v[132:133], v[162:163]
	s_nop 0
	v_pk_mul_f32 v[130:131], v[130:131], s[68:69] op_sel_hi:[1,0]
	s_nop 0
	v_fma_f32 v0, -v131, v131, v130
	v_add_f32_e32 v0, 0x3727c5ac, v0
	v_rsq_f32_e32 v130, v0
	v_add_u32_e32 v0, v229, v159
	v_lshl_add_u64 v[132:133], v[0:1], 2, s[18:19]
	v_mov_b32_e32 v159, s52
	v_mul_f32_e32 v131, v131, v130
	ds_write_b64 v209, v[130:131] offset:1280
	global_load_dwordx2 v[132:133], v[132:133], off
	v_mov_b32_e32 v160, v131
	s_waitcnt vmcnt(0) lgkmcnt(0)
	v_mov_b32_e32 v0, v132
	s_nop 1
	v_permlane16_swap_b32_e32 v132, v0
	v_add_f32_e32 v163, v132, v0
	v_mov_b32_e32 v0, v133
	s_nop 1
	v_permlane16_swap_b32_e32 v133, v0
	v_add_f32_e32 v162, v133, v0
	v_mov_b32_e32 v165, v163
	v_mov_b32_e32 v164, v162
	s_nop 0
	v_permlane32_swap_b32_e32 v163, v165
	v_permlane32_swap_b32_e32 v162, v164
	v_pk_add_f32 v[132:133], v[162:163], v[164:165]
	s_nop 0
	v_pk_mul_f32 v[132:133], v[132:133], s[68:69] op_sel_hi:[1,0]
	s_nop 0
	v_fma_f32 v0, -v133, v133, v132
	v_add_f32_e32 v0, 0x3727c5ac, v0
	v_rsq_f32_e32 v132, v0
	v_mov_b32_e32 v0, s47
	v_mul_f32_e32 v133, v133, v132
	ds_write_b64 v209, v[132:133] offset:1408
	s_waitcnt lgkmcnt(0)
	ds_write_b32 v0, v159
	v_mov_b32_e32 v0, v133

; #define PG8_LAS __attribute__((address_space(3)))
; __device__ __forceinline__ unsigned cvt_pk_bf16(float lo, float hi) { unsigned r; asm volatile("v_cvt_pk_bf16_f32 %0, %1, %2" : "=v"(r) : "v"(lo), "v"(hi)); return r; }
;     __device__ __forceinline__ void operator()(const f32x4 (&acc)[2][2][4][2], const Unit& u, int wr, int wc, int fr, int fq, PG8_LAS unsigned char* ldsb) const {
;     ...
;                 for (int n = 0; n < 2; ++n) { const u32x4 cw = *(const PG8_LAS u32x4*)(CV + col0 + bj * HALF + 4 * n);
; #pragma unroll
;                     for (int i = 0; i < 4; ++i) { c1v[bj][n][i] = __uint_as_float(cw[i] << 16); c2v[bj][n][i] = __uint_as_float(cw[i] & 0xffff0000u); } }
;         }
; #pragma unroll
;         for (int ai = 0; ai < 2; ++ai)
; #pragma unroll
;             for (int m = 0; m < 4; ++m) {
;                 bf16_t* rowp = O + (size_t)(row0 + ai * HALF + m * 16) * ldc + col0;
;                 const float rs = rsv[ai][m], ms = msv[ai][m];
; #pragma unroll
;                 for (int bj = 0; bj < 2; ++bj) { const f32x4 v0 = acc[ai][bj][m][0] * rs - c1v[bj][0] * ms + c2v[bj][0], v1 = acc[ai][bj][m][1] * rs - c1v[bj][1] * ms + c2v[bj][1];
;                     u32x4 w; w.x = cvt_pk_bf16(v0[0], v0[1]); w.y = cvt_pk_bf16(v0[2], v0[3]); w.z = cvt_pk_bf16(v1[0], v1[1]); w.w = cvt_pk_bf16(v1[2], v1[3]);
;                     *(u32x4*)(rowp + bj * HALF) = w; }
.LBB0_524:
	v_lshl_or_b32 v202, s53, 8, v230
	v_lshl_add_u32 v131, v202, 2, 0
	v_add_u32_e32 v131, 0x20000, v131
	ds_read_b128 v[162:165], v131
	ds_read_b128 v[166:169], v131 offset:16
	v_ashrrev_i32_e32 v159, 31, v158
	v_ashrrev_i32_e32 v203, 31, v202
	v_lshlrev_b64 v[216:217], 11, v[158:159]
	s_waitcnt lgkmcnt(0)
	v_lshlrev_b32_e32 v200, 16, v164
	v_and_b32_e32 v184, 0xffff0000, v164
	v_lshlrev_b32_e32 v201, 16, v165
	v_and_b32_e32 v185, 0xffff0000, v165
	v_lshlrev_b32_e32 v182, 16, v166
	v_and_b32_e32 v176, 0xffff0000, v166
	v_lshlrev_b32_e32 v183, 16, v167
	v_and_b32_e32 v177, 0xffff0000, v167
	ds_read_b128 v[164:167], v131 offset:512
	ds_read_b128 v[232:235], v131 offset:528
	v_lshlrev_b32_e32 v196, 16, v162
	v_and_b32_e32 v180, 0xffff0000, v162
	v_lshlrev_b32_e32 v197, 16, v163
	v_and_b32_e32 v181, 0xffff0000, v163
	v_lshlrev_b32_e32 v198, 16, v168
	v_and_b32_e32 v194, 0xffff0000, v168
	v_lshlrev_b32_e32 v199, 16, v169
	v_and_b32_e32 v195, 0xffff0000, v169
	s_waitcnt lgkmcnt(0)
	v_lshlrev_b32_e32 v168, 16, v232
	v_and_b32_e32 v162, 0xffff0000, v232
	v_lshlrev_b32_e32 v169, 16, v233
	v_and_b32_e32 v163, 0xffff0000, v233
	v_lshl_add_u64 v[232:233], s[16:17], 0, v[216:217]
	v_lshlrev_b64 v[216:217], 1, v[202:203]
	v_lshlrev_b32_e32 v178, 16, v166
	v_and_b32_e32 v170, 0xffff0000, v166
	v_lshlrev_b32_e32 v179, 16, v167
	v_and_b32_e32 v171, 0xffff0000, v167
	v_lshlrev_b32_e32 v174, 16, v234
	v_and_b32_e32 v166, 0xffff0000, v234
	v_lshlrev_b32_e32 v175, 16, v235
	v_and_b32_e32 v167, 0xffff0000, v235
	v_lshl_add_u64 v[202:203], v[232:233], 0, v[216:217]
	v_pk_mul_f32 v[232:233], v[214:215], v[200:201] op_sel_hi:[0,1]
	v_pk_mul_f32 v[234:235], v[214:215], v[196:197] op_sel_hi:[0,1]
	v_pk_fma_f32 v[126:127], v[126:127], v[142:143], v[234:235] op_sel_hi:[1,0,1] neg_lo:[0,0,1] neg_hi:[0,0,1]
	v_pk_fma_f32 v[128:129], v[128:129], v[142:143], v[232:233] op_sel_hi:[1,0,1] neg_lo:[0,0,1] neg_hi:[0,0,1]
	v_pk_mul_f32 v[232:233], v[214:215], v[198:199] op_sel_hi:[0,1]
	v_pk_mul_f32 v[234:235], v[214:215], v[182:183] op_sel_hi:[0,1]
	v_pk_fma_f32 v[122:123], v[122:123], v[142:143], v[234:235] op_sel_hi:[1,0,1] neg_lo:[0,0,1] neg_hi:[0,0,1]
	v_pk_fma_f32 v[124:125], v[124:125], v[142:143], v[232:233] op_sel_hi:[1,0,1] neg_lo:[0,0,1] neg_hi:[0,0,1]
	v_lshlrev_b32_e32 v172, 16, v164
	v_pk_add_f32 v[232:233], v[124:125], v[194:195]
	v_pk_add_f32 v[124:125], v[122:123], v[176:177]
	v_lshlrev_b32_e32 v173, 16, v165
	v_pk_add_f32 v[128:129], v[128:129], v[184:185]
	v_pk_add_f32 v[126:127], v[126:127], v[180:181]
	v_and_b32_e32 v164, 0xffff0000, v164
	v_cvt_pk_bf16_f32 v122, v126, v127
	v_cvt_pk_bf16_f32 v123, v128, v129
	v_cvt_pk_bf16_f32 v124, v124, v125
	v_cvt_pk_bf16_f32 v125, v232, v233
	global_store_dwordx4 v[202:203], v[122:125], off
	v_and_b32_e32 v165, 0xffff0000, v165
	s_mov_b64 s[26:27], 0x48000
	v_pk_mul_f32 v[122:123], v[214:215], v[178:179] op_sel_hi:[0,1]
	v_pk_mul_f32 v[124:125], v[214:215], v[172:173] op_sel_hi:[0,1]
	v_pk_fma_f32 v[118:119], v[118:119], v[142:143], v[124:125] op_sel_hi:[1,0,1] neg_lo:[0,0,1] neg_hi:[0,0,1]
	v_pk_fma_f32 v[120:121], v[120:121], v[142:143], v[122:123] op_sel_hi:[1,0,1] neg_lo:[0,0,1] neg_hi:[0,0,1]
	v_pk_mul_f32 v[122:123], v[214:215], v[174:175] op_sel_hi:[0,1]
	v_pk_mul_f32 v[124:125], v[214:215], v[168:169] op_sel_hi:[0,1]
	v_pk_fma_f32 v[114:115], v[114:115], v[142:143], v[124:125] op_sel_hi:[1,0,1] neg_lo:[0,0,1] neg_hi:[0,0,1]
	v_pk_fma_f32 v[116:117], v[116:117], v[142:143], v[122:123] op_sel_hi:[1,0,1] neg_lo:[0,0,1] neg_hi:[0,0,1]
	v_pk_add_f32 v[120:121], v[120:121], v[170:171]
	v_pk_add_f32 v[122:123], v[116:117], v[166:167]
	v_pk_add_f32 v[116:117], v[114:115], v[162:163]
	v_pk_add_f32 v[118:119], v[118:119], v[164:165]
	s_nop 0
	v_cvt_pk_bf16_f32 v114, v118, v119
	v_cvt_pk_bf16_f32 v115, v120, v121
	v_cvt_pk_bf16_f32 v116, v116, v117
	v_cvt_pk_bf16_f32 v117, v122, v123
	global_store_dwordx4 v[202:203], v[114:117], off offset:256
	v_pk_mul_f32 v[118:119], v[212:213], v[196:197] op_sel_hi:[0,1]
	v_pk_fma_f32 v[110:111], v[110:111], v[144:145], v[118:119] op_sel_hi:[1,0,1] neg_lo:[0,0,1] neg_hi:[0,0,1]
	v_or_b32_e32 v114, 16, v158
	v_pk_mul_f32 v[116:117], v[212:213], v[200:201] op_sel_hi:[0,1]
	v_ashrrev_i32_e32 v115, 31, v114
	v_pk_fma_f32 v[112:113], v[112:113], v[144:145], v[116:117] op_sel_hi:[1,0,1] neg_lo:[0,0,1] neg_hi:[0,0,1]
	v_pk_mul_f32 v[116:117], v[212:213], v[198:199] op_sel_hi:[0,1]
	v_pk_mul_f32 v[118:119], v[212:213], v[182:183] op_sel_hi:[0,1]
	v_lshlrev_b64 v[114:115], 11, v[114:115]
	v_pk_fma_f32 v[106:107], v[106:107], v[144:145], v[118:119] op_sel_hi:[1,0,1] neg_lo:[0,0,1] neg_hi:[0,0,1]
	v_pk_fma_f32 v[108:109], v[108:109], v[144:145], v[116:117] op_sel_hi:[1,0,1] neg_lo:[0,0,1] neg_hi:[0,0,1]
	v_lshl_add_u64 v[114:115], s[16:17], 0, v[114:115]
	v_pk_add_f32 v[116:117], v[108:109], v[194:195]
	v_pk_add_f32 v[108:109], v[106:107], v[176:177]
	v_lshl_add_u64 v[114:115], v[114:115], 0, v[216:217]
	v_pk_add_f32 v[112:113], v[112:113], v[184:185]
	v_pk_add_f32 v[110:111], v[110:111], v[180:181]
	s_nop 0
	v_cvt_pk_bf16_f32 v106, v110, v111
	v_cvt_pk_bf16_f32 v107, v112, v113
	v_cvt_pk_bf16_f32 v108, v108, v109
	v_cvt_pk_bf16_f32 v109, v116, v117
	global_store_dwordx4 v[114:115], v[106:109], off
	s_nop 1
	v_pk_mul_f32 v[106:107], v[212:213], v[178:179] op_sel_hi:[0,1]
	v_pk_mul_f32 v[108:109], v[212:213], v[172:173] op_sel_hi:[0,1]
	v_pk_fma_f32 v[102:103], v[102:103], v[144:145], v[108:109] op_sel_hi:[1,0,1] neg_lo:[0,0,1] neg_hi:[0,0,1]
	v_pk_fma_f32 v[104:105], v[104:105], v[144:145], v[106:107] op_sel_hi:[1,0,1] neg_lo:[0,0,1] neg_hi:[0,0,1]
	v_pk_mul_f32 v[106:107], v[212:213], v[174:175] op_sel_hi:[0,1]
; __device__ __forceinline__ unsigned cvt_pk_bf16(float lo, float hi) { unsigned r; asm volatile("v_cvt_pk_bf16_f32 %0, %1, %2" : "=v"(r) : "v"(lo), "v"(hi)); return r; }
;     __device__ __forceinline__ void operator()(const f32x4 (&acc)[2][2][4][2], const Unit& u, int wr, int wc, int fr, int fq, PG8_LAS unsigned char* ldsb) const {
;     ...
;         for (int ai = 0; ai < 2; ++ai)
; #pragma unroll
;             for (int m = 0; m < 4; ++m) {
;                 bf16_t* rowp = O + (size_t)(row0 + ai * HALF + m * 16) * ldc + col0;
;                 const float rs = rsv[ai][m], ms = msv[ai][m];
; #pragma unroll
;                 for (int bj = 0; bj < 2; ++bj) { const f32x4 v0 = acc[ai][bj][m][0] * rs - c1v[bj][0] * ms + c2v[bj][0], v1 = acc[ai][bj][m][1] * rs - c1v[bj][1] * ms + c2v[bj][1];
;                     u32x4 w; w.x = cvt_pk_bf16(v0[0], v0[1]); w.y = cvt_pk_bf16(v0[2], v0[3]); w.z = cvt_pk_bf16(v1[0], v1[1]); w.w = cvt_pk_bf16(v1[2], v1[3]);
;                     *(u32x4*)(rowp + bj * HALF) = w; }
	v_pk_mul_f32 v[108:109], v[212:213], v[168:169] op_sel_hi:[0,1]
	v_pk_fma_f32 v[98:99], v[98:99], v[144:145], v[108:109] op_sel_hi:[1,0,1] neg_lo:[0,0,1] neg_hi:[0,0,1]
	v_pk_fma_f32 v[100:101], v[100:101], v[144:145], v[106:107] op_sel_hi:[1,0,1] neg_lo:[0,0,1] neg_hi:[0,0,1]
	v_pk_add_f32 v[104:105], v[104:105], v[170:171]
	v_pk_add_f32 v[106:107], v[100:101], v[166:167]
	v_pk_add_f32 v[100:101], v[98:99], v[162:163]
	v_pk_add_f32 v[102:103], v[102:103], v[164:165]
	s_nop 0
	v_cvt_pk_bf16_f32 v98, v102, v103
	v_cvt_pk_bf16_f32 v99, v104, v105
	v_cvt_pk_bf16_f32 v100, v100, v101
	v_cvt_pk_bf16_f32 v101, v106, v107
	global_store_dwordx4 v[114:115], v[98:101], off offset:256
	v_pk_mul_f32 v[102:103], v[210:211], v[196:197] op_sel_hi:[0,1]
	v_pk_fma_f32 v[94:95], v[94:95], v[138:139], v[102:103] op_sel_hi:[1,0,1] neg_lo:[0,0,1] neg_hi:[0,0,1]
	v_or_b32_e32 v98, 32, v158
	v_pk_mul_f32 v[100:101], v[210:211], v[200:201] op_sel_hi:[0,1]
	v_ashrrev_i32_e32 v99, 31, v98
	v_pk_fma_f32 v[96:97], v[96:97], v[138:139], v[100:101] op_sel_hi:[1,0,1] neg_lo:[0,0,1] neg_hi:[0,0,1]
	v_pk_mul_f32 v[100:101], v[210:211], v[198:199] op_sel_hi:[0,1]
	v_pk_mul_f32 v[102:103], v[210:211], v[182:183] op_sel_hi:[0,1]
	v_lshlrev_b64 v[98:99], 11, v[98:99]
	v_pk_fma_f32 v[90:91], v[90:91], v[138:139], v[102:103] op_sel_hi:[1,0,1] neg_lo:[0,0,1] neg_hi:[0,0,1]
	v_pk_fma_f32 v[92:93], v[92:93], v[138:139], v[100:101] op_sel_hi:[1,0,1] neg_lo:[0,0,1] neg_hi:[0,0,1]
	v_lshl_add_u64 v[98:99], s[16:17], 0, v[98:99]
	v_pk_add_f32 v[100:101], v[92:93], v[194:195]
	v_pk_add_f32 v[92:93], v[90:91], v[176:177]
	v_lshl_add_u64 v[98:99], v[98:99], 0, v[216:217]
	v_pk_add_f32 v[96:97], v[96:97], v[184:185]
	v_pk_add_f32 v[94:95], v[94:95], v[180:181]
	s_nop 0
	v_cvt_pk_bf16_f32 v90, v94, v95
	v_cvt_pk_bf16_f32 v91, v96, v97
	v_cvt_pk_bf16_f32 v92, v92, v93
	v_cvt_pk_bf16_f32 v93, v100, v101
	global_store_dwordx4 v[98:99], v[90:93], off
	s_nop 1
	v_pk_mul_f32 v[90:91], v[210:211], v[178:179] op_sel_hi:[0,1]
	v_pk_mul_f32 v[92:93], v[210:211], v[172:173] op_sel_hi:[0,1]
	v_pk_fma_f32 v[86:87], v[86:87], v[138:139], v[92:93] op_sel_hi:[1,0,1] neg_lo:[0,0,1] neg_hi:[0,0,1]
	v_pk_fma_f32 v[88:89], v[88:89], v[138:139], v[90:91] op_sel_hi:[1,0,1] neg_lo:[0,0,1] neg_hi:[0,0,1]
	v_pk_mul_f32 v[90:91], v[210:211], v[174:175] op_sel_hi:[0,1]
	v_pk_mul_f32 v[92:93], v[210:211], v[168:169] op_sel_hi:[0,1]
	v_pk_fma_f32 v[82:83], v[82:83], v[138:139], v[92:93] op_sel_hi:[1,0,1] neg_lo:[0,0,1] neg_hi:[0,0,1]
	v_pk_fma_f32 v[84:85], v[84:85], v[138:139], v[90:91] op_sel_hi:[1,0,1] neg_lo:[0,0,1] neg_hi:[0,0,1]
	v_pk_add_f32 v[88:89], v[88:89], v[170:171]
	v_pk_add_f32 v[90:91], v[84:85], v[166:167]
	v_pk_add_f32 v[84:85], v[82:83], v[162:163]
	v_pk_add_f32 v[86:87], v[86:87], v[164:165]
	s_nop 0
	v_cvt_pk_bf16_f32 v82, v86, v87
	v_cvt_pk_bf16_f32 v83, v88, v89
	v_cvt_pk_bf16_f32 v84, v84, v85
	v_cvt_pk_bf16_f32 v85, v90, v91
	global_store_dwordx4 v[98:99], v[82:85], off offset:256
	v_pk_mul_f32 v[86:87], v[208:209], v[196:197] op_sel_hi:[0,1]
	v_pk_fma_f32 v[78:79], v[78:79], v[140:141], v[86:87] op_sel_hi:[1,0,1] neg_lo:[0,0,1] neg_hi:[0,0,1]
	v_or_b32_e32 v82, 48, v158
	v_pk_mul_f32 v[84:85], v[208:209], v[200:201] op_sel_hi:[0,1]
	v_ashrrev_i32_e32 v83, 31, v82
	v_pk_fma_f32 v[80:81], v[80:81], v[140:141], v[84:85] op_sel_hi:[1,0,1] neg_lo:[0,0,1] neg_hi:[0,0,1]
	v_pk_mul_f32 v[84:85], v[208:209], v[198:199] op_sel_hi:[0,1]
	v_pk_mul_f32 v[86:87], v[208:209], v[182:183] op_sel_hi:[0,1]
	v_lshlrev_b64 v[82:83], 11, v[82:83]
	v_pk_fma_f32 v[74:75], v[74:75], v[140:141], v[86:87] op_sel_hi:[1,0,1] neg_lo:[0,0,1] neg_hi:[0,0,1]
	v_pk_fma_f32 v[76:77], v[76:77], v[140:141], v[84:85] op_sel_hi:[1,0,1] neg_lo:[0,0,1] neg_hi:[0,0,1]
	v_lshl_add_u64 v[82:83], s[16:17], 0, v[82:83]
	v_pk_add_f32 v[84:85], v[76:77], v[194:195]
	v_pk_add_f32 v[76:77], v[74:75], v[176:177]
	v_lshl_add_u64 v[82:83], v[82:83], 0, v[216:217]
	v_pk_add_f32 v[80:81], v[80:81], v[184:185]
	v_pk_add_f32 v[78:79], v[78:79], v[180:181]
	s_nop 0
	v_cvt_pk_bf16_f32 v74, v78, v79
	v_cvt_pk_bf16_f32 v75, v80, v81
	v_cvt_pk_bf16_f32 v76, v76, v77
	v_cvt_pk_bf16_f32 v77, v84, v85
	global_store_dwordx4 v[82:83], v[74:77], off
	s_nop 1
	v_pk_mul_f32 v[74:75], v[208:209], v[178:179] op_sel_hi:[0,1]
	v_pk_mul_f32 v[76:77], v[208:209], v[172:173] op_sel_hi:[0,1]
	v_pk_fma_f32 v[70:71], v[70:71], v[140:141], v[76:77] op_sel_hi:[1,0,1] neg_lo:[0,0,1] neg_hi:[0,0,1]
	v_pk_fma_f32 v[72:73], v[72:73], v[140:141], v[74:75] op_sel_hi:[1,0,1] neg_lo:[0,0,1] neg_hi:[0,0,1]
	v_pk_mul_f32 v[74:75], v[208:209], v[174:175] op_sel_hi:[0,1]
	v_pk_mul_f32 v[76:77], v[208:209], v[168:169] op_sel_hi:[0,1]
	v_pk_fma_f32 v[66:67], v[66:67], v[140:141], v[76:77] op_sel_hi:[1,0,1] neg_lo:[0,0,1] neg_hi:[0,0,1]
	v_pk_fma_f32 v[68:69], v[68:69], v[140:141], v[74:75] op_sel_hi:[1,0,1] neg_lo:[0,0,1] neg_hi:[0,0,1]
	v_pk_add_f32 v[72:73], v[72:73], v[170:171]
	v_pk_add_f32 v[74:75], v[68:69], v[166:167]
	v_pk_add_f32 v[68:69], v[66:67], v[162:163]
	v_pk_add_f32 v[70:71], v[70:71], v[164:165]
	s_nop 0
	v_cvt_pk_bf16_f32 v66, v70, v71
	v_cvt_pk_bf16_f32 v67, v72, v73
	v_cvt_pk_bf16_f32 v68, v68, v69
	v_cvt_pk_bf16_f32 v69, v74, v75
	global_store_dwordx4 v[82:83], v[66:69], off offset:256
	v_pk_mul_f32 v[70:71], v[206:207], v[196:197] op_sel_hi:[0,1]
	v_pk_fma_f32 v[62:63], v[62:63], v[134:135], v[70:71] op_sel_hi:[1,0,1] neg_lo:[0,0,1] neg_hi:[0,0,1]
	v_pk_mul_f32 v[68:69], v[206:207], v[200:201] op_sel_hi:[0,1]
	v_pk_fma_f32 v[64:65], v[64:65], v[134:135], v[68:69] op_sel_hi:[1,0,1] neg_lo:[0,0,1] neg_hi:[0,0,1]
	v_pk_mul_f32 v[68:69], v[206:207], v[198:199] op_sel_hi:[0,1]
; __device__ __forceinline__ unsigned cvt_pk_bf16(float lo, float hi) { unsigned r; asm volatile("v_cvt_pk_bf16_f32 %0, %1, %2" : "=v"(r) : "v"(lo), "v"(hi)); return r; }
;     __device__ __forceinline__ void operator()(const f32x4 (&acc)[2][2][4][2], const Unit& u, int wr, int wc, int fr, int fq, PG8_LAS unsigned char* ldsb) const {
;     ...
;         for (int ai = 0; ai < 2; ++ai)
; #pragma unroll
;             for (int m = 0; m < 4; ++m) {
;                 bf16_t* rowp = O + (size_t)(row0 + ai * HALF + m * 16) * ldc + col0;
;                 const float rs = rsv[ai][m], ms = msv[ai][m];
; #pragma unroll
;                 for (int bj = 0; bj < 2; ++bj) { const f32x4 v0 = acc[ai][bj][m][0] * rs - c1v[bj][0] * ms + c2v[bj][0], v1 = acc[ai][bj][m][1] * rs - c1v[bj][1] * ms + c2v[bj][1];
;                     u32x4 w; w.x = cvt_pk_bf16(v0[0], v0[1]); w.y = cvt_pk_bf16(v0[2], v0[3]); w.z = cvt_pk_bf16(v1[0], v1[1]); w.w = cvt_pk_bf16(v1[2], v1[3]);
;                     *(u32x4*)(rowp + bj * HALF) = w; }
	v_pk_mul_f32 v[70:71], v[206:207], v[182:183] op_sel_hi:[0,1]
	v_pk_add_f32 v[62:63], v[62:63], v[180:181]
	v_pk_fma_f32 v[58:59], v[58:59], v[134:135], v[70:71] op_sel_hi:[1,0,1] neg_lo:[0,0,1] neg_hi:[0,0,1]
	v_pk_fma_f32 v[60:61], v[60:61], v[134:135], v[68:69] op_sel_hi:[1,0,1] neg_lo:[0,0,1] neg_hi:[0,0,1]
	v_pk_add_f32 v[64:65], v[64:65], v[184:185]
	v_pk_add_f32 v[68:69], v[60:61], v[194:195]
	v_pk_add_f32 v[60:61], v[58:59], v[176:177]
	v_cvt_pk_bf16_f32 v58, v62, v63
	v_add_co_u32_e32 v62, vcc, s35, v202
	v_cvt_pk_bf16_f32 v59, v64, v65
	v_cvt_pk_bf16_f32 v60, v60, v61
	v_cvt_pk_bf16_f32 v61, v68, v69
	v_lshl_add_u64 v[66:67], v[202:203], 0, s[72:73]
	s_nop 0
	v_addc_co_u32_e32 v63, vcc, 0, v203, vcc
	global_store_dwordx4 v[62:63], v[58:61], off
	s_nop 1
	v_pk_mul_f32 v[58:59], v[206:207], v[178:179] op_sel_hi:[0,1]
	v_pk_mul_f32 v[60:61], v[206:207], v[172:173] op_sel_hi:[0,1]
	v_pk_fma_f32 v[54:55], v[54:55], v[134:135], v[60:61] op_sel_hi:[1,0,1] neg_lo:[0,0,1] neg_hi:[0,0,1]
	v_pk_fma_f32 v[56:57], v[56:57], v[134:135], v[58:59] op_sel_hi:[1,0,1] neg_lo:[0,0,1] neg_hi:[0,0,1]
	v_pk_mul_f32 v[58:59], v[206:207], v[174:175] op_sel_hi:[0,1]
	v_pk_mul_f32 v[60:61], v[206:207], v[168:169] op_sel_hi:[0,1]
	v_pk_fma_f32 v[50:51], v[50:51], v[134:135], v[60:61] op_sel_hi:[1,0,1] neg_lo:[0,0,1] neg_hi:[0,0,1]
	v_pk_fma_f32 v[52:53], v[52:53], v[134:135], v[58:59] op_sel_hi:[1,0,1] neg_lo:[0,0,1] neg_hi:[0,0,1]
	v_pk_add_f32 v[56:57], v[56:57], v[170:171]
	v_pk_add_f32 v[58:59], v[52:53], v[166:167]
	v_pk_add_f32 v[52:53], v[50:51], v[162:163]
	v_pk_add_f32 v[54:55], v[54:55], v[164:165]
	s_nop 0
	v_cvt_pk_bf16_f32 v50, v54, v55
	v_cvt_pk_bf16_f32 v51, v56, v57
	v_cvt_pk_bf16_f32 v52, v52, v53
	v_cvt_pk_bf16_f32 v53, v58, v59
	global_store_dwordx4 v[66:67], v[50:53], off offset:256
	v_pk_mul_f32 v[54:55], v[204:205], v[196:197] op_sel_hi:[0,1]
	v_pk_fma_f32 v[46:47], v[46:47], v[136:137], v[54:55] op_sel_hi:[1,0,1] neg_lo:[0,0,1] neg_hi:[0,0,1]
	v_pk_mul_f32 v[52:53], v[204:205], v[200:201] op_sel_hi:[0,1]
	v_pk_fma_f32 v[48:49], v[48:49], v[136:137], v[52:53] op_sel_hi:[1,0,1] neg_lo:[0,0,1] neg_hi:[0,0,1]
	v_pk_mul_f32 v[52:53], v[204:205], v[198:199] op_sel_hi:[0,1]
	v_pk_mul_f32 v[54:55], v[204:205], v[182:183] op_sel_hi:[0,1]
	v_lshl_add_u64 v[50:51], v[202:203], 0, s[26:27]
	v_pk_add_f32 v[46:47], v[46:47], v[180:181]
	v_pk_fma_f32 v[42:43], v[42:43], v[136:137], v[54:55] op_sel_hi:[1,0,1] neg_lo:[0,0,1] neg_hi:[0,0,1]
	v_pk_fma_f32 v[44:45], v[44:45], v[136:137], v[52:53] op_sel_hi:[1,0,1] neg_lo:[0,0,1] neg_hi:[0,0,1]
	s_mov_b32 s26, 0x48000
	v_pk_add_f32 v[52:53], v[44:45], v[194:195]
	v_pk_add_f32 v[44:45], v[42:43], v[176:177]
	v_cvt_pk_bf16_f32 v42, v46, v47
	v_add_co_u32_e32 v46, vcc, s26, v202
	v_pk_add_f32 v[48:49], v[48:49], v[184:185]
	s_nop 0
	v_addc_co_u32_e32 v47, vcc, 0, v203, vcc
	v_cvt_pk_bf16_f32 v43, v48, v49
	v_cvt_pk_bf16_f32 v44, v44, v45
	v_cvt_pk_bf16_f32 v45, v52, v53
	global_store_dwordx4 v[46:47], v[42:45], off
	s_mov_b64 s[26:27], 0x50000
	s_nop 0
	v_pk_mul_f32 v[42:43], v[204:205], v[178:179] op_sel_hi:[0,1]
	v_pk_mul_f32 v[44:45], v[204:205], v[172:173] op_sel_hi:[0,1]
	v_pk_fma_f32 v[38:39], v[38:39], v[136:137], v[44:45] op_sel_hi:[1,0,1] neg_lo:[0,0,1] neg_hi:[0,0,1]
	v_pk_fma_f32 v[40:41], v[40:41], v[136:137], v[42:43] op_sel_hi:[1,0,1] neg_lo:[0,0,1] neg_hi:[0,0,1]
	v_pk_mul_f32 v[42:43], v[204:205], v[174:175] op_sel_hi:[0,1]
	v_pk_mul_f32 v[44:45], v[204:205], v[168:169] op_sel_hi:[0,1]
	v_pk_fma_f32 v[34:35], v[34:35], v[136:137], v[44:45] op_sel_hi:[1,0,1] neg_lo:[0,0,1] neg_hi:[0,0,1]
	v_pk_fma_f32 v[36:37], v[36:37], v[136:137], v[42:43] op_sel_hi:[1,0,1] neg_lo:[0,0,1] neg_hi:[0,0,1]
	v_pk_add_f32 v[40:41], v[40:41], v[170:171]
	v_pk_add_f32 v[42:43], v[36:37], v[166:167]
	v_pk_add_f32 v[36:37], v[34:35], v[162:163]
	v_pk_add_f32 v[38:39], v[38:39], v[164:165]
	s_nop 0
	v_cvt_pk_bf16_f32 v34, v38, v39
	v_cvt_pk_bf16_f32 v35, v40, v41
	v_cvt_pk_bf16_f32 v36, v36, v37
	v_cvt_pk_bf16_f32 v37, v42, v43
	global_store_dwordx4 v[50:51], v[34:37], off offset:256
	v_pk_mul_f32 v[38:39], v[160:161], v[196:197] op_sel_hi:[0,1]
	v_pk_fma_f32 v[30:31], v[30:31], v[130:131], v[38:39] op_sel_hi:[1,0,1] neg_lo:[0,0,1] neg_hi:[0,0,1]
	v_pk_mul_f32 v[36:37], v[160:161], v[200:201] op_sel_hi:[0,1]
; __device__ __forceinline__ unsigned cvt_pk_bf16(float lo, float hi) { unsigned r; asm volatile("v_cvt_pk_bf16_f32 %0, %1, %2" : "=v"(r) : "v"(lo), "v"(hi)); return r; }
; #define PG8_BAR __builtin_amdgcn_s_barrier()
;     __device__ __forceinline__ void operator()(const f32x4 (&acc)[2][2][4][2], const Unit& u, int wr, int wc, int fr, int fq, PG8_LAS unsigned char* ldsb) const {
;     ...
;         for (int ai = 0; ai < 2; ++ai)
; #pragma unroll
;             for (int m = 0; m < 4; ++m) {
;                 bf16_t* rowp = O + (size_t)(row0 + ai * HALF + m * 16) * ldc + col0;
;                 const float rs = rsv[ai][m], ms = msv[ai][m];
; #pragma unroll
;                 for (int bj = 0; bj < 2; ++bj) { const f32x4 v0 = acc[ai][bj][m][0] * rs - c1v[bj][0] * ms + c2v[bj][0], v1 = acc[ai][bj][m][1] * rs - c1v[bj][1] * ms + c2v[bj][1];
;                     u32x4 w; w.x = cvt_pk_bf16(v0[0], v0[1]); w.y = cvt_pk_bf16(v0[2], v0[3]); w.z = cvt_pk_bf16(v1[0], v1[1]); w.w = cvt_pk_bf16(v1[2], v1[3]);
;                     *(u32x4*)(rowp + bj * HALF) = w; }
; template <class Epi, class Sched, bool ALIGN_EPI = false, bool SP2 = false>
; __device__ __forceinline__ void gemm_phase(PG8_LAS unsigned char* lds, const Gemm g, const Sched& S, const Epi& E) {
;     ...
;         if (!has_next) break;
; #pragma unroll
;         for (int a = 0; a < 2; ++a)
; #pragma unroll
;             for (int b = 0; b < 2; ++b)
; #pragma unroll
;                 for (int m = 0; m < 4; ++m)
; #pragma unroll
;                     for (int n = 0; n < 2; ++n) acc[a][b][m][n] = (f32x4){0.f, 0.f, 0.f, 0.f};
;         cur = nxt; cA = nA; cB = nB; ++ui;
;         if constexpr (ALIGN_EPI) { if (wr == 1) PG8_BAR; }
	v_pk_fma_f32 v[32:33], v[32:33], v[130:131], v[36:37] op_sel_hi:[1,0,1] neg_lo:[0,0,1] neg_hi:[0,0,1]
	v_pk_mul_f32 v[36:37], v[160:161], v[198:199] op_sel_hi:[0,1]
	v_pk_mul_f32 v[38:39], v[160:161], v[182:183] op_sel_hi:[0,1]
	v_lshl_add_u64 v[34:35], v[202:203], 0, s[26:27]
	v_pk_add_f32 v[30:31], v[30:31], v[180:181]
	v_pk_fma_f32 v[26:27], v[26:27], v[130:131], v[38:39] op_sel_hi:[1,0,1] neg_lo:[0,0,1] neg_hi:[0,0,1]
	v_pk_fma_f32 v[28:29], v[28:29], v[130:131], v[36:37] op_sel_hi:[1,0,1] neg_lo:[0,0,1] neg_hi:[0,0,1]
	s_mov_b32 s26, 0x50000
	v_pk_add_f32 v[36:37], v[28:29], v[194:195]
	v_pk_add_f32 v[28:29], v[26:27], v[176:177]
	v_cvt_pk_bf16_f32 v26, v30, v31
	v_add_co_u32_e32 v30, vcc, s26, v202
	v_pk_add_f32 v[32:33], v[32:33], v[184:185]
	s_nop 0
	v_addc_co_u32_e32 v31, vcc, 0, v203, vcc
	v_cvt_pk_bf16_f32 v27, v32, v33
	v_cvt_pk_bf16_f32 v28, v28, v29
	v_cvt_pk_bf16_f32 v29, v36, v37
	global_store_dwordx4 v[30:31], v[26:29], off
	s_mov_b64 s[26:27], 0x58000
	s_nop 0
	v_pk_mul_f32 v[26:27], v[160:161], v[178:179] op_sel_hi:[0,1]
	v_pk_mul_f32 v[28:29], v[160:161], v[172:173] op_sel_hi:[0,1]
	v_pk_fma_f32 v[22:23], v[22:23], v[130:131], v[28:29] op_sel_hi:[1,0,1] neg_lo:[0,0,1] neg_hi:[0,0,1]
	v_pk_fma_f32 v[24:25], v[24:25], v[130:131], v[26:27] op_sel_hi:[1,0,1] neg_lo:[0,0,1] neg_hi:[0,0,1]
	v_pk_mul_f32 v[26:27], v[160:161], v[174:175] op_sel_hi:[0,1]
	v_pk_mul_f32 v[28:29], v[160:161], v[168:169] op_sel_hi:[0,1]
	v_pk_fma_f32 v[18:19], v[18:19], v[130:131], v[28:29] op_sel_hi:[1,0,1] neg_lo:[0,0,1] neg_hi:[0,0,1]
	v_pk_fma_f32 v[20:21], v[20:21], v[130:131], v[26:27] op_sel_hi:[1,0,1] neg_lo:[0,0,1] neg_hi:[0,0,1]
	v_pk_add_f32 v[24:25], v[24:25], v[170:171]
	v_pk_add_f32 v[26:27], v[20:21], v[166:167]
	v_pk_add_f32 v[20:21], v[18:19], v[162:163]
	v_pk_add_f32 v[22:23], v[22:23], v[164:165]
	s_nop 0
	v_cvt_pk_bf16_f32 v18, v22, v23
	v_cvt_pk_bf16_f32 v19, v24, v25
	v_cvt_pk_bf16_f32 v20, v20, v21
	v_cvt_pk_bf16_f32 v21, v26, v27
	global_store_dwordx4 v[34:35], v[18:21], off offset:256
	v_pk_mul_f32 v[22:23], v[0:1], v[196:197] op_sel_hi:[0,1]
	v_pk_fma_f32 v[14:15], v[14:15], v[132:133], v[22:23] op_sel_hi:[1,0,1] neg_lo:[0,0,1] neg_hi:[0,0,1]
	v_pk_mul_f32 v[20:21], v[0:1], v[200:201] op_sel_hi:[0,1]
	v_pk_fma_f32 v[16:17], v[16:17], v[132:133], v[20:21] op_sel_hi:[1,0,1] neg_lo:[0,0,1] neg_hi:[0,0,1]
	v_pk_mul_f32 v[20:21], v[0:1], v[198:199] op_sel_hi:[0,1]
	v_pk_mul_f32 v[22:23], v[0:1], v[182:183] op_sel_hi:[0,1]
	v_lshl_add_u64 v[18:19], v[202:203], 0, s[26:27]
	v_pk_add_f32 v[14:15], v[14:15], v[180:181]
	v_pk_fma_f32 v[10:11], v[10:11], v[132:133], v[22:23] op_sel_hi:[1,0,1] neg_lo:[0,0,1] neg_hi:[0,0,1]
	v_pk_fma_f32 v[12:13], v[12:13], v[132:133], v[20:21] op_sel_hi:[1,0,1] neg_lo:[0,0,1] neg_hi:[0,0,1]
	s_mov_b32 s26, 0x58000
	v_pk_add_f32 v[20:21], v[12:13], v[194:195]
	v_pk_add_f32 v[12:13], v[10:11], v[176:177]
	v_cvt_pk_bf16_f32 v10, v14, v15
	v_add_co_u32_e32 v14, vcc, s26, v202
	v_pk_add_f32 v[16:17], v[16:17], v[184:185]
	s_nop 0
	v_addc_co_u32_e32 v15, vcc, 0, v203, vcc
	v_cvt_pk_bf16_f32 v11, v16, v17
	v_cvt_pk_bf16_f32 v12, v12, v13
	v_cvt_pk_bf16_f32 v13, v20, v21
	global_store_dwordx4 v[14:15], v[10:13], off
	s_and_b64 vcc, exec, s[2:3]
	s_mov_b64 s[2:3], -1
	v_pk_mul_f32 v[10:11], v[0:1], v[178:179] op_sel_hi:[0,1]
	v_pk_mul_f32 v[12:13], v[0:1], v[172:173] op_sel_hi:[0,1]
	v_pk_fma_f32 v[6:7], v[6:7], v[132:133], v[12:13] op_sel_hi:[1,0,1] neg_lo:[0,0,1] neg_hi:[0,0,1]
	v_pk_fma_f32 v[8:9], v[8:9], v[132:133], v[10:11] op_sel_hi:[1,0,1] neg_lo:[0,0,1] neg_hi:[0,0,1]
	v_pk_mul_f32 v[10:11], v[0:1], v[174:175] op_sel_hi:[0,1]
	v_pk_mul_f32 v[12:13], v[0:1], v[168:169] op_sel_hi:[0,1]
	v_pk_fma_f32 v[2:3], v[2:3], v[132:133], v[12:13] op_sel_hi:[1,0,1] neg_lo:[0,0,1] neg_hi:[0,0,1]
	v_pk_fma_f32 v[4:5], v[4:5], v[132:133], v[10:11] op_sel_hi:[1,0,1] neg_lo:[0,0,1] neg_hi:[0,0,1]
	v_pk_add_f32 v[8:9], v[8:9], v[170:171]
	v_pk_add_f32 v[10:11], v[4:5], v[166:167]
	v_pk_add_f32 v[4:5], v[2:3], v[162:163]
	v_pk_add_f32 v[6:7], v[6:7], v[164:165]
	s_nop 0
	v_cvt_pk_bf16_f32 v2, v6, v7
	v_cvt_pk_bf16_f32 v3, v8, v9
	v_cvt_pk_bf16_f32 v4, v4, v5
	v_cvt_pk_bf16_f32 v5, v10, v11
	global_store_dwordx4 v[18:19], v[2:5], off offset:256
	s_cbranch_vccnz .LBB0_504
	s_andn2_b64 vcc, exec, s[14:15]
	s_cbranch_vccnz .LBB0_503
	s_barrier
	s_branch .LBB0_503

; #define PG8_STAGE(bufoff, gbase, voff) do { _Pragma("unroll") for (int _i = 0; _i < 2; ++_i) \
;         __builtin_amdgcn_global_load_lds((const unsigned*)((const char*)(gbase) + (voff)[_i]), (PG8_LAS unsigned*)(lds + (bufoff) + ldsw + _i * 8192), 16, 0, 0); } while (0)
; #define PG8_LDA(dst, b, h) do { _Pragma("unroll") for (int m = 0; m < 4; ++m) _Pragma("unroll") for (int k = 0; k < 2; ++k) dst[m][k] = *(const PG8_LAS bf16x8*)(lds + PG8_SA(b, h) + aoff + m * 2048 + k * 1024); } while (0)
; #define PG8_LDB(dst, b, h) do { _Pragma("unroll") for (int n = 0; n < 2; ++n) _Pragma("unroll") for (int k = 0; k < 2; ++k) dst[n][k] = *(const PG8_LAS bf16x8*)(lds + PG8_SB(b, h) + boff + n * 2048 + k * 1024); } while (0)
; #define PG8_MMA(ai, bj, At, Bt) do { __builtin_amdgcn_s_setprio(1); _Pragma("unroll") for (int m = 0; m < 4; ++m) _Pragma("unroll") for (int n = 0; n < 2; ++n) _Pragma("unroll") for (int k = 0; k < 2; ++k) \
;         acc[ai][bj][m][n] = __builtin_amdgcn_mfma_f32_16x16x32_bf16(Bt[n][k], At[m][k], acc[ai][bj][m][n], 0, 0, 0); __builtin_amdgcn_s_setprio(0); } while (0)
; #define PG8_WAIT_V(n) asm volatile("s_waitcnt vmcnt(" #n ")" ::: "memory")
; #define PG8_WAIT_L(n) asm volatile("s_waitcnt lgkmcnt(" #n ")" ::: "memory")
; template <class Epi, class Sched, bool ALIGN_EPI = false, bool SP2 = false>
; __device__ __forceinline__ void gemm_phase(PG8_LAS unsigned char* lds, const Gemm g, const Sched& S, const Epi& E) {
;     ...
;             const bool last = (t == nt - 2);
;             const char* a1 = cA + (size_t)(t + 1) * kstep;
;             const char* a2 = last ? nA : cA + (size_t)(t + 2) * kstep; const char* b2 = last ? nB : cB + (size_t)(t + 2) * kstep;
;             const char* a3 = a2 + kstep; const char* b3 = b2 + kstep;
;             if (last && has_next) S.a_ready(nxt);
;             if constexpr (SP2) {
;             PG8_LDB(B0, 0, 0); PG8_LDB(B1, 0, 1); PG8_SCHED; PG8_LDA(At, 0, 0); PG8_STAGE(PG8_SA(1, 1), a1 + hstep, voffA);
;             PG8_WAIT_V(8); PG8_WAIT_L(0); PG8_BAR; PG8_MMA(0, 0, At, B0); PG8_MMA(0, 1, At, B1); PG8_BAR; PG8_SCHED;
;             PG8_LDA(At, 0, 1); PG8_STAGE(PG8_SB(0, 0), b2, voffB); PG8_STAGE(PG8_SB(0, 1), b2 + hstep, voffB); PG8_STAGE(PG8_SA(0, 0), a2, voffA);
;             PG8_WAIT_V(8); PG8_WAIT_L(0); PG8_BAR; PG8_MMA(1, 0, At, B0); PG8_MMA(1, 1, At, B1); PG8_BAR; PG8_SCHED;
.LBB0_550:
	s_add_i32 s53, s26, 2
	s_add_u32 s56, s24, 0x80
	s_addc_u32 s27, s25, 0
	s_add_i32 s61, 0, 0x10000
	s_cmp_eq_u32 s45, s26
	s_cselect_b32 s27, s5, s27
	s_cselect_b32 s26, s4, s56
	s_cselect_b32 s63, s23, s52
	s_cselect_b32 s62, s22, s51
	s_add_i32 s56, 0, 0x14000
	v_add_u32_e32 v156, s61, v149
	v_add_u32_e32 v172, s56, v149
	ds_read_b128 v[140:143], v156
	ds_read_b128 v[144:147], v156 offset:1024
	ds_read_b128 v[152:155], v156 offset:2048
	ds_read_b128 v[156:159], v156 offset:3072
	ds_read_b128 v[160:163], v172
	ds_read_b128 v[164:167], v172 offset:1024
	ds_read_b128 v[168:171], v172 offset:2048
	ds_read_b128 v[172:175], v172 offset:3072
	v_lshl_add_u64 v[184:185], s[24:25], 0, v[138:139]
	s_add_i32 m0, s31, 0xc000
	ds_read_b128 v[176:179], v151
	ds_read_b128 v[180:183], v151 offset:1024
	ds_read_b128 v[194:197], v151 offset:2048
	ds_read_b128 v[198:201], v151 offset:3072
	ds_read_b128 v[202:205], v151 offset:4096
	ds_read_b128 v[206:209], v151 offset:5120
	ds_read_b128 v[226:229], v151 offset:6144
	ds_read_b128 v[230:233], v151 offset:7168
	global_load_lds_dwordx4 v[184:185], off
	v_lshl_add_u64 v[184:185], s[24:25], 0, v[136:137]
	s_add_i32 m0, s31, 0xe000
	s_nop 0
	global_load_lds_dwordx4 v[184:185], off
	s_waitcnt vmcnt(8)
	s_waitcnt lgkmcnt(0)
	s_barrier
	s_setprio 1
	v_mfma_f32_16x16x32_bf16 v[126:129], v[140:143], v[176:179], v[126:129]
	v_mfma_f32_16x16x32_bf16 v[122:125], v[152:155], v[176:179], v[122:125]
	v_mfma_f32_16x16x32_bf16 v[118:121], v[140:143], v[194:197], v[118:121]
	v_mfma_f32_16x16x32_bf16 v[114:117], v[152:155], v[194:197], v[114:117]
	v_mfma_f32_16x16x32_bf16 v[106:109], v[140:143], v[202:205], v[106:109]
	v_mfma_f32_16x16x32_bf16 v[98:101], v[152:155], v[202:205], v[98:101]
	v_mfma_f32_16x16x32_bf16 v[90:93], v[140:143], v[226:229], v[90:93]
	v_mfma_f32_16x16x32_bf16 v[82:85], v[152:155], v[226:229], v[82:85]
	v_mfma_f32_16x16x32_bf16 v[126:129], v[144:147], v[180:183], v[126:129]
	v_mfma_f32_16x16x32_bf16 v[122:125], v[156:159], v[180:183], v[122:125]
	v_mfma_f32_16x16x32_bf16 v[118:121], v[144:147], v[198:201], v[118:121]
	v_mfma_f32_16x16x32_bf16 v[114:117], v[156:159], v[198:201], v[114:117]
	v_mfma_f32_16x16x32_bf16 v[106:109], v[144:147], v[206:209], v[106:109]
	v_mfma_f32_16x16x32_bf16 v[98:101], v[156:159], v[206:209], v[98:101]
	v_mfma_f32_16x16x32_bf16 v[90:93], v[144:147], v[230:233], v[90:93]
	v_mfma_f32_16x16x32_bf16 v[82:85], v[156:159], v[230:233], v[82:85]
	s_setprio 0
	s_setprio 1
	v_mfma_f32_16x16x32_bf16 v[110:113], v[160:163], v[176:179], v[110:113]
	v_mfma_f32_16x16x32_bf16 v[102:105], v[168:171], v[176:179], v[102:105]
	v_mfma_f32_16x16x32_bf16 v[94:97], v[160:163], v[194:197], v[94:97]
	v_mfma_f32_16x16x32_bf16 v[86:89], v[168:171], v[194:197], v[86:89]
	v_mfma_f32_16x16x32_bf16 v[78:81], v[160:163], v[202:205], v[78:81]
	v_mfma_f32_16x16x32_bf16 v[74:77], v[168:171], v[202:205], v[74:77]
	v_mfma_f32_16x16x32_bf16 v[70:73], v[160:163], v[226:229], v[70:73]
	v_mfma_f32_16x16x32_bf16 v[66:69], v[168:171], v[226:229], v[66:69]
	v_mfma_f32_16x16x32_bf16 v[110:113], v[164:167], v[180:183], v[110:113]
	v_mfma_f32_16x16x32_bf16 v[102:105], v[172:175], v[180:183], v[102:105]
	v_mfma_f32_16x16x32_bf16 v[94:97], v[164:167], v[198:201], v[94:97]
	v_mfma_f32_16x16x32_bf16 v[86:89], v[172:175], v[198:201], v[86:89]
	v_mfma_f32_16x16x32_bf16 v[78:81], v[164:167], v[206:209], v[78:81]
	v_mfma_f32_16x16x32_bf16 v[74:77], v[172:175], v[206:209], v[74:77]
	v_mfma_f32_16x16x32_bf16 v[70:73], v[164:167], v[230:233], v[70:73]
	v_mfma_f32_16x16x32_bf16 v[66:69], v[172:175], v[230:233], v[66:69]
	s_setprio 0
	s_barrier
	s_add_i32 s61, s61, s30
	v_lshl_add_u64 v[184:185], s[62:63], 0, v[0:1]
	s_mov_b32 m0, s61
	ds_read_b128 v[176:179], v151 offset:16384
	ds_read_b128 v[180:183], v151 offset:17408
	ds_read_b128 v[194:197], v151 offset:18432
	ds_read_b128 v[198:201], v151 offset:19456
	ds_read_b128 v[202:205], v151 offset:20480
	ds_read_b128 v[206:209], v151 offset:21504
	ds_read_b128 v[226:229], v151 offset:22528
	ds_read_b128 v[230:233], v151 offset:23552
	global_load_lds_dwordx4 v[184:185], off
	s_add_i32 m0, s61, 0x2000
	v_lshl_add_u64 v[212:213], s[62:63], 0, v[134:135]
	s_add_u32 s62, s62, s10
	s_addc_u32 s63, s63, s11
	s_add_i32 s56, s56, s30
	global_load_lds_dwordx4 v[212:213], off
	v_lshl_add_u64 v[214:215], s[62:63], 0, v[0:1]
	s_mov_b32 m0, s56
	v_lshl_add_u64 v[216:217], s[62:63], 0, v[134:135]
	global_load_lds_dwordx4 v[214:215], off
	s_add_i32 m0, s56, 0x2000
	v_lshl_add_u64 v[234:235], s[26:27], 0, v[130:131]
	global_load_lds_dwordx4 v[216:217], off
	s_mov_b32 m0, s31
	v_lshl_add_u64 v[236:237], s[26:27], 0, v[132:133]
	global_load_lds_dwordx4 v[234:235], off
	s_mov_b32 m0, s33
	s_nop 0
	global_load_lds_dwordx4 v[236:237], off
	s_waitcnt vmcnt(8)
	s_waitcnt lgkmcnt(0)
	s_barrier
; #define PG8_STAGE(bufoff, gbase, voff) do { _Pragma("unroll") for (int _i = 0; _i < 2; ++_i) \
;         __builtin_amdgcn_global_load_lds((const unsigned*)((const char*)(gbase) + (voff)[_i]), (PG8_LAS unsigned*)(lds + (bufoff) + ldsw + _i * 8192), 16, 0, 0); } while (0)
; #define PG8_LDA(dst, b, h) do { _Pragma("unroll") for (int m = 0; m < 4; ++m) _Pragma("unroll") for (int k = 0; k < 2; ++k) dst[m][k] = *(const PG8_LAS bf16x8*)(lds + PG8_SA(b, h) + aoff + m * 2048 + k * 1024); } while (0)
; #define PG8_LDB(dst, b, h) do { _Pragma("unroll") for (int n = 0; n < 2; ++n) _Pragma("unroll") for (int k = 0; k < 2; ++k) dst[n][k] = *(const PG8_LAS bf16x8*)(lds + PG8_SB(b, h) + boff + n * 2048 + k * 1024); } while (0)
; #define PG8_MMA(ai, bj, At, Bt) do { __builtin_amdgcn_s_setprio(1); _Pragma("unroll") for (int m = 0; m < 4; ++m) _Pragma("unroll") for (int n = 0; n < 2; ++n) _Pragma("unroll") for (int k = 0; k < 2; ++k) \
;         acc[ai][bj][m][n] = __builtin_amdgcn_mfma_f32_16x16x32_bf16(Bt[n][k], At[m][k], acc[ai][bj][m][n], 0, 0, 0); __builtin_amdgcn_s_setprio(0); } while (0)
; #define PG8_WAIT_V(n) asm volatile("s_waitcnt vmcnt(" #n ")" ::: "memory")
; #define PG8_WAIT_L(n) asm volatile("s_waitcnt lgkmcnt(" #n ")" ::: "memory")
; #define PG8_BAR __builtin_amdgcn_s_barrier()
; #define PG8_SCHED __builtin_amdgcn_sched_barrier(0)
; template <class Epi, class Sched, bool ALIGN_EPI = false, bool SP2 = false>
; __device__ __forceinline__ void gemm_phase(PG8_LAS unsigned char* lds, const Gemm g, const Sched& S, const Epi& E) {
;     ...
;             PG8_WAIT_V(8); PG8_WAIT_L(0); PG8_BAR; PG8_MMA(1, 0, At, B0); PG8_MMA(1, 1, At, B1); PG8_BAR; PG8_SCHED;
;             PG8_LDB(B0, 1, 0); PG8_LDB(B1, 1, 1); PG8_SCHED; PG8_LDA(At, 1, 0); PG8_STAGE(PG8_SA(0, 1), a2 + hstep, voffA);
;             PG8_WAIT_V(8); PG8_WAIT_L(0); PG8_BAR; PG8_MMA(0, 0, At, B0); PG8_MMA(0, 1, At, B1); PG8_BAR; PG8_SCHED;
	s_setprio 1
	v_mfma_f32_16x16x32_bf16 v[62:65], v[140:143], v[176:179], v[62:65]
	v_mfma_f32_16x16x32_bf16 v[58:61], v[152:155], v[176:179], v[58:61]
	v_mfma_f32_16x16x32_bf16 v[54:57], v[140:143], v[194:197], v[54:57]
	v_mfma_f32_16x16x32_bf16 v[50:53], v[152:155], v[194:197], v[50:53]
	v_mfma_f32_16x16x32_bf16 v[42:45], v[140:143], v[202:205], v[42:45]
	v_mfma_f32_16x16x32_bf16 v[34:37], v[152:155], v[202:205], v[34:37]
	v_mfma_f32_16x16x32_bf16 v[26:29], v[140:143], v[226:229], v[26:29]
	v_mfma_f32_16x16x32_bf16 v[18:21], v[152:155], v[226:229], v[18:21]
	v_mfma_f32_16x16x32_bf16 v[62:65], v[144:147], v[180:183], v[62:65]
	v_mfma_f32_16x16x32_bf16 v[58:61], v[156:159], v[180:183], v[58:61]
	v_mfma_f32_16x16x32_bf16 v[54:57], v[144:147], v[198:201], v[54:57]
	v_mfma_f32_16x16x32_bf16 v[50:53], v[156:159], v[198:201], v[50:53]
	v_mfma_f32_16x16x32_bf16 v[42:45], v[144:147], v[206:209], v[42:45]
	v_mfma_f32_16x16x32_bf16 v[34:37], v[156:159], v[206:209], v[34:37]
	v_mfma_f32_16x16x32_bf16 v[26:29], v[144:147], v[230:233], v[26:29]
	v_mfma_f32_16x16x32_bf16 v[18:21], v[156:159], v[230:233], v[18:21]
	s_setprio 0
	s_setprio 1
	v_mfma_f32_16x16x32_bf16 v[46:49], v[160:163], v[176:179], v[46:49]
	v_mfma_f32_16x16x32_bf16 v[38:41], v[168:171], v[176:179], v[38:41]
	v_mfma_f32_16x16x32_bf16 v[30:33], v[160:163], v[194:197], v[30:33]
	v_mfma_f32_16x16x32_bf16 v[22:25], v[168:171], v[194:197], v[22:25]
	v_mfma_f32_16x16x32_bf16 v[14:17], v[160:163], v[202:205], v[14:17]
	v_mfma_f32_16x16x32_bf16 v[10:13], v[168:171], v[202:205], v[10:13]
	v_mfma_f32_16x16x32_bf16 v[6:9], v[160:163], v[226:229], v[6:9]
	v_mfma_f32_16x16x32_bf16 v[2:5], v[168:171], v[226:229], v[2:5]
	v_mfma_f32_16x16x32_bf16 v[46:49], v[164:167], v[180:183], v[46:49]
	v_mfma_f32_16x16x32_bf16 v[38:41], v[172:175], v[180:183], v[38:41]
	v_mfma_f32_16x16x32_bf16 v[30:33], v[164:167], v[198:201], v[30:33]
	v_mfma_f32_16x16x32_bf16 v[22:25], v[172:175], v[198:201], v[22:25]
	v_mfma_f32_16x16x32_bf16 v[14:17], v[164:167], v[206:209], v[14:17]
	v_mfma_f32_16x16x32_bf16 v[10:13], v[172:175], v[206:209], v[10:13]
	v_mfma_f32_16x16x32_bf16 v[6:9], v[164:167], v[230:233], v[6:9]
	v_mfma_f32_16x16x32_bf16 v[2:5], v[172:175], v[230:233], v[2:5]
	s_setprio 0
	s_barrier
	s_add_i32 s56, 0, 0x18000
	s_add_i32 s61, 0, 0x1c000
	v_add_u32_e32 v156, s56, v149
	v_add_u32_e32 v172, s61, v149
	ds_read_b128 v[140:143], v156
	ds_read_b128 v[144:147], v156 offset:1024
	ds_read_b128 v[152:155], v156 offset:2048
	ds_read_b128 v[156:159], v156 offset:3072
	ds_read_b128 v[160:163], v172
	ds_read_b128 v[164:167], v172 offset:1024
	ds_read_b128 v[168:171], v172 offset:2048
	ds_read_b128 v[172:175], v172 offset:3072
	s_add_u32 s26, s26, s10
	s_addc_u32 s27, s27, s11
	s_mov_b32 m0, s34
	v_lshl_add_u64 v[238:239], s[26:27], 0, v[130:131]
	ds_read_b128 v[176:179], v151 offset:32768
	ds_read_b128 v[180:183], v151 offset:33792
	ds_read_b128 v[194:197], v151 offset:34816
	ds_read_b128 v[198:201], v151 offset:35840
	ds_read_b128 v[202:205], v151 offset:36864
	ds_read_b128 v[206:209], v151 offset:37888
	ds_read_b128 v[226:229], v151 offset:38912
	ds_read_b128 v[230:233], v151 offset:39936
	global_load_lds_dwordx4 v[238:239], off
	v_lshl_add_u64 v[238:239], s[26:27], 0, v[132:133]
	s_mov_b32 m0, s40
	s_nop 0
	global_load_lds_dwordx4 v[238:239], off
	s_waitcnt vmcnt(8)
	s_waitcnt lgkmcnt(0)
	s_barrier
	s_setprio 1
	v_mfma_f32_16x16x32_bf16 v[126:129], v[140:143], v[176:179], v[126:129]
	v_mfma_f32_16x16x32_bf16 v[122:125], v[152:155], v[176:179], v[122:125]
	v_mfma_f32_16x16x32_bf16 v[118:121], v[140:143], v[194:197], v[118:121]
	v_mfma_f32_16x16x32_bf16 v[114:117], v[152:155], v[194:197], v[114:117]
	v_mfma_f32_16x16x32_bf16 v[106:109], v[140:143], v[202:205], v[106:109]
	v_mfma_f32_16x16x32_bf16 v[98:101], v[152:155], v[202:205], v[98:101]
	v_mfma_f32_16x16x32_bf16 v[90:93], v[140:143], v[226:229], v[90:93]
	v_mfma_f32_16x16x32_bf16 v[82:85], v[152:155], v[226:229], v[82:85]
	v_mfma_f32_16x16x32_bf16 v[126:129], v[144:147], v[180:183], v[126:129]
	v_mfma_f32_16x16x32_bf16 v[122:125], v[156:159], v[180:183], v[122:125]
	v_mfma_f32_16x16x32_bf16 v[118:121], v[144:147], v[198:201], v[118:121]
	v_mfma_f32_16x16x32_bf16 v[114:117], v[156:159], v[198:201], v[114:117]
	v_mfma_f32_16x16x32_bf16 v[106:109], v[144:147], v[206:209], v[106:109]
	v_mfma_f32_16x16x32_bf16 v[98:101], v[156:159], v[206:209], v[98:101]
	v_mfma_f32_16x16x32_bf16 v[90:93], v[144:147], v[230:233], v[90:93]
	v_mfma_f32_16x16x32_bf16 v[82:85], v[156:159], v[230:233], v[82:85]
	s_setprio 0
	s_setprio 1
	v_mfma_f32_16x16x32_bf16 v[110:113], v[160:163], v[176:179], v[110:113]
	v_mfma_f32_16x16x32_bf16 v[102:105], v[168:171], v[176:179], v[102:105]
	v_mfma_f32_16x16x32_bf16 v[94:97], v[160:163], v[194:197], v[94:97]
	v_mfma_f32_16x16x32_bf16 v[86:89], v[168:171], v[194:197], v[86:89]
	v_mfma_f32_16x16x32_bf16 v[78:81], v[160:163], v[202:205], v[78:81]
	v_mfma_f32_16x16x32_bf16 v[74:77], v[168:171], v[202:205], v[74:77]
	v_mfma_f32_16x16x32_bf16 v[70:73], v[160:163], v[226:229], v[70:73]
	v_mfma_f32_16x16x32_bf16 v[66:69], v[168:171], v[226:229], v[66:69]
	v_mfma_f32_16x16x32_bf16 v[110:113], v[164:167], v[180:183], v[110:113]
	v_mfma_f32_16x16x32_bf16 v[102:105], v[172:175], v[180:183], v[102:105]
	v_mfma_f32_16x16x32_bf16 v[94:97], v[164:167], v[198:201], v[94:97]
	v_mfma_f32_16x16x32_bf16 v[86:89], v[172:175], v[198:201], v[86:89]
	v_mfma_f32_16x16x32_bf16 v[78:81], v[164:167], v[206:209], v[78:81]
	v_mfma_f32_16x16x32_bf16 v[74:77], v[172:175], v[206:209], v[74:77]
	v_mfma_f32_16x16x32_bf16 v[70:73], v[164:167], v[230:233], v[70:73]
	v_mfma_f32_16x16x32_bf16 v[66:69], v[172:175], v[230:233], v[66:69]
	s_setprio 0
	s_barrier
; #define PG8_STAGE(bufoff, gbase, voff) do { _Pragma("unroll") for (int _i = 0; _i < 2; ++_i) \
;         __builtin_amdgcn_global_load_lds((const unsigned*)((const char*)(gbase) + (voff)[_i]), (PG8_LAS unsigned*)(lds + (bufoff) + ldsw + _i * 8192), 16, 0, 0); } while (0)
; #define PG8_LDA(dst, b, h) do { _Pragma("unroll") for (int m = 0; m < 4; ++m) _Pragma("unroll") for (int k = 0; k < 2; ++k) dst[m][k] = *(const PG8_LAS bf16x8*)(lds + PG8_SA(b, h) + aoff + m * 2048 + k * 1024); } while (0)
; #define PG8_MMA(ai, bj, At, Bt) do { __builtin_amdgcn_s_setprio(1); _Pragma("unroll") for (int m = 0; m < 4; ++m) _Pragma("unroll") for (int n = 0; n < 2; ++n) _Pragma("unroll") for (int k = 0; k < 2; ++k) \
;         acc[ai][bj][m][n] = __builtin_amdgcn_mfma_f32_16x16x32_bf16(Bt[n][k], At[m][k], acc[ai][bj][m][n], 0, 0, 0); __builtin_amdgcn_s_setprio(0); } while (0)
; #define PG8_WAIT_V(n) asm volatile("s_waitcnt vmcnt(" #n ")" ::: "memory")
; #define PG8_WAIT_L(n) asm volatile("s_waitcnt lgkmcnt(" #n ")" ::: "memory")
; #define PG8_BAR __builtin_amdgcn_s_barrier()
; #define PG8_SCHED __builtin_amdgcn_sched_barrier(0)
;     __device__ __forceinline__ void operator()(const f32x4 (&acc)[2][2][4][2], const Unit& u, int wr, int wc, int fr, int fq, PG8_LAS unsigned char* ldsb) const {
;     ...
;                 for (int bj = 0; bj < 2; ++bj) { const f32x4 v0 = acc[ai][bj][m][0] * rs - c1v[bj][0] * ms + c2v[bj][0], v1 = acc[ai][bj][m][1] * rs - c1v[bj][1] * ms + c2v[bj][1];
; template <class Epi, class Sched, bool ALIGN_EPI = false, bool SP2 = false>
; __device__ __forceinline__ void gemm_phase(PG8_LAS unsigned char* lds, const Gemm g, const Sched& S, const Epi& E) {
;     ...
;             PG8_WAIT_V(8); PG8_WAIT_L(0); PG8_BAR; PG8_MMA(0, 0, At, B0); PG8_MMA(0, 1, At, B1); PG8_BAR; PG8_SCHED;
;             PG8_LDA(At, 1, 1); PG8_STAGE(PG8_SB(1, 0), b3, voffB); PG8_STAGE(PG8_SB(1, 1), b3 + hstep, voffB); PG8_STAGE(PG8_SA(1, 0), a3, voffA);
;             PG8_WAIT_V(8); PG8_WAIT_L(0); PG8_BAR; PG8_MMA(1, 0, At, B0); PG8_MMA(1, 1, At, B1); PG8_BAR; PG8_SCHED;
	s_add_i32 s26, s56, s30
	v_lshl_add_u64 v[184:185], v[184:185], 0, s[38:39]
	s_mov_b32 m0, s26
	ds_read_b128 v[176:179], v151 offset:49152
	ds_read_b128 v[180:183], v151 offset:50176
	ds_read_b128 v[194:197], v151 offset:51200
	ds_read_b128 v[198:201], v151 offset:52224
	ds_read_b128 v[202:205], v151 offset:53248
	ds_read_b128 v[206:209], v151 offset:54272
	ds_read_b128 v[226:229], v151 offset:55296
	ds_read_b128 v[230:233], v151 offset:56320
	global_load_lds_dwordx4 v[184:185], off
	v_lshl_add_u64 v[184:185], v[212:213], 0, s[38:39]
	s_add_i32 m0, s26, 0x2000
	s_add_i32 s26, s61, s30
	global_load_lds_dwordx4 v[184:185], off
	v_lshl_add_u64 v[184:185], v[214:215], 0, s[38:39]
	s_mov_b32 m0, s26
	s_nop 0
	global_load_lds_dwordx4 v[184:185], off
	v_lshl_add_u64 v[184:185], v[216:217], 0, s[38:39]
	s_add_i32 m0, s26, 0x2000
	s_nop 0
	global_load_lds_dwordx4 v[184:185], off
	v_lshl_add_u64 v[184:185], v[234:235], 0, s[38:39]
	s_mov_b32 m0, s43
	s_nop 0
	global_load_lds_dwordx4 v[184:185], off
	v_lshl_add_u64 v[184:185], v[236:237], 0, s[38:39]
	s_mov_b32 m0, s44
	s_nop 0
	global_load_lds_dwordx4 v[184:185], off
	s_waitcnt vmcnt(8)
	s_waitcnt lgkmcnt(0)
	s_barrier
	s_setprio 1
	v_mfma_f32_16x16x32_bf16 v[62:65], v[140:143], v[176:179], v[62:65]
	v_mfma_f32_16x16x32_bf16 v[58:61], v[152:155], v[176:179], v[58:61]
	v_mfma_f32_16x16x32_bf16 v[54:57], v[140:143], v[194:197], v[54:57]
	v_mfma_f32_16x16x32_bf16 v[50:53], v[152:155], v[194:197], v[50:53]
	v_mfma_f32_16x16x32_bf16 v[42:45], v[140:143], v[202:205], v[42:45]
	v_mfma_f32_16x16x32_bf16 v[34:37], v[152:155], v[202:205], v[34:37]
	v_mfma_f32_16x16x32_bf16 v[26:29], v[140:143], v[226:229], v[26:29]
	v_mfma_f32_16x16x32_bf16 v[18:21], v[152:155], v[226:229], v[18:21]
	v_mfma_f32_16x16x32_bf16 v[62:65], v[144:147], v[180:183], v[62:65]
	v_mfma_f32_16x16x32_bf16 v[58:61], v[156:159], v[180:183], v[58:61]
	v_mfma_f32_16x16x32_bf16 v[54:57], v[144:147], v[198:201], v[54:57]
	v_mfma_f32_16x16x32_bf16 v[50:53], v[156:159], v[198:201], v[50:53]
	v_mfma_f32_16x16x32_bf16 v[42:45], v[144:147], v[206:209], v[42:45]
	v_mfma_f32_16x16x32_bf16 v[34:37], v[156:159], v[206:209], v[34:37]
	v_mfma_f32_16x16x32_bf16 v[26:29], v[144:147], v[230:233], v[26:29]
	v_mfma_f32_16x16x32_bf16 v[18:21], v[156:159], v[230:233], v[18:21]
	s_setprio 0
	s_setprio 1
	v_mfma_f32_16x16x32_bf16 v[46:49], v[160:163], v[176:179], v[46:49]
	v_mfma_f32_16x16x32_bf16 v[38:41], v[168:171], v[176:179], v[38:41]
	v_mfma_f32_16x16x32_bf16 v[30:33], v[160:163], v[194:197], v[30:33]
	v_mfma_f32_16x16x32_bf16 v[22:25], v[168:171], v[194:197], v[22:25]
	v_mfma_f32_16x16x32_bf16 v[14:17], v[160:163], v[202:205], v[14:17]
	v_mfma_f32_16x16x32_bf16 v[10:13], v[168:171], v[202:205], v[10:13]
	v_mfma_f32_16x16x32_bf16 v[6:9], v[160:163], v[226:229], v[6:9]
	v_mfma_f32_16x16x32_bf16 v[2:5], v[168:171], v[226:229], v[2:5]
	v_mfma_f32_16x16x32_bf16 v[46:49], v[164:167], v[180:183], v[46:49]
	v_mfma_f32_16x16x32_bf16 v[38:41], v[172:175], v[180:183], v[38:41]
	v_mfma_f32_16x16x32_bf16 v[30:33], v[164:167], v[198:201], v[30:33]
	v_mfma_f32_16x16x32_bf16 v[22:25], v[172:175], v[198:201], v[22:25]
	v_mfma_f32_16x16x32_bf16 v[14:17], v[164:167], v[206:209], v[14:17]
	v_mfma_f32_16x16x32_bf16 v[10:13], v[172:175], v[206:209], v[10:13]
	v_mfma_f32_16x16x32_bf16 v[6:9], v[164:167], v[230:233], v[6:9]
	v_mfma_f32_16x16x32_bf16 v[2:5], v[172:175], v[230:233], v[2:5]
	s_setprio 0
	s_barrier
	s_add_u32 s51, s51, 0x100
	s_addc_u32 s52, s52, 0
	s_add_u32 s24, s24, 0x100
	s_addc_u32 s25, s25, 0
	s_cmp_ge_i32 s53, s41
	s_mov_b32 s26, s53
	s_cbranch_scc0 .LBB0_550
	v_pk_add_f32 v[128:129], v[128:129], 0 op_sel_hi:[1,0]
	v_pk_add_f32 v[126:127], v[126:127], 0 op_sel_hi:[1,0]
	v_pk_add_f32 v[124:125], v[124:125], 0 op_sel_hi:[1,0]
	v_pk_add_f32 v[122:123], v[122:123], 0 op_sel_hi:[1,0]
	v_pk_add_f32 v[140:141], v[112:113], 0 op_sel_hi:[1,0]
	v_pk_add_f32 v[142:143], v[110:111], 0 op_sel_hi:[1,0]
	v_pk_add_f32 v[144:145], v[104:105], 0 op_sel_hi:[1,0]
	v_pk_add_f32 v[146:147], v[102:103], 0 op_sel_hi:[1,0]
	v_pk_add_f32 v[102:103], v[120:121], 0 op_sel_hi:[1,0]
	v_pk_add_f32 v[104:105], v[118:119], 0 op_sel_hi:[1,0]
	v_pk_add_f32 v[110:111], v[116:117], 0 op_sel_hi:[1,0]
	v_pk_add_f32 v[112:113], v[114:115], 0 op_sel_hi:[1,0]
	v_pk_add_f32 v[114:115], v[96:97], 0 op_sel_hi:[1,0]
	v_pk_add_f32 v[116:117], v[94:95], 0 op_sel_hi:[1,0]
	v_pk_add_f32 v[118:119], v[88:89], 0 op_sel_hi:[1,0]
	v_pk_add_f32 v[120:121], v[86:87], 0 op_sel_hi:[1,0]
	v_pk_add_f32 v[86:87], v[108:109], 0 op_sel_hi:[1,0]
	v_pk_add_f32 v[88:89], v[106:107], 0 op_sel_hi:[1,0]
	v_pk_add_f32 v[94:95], v[100:101], 0 op_sel_hi:[1,0]
	v_pk_add_f32 v[96:97], v[98:99], 0 op_sel_hi:[1,0]
	v_pk_add_f32 v[98:99], v[80:81], 0 op_sel_hi:[1,0]
	v_pk_add_f32 v[100:101], v[78:79], 0 op_sel_hi:[1,0]
	v_pk_add_f32 v[106:107], v[76:77], 0 op_sel_hi:[1,0]
	v_pk_add_f32 v[108:109], v[74:75], 0 op_sel_hi:[1,0]
	v_pk_add_f32 v[74:75], v[92:93], 0 op_sel_hi:[1,0]
	v_pk_add_f32 v[76:77], v[90:91], 0 op_sel_hi:[1,0]
	v_pk_add_f32 v[78:79], v[84:85], 0 op_sel_hi:[1,0]
	v_pk_add_f32 v[80:81], v[82:83], 0 op_sel_hi:[1,0]
	v_pk_add_f32 v[72:73], v[72:73], 0 op_sel_hi:[1,0]
	v_pk_add_f32 v[70:71], v[70:71], 0 op_sel_hi:[1,0]
	v_pk_add_f32 v[68:69], v[68:69], 0 op_sel_hi:[1,0]
	v_pk_add_f32 v[66:67], v[66:67], 0 op_sel_hi:[1,0]
	v_pk_add_f32 v[64:65], v[64:65], 0 op_sel_hi:[1,0]
	v_pk_add_f32 v[62:63], v[62:63], 0 op_sel_hi:[1,0]
	v_pk_add_f32 v[60:61], v[60:61], 0 op_sel_hi:[1,0]
	v_pk_add_f32 v[58:59], v[58:59], 0 op_sel_hi:[1,0]
	v_pk_add_f32 v[82:83], v[48:49], 0 op_sel_hi:[1,0]
	v_pk_add_f32 v[84:85], v[46:47], 0 op_sel_hi:[1,0]
	v_pk_add_f32 v[90:91], v[40:41], 0 op_sel_hi:[1,0]
	v_pk_add_f32 v[92:93], v[38:39], 0 op_sel_hi:[1,0]
	v_pk_add_f32 v[38:39], v[56:57], 0 op_sel_hi:[1,0]
	v_pk_add_f32 v[40:41], v[54:55], 0 op_sel_hi:[1,0]
	v_pk_add_f32 v[46:47], v[52:53], 0 op_sel_hi:[1,0]
	v_pk_add_f32 v[48:49], v[50:51], 0 op_sel_hi:[1,0]
	v_pk_add_f32 v[50:51], v[32:33], 0 op_sel_hi:[1,0]
	v_pk_add_f32 v[52:53], v[30:31], 0 op_sel_hi:[1,0]
	v_pk_add_f32 v[54:55], v[24:25], 0 op_sel_hi:[1,0]
	v_pk_add_f32 v[56:57], v[22:23], 0 op_sel_hi:[1,0]
	v_pk_add_f32 v[22:23], v[44:45], 0 op_sel_hi:[1,0]
	v_pk_add_f32 v[24:25], v[42:43], 0 op_sel_hi:[1,0]
	v_pk_add_f32 v[30:31], v[36:37], 0 op_sel_hi:[1,0]
	v_pk_add_f32 v[32:33], v[34:35], 0 op_sel_hi:[1,0]
	v_pk_add_f32 v[34:35], v[16:17], 0 op_sel_hi:[1,0]
	v_pk_add_f32 v[36:37], v[14:15], 0 op_sel_hi:[1,0]
	v_pk_add_f32 v[42:43], v[12:13], 0 op_sel_hi:[1,0]
	v_pk_add_f32 v[44:45], v[10:11], 0 op_sel_hi:[1,0]
	v_pk_add_f32 v[10:11], v[28:29], 0 op_sel_hi:[1,0]
	v_pk_add_f32 v[12:13], v[26:27], 0 op_sel_hi:[1,0]
	v_pk_add_f32 v[14:15], v[20:21], 0 op_sel_hi:[1,0]
	v_pk_add_f32 v[16:17], v[18:19], 0 op_sel_hi:[1,0]
	v_pk_add_f32 v[8:9], v[8:9], 0 op_sel_hi:[1,0]
	v_pk_add_f32 v[6:7], v[6:7], 0 op_sel_hi:[1,0]
	v_pk_add_f32 v[4:5], v[4:5], 0 op_sel_hi:[1,0]
	v_pk_add_f32 v[2:3], v[2:3], 0 op_sel_hi:[1,0]

; __device__ __forceinline__ unsigned cvt_pk_bf16(float lo, float hi) { unsigned r; asm volatile("v_cvt_pk_bf16_f32 %0, %1, %2" : "=v"(r) : "v"(lo), "v"(hi)); return r; }
;     __device__ __forceinline__ void operator()(const f32x4 (&acc)[2][2][4][2], const Unit& u, int wr, int wc, int fr, int fq, PG8_LAS unsigned char* ldsb) const {
;     ...
;         for (int ai = 0; ai < 2; ++ai)
; #pragma unroll
;             for (int m = 0; m < 4; ++m) {
;                 bf16_t* rowp = O + (size_t)(row0 + ai * HALF + m * 16) * ldc + col0;
;                 const float rs = rsv[ai][m], ms = msv[ai][m];
; #pragma unroll
;                 for (int bj = 0; bj < 2; ++bj) { const f32x4 v0 = acc[ai][bj][m][0] * rs - c1v[bj][0] * ms + c2v[bj][0], v1 = acc[ai][bj][m][1] * rs - c1v[bj][1] * ms + c2v[bj][1];
;                     u32x4 w; w.x = cvt_pk_bf16(v0[0], v0[1]); w.y = cvt_pk_bf16(v0[2], v0[3]); w.z = cvt_pk_bf16(v1[0], v1[1]); w.w = cvt_pk_bf16(v1[2], v1[3]);
;                     *(u32x4*)(rowp + bj * HALF) = w; }
.LBB0_554:
	v_lshl_add_u32 v26, s42, 8, v148
	v_lshl_or_b32 v18, s48, 8, v150
	v_ashrrev_i32_e32 v27, 31, v26
	v_ashrrev_i32_e32 v19, 31, v18
	v_lshlrev_b64 v[20:21], 12, v[26:27]
	v_lshl_add_u64 v[20:21], s[16:17], 0, v[20:21]
	v_lshlrev_b64 v[28:29], 1, v[18:19]
	v_lshl_add_u64 v[152:153], v[20:21], 0, v[28:29]
	v_cvt_pk_bf16_f32 v18, v126, v127
	v_cvt_pk_bf16_f32 v19, v128, v129
	v_cvt_pk_bf16_f32 v20, v122, v123
	v_cvt_pk_bf16_f32 v21, v124, v125
	global_store_dwordx4 v[152:153], v[18:21], off
	s_mov_b64 s[24:25], 0x80000
	s_nop 0
	v_cvt_pk_bf16_f32 v18, v142, v143
	v_cvt_pk_bf16_f32 v19, v140, v141
	v_cvt_pk_bf16_f32 v20, v146, v147
	v_cvt_pk_bf16_f32 v21, v144, v145
	global_store_dwordx4 v[152:153], v[18:21], off offset:256
	s_nop 1
	v_or_b32_e32 v18, 16, v26
	v_ashrrev_i32_e32 v19, 31, v18
	v_lshlrev_b64 v[18:19], 12, v[18:19]
	v_lshl_add_u64 v[18:19], s[16:17], 0, v[18:19]
	v_lshl_add_u64 v[122:123], v[18:19], 0, v[28:29]
	v_cvt_pk_bf16_f32 v18, v104, v105
	v_cvt_pk_bf16_f32 v19, v102, v103
	v_cvt_pk_bf16_f32 v20, v112, v113
	v_cvt_pk_bf16_f32 v21, v110, v111
	global_store_dwordx4 v[122:123], v[18:21], off
	s_nop 1
	v_cvt_pk_bf16_f32 v18, v116, v117
	v_cvt_pk_bf16_f32 v19, v114, v115
	v_cvt_pk_bf16_f32 v20, v120, v121
	v_cvt_pk_bf16_f32 v21, v118, v119
	global_store_dwordx4 v[122:123], v[18:21], off offset:256
	s_nop 1
	v_or_b32_e32 v18, 32, v26
	v_ashrrev_i32_e32 v19, 31, v18
	v_lshlrev_b64 v[18:19], 12, v[18:19]
	v_lshl_add_u64 v[18:19], s[16:17], 0, v[18:19]
	v_lshl_add_u64 v[102:103], v[18:19], 0, v[28:29]
	v_cvt_pk_bf16_f32 v18, v88, v89
	v_cvt_pk_bf16_f32 v19, v86, v87
	v_cvt_pk_bf16_f32 v20, v96, v97
	v_cvt_pk_bf16_f32 v21, v94, v95
	global_store_dwordx4 v[102:103], v[18:21], off
	s_nop 1
	v_cvt_pk_bf16_f32 v18, v100, v101
	v_cvt_pk_bf16_f32 v19, v98, v99
	v_cvt_pk_bf16_f32 v20, v108, v109
	v_cvt_pk_bf16_f32 v21, v106, v107
	global_store_dwordx4 v[102:103], v[18:21], off offset:256
	s_nop 1
	v_or_b32_e32 v18, 48, v26
	v_ashrrev_i32_e32 v19, 31, v18
	v_lshlrev_b64 v[18:19], 12, v[18:19]
	v_lshl_add_u64 v[18:19], s[16:17], 0, v[18:19]
	v_lshl_add_u64 v[26:27], v[18:19], 0, v[28:29]
	v_cvt_pk_bf16_f32 v18, v76, v77
	v_cvt_pk_bf16_f32 v19, v74, v75
	v_cvt_pk_bf16_f32 v20, v80, v81
	v_cvt_pk_bf16_f32 v21, v78, v79
	global_store_dwordx4 v[26:27], v[18:21], off
	s_nop 1
	v_cvt_pk_bf16_f32 v18, v70, v71
	v_cvt_pk_bf16_f32 v19, v72, v73
	v_cvt_pk_bf16_f32 v20, v66, v67
	v_cvt_pk_bf16_f32 v21, v68, v69
	global_store_dwordx4 v[26:27], v[18:21], off offset:256
	v_lshl_add_u64 v[26:27], v[152:153], 0, s[24:25]
	s_mov_b32 s24, 0x80000
	v_add_co_u32_e32 v28, vcc, s24, v152
	v_cvt_pk_bf16_f32 v18, v62, v63
	v_cvt_pk_bf16_f32 v19, v64, v65
	v_cvt_pk_bf16_f32 v20, v58, v59
	v_cvt_pk_bf16_f32 v21, v60, v61
	s_nop 1
	v_addc_co_u32_e32 v29, vcc, 0, v153, vcc
	s_mov_b64 s[24:25], 0x90000
	global_store_dwordx4 v[28:29], v[18:21], off
	s_nop 1
	v_cvt_pk_bf16_f32 v18, v84, v85
	v_cvt_pk_bf16_f32 v19, v82, v83
	v_cvt_pk_bf16_f32 v20, v92, v93
	v_cvt_pk_bf16_f32 v21, v90, v91
	global_store_dwordx4 v[26:27], v[18:21], off offset:256
	v_lshl_add_u64 v[26:27], v[152:153], 0, s[24:25]
	s_mov_b32 s24, 0x90000
	v_add_co_u32_e32 v28, vcc, s24, v152
	v_cvt_pk_bf16_f32 v18, v40, v41
	v_cvt_pk_bf16_f32 v19, v38, v39
	v_cvt_pk_bf16_f32 v20, v48, v49
	v_cvt_pk_bf16_f32 v21, v46, v47
	s_nop 1
	v_addc_co_u32_e32 v29, vcc, 0, v153, vcc
	s_mov_b64 s[24:25], 0xa0000
	global_store_dwordx4 v[28:29], v[18:21], off
	s_nop 1
	v_cvt_pk_bf16_f32 v18, v52, v53
	v_cvt_pk_bf16_f32 v19, v50, v51
	v_cvt_pk_bf16_f32 v20, v56, v57
	v_cvt_pk_bf16_f32 v21, v54, v55
	global_store_dwordx4 v[26:27], v[18:21], off offset:256
	v_lshl_add_u64 v[26:27], v[152:153], 0, s[24:25]
	s_mov_b32 s24, 0xa0000
	v_cvt_pk_bf16_f32 v18, v24, v25
	v_cvt_pk_bf16_f32 v19, v22, v23
	v_add_co_u32_e32 v22, vcc, s24, v152
	v_cvt_pk_bf16_f32 v20, v32, v33
	v_cvt_pk_bf16_f32 v21, v30, v31
	s_mov_b64 s[24:25], 0xb0000
	s_nop 0
	v_addc_co_u32_e32 v23, vcc, 0, v153, vcc
	global_store_dwordx4 v[22:23], v[18:21], off
	v_lshl_add_u64 v[22:23], v[152:153], 0, s[24:25]
	s_nop 0
	v_cvt_pk_bf16_f32 v18, v36, v37
	v_cvt_pk_bf16_f32 v19, v34, v35
	v_cvt_pk_bf16_f32 v20, v44, v45
	v_cvt_pk_bf16_f32 v21, v42, v43
	global_store_dwordx4 v[26:27], v[18:21], off offset:256
	s_nop 1
	v_cvt_pk_bf16_f32 v18, v12, v13
	v_cvt_pk_bf16_f32 v19, v10, v11
	v_add_co_u32_e32 v10, vcc, 0xb0000, v152
	v_cvt_pk_bf16_f32 v20, v16, v17
	v_cvt_pk_bf16_f32 v21, v14, v15
	s_nop 1
	v_addc_co_u32_e32 v11, vcc, 0, v153, vcc
	s_and_b64 vcc, exec, s[2:3]
	s_mov_b64 s[2:3], -1
	global_store_dwordx4 v[10:11], v[18:21], off
	v_cvt_pk_bf16_f32 v6, v6, v7
	v_cvt_pk_bf16_f32 v7, v8, v9
	v_cvt_pk_bf16_f32 v8, v2, v3
	v_cvt_pk_bf16_f32 v9, v4, v5
	global_store_dwordx4 v[22:23], v[6:9], off offset:256
	s_cbranch_vccnz .LBB0_537
	s_andn2_b64 vcc, exec, s[14:15]
	s_cbranch_vccnz .LBB0_536
	s_barrier
	s_branch .LBB0_536

; __device__ __forceinline__ unsigned cvt_pk_bf16(float lo, float hi) { unsigned r; asm volatile("v_cvt_pk_bf16_f32 %0, %1, %2" : "=v"(r) : "v"(lo), "v"(hi)); return r; }
; template <int D, int DV, int MODE, int NMAP, int KT> ...
;     ...
;                     const float nm = -m[mp]; float ps = 0.f;
; #pragma unroll
;                     for (int nb = 0; nb < NB; ++nb)
; #pragma unroll
;                         for (int j = 0; j < 4; ++j) { const float p = __builtin_amdgcn_exp2f(fmaf(s[nb][j], sc, nm)); ps += p; s[nb][j] = p; }
;                     l[mp] += ps;
;                 } else {
;                     const float rowf = __builtin_amdgcn_exp2f(l2g * (float)(myrow - kt * KT));
; #pragma unroll
;                     for (int nb = 0; nb < NB; ++nb)
; #pragma unroll
;                         for (int j = 0; j < 4; ++j) { float p = s[nb][j] * (rowf * ck[nb][j]); if (diag && (kt * KT + nb * 16 + g4 * 4 + j > myrow)) p = 0.f; s[nb][j] = p; }
;                 }
; #pragma unroll
;                 for (int kk = 0; kk < KK2; ++kk) { u32x4 wv; wv.x = cvt_pk_bf16(s[2 * kk][0], s[2 * kk][1]); wv.y = cvt_pk_bf16(s[2 * kk][2], s[2 * kk][3]);
;                     wv.z = cvt_pk_bf16(s[2 * kk + 1][0], s[2 * kk + 1][1]); wv.w = cvt_pk_bf16(s[2 * kk + 1][2], s[2 * kk + 1][3]); pb[mp][kk] = __builtin_bit_cast(bf16x8, wv); }
;             }
;             {
;                 constexpr int CBB = 4, NCB = (DV / 16) / CBB, NVB = KK2 * NCB;
;                 bf16x8 vfr[2][CBB];
;     ...
;                 AT_VLOAD(0, 0);
; #pragma unroll
;                 for (int b_ = 0; b_ < NVB; ++b_) {
;                     if (b_ + 1 < NVB) AT_VLOAD(b_ + 1, (b_ + 1) & 1);
;                     __builtin_amdgcn_sched_barrier(0);
;                     const int kk_ = b_ / NCB, c0_ = (b_ % NCB) * CBB;
;                     __builtin_amdgcn_s_setprio(1);
; #pragma unroll
;                     for (int x_ = 0; x_ < CBB; ++x_)
; #pragma unroll
;                         for (int mp = 0; mp < NMAP; ++mp) o[mp][c0_ + x_] = __builtin_amdgcn_mfma_f32_16x16x32_bf16(vfr[b_ & 1][x_], pb[mp][kk_], o[mp][c0_ + x_], 0, 0, 0);
;                     __builtin_amdgcn_s_setprio(0);
;                     __builtin_amdgcn_sched_barrier(0);
;                 }
.LBB0_599:
	v_fmamk_f32 v71, v106, 0x3db8aa3b, v70
	v_exp_f32_e32 v71, v71
	v_fmamk_f32 v73, v107, 0x3db8aa3b, v70
	v_exp_f32_e32 v73, v73
	v_fmamk_f32 v74, v108, 0x3db8aa3b, v70
	v_exp_f32_e32 v74, v74
	v_fmamk_f32 v75, v109, 0x3db8aa3b, v70
	v_exp_f32_e32 v75, v75
	v_fmamk_f32 v76, v102, 0x3db8aa3b, v70
	v_add_f32_e32 v72, 0, v71
	v_exp_f32_e32 v76, v76
	v_fmamk_f32 v77, v103, 0x3db8aa3b, v70
	v_add_f32_e32 v72, v73, v72
	v_exp_f32_e32 v77, v77
	v_fmamk_f32 v78, v104, 0x3db8aa3b, v70
	v_add_f32_e32 v72, v74, v72
	v_exp_f32_e32 v78, v78
	v_fmamk_f32 v79, v105, 0x3db8aa3b, v70
	v_add_f32_e32 v72, v75, v72
	v_exp_f32_e32 v79, v79
	v_fmamk_f32 v80, v98, 0x3db8aa3b, v70
	v_add_f32_e32 v72, v76, v72
	v_exp_f32_e32 v80, v80
	v_fmamk_f32 v81, v99, 0x3db8aa3b, v70
	v_add_f32_e32 v72, v77, v72
	v_exp_f32_e32 v81, v81
	v_fmamk_f32 v82, v100, 0x3db8aa3b, v70
	v_add_f32_e32 v72, v78, v72
	v_exp_f32_e32 v82, v82
	v_fmamk_f32 v83, v101, 0x3db8aa3b, v70
	v_add_f32_e32 v72, v79, v72
	v_exp_f32_e32 v83, v83
	v_fmamk_f32 v66, v66, 0x3db8aa3b, v70
	v_add_f32_e32 v72, v80, v72
	v_exp_f32_e32 v84, v66
	v_fmamk_f32 v67, v67, 0x3db8aa3b, v70
	v_add_f32_e32 v72, v81, v72
	v_exp_f32_e32 v85, v67
	v_fmamk_f32 v67, v68, 0x3db8aa3b, v70
	v_add_f32_e32 v72, v82, v72
	v_exp_f32_e32 v86, v67
	v_fmac_f32_e32 v70, 0x3db8aa3b, v69
	v_add_f32_e32 v72, v83, v72
	v_exp_f32_e32 v69, v70
	v_add_f32_e32 v66, v84, v72
	v_add_f32_e32 v66, v85, v66
	v_readlane_b32 s6, v255, 12
	v_add_f32_e32 v66, v86, v66
	v_add_f32_e32 v66, v69, v66
	v_add3_u32 v107, s6, v158, v149
	v_add_u32_e32 v108, 0x800, v107
	v_add_u32_e32 v109, 0x1000, v107
	v_add_u32_e32 v110, 0x1800, v107
	v_add_u32_e32 v111, 0x2000, v107
	v_add_u32_e32 v112, 0x2800, v107
	v_add_u32_e32 v113, 0x3000, v107
	v_add_u32_e32 v114, 0x3800, v107
	v_add_f32_e32 v106, v159, v66
	v_cvt_pk_bf16_f32 v70, v71, v73
	v_cvt_pk_bf16_f32 v71, v74, v75
	v_cvt_pk_bf16_f32 v72, v76, v77
	v_cvt_pk_bf16_f32 v73, v78, v79
	v_cvt_pk_bf16_f32 v66, v80, v81
	v_cvt_pk_bf16_f32 v67, v82, v83
	v_cvt_pk_bf16_f32 v68, v84, v85
	v_cvt_pk_bf16_f32 v69, v86, v69
	ds_read2_b64 v[74:77], v107 offset1:4
	ds_read2_b64 v[78:81], v108 offset0:32 offset1:36
	ds_read2_b64 v[82:85], v109 offset0:64 offset1:68
	ds_read2_b64 v[86:89], v110 offset0:96 offset1:100
	ds_read2_b64 v[90:93], v111 offset0:128 offset1:132
	ds_read2_b64 v[94:97], v112 offset0:160 offset1:164
	ds_read2_b64 v[98:101], v113 offset0:192 offset1:196
	ds_read2_b64 v[102:105], v114 offset0:224 offset1:228
	s_mov_b64 s[42:43], 0x800
	s_setprio 1
	s_waitcnt lgkmcnt(7)
	v_mfma_f32_16x16x32_bf16 v[62:65], v[74:77], v[70:73], v[62:65]
	s_waitcnt lgkmcnt(6)
	v_mfma_f32_16x16x32_bf16 v[58:61], v[78:81], v[70:73], v[58:61]
	s_waitcnt lgkmcnt(5)
	v_mfma_f32_16x16x32_bf16 v[54:57], v[82:85], v[70:73], v[54:57]
	s_waitcnt lgkmcnt(4)
	v_mfma_f32_16x16x32_bf16 v[50:53], v[86:89], v[70:73], v[50:53]
	s_setprio 0
	v_add_u32_e32 v115, 0x4800, v107
	v_add_u32_e32 v116, 0x5000, v107
	v_add_u32_e32 v117, 0x5800, v107
	v_add_u32_e32 v118, 0x6000, v107
	ds_read2_b64 v[74:77], v115 offset1:4
	ds_read2_b64 v[78:81], v116 offset0:32 offset1:36
	ds_read2_b64 v[82:85], v117 offset0:64 offset1:68
	ds_read2_b64 v[86:89], v118 offset0:96 offset1:100
	s_setprio 1
	s_waitcnt lgkmcnt(7)
	v_mfma_f32_16x16x32_bf16 v[46:49], v[90:93], v[70:73], v[46:49]
	s_waitcnt lgkmcnt(6)
	v_mfma_f32_16x16x32_bf16 v[42:45], v[94:97], v[70:73], v[42:45]
	s_waitcnt lgkmcnt(5)
	v_mfma_f32_16x16x32_bf16 v[38:41], v[98:101], v[70:73], v[38:41]
	s_waitcnt lgkmcnt(4)
	v_mfma_f32_16x16x32_bf16 v[34:37], v[102:105], v[70:73], v[34:37]
	s_setprio 0
	v_add_u32_e32 v119, 0x6800, v107
	v_add_u32_e32 v120, 0x7000, v107
	v_add_u32_e32 v121, 0x7800, v107
	v_add_u32_e32 v122, 0x8000, v107
	ds_read2_b64 v[90:93], v119 offset0:128 offset1:132
	ds_read2_b64 v[94:97], v120 offset0:160 offset1:164
	ds_read2_b64 v[98:101], v121 offset0:192 offset1:196
	ds_read2_b64 v[102:105], v122 offset0:224 offset1:228
	s_setprio 1
	s_waitcnt lgkmcnt(7)
	v_mfma_f32_16x16x32_bf16 v[30:33], v[74:77], v[70:73], v[30:33]
	s_waitcnt lgkmcnt(6)
	v_mfma_f32_16x16x32_bf16 v[26:29], v[78:81], v[70:73], v[26:29]
	s_waitcnt lgkmcnt(5)
	v_mfma_f32_16x16x32_bf16 v[22:25], v[82:85], v[70:73], v[22:25]
	s_waitcnt lgkmcnt(4)
	v_mfma_f32_16x16x32_bf16 v[18:21], v[86:89], v[70:73], v[18:21]
	s_setprio 0
	ds_read2_b64 v[74:77], v107 offset0:8 offset1:12
	ds_read2_b64 v[78:81], v108 offset0:40 offset1:44
	ds_read2_b64 v[82:85], v109 offset0:72 offset1:76
	ds_read2_b64 v[86:89], v110 offset0:104 offset1:108
	s_setprio 1
	s_waitcnt lgkmcnt(7)
	v_mfma_f32_16x16x32_bf16 v[14:17], v[90:93], v[70:73], v[14:17]
	s_waitcnt lgkmcnt(6)
	v_mfma_f32_16x16x32_bf16 v[10:13], v[94:97], v[70:73], v[10:13]
	s_waitcnt lgkmcnt(5)
	v_mfma_f32_16x16x32_bf16 v[6:9], v[98:101], v[70:73], v[6:9]
	s_waitcnt lgkmcnt(4)
	v_mfma_f32_16x16x32_bf16 v[2:5], v[102:105], v[70:73], v[2:5]
	s_setprio 0
	ds_read2_b64 v[70:73], v111 offset0:136 offset1:140
	ds_read2_b64 v[90:93], v112 offset0:168 offset1:172
	ds_read2_b64 v[94:97], v113 offset0:200 offset1:204
	ds_read2_b64 v[98:101], v114 offset0:232 offset1:236
	s_setprio 1
	s_waitcnt lgkmcnt(7)
	v_mfma_f32_16x16x32_bf16 v[62:65], v[74:77], v[66:69], v[62:65]
	s_waitcnt lgkmcnt(6)
	v_mfma_f32_16x16x32_bf16 v[58:61], v[78:81], v[66:69], v[58:61]
	s_waitcnt lgkmcnt(5)
	v_mfma_f32_16x16x32_bf16 v[54:57], v[82:85], v[66:69], v[54:57]
	s_waitcnt lgkmcnt(4)
	v_mfma_f32_16x16x32_bf16 v[50:53], v[86:89], v[66:69], v[50:53]
	s_setprio 0
	ds_read2_b64 v[74:77], v115 offset0:8 offset1:12
	ds_read2_b64 v[78:81], v116 offset0:40 offset1:44
	ds_read2_b64 v[82:85], v117 offset0:72 offset1:76
	ds_read2_b64 v[86:89], v118 offset0:104 offset1:108
	s_setprio 1
	s_waitcnt lgkmcnt(7)
; __device__ __forceinline__ float xsum_rows(float v) { return xsum32(xsum16(v)); }
; template <int D, int DV, int MODE, int NMAP, int KT> ...
;     ...
; #pragma unroll
;                     for (int nb = 0; nb < NB; ++nb)
; #pragma unroll
;                         for (int j = 0; j < 4; ++j) { float p = s[nb][j] * (rowf * ck[nb][j]); if (diag && (kt * KT + nb * 16 + g4 * 4 + j > myrow)) p = 0.f; s[nb][j] = p; }
;                 }
; #pragma unroll
;                 for (int kk = 0; kk < KK2; ++kk) { u32x4 wv; wv.x = cvt_pk_bf16(s[2 * kk][0], s[2 * kk][1]); wv.y = cvt_pk_bf16(s[2 * kk][2], s[2 * kk][3]);
;                     wv.z = cvt_pk_bf16(s[2 * kk + 1][0], s[2 * kk + 1][1]); wv.w = cvt_pk_bf16(s[2 * kk + 1][2], s[2 * kk + 1][3]); pb[mp][kk] = __builtin_bit_cast(bf16x8, wv); }
;             }
;             {
;                 constexpr int CBB = 4, NCB = (DV / 16) / CBB, NVB = KK2 * NCB;
;                 bf16x8 vfr[2][CBB];
;     ...
;                 AT_VLOAD(0, 0);
; #pragma unroll
;                 for (int b_ = 0; b_ < NVB; ++b_) {
;                     if (b_ + 1 < NVB) AT_VLOAD(b_ + 1, (b_ + 1) & 1);
;                     __builtin_amdgcn_sched_barrier(0);
;                     const int kk_ = b_ / NCB, c0_ = (b_ % NCB) * CBB;
;                     __builtin_amdgcn_s_setprio(1);
; #pragma unroll
;                     for (int x_ = 0; x_ < CBB; ++x_)
; #pragma unroll
;                         for (int mp = 0; mp < NMAP; ++mp) o[mp][c0_ + x_] = __builtin_amdgcn_mfma_f32_16x16x32_bf16(vfr[b_ & 1][x_], pb[mp][kk_], o[mp][c0_ + x_], 0, 0, 0);
;                     __builtin_amdgcn_s_setprio(0);
;                     __builtin_amdgcn_sched_barrier(0);
;                 }
;     ...
;     if (MODE < 2) {
; #pragma unroll
;         for (int mp = 0; mp < NMAP; ++mp) l[mp] = xsum_rows(l[mp]);
;     }
; __global__ void __launch_bounds__(512, 2) mega_fwd(Params P) {
;     ...
;                         const float iv = 1.0f / ll[0]; const size_t row = rb + q0 + wave * 16 + r;
; #pragma unroll
;                         for (int cb = 0; cb < 16; ++cb) { const f32x4 v = o[0][cb] * iv; u32x2 wv; wv.x = cvt_pk_bf16(v[0], v[1]); wv.y = cvt_pk_bf16(v[2], v[3]);
;                             *(u32x2*)(CAT + row * 1024 + h * 256 + cb * 16 + g4 * 4) = wv; }
	v_mfma_f32_16x16x32_bf16 v[46:49], v[70:73], v[66:69], v[46:49]
	s_waitcnt lgkmcnt(6)
	v_mfma_f32_16x16x32_bf16 v[42:45], v[90:93], v[66:69], v[42:45]
	s_waitcnt lgkmcnt(5)
	v_mfma_f32_16x16x32_bf16 v[38:41], v[94:97], v[66:69], v[38:41]
	s_waitcnt lgkmcnt(4)
	v_mfma_f32_16x16x32_bf16 v[34:37], v[98:101], v[66:69], v[34:37]
	s_setprio 0
	ds_read2_b64 v[70:73], v119 offset0:136 offset1:140
	ds_read2_b64 v[90:93], v120 offset0:168 offset1:172
	ds_read2_b64 v[94:97], v121 offset0:200 offset1:204
	ds_read2_b64 v[98:101], v122 offset0:232 offset1:236
	s_setprio 1
	s_waitcnt lgkmcnt(7)
	v_mfma_f32_16x16x32_bf16 v[30:33], v[74:77], v[66:69], v[30:33]
	s_waitcnt lgkmcnt(6)
	v_mfma_f32_16x16x32_bf16 v[26:29], v[78:81], v[66:69], v[26:29]
	s_waitcnt lgkmcnt(5)
	v_mfma_f32_16x16x32_bf16 v[22:25], v[82:85], v[66:69], v[22:25]
	s_waitcnt lgkmcnt(4)
	v_mfma_f32_16x16x32_bf16 v[18:21], v[86:89], v[66:69], v[18:21]
	s_setprio 0
	s_setprio 1
	s_waitcnt lgkmcnt(3)
	v_mfma_f32_16x16x32_bf16 v[14:17], v[70:73], v[66:69], v[14:17]
	s_waitcnt lgkmcnt(2)
	v_mfma_f32_16x16x32_bf16 v[10:13], v[90:93], v[66:69], v[10:13]
	s_waitcnt lgkmcnt(1)
	v_mfma_f32_16x16x32_bf16 v[6:9], v[94:97], v[66:69], v[6:9]
	s_waitcnt lgkmcnt(0)
	v_mfma_f32_16x16x32_bf16 v[2:5], v[98:101], v[66:69], v[2:5]
	s_setprio 0
	v_mov_b32_e32 v66, v106
	s_nop 1
	v_permlane16_swap_b32_e32 v106, v66
	v_add_f32_e32 v66, v106, v66
	v_mov_b32_e32 v67, v66
	s_nop 1
	v_permlane32_swap_b32_e32 v66, v67
	v_add_f32_e32 v66, v66, v67
	v_div_scale_f32 v67, s[6:7], v66, v66, 1.0
	v_rcp_f32_e32 v68, v67
	s_nop 0
	v_fma_f32 v69, -v67, v68, 1.0
	v_fmac_f32_e32 v68, v69, v68
	v_div_scale_f32 v69, vcc, 1.0, v66, 1.0
	v_mul_f32_e32 v70, v69, v68
	v_fma_f32 v71, -v67, v70, v69
	v_fmac_f32_e32 v70, v71, v68
	v_fma_f32 v67, -v67, v70, v69
	v_div_fmas_f32 v67, v67, v68, v70
	v_lshl_add_u64 v[68:69], s[4:5], 0, v[146:147]
	s_lshl_b32 s4, s29, 1
	s_add_u32 s4, s23, s4
	s_addc_u32 s5, s24, 0
	v_lshlrev_b64 v[68:69], 11, v[68:69]
	v_div_fixup_f32 v66, v67, v66, 1.0
	v_lshl_add_u64 v[68:69], s[4:5], 0, v[68:69]
	s_add_i32 s1, s1, s20
	s_add_i32 s27, s27, s28
	v_lshl_add_u64 v[68:69], v[68:69], 0, v[0:1]
	v_pk_mul_f32 v[62:63], v[66:67], v[62:63] op_sel_hi:[0,1]
	v_pk_mul_f32 v[58:59], v[66:67], v[58:59] op_sel_hi:[0,1]
	v_pk_mul_f32 v[54:55], v[66:67], v[54:55] op_sel_hi:[0,1]
	v_pk_mul_f32 v[50:51], v[66:67], v[50:51] op_sel_hi:[0,1]
	v_pk_mul_f32 v[46:47], v[66:67], v[46:47] op_sel_hi:[0,1]
	v_pk_mul_f32 v[42:43], v[66:67], v[42:43] op_sel_hi:[0,1]
	v_pk_mul_f32 v[38:39], v[66:67], v[38:39] op_sel_hi:[0,1]
	v_pk_mul_f32 v[34:35], v[66:67], v[34:35] op_sel_hi:[0,1]
	v_pk_mul_f32 v[30:31], v[66:67], v[30:31] op_sel_hi:[0,1]
	v_pk_mul_f32 v[26:27], v[66:67], v[26:27] op_sel_hi:[0,1]
	v_pk_mul_f32 v[22:23], v[66:67], v[22:23] op_sel_hi:[0,1]
	v_pk_mul_f32 v[18:19], v[66:67], v[18:19] op_sel_hi:[0,1]
	v_pk_mul_f32 v[14:15], v[66:67], v[14:15] op_sel_hi:[0,1]
	v_pk_mul_f32 v[10:11], v[66:67], v[10:11] op_sel_hi:[0,1]
	v_pk_mul_f32 v[6:7], v[66:67], v[6:7] op_sel_hi:[0,1]
	v_pk_mul_f32 v[2:3], v[66:67], v[2:3] op_sel_hi:[0,1]
	s_cmpk_gt_i32 s1, 0x7ff
	v_pk_mul_f32 v[64:65], v[66:67], v[64:65] op_sel_hi:[0,1]
	v_cvt_pk_bf16_f32 v62, v62, v63
	v_cvt_pk_bf16_f32 v63, v64, v65
	global_store_dwordx2 v[68:69], v[62:63], off
	v_pk_mul_f32 v[60:61], v[66:67], v[60:61] op_sel_hi:[0,1]
	v_cvt_pk_bf16_f32 v58, v58, v59
	v_cvt_pk_bf16_f32 v59, v60, v61
	global_store_dwordx2 v[68:69], v[58:59], off offset:32
	v_pk_mul_f32 v[56:57], v[66:67], v[56:57] op_sel_hi:[0,1]
	v_cvt_pk_bf16_f32 v54, v54, v55
	v_cvt_pk_bf16_f32 v55, v56, v57
	global_store_dwordx2 v[68:69], v[54:55], off offset:64
	v_pk_mul_f32 v[52:53], v[66:67], v[52:53] op_sel_hi:[0,1]
	v_cvt_pk_bf16_f32 v50, v50, v51
	v_cvt_pk_bf16_f32 v51, v52, v53
	global_store_dwordx2 v[68:69], v[50:51], off offset:96
	v_pk_mul_f32 v[48:49], v[66:67], v[48:49] op_sel_hi:[0,1]
	v_cvt_pk_bf16_f32 v46, v46, v47
	v_cvt_pk_bf16_f32 v47, v48, v49
	global_store_dwordx2 v[68:69], v[46:47], off offset:128
	v_pk_mul_f32 v[44:45], v[66:67], v[44:45] op_sel_hi:[0,1]
	v_cvt_pk_bf16_f32 v42, v42, v43
	v_cvt_pk_bf16_f32 v43, v44, v45
	global_store_dwordx2 v[68:69], v[42:43], off offset:160
	v_pk_mul_f32 v[40:41], v[66:67], v[40:41] op_sel_hi:[0,1]
	v_cvt_pk_bf16_f32 v38, v38, v39
	v_cvt_pk_bf16_f32 v39, v40, v41
	global_store_dwordx2 v[68:69], v[38:39], off offset:192
	v_pk_mul_f32 v[36:37], v[66:67], v[36:37] op_sel_hi:[0,1]
	v_cvt_pk_bf16_f32 v34, v34, v35
	v_cvt_pk_bf16_f32 v35, v36, v37
	global_store_dwordx2 v[68:69], v[34:35], off offset:224
	v_pk_mul_f32 v[32:33], v[66:67], v[32:33] op_sel_hi:[0,1]
	v_cvt_pk_bf16_f32 v30, v30, v31
	v_cvt_pk_bf16_f32 v31, v32, v33
	global_store_dwordx2 v[68:69], v[30:31], off offset:256
	v_pk_mul_f32 v[28:29], v[66:67], v[28:29] op_sel_hi:[0,1]
	v_cvt_pk_bf16_f32 v26, v26, v27
	v_cvt_pk_bf16_f32 v27, v28, v29
	global_store_dwordx2 v[68:69], v[26:27], off offset:288
	v_pk_mul_f32 v[24:25], v[66:67], v[24:25] op_sel_hi:[0,1]
	v_cvt_pk_bf16_f32 v22, v22, v23
	v_cvt_pk_bf16_f32 v23, v24, v25
	global_store_dwordx2 v[68:69], v[22:23], off offset:320
	v_pk_mul_f32 v[20:21], v[66:67], v[20:21] op_sel_hi:[0,1]
	v_cvt_pk_bf16_f32 v18, v18, v19
	v_cvt_pk_bf16_f32 v19, v20, v21
	global_store_dwordx2 v[68:69], v[18:19], off offset:352
	v_pk_mul_f32 v[16:17], v[66:67], v[16:17] op_sel_hi:[0,1]
	v_cvt_pk_bf16_f32 v14, v14, v15
	v_cvt_pk_bf16_f32 v15, v16, v17
	global_store_dwordx2 v[68:69], v[14:15], off offset:384
	v_pk_mul_f32 v[12:13], v[66:67], v[12:13] op_sel_hi:[0,1]
	v_cvt_pk_bf16_f32 v10, v10, v11
	v_cvt_pk_bf16_f32 v11, v12, v13
	global_store_dwordx2 v[68:69], v[10:11], off offset:416
	v_pk_mul_f32 v[8:9], v[66:67], v[8:9] op_sel_hi:[0,1]
	v_cvt_pk_bf16_f32 v6, v6, v7
	v_cvt_pk_bf16_f32 v7, v8, v9
	global_store_dwordx2 v[68:69], v[6:7], off offset:448
	v_pk_mul_f32 v[4:5], v[66:67], v[4:5] op_sel_hi:[0,1]
	v_cvt_pk_bf16_f32 v2, v2, v3
	v_cvt_pk_bf16_f32 v3, v4, v5
	global_store_dwordx2 v[68:69], v[2:3], off offset:480
	s_cbranch_scc1 .LBB0_608
; template <int D, int DV, int MODE, int NMAP, int KT> ...
;     ...
;     { const bf16_t* qr = Qp + (size_t)(w * 16 + r) * ldq + g4 * 8;
; #pragma unroll
;       for (int mp = 0; mp < NMAP; ++mp)
; #pragma unroll
;         for (int kk = 0; kk < D / 32; ++kk) qf[mp][kk] = *(const bf16x8*)(qr + mp * D + kk * 32); }
;     float m[NMAP];
; #pragma unroll
;     for (int mp = 0; mp < NMAP; ++mp) { m[mp] = -INFINITY; l[mp] = 0.f;
; #pragma unroll
;         for (int cb = 0; cb < DV / 16; ++cb) o[mp][cb] = (f32x4){0.f, 0.f, 0.f, 0.f}; }
;     const int rowmin = q0 + w * 16, myrow = rowmin + r;
;     float ck[NB][4];
;     if (MODE == 2) {
; #pragma unroll
;         for (int nb = 0; nb < NB; ++nb)
; #pragma unroll
;             for (int j = 0; j < 4; ++j) ck[nb][j] = __builtin_amdgcn_exp2f(-l2g * (float)(nb * 16 + g4 * 4 + j));
;     }
;     u32x4 kreg[KN], vreg[VN];
;     ...
;     AT_LOAD(0);
; __global__ void __launch_bounds__(512, 2) mega_fwd(Params P) {
;     ...
;                     for (int u = blk; u < 2048; u += G) {
;                         const int bh = u & 127, b = bh >> 2, h = bh & 3, qt = u >> 7, q0 = qt * 128;
;                         const size_t rb = (size_t)b * SEQ;
;                         f32x4 o[1][16]; float ll[1];
;                         attn_core3<256, 256, 0, 1, 64>(lds, BIG + (rb + q0) * 1024 + h * 256, 1024, KV + (size_t)b * 256 * 2048 + h * 256, 2048, KV + (size_t)b * 256 * 2048 + 1024 + h * 256, 2048, q0, 4, 0.0625f * LOG2E, 0.f, o, ll);
.LBB0_600:
	s_lshl_b32 s4, s27, 1
	s_and_b32 s94, s4, 0x600
	s_bfe_u32 s4, s1, 0x50002
	s_and_b32 s5, s1, 0xffffff80
	s_lshl_b32 s14, s4, 20
	s_lshl_b32 s4, s4, 11
	s_ashr_i32 s6, s5, 31
	s_add_u32 s4, s4, s5
	s_addc_u32 s5, 0, s6
	s_lshl_b64 s[6:7], s[4:5], 11
	s_add_u32 s6, s21, s6
	s_addc_u32 s7, s22, s7
	s_lshl_b32 s8, s1, 8
	s_and_b32 s29, s8, 0x300
	v_mov_b32_e32 v66, v211
	s_lshl_b32 s10, s29, 1
	s_add_u32 s8, s6, s10
	v_ashrrev_i32_e32 v2, 31, v66
	v_lshrrev_b32_e32 v2, 27, v2
	s_addc_u32 s9, s7, 0
	v_add_u32_e32 v2, v66, v2
	s_add_u32 s6, s25, s14
	v_ashrrev_i32_e32 v56, 5, v2
	v_and_b32_e32 v2, 0xffffffe0, v2
	s_addc_u32 s7, s26, 0
	v_sub_u32_e32 v98, v66, v2
	s_add_u32 s12, s6, s10
	v_ashrrev_i32_e32 v57, 31, v56
	v_lshlrev_b32_e32 v4, 3, v98
	s_addc_u32 s13, s7, 0
	v_lshlrev_b64 v[2:3], 12, v[56:57]
	v_ashrrev_i32_e32 v5, 31, v4
	v_lshl_add_u64 v[6:7], s[12:13], 0, v[2:3]
	v_lshlrev_b64 v[4:5], 1, v[4:5]
	v_lshl_add_u64 v[18:19], v[6:7], 0, v[4:5]
	v_add_u32_e32 v6, 0x200, v66
	v_ashrrev_i32_e32 v7, 31, v6
	v_lshrrev_b32_e32 v7, 27, v7
	v_add_u32_e32 v7, v6, v7
	v_ashrrev_i32_e32 v58, 5, v7
	v_and_b32_e32 v7, 0xffffffe0, v7
	v_sub_u32_e32 v57, v6, v7
	v_ashrrev_i32_e32 v59, 31, v58
	v_lshlrev_b32_e32 v8, 3, v57
	v_lshlrev_b64 v[6:7], 12, v[58:59]
	v_ashrrev_i32_e32 v9, 31, v8
	v_lshl_add_u64 v[10:11], s[12:13], 0, v[6:7]
	v_lshlrev_b64 v[8:9], 1, v[8:9]
	v_lshl_add_u64 v[20:21], v[10:11], 0, v[8:9]
	v_add_u32_e32 v10, 0x400, v66
	v_ashrrev_i32_e32 v11, 31, v10
	v_lshrrev_b32_e32 v11, 27, v11
	v_add_u32_e32 v11, v10, v11
	v_ashrrev_i32_e32 v60, 5, v11
	v_and_b32_e32 v11, 0xffffffe0, v11
	v_sub_u32_e32 v59, v10, v11
	v_ashrrev_i32_e32 v61, 31, v60
	v_lshlrev_b32_e32 v12, 3, v59
	v_lshlrev_b64 v[10:11], 12, v[60:61]
	v_ashrrev_i32_e32 v13, 31, v12
	v_lshl_add_u64 v[14:15], s[12:13], 0, v[10:11]
	v_lshlrev_b64 v[12:13], 1, v[12:13]
	v_readfirstlane_b32 s6, v66
	v_lshl_add_u64 v[62:63], v[14:15], 0, v[12:13]
	v_add_u32_e32 v14, 0x600, v66
	s_ashr_i32 s15, s6, 6
	v_ashrrev_i32_e32 v15, 31, v14
	v_lshrrev_b32_e32 v15, 27, v15
	s_ashr_i32 s6, s15, 31
	v_add_u32_e32 v15, v14, v15
	s_lshr_b32 s6, s6, 27
	s_add_i32 s10, s15, 8
	v_ashrrev_i32_e32 v64, 5, v15
	s_add_i32 s6, s15, s6
	s_ashr_i32 s11, s10, 31
	v_and_b32_e32 v160, 15, v66
	v_and_b32_e32 v15, 0xffffffe0, v15
	v_ashrrev_i32_e32 v65, 31, v64
	s_ashr_i32 s31, s6, 5
	s_andn2_b32 s6, s6, 31
	s_lshr_b32 s11, s11, 27
	s_add_i32 s16, s15, 16
	v_lshl_or_b32 v54, s15, 4, v160
	v_sub_u32_e32 v61, v14, v15
	v_lshlrev_b64 v[14:15], 12, v[64:65]
	v_and_b32_e32 v65, 63, v66
	s_sub_i32 s30, s15, s6
	s_lshl_b32 s45, s31, 6
	s_add_i32 s11, s10, s11
	s_ashr_i32 s17, s16, 31
	s_add_i32 s15, s15, 24
	v_lshlrev_b32_e32 v16, 3, v61
	v_or_b32_e32 v38, s45, v65
	s_ashr_i32 s34, s11, 5
	s_lshr_b32 s17, s17, 27
	s_ashr_i32 s18, s15, 31
	global_load_dwordx4 v[22:25], v[18:19], off
	global_load_dwordx4 v[26:29], v[20:21], off
	v_ashrrev_i32_e32 v17, 31, v16
	v_ashrrev_i32_e32 v39, 31, v38
	s_lshl_b32 s6, s30, 3
	s_andn2_b32 s11, s11, 31
	s_lshl_b32 s46, s34, 6
	s_add_i32 s17, s16, s17
	s_lshr_b32 s18, s18, 27
	v_lshl_add_u64 v[30:31], s[12:13], 0, v[14:15]
	v_lshlrev_b64 v[16:17], 1, v[16:17]
	v_lshlrev_b64 v[38:39], 12, v[38:39]
	s_ashr_i32 s7, s6, 31
	s_sub_i32 s33, s10, s11
	v_or_b32_e32 v40, s46, v65
	s_ashr_i32 s41, s17, 5
	s_add_i32 s18, s15, s18
	v_lshl_add_u64 v[106:107], v[30:31], 0, v[16:17]
	global_load_dwordx4 v[30:33], v[62:63], off
	global_load_dwordx4 v[34:37], v[106:107], off
	v_lshl_add_u64 v[38:39], s[12:13], 0, v[38:39]
	s_lshl_b64 s[6:7], s[6:7], 1
	v_ashrrev_i32_e32 v41, 31, v40
	s_lshl_b32 s10, s33, 3
	s_andn2_b32 s17, s17, 31
	s_lshl_b32 s47, s41, 6
	s_ashr_i32 s43, s18, 5
	v_lshl_add_u64 v[38:39], v[38:39], 0, s[6:7]
	v_lshlrev_b64 v[40:41], 12, v[40:41]
	s_ashr_i32 s11, s10, 31
	s_sub_i32 s40, s16, s17
	v_or_b32_e32 v46, s47, v65
	s_andn2_b32 s18, s18, 31
	s_lshl_b32 s48, s43, 6
	v_lshl_add_u64 v[42:43], s[12:13], 0, v[40:41]
	global_load_dwordx4 v[38:41], v[38:39], off offset:2048
	s_lshl_b64 s[10:11], s[10:11], 1
	v_ashrrev_i32_e32 v47, 31, v46
	s_lshl_b32 s16, s40, 3
	s_sub_i32 s42, s15, s18
	v_or_b32_e32 v50, s48, v65
	v_lshl_add_u64 v[42:43], v[42:43], 0, s[10:11]
	v_lshlrev_b64 v[46:47], 12, v[46:47]
	s_ashr_i32 s17, s16, 31
	v_ashrrev_i32_e32 v51, 31, v50
	s_lshl_b32 s18, s42, 3
	global_load_dwordx4 v[42:45], v[42:43], off offset:2048
	v_lshl_add_u64 v[46:47], s[12:13], 0, v[46:47]
	s_lshl_b64 s[16:17], s[16:17], 1
	v_lshlrev_b64 v[50:51], 12, v[50:51]
	s_ashr_i32 s19, s18, 31
	v_lshl_add_u64 v[46:47], v[46:47], 0, s[16:17]
	v_lshl_add_u64 v[50:51], s[12:13], 0, v[50:51]
	s_lshl_b64 s[18:19], s[18:19], 1
	global_load_dwordx4 v[46:49], v[46:47], off offset:2048
	v_lshl_add_u64 v[50:51], v[50:51], 0, s[18:19]
	global_load_dwordx4 v[50:53], v[50:51], off offset:2048
	v_ashrrev_i32_e32 v55, 31, v54
	v_lshrrev_b32_e32 v66, 1, v66
	v_lshlrev_b64 v[54:55], 11, v[54:55]
	v_and_b32_e32 v158, 24, v66
	v_lshl_add_u64 v[54:55], s[8:9], 0, v[54:55]
	v_lshlrev_b32_e32 v148, 1, v158
	v_mov_b32_e32 v149, v1
	v_lshl_add_u64 v[54:55], v[54:55], 0, v[148:149]
	v_mul_lo_u32 v161, v56, s66
	v_lshlrev_b32_e32 v162, 4, v98
	global_load_dwordx4 v[66:69], v[54:55], off
	global_load_dwordx4 v[70:73], v[54:55], off offset:64
	global_load_dwordx4 v[74:77], v[54:55], off offset:128
	global_load_dwordx4 v[78:81], v[54:55], off offset:192
	global_load_dwordx4 v[82:85], v[54:55], off offset:256
	global_load_dwordx4 v[86:89], v[54:55], off offset:320
	global_load_dwordx4 v[90:93], v[54:55], off offset:384
	global_load_dwordx4 v[94:97], v[54:55], off offset:448
	v_add3_u32 v54, 0, v161, v162
	v_mul_lo_u32 v163, v58, s66
	v_lshlrev_b32_e32 v164, 4, v57
	s_waitcnt lgkmcnt(0)
	s_barrier
; template <int D, int DV, int MODE, int NMAP, int KT> ...
;     ...
;     float m[NMAP];
; #pragma unroll
;     for (int mp = 0; mp < NMAP; ++mp) { m[mp] = -INFINITY; l[mp] = 0.f;
; #pragma unroll
;         for (int cb = 0; cb < DV / 16; ++cb) o[mp][cb] = (f32x4){0.f, 0.f, 0.f, 0.f}; }
;     const int rowmin = q0 + w * 16, myrow = rowmin + r;
;     float ck[NB][4];
;     if (MODE == 2) {
; #pragma unroll
;         for (int nb = 0; nb < NB; ++nb)
; #pragma unroll
;             for (int j = 0; j < 4; ++j) ck[nb][j] = __builtin_amdgcn_exp2f(-l2g * (float)(nb * 16 + g4 * 4 + j));
;     }
;     u32x4 kreg[KN], vreg[VN];
;     ...
;     AT_LOAD(0);
;     __syncthreads();
;     AT_STORE(0);
;     if (nkt > 1) AT_LOAD(1);
	v_mul_lo_u32 v165, v60, s66
	v_lshlrev_b32_e32 v166, 4, v59
	s_mulk_i32 s30, 0x480
	v_mul_lo_u32 v167, v64, s66
	v_lshlrev_b32_e32 v168, 4, v61
	s_add_i32 s8, s30, 0
	s_lshl_b32 s31, s31, 7
	s_waitcnt vmcnt(0)
	ds_write_b128 v54, v[22:25]
	v_add3_u32 v22, 0, v163, v164
	ds_write_b128 v22, v[26:29]
	v_add3_u32 v22, 0, v165, v166
	s_add_i32 s8, s8, s31
	v_lshlrev_b32_e32 v169, 1, v65
	s_mulk_i32 s33, 0x480
	s_lshl_b32 s34, s34, 7
	s_mulk_i32 s40, 0x480
	s_lshl_b32 s41, s41, 7
	s_mulk_i32 s42, 0x480
	s_lshl_b32 s43, s43, 7
	v_add_co_u32_e32 v18, vcc, s35, v18
	s_mov_b32 s15, s95
	s_nop 0
	v_addc_co_u32_e32 v19, vcc, 0, v19, vcc
	ds_write_b128 v22, v[30:33]
	v_add3_u32 v22, 0, v167, v168
	ds_write_b128 v22, v[34:37]
	v_add_u32_e32 v22, s8, v169
	s_add_i32 s8, s33, 0
	s_add_i32 s8, s8, s34
	ds_write_b16 v22, v38 offset:33792
	ds_write_b16_d16_hi v22, v38 offset:33936
	ds_write_b16 v22, v39 offset:34080
	ds_write_b16_d16_hi v22, v39 offset:34224
	ds_write_b16 v22, v40 offset:34368
	ds_write_b16_d16_hi v22, v40 offset:34512
	ds_write_b16 v22, v41 offset:34656
	ds_write_b16_d16_hi v22, v41 offset:34800
	v_add_u32_e32 v22, s8, v169
	s_add_i32 s8, s40, 0
	s_add_i32 s8, s8, s41
	ds_write_b16 v22, v42 offset:33792
	ds_write_b16_d16_hi v22, v42 offset:33936
	ds_write_b16 v22, v43 offset:34080
	ds_write_b16_d16_hi v22, v43 offset:34224
	ds_write_b16 v22, v44 offset:34368
	ds_write_b16_d16_hi v22, v44 offset:34512
	ds_write_b16 v22, v45 offset:34656
	ds_write_b16_d16_hi v22, v45 offset:34800
	v_add_u32_e32 v22, s8, v169
	s_add_i32 s8, s42, 0
	s_add_i32 s8, s8, s43
	ds_write_b16 v22, v46 offset:33792
	ds_write_b16_d16_hi v22, v46 offset:33936
	ds_write_b16 v22, v47 offset:34080
	ds_write_b16_d16_hi v22, v47 offset:34224
	ds_write_b16 v22, v48 offset:34368
	ds_write_b16_d16_hi v22, v48 offset:34512
	ds_write_b16 v22, v49 offset:34656
	ds_write_b16_d16_hi v22, v49 offset:34800
	v_add_u32_e32 v22, s8, v169
	v_add_co_u32_e32 v20, vcc, s35, v20
	ds_write_b16 v22, v50 offset:33792
	ds_write_b16_d16_hi v22, v50 offset:33936
	ds_write_b16 v22, v51 offset:34080
	ds_write_b16_d16_hi v22, v51 offset:34224
	ds_write_b16 v22, v52 offset:34368
	ds_write_b16_d16_hi v22, v52 offset:34512
	ds_write_b16 v22, v53 offset:34656
	ds_write_b16_d16_hi v22, v53 offset:34800
	v_addc_co_u32_e32 v21, vcc, 0, v21, vcc
	global_load_dwordx4 v[98:101], v[18:19], off
	global_load_dwordx4 v[102:105], v[20:21], off
	v_add_co_u32_e32 v18, vcc, s35, v62
	v_or_b32_e32 v22, 64, v65
	s_nop 0
	v_addc_co_u32_e32 v19, vcc, 0, v63, vcc
	v_add_co_u32_e32 v20, vcc, s35, v106
	v_lshl_add_u64 v[14:15], s[14:15], 0, v[14:15]
	s_nop 0
	v_addc_co_u32_e32 v21, vcc, 0, v107, vcc
	global_load_dwordx4 v[106:109], v[18:19], off
	global_load_dwordx4 v[110:113], v[20:21], off
	v_add_u32_e32 v18, s45, v22
	v_ashrrev_i32_e32 v19, 31, v18
	v_add_u32_e32 v20, s46, v22
	v_lshlrev_b64 v[18:19], 12, v[18:19]
	v_ashrrev_i32_e32 v21, 31, v20
	v_lshl_add_u64 v[18:19], s[12:13], 0, v[18:19]
	v_lshlrev_b64 v[20:21], 12, v[20:21]
	v_lshl_add_u64 v[18:19], v[18:19], 0, s[6:7]
	v_lshl_add_u64 v[20:21], s[12:13], 0, v[20:21]
	v_lshl_add_u64 v[20:21], v[20:21], 0, s[10:11]
	global_load_dwordx4 v[114:117], v[18:19], off offset:2048
	global_load_dwordx4 v[118:121], v[20:21], off offset:2048
	v_add_u32_e32 v18, s47, v22
	v_ashrrev_i32_e32 v19, 31, v18
	v_add_u32_e32 v20, s48, v22
	v_lshlrev_b64 v[18:19], 12, v[18:19]
	v_ashrrev_i32_e32 v21, 31, v20
	v_lshl_add_u64 v[18:19], s[12:13], 0, v[18:19]
	v_lshlrev_b64 v[20:21], 12, v[20:21]
	v_lshl_add_u64 v[18:19], v[18:19], 0, s[16:17]
	v_lshl_add_u64 v[20:21], s[12:13], 0, v[20:21]
	v_lshl_add_u64 v[20:21], v[20:21], 0, s[18:19]
	global_load_dwordx4 v[122:125], v[18:19], off offset:2048
	global_load_dwordx4 v[126:129], v[20:21], off offset:2048
	s_add_u32 s6, s12, s6
	s_addc_u32 s7, s13, s7
	s_add_u32 s8, s12, s10
	s_addc_u32 s9, s13, s11
	s_add_u32 s10, s12, s16
	s_addc_u32 s11, s13, s17
	s_add_u32 s12, s12, s18
	v_lshl_add_u64 v[10:11], s[14:15], 0, v[10:11]
	v_lshl_add_u64 v[6:7], s[14:15], 0, v[6:7]
	v_lshl_add_u64 v[2:3], s[14:15], 0, v[2:3]
	s_addc_u32 s13, s13, s19
	s_addk_i32 s48, 0x80
	s_addk_i32 s47, 0x80
	s_addk_i32 s46, 0x80
	s_addk_i32 s45, 0x80
	v_lshl_add_u64 v[14:15], v[14:15], 0, v[16:17]
	v_lshl_add_u64 v[10:11], v[10:11], 0, v[12:13]
	v_lshl_add_u64 v[6:7], v[6:7], 0, v[8:9]
	v_lshl_add_u64 v[2:3], v[2:3], 0, v[4:5]
	v_mov_b32_e32 v4, v1
	v_mov_b32_e32 v5, v1
	v_or_b32_e32 v171, s48, v65
	v_or_b32_e32 v172, s47, v65
	v_or_b32_e32 v173, s46, v65
	v_or_b32_e32 v174, s45, v65
	v_lshl_add_u64 v[150:151], s[2:3], 0, v[14:15]
	v_lshl_add_u64 v[152:153], s[2:3], 0, v[10:11]
	v_lshl_add_u64 v[154:155], s[2:3], 0, v[6:7]
	v_lshl_add_u64 v[156:157], s[2:3], 0, v[2:3]
	v_mov_b32_e32 v2, v1
	v_mov_b32_e32 v3, v1
	v_mov_b64_e32 v[8:9], v[4:5]
	v_mov_b64_e32 v[12:13], v[4:5]
	v_mov_b64_e32 v[16:17], v[4:5]
	v_mov_b64_e32 v[20:21], v[4:5]
	v_mov_b64_e32 v[24:25], v[4:5]
	v_mov_b64_e32 v[28:29], v[4:5]
	v_mov_b64_e32 v[32:33], v[4:5]
	v_mov_b64_e32 v[36:37], v[4:5]
	v_mov_b64_e32 v[40:41], v[4:5]
	v_mov_b64_e32 v[44:45], v[4:5]
	v_mov_b64_e32 v[48:49], v[4:5]
	v_mov_b64_e32 v[52:53], v[4:5]
	v_mov_b64_e32 v[56:57], v[4:5]
	v_mov_b64_e32 v[60:61], v[4:5]
	v_mov_b64_e32 v[64:65], v[4:5]
	s_mov_b32 s44, 0
	v_mul_u32_u24_e32 v170, 0x210, v160
	v_mul_u32_u24_e32 v149, 0x90, v160
	v_readlane_b32 s46, v254, 1
	v_mov_b32_e32 v175, 0xff800000
	v_mov_b32_e32 v159, 0
	v_mov_b64_e32 v[6:7], v[2:3]
	v_mov_b64_e32 v[10:11], v[2:3]
	v_mov_b64_e32 v[14:15], v[2:3]
	v_mov_b64_e32 v[18:19], v[2:3]
	v_mov_b64_e32 v[22:23], v[2:3]
	v_mov_b64_e32 v[26:27], v[2:3]
	v_mov_b64_e32 v[30:31], v[2:3]
	v_mov_b64_e32 v[34:35], v[2:3]
	v_mov_b64_e32 v[38:39], v[2:3]
	v_mov_b64_e32 v[42:43], v[2:3]
	v_mov_b64_e32 v[46:47], v[2:3]
	v_mov_b64_e32 v[50:51], v[2:3]
	v_mov_b64_e32 v[54:55], v[2:3]
	v_mov_b64_e32 v[58:59], v[2:3]
	v_mov_b64_e32 v[62:63], v[2:3]
	s_mov_b32 s15, 0
	v_readlane_b32 s47, v254, 2
; template <int D, int DV, int MODE, int NMAP, int KT> ...
;     ...
;     for (int kt = 0; kt < nkt; ++kt) {
;         __syncthreads();
;         const int cur = (kt & 1) * BUF_BYTES;
;         if (kt + 1 < nkt) { AT_STORE(((kt + 1) & 1) * BUF_BYTES); if (kt + 2 < nkt) AT_LOAD(kt + 2); }
.LBB0_601:
	s_add_i32 s14, s15, 1
	s_bitcmp1_b32 s14, 0
	s_cselect_b32 s16, 0x11400, 0
	s_add_i32 s16, s16, 0
	v_add3_u32 v130, s16, v161, v162
	s_waitcnt lgkmcnt(0)
	s_barrier
	s_waitcnt vmcnt(0)
	ds_write_b128 v130, v[98:101]
	v_add3_u32 v130, s16, v163, v164
	ds_write_b128 v130, v[102:105]
	v_add3_u32 v130, s16, v165, v166
	s_add_i32 s17, s16, s30
	ds_write_b128 v130, v[106:109]
	v_add3_u32 v130, s16, v167, v168
	s_add_i32 s17, s17, s31
	ds_write_b128 v130, v[110:113]
	v_add_u32_e32 v130, s17, v169
	s_add_i32 s17, s16, s33
	s_add_i32 s17, s17, s34
	ds_write_b16 v130, v114 offset:33792
	ds_write_b16_d16_hi v130, v114 offset:33936
	ds_write_b16 v130, v115 offset:34080
	ds_write_b16_d16_hi v130, v115 offset:34224
	ds_write_b16 v130, v116 offset:34368
	ds_write_b16_d16_hi v130, v116 offset:34512
	ds_write_b16 v130, v117 offset:34656
	ds_write_b16_d16_hi v130, v117 offset:34800
	v_add_u32_e32 v130, s17, v169
	s_add_i32 s17, s16, s40
	s_add_i32 s17, s17, s41
	s_add_i32 s16, s16, s42
	ds_write_b16 v130, v118 offset:33792
	ds_write_b16_d16_hi v130, v118 offset:33936
	ds_write_b16 v130, v119 offset:34080
	ds_write_b16_d16_hi v130, v119 offset:34224
	ds_write_b16 v130, v120 offset:34368
	ds_write_b16_d16_hi v130, v120 offset:34512
	ds_write_b16 v130, v121 offset:34656
	ds_write_b16_d16_hi v130, v121 offset:34800
	v_add_u32_e32 v130, s17, v169
	s_add_i32 s16, s16, s43
	ds_write_b16 v130, v122 offset:33792
	ds_write_b16_d16_hi v130, v122 offset:33936
	ds_write_b16 v130, v123 offset:34080
	ds_write_b16_d16_hi v130, v123 offset:34224
	ds_write_b16 v130, v124 offset:34368
	ds_write_b16_d16_hi v130, v124 offset:34512
	ds_write_b16 v130, v125 offset:34656
	ds_write_b16_d16_hi v130, v125 offset:34800
	v_add_u32_e32 v130, s16, v169
	s_cmp_gt_u32 s15, 1
	ds_write_b16 v130, v126 offset:33792
	ds_write_b16_d16_hi v130, v126 offset:33936
	ds_write_b16 v130, v127 offset:34080
	ds_write_b16_d16_hi v130, v127 offset:34224
	ds_write_b16 v130, v128 offset:34368
	ds_write_b16_d16_hi v130, v128 offset:34512
	ds_write_b16 v130, v129 offset:34656
	ds_write_b16_d16_hi v130, v129 offset:34800
	s_cbranch_scc1 .LBB0_603
	v_add_u32_e32 v114, s44, v174
	v_add_u32_e32 v116, s44, v173
	v_add_u32_e32 v122, s44, v172
	v_add_u32_e32 v124, s44, v171
	v_ashrrev_i32_e32 v115, 31, v114
	v_ashrrev_i32_e32 v117, 31, v116
	v_ashrrev_i32_e32 v123, 31, v122
	v_ashrrev_i32_e32 v125, 31, v124
	v_lshlrev_b64 v[114:115], 12, v[114:115]
	v_lshlrev_b64 v[116:117], 12, v[116:117]
	v_lshlrev_b64 v[122:123], 12, v[122:123]
	v_lshlrev_b64 v[124:125], 12, v[124:125]
	v_lshl_add_u64 v[98:99], v[156:157], 0, s[94:95]
	v_lshl_add_u64 v[102:103], v[154:155], 0, s[94:95]
	v_lshl_add_u64 v[106:107], v[152:153], 0, s[94:95]
	v_lshl_add_u64 v[110:111], v[150:151], 0, s[94:95]
	v_lshl_add_u64 v[114:115], s[6:7], 0, v[114:115]
	v_lshl_add_u64 v[118:119], s[8:9], 0, v[116:117]
	v_lshl_add_u64 v[122:123], s[10:11], 0, v[122:123]
	v_lshl_add_u64 v[126:127], s[12:13], 0, v[124:125]
	global_load_dwordx4 v[98:101], v[98:99], off
	s_nop 0
	global_load_dwordx4 v[102:105], v[102:103], off
	s_nop 0
	global_load_dwordx4 v[106:109], v[106:107], off
	s_nop 0
	global_load_dwordx4 v[110:113], v[110:111], off
	s_nop 0
	global_load_dwordx4 v[114:117], v[114:115], off offset:2048
	s_nop 0
	global_load_dwordx4 v[118:121], v[118:119], off offset:2048
	s_nop 0
	global_load_dwordx4 v[122:125], v[122:123], off offset:2048
	s_nop 0
	global_load_dwordx4 v[126:129], v[126:127], off offset:2048

; __device__ __forceinline__ unsigned cvt_pk_bf16(float lo, float hi) { unsigned r; asm volatile("v_cvt_pk_bf16_f32 %0, %1, %2" : "=v"(r) : "v"(lo), "v"(hi)); return r; }
; #define LAS __attribute__((address_space(3)))
; __global__ void __launch_bounds__(512, 2) mega_fwd(Params P) {
;     ...
;                   { LAS unsigned* CV = (LAS unsigned*)(lds + 131072); for (int i = tid; i < nin; i += 512) CV[i] = (cvt_pk_bf16(cvk[i], 0.f) & 0xffffu) | (cvt_pk_bf16(cvk[5632 + i], 0.f) << 16);
.LBB0_648:
	v_add_co_u32_e32 v6, vcc, 0xffffa800, v4
	v_add_u32_e32 v3, 0x200, v3
	s_nop 0
	v_addc_co_u32_e32 v7, vcc, -1, v5, vcc
	global_load_dword v6, v[6:7], off
	s_waitcnt vmcnt(0) lgkmcnt(0)
	v_cvt_pk_bf16_f32 v6, v6, v1
	global_load_dword v7, v[4:5], off
	v_and_b32_e32 v6, 0xffff, v6
	v_cmp_le_i32_e32 vcc, s46, v3
	s_waitcnt vmcnt(0) lgkmcnt(0)
	v_cvt_pk_bf16_f32 v7, v7, v1
	s_or_b64 s[6:7], vcc, s[6:7]
	v_lshl_or_b32 v6, v7, 16, v6
	v_lshl_add_u64 v[4:5], v[4:5], 0, s[42:43]
	ds_write_b32 v0, v6
	v_add_u32_e32 v0, 0x800, v0
	s_andn2_b64 exec, exec, s[6:7]
	s_cbranch_execnz .LBB0_648

; #define PG8_STAGE(bufoff, gbase, voff) do { _Pragma("unroll") for (int _i = 0; _i < 2; ++_i) \
;         __builtin_amdgcn_global_load_lds((const unsigned*)((const char*)(gbase) + (voff)[_i]), (PG8_LAS unsigned*)(lds + (bufoff) + ldsw + _i * 8192), 16, 0, 0); } while (0)
; #define PG8_LDA(dst, b, h) do { _Pragma("unroll") for (int m = 0; m < 4; ++m) _Pragma("unroll") for (int k = 0; k < 2; ++k) dst[m][k] = *(const PG8_LAS bf16x8*)(lds + PG8_SA(b, h) + aoff + m * 2048 + k * 1024); } while (0)
; #define PG8_LDB(dst, b, h) do { _Pragma("unroll") for (int n = 0; n < 2; ++n) _Pragma("unroll") for (int k = 0; k < 2; ++k) dst[n][k] = *(const PG8_LAS bf16x8*)(lds + PG8_SB(b, h) + boff + n * 2048 + k * 1024); } while (0)
; #define PG8_MMA(ai, bj, At, Bt) do { __builtin_amdgcn_s_setprio(1); _Pragma("unroll") for (int m = 0; m < 4; ++m) _Pragma("unroll") for (int n = 0; n < 2; ++n) _Pragma("unroll") for (int k = 0; k < 2; ++k) \
;         acc[ai][bj][m][n] = __builtin_amdgcn_mfma_f32_16x16x32_bf16(Bt[n][k], At[m][k], acc[ai][bj][m][n], 0, 0, 0); __builtin_amdgcn_s_setprio(0); } while (0)
; #define PG8_WAIT_V(n) asm volatile("s_waitcnt vmcnt(" #n ")" ::: "memory")
; #define PG8_WAIT_L(n) asm volatile("s_waitcnt lgkmcnt(" #n ")" ::: "memory")
; template <class Epi, class Sched, bool ALIGN_EPI = false, bool SP2 = false>
; __device__ __forceinline__ void gemm_phase(PG8_LAS unsigned char* lds, const Gemm g, const Sched& S, const Epi& E) {
;     ...
;             const bool last = (t == nt - 2);
;             const char* a1 = cA + (size_t)(t + 1) * kstep;
;             const char* a2 = last ? nA : cA + (size_t)(t + 2) * kstep; const char* b2 = last ? nB : cB + (size_t)(t + 2) * kstep;
;             const char* a3 = a2 + kstep; const char* b3 = b2 + kstep;
;             if (last && has_next) S.a_ready(nxt);
;             if constexpr (SP2) {
;             PG8_LDB(B0, 0, 0); PG8_LDB(B1, 0, 1); PG8_SCHED; PG8_LDA(At, 0, 0); PG8_STAGE(PG8_SA(1, 1), a1 + hstep, voffA);
;             PG8_WAIT_V(8); PG8_WAIT_L(0); PG8_BAR; PG8_MMA(0, 0, At, B0); PG8_MMA(0, 1, At, B1); PG8_BAR; PG8_SCHED;
;             PG8_LDA(At, 0, 1); PG8_STAGE(PG8_SB(0, 0), b2, voffB); PG8_STAGE(PG8_SB(0, 1), b2 + hstep, voffB); PG8_STAGE(PG8_SA(0, 0), a2, voffA);
;             PG8_WAIT_V(8); PG8_WAIT_L(0); PG8_BAR; PG8_MMA(1, 0, At, B0); PG8_MMA(1, 1, At, B1); PG8_BAR; PG8_SCHED;
.LBB0_665:
	s_add_i32 s67, s28, 2
	s_add_u32 s74, s26, 0x80
	s_addc_u32 s29, s27, 0
	s_add_i32 s76, 0, 0x10000
	s_cmp_eq_u32 s46, s28
	s_cselect_b32 s29, s5, s29
	s_cselect_b32 s28, s4, s74
	v_add_u32_e32 v0, s76, v201
	s_cselect_b32 s75, s25, s61
	s_cselect_b32 s74, s24, s56
	s_add_i32 s77, 0, 0x14000
	ds_read_b128 v[130:133], v0
	ds_read_b128 v[134:137], v0 offset:1024
	ds_read_b128 v[138:141], v0 offset:2048
	ds_read_b128 v[142:145], v0 offset:3072
	v_add_u32_e32 v0, s77, v201
	ds_read_b128 v[160:163], v0
	ds_read_b128 v[164:167], v0 offset:1024
	ds_read_b128 v[168:171], v0 offset:2048
	ds_read_b128 v[172:175], v0 offset:3072
	v_lshl_add_u64 v[184:185], s[26:27], 0, v[156:157]
	s_add_i32 m0, s34, 0xc000
	ds_read_b128 v[176:179], v229
	ds_read_b128 v[180:183], v229 offset:1024
	ds_read_b128 v[194:197], v229 offset:2048
	ds_read_b128 v[202:205], v229 offset:3072
	ds_read_b128 v[230:233], v229 offset:4096
	ds_read_b128 v[234:237], v229 offset:5120
	ds_read_b128 v[238:241], v229 offset:6144
	ds_read_b128 v[242:245], v229 offset:7168
	global_load_lds_dwordx4 v[184:185], off
	v_lshl_add_u64 v[184:185], s[26:27], 0, v[154:155]
	s_add_i32 m0, s34, 0xe000
	s_nop 0
	global_load_lds_dwordx4 v[184:185], off
	s_waitcnt vmcnt(8)
	s_waitcnt lgkmcnt(0)
	s_barrier
	s_setprio 1
	v_mfma_f32_16x16x32_bf16 v[126:129], v[130:133], v[176:179], v[126:129]
	v_mfma_f32_16x16x32_bf16 v[122:125], v[138:141], v[176:179], v[122:125]
	v_mfma_f32_16x16x32_bf16 v[110:113], v[130:133], v[194:197], v[110:113]
	v_mfma_f32_16x16x32_bf16 v[106:109], v[138:141], v[194:197], v[106:109]
	v_mfma_f32_16x16x32_bf16 v[94:97], v[130:133], v[230:233], v[94:97]
	v_mfma_f32_16x16x32_bf16 v[90:93], v[138:141], v[230:233], v[90:93]
	v_mfma_f32_16x16x32_bf16 v[78:81], v[130:133], v[238:241], v[78:81]
	v_mfma_f32_16x16x32_bf16 v[74:77], v[138:141], v[238:241], v[74:77]
	v_mfma_f32_16x16x32_bf16 v[126:129], v[134:137], v[180:183], v[126:129]
	v_mfma_f32_16x16x32_bf16 v[122:125], v[142:145], v[180:183], v[122:125]
	v_mfma_f32_16x16x32_bf16 v[110:113], v[134:137], v[202:205], v[110:113]
	v_mfma_f32_16x16x32_bf16 v[106:109], v[142:145], v[202:205], v[106:109]
	v_mfma_f32_16x16x32_bf16 v[94:97], v[134:137], v[234:237], v[94:97]
	v_mfma_f32_16x16x32_bf16 v[90:93], v[142:145], v[234:237], v[90:93]
	v_mfma_f32_16x16x32_bf16 v[78:81], v[134:137], v[242:245], v[78:81]
	v_mfma_f32_16x16x32_bf16 v[74:77], v[142:145], v[242:245], v[74:77]
	s_setprio 0
	s_setprio 1
	v_mfma_f32_16x16x32_bf16 v[118:121], v[160:163], v[176:179], v[118:121]
	v_mfma_f32_16x16x32_bf16 v[114:117], v[168:171], v[176:179], v[114:117]
	v_mfma_f32_16x16x32_bf16 v[102:105], v[160:163], v[194:197], v[102:105]
	v_mfma_f32_16x16x32_bf16 v[98:101], v[168:171], v[194:197], v[98:101]
	v_mfma_f32_16x16x32_bf16 v[86:89], v[160:163], v[230:233], v[86:89]
	v_mfma_f32_16x16x32_bf16 v[82:85], v[168:171], v[230:233], v[82:85]
	v_mfma_f32_16x16x32_bf16 v[70:73], v[160:163], v[238:241], v[70:73]
	v_mfma_f32_16x16x32_bf16 v[66:69], v[168:171], v[238:241], v[66:69]
	v_mfma_f32_16x16x32_bf16 v[118:121], v[164:167], v[180:183], v[118:121]
	v_mfma_f32_16x16x32_bf16 v[114:117], v[172:175], v[180:183], v[114:117]
	v_mfma_f32_16x16x32_bf16 v[102:105], v[164:167], v[202:205], v[102:105]
	v_mfma_f32_16x16x32_bf16 v[98:101], v[172:175], v[202:205], v[98:101]
	v_mfma_f32_16x16x32_bf16 v[86:89], v[164:167], v[234:237], v[86:89]
	v_mfma_f32_16x16x32_bf16 v[82:85], v[172:175], v[234:237], v[82:85]
	v_mfma_f32_16x16x32_bf16 v[70:73], v[164:167], v[242:245], v[70:73]
	v_mfma_f32_16x16x32_bf16 v[66:69], v[172:175], v[242:245], v[66:69]
	s_setprio 0
	s_barrier
	s_add_i32 s76, s76, s31
	v_lshl_add_u64 v[184:185], s[74:75], 0, v[150:151]
	s_mov_b32 m0, s76
	ds_read_b128 v[176:179], v229 offset:16384
	ds_read_b128 v[180:183], v229 offset:17408
	ds_read_b128 v[194:197], v229 offset:18432
	ds_read_b128 v[202:205], v229 offset:19456
	ds_read_b128 v[230:233], v229 offset:20480
	ds_read_b128 v[234:237], v229 offset:21504
	ds_read_b128 v[238:241], v229 offset:22528
	ds_read_b128 v[242:245], v229 offset:23552
	global_load_lds_dwordx4 v[184:185], off
	s_add_i32 m0, s76, 0x2000
	v_lshl_add_u64 v[198:199], s[74:75], 0, v[146:147]
	s_add_u32 s74, s74, s10
	s_addc_u32 s75, s75, s11
	s_add_i32 s76, s77, s31
	global_load_lds_dwordx4 v[198:199], off
	v_lshl_add_u64 v[212:213], s[74:75], 0, v[150:151]
	s_mov_b32 m0, s76
	v_lshl_add_u64 v[214:215], s[74:75], 0, v[146:147]
	global_load_lds_dwordx4 v[212:213], off
	s_add_i32 m0, s76, 0x2000
	v_lshl_add_u64 v[246:247], s[28:29], 0, v[152:153]
	global_load_lds_dwordx4 v[214:215], off
	s_mov_b32 m0, s34
	v_lshl_add_u64 v[248:249], s[28:29], 0, v[148:149]
	global_load_lds_dwordx4 v[246:247], off
	s_mov_b32 m0, s40
	s_nop 0
	global_load_lds_dwordx4 v[248:249], off
	s_waitcnt vmcnt(8)
	s_waitcnt lgkmcnt(0)
	s_barrier
; #define PG8_STAGE(bufoff, gbase, voff) do { _Pragma("unroll") for (int _i = 0; _i < 2; ++_i) \
;         __builtin_amdgcn_global_load_lds((const unsigned*)((const char*)(gbase) + (voff)[_i]), (PG8_LAS unsigned*)(lds + (bufoff) + ldsw + _i * 8192), 16, 0, 0); } while (0)
; #define PG8_LDA(dst, b, h) do { _Pragma("unroll") for (int m = 0; m < 4; ++m) _Pragma("unroll") for (int k = 0; k < 2; ++k) dst[m][k] = *(const PG8_LAS bf16x8*)(lds + PG8_SA(b, h) + aoff + m * 2048 + k * 1024); } while (0)
; #define PG8_LDB(dst, b, h) do { _Pragma("unroll") for (int n = 0; n < 2; ++n) _Pragma("unroll") for (int k = 0; k < 2; ++k) dst[n][k] = *(const PG8_LAS bf16x8*)(lds + PG8_SB(b, h) + boff + n * 2048 + k * 1024); } while (0)
; #define PG8_MMA(ai, bj, At, Bt) do { __builtin_amdgcn_s_setprio(1); _Pragma("unroll") for (int m = 0; m < 4; ++m) _Pragma("unroll") for (int n = 0; n < 2; ++n) _Pragma("unroll") for (int k = 0; k < 2; ++k) \
;         acc[ai][bj][m][n] = __builtin_amdgcn_mfma_f32_16x16x32_bf16(Bt[n][k], At[m][k], acc[ai][bj][m][n], 0, 0, 0); __builtin_amdgcn_s_setprio(0); } while (0)
; #define PG8_WAIT_V(n) asm volatile("s_waitcnt vmcnt(" #n ")" ::: "memory")
; #define PG8_WAIT_L(n) asm volatile("s_waitcnt lgkmcnt(" #n ")" ::: "memory")
; #define PG8_BAR __builtin_amdgcn_s_barrier()
; #define PG8_SCHED __builtin_amdgcn_sched_barrier(0)
; template <class Epi, class Sched, bool ALIGN_EPI = false, bool SP2 = false>
; __device__ __forceinline__ void gemm_phase(PG8_LAS unsigned char* lds, const Gemm g, const Sched& S, const Epi& E) {
;     ...
;             PG8_WAIT_V(8); PG8_WAIT_L(0); PG8_BAR; PG8_MMA(0, 0, At, B0); PG8_MMA(0, 1, At, B1); PG8_BAR; PG8_SCHED;
;             PG8_LDA(At, 0, 1); PG8_STAGE(PG8_SB(0, 0), b2, voffB); PG8_STAGE(PG8_SB(0, 1), b2 + hstep, voffB); PG8_STAGE(PG8_SA(0, 0), a2, voffA);
;             PG8_WAIT_V(8); PG8_WAIT_L(0); PG8_BAR; PG8_MMA(1, 0, At, B0); PG8_MMA(1, 1, At, B1); PG8_BAR; PG8_SCHED;
;             PG8_LDB(B0, 1, 0); PG8_LDB(B1, 1, 1); PG8_SCHED; PG8_LDA(At, 1, 0); PG8_STAGE(PG8_SA(0, 1), a2 + hstep, voffA);
;             PG8_WAIT_V(8); PG8_WAIT_L(0); PG8_BAR; PG8_MMA(0, 0, At, B0); PG8_MMA(0, 1, At, B1); PG8_BAR; PG8_SCHED;
	s_setprio 1
	v_mfma_f32_16x16x32_bf16 v[62:65], v[130:133], v[176:179], v[62:65]
	v_mfma_f32_16x16x32_bf16 v[58:61], v[138:141], v[176:179], v[58:61]
	v_mfma_f32_16x16x32_bf16 v[46:49], v[130:133], v[194:197], v[46:49]
	v_mfma_f32_16x16x32_bf16 v[42:45], v[138:141], v[194:197], v[42:45]
	v_mfma_f32_16x16x32_bf16 v[30:33], v[130:133], v[230:233], v[30:33]
	v_mfma_f32_16x16x32_bf16 v[26:29], v[138:141], v[230:233], v[26:29]
	v_mfma_f32_16x16x32_bf16 v[14:17], v[130:133], v[238:241], v[14:17]
	v_mfma_f32_16x16x32_bf16 v[10:13], v[138:141], v[238:241], v[10:13]
	v_mfma_f32_16x16x32_bf16 v[62:65], v[134:137], v[180:183], v[62:65]
	v_mfma_f32_16x16x32_bf16 v[58:61], v[142:145], v[180:183], v[58:61]
	v_mfma_f32_16x16x32_bf16 v[46:49], v[134:137], v[202:205], v[46:49]
	v_mfma_f32_16x16x32_bf16 v[42:45], v[142:145], v[202:205], v[42:45]
	v_mfma_f32_16x16x32_bf16 v[30:33], v[134:137], v[234:237], v[30:33]
	v_mfma_f32_16x16x32_bf16 v[26:29], v[142:145], v[234:237], v[26:29]
	v_mfma_f32_16x16x32_bf16 v[14:17], v[134:137], v[242:245], v[14:17]
	v_mfma_f32_16x16x32_bf16 v[10:13], v[142:145], v[242:245], v[10:13]
	s_setprio 0
	s_setprio 1
	v_mfma_f32_16x16x32_bf16 v[54:57], v[160:163], v[176:179], v[54:57]
	v_mfma_f32_16x16x32_bf16 v[50:53], v[168:171], v[176:179], v[50:53]
	v_mfma_f32_16x16x32_bf16 v[38:41], v[160:163], v[194:197], v[38:41]
	v_mfma_f32_16x16x32_bf16 v[34:37], v[168:171], v[194:197], v[34:37]
	v_mfma_f32_16x16x32_bf16 v[22:25], v[160:163], v[230:233], v[22:25]
	v_mfma_f32_16x16x32_bf16 v[18:21], v[168:171], v[230:233], v[18:21]
	v_mfma_f32_16x16x32_bf16 v[6:9], v[160:163], v[238:241], v[6:9]
	v_mfma_f32_16x16x32_bf16 v[2:5], v[168:171], v[238:241], v[2:5]
	v_mfma_f32_16x16x32_bf16 v[54:57], v[164:167], v[180:183], v[54:57]
	v_mfma_f32_16x16x32_bf16 v[50:53], v[172:175], v[180:183], v[50:53]
	v_mfma_f32_16x16x32_bf16 v[38:41], v[164:167], v[202:205], v[38:41]
	v_mfma_f32_16x16x32_bf16 v[34:37], v[172:175], v[202:205], v[34:37]
	v_mfma_f32_16x16x32_bf16 v[22:25], v[164:167], v[234:237], v[22:25]
	v_mfma_f32_16x16x32_bf16 v[18:21], v[172:175], v[234:237], v[18:21]
	v_mfma_f32_16x16x32_bf16 v[6:9], v[164:167], v[242:245], v[6:9]
	v_mfma_f32_16x16x32_bf16 v[2:5], v[172:175], v[242:245], v[2:5]
	s_setprio 0
	s_barrier
	s_add_i32 s74, 0, 0x18000
	v_add_u32_e32 v0, s74, v201
	s_add_i32 s75, 0, 0x1c000
	ds_read_b128 v[130:133], v0
	ds_read_b128 v[134:137], v0 offset:1024
	ds_read_b128 v[138:141], v0 offset:2048
	ds_read_b128 v[142:145], v0 offset:3072
	v_add_u32_e32 v0, s75, v201
	ds_read_b128 v[160:163], v0
	ds_read_b128 v[164:167], v0 offset:1024
	ds_read_b128 v[168:171], v0 offset:2048
	ds_read_b128 v[172:175], v0 offset:3072
	s_add_u32 s28, s28, s10
	s_addc_u32 s29, s29, s11
	s_mov_b32 m0, s41
	v_lshl_add_u64 v[250:251], s[28:29], 0, v[152:153]
	ds_read_b128 v[176:179], v229 offset:32768
	ds_read_b128 v[180:183], v229 offset:33792
	ds_read_b128 v[194:197], v229 offset:34816
	ds_read_b128 v[202:205], v229 offset:35840
	ds_read_b128 v[230:233], v229 offset:36864
	ds_read_b128 v[234:237], v229 offset:37888
	ds_read_b128 v[238:241], v229 offset:38912
	ds_read_b128 v[242:245], v229 offset:39936
	global_load_lds_dwordx4 v[250:251], off
	v_lshl_add_u64 v[250:251], s[28:29], 0, v[148:149]
	s_mov_b32 m0, s42
	s_nop 0
	global_load_lds_dwordx4 v[250:251], off
	s_waitcnt vmcnt(8)
	s_waitcnt lgkmcnt(0)
	s_barrier
	s_setprio 1
	v_mfma_f32_16x16x32_bf16 v[126:129], v[130:133], v[176:179], v[126:129]
	v_mfma_f32_16x16x32_bf16 v[122:125], v[138:141], v[176:179], v[122:125]
	v_mfma_f32_16x16x32_bf16 v[110:113], v[130:133], v[194:197], v[110:113]
	v_mfma_f32_16x16x32_bf16 v[106:109], v[138:141], v[194:197], v[106:109]
	v_mfma_f32_16x16x32_bf16 v[94:97], v[130:133], v[230:233], v[94:97]
	v_mfma_f32_16x16x32_bf16 v[90:93], v[138:141], v[230:233], v[90:93]
	v_mfma_f32_16x16x32_bf16 v[78:81], v[130:133], v[238:241], v[78:81]
	v_mfma_f32_16x16x32_bf16 v[74:77], v[138:141], v[238:241], v[74:77]
	v_mfma_f32_16x16x32_bf16 v[126:129], v[134:137], v[180:183], v[126:129]
	v_mfma_f32_16x16x32_bf16 v[122:125], v[142:145], v[180:183], v[122:125]
	v_mfma_f32_16x16x32_bf16 v[110:113], v[134:137], v[202:205], v[110:113]
	v_mfma_f32_16x16x32_bf16 v[106:109], v[142:145], v[202:205], v[106:109]
	v_mfma_f32_16x16x32_bf16 v[94:97], v[134:137], v[234:237], v[94:97]
	v_mfma_f32_16x16x32_bf16 v[90:93], v[142:145], v[234:237], v[90:93]
	v_mfma_f32_16x16x32_bf16 v[78:81], v[134:137], v[242:245], v[78:81]
	v_mfma_f32_16x16x32_bf16 v[74:77], v[142:145], v[242:245], v[74:77]
	s_setprio 0
	s_setprio 1
	v_mfma_f32_16x16x32_bf16 v[118:121], v[160:163], v[176:179], v[118:121]
	v_mfma_f32_16x16x32_bf16 v[114:117], v[168:171], v[176:179], v[114:117]
	v_mfma_f32_16x16x32_bf16 v[102:105], v[160:163], v[194:197], v[102:105]
	v_mfma_f32_16x16x32_bf16 v[98:101], v[168:171], v[194:197], v[98:101]
	v_mfma_f32_16x16x32_bf16 v[86:89], v[160:163], v[230:233], v[86:89]
	v_mfma_f32_16x16x32_bf16 v[82:85], v[168:171], v[230:233], v[82:85]
	v_mfma_f32_16x16x32_bf16 v[70:73], v[160:163], v[238:241], v[70:73]
	v_mfma_f32_16x16x32_bf16 v[66:69], v[168:171], v[238:241], v[66:69]
	v_mfma_f32_16x16x32_bf16 v[118:121], v[164:167], v[180:183], v[118:121]
	v_mfma_f32_16x16x32_bf16 v[114:117], v[172:175], v[180:183], v[114:117]
	v_mfma_f32_16x16x32_bf16 v[102:105], v[164:167], v[202:205], v[102:105]
	v_mfma_f32_16x16x32_bf16 v[98:101], v[172:175], v[202:205], v[98:101]
	v_mfma_f32_16x16x32_bf16 v[86:89], v[164:167], v[234:237], v[86:89]
	v_mfma_f32_16x16x32_bf16 v[82:85], v[172:175], v[234:237], v[82:85]
	v_mfma_f32_16x16x32_bf16 v[70:73], v[164:167], v[242:245], v[70:73]
	v_mfma_f32_16x16x32_bf16 v[66:69], v[172:175], v[242:245], v[66:69]
	s_setprio 0
	s_barrier
; #define PG8_STAGE(bufoff, gbase, voff) do { _Pragma("unroll") for (int _i = 0; _i < 2; ++_i) \
;         __builtin_amdgcn_global_load_lds((const unsigned*)((const char*)(gbase) + (voff)[_i]), (PG8_LAS unsigned*)(lds + (bufoff) + ldsw + _i * 8192), 16, 0, 0); } while (0)
; #define PG8_LDA(dst, b, h) do { _Pragma("unroll") for (int m = 0; m < 4; ++m) _Pragma("unroll") for (int k = 0; k < 2; ++k) dst[m][k] = *(const PG8_LAS bf16x8*)(lds + PG8_SA(b, h) + aoff + m * 2048 + k * 1024); } while (0)
; #define PG8_MMA(ai, bj, At, Bt) do { __builtin_amdgcn_s_setprio(1); _Pragma("unroll") for (int m = 0; m < 4; ++m) _Pragma("unroll") for (int n = 0; n < 2; ++n) _Pragma("unroll") for (int k = 0; k < 2; ++k) \
;         acc[ai][bj][m][n] = __builtin_amdgcn_mfma_f32_16x16x32_bf16(Bt[n][k], At[m][k], acc[ai][bj][m][n], 0, 0, 0); __builtin_amdgcn_s_setprio(0); } while (0)
; #define PG8_WAIT_V(n) asm volatile("s_waitcnt vmcnt(" #n ")" ::: "memory")
; #define PG8_WAIT_L(n) asm volatile("s_waitcnt lgkmcnt(" #n ")" ::: "memory")
; #define PG8_BAR __builtin_amdgcn_s_barrier()
; #define PG8_SCHED __builtin_amdgcn_sched_barrier(0)
; template <class Epi, class Sched, bool ALIGN_EPI = false, bool SP2 = false>
; __device__ __forceinline__ void gemm_phase(PG8_LAS unsigned char* lds, const Gemm g, const Sched& S, const Epi& E) {
;     ...
;             PG8_LDA(At, 1, 1); PG8_STAGE(PG8_SB(1, 0), b3, voffB); PG8_STAGE(PG8_SB(1, 1), b3 + hstep, voffB); PG8_STAGE(PG8_SA(1, 0), a3, voffA);
;             PG8_WAIT_V(8); PG8_WAIT_L(0); PG8_BAR; PG8_MMA(1, 0, At, B0); PG8_MMA(1, 1, At, B1); PG8_BAR; PG8_SCHED;
	s_add_i32 s28, s74, s31
	v_lshl_add_u64 v[184:185], v[184:185], 0, s[38:39]
	s_mov_b32 m0, s28
	ds_read_b128 v[176:179], v229 offset:49152
	ds_read_b128 v[180:183], v229 offset:50176
	ds_read_b128 v[194:197], v229 offset:51200
	ds_read_b128 v[202:205], v229 offset:52224
	ds_read_b128 v[230:233], v229 offset:53248
	ds_read_b128 v[234:237], v229 offset:54272
	ds_read_b128 v[238:241], v229 offset:55296
	ds_read_b128 v[242:245], v229 offset:56320
	global_load_lds_dwordx4 v[184:185], off
	v_lshl_add_u64 v[184:185], v[198:199], 0, s[38:39]
	s_add_i32 m0, s28, 0x2000
	s_add_i32 s28, s75, s31
	global_load_lds_dwordx4 v[184:185], off
	v_lshl_add_u64 v[184:185], v[212:213], 0, s[38:39]
	s_mov_b32 m0, s28
	s_nop 0
	global_load_lds_dwordx4 v[184:185], off
	v_lshl_add_u64 v[184:185], v[214:215], 0, s[38:39]
	s_add_i32 m0, s28, 0x2000
	s_nop 0
	global_load_lds_dwordx4 v[184:185], off
	v_lshl_add_u64 v[184:185], v[246:247], 0, s[38:39]
	s_mov_b32 m0, s44
	s_nop 0
	global_load_lds_dwordx4 v[184:185], off
	v_lshl_add_u64 v[184:185], v[248:249], 0, s[38:39]
	s_mov_b32 m0, s45
	s_nop 0
	global_load_lds_dwordx4 v[184:185], off
	s_waitcnt vmcnt(8)
	s_waitcnt lgkmcnt(0)
	s_barrier
	s_setprio 1
	v_mfma_f32_16x16x32_bf16 v[62:65], v[130:133], v[176:179], v[62:65]
	v_mfma_f32_16x16x32_bf16 v[58:61], v[138:141], v[176:179], v[58:61]
	v_mfma_f32_16x16x32_bf16 v[46:49], v[130:133], v[194:197], v[46:49]
	v_mfma_f32_16x16x32_bf16 v[42:45], v[138:141], v[194:197], v[42:45]
	v_mfma_f32_16x16x32_bf16 v[30:33], v[130:133], v[230:233], v[30:33]
	v_mfma_f32_16x16x32_bf16 v[26:29], v[138:141], v[230:233], v[26:29]
	v_mfma_f32_16x16x32_bf16 v[14:17], v[130:133], v[238:241], v[14:17]
	v_mfma_f32_16x16x32_bf16 v[10:13], v[138:141], v[238:241], v[10:13]
	v_mfma_f32_16x16x32_bf16 v[62:65], v[134:137], v[180:183], v[62:65]
	v_mfma_f32_16x16x32_bf16 v[58:61], v[142:145], v[180:183], v[58:61]
	v_mfma_f32_16x16x32_bf16 v[46:49], v[134:137], v[202:205], v[46:49]
	v_mfma_f32_16x16x32_bf16 v[42:45], v[142:145], v[202:205], v[42:45]
	v_mfma_f32_16x16x32_bf16 v[30:33], v[134:137], v[234:237], v[30:33]
	v_mfma_f32_16x16x32_bf16 v[26:29], v[142:145], v[234:237], v[26:29]
	v_mfma_f32_16x16x32_bf16 v[14:17], v[134:137], v[242:245], v[14:17]
	v_mfma_f32_16x16x32_bf16 v[10:13], v[142:145], v[242:245], v[10:13]
	s_setprio 0
	s_setprio 1
	v_mfma_f32_16x16x32_bf16 v[54:57], v[160:163], v[176:179], v[54:57]
	v_mfma_f32_16x16x32_bf16 v[50:53], v[168:171], v[176:179], v[50:53]
	v_mfma_f32_16x16x32_bf16 v[38:41], v[160:163], v[194:197], v[38:41]
	v_mfma_f32_16x16x32_bf16 v[34:37], v[168:171], v[194:197], v[34:37]
	v_mfma_f32_16x16x32_bf16 v[22:25], v[160:163], v[230:233], v[22:25]
	v_mfma_f32_16x16x32_bf16 v[18:21], v[168:171], v[230:233], v[18:21]
	v_mfma_f32_16x16x32_bf16 v[6:9], v[160:163], v[238:241], v[6:9]
	v_mfma_f32_16x16x32_bf16 v[2:5], v[168:171], v[238:241], v[2:5]
	v_mfma_f32_16x16x32_bf16 v[54:57], v[164:167], v[180:183], v[54:57]
	v_mfma_f32_16x16x32_bf16 v[50:53], v[172:175], v[180:183], v[50:53]
	v_mfma_f32_16x16x32_bf16 v[38:41], v[164:167], v[202:205], v[38:41]
	v_mfma_f32_16x16x32_bf16 v[34:37], v[172:175], v[202:205], v[34:37]
	v_mfma_f32_16x16x32_bf16 v[22:25], v[164:167], v[234:237], v[22:25]
	v_mfma_f32_16x16x32_bf16 v[18:21], v[172:175], v[234:237], v[18:21]
	v_mfma_f32_16x16x32_bf16 v[6:9], v[164:167], v[242:245], v[6:9]
	v_mfma_f32_16x16x32_bf16 v[2:5], v[172:175], v[242:245], v[2:5]
	s_setprio 0
	s_barrier
	s_add_u32 s56, s56, 0x100
	s_addc_u32 s61, s61, 0
	s_add_u32 s26, s26, 0x100
	s_addc_u32 s27, s27, 0
	s_cmp_ge_i32 s67, s43
	s_mov_b32 s28, s67
	s_cbranch_scc0 .LBB0_665
	s_mov_b64 s[76:77], 0x28000

; __device__ __forceinline__ float xsum_rows(float v) { return xsum32(xsum16(v)); }
; __device__ __forceinline__ void ln_row(const float* st, int row, int fq, float& rs, float& ms) {
;     f32x2 v = *(const f32x2*)(st + (unsigned)(8 * row + 2 * fq));
;     v.x = xsum_rows(v.x); v.y = xsum_rows(v.y);
;     const float mean = v.x * (1.0f / 1024.0f); const float var = v.y * (1.0f / 1024.0f) - mean * mean;
;     rs = __builtin_amdgcn_rsqf(var + 1e-5f); ms = rs * mean;
; }
;     __device__ __forceinline__ void operator()(const f32x4 (&acc)[2][2][4][2], const Unit& u, int wr, int wc, int fr, int fq, PG8_LAS unsigned char* ldsb) const {
;     ...
;             if (TAG[wr] != u.pm) {
; #pragma unroll
;                 for (int ai = 0; ai < 2; ++ai)
; #pragma unroll
;                     for (int m = 0; m < 4; ++m) { ln_row(ln.st, row0 + ai * HALF + m * 16, fq, rsv[ai][m], msv[ai][m]);
;                         f32x2 pr; pr.x = rsv[ai][m]; pr.y = msv[ai][m]; ST[ai * HALF + wr * 64 + m * 16 + fr] = pr; }
;                 asm volatile("s_waitcnt lgkmcnt(0)" ::: "memory");
;                 TAG[wr] = u.pm;
.LBB0_669:
	v_mov_b32_e32 v0, s47
	ds_read_b32 v0, v0
	v_lshl_add_u32 v230, s53, 8, v159
	s_mov_b64 s[26:27], -1
	s_waitcnt lgkmcnt(0)
	v_cmp_eq_u32_e32 vcc, s53, v0
	s_cbranch_vccnz .LBB0_671
	v_lshlrev_b32_e32 v158, 3, v230
	v_or_b32_e32 v0, v158, v207
	v_lshl_add_u64 v[130:131], v[0:1], 2, s[18:19]
	global_load_dwordx2 v[132:133], v[130:131], off
	s_mov_b64 s[26:27], 0
	s_waitcnt vmcnt(0) lgkmcnt(0)
	v_mov_b32_e32 v0, v132
	s_nop 1
	v_permlane16_swap_b32_e32 v132, v0
	v_add_f32_e32 v135, v132, v0
	v_mov_b32_e32 v0, v133
	s_nop 1
	v_permlane16_swap_b32_e32 v133, v0
	v_add_f32_e32 v134, v133, v0
	v_mov_b32_e32 v137, v135
	v_mov_b32_e32 v136, v134
	s_nop 0
	v_permlane32_swap_b32_e32 v135, v137
	v_permlane32_swap_b32_e32 v134, v136
	v_pk_add_f32 v[132:133], v[134:135], v[136:137]
	s_nop 0
	v_pk_mul_f32 v[132:133], v[132:133], s[68:69] op_sel_hi:[1,0]
	s_nop 0
	v_fma_f32 v0, -v133, v133, v132
	v_add_f32_e32 v0, 0x3727c5ac, v0
	v_rsq_f32_e32 v142, v0
	s_nop 0
	v_mul_f32_e32 v143, v133, v142
	ds_write_b64 v209, v[142:143]
	global_load_dwordx2 v[132:133], v[130:131], off offset:512
	v_mov_b32_e32 v214, v143
	s_waitcnt vmcnt(0) lgkmcnt(0)
	v_mov_b32_e32 v0, v132
	s_nop 1
	v_permlane16_swap_b32_e32 v132, v0
	v_add_f32_e32 v135, v132, v0
	v_mov_b32_e32 v0, v133
	s_nop 1
	v_permlane16_swap_b32_e32 v133, v0
	v_add_f32_e32 v134, v133, v0
	v_mov_b32_e32 v137, v135
	v_mov_b32_e32 v136, v134
	s_nop 0
	v_permlane32_swap_b32_e32 v135, v137
	v_permlane32_swap_b32_e32 v134, v136
	v_pk_add_f32 v[132:133], v[134:135], v[136:137]
	s_nop 0
	v_pk_mul_f32 v[132:133], v[132:133], s[68:69] op_sel_hi:[1,0]
	s_nop 0
	v_fma_f32 v0, -v133, v133, v132
	v_add_f32_e32 v0, 0x3727c5ac, v0
	v_rsq_f32_e32 v144, v0
	s_nop 0
	v_mul_f32_e32 v145, v133, v144
	ds_write_b64 v209, v[144:145] offset:128
	global_load_dwordx2 v[132:133], v[130:131], off offset:1024
	v_mov_b32_e32 v212, v145
	s_waitcnt vmcnt(0) lgkmcnt(0)
	v_mov_b32_e32 v0, v132
	s_nop 1
	v_permlane16_swap_b32_e32 v132, v0
	v_add_f32_e32 v135, v132, v0
	v_mov_b32_e32 v0, v133
	s_nop 1
	v_permlane16_swap_b32_e32 v133, v0
	v_add_f32_e32 v134, v133, v0
	v_mov_b32_e32 v137, v135
	v_mov_b32_e32 v136, v134
	s_nop 0
	v_permlane32_swap_b32_e32 v135, v137
	v_permlane32_swap_b32_e32 v134, v136
	v_pk_add_f32 v[132:133], v[134:135], v[136:137]
	s_nop 0
	v_pk_mul_f32 v[132:133], v[132:133], s[68:69] op_sel_hi:[1,0]
	s_nop 0
	v_fma_f32 v0, -v133, v133, v132
	v_add_f32_e32 v0, 0x3727c5ac, v0
	v_rsq_f32_e32 v138, v0
	s_nop 0
	v_mul_f32_e32 v139, v133, v138
	ds_write_b64 v209, v[138:139] offset:256
	global_load_dwordx2 v[130:131], v[130:131], off offset:1536
	v_mov_b32_e32 v210, v139
	s_waitcnt vmcnt(0) lgkmcnt(0)
	v_mov_b32_e32 v0, v130
	s_nop 1
	v_permlane16_swap_b32_e32 v130, v0
	v_add_f32_e32 v133, v130, v0
	v_mov_b32_e32 v0, v131
	s_nop 1
	v_permlane16_swap_b32_e32 v131, v0
	v_add_f32_e32 v132, v131, v0
	v_mov_b32_e32 v135, v133
	v_mov_b32_e32 v134, v132
	s_nop 0
	v_permlane32_swap_b32_e32 v133, v135
	v_permlane32_swap_b32_e32 v132, v134
	v_pk_add_f32 v[130:131], v[132:133], v[134:135]
	s_nop 0
	v_pk_mul_f32 v[130:131], v[130:131], s[68:69] op_sel_hi:[1,0]
	s_nop 0
	v_fma_f32 v0, -v131, v131, v130
	v_add_f32_e32 v0, 0x3727c5ac, v0
	v_rsq_f32_e32 v140, v0
	v_add_u32_e32 v0, v216, v158
	v_mul_f32_e32 v141, v131, v140
	ds_write_b64 v209, v[140:141] offset:384
	v_lshl_add_u64 v[130:131], v[0:1], 2, s[18:19]
	global_load_dwordx2 v[130:131], v[130:131], off
	v_mov_b32_e32 v208, v141
	s_waitcnt vmcnt(0) lgkmcnt(0)
	v_mov_b32_e32 v0, v130
	s_nop 1
	v_permlane16_swap_b32_e32 v130, v0
	v_add_f32_e32 v133, v130, v0
	v_mov_b32_e32 v0, v131
	s_nop 1
	v_permlane16_swap_b32_e32 v131, v0
	v_add_f32_e32 v132, v131, v0
	v_mov_b32_e32 v135, v133
	v_mov_b32_e32 v134, v132
	s_nop 0
	v_permlane32_swap_b32_e32 v133, v135
	v_permlane32_swap_b32_e32 v132, v134
	v_pk_add_f32 v[130:131], v[132:133], v[134:135]
	s_nop 0
	v_pk_mul_f32 v[130:131], v[130:131], s[68:69] op_sel_hi:[1,0]
	s_nop 0
	v_fma_f32 v0, -v131, v131, v130
	v_add_f32_e32 v0, 0x3727c5ac, v0
	v_rsq_f32_e32 v130, v0
	v_add_u32_e32 v0, v217, v158
	v_lshl_add_u64 v[132:133], v[0:1], 2, s[18:19]
	v_mul_f32_e32 v131, v131, v130
	ds_write_b64 v209, v[130:131] offset:1024
	global_load_dwordx2 v[132:133], v[132:133], off
	v_mov_b32_e32 v206, v131
	s_waitcnt vmcnt(0) lgkmcnt(0)
	v_mov_b32_e32 v0, v132
	s_nop 1
	v_permlane16_swap_b32_e32 v132, v0
	v_add_f32_e32 v135, v132, v0
	v_mov_b32_e32 v0, v133
	s_nop 1
	v_permlane16_swap_b32_e32 v133, v0
	v_add_f32_e32 v134, v133, v0
	v_mov_b32_e32 v137, v135
	v_mov_b32_e32 v136, v134
	s_nop 0
	v_permlane32_swap_b32_e32 v135, v137
	v_permlane32_swap_b32_e32 v134, v136
	v_pk_add_f32 v[132:133], v[134:135], v[136:137]
	s_nop 0
	v_pk_mul_f32 v[132:133], v[132:133], s[68:69] op_sel_hi:[1,0]
	s_nop 0
	v_fma_f32 v0, -v133, v133, v132
	v_add_f32_e32 v0, 0x3727c5ac, v0
	v_rsq_f32_e32 v132, v0
	v_add_u32_e32 v0, v226, v158
	v_lshl_add_u64 v[134:135], v[0:1], 2, s[18:19]
	v_mul_f32_e32 v133, v133, v132
	ds_write_b64 v209, v[132:133] offset:1152
	global_load_dwordx2 v[134:135], v[134:135], off
	v_mov_b32_e32 v200, v133
	s_waitcnt vmcnt(0) lgkmcnt(0)
	v_mov_b32_e32 v0, v134
	s_nop 1
	v_permlane16_swap_b32_e32 v134, v0
	v_add_f32_e32 v137, v134, v0
	v_mov_b32_e32 v0, v135
	s_nop 1
	v_permlane16_swap_b32_e32 v135, v0
	v_add_f32_e32 v136, v135, v0
	v_mov_b32_e32 v161, v137
	v_mov_b32_e32 v160, v136
	s_nop 0
	v_permlane32_swap_b32_e32 v137, v161
	v_permlane32_swap_b32_e32 v136, v160
	v_pk_add_f32 v[134:135], v[136:137], v[160:161]
	s_nop 0
	v_pk_mul_f32 v[134:135], v[134:135], s[68:69] op_sel_hi:[1,0]
	s_nop 0
	v_fma_f32 v0, -v135, v135, v134
	v_add_f32_e32 v0, 0x3727c5ac, v0
	v_rsq_f32_e32 v134, v0
	v_add_u32_e32 v0, v227, v158
	v_lshl_add_u64 v[136:137], v[0:1], 2, s[18:19]
	v_mov_b32_e32 v158, s53
	v_mul_f32_e32 v135, v135, v134
	ds_write_b64 v209, v[134:135] offset:1280
	global_load_dwordx2 v[136:137], v[136:137], off
	s_waitcnt vmcnt(0) lgkmcnt(0)
	v_mov_b32_e32 v0, v136
	s_nop 1
	v_permlane16_swap_b32_e32 v136, v0
	v_add_f32_e32 v161, v136, v0
	v_mov_b32_e32 v0, v137
	s_nop 1
	v_permlane16_swap_b32_e32 v137, v0
	v_add_f32_e32 v160, v137, v0
	v_mov_b32_e32 v163, v161
	v_mov_b32_e32 v162, v160
	s_nop 0
	v_permlane32_swap_b32_e32 v161, v163
	v_permlane32_swap_b32_e32 v160, v162
	v_pk_add_f32 v[136:137], v[160:161], v[162:163]
	s_nop 0
	v_pk_mul_f32 v[136:137], v[136:137], s[68:69] op_sel_hi:[1,0]
	s_nop 0
	v_fma_f32 v0, -v137, v137, v136
	v_add_f32_e32 v0, 0x3727c5ac, v0
	v_rsq_f32_e32 v136, v0
	v_mov_b32_e32 v0, s47
	v_mul_f32_e32 v137, v137, v136
	ds_write_b64 v209, v[136:137] offset:1408
	s_waitcnt lgkmcnt(0)
	ds_write_b32 v0, v158
	v_mov_b32_e32 v158, v135
	v_mov_b32_e32 v0, v137

; #define PG8_LAS __attribute__((address_space(3)))
; __device__ __forceinline__ unsigned cvt_pk_bf16(float lo, float hi) { unsigned r; asm volatile("v_cvt_pk_bf16_f32 %0, %1, %2" : "=v"(r) : "v"(lo), "v"(hi)); return r; }
;     __device__ __forceinline__ void operator()(const f32x4 (&acc)[2][2][4][2], const Unit& u, int wr, int wc, int fr, int fq, PG8_LAS unsigned char* ldsb) const {
;     ...
; #pragma unroll
;             for (int bj = 0; bj < 2; ++bj)
; #pragma unroll
;                 for (int n = 0; n < 2; ++n) { const u32x4 cw = *(const PG8_LAS u32x4*)(CV + col0 + bj * HALF + 4 * n);
; #pragma unroll
;                     for (int i = 0; i < 4; ++i) { c1v[bj][n][i] = __uint_as_float(cw[i] << 16); c2v[bj][n][i] = __uint_as_float(cw[i] & 0xffff0000u); } }
;         }
; #pragma unroll
;         for (int ai = 0; ai < 2; ++ai)
; #pragma unroll
;             for (int m = 0; m < 4; ++m) {
;                 bf16_t* rowp = O + (size_t)(row0 + ai * HALF + m * 16) * ldc + col0;
;                 const float rs = rsv[ai][m], ms = msv[ai][m];
; #pragma unroll
;                 for (int bj = 0; bj < 2; ++bj) { const f32x4 v0 = acc[ai][bj][m][0] * rs - c1v[bj][0] * ms + c2v[bj][0], v1 = acc[ai][bj][m][1] * rs - c1v[bj][1] * ms + c2v[bj][1];
;                     u32x4 w; w.x = cvt_pk_bf16(v0[0], v0[1]); w.y = cvt_pk_bf16(v0[2], v0[3]); w.z = cvt_pk_bf16(v1[0], v1[1]); w.w = cvt_pk_bf16(v1[2], v1[3]);
;                     *(u32x4*)(rowp + bj * HALF) = w; }
.LBB0_673:
	v_lshl_or_b32 v232, s52, 8, v228
	v_lshl_add_u32 v131, v232, 2, 0
	v_add_u32_e32 v131, 0x20000, v131
	ds_read_b128 v[160:163], v131
	ds_read_b128 v[164:167], v131 offset:16
	v_ashrrev_i32_e32 v233, 31, v232
	s_and_b64 vcc, exec, s[2:3]
	s_mov_b64 s[2:3], -1
	s_waitcnt lgkmcnt(0)
	v_lshlrev_b32_e32 v198, 16, v162
	v_and_b32_e32 v182, 0xffff0000, v162
	v_lshlrev_b32_e32 v199, 16, v163
	v_and_b32_e32 v183, 0xffff0000, v163
	v_lshlrev_b32_e32 v180, 16, v164
	v_and_b32_e32 v170, 0xffff0000, v164
	v_lshlrev_b32_e32 v181, 16, v165
	v_and_b32_e32 v171, 0xffff0000, v165
	ds_read_b128 v[162:165], v131 offset:512
	ds_read_b128 v[202:205], v131 offset:528
	v_lshlrev_b32_e32 v194, 16, v160
	v_and_b32_e32 v174, 0xffff0000, v160
	v_lshlrev_b32_e32 v195, 16, v161
	v_and_b32_e32 v175, 0xffff0000, v161
	v_lshlrev_b32_e32 v196, 16, v166
	v_and_b32_e32 v184, 0xffff0000, v166
	v_lshlrev_b32_e32 v197, 16, v167
	v_and_b32_e32 v185, 0xffff0000, v167
	s_waitcnt lgkmcnt(0)
	v_lshlrev_b32_e32 v166, 16, v202
	v_and_b32_e32 v160, 0xffff0000, v202
	v_lshlrev_b32_e32 v167, 16, v203
	v_and_b32_e32 v161, 0xffff0000, v203
	v_mov_b64_e32 v[202:203], s[16:17]
	v_lshlrev_b32_e32 v178, 16, v164
	v_and_b32_e32 v168, 0xffff0000, v164
	v_lshlrev_b32_e32 v179, 16, v165
	v_and_b32_e32 v169, 0xffff0000, v165
	v_lshlrev_b32_e32 v176, 16, v204
	v_and_b32_e32 v164, 0xffff0000, v204
	v_lshlrev_b32_e32 v177, 16, v205
	v_and_b32_e32 v165, 0xffff0000, v205
	v_mad_i64_i32 v[234:235], s[26:27], v230, s57, v[202:203]
	v_lshlrev_b64 v[204:205], 1, v[232:233]
	v_lshl_add_u64 v[232:233], v[234:235], 0, v[204:205]
	v_pk_mul_f32 v[234:235], v[214:215], v[198:199] op_sel_hi:[0,1]
	v_pk_mul_f32 v[236:237], v[214:215], v[194:195] op_sel_hi:[0,1]
	v_pk_fma_f32 v[126:127], v[126:127], v[142:143], v[236:237] op_sel_hi:[1,0,1] neg_lo:[0,0,1] neg_hi:[0,0,1]
	v_pk_fma_f32 v[128:129], v[128:129], v[142:143], v[234:235] op_sel_hi:[1,0,1] neg_lo:[0,0,1] neg_hi:[0,0,1]
	v_pk_mul_f32 v[234:235], v[214:215], v[196:197] op_sel_hi:[0,1]
	v_pk_mul_f32 v[236:237], v[214:215], v[180:181] op_sel_hi:[0,1]
	v_pk_fma_f32 v[122:123], v[122:123], v[142:143], v[236:237] op_sel_hi:[1,0,1] neg_lo:[0,0,1] neg_hi:[0,0,1]
	v_pk_fma_f32 v[124:125], v[124:125], v[142:143], v[234:235] op_sel_hi:[1,0,1] neg_lo:[0,0,1] neg_hi:[0,0,1]
	v_lshlrev_b32_e32 v172, 16, v162
	v_pk_add_f32 v[234:235], v[124:125], v[184:185]
	v_pk_add_f32 v[124:125], v[122:123], v[170:171]
	v_lshlrev_b32_e32 v173, 16, v163
	v_pk_add_f32 v[128:129], v[128:129], v[182:183]
	v_pk_add_f32 v[126:127], v[126:127], v[174:175]
	v_and_b32_e32 v162, 0xffff0000, v162
	v_cvt_pk_bf16_f32 v122, v126, v127
	v_cvt_pk_bf16_f32 v123, v128, v129
	v_cvt_pk_bf16_f32 v124, v124, v125
	v_cvt_pk_bf16_f32 v125, v234, v235
	global_store_dwordx4 v[232:233], v[122:125], off
	v_and_b32_e32 v163, 0xffff0000, v163
	s_nop 0
	v_pk_mul_f32 v[122:123], v[214:215], v[178:179] op_sel_hi:[0,1]
	v_pk_mul_f32 v[124:125], v[214:215], v[172:173] op_sel_hi:[0,1]
	v_pk_fma_f32 v[118:119], v[118:119], v[142:143], v[124:125] op_sel_hi:[1,0,1] neg_lo:[0,0,1] neg_hi:[0,0,1]
	v_pk_fma_f32 v[120:121], v[120:121], v[142:143], v[122:123] op_sel_hi:[1,0,1] neg_lo:[0,0,1] neg_hi:[0,0,1]
	v_pk_mul_f32 v[122:123], v[214:215], v[176:177] op_sel_hi:[0,1]
	v_pk_mul_f32 v[124:125], v[214:215], v[166:167] op_sel_hi:[0,1]
	v_pk_fma_f32 v[114:115], v[114:115], v[142:143], v[124:125] op_sel_hi:[1,0,1] neg_lo:[0,0,1] neg_hi:[0,0,1]
	v_pk_fma_f32 v[116:117], v[116:117], v[142:143], v[122:123] op_sel_hi:[1,0,1] neg_lo:[0,0,1] neg_hi:[0,0,1]
	v_pk_add_f32 v[120:121], v[120:121], v[168:169]
	v_pk_add_f32 v[122:123], v[116:117], v[164:165]
	v_pk_add_f32 v[116:117], v[114:115], v[160:161]
	v_pk_add_f32 v[118:119], v[118:119], v[162:163]
	s_nop 0
	v_cvt_pk_bf16_f32 v114, v118, v119
	v_cvt_pk_bf16_f32 v115, v120, v121
	v_cvt_pk_bf16_f32 v116, v116, v117
	v_cvt_pk_bf16_f32 v117, v122, v123
	global_store_dwordx4 v[232:233], v[114:117], off offset:256
	v_pk_mul_f32 v[118:119], v[212:213], v[194:195] op_sel_hi:[0,1]
	v_pk_fma_f32 v[110:111], v[110:111], v[144:145], v[118:119] op_sel_hi:[1,0,1] neg_lo:[0,0,1] neg_hi:[0,0,1]
	v_pk_mul_f32 v[116:117], v[212:213], v[198:199] op_sel_hi:[0,1]
	v_pk_fma_f32 v[112:113], v[112:113], v[144:145], v[116:117] op_sel_hi:[1,0,1] neg_lo:[0,0,1] neg_hi:[0,0,1]
	v_pk_mul_f32 v[116:117], v[212:213], v[196:197] op_sel_hi:[0,1]
	v_pk_mul_f32 v[118:119], v[212:213], v[180:181] op_sel_hi:[0,1]
	v_or_b32_e32 v114, 16, v230
	v_pk_fma_f32 v[106:107], v[106:107], v[144:145], v[118:119] op_sel_hi:[1,0,1] neg_lo:[0,0,1] neg_hi:[0,0,1]
	v_pk_fma_f32 v[108:109], v[108:109], v[144:145], v[116:117] op_sel_hi:[1,0,1] neg_lo:[0,0,1] neg_hi:[0,0,1]
	v_mad_i64_i32 v[114:115], s[26:27], v114, s57, v[202:203]
	v_pk_add_f32 v[116:117], v[108:109], v[184:185]
	v_pk_add_f32 v[108:109], v[106:107], v[170:171]
	v_lshl_add_u64 v[114:115], v[114:115], 0, v[204:205]
	v_pk_add_f32 v[112:113], v[112:113], v[182:183]
	v_pk_add_f32 v[110:111], v[110:111], v[174:175]
	s_nop 0
	v_cvt_pk_bf16_f32 v106, v110, v111
	v_cvt_pk_bf16_f32 v107, v112, v113
	v_cvt_pk_bf16_f32 v108, v108, v109
	v_cvt_pk_bf16_f32 v109, v116, v117
	global_store_dwordx4 v[114:115], v[106:109], off
	s_nop 1
	v_pk_mul_f32 v[106:107], v[212:213], v[178:179] op_sel_hi:[0,1]
	v_pk_mul_f32 v[108:109], v[212:213], v[172:173] op_sel_hi:[0,1]
	v_pk_fma_f32 v[102:103], v[102:103], v[144:145], v[108:109] op_sel_hi:[1,0,1] neg_lo:[0,0,1] neg_hi:[0,0,1]
	v_pk_fma_f32 v[104:105], v[104:105], v[144:145], v[106:107] op_sel_hi:[1,0,1] neg_lo:[0,0,1] neg_hi:[0,0,1]
	v_pk_mul_f32 v[106:107], v[212:213], v[176:177] op_sel_hi:[0,1]
	v_pk_mul_f32 v[108:109], v[212:213], v[166:167] op_sel_hi:[0,1]
; __device__ __forceinline__ unsigned cvt_pk_bf16(float lo, float hi) { unsigned r; asm volatile("v_cvt_pk_bf16_f32 %0, %1, %2" : "=v"(r) : "v"(lo), "v"(hi)); return r; }
;     __device__ __forceinline__ void operator()(const f32x4 (&acc)[2][2][4][2], const Unit& u, int wr, int wc, int fr, int fq, PG8_LAS unsigned char* ldsb) const {
;     ...
;         for (int ai = 0; ai < 2; ++ai)
; #pragma unroll
;             for (int m = 0; m < 4; ++m) {
;                 bf16_t* rowp = O + (size_t)(row0 + ai * HALF + m * 16) * ldc + col0;
;                 const float rs = rsv[ai][m], ms = msv[ai][m];
; #pragma unroll
;                 for (int bj = 0; bj < 2; ++bj) { const f32x4 v0 = acc[ai][bj][m][0] * rs - c1v[bj][0] * ms + c2v[bj][0], v1 = acc[ai][bj][m][1] * rs - c1v[bj][1] * ms + c2v[bj][1];
;                     u32x4 w; w.x = cvt_pk_bf16(v0[0], v0[1]); w.y = cvt_pk_bf16(v0[2], v0[3]); w.z = cvt_pk_bf16(v1[0], v1[1]); w.w = cvt_pk_bf16(v1[2], v1[3]);
;                     *(u32x4*)(rowp + bj * HALF) = w; }
	v_pk_fma_f32 v[98:99], v[98:99], v[144:145], v[108:109] op_sel_hi:[1,0,1] neg_lo:[0,0,1] neg_hi:[0,0,1]
	v_pk_fma_f32 v[100:101], v[100:101], v[144:145], v[106:107] op_sel_hi:[1,0,1] neg_lo:[0,0,1] neg_hi:[0,0,1]
	v_pk_add_f32 v[104:105], v[104:105], v[168:169]
	v_pk_add_f32 v[106:107], v[100:101], v[164:165]
	v_pk_add_f32 v[100:101], v[98:99], v[160:161]
	v_pk_add_f32 v[102:103], v[102:103], v[162:163]
	s_nop 0
	v_cvt_pk_bf16_f32 v98, v102, v103
	v_cvt_pk_bf16_f32 v99, v104, v105
	v_cvt_pk_bf16_f32 v100, v100, v101
	v_cvt_pk_bf16_f32 v101, v106, v107
	global_store_dwordx4 v[114:115], v[98:101], off offset:256
	v_pk_mul_f32 v[102:103], v[210:211], v[194:195] op_sel_hi:[0,1]
	v_pk_fma_f32 v[94:95], v[94:95], v[138:139], v[102:103] op_sel_hi:[1,0,1] neg_lo:[0,0,1] neg_hi:[0,0,1]
	v_pk_mul_f32 v[100:101], v[210:211], v[198:199] op_sel_hi:[0,1]
	v_pk_fma_f32 v[96:97], v[96:97], v[138:139], v[100:101] op_sel_hi:[1,0,1] neg_lo:[0,0,1] neg_hi:[0,0,1]
	v_pk_mul_f32 v[100:101], v[210:211], v[196:197] op_sel_hi:[0,1]
	v_pk_mul_f32 v[102:103], v[210:211], v[180:181] op_sel_hi:[0,1]
	v_or_b32_e32 v98, 32, v230
	v_pk_fma_f32 v[90:91], v[90:91], v[138:139], v[102:103] op_sel_hi:[1,0,1] neg_lo:[0,0,1] neg_hi:[0,0,1]
	v_pk_fma_f32 v[92:93], v[92:93], v[138:139], v[100:101] op_sel_hi:[1,0,1] neg_lo:[0,0,1] neg_hi:[0,0,1]
	v_mad_i64_i32 v[98:99], s[26:27], v98, s57, v[202:203]
	v_pk_add_f32 v[100:101], v[92:93], v[184:185]
	v_pk_add_f32 v[92:93], v[90:91], v[170:171]
	v_lshl_add_u64 v[98:99], v[98:99], 0, v[204:205]
	v_pk_add_f32 v[96:97], v[96:97], v[182:183]
	v_pk_add_f32 v[94:95], v[94:95], v[174:175]
	s_nop 0
	v_cvt_pk_bf16_f32 v90, v94, v95
	v_cvt_pk_bf16_f32 v91, v96, v97
	v_cvt_pk_bf16_f32 v92, v92, v93
	v_cvt_pk_bf16_f32 v93, v100, v101
	global_store_dwordx4 v[98:99], v[90:93], off
	s_nop 1
	v_pk_mul_f32 v[90:91], v[210:211], v[178:179] op_sel_hi:[0,1]
	v_pk_mul_f32 v[92:93], v[210:211], v[172:173] op_sel_hi:[0,1]
	v_pk_fma_f32 v[86:87], v[86:87], v[138:139], v[92:93] op_sel_hi:[1,0,1] neg_lo:[0,0,1] neg_hi:[0,0,1]
	v_pk_fma_f32 v[88:89], v[88:89], v[138:139], v[90:91] op_sel_hi:[1,0,1] neg_lo:[0,0,1] neg_hi:[0,0,1]
	v_pk_mul_f32 v[90:91], v[210:211], v[176:177] op_sel_hi:[0,1]
	v_pk_mul_f32 v[92:93], v[210:211], v[166:167] op_sel_hi:[0,1]
	v_pk_fma_f32 v[82:83], v[82:83], v[138:139], v[92:93] op_sel_hi:[1,0,1] neg_lo:[0,0,1] neg_hi:[0,0,1]
	v_pk_fma_f32 v[84:85], v[84:85], v[138:139], v[90:91] op_sel_hi:[1,0,1] neg_lo:[0,0,1] neg_hi:[0,0,1]
	v_pk_add_f32 v[88:89], v[88:89], v[168:169]
	v_pk_add_f32 v[90:91], v[84:85], v[164:165]
	v_pk_add_f32 v[84:85], v[82:83], v[160:161]
	v_pk_add_f32 v[86:87], v[86:87], v[162:163]
	s_nop 0
	v_cvt_pk_bf16_f32 v82, v86, v87
	v_cvt_pk_bf16_f32 v83, v88, v89
	v_cvt_pk_bf16_f32 v84, v84, v85
	v_cvt_pk_bf16_f32 v85, v90, v91
	global_store_dwordx4 v[98:99], v[82:85], off offset:256
	v_pk_mul_f32 v[86:87], v[208:209], v[194:195] op_sel_hi:[0,1]
	v_pk_fma_f32 v[78:79], v[78:79], v[140:141], v[86:87] op_sel_hi:[1,0,1] neg_lo:[0,0,1] neg_hi:[0,0,1]
	v_pk_mul_f32 v[84:85], v[208:209], v[198:199] op_sel_hi:[0,1]
	v_pk_fma_f32 v[80:81], v[80:81], v[140:141], v[84:85] op_sel_hi:[1,0,1] neg_lo:[0,0,1] neg_hi:[0,0,1]
	v_pk_mul_f32 v[84:85], v[208:209], v[196:197] op_sel_hi:[0,1]
	v_pk_mul_f32 v[86:87], v[208:209], v[180:181] op_sel_hi:[0,1]
	v_or_b32_e32 v82, 48, v230
	v_pk_fma_f32 v[74:75], v[74:75], v[140:141], v[86:87] op_sel_hi:[1,0,1] neg_lo:[0,0,1] neg_hi:[0,0,1]
	v_pk_fma_f32 v[76:77], v[76:77], v[140:141], v[84:85] op_sel_hi:[1,0,1] neg_lo:[0,0,1] neg_hi:[0,0,1]
	v_mad_i64_i32 v[82:83], s[26:27], v82, s57, v[202:203]
	v_pk_add_f32 v[84:85], v[76:77], v[184:185]
	v_pk_add_f32 v[76:77], v[74:75], v[170:171]
	v_lshl_add_u64 v[82:83], v[82:83], 0, v[204:205]
	v_pk_add_f32 v[80:81], v[80:81], v[182:183]
	v_pk_add_f32 v[78:79], v[78:79], v[174:175]
	s_nop 0
	v_cvt_pk_bf16_f32 v74, v78, v79
	v_cvt_pk_bf16_f32 v75, v80, v81
	v_cvt_pk_bf16_f32 v76, v76, v77
	v_cvt_pk_bf16_f32 v77, v84, v85
	global_store_dwordx4 v[82:83], v[74:77], off
	s_nop 1
	v_pk_mul_f32 v[74:75], v[208:209], v[178:179] op_sel_hi:[0,1]
	v_pk_mul_f32 v[76:77], v[208:209], v[172:173] op_sel_hi:[0,1]
	v_pk_fma_f32 v[70:71], v[70:71], v[140:141], v[76:77] op_sel_hi:[1,0,1] neg_lo:[0,0,1] neg_hi:[0,0,1]
	v_pk_fma_f32 v[72:73], v[72:73], v[140:141], v[74:75] op_sel_hi:[1,0,1] neg_lo:[0,0,1] neg_hi:[0,0,1]
	v_pk_mul_f32 v[74:75], v[208:209], v[176:177] op_sel_hi:[0,1]
	v_pk_mul_f32 v[76:77], v[208:209], v[166:167] op_sel_hi:[0,1]
	v_pk_fma_f32 v[66:67], v[66:67], v[140:141], v[76:77] op_sel_hi:[1,0,1] neg_lo:[0,0,1] neg_hi:[0,0,1]
	v_pk_fma_f32 v[68:69], v[68:69], v[140:141], v[74:75] op_sel_hi:[1,0,1] neg_lo:[0,0,1] neg_hi:[0,0,1]
	v_pk_add_f32 v[72:73], v[72:73], v[168:169]
	v_pk_add_f32 v[74:75], v[68:69], v[164:165]
	v_pk_add_f32 v[68:69], v[66:67], v[160:161]
	v_pk_add_f32 v[70:71], v[70:71], v[162:163]
	s_nop 0
	v_cvt_pk_bf16_f32 v66, v70, v71
	v_cvt_pk_bf16_f32 v67, v72, v73
	v_cvt_pk_bf16_f32 v68, v68, v69
	v_cvt_pk_bf16_f32 v69, v74, v75
	global_store_dwordx4 v[82:83], v[66:69], off offset:256
	v_pk_mul_f32 v[70:71], v[206:207], v[194:195] op_sel_hi:[0,1]
	v_pk_fma_f32 v[62:63], v[62:63], v[130:131], v[70:71] op_sel_hi:[1,0,1] neg_lo:[0,0,1] neg_hi:[0,0,1]
	v_pk_mul_f32 v[68:69], v[206:207], v[198:199] op_sel_hi:[0,1]
	v_pk_fma_f32 v[64:65], v[64:65], v[130:131], v[68:69] op_sel_hi:[1,0,1] neg_lo:[0,0,1] neg_hi:[0,0,1]
	v_pk_mul_f32 v[68:69], v[206:207], v[196:197] op_sel_hi:[0,1]
	v_pk_mul_f32 v[70:71], v[206:207], v[180:181] op_sel_hi:[0,1]
	v_add_u32_e32 v66, 0x80, v230
	v_pk_fma_f32 v[58:59], v[58:59], v[130:131], v[70:71] op_sel_hi:[1,0,1] neg_lo:[0,0,1] neg_hi:[0,0,1]
; __device__ __forceinline__ unsigned cvt_pk_bf16(float lo, float hi) { unsigned r; asm volatile("v_cvt_pk_bf16_f32 %0, %1, %2" : "=v"(r) : "v"(lo), "v"(hi)); return r; }
;     __device__ __forceinline__ void operator()(const f32x4 (&acc)[2][2][4][2], const Unit& u, int wr, int wc, int fr, int fq, PG8_LAS unsigned char* ldsb) const {
;     ...
;         for (int ai = 0; ai < 2; ++ai)
; #pragma unroll
;             for (int m = 0; m < 4; ++m) {
;                 bf16_t* rowp = O + (size_t)(row0 + ai * HALF + m * 16) * ldc + col0;
;                 const float rs = rsv[ai][m], ms = msv[ai][m];
; #pragma unroll
;                 for (int bj = 0; bj < 2; ++bj) { const f32x4 v0 = acc[ai][bj][m][0] * rs - c1v[bj][0] * ms + c2v[bj][0], v1 = acc[ai][bj][m][1] * rs - c1v[bj][1] * ms + c2v[bj][1];
;                     u32x4 w; w.x = cvt_pk_bf16(v0[0], v0[1]); w.y = cvt_pk_bf16(v0[2], v0[3]); w.z = cvt_pk_bf16(v1[0], v1[1]); w.w = cvt_pk_bf16(v1[2], v1[3]);
;                     *(u32x4*)(rowp + bj * HALF) = w; }
	v_pk_fma_f32 v[60:61], v[60:61], v[130:131], v[68:69] op_sel_hi:[1,0,1] neg_lo:[0,0,1] neg_hi:[0,0,1]
	v_mad_i64_i32 v[66:67], s[26:27], v66, s57, v[202:203]
	v_pk_add_f32 v[68:69], v[60:61], v[184:185]
	v_pk_add_f32 v[60:61], v[58:59], v[170:171]
	v_lshl_add_u64 v[66:67], v[66:67], 0, v[204:205]
	v_pk_add_f32 v[64:65], v[64:65], v[182:183]
	v_pk_add_f32 v[62:63], v[62:63], v[174:175]
	s_nop 0
	v_cvt_pk_bf16_f32 v58, v62, v63
	v_cvt_pk_bf16_f32 v59, v64, v65
	v_cvt_pk_bf16_f32 v60, v60, v61
	v_cvt_pk_bf16_f32 v61, v68, v69
	global_store_dwordx4 v[66:67], v[58:61], off
	s_nop 1
	v_pk_mul_f32 v[58:59], v[206:207], v[178:179] op_sel_hi:[0,1]
	v_pk_mul_f32 v[60:61], v[206:207], v[172:173] op_sel_hi:[0,1]
	v_pk_fma_f32 v[54:55], v[54:55], v[130:131], v[60:61] op_sel_hi:[1,0,1] neg_lo:[0,0,1] neg_hi:[0,0,1]
	v_pk_fma_f32 v[56:57], v[56:57], v[130:131], v[58:59] op_sel_hi:[1,0,1] neg_lo:[0,0,1] neg_hi:[0,0,1]
	v_pk_mul_f32 v[58:59], v[206:207], v[176:177] op_sel_hi:[0,1]
	v_pk_mul_f32 v[60:61], v[206:207], v[166:167] op_sel_hi:[0,1]
	v_pk_fma_f32 v[50:51], v[50:51], v[130:131], v[60:61] op_sel_hi:[1,0,1] neg_lo:[0,0,1] neg_hi:[0,0,1]
	v_pk_fma_f32 v[52:53], v[52:53], v[130:131], v[58:59] op_sel_hi:[1,0,1] neg_lo:[0,0,1] neg_hi:[0,0,1]
	v_pk_add_f32 v[56:57], v[56:57], v[168:169]
	v_pk_add_f32 v[58:59], v[52:53], v[164:165]
	v_pk_add_f32 v[52:53], v[50:51], v[160:161]
	v_pk_add_f32 v[54:55], v[54:55], v[162:163]
	s_nop 0
	v_cvt_pk_bf16_f32 v50, v54, v55
	v_cvt_pk_bf16_f32 v51, v56, v57
	v_cvt_pk_bf16_f32 v52, v52, v53
	v_cvt_pk_bf16_f32 v53, v58, v59
	global_store_dwordx4 v[66:67], v[50:53], off offset:256
	v_pk_mul_f32 v[54:55], v[200:201], v[194:195] op_sel_hi:[0,1]
	v_pk_fma_f32 v[46:47], v[46:47], v[132:133], v[54:55] op_sel_hi:[1,0,1] neg_lo:[0,0,1] neg_hi:[0,0,1]
	v_pk_mul_f32 v[52:53], v[200:201], v[198:199] op_sel_hi:[0,1]
	v_pk_fma_f32 v[48:49], v[48:49], v[132:133], v[52:53] op_sel_hi:[1,0,1] neg_lo:[0,0,1] neg_hi:[0,0,1]
	v_pk_mul_f32 v[52:53], v[200:201], v[196:197] op_sel_hi:[0,1]
	v_pk_mul_f32 v[54:55], v[200:201], v[180:181] op_sel_hi:[0,1]
	v_add_u32_e32 v50, 0x90, v230
	v_pk_fma_f32 v[42:43], v[42:43], v[132:133], v[54:55] op_sel_hi:[1,0,1] neg_lo:[0,0,1] neg_hi:[0,0,1]
	v_pk_fma_f32 v[44:45], v[44:45], v[132:133], v[52:53] op_sel_hi:[1,0,1] neg_lo:[0,0,1] neg_hi:[0,0,1]
	v_mad_i64_i32 v[50:51], s[26:27], v50, s57, v[202:203]
	v_pk_add_f32 v[52:53], v[44:45], v[184:185]
	v_pk_add_f32 v[44:45], v[42:43], v[170:171]
	v_lshl_add_u64 v[50:51], v[50:51], 0, v[204:205]
	v_pk_add_f32 v[48:49], v[48:49], v[182:183]
	v_pk_add_f32 v[46:47], v[46:47], v[174:175]
	s_nop 0
	v_cvt_pk_bf16_f32 v42, v46, v47
	v_cvt_pk_bf16_f32 v43, v48, v49
	v_cvt_pk_bf16_f32 v44, v44, v45
	v_cvt_pk_bf16_f32 v45, v52, v53
	global_store_dwordx4 v[50:51], v[42:45], off
	s_nop 1
	v_pk_mul_f32 v[42:43], v[200:201], v[178:179] op_sel_hi:[0,1]
	v_pk_mul_f32 v[44:45], v[200:201], v[172:173] op_sel_hi:[0,1]
	v_pk_fma_f32 v[38:39], v[38:39], v[132:133], v[44:45] op_sel_hi:[1,0,1] neg_lo:[0,0,1] neg_hi:[0,0,1]
	v_pk_fma_f32 v[40:41], v[40:41], v[132:133], v[42:43] op_sel_hi:[1,0,1] neg_lo:[0,0,1] neg_hi:[0,0,1]
	v_pk_mul_f32 v[42:43], v[200:201], v[176:177] op_sel_hi:[0,1]
	v_pk_mul_f32 v[44:45], v[200:201], v[166:167] op_sel_hi:[0,1]
	v_pk_fma_f32 v[34:35], v[34:35], v[132:133], v[44:45] op_sel_hi:[1,0,1] neg_lo:[0,0,1] neg_hi:[0,0,1]
	v_pk_fma_f32 v[36:37], v[36:37], v[132:133], v[42:43] op_sel_hi:[1,0,1] neg_lo:[0,0,1] neg_hi:[0,0,1]
	v_pk_add_f32 v[40:41], v[40:41], v[168:169]
	v_pk_add_f32 v[42:43], v[36:37], v[164:165]
	v_pk_add_f32 v[36:37], v[34:35], v[160:161]
	v_pk_add_f32 v[38:39], v[38:39], v[162:163]
	s_nop 0
	v_cvt_pk_bf16_f32 v34, v38, v39
	v_cvt_pk_bf16_f32 v35, v40, v41
	v_cvt_pk_bf16_f32 v36, v36, v37
	v_cvt_pk_bf16_f32 v37, v42, v43
	global_store_dwordx4 v[50:51], v[34:37], off offset:256
	v_pk_mul_f32 v[38:39], v[158:159], v[194:195] op_sel_hi:[0,1]
	v_pk_fma_f32 v[30:31], v[30:31], v[134:135], v[38:39] op_sel_hi:[1,0,1] neg_lo:[0,0,1] neg_hi:[0,0,1]
	v_pk_mul_f32 v[36:37], v[158:159], v[198:199] op_sel_hi:[0,1]
	v_pk_fma_f32 v[32:33], v[32:33], v[134:135], v[36:37] op_sel_hi:[1,0,1] neg_lo:[0,0,1] neg_hi:[0,0,1]
; __device__ __forceinline__ unsigned cvt_pk_bf16(float lo, float hi) { unsigned r; asm volatile("v_cvt_pk_bf16_f32 %0, %1, %2" : "=v"(r) : "v"(lo), "v"(hi)); return r; }
; #define PG8_BAR __builtin_amdgcn_s_barrier()
;     __device__ __forceinline__ void operator()(const f32x4 (&acc)[2][2][4][2], const Unit& u, int wr, int wc, int fr, int fq, PG8_LAS unsigned char* ldsb) const {
;     ...
;             for (int m = 0; m < 4; ++m) {
;                 bf16_t* rowp = O + (size_t)(row0 + ai * HALF + m * 16) * ldc + col0;
;                 const float rs = rsv[ai][m], ms = msv[ai][m];
; #pragma unroll
;                 for (int bj = 0; bj < 2; ++bj) { const f32x4 v0 = acc[ai][bj][m][0] * rs - c1v[bj][0] * ms + c2v[bj][0], v1 = acc[ai][bj][m][1] * rs - c1v[bj][1] * ms + c2v[bj][1];
;                     u32x4 w; w.x = cvt_pk_bf16(v0[0], v0[1]); w.y = cvt_pk_bf16(v0[2], v0[3]); w.z = cvt_pk_bf16(v1[0], v1[1]); w.w = cvt_pk_bf16(v1[2], v1[3]);
;                     *(u32x4*)(rowp + bj * HALF) = w; }
; template <class Epi, class Sched, bool ALIGN_EPI = false, bool SP2 = false>
; __device__ __forceinline__ void gemm_phase(PG8_LAS unsigned char* lds, const Gemm g, const Sched& S, const Epi& E) {
;     ...
;         if constexpr (ALIGN_EPI) { if (wr == 0) PG8_BAR; }
;         if constexpr (!Epi::AFTER_DRAIN) { E(acc, cur, wr, wc, fr, fq, lds); S.done(cur); }
;         if (!has_next) break;
; #pragma unroll
;         for (int a = 0; a < 2; ++a)
; #pragma unroll
;             for (int b = 0; b < 2; ++b)
; #pragma unroll
;                 for (int m = 0; m < 4; ++m)
; #pragma unroll
;                     for (int n = 0; n < 2; ++n) acc[a][b][m][n] = (f32x4){0.f, 0.f, 0.f, 0.f};
;         cur = nxt; cA = nA; cB = nB; ++ui;
;         if constexpr (ALIGN_EPI) { if (wr == 1) PG8_BAR; }
	v_pk_mul_f32 v[36:37], v[158:159], v[196:197] op_sel_hi:[0,1]
	v_pk_mul_f32 v[38:39], v[158:159], v[180:181] op_sel_hi:[0,1]
	v_add_u32_e32 v34, 0xa0, v230
	v_pk_fma_f32 v[26:27], v[26:27], v[134:135], v[38:39] op_sel_hi:[1,0,1] neg_lo:[0,0,1] neg_hi:[0,0,1]
	v_pk_fma_f32 v[28:29], v[28:29], v[134:135], v[36:37] op_sel_hi:[1,0,1] neg_lo:[0,0,1] neg_hi:[0,0,1]
	v_mad_i64_i32 v[34:35], s[26:27], v34, s57, v[202:203]
	v_pk_add_f32 v[36:37], v[28:29], v[184:185]
	v_pk_add_f32 v[28:29], v[26:27], v[170:171]
	v_lshl_add_u64 v[34:35], v[34:35], 0, v[204:205]
	v_pk_add_f32 v[32:33], v[32:33], v[182:183]
	v_pk_add_f32 v[30:31], v[30:31], v[174:175]
	s_nop 0
	v_cvt_pk_bf16_f32 v26, v30, v31
	v_cvt_pk_bf16_f32 v27, v32, v33
	v_cvt_pk_bf16_f32 v28, v28, v29
	v_cvt_pk_bf16_f32 v29, v36, v37
	global_store_dwordx4 v[34:35], v[26:29], off
	s_nop 1
	v_pk_mul_f32 v[26:27], v[158:159], v[178:179] op_sel_hi:[0,1]
	v_pk_mul_f32 v[28:29], v[158:159], v[172:173] op_sel_hi:[0,1]
	v_pk_fma_f32 v[22:23], v[22:23], v[134:135], v[28:29] op_sel_hi:[1,0,1] neg_lo:[0,0,1] neg_hi:[0,0,1]
	v_pk_fma_f32 v[24:25], v[24:25], v[134:135], v[26:27] op_sel_hi:[1,0,1] neg_lo:[0,0,1] neg_hi:[0,0,1]
	v_pk_mul_f32 v[26:27], v[158:159], v[176:177] op_sel_hi:[0,1]
	v_pk_mul_f32 v[28:29], v[158:159], v[166:167] op_sel_hi:[0,1]
	v_pk_fma_f32 v[18:19], v[18:19], v[134:135], v[28:29] op_sel_hi:[1,0,1] neg_lo:[0,0,1] neg_hi:[0,0,1]
	v_pk_fma_f32 v[20:21], v[20:21], v[134:135], v[26:27] op_sel_hi:[1,0,1] neg_lo:[0,0,1] neg_hi:[0,0,1]
	v_pk_add_f32 v[24:25], v[24:25], v[168:169]
	v_pk_add_f32 v[26:27], v[20:21], v[164:165]
	v_pk_add_f32 v[20:21], v[18:19], v[160:161]
	v_pk_add_f32 v[22:23], v[22:23], v[162:163]
	s_nop 0
	v_cvt_pk_bf16_f32 v18, v22, v23
	v_cvt_pk_bf16_f32 v19, v24, v25
	v_cvt_pk_bf16_f32 v20, v20, v21
	v_cvt_pk_bf16_f32 v21, v26, v27
	global_store_dwordx4 v[34:35], v[18:21], off offset:256
	v_pk_mul_f32 v[22:23], v[0:1], v[194:195] op_sel_hi:[0,1]
	v_pk_fma_f32 v[14:15], v[14:15], v[136:137], v[22:23] op_sel_hi:[1,0,1] neg_lo:[0,0,1] neg_hi:[0,0,1]
	v_pk_mul_f32 v[20:21], v[0:1], v[198:199] op_sel_hi:[0,1]
	v_pk_fma_f32 v[16:17], v[16:17], v[136:137], v[20:21] op_sel_hi:[1,0,1] neg_lo:[0,0,1] neg_hi:[0,0,1]
	v_pk_mul_f32 v[20:21], v[0:1], v[196:197] op_sel_hi:[0,1]
	v_pk_mul_f32 v[22:23], v[0:1], v[180:181] op_sel_hi:[0,1]
	v_add_u32_e32 v18, 0xb0, v230
	v_pk_fma_f32 v[10:11], v[10:11], v[136:137], v[22:23] op_sel_hi:[1,0,1] neg_lo:[0,0,1] neg_hi:[0,0,1]
	v_pk_fma_f32 v[12:13], v[12:13], v[136:137], v[20:21] op_sel_hi:[1,0,1] neg_lo:[0,0,1] neg_hi:[0,0,1]
	v_mad_i64_i32 v[18:19], s[26:27], v18, s57, v[202:203]
	v_pk_add_f32 v[20:21], v[12:13], v[184:185]
	v_pk_add_f32 v[12:13], v[10:11], v[170:171]
	v_lshl_add_u64 v[18:19], v[18:19], 0, v[204:205]
	v_pk_add_f32 v[16:17], v[16:17], v[182:183]
	v_pk_add_f32 v[14:15], v[14:15], v[174:175]
	s_nop 0
	v_cvt_pk_bf16_f32 v10, v14, v15
	v_cvt_pk_bf16_f32 v11, v16, v17
	v_cvt_pk_bf16_f32 v12, v12, v13
	v_cvt_pk_bf16_f32 v13, v20, v21
	global_store_dwordx4 v[18:19], v[10:13], off
	s_nop 1
	v_pk_mul_f32 v[10:11], v[0:1], v[178:179] op_sel_hi:[0,1]
	v_pk_mul_f32 v[12:13], v[0:1], v[172:173] op_sel_hi:[0,1]
	v_pk_fma_f32 v[6:7], v[6:7], v[136:137], v[12:13] op_sel_hi:[1,0,1] neg_lo:[0,0,1] neg_hi:[0,0,1]
	v_pk_fma_f32 v[8:9], v[8:9], v[136:137], v[10:11] op_sel_hi:[1,0,1] neg_lo:[0,0,1] neg_hi:[0,0,1]
	v_pk_mul_f32 v[10:11], v[0:1], v[176:177] op_sel_hi:[0,1]
	v_pk_mul_f32 v[12:13], v[0:1], v[166:167] op_sel_hi:[0,1]
	v_pk_fma_f32 v[2:3], v[2:3], v[136:137], v[12:13] op_sel_hi:[1,0,1] neg_lo:[0,0,1] neg_hi:[0,0,1]
	v_pk_fma_f32 v[4:5], v[4:5], v[136:137], v[10:11] op_sel_hi:[1,0,1] neg_lo:[0,0,1] neg_hi:[0,0,1]
	v_pk_add_f32 v[8:9], v[8:9], v[168:169]
	v_pk_add_f32 v[10:11], v[4:5], v[164:165]
	v_pk_add_f32 v[4:5], v[2:3], v[160:161]
	v_pk_add_f32 v[6:7], v[6:7], v[162:163]
	s_nop 0
	v_cvt_pk_bf16_f32 v2, v6, v7
	v_cvt_pk_bf16_f32 v3, v8, v9
	v_cvt_pk_bf16_f32 v4, v4, v5
	v_cvt_pk_bf16_f32 v5, v10, v11
	global_store_dwordx4 v[18:19], v[2:5], off offset:256
	s_cbranch_vccnz .LBB0_656
	s_andn2_b64 vcc, exec, s[14:15]
	s_cbranch_vccnz .LBB0_655
	s_barrier
	s_branch .LBB0_655

; __global__ void __launch_bounds__(512, 2) mega_fwd(Params P) {
;     ...
;                     for (size_t idx0 = gtid; idx0 < (size_t)T_TOK * 32; idx0 += GT * 4) {
;                         u32x4 av[4], bv4[4]; f32x4 tv[4][4];
; #pragma unroll
;                         for (int q = 0; q < 4; ++q) { const size_t idx = idx0 + (size_t)q * GT; const bool ok = idx < (size_t)T_TOK * 32; const size_t ix = ok ? idx : 0;
;                             const int row = (int)(ix >> 5), sub = (int)(ix & 31), qk = sub >> 4, h = (sub >> 2) & 3, c = sub & 3, pos = row & (SEQ - 1);
;                             const bf16_t* p = Z + (size_t)row * ZW + 512 + qk * 256 + h * 64 + c * 8; av[q] = *(const u32x4*)p; bv4[q] = *(const u32x4*)(p + 32);
; #pragma unroll
;                             for (int e = 0; e < 4; ++e) tv[q][e] = ((const f32x4*)(ROPE_RET + pos * 32 + c * 8))[e]; }
.LBB0_718:
	v_lshl_add_u64 v[86:87], s[10:11], 0, v[74:75]
	v_cmp_gt_u64_e64 s[4:5], s[28:29], v[86:87]
	v_mov_b64_e32 v[2:3], s[14:15]
	v_lshl_add_u64 v[84:85], s[22:23], 0, v[74:75]
	v_cndmask_b32_e64 v0, 0, v87, s[4:5]
	v_cndmask_b32_e64 v6, 0, v86, s[4:5]
	v_alignbit_b32 v0, v0, v6, 5
	v_lshlrev_b32_e32 v7, 5, v6
	v_mad_i64_i32 v[4:5], s[2:3], v0, s57, v[2:3]
	v_and_b32_e32 v0, 0x200, v7
	v_lshl_add_u64 v[4:5], v[4:5], 0, v[0:1]
	v_and_b32_e32 v0, 0x180, v7
	v_lshl_add_u64 v[4:5], v[4:5], 0, v[0:1]
	v_lshlrev_b32_e32 v0, 3, v6
	v_and_b32_e32 v8, 24, v0
	v_lshlrev_b32_e32 v0, 1, v8
	v_lshl_add_u64 v[4:5], v[4:5], 0, v[0:1]
	v_and_b32_e32 v0, 0xffe0, v6
	v_lshlrev_b32_e32 v0, 3, v0
	v_lshl_add_u64 v[6:7], s[12:13], 0, v[0:1]
	v_lshlrev_b32_e32 v0, 3, v8
	v_cmp_gt_u64_e64 s[2:3], s[28:29], v[84:85]
	v_lshl_add_u64 v[6:7], v[6:7], 0, v[0:1]
	v_lshl_add_u64 v[82:83], s[24:25], 0, v[74:75]
	v_cndmask_b32_e64 v0, 0, v85, s[2:3]
	v_cndmask_b32_e64 v10, 0, v84, s[2:3]
	v_alignbit_b32 v0, v0, v10, 5
	v_lshlrev_b32_e32 v11, 5, v10
	v_mad_i64_i32 v[8:9], s[6:7], v0, s57, v[2:3]
	v_and_b32_e32 v0, 0x200, v11
	v_lshl_add_u64 v[8:9], v[8:9], 0, v[0:1]
	v_and_b32_e32 v0, 0x180, v11
	v_lshl_add_u64 v[8:9], v[8:9], 0, v[0:1]
	v_lshlrev_b32_e32 v0, 3, v10
	v_and_b32_e32 v12, 24, v0
	v_lshlrev_b32_e32 v0, 1, v12
	v_lshl_add_u64 v[8:9], v[8:9], 0, v[0:1]
	v_and_b32_e32 v0, 0xffe0, v10
	v_lshlrev_b32_e32 v0, 3, v0
	v_lshl_add_u64 v[10:11], s[12:13], 0, v[0:1]
	v_lshlrev_b32_e32 v0, 3, v12
	v_cmp_gt_u64_e32 vcc, s[28:29], v[82:83]
	v_lshl_add_u64 v[10:11], v[10:11], 0, v[0:1]
	v_and_b32_e32 v17, 24, v78
	v_cndmask_b32_e32 v0, 0, v83, vcc
	v_cndmask_b32_e32 v14, 0, v82, vcc
	v_alignbit_b32 v0, v0, v14, 5
	v_lshlrev_b32_e32 v15, 5, v14
	v_mad_i64_i32 v[12:13], s[6:7], v0, s57, v[2:3]
	v_and_b32_e32 v0, 0x200, v15
	v_lshl_add_u64 v[12:13], v[12:13], 0, v[0:1]
	v_and_b32_e32 v0, 0x180, v15
	v_lshl_add_u64 v[12:13], v[12:13], 0, v[0:1]
	v_lshlrev_b32_e32 v0, 3, v14
	v_and_b32_e32 v18, 24, v0
	v_lshlrev_b32_e32 v0, 1, v18
	v_lshl_add_u64 v[12:13], v[12:13], 0, v[0:1]
	v_and_b32_e32 v0, 0xffe0, v14
	v_lshlrev_b32_e32 v0, 3, v0
	v_lshl_add_u64 v[14:15], s[12:13], 0, v[0:1]
	v_lshlrev_b32_e32 v0, 3, v18
	v_lshl_add_u64 v[88:89], v[14:15], 0, v[0:1]
	v_and_b32_e32 v0, 0xffe0, v74
	v_lshlrev_b32_e32 v0, 3, v0
	v_lshl_add_u64 v[14:15], s[12:13], 0, v[0:1]
	v_lshlrev_b32_e32 v0, 3, v17
	v_lshl_add_u64 v[14:15], v[14:15], 0, v[0:1]
	v_alignbit_b32 v0, v75, v74, 5
	v_mad_u64_u32 v[116:117], s[6:7], v0, s57, v[2:3]
	v_mov_b32_e32 v0, v117
	v_lshrrev_b32_e32 v2, 5, v75
	v_mad_u64_u32 v[2:3], s[6:7], v2, s57, v[0:1]
	v_and_b32_e32 v0, 0x100, v76
	v_and_b32_e32 v16, 0xc0, v76
	v_mov_b32_e32 v117, v2
	v_lshlrev_b32_e32 v0, 1, v0
	v_lshl_add_u64 v[2:3], v[116:117], 0, v[0:1]
	v_lshlrev_b32_e32 v0, 1, v16
	v_lshl_add_u64 v[2:3], v[2:3], 0, v[0:1]
	v_lshlrev_b32_e32 v80, 1, v17
	v_mov_b32_e32 v81, v1
	v_lshl_add_u64 v[2:3], v[2:3], 0, v[80:81]
	global_load_dwordx4 v[92:95], v[2:3], off offset:1024
	global_load_dwordx4 v[96:99], v[2:3], off offset:1088
	global_load_dwordx4 v[100:103], v[14:15], off
	global_load_dwordx4 v[104:107], v[14:15], off offset:16
	global_load_dwordx4 v[108:111], v[14:15], off offset:32
	global_load_dwordx4 v[112:115], v[14:15], off offset:48
	global_load_dwordx4 v[54:57], v[4:5], off offset:1024
	global_load_dwordx4 v[58:61], v[4:5], off offset:1088
	global_load_dwordx4 v[70:73], v[6:7], off
	global_load_dwordx4 v[66:69], v[6:7], off offset:16
	global_load_dwordx4 v[62:65], v[6:7], off offset:32
	global_load_dwordx4 v[50:53], v[6:7], off offset:48
	global_load_dwordx4 v[30:33], v[8:9], off offset:1024
	global_load_dwordx4 v[34:37], v[8:9], off offset:1088
	global_load_dwordx4 v[46:49], v[10:11], off
	global_load_dwordx4 v[42:45], v[10:11], off offset:16
	global_load_dwordx4 v[38:41], v[10:11], off offset:32
	global_load_dwordx4 v[26:29], v[10:11], off offset:48
	s_nop 0
	global_load_dwordx4 v[6:9], v[12:13], off offset:1024
	s_nop 0
	global_load_dwordx4 v[10:13], v[12:13], off offset:1088
	s_nop 0
	global_load_dwordx4 v[22:25], v[88:89], off
	global_load_dwordx4 v[18:21], v[88:89], off offset:16
	global_load_dwordx4 v[14:17], v[88:89], off offset:32
	global_load_dwordx4 v[2:5], v[88:89], off offset:48
	v_bfe_u32 v88, v74, 4, 1
	v_cmp_eq_u32_e64 s[6:7], 0, v88
	v_mov_b32_e32 v89, 0x3e000000
	v_lshlrev_b32_e32 v91, 8, v88
	v_cndmask_b32_e64 v90, v89, 1.0, s[6:7]
	v_lshlrev_b32_e32 v88, 9, v88
	v_mov_b32_e32 v89, v1
	v_lshl_add_u64 v[88:89], v[116:117], 0, v[88:89]
	v_lshl_add_u64 v[88:89], v[88:89], 0, v[0:1]
	v_lshl_add_u64 v[88:89], v[88:89], 0, v[80:81]
	s_waitcnt vmcnt(0) lgkmcnt(0)
; __device__ __forceinline__ unsigned cvt_pk_bf16(float lo, float hi) { unsigned r; asm volatile("v_cvt_pk_bf16_f32 %0, %1, %2" : "=v"(r) : "v"(lo), "v"(hi)); return r; }
; __device__ __forceinline__ float bflo(unsigned w) { return __uint_as_float(w << 16); }
; __device__ __forceinline__ float bfhi(unsigned w) { return __uint_as_float(w & 0xffff0000u); }
; __global__ void __launch_bounds__(512, 2) mega_fwd(Params P) {
;     ...
; #pragma unroll
;                         for (int q = 0; q < 4; ++q) { const size_t idx = idx0 + (size_t)q * GT; if (idx < (size_t)T_TOK * 32) {
;                             const int row = (int)(idx >> 5), sub = (int)(idx & 31), qk = sub >> 4, h = (sub >> 2) & 3, c = sub & 3;
;                             bf16_t* p = Z + (size_t)row * ZW + 512 + qk * 256 + h * 64 + c * 8; const float ksc = qk ? 0.125f : 1.0f; float o1[8], o2[8];
; #pragma unroll
;                             for (int e = 0; e < 8; ++e) { const unsigned wa = av[q][e >> 1], wb = bv4[q][e >> 1]; const float x1 = (e & 1) ? bfhi(wa) : bflo(wa), x2 = (e & 1) ? bfhi(wb) : bflo(wb);
;                                 const float cs_ = tv[q][e >> 1][(e & 1) * 2], sn_ = tv[q][e >> 1][(e & 1) * 2 + 1]; o1[e] = (x1 * cs_ - x2 * sn_) * ksc; o2[e] = (x1 * sn_ + x2 * cs_) * ksc; }
;                             u32x4 wa, wb; wa.x = cvt_pk_bf16(o1[0], o1[1]); wa.y = cvt_pk_bf16(o1[2], o1[3]); wa.z = cvt_pk_bf16(o1[4], o1[5]); wa.w = cvt_pk_bf16(o1[6], o1[7]);
;                             wb.x = cvt_pk_bf16(o2[0], o2[1]); wb.y = cvt_pk_bf16(o2[2], o2[3]); wb.z = cvt_pk_bf16(o2[4], o2[5]); wb.w = cvt_pk_bf16(o2[6], o2[7]);
;                             *(u32x4*)p = wa; *(u32x4*)(p + 32) = wb; } }
	v_lshlrev_b32_e32 v117, 16, v92
	v_lshlrev_b32_e32 v116, 16, v96
	v_pk_mul_f32 v[118:119], v[100:101], v[116:117] op_sel:[0,1] op_sel_hi:[1,0]
	v_pk_mul_f32 v[100:101], v[100:101], v[116:117]
	v_sub_f32_e32 v118, v118, v119
	v_add_f32_e32 v100, v101, v100
	v_mul_f32_e32 v119, v90, v100
	v_and_b32_e32 v101, 0xffff0000, v92
	v_and_b32_e32 v100, 0xffff0000, v96
	v_pk_mul_f32 v[116:117], v[102:103], v[100:101] op_sel:[0,1] op_sel_hi:[1,0]
	v_pk_mul_f32 v[100:101], v[102:103], v[100:101]
	v_sub_f32_e32 v92, v116, v117
	v_mul_f32_e32 v116, v90, v92
	v_add_f32_e32 v92, v101, v100
	v_lshlrev_b32_e32 v101, 16, v93
	v_lshlrev_b32_e32 v100, 16, v97
	v_pk_mul_f32 v[102:103], v[104:105], v[100:101] op_sel:[0,1] op_sel_hi:[1,0]
	v_mul_f32_e32 v117, v90, v92
	v_sub_f32_e32 v92, v102, v103
	v_pk_mul_f32 v[100:101], v[104:105], v[100:101]
	v_mul_f32_e32 v102, v90, v92
	v_add_f32_e32 v92, v101, v100
	v_mul_f32_e32 v100, v90, v92
	v_and_b32_e32 v93, 0xffff0000, v93
	v_and_b32_e32 v92, 0xffff0000, v97
	v_pk_mul_f32 v[96:97], v[106:107], v[92:93] op_sel:[0,1] op_sel_hi:[1,0]
	v_pk_mul_f32 v[92:93], v[106:107], v[92:93]
	v_sub_f32_e32 v96, v96, v97
	v_add_f32_e32 v92, v93, v92
	v_mul_f32_e32 v103, v90, v92
	v_lshlrev_b32_e32 v93, 16, v94
	v_lshlrev_b32_e32 v92, 16, v98
	v_mul_f32_e32 v101, v90, v96
	v_pk_mul_f32 v[96:97], v[108:109], v[92:93] op_sel:[0,1] op_sel_hi:[1,0]
	v_pk_mul_f32 v[92:93], v[108:109], v[92:93]
	v_sub_f32_e32 v96, v96, v97
	v_add_f32_e32 v92, v93, v92
	v_mul_f32_e32 v105, v90, v92
	v_and_b32_e32 v93, 0xffff0000, v94
	v_and_b32_e32 v92, 0xffff0000, v98
	v_mul_f32_e32 v104, v90, v96
	v_pk_mul_f32 v[96:97], v[110:111], v[92:93] op_sel:[0,1] op_sel_hi:[1,0]
	v_pk_mul_f32 v[92:93], v[110:111], v[92:93]
	v_sub_f32_e32 v94, v96, v97
	v_add_f32_e32 v92, v93, v92
	v_mul_f32_e32 v106, v90, v92
	v_lshlrev_b32_e32 v93, 16, v95
	v_lshlrev_b32_e32 v92, 16, v99
	v_pk_mul_f32 v[96:97], v[112:113], v[92:93] op_sel:[0,1] op_sel_hi:[1,0]
	v_pk_mul_f32 v[92:93], v[112:113], v[92:93]
	v_mul_f32_e32 v98, v90, v94
	v_add_f32_e32 v92, v93, v92
	v_sub_f32_e32 v94, v96, v97
	v_mul_f32_e32 v107, v90, v92
	v_and_b32_e32 v93, 0xffff0000, v95
	v_and_b32_e32 v92, 0xffff0000, v99
	v_mul_f32_e32 v96, v90, v94
	v_pk_mul_f32 v[94:95], v[114:115], v[92:93] op_sel:[0,1] op_sel_hi:[1,0]
	v_pk_mul_f32 v[92:93], v[114:115], v[92:93]
	v_sub_f32_e32 v94, v94, v95
	v_mul_f32_e32 v95, v90, v94
	v_add_f32_e32 v92, v93, v92
	v_mul_f32_e32 v118, v90, v118
	v_mul_f32_e32 v99, v90, v92
	v_cvt_pk_bf16_f32 v92, v118, v116
	v_cvt_pk_bf16_f32 v93, v102, v101
	v_cvt_pk_bf16_f32 v94, v104, v98
	v_cvt_pk_bf16_f32 v95, v96, v95
	v_cvt_pk_bf16_f32 v96, v119, v117
	v_cvt_pk_bf16_f32 v97, v100, v103
	v_cvt_pk_bf16_f32 v98, v105, v106
	v_cvt_pk_bf16_f32 v99, v107, v99
	global_store_dwordx4 v[88:89], v[92:95], off offset:1024
	global_store_dwordx4 v[88:89], v[96:99], off offset:1088
	v_lshlrev_b32_e32 v88, 1, v91
	s_and_saveexec_b64 s[6:7], s[4:5]
	s_cbranch_execnz .LBB0_721
	s_or_b64 exec, exec, s[6:7]
	s_and_saveexec_b64 s[4:5], s[2:3]
	s_cbranch_execnz .LBB0_722

; __device__ __forceinline__ unsigned cvt_pk_bf16(float lo, float hi) { unsigned r; asm volatile("v_cvt_pk_bf16_f32 %0, %1, %2" : "=v"(r) : "v"(lo), "v"(hi)); return r; }
; __device__ __forceinline__ float bflo(unsigned w) { return __uint_as_float(w << 16); }
; __device__ __forceinline__ float bfhi(unsigned w) { return __uint_as_float(w & 0xffff0000u); }
; __global__ void __launch_bounds__(512, 2) mega_fwd(Params P) {
;     ...
;                         for (int q = 0; q < 4; ++q) { const size_t idx = idx0 + (size_t)q * GT; if (idx < (size_t)T_TOK * 32) {
;                             const int row = (int)(idx >> 5), sub = (int)(idx & 31), qk = sub >> 4, h = (sub >> 2) & 3, c = sub & 3;
;                             bf16_t* p = Z + (size_t)row * ZW + 512 + qk * 256 + h * 64 + c * 8; const float ksc = qk ? 0.125f : 1.0f; float o1[8], o2[8];
; #pragma unroll
;                             for (int e = 0; e < 8; ++e) { const unsigned wa = av[q][e >> 1], wb = bv4[q][e >> 1]; const float x1 = (e & 1) ? bfhi(wa) : bflo(wa), x2 = (e & 1) ? bfhi(wb) : bflo(wb);
;                                 const float cs_ = tv[q][e >> 1][(e & 1) * 2], sn_ = tv[q][e >> 1][(e & 1) * 2 + 1]; o1[e] = (x1 * cs_ - x2 * sn_) * ksc; o2[e] = (x1 * sn_ + x2 * cs_) * ksc; }
;                             u32x4 wa, wb; wa.x = cvt_pk_bf16(o1[0], o1[1]); wa.y = cvt_pk_bf16(o1[2], o1[3]); wa.z = cvt_pk_bf16(o1[4], o1[5]); wa.w = cvt_pk_bf16(o1[6], o1[7]);
;                             wb.x = cvt_pk_bf16(o2[0], o2[1]); wb.y = cvt_pk_bf16(o2[2], o2[3]); wb.z = cvt_pk_bf16(o2[4], o2[5]); wb.w = cvt_pk_bf16(o2[6], o2[7]);
;                             *(u32x4*)p = wa; *(u32x4*)(p + 32) = wb; } }
.LBB0_721:
	v_alignbit_b32 v86, v87, v86, 5
	v_mov_b64_e32 v[92:93], s[14:15]
	v_mad_u64_u32 v[92:93], s[4:5], v86, s57, v[92:93]
	v_mov_b32_e32 v86, v93
	v_lshrrev_b32_e32 v87, 5, v87
	v_mad_u64_u32 v[86:87], s[4:5], v87, s57, v[86:87]
	v_mov_b32_e32 v93, v86
	v_mov_b32_e32 v89, v1
	v_lshl_add_u64 v[86:87], v[92:93], 0, v[88:89]
	v_lshlrev_b32_e32 v93, 16, v54
	v_lshlrev_b32_e32 v92, 16, v58
	v_pk_mul_f32 v[94:95], v[70:71], v[92:93] op_sel:[0,1] op_sel_hi:[1,0]
	v_pk_mul_f32 v[70:71], v[70:71], v[92:93]
	v_lshl_add_u64 v[86:87], v[86:87], 0, v[0:1]
	v_add_f32_e32 v70, v71, v70
	v_mul_f32_e32 v91, v90, v70
	v_and_b32_e32 v71, 0xffff0000, v54
	v_and_b32_e32 v70, 0xffff0000, v58
	v_pk_mul_f32 v[92:93], v[72:73], v[70:71] op_sel:[0,1] op_sel_hi:[1,0]
	v_pk_mul_f32 v[70:71], v[72:73], v[70:71]
	v_sub_f32_e32 v54, v92, v93
	v_mul_f32_e32 v92, v90, v54
	v_add_f32_e32 v54, v71, v70
	v_lshlrev_b32_e32 v71, 16, v55
	v_lshlrev_b32_e32 v70, 16, v59
	v_pk_mul_f32 v[72:73], v[66:67], v[70:71] op_sel:[0,1] op_sel_hi:[1,0]
	v_mul_f32_e32 v93, v90, v54
	v_sub_f32_e32 v54, v72, v73
	v_pk_mul_f32 v[66:67], v[66:67], v[70:71]
	v_mul_f32_e32 v72, v90, v54
	v_add_f32_e32 v54, v67, v66
	v_mul_f32_e32 v66, v90, v54
	v_and_b32_e32 v55, 0xffff0000, v55
	v_and_b32_e32 v54, 0xffff0000, v59
	v_pk_mul_f32 v[58:59], v[68:69], v[54:55] op_sel:[0,1] op_sel_hi:[1,0]
	v_pk_mul_f32 v[54:55], v[68:69], v[54:55]
	v_sub_f32_e32 v58, v58, v59
	v_add_f32_e32 v54, v55, v54
	v_mul_f32_e32 v68, v90, v54
	v_lshlrev_b32_e32 v55, 16, v56
	v_lshlrev_b32_e32 v54, 16, v60
	v_mul_f32_e32 v67, v90, v58
	v_pk_mul_f32 v[58:59], v[62:63], v[54:55] op_sel:[0,1] op_sel_hi:[1,0]
	v_pk_mul_f32 v[54:55], v[62:63], v[54:55]
	v_sub_f32_e32 v58, v58, v59
	v_add_f32_e32 v54, v55, v54
	v_mul_f32_e32 v62, v90, v54
	v_and_b32_e32 v55, 0xffff0000, v56
	v_and_b32_e32 v54, 0xffff0000, v60
	v_mul_f32_e32 v69, v90, v58
	v_pk_mul_f32 v[58:59], v[64:65], v[54:55] op_sel:[0,1] op_sel_hi:[1,0]
	v_pk_mul_f32 v[54:55], v[64:65], v[54:55]
	v_sub_f32_e32 v56, v58, v59
	v_add_f32_e32 v54, v55, v54
	v_mul_f32_e32 v60, v90, v54
	v_lshlrev_b32_e32 v55, 16, v57
	v_lshlrev_b32_e32 v54, 16, v61
	v_pk_mul_f32 v[58:59], v[50:51], v[54:55] op_sel:[0,1] op_sel_hi:[1,0]
	v_pk_mul_f32 v[50:51], v[50:51], v[54:55]
	v_sub_f32_e32 v89, v94, v95
	v_add_f32_e32 v50, v51, v50
	v_mul_f32_e32 v64, v90, v50
	v_and_b32_e32 v51, 0xffff0000, v57
	v_and_b32_e32 v50, 0xffff0000, v61
	v_pk_mul_f32 v[54:55], v[52:53], v[50:51] op_sel:[0,1] op_sel_hi:[1,0]
	v_pk_mul_f32 v[50:51], v[52:53], v[50:51]
	v_sub_f32_e32 v58, v58, v59
	v_sub_f32_e32 v54, v54, v55
	v_add_f32_e32 v50, v51, v50
	v_mul_f32_e32 v89, v90, v89
	v_mul_f32_e32 v56, v90, v56
	v_mul_f32_e32 v63, v90, v58
	v_mul_f32_e32 v54, v90, v54
	v_mul_f32_e32 v57, v90, v50
	v_lshl_add_u64 v[58:59], v[86:87], 0, v[80:81]
	v_cvt_pk_bf16_f32 v50, v89, v92
	v_cvt_pk_bf16_f32 v51, v72, v67
	v_cvt_pk_bf16_f32 v52, v69, v56
	v_cvt_pk_bf16_f32 v53, v63, v54
	v_cvt_pk_bf16_f32 v54, v91, v93
	v_cvt_pk_bf16_f32 v55, v66, v68
	v_cvt_pk_bf16_f32 v56, v62, v60
	v_cvt_pk_bf16_f32 v57, v64, v57
	global_store_dwordx4 v[58:59], v[50:53], off offset:1024
	global_store_dwordx4 v[58:59], v[54:57], off offset:1088
	s_or_b64 exec, exec, s[6:7]
	s_and_saveexec_b64 s[4:5], s[2:3]
	s_cbranch_execz .LBB0_720
; __device__ __forceinline__ unsigned cvt_pk_bf16(float lo, float hi) { unsigned r; asm volatile("v_cvt_pk_bf16_f32 %0, %1, %2" : "=v"(r) : "v"(lo), "v"(hi)); return r; }
; __device__ __forceinline__ float bflo(unsigned w) { return __uint_as_float(w << 16); }
; __device__ __forceinline__ float bfhi(unsigned w) { return __uint_as_float(w & 0xffff0000u); }
; __global__ void __launch_bounds__(512, 2) mega_fwd(Params P) {
;     ...
;                         for (int q = 0; q < 4; ++q) { const size_t idx = idx0 + (size_t)q * GT; if (idx < (size_t)T_TOK * 32) {
;                             const int row = (int)(idx >> 5), sub = (int)(idx & 31), qk = sub >> 4, h = (sub >> 2) & 3, c = sub & 3;
;                             bf16_t* p = Z + (size_t)row * ZW + 512 + qk * 256 + h * 64 + c * 8; const float ksc = qk ? 0.125f : 1.0f; float o1[8], o2[8];
; #pragma unroll
;                             for (int e = 0; e < 8; ++e) { const unsigned wa = av[q][e >> 1], wb = bv4[q][e >> 1]; const float x1 = (e & 1) ? bfhi(wa) : bflo(wa), x2 = (e & 1) ? bfhi(wb) : bflo(wb);
;                                 const float cs_ = tv[q][e >> 1][(e & 1) * 2], sn_ = tv[q][e >> 1][(e & 1) * 2 + 1]; o1[e] = (x1 * cs_ - x2 * sn_) * ksc; o2[e] = (x1 * sn_ + x2 * cs_) * ksc; }
;                             u32x4 wa, wb; wa.x = cvt_pk_bf16(o1[0], o1[1]); wa.y = cvt_pk_bf16(o1[2], o1[3]); wa.z = cvt_pk_bf16(o1[4], o1[5]); wa.w = cvt_pk_bf16(o1[6], o1[7]);
;                             wb.x = cvt_pk_bf16(o2[0], o2[1]); wb.y = cvt_pk_bf16(o2[2], o2[3]); wb.z = cvt_pk_bf16(o2[4], o2[5]); wb.w = cvt_pk_bf16(o2[6], o2[7]);
;                             *(u32x4*)p = wa; *(u32x4*)(p + 32) = wb; } }
.LBB0_722:
	v_alignbit_b32 v52, v85, v84, 5
	v_mov_b64_e32 v[50:51], s[14:15]
	v_mad_u64_u32 v[50:51], s[2:3], v52, s57, v[50:51]
	v_mov_b32_e32 v52, v51
	v_lshrrev_b32_e32 v51, 5, v85
	v_mad_u64_u32 v[52:53], s[2:3], v51, s57, v[52:53]
	v_mov_b32_e32 v51, v52
	v_lshlrev_b32_e32 v53, 16, v30
	v_lshlrev_b32_e32 v52, 16, v34
	v_pk_mul_f32 v[54:55], v[46:47], v[52:53] op_sel:[0,1] op_sel_hi:[1,0]
	v_pk_mul_f32 v[46:47], v[46:47], v[52:53]
	v_sub_f32_e32 v54, v54, v55
	v_add_f32_e32 v46, v47, v46
	v_mul_f32_e32 v55, v90, v46
	v_and_b32_e32 v47, 0xffff0000, v30
	v_and_b32_e32 v46, 0xffff0000, v34
	v_pk_mul_f32 v[52:53], v[48:49], v[46:47] op_sel:[0,1] op_sel_hi:[1,0]
	v_pk_mul_f32 v[46:47], v[48:49], v[46:47]
	v_sub_f32_e32 v30, v52, v53
	v_mul_f32_e32 v52, v90, v30
	v_add_f32_e32 v30, v47, v46
	v_lshlrev_b32_e32 v47, 16, v31
	v_lshlrev_b32_e32 v46, 16, v35
	v_pk_mul_f32 v[48:49], v[42:43], v[46:47] op_sel:[0,1] op_sel_hi:[1,0]
	v_mul_f32_e32 v53, v90, v30
	v_sub_f32_e32 v30, v48, v49
	v_pk_mul_f32 v[42:43], v[42:43], v[46:47]
	v_mul_f32_e32 v48, v90, v30
	v_add_f32_e32 v30, v43, v42
	v_mul_f32_e32 v42, v90, v30
	v_and_b32_e32 v31, 0xffff0000, v31
	v_and_b32_e32 v30, 0xffff0000, v35
	v_pk_mul_f32 v[34:35], v[44:45], v[30:31] op_sel:[0,1] op_sel_hi:[1,0]
	v_pk_mul_f32 v[30:31], v[44:45], v[30:31]
	v_sub_f32_e32 v34, v34, v35
	v_add_f32_e32 v30, v31, v30
	v_mul_f32_e32 v44, v90, v30
	v_lshlrev_b32_e32 v31, 16, v32
	v_lshlrev_b32_e32 v30, 16, v36
	v_mul_f32_e32 v43, v90, v34
	v_pk_mul_f32 v[34:35], v[38:39], v[30:31] op_sel:[0,1] op_sel_hi:[1,0]
	v_pk_mul_f32 v[30:31], v[38:39], v[30:31]
	v_sub_f32_e32 v34, v34, v35
	v_add_f32_e32 v30, v31, v30
	v_mul_f32_e32 v38, v90, v30
	v_and_b32_e32 v31, 0xffff0000, v32
	v_and_b32_e32 v30, 0xffff0000, v36
	v_mul_f32_e32 v45, v90, v34
	v_pk_mul_f32 v[34:35], v[40:41], v[30:31] op_sel:[0,1] op_sel_hi:[1,0]
	v_pk_mul_f32 v[30:31], v[40:41], v[30:31]
	v_sub_f32_e32 v32, v34, v35
	v_add_f32_e32 v30, v31, v30
	v_mul_f32_e32 v36, v90, v30
	v_lshlrev_b32_e32 v31, 16, v33
	v_lshlrev_b32_e32 v30, 16, v37
	v_pk_mul_f32 v[34:35], v[26:27], v[30:31] op_sel:[0,1] op_sel_hi:[1,0]
	v_pk_mul_f32 v[26:27], v[26:27], v[30:31]
	v_mov_b32_e32 v89, v1
	v_add_f32_e32 v26, v27, v26
	v_mul_f32_e32 v40, v90, v26
	v_and_b32_e32 v27, 0xffff0000, v33
	v_and_b32_e32 v26, 0xffff0000, v37
	v_lshl_add_u64 v[50:51], v[50:51], 0, v[88:89]
	v_pk_mul_f32 v[30:31], v[28:29], v[26:27] op_sel:[0,1] op_sel_hi:[1,0]
	v_pk_mul_f32 v[26:27], v[28:29], v[26:27]
	v_lshl_add_u64 v[50:51], v[50:51], 0, v[0:1]
	v_sub_f32_e32 v34, v34, v35
	v_sub_f32_e32 v30, v30, v31
	v_add_f32_e32 v26, v27, v26
	v_mov_b32_e32 v81, v1
	v_mul_f32_e32 v54, v90, v54
	v_mul_f32_e32 v32, v90, v32
	v_mul_f32_e32 v39, v90, v34
	v_mul_f32_e32 v30, v90, v30
	v_mul_f32_e32 v33, v90, v26
	v_lshl_add_u64 v[34:35], v[50:51], 0, v[80:81]
	v_cvt_pk_bf16_f32 v26, v54, v52
	v_cvt_pk_bf16_f32 v27, v48, v43
	v_cvt_pk_bf16_f32 v28, v45, v32
	v_cvt_pk_bf16_f32 v29, v39, v30
	v_cvt_pk_bf16_f32 v30, v55, v53
	v_cvt_pk_bf16_f32 v31, v42, v44
	v_cvt_pk_bf16_f32 v32, v38, v36
	v_cvt_pk_bf16_f32 v33, v40, v33
	global_store_dwordx4 v[34:35], v[26:29], off offset:1024
	global_store_dwordx4 v[34:35], v[30:33], off offset:1088
	s_or_b64 exec, exec, s[4:5]
	s_and_saveexec_b64 s[2:3], vcc
	s_cbranch_execz .LBB0_717
.LBB0_723:
	v_alignbit_b32 v28, v83, v82, 5
	v_mov_b64_e32 v[26:27], s[14:15]
	v_mad_u64_u32 v[26:27], s[4:5], v28, s57, v[26:27]
	v_mov_b32_e32 v28, v27
	v_lshrrev_b32_e32 v27, 5, v83
	v_mad_u64_u32 v[28:29], s[4:5], v27, s57, v[28:29]
	v_mov_b32_e32 v27, v28
	v_lshlrev_b32_e32 v29, 16, v6
	v_lshlrev_b32_e32 v28, 16, v10
	v_mov_b32_e32 v89, v1
	v_pk_mul_f32 v[30:31], v[22:23], v[28:29] op_sel:[0,1] op_sel_hi:[1,0]
	v_pk_mul_f32 v[22:23], v[22:23], v[28:29]
	v_lshl_add_u64 v[26:27], v[26:27], 0, v[88:89]
	v_add_f32_e32 v22, v23, v22
	v_lshl_add_u64 v[26:27], v[26:27], 0, v[0:1]
	v_sub_f32_e32 v0, v30, v31
	v_mul_f32_e32 v30, v90, v22
	v_and_b32_e32 v23, 0xffff0000, v6
	v_and_b32_e32 v22, 0xffff0000, v10
	v_pk_mul_f32 v[28:29], v[24:25], v[22:23] op_sel:[0,1] op_sel_hi:[1,0]
	v_pk_mul_f32 v[22:23], v[24:25], v[22:23]
	v_sub_f32_e32 v6, v28, v29
	v_mul_f32_e32 v28, v90, v6
	v_add_f32_e32 v6, v23, v22
	v_lshlrev_b32_e32 v23, 16, v7
	v_lshlrev_b32_e32 v22, 16, v11
	v_pk_mul_f32 v[24:25], v[18:19], v[22:23] op_sel:[0,1] op_sel_hi:[1,0]
	v_mul_f32_e32 v29, v90, v6
	v_sub_f32_e32 v6, v24, v25
	v_pk_mul_f32 v[18:19], v[18:19], v[22:23]
	v_mul_f32_e32 v24, v90, v6
	v_add_f32_e32 v6, v19, v18
	v_mul_f32_e32 v18, v90, v6
	v_and_b32_e32 v7, 0xffff0000, v7
	v_and_b32_e32 v6, 0xffff0000, v11
	v_pk_mul_f32 v[10:11], v[20:21], v[6:7] op_sel:[0,1] op_sel_hi:[1,0]
	v_pk_mul_f32 v[6:7], v[20:21], v[6:7]
	v_sub_f32_e32 v10, v10, v11
	v_add_f32_e32 v6, v7, v6
	v_mul_f32_e32 v20, v90, v6
	v_lshlrev_b32_e32 v7, 16, v8
	v_lshlrev_b32_e32 v6, 16, v12
	v_mul_f32_e32 v19, v90, v10
	v_pk_mul_f32 v[10:11], v[14:15], v[6:7] op_sel:[0,1] op_sel_hi:[1,0]
	v_pk_mul_f32 v[6:7], v[14:15], v[6:7]
	v_sub_f32_e32 v10, v10, v11
	v_add_f32_e32 v6, v7, v6
	v_mul_f32_e32 v14, v90, v6
	v_and_b32_e32 v7, 0xffff0000, v8
	v_and_b32_e32 v6, 0xffff0000, v12
	v_mul_f32_e32 v21, v90, v10
	v_pk_mul_f32 v[10:11], v[16:17], v[6:7] op_sel:[0,1] op_sel_hi:[1,0]
	v_pk_mul_f32 v[6:7], v[16:17], v[6:7]
	v_sub_f32_e32 v8, v10, v11
	v_add_f32_e32 v6, v7, v6
	v_mul_f32_e32 v12, v90, v6
	v_lshlrev_b32_e32 v7, 16, v9
	v_lshlrev_b32_e32 v6, 16, v13
	v_pk_mul_f32 v[10:11], v[2:3], v[6:7] op_sel:[0,1] op_sel_hi:[1,0]
	v_pk_mul_f32 v[2:3], v[2:3], v[6:7]
	v_sub_f32_e32 v10, v10, v11
	v_add_f32_e32 v2, v3, v2
	v_mul_f32_e32 v16, v90, v2
	v_and_b32_e32 v3, 0xffff0000, v9
	v_and_b32_e32 v2, 0xffff0000, v13
	v_pk_mul_f32 v[6:7], v[4:5], v[2:3] op_sel:[0,1] op_sel_hi:[1,0]
	v_pk_mul_f32 v[2:3], v[4:5], v[2:3]
	v_sub_f32_e32 v6, v6, v7
	v_add_f32_e32 v2, v3, v2
	v_mov_b32_e32 v81, v1
	v_mul_f32_e32 v0, v90, v0
	v_mul_f32_e32 v8, v90, v8
	v_mul_f32_e32 v15, v90, v10
	v_mul_f32_e32 v6, v90, v6
	v_mul_f32_e32 v9, v90, v2
	v_lshl_add_u64 v[10:11], v[26:27], 0, v[80:81]
	v_cvt_pk_bf16_f32 v2, v0, v28
	v_cvt_pk_bf16_f32 v3, v24, v19
	v_cvt_pk_bf16_f32 v4, v21, v8
	v_cvt_pk_bf16_f32 v5, v15, v6
	v_cvt_pk_bf16_f32 v6, v30, v29
	v_cvt_pk_bf16_f32 v7, v18, v20
	v_cvt_pk_bf16_f32 v8, v14, v12
	v_cvt_pk_bf16_f32 v9, v16, v9
	global_store_dwordx4 v[10:11], v[2:5], off offset:1024
	global_store_dwordx4 v[10:11], v[6:9], off offset:1088
	s_branch .LBB0_717

; __device__ __forceinline__ unsigned short f2bf(float f) { return (unsigned short)(cvt_pk_bf16(f, 0.f) & 0xffffu); }
; __device__ __forceinline__ void s5_unit(LAS unsigned char* lw, int b, int g, const float* lam_re, const float* lam_im, const float* log_step, ...
;     ...
;     bf16x8 CfT[4];
; #pragma unroll
;     for (int kk = 0; kk < 4; ++kk)
; #pragma unroll
;         for (int e = 0; e < 8; ++e) { const int kf_ = kk * 32 + g4 * 8 + e, n_ = kf_ >> 1;
;             const float v = (kf_ & 1) ? -c_im[(size_t)(g * 16 + r) * 64 + n_] : c_re[(size_t)(g * 16 + r) * 64 + n_];
;             CfT[kk][e] = (short)f2bf(v); }
;     const f32x4 dsk4 = *(const f32x4*)(d_skip + g * 16 + g4 * 4);
;     float hr = 0.f, hi = 0.f;
;     const bf16_t* zb = Z + (size_t)b * SEQ * ZW + g * 16;
;     bf16_t* ob = Z5 + (size_t)b * SEQ * 512 + g * 16;
;     const int g4c = g4 < 2 ? g4 : 0;
;     u32x4 vnext = *(const u32x4*)(zb + (size_t)(lane >> 1) * ZW + (lane & 1) * 8);
;     u32x4 an0 = *(const u32x4*)(zb + (size_t)r * ZW + g4c * 8), an1 = *(const u32x4*)(zb + (size_t)(16 + r) * ZW + g4c * 8);
.LBB0_743:
	s_or_b64 exec, exec, s[20:21]
	v_lshl_or_b32 v11, s26, 12, v145
	global_load_dword v12, v11, s[14:15]
	s_waitcnt vmcnt(0)
	v_cvt_pk_bf16_f32 v28, v12, v1
	global_load_dword v12, v11, s[16:17]
	s_and_b32 s21, s25, 31
	s_ashr_i32 s20, s1, 5
	s_lshl_b32 s27, s26, 4
	s_mov_b32 s19, s95
	s_lshl_b32 s94, s21, 5
	s_ashr_i32 s21, s20, 31
	s_mul_i32 s29, s20, 0xa00000
	v_lshlrev_b32_e32 v94, 1, v10
	s_mul_hi_i32 s28, s20, 0xa00000
	v_mov_b32_e32 v85, v1
	v_mov_b32_e32 v95, v1
	v_mov_b32_e32 v83, v1
	s_waitcnt vmcnt(0)
	v_xor_b32_e32 v12, 0x80000000, v12
	v_cvt_pk_bf16_f32 v29, v12, v1
	global_load_dword v12, v11, s[14:15] offset:4
	s_waitcnt vmcnt(0)
	v_cvt_pk_bf16_f32 v30, v12, v1
	global_load_dword v12, v11, s[16:17] offset:4
	s_waitcnt vmcnt(0)
	v_xor_b32_e32 v12, 0x80000000, v12
	v_cvt_pk_bf16_f32 v31, v12, v1
	global_load_dword v12, v11, s[14:15] offset:8
	s_waitcnt vmcnt(0)
	v_cvt_pk_bf16_f32 v32, v12, v1
	global_load_dword v12, v11, s[16:17] offset:8
	s_waitcnt vmcnt(0)
	v_xor_b32_e32 v12, 0x80000000, v12
	v_cvt_pk_bf16_f32 v33, v12, v1
	global_load_dword v12, v11, s[14:15] offset:12
	s_waitcnt vmcnt(0)
	v_cvt_pk_bf16_f32 v34, v12, v1
	global_load_dword v12, v11, s[16:17] offset:12
	s_waitcnt vmcnt(0)
	v_xor_b32_e32 v12, 0x80000000, v12
	v_cvt_pk_bf16_f32 v35, v12, v1
	global_load_dword v12, v11, s[14:15] offset:64
	s_waitcnt vmcnt(0)
	v_cvt_pk_bf16_f32 v36, v12, v1
	global_load_dword v12, v11, s[16:17] offset:64
	s_waitcnt vmcnt(0)
	v_xor_b32_e32 v12, 0x80000000, v12
	v_cvt_pk_bf16_f32 v37, v12, v1
	global_load_dword v12, v11, s[14:15] offset:68
	s_waitcnt vmcnt(0)
	v_cvt_pk_bf16_f32 v87, v12, v1
	global_load_dword v12, v11, s[16:17] offset:68
	s_waitcnt vmcnt(0)
	v_xor_b32_e32 v12, 0x80000000, v12
	v_cvt_pk_bf16_f32 v89, v12, v1
	global_load_dword v12, v11, s[14:15] offset:72
	s_waitcnt vmcnt(0)
	v_cvt_pk_bf16_f32 v96, v12, v1
	global_load_dword v12, v11, s[16:17] offset:72
	s_waitcnt vmcnt(0)
	v_xor_b32_e32 v12, 0x80000000, v12
	v_cvt_pk_bf16_f32 v97, v12, v1
	global_load_dword v12, v11, s[14:15] offset:76
	s_waitcnt vmcnt(0)
	v_cvt_pk_bf16_f32 v98, v12, v1
	global_load_dword v12, v11, s[16:17] offset:76
	s_waitcnt vmcnt(0)
	v_xor_b32_e32 v12, 0x80000000, v12
	v_cvt_pk_bf16_f32 v99, v12, v1
	global_load_dword v12, v11, s[14:15] offset:128
	s_waitcnt vmcnt(0)
	v_cvt_pk_bf16_f32 v100, v12, v1
	global_load_dword v12, v11, s[16:17] offset:128
	s_waitcnt vmcnt(0)
	v_xor_b32_e32 v12, 0x80000000, v12
	v_cvt_pk_bf16_f32 v101, v12, v1
	global_load_dword v12, v11, s[14:15] offset:132
	s_waitcnt vmcnt(0)
	v_cvt_pk_bf16_f32 v102, v12, v1
	global_load_dword v12, v11, s[16:17] offset:132
	s_waitcnt vmcnt(0)
	v_xor_b32_e32 v12, 0x80000000, v12
	v_cvt_pk_bf16_f32 v103, v12, v1
	global_load_dword v12, v11, s[14:15] offset:136
	s_waitcnt vmcnt(0)
	v_cvt_pk_bf16_f32 v104, v12, v1
	global_load_dword v12, v11, s[16:17] offset:136
	s_waitcnt vmcnt(0)
	v_xor_b32_e32 v12, 0x80000000, v12
	v_cvt_pk_bf16_f32 v105, v12, v1
	global_load_dword v12, v11, s[14:15] offset:140
	s_waitcnt vmcnt(0)
	v_cvt_pk_bf16_f32 v106, v12, v1
	global_load_dword v12, v11, s[16:17] offset:140
	s_waitcnt vmcnt(0)
	v_xor_b32_e32 v12, 0x80000000, v12
	v_cvt_pk_bf16_f32 v107, v12, v1
	global_load_dword v12, v11, s[14:15] offset:192
	s_waitcnt vmcnt(0)
	v_cvt_pk_bf16_f32 v108, v12, v1
	global_load_dword v12, v11, s[16:17] offset:192
	s_waitcnt vmcnt(0)
	v_xor_b32_e32 v12, 0x80000000, v12
	v_cvt_pk_bf16_f32 v109, v12, v1
	global_load_dword v12, v11, s[14:15] offset:196
	s_waitcnt vmcnt(0)
	v_cvt_pk_bf16_f32 v110, v12, v1
	global_load_dword v12, v11, s[16:17] offset:196
	s_waitcnt vmcnt(0)
	v_xor_b32_e32 v12, 0x80000000, v12
	v_cvt_pk_bf16_f32 v111, v12, v1
	global_load_dword v12, v11, s[14:15] offset:200
	s_waitcnt vmcnt(0)
	v_cvt_pk_bf16_f32 v112, v12, v1
	global_load_dword v12, v11, s[16:17] offset:200
	s_waitcnt vmcnt(0)
	v_xor_b32_e32 v12, 0x80000000, v12
	v_cvt_pk_bf16_f32 v113, v12, v1
	global_load_dword v12, v11, s[14:15] offset:204
	s_waitcnt vmcnt(0)
	v_cvt_pk_bf16_f32 v114, v12, v1
	global_load_dword v54, v11, s[16:17] offset:204
	v_lshl_add_u64 v[10:11], v[72:73], 0, s[18:19]
	s_add_u32 s18, s6, s29
	s_addc_u32 s19, s7, s28
	s_lshl_b32 s26, s26, 5
	s_add_u32 s18, s18, s26
	s_addc_u32 s19, s19, 0
	v_lshl_add_u64 v[18:19], s[18:19], 0, v[84:85]
	v_lshl_add_u64 v[12:13], s[18:19], 0, v[0:1]
	v_lshl_add_u64 v[18:19], v[18:19], 0, v[94:95]
	s_mov_b32 s18, 0x14000
	v_lshl_add_u64 v[20:21], v[12:13], 0, v[82:83]
	v_add_co_u32_e32 v26, vcc, s18, v18
	s_lshl_b64 s[18:19], s[20:21], 21
	s_nop 0
	v_addc_co_u32_e32 v27, vcc, 0, v19, vcc
	s_mov_b32 s21, 0x5040100
	v_or_b32_e32 v94, s29, v94
	v_mov_b32_e32 v95, s28
	s_waitcnt vmcnt(0)
	v_xor_b32_e32 v12, 0x80000000, v54
	v_cvt_pk_bf16_f32 v83, v12, v1
	global_load_dwordx4 v[10:13], v[10:11], off
	s_nop 0
	global_load_dwordx4 v[62:65], v[20:21], off
	global_load_dwordx4 v[58:61], v[18:19], off
	global_load_dwordx4 v[54:57], v[26:27], off
	v_perm_b32 v18, v29, v28, s21
	v_perm_b32 v19, v31, v30, s21
	v_perm_b32 v20, v33, v32, s21
	v_perm_b32 v21, v35, v34, s21
	v_perm_b32 v26, v37, v36, s21
	v_perm_b32 v27, v89, v87, s21
	v_perm_b32 v28, v97, v96, s21
	v_perm_b32 v29, v99, v98, s21
	v_perm_b32 v30, v101, v100, s21
	v_perm_b32 v31, v103, v102, s21
	v_perm_b32 v32, v105, v104, s21
	v_perm_b32 v33, v107, v106, s21
	v_perm_b32 v34, v109, v108, s21
	v_perm_b32 v35, v111, v110, s21
	v_perm_b32 v36, v113, v112, s21
	v_perm_b32 v37, v83, v114, s21
	v_lshl_add_u64 v[102:103], v[76:77], 0, v[94:95]
	v_lshl_add_u64 v[104:105], v[78:79], 0, v[94:95]
	v_mad_i64_i32 v[106:107], s[20:21], s20, v223, v[80:81]
	v_mov_b32_e32 v94, 0
	v_mov_b32_e32 v96, v90
	v_mov_b32_e32 v97, v90
	v_mov_b32_e32 v98, v91
	v_mov_b32_e32 v99, v91
	v_lshl_add_u64 v[100:101], v[74:75], 0, s[18:19]
	s_mov_b32 s20, 63
	v_mov_b32_e32 v95, v94
; #define LAS __attribute__((address_space(3)))
; __device__ __forceinline__ float bflo(unsigned w) { return __uint_as_float(w << 16); }
; __device__ __forceinline__ float bfhi(unsigned w) { return __uint_as_float(w & 0xffff0000u); }
; #define WSYNC() asm volatile("s_waitcnt lgkmcnt(0)" ::: "memory")
; __device__ __forceinline__ void s5_unit(LAS unsigned char* lw, int b, int g, const float* lam_re, const float* lam_im, const float* log_step, ...
;     ...
;     for (int tc = 0; tc < SEQ / 32; ++tc) {
;         const int t0 = tc * 32;
;         u32x4 a0 = an0, a1 = an1; if (g4 >= 2) { a0 = (u32x4){0u, 0u, 0u, 0u}; a1 = a0; }
;         { const int tk = lane >> 1, hf = lane & 1; const u32x4 v = vnext;
;           if (tc + 1 < SEQ / 32) { vnext = *(const u32x4*)(zb + (size_t)(t0 + 32 + tk) * ZW + hf * 8);
;               an0 = *(const u32x4*)(zb + (size_t)(t0 + 32 + r) * ZW + g4c * 8); an1 = *(const u32x4*)(zb + (size_t)(t0 + 48 + r) * ZW + g4c * 8); }
;           f32x4 a, c2; a[0] = bflo(v.x); a[1] = bfhi(v.x); a[2] = bflo(v.y); a[3] = bfhi(v.y); c2[0] = bflo(v.z); c2[1] = bfhi(v.z); c2[2] = bflo(v.w); c2[3] = bfhi(v.w);
;           *(LAS f32x4*)(U + tk * 16 + hf * 8) = a; *(LAS f32x4*)(U + tk * 16 + hf * 8 + 4) = c2; }
; #pragma unroll
;         for (int rb = 0; rb < 2; ++rb) { const bf16x8 af = __builtin_bit_cast(bf16x8, rb ? a1 : a0);
; #pragma unroll
;             for (int nb = 0; nb < 8; ++nb) { const f32x4 xa = __builtin_amdgcn_mfma_f32_16x16x32_bf16(Bf[nb], af, (f32x4){0.f, 0.f, 0.f, 0.f}, 0, 0, 0);
;                 *(LAS f32x4*)(Xs + (rb * 16 + r) * 132 + nb * 16 + g4 * 4) = xa; } }
;         WSYNC();
;         {
;             float xrv[32], xiv[32]; unsigned hp[32];
; #pragma unroll
;             for (int t = 0; t < 32; ++t) { xrv[t] = Xs[t * 132 + n]; xiv[t] = Xs[t * 132 + 64 + n]; }
.LBB0_744:
	s_waitcnt vmcnt(0) lgkmcnt(0)
	v_mov_b64_e32 v[126:127], v[56:57]
	v_mov_b64_e32 v[124:125], v[54:55]
	v_mov_b64_e32 v[150:151], v[64:65]
	v_lshl_add_u64 v[54:55], v[106:107], 0, s[94:95]
	v_mov_b64_e32 v[148:149], v[62:63]
	global_load_dwordx4 v[62:65], v[54:55], off
	v_lshl_add_u64 v[54:55], v[104:105], 0, s[94:95]
	v_cndmask_b32_e64 v111, v61, 0, s[4:5]
	v_cndmask_b32_e64 v110, v60, 0, s[4:5]
	v_cndmask_b32_e64 v109, v59, 0, s[4:5]
	v_cndmask_b32_e64 v108, v58, 0, s[4:5]
	global_load_dwordx4 v[58:61], v[54:55], off
	v_lshl_add_u64 v[54:55], v[102:103], 0, s[94:95]
	global_load_dwordx4 v[54:57], v[54:55], off
	v_mfma_f32_16x16x32_bf16 v[112:115], v[6:9], v[108:111], 0
	v_cndmask_b32_e64 v127, v127, 0, s[4:5]
	v_cndmask_b32_e64 v126, v126, 0, s[4:5]
	v_cndmask_b32_e64 v125, v125, 0, s[4:5]
	v_mfma_f32_16x16x32_bf16 v[116:119], v[2:5], v[108:111], 0
	v_cndmask_b32_e64 v124, v124, 0, s[4:5]
	v_lshlrev_b32_e32 v160, 16, v148
	v_and_b32_e32 v161, 0xffff0000, v148
	v_mfma_f32_16x16x32_bf16 v[128:131], v[14:17], v[108:111], 0
	v_lshlrev_b32_e32 v162, 16, v149
	v_and_b32_e32 v163, 0xffff0000, v149
	v_lshlrev_b32_e32 v148, 16, v150
	v_mfma_f32_16x16x32_bf16 v[164:167], v[50:53], v[108:111], 0
	v_and_b32_e32 v149, 0xffff0000, v150
	v_lshlrev_b32_e32 v150, 16, v151
	v_and_b32_e32 v151, 0xffff0000, v151
	v_mfma_f32_16x16x32_bf16 v[120:123], v[22:25], v[108:111], 0
	ds_write_b128 v142, v[160:163]
	ds_write_b128 v142, v[148:151] offset:16
	ds_write_b128 v146, v[112:115] offset:10752
	ds_write_b128 v146, v[116:119] offset:10816
	s_nop 3
	ds_write_b128 v146, v[120:123] offset:10880
	v_add_u32_e32 v85, 0xd0, v144
	v_mfma_f32_16x16x32_bf16 v[152:155], v[42:45], v[108:111], 0
	v_add_u32_e32 v89, 0xe0, v144
	v_add_u32_e32 v83, 0xf0, v144
	v_mfma_f32_16x16x32_bf16 v[156:159], v[38:41], v[108:111], 0
	ds_write_b128 v146, v[128:131] offset:10944
	s_nop 3
	ds_write_b128 v146, v[152:155] offset:11008
	s_nop 1
	ds_write_b128 v146, v[156:159] offset:11072
	v_add_u32_e32 v158, 16, v144
	v_mfma_f32_16x16x32_bf16 v[108:111], v[46:49], v[108:111], 0
	v_add_u32_e32 v159, 32, v144
	v_add_u32_e32 v156, 48, v144
	v_add_u32_e32 v157, 64, v144
	v_mfma_f32_16x16x32_bf16 v[172:175], v[2:5], v[124:127], 0
	v_add_u32_e32 v154, 0x50, v144
	v_add_u32_e32 v155, 0x60, v144
	v_add_u32_e32 v152, 0x70, v144
	v_mfma_f32_16x16x32_bf16 v[168:171], v[6:9], v[124:127], 0
	ds_write_b128 v146, v[164:167] offset:11136
	ds_write_b128 v146, v[108:111] offset:11200
	s_nop 5
	ds_write_b128 v146, v[168:171] offset:19200
	v_add_u32_e32 v153, 0x80, v144
	v_mfma_f32_16x16x32_bf16 v[148:151], v[22:25], v[124:127], 0
	v_mfma_f32_16x16x32_bf16 v[112:115], v[14:17], v[124:127], 0
	ds_write_b128 v146, v[172:175] offset:19264
	s_nop 5
	ds_write_b128 v146, v[148:151] offset:19328
	ds_write_b128 v146, v[112:115] offset:19392
	v_add_u32_e32 v150, 0x90, v144
	v_mfma_f32_16x16x32_bf16 v[116:119], v[42:45], v[124:127], 0
	v_add_u32_e32 v151, 0xa0, v144
	v_add_u32_e32 v148, 0xb0, v144
	v_add_u32_e32 v149, 0xc0, v144
	v_mfma_f32_16x16x32_bf16 v[108:111], v[38:41], v[124:127], 0
	v_mfma_f32_16x16x32_bf16 v[112:115], v[50:53], v[124:127], 0
	s_nop 2
	ds_write_b128 v146, v[116:119] offset:19456
	s_nop 2
	ds_write_b128 v146, v[108:111] offset:19520
	ds_write_b128 v146, v[112:115] offset:19584
	v_mfma_f32_16x16x32_bf16 v[108:111], v[46:49], v[124:127], 0
	s_nop 7
	ds_write_b128 v146, v[108:111] offset:19648
	s_waitcnt lgkmcnt(0)
	ds_read2st64_b32 v[160:161], v144 offset0:42 offset1:43
	ds_read2st64_b32 v[162:163], v144 offset0:75 offset1:76
	ds_read2st64_b32 v[164:165], v158 offset0:44 offset1:45
	ds_read2st64_b32 v[166:167], v158 offset0:77 offset1:78
	ds_read2st64_b32 v[168:169], v159 offset0:46 offset1:47
	ds_read2st64_b32 v[170:171], v159 offset0:79 offset1:80
	ds_read2st64_b32 v[172:173], v156 offset0:48 offset1:49
	ds_read2st64_b32 v[132:133], v156 offset0:81 offset1:82
	ds_read2st64_b32 v[174:175], v157 offset0:50 offset1:51
	ds_read2st64_b32 v[130:131], v157 offset0:83 offset1:84
	ds_read2st64_b32 v[176:177], v154 offset0:52 offset1:53
	ds_read2st64_b32 v[128:129], v154 offset0:85 offset1:86
	ds_read2st64_b32 v[178:179], v155 offset0:54 offset1:55
	ds_read2st64_b32 v[126:127], v155 offset0:87 offset1:88
	ds_read2st64_b32 v[180:181], v152 offset0:56 offset1:57
	ds_read2st64_b32 v[124:125], v152 offset0:89 offset1:90
	ds_read2st64_b32 v[182:183], v153 offset0:58 offset1:59
	ds_read2st64_b32 v[122:123], v153 offset0:91 offset1:92
	ds_read2st64_b32 v[184:185], v150 offset0:60 offset1:61
	ds_read2st64_b32 v[120:121], v150 offset0:93 offset1:94
	ds_read2st64_b32 v[194:195], v151 offset0:62 offset1:63
	ds_read2st64_b32 v[118:119], v151 offset0:95 offset1:96
	ds_read2st64_b32 v[196:197], v148 offset0:64 offset1:65
	ds_read2st64_b32 v[116:117], v148 offset0:97 offset1:98
	ds_read2st64_b32 v[198:199], v149 offset0:66 offset1:67
	ds_read2st64_b32 v[114:115], v149 offset0:99 offset1:100
	ds_read2st64_b32 v[200:201], v85 offset0:68 offset1:69
	ds_read2st64_b32 v[112:113], v85 offset0:101 offset1:102
	ds_read2st64_b32 v[202:203], v89 offset0:70 offset1:71
	ds_read2st64_b32 v[110:111], v89 offset0:103 offset1:104
	ds_read2st64_b32 v[204:205], v83 offset0:72 offset1:73
	ds_read2st64_b32 v[108:109], v83 offset0:105 offset1:106
	v_pk_mul_f32 v[206:207], v[90:91], v[94:95]
	v_pk_mul_f32 v[94:95], v[92:93], v[94:95]
	v_sub_f32_e32 v87, v206, v207
	s_waitcnt lgkmcnt(0)
; __device__ __forceinline__ unsigned cvt_pk_bf16(float lo, float hi) { unsigned r; asm volatile("v_cvt_pk_bf16_f32 %0, %1, %2" : "=v"(r) : "v"(lo), "v"(hi)); return r; }
; __device__ __forceinline__ void s5_unit(LAS unsigned char* lw, int b, int g, const float* lam_re, const float* lam_im, const float* log_step, ...
;     ...
; #pragma unroll
;             for (int t = 0; t < 32; ++t) { const float nhr = are * hr - aim * hi + xrv[t], nhi = are * hi + aim * hr + xiv[t]; hr = nhr; hi = nhi; hp[t] = cvt_pk_bf16(hr, hi); }
	v_add_f32_e32 v160, v87, v160
	v_add_f32_e32 v87, v94, v95
	v_add_f32_e32 v94, v87, v161
	v_cvt_pk_bf16_f32 v87, v160, v94
	v_pk_mul_f32 v[94:95], v[92:93], v[94:95] op_sel_hi:[1,0]
	s_nop 0
	v_pk_fma_f32 v[206:207], v[90:91], v[160:161], v[94:95] neg_lo:[0,0,1] neg_hi:[0,0,1]
	v_pk_fma_f32 v[94:95], v[90:91], v[160:161], v[94:95] op_sel_hi:[1,0,1]
	s_nop 0
	v_mov_b32_e32 v207, v95
	v_pk_add_f32 v[94:95], v[164:165], v[206:207]
	s_nop 0
	v_cvt_pk_bf16_f32 v206, v94, v95
	v_pk_mul_f32 v[160:161], v[90:91], v[94:95]
	v_pk_mul_f32 v[94:95], v[90:91], v[94:95] op_sel:[0,1] op_sel_hi:[1,0]
	v_sub_f32_e32 v160, v160, v161
	v_add_f32_e32 v94, v94, v95
	v_add_f32_e32 v94, v169, v94
	v_add_f32_e32 v160, v168, v160
	v_cvt_pk_bf16_f32 v168, v160, v94
	v_pk_mul_f32 v[94:95], v[92:93], v[94:95] op_sel_hi:[1,0]
	s_nop 0
	v_pk_fma_f32 v[164:165], v[90:91], v[160:161], v[94:95] neg_lo:[0,0,1] neg_hi:[0,0,1]
	v_pk_fma_f32 v[94:95], v[90:91], v[160:161], v[94:95] op_sel_hi:[1,0,1]
	s_nop 0
	v_mov_b32_e32 v165, v95
	v_pk_add_f32 v[94:95], v[172:173], v[164:165]
	s_nop 0
	v_cvt_pk_bf16_f32 v169, v94, v95
	v_pk_mul_f32 v[160:161], v[90:91], v[94:95]
	v_pk_mul_f32 v[94:95], v[90:91], v[94:95] op_sel:[0,1] op_sel_hi:[1,0]
	v_sub_f32_e32 v160, v160, v161
	v_add_f32_e32 v94, v94, v95
	v_add_f32_e32 v94, v175, v94
	v_add_f32_e32 v160, v174, v160
	v_cvt_pk_bf16_f32 v172, v160, v94
	v_pk_mul_f32 v[94:95], v[92:93], v[94:95] op_sel_hi:[1,0]
	s_nop 0
	v_pk_fma_f32 v[164:165], v[90:91], v[160:161], v[94:95] neg_lo:[0,0,1] neg_hi:[0,0,1]
	v_pk_fma_f32 v[94:95], v[90:91], v[160:161], v[94:95] op_sel_hi:[1,0,1]
	s_nop 0
	v_mov_b32_e32 v165, v95
	v_pk_add_f32 v[94:95], v[176:177], v[164:165]
	s_nop 0
	v_cvt_pk_bf16_f32 v173, v94, v95
	v_pk_mul_f32 v[160:161], v[90:91], v[94:95]
	v_pk_mul_f32 v[94:95], v[90:91], v[94:95] op_sel:[0,1] op_sel_hi:[1,0]
	v_sub_f32_e32 v160, v160, v161
	v_add_f32_e32 v94, v94, v95
	v_add_f32_e32 v94, v179, v94
	v_add_f32_e32 v160, v178, v160
	v_cvt_pk_bf16_f32 v174, v160, v94
	v_pk_mul_f32 v[94:95], v[92:93], v[94:95] op_sel_hi:[1,0]
	s_nop 0
	v_pk_fma_f32 v[164:165], v[90:91], v[160:161], v[94:95] neg_lo:[0,0,1] neg_hi:[0,0,1]
	v_pk_fma_f32 v[94:95], v[90:91], v[160:161], v[94:95] op_sel_hi:[1,0,1]
	s_nop 0
	v_mov_b32_e32 v165, v95
	v_pk_add_f32 v[94:95], v[180:181], v[164:165]
	s_nop 0
	v_cvt_pk_bf16_f32 v175, v94, v95
	v_pk_mul_f32 v[160:161], v[90:91], v[94:95]
	v_pk_mul_f32 v[94:95], v[90:91], v[94:95] op_sel:[0,1] op_sel_hi:[1,0]
	v_sub_f32_e32 v160, v160, v161
	v_add_f32_e32 v94, v94, v95
	v_add_f32_e32 v94, v183, v94
	v_add_f32_e32 v160, v182, v160
	v_cvt_pk_bf16_f32 v176, v160, v94
	v_pk_mul_f32 v[94:95], v[92:93], v[94:95] op_sel_hi:[1,0]
	s_nop 0
	v_pk_fma_f32 v[164:165], v[90:91], v[160:161], v[94:95] neg_lo:[0,0,1] neg_hi:[0,0,1]
	v_pk_fma_f32 v[94:95], v[90:91], v[160:161], v[94:95] op_sel_hi:[1,0,1]
	s_nop 0
	v_mov_b32_e32 v165, v95
	v_pk_add_f32 v[94:95], v[184:185], v[164:165]
	s_nop 0
	v_cvt_pk_bf16_f32 v177, v94, v95
	v_pk_mul_f32 v[160:161], v[90:91], v[94:95]
	v_pk_mul_f32 v[94:95], v[90:91], v[94:95] op_sel:[0,1] op_sel_hi:[1,0]
	v_sub_f32_e32 v160, v160, v161
	v_add_f32_e32 v94, v94, v95
	v_add_f32_e32 v94, v195, v94
	v_add_f32_e32 v160, v194, v160
	v_cvt_pk_bf16_f32 v178, v160, v94
	v_pk_mul_f32 v[94:95], v[92:93], v[94:95] op_sel_hi:[1,0]
	s_nop 0
	v_pk_fma_f32 v[164:165], v[90:91], v[160:161], v[94:95] neg_lo:[0,0,1] neg_hi:[0,0,1]
	v_pk_fma_f32 v[94:95], v[90:91], v[160:161], v[94:95] op_sel_hi:[1,0,1]
	s_nop 0
	v_mov_b32_e32 v165, v95
	v_pk_add_f32 v[94:95], v[196:197], v[164:165]
	s_nop 0
	v_cvt_pk_bf16_f32 v179, v94, v95
	v_pk_mul_f32 v[160:161], v[90:91], v[94:95]
	v_pk_mul_f32 v[94:95], v[90:91], v[94:95] op_sel:[0,1] op_sel_hi:[1,0]
	v_sub_f32_e32 v160, v160, v161
	v_add_f32_e32 v94, v94, v95
	v_add_f32_e32 v94, v199, v94
	v_add_f32_e32 v160, v198, v160
	v_cvt_pk_bf16_f32 v180, v160, v94
	v_pk_mul_f32 v[94:95], v[92:93], v[94:95] op_sel_hi:[1,0]
	s_nop 0
	v_pk_fma_f32 v[164:165], v[90:91], v[160:161], v[94:95] neg_lo:[0,0,1] neg_hi:[0,0,1]
	v_pk_fma_f32 v[94:95], v[90:91], v[160:161], v[94:95] op_sel_hi:[1,0,1]
	s_nop 0
	v_mov_b32_e32 v165, v95
	v_pk_add_f32 v[94:95], v[200:201], v[164:165]
	s_nop 0
	v_cvt_pk_bf16_f32 v181, v94, v95
	v_pk_mul_f32 v[160:161], v[90:91], v[94:95]
	v_pk_mul_f32 v[94:95], v[90:91], v[94:95] op_sel:[0,1] op_sel_hi:[1,0]
	v_sub_f32_e32 v160, v160, v161
	v_add_f32_e32 v94, v94, v95
	v_add_f32_e32 v94, v203, v94
	v_add_f32_e32 v160, v202, v160
	v_cvt_pk_bf16_f32 v182, v160, v94
	v_pk_mul_f32 v[94:95], v[92:93], v[94:95] op_sel_hi:[1,0]
	s_nop 0
	v_pk_fma_f32 v[164:165], v[90:91], v[160:161], v[94:95] neg_lo:[0,0,1] neg_hi:[0,0,1]
	v_pk_fma_f32 v[94:95], v[90:91], v[160:161], v[94:95] op_sel_hi:[1,0,1]
	s_nop 0
	v_mov_b32_e32 v165, v95
	v_pk_add_f32 v[94:95], v[204:205], v[164:165]
	s_nop 0
	v_cvt_pk_bf16_f32 v164, v94, v95
	v_pk_mul_f32 v[160:161], v[90:91], v[94:95]
	v_pk_mul_f32 v[94:95], v[90:91], v[94:95] op_sel:[0,1] op_sel_hi:[1,0]
	v_sub_f32_e32 v160, v160, v161
	v_add_f32_e32 v94, v94, v95
	v_add_f32_e32 v94, v163, v94
	v_add_f32_e32 v160, v162, v160
	v_cvt_pk_bf16_f32 v165, v160, v94
	v_pk_mul_f32 v[94:95], v[90:91], v[94:95] op_sel_hi:[1,0]
	s_nop 0
	v_pk_fma_f32 v[162:163], v[92:93], v[160:161], v[94:95]
	v_pk_fma_f32 v[94:95], v[92:93], v[160:161], v[94:95] op_sel_hi:[1,0,1] neg_lo:[0,0,1] neg_hi:[0,0,1]
	s_nop 0
	v_mov_b32_e32 v163, v95
	v_mov_b32_e32 v94, v167
	v_mov_b32_e32 v95, v166
	v_pk_add_f32 v[94:95], v[94:95], v[162:163]
	s_nop 0
	v_pk_mul_f32 v[160:161], v[98:99], v[94:95]
	v_cvt_pk_bf16_f32 v166, v95, v94
	s_nop 0
	v_pk_fma_f32 v[162:163], v[96:97], v[94:95], v[160:161] op_sel:[0,0,1] op_sel_hi:[1,1,0]
; __device__ __forceinline__ unsigned cvt_pk_bf16(float lo, float hi) { unsigned r; asm volatile("v_cvt_pk_bf16_f32 %0, %1, %2" : "=v"(r) : "v"(lo), "v"(hi)); return r; }
; #define LAS __attribute__((address_space(3)))
; __device__ __forceinline__ void s5_unit(LAS unsigned char* lw, int b, int g, const float* lam_re, const float* lam_im, const float* log_step, ...
;     ...
;             for (int t = 0; t < 32; ++t) { const float nhr = are * hr - aim * hi + xrv[t], nhi = are * hi + aim * hr + xiv[t]; hr = nhr; hi = nhi; hp[t] = cvt_pk_bf16(hr, hi); }
;             __builtin_amdgcn_sched_barrier(0);
; #pragma unroll
;             for (int t = 0; t < 32; ++t) *(LAS unsigned*)(H + t * 136 + 2 * n) = hp[t];
	v_pk_fma_f32 v[94:95], v[96:97], v[94:95], v[160:161] op_sel:[0,0,1] op_sel_hi:[1,1,0] neg_lo:[0,0,1] neg_hi:[0,0,1]
	s_nop 0
	v_mov_b32_e32 v163, v95
	v_mov_b32_e32 v94, v171
	v_mov_b32_e32 v95, v170
	v_pk_add_f32 v[94:95], v[94:95], v[162:163]
	s_nop 0
	v_pk_mul_f32 v[160:161], v[98:99], v[94:95]
	v_cvt_pk_bf16_f32 v167, v95, v94
	s_nop 0
	v_pk_fma_f32 v[162:163], v[96:97], v[94:95], v[160:161] op_sel:[0,0,1] op_sel_hi:[1,1,0]
	v_pk_fma_f32 v[94:95], v[96:97], v[94:95], v[160:161] op_sel:[0,0,1] op_sel_hi:[1,1,0] neg_lo:[0,0,1] neg_hi:[0,0,1]
	s_nop 0
	v_mov_b32_e32 v163, v95
	v_mov_b32_e32 v94, v133
	v_mov_b32_e32 v95, v132
	v_pk_add_f32 v[94:95], v[94:95], v[162:163]
	s_nop 0
	v_pk_mul_f32 v[132:133], v[98:99], v[94:95]
	v_cvt_pk_bf16_f32 v162, v95, v94
	s_nop 0
	v_pk_fma_f32 v[160:161], v[96:97], v[94:95], v[132:133] op_sel:[0,0,1] op_sel_hi:[1,1,0]
	v_pk_fma_f32 v[94:95], v[96:97], v[94:95], v[132:133] op_sel:[0,0,1] op_sel_hi:[1,1,0] neg_lo:[0,0,1] neg_hi:[0,0,1]
	s_nop 0
	v_mov_b32_e32 v161, v95
	v_mov_b32_e32 v94, v131
	v_mov_b32_e32 v95, v130
	v_pk_add_f32 v[94:95], v[94:95], v[160:161]
	s_nop 0
	v_mul_f32_e32 v130, v91, v94
	v_mul_f32_e32 v132, v90, v94
	v_cvt_pk_bf16_f32 v133, v95, v94
	v_pk_fma_f32 v[130:131], v[90:91], v[94:95], v[130:131] op_sel:[0,1,0] op_sel_hi:[1,0,0] neg_lo:[0,0,1] neg_hi:[0,0,1]
	v_pk_fma_f32 v[94:95], v[90:91], v[94:95], v[132:133] op_sel_hi:[1,1,0]
	s_nop 0
	v_mov_b32_e32 v131, v95
	v_pk_add_f32 v[94:95], v[128:129], v[130:131]
	s_nop 0
	v_pk_mul_f32 v[128:129], v[98:99], v[94:95]
	v_cvt_pk_bf16_f32 v132, v94, v95
	s_nop 0
	v_pk_fma_f32 v[130:131], v[96:97], v[94:95], v[128:129] op_sel:[0,0,1] op_sel_hi:[1,1,0] neg_lo:[0,0,1] neg_hi:[0,0,1]
	v_pk_fma_f32 v[94:95], v[96:97], v[94:95], v[128:129] op_sel:[0,0,1] op_sel_hi:[1,1,0]
	s_nop 0
	v_mov_b32_e32 v131, v95
	v_pk_add_f32 v[94:95], v[126:127], v[130:131]
	s_nop 0
	v_pk_mul_f32 v[126:127], v[98:99], v[94:95]
	v_cvt_pk_bf16_f32 v130, v94, v95
	s_nop 0
	v_pk_fma_f32 v[128:129], v[96:97], v[94:95], v[126:127] op_sel:[0,0,1] op_sel_hi:[1,1,0] neg_lo:[0,0,1] neg_hi:[0,0,1]
	v_pk_fma_f32 v[94:95], v[96:97], v[94:95], v[126:127] op_sel:[0,0,1] op_sel_hi:[1,1,0]
	s_nop 0
	v_mov_b32_e32 v129, v95
	v_pk_add_f32 v[94:95], v[124:125], v[128:129]
	s_nop 0
	v_pk_mul_f32 v[124:125], v[98:99], v[94:95]
	v_cvt_pk_bf16_f32 v128, v94, v95
	s_nop 0
	v_pk_fma_f32 v[126:127], v[96:97], v[94:95], v[124:125] op_sel:[0,0,1] op_sel_hi:[1,1,0] neg_lo:[0,0,1] neg_hi:[0,0,1]
	v_pk_fma_f32 v[94:95], v[96:97], v[94:95], v[124:125] op_sel:[0,0,1] op_sel_hi:[1,1,0]
	s_nop 0
	v_mov_b32_e32 v127, v95
	v_pk_add_f32 v[94:95], v[122:123], v[126:127]
	s_nop 0
	v_pk_mul_f32 v[122:123], v[98:99], v[94:95]
	v_cvt_pk_bf16_f32 v126, v94, v95
	s_nop 0
	v_pk_fma_f32 v[124:125], v[96:97], v[94:95], v[122:123] op_sel:[0,0,1] op_sel_hi:[1,1,0] neg_lo:[0,0,1] neg_hi:[0,0,1]
	v_pk_fma_f32 v[94:95], v[96:97], v[94:95], v[122:123] op_sel:[0,0,1] op_sel_hi:[1,1,0]
	s_nop 0
	v_mov_b32_e32 v125, v95
	v_pk_add_f32 v[94:95], v[120:121], v[124:125]
	s_nop 0
	v_pk_mul_f32 v[120:121], v[98:99], v[94:95]
	v_cvt_pk_bf16_f32 v124, v94, v95
	s_nop 0
	v_pk_fma_f32 v[122:123], v[96:97], v[94:95], v[120:121] op_sel:[0,0,1] op_sel_hi:[1,1,0] neg_lo:[0,0,1] neg_hi:[0,0,1]
	v_pk_fma_f32 v[94:95], v[96:97], v[94:95], v[120:121] op_sel:[0,0,1] op_sel_hi:[1,1,0]
	s_nop 0
	v_mov_b32_e32 v123, v95
	v_pk_add_f32 v[94:95], v[118:119], v[122:123]
	s_nop 0
	v_pk_mul_f32 v[118:119], v[98:99], v[94:95]
	v_cvt_pk_bf16_f32 v122, v94, v95
	s_nop 0
	v_pk_fma_f32 v[120:121], v[96:97], v[94:95], v[118:119] op_sel:[0,0,1] op_sel_hi:[1,1,0] neg_lo:[0,0,1] neg_hi:[0,0,1]
	v_pk_fma_f32 v[94:95], v[96:97], v[94:95], v[118:119] op_sel:[0,0,1] op_sel_hi:[1,1,0]
	s_nop 0
	v_mov_b32_e32 v121, v95
	v_pk_add_f32 v[94:95], v[116:117], v[120:121]
	s_nop 0
	v_pk_mul_f32 v[116:117], v[98:99], v[94:95]
	v_cvt_pk_bf16_f32 v120, v94, v95
	s_nop 0
	v_pk_fma_f32 v[118:119], v[96:97], v[94:95], v[116:117] op_sel:[0,0,1] op_sel_hi:[1,1,0] neg_lo:[0,0,1] neg_hi:[0,0,1]
	v_pk_fma_f32 v[94:95], v[96:97], v[94:95], v[116:117] op_sel:[0,0,1] op_sel_hi:[1,1,0]
	s_nop 0
	v_mov_b32_e32 v119, v95
	v_pk_add_f32 v[94:95], v[114:115], v[118:119]
	s_nop 0
	v_pk_mul_f32 v[114:115], v[98:99], v[94:95]
	v_cvt_pk_bf16_f32 v121, v94, v95
	s_nop 0
	v_pk_fma_f32 v[116:117], v[96:97], v[94:95], v[114:115] op_sel:[0,0,1] op_sel_hi:[1,1,0] neg_lo:[0,0,1] neg_hi:[0,0,1]
	v_pk_fma_f32 v[94:95], v[96:97], v[94:95], v[114:115] op_sel:[0,0,1] op_sel_hi:[1,1,0]
	s_nop 0
	v_mov_b32_e32 v117, v95
	v_pk_add_f32 v[94:95], v[112:113], v[116:117]
	s_nop 0
	v_pk_mul_f32 v[112:113], v[98:99], v[94:95]
	v_cvt_pk_bf16_f32 v123, v94, v95
	s_nop 0
	v_pk_fma_f32 v[114:115], v[96:97], v[94:95], v[112:113] op_sel:[0,0,1] op_sel_hi:[1,1,0] neg_lo:[0,0,1] neg_hi:[0,0,1]
	v_pk_fma_f32 v[94:95], v[96:97], v[94:95], v[112:113] op_sel:[0,0,1] op_sel_hi:[1,1,0]
	s_nop 0
	v_mov_b32_e32 v115, v95
	v_pk_add_f32 v[94:95], v[110:111], v[114:115]
	s_nop 0
	v_pk_mul_f32 v[110:111], v[98:99], v[94:95]
	v_cvt_pk_bf16_f32 v114, v94, v95
	s_nop 0
	v_pk_fma_f32 v[112:113], v[96:97], v[94:95], v[110:111] op_sel:[0,0,1] op_sel_hi:[1,1,0] neg_lo:[0,0,1] neg_hi:[0,0,1]
	v_pk_fma_f32 v[94:95], v[96:97], v[94:95], v[110:111] op_sel:[0,0,1] op_sel_hi:[1,1,0]
	s_nop 0
	v_mov_b32_e32 v113, v95
	v_pk_add_f32 v[94:95], v[108:109], v[112:113]
	s_nop 0
	v_cvt_pk_bf16_f32 v125, v94, v95
	v_add_u32_e32 v108, 0x800, v144
	v_add_u32_e32 v109, 0xc00, v144
	v_add_u32_e32 v110, 0x1000, v144
	v_add_u32_e32 v111, 0x1400, v144
	v_add_u32_e32 v118, 0x2200, v144
	ds_write2_b32 v108, v87, v206 offset1:68
	ds_write2_b32 v108, v168, v169 offset0:136 offset1:204
	ds_write2_b32 v109, v172, v173 offset0:16 offset1:84
	ds_write2_b32 v109, v174, v175 offset0:152 offset1:220
	ds_write2_b32 v110, v176, v177 offset0:32 offset1:100
	ds_write2_b32 v110, v178, v179 offset0:168 offset1:236
	ds_write2_b32 v111, v180, v181 offset0:48 offset1:116
	ds_write2_b32 v111, v182, v164 offset0:184 offset1:252
	v_add_u32_e32 v112, 0x1800, v144
	v_add_u32_e32 v113, 0x1a00, v144
	v_add_u32_e32 v115, 0x1c00, v144
	v_add_u32_e32 v116, 0x1e00, v144
	v_add_u32_e32 v117, 0x2000, v144
	ds_write2_b32 v118, v122, v120 offset0:104 offset1:172
	v_add_u32_e32 v119, 0x2400, v144
	v_add_u32_e32 v120, 0x2600, v144
	ds_write2_b32 v112, v165, v166 offset0:64 offset1:132
	ds_write2_b32 v113, v167, v162 offset0:72 offset1:140
	ds_write2_b32 v115, v133, v132 offset0:80 offset1:148
	ds_write2_b32 v116, v130, v128 offset0:88 offset1:156
	ds_write2_b32 v117, v126, v124 offset0:96 offset1:164
	ds_write2_b32 v119, v121, v123 offset0:112 offset1:180
	ds_write2_b32 v120, v114, v125 offset0:120 offset1:188
	s_waitcnt lgkmcnt(0)
; __device__ __forceinline__ unsigned cvt_pk_bf16(float lo, float hi) { unsigned r; asm volatile("v_cvt_pk_bf16_f32 %0, %1, %2" : "=v"(r) : "v"(lo), "v"(hi)); return r; }
; #define LAS __attribute__((address_space(3)))
; __device__ __forceinline__ float gelu_tanh(float x) { const float t = 1.5957691216057308f * (x + 0.044715f * x * x * x); return x * __builtin_amdgcn_rcpf(1.0f + __expf(-t)); }
; #define WSYNC() asm volatile("s_waitcnt lgkmcnt(0)" ::: "memory")
; __device__ __forceinline__ void s5_unit(LAS unsigned char* lw, int b, int g, const float* lam_re, const float* lam_im, const float* log_step, ...
;     ...
;         {
;             bf16x8 hf[2][4]; f32x4 uu[2];
; #pragma unroll
;             for (int rb = 0; rb < 2; ++rb) {
; #pragma unroll
;                 for (int kk = 0; kk < 4; ++kk) hf[rb][kk] = *(const LAS bf16x8*)(H + (rb * 16 + r) * 136 + kk * 32 + g4 * 8);
;                 uu[rb] = *(const LAS f32x4*)(U + (rb * 16 + r) * 16 + g4 * 4); }
;             __builtin_amdgcn_sched_barrier(0);
; #pragma unroll
;             for (int rb = 0; rb < 2; ++rb) {
;                 f32x4 acc = __builtin_amdgcn_mfma_f32_16x16x32_bf16(CfT[0], hf[rb][0], (f32x4){0.f, 0.f, 0.f, 0.f}, 0, 0, 0);
; #pragma unroll
;                 for (int kk = 1; kk < 4; ++kk) acc = __builtin_amdgcn_mfma_f32_16x16x32_bf16(CfT[kk], hf[rb][kk], acc, 0, 0, 0);
;                 const f32x4 y = acc + dsk4 * uu[rb];
;                 u32x2 ow; ow.x = cvt_pk_bf16(gelu_tanh(y[0]), gelu_tanh(y[1])); ow.y = cvt_pk_bf16(gelu_tanh(y[2]), gelu_tanh(y[3]));
;                 *(u32x2*)(ob + (size_t)(t0 + rb * 16 + r) * 512 + g4 * 4) = ow;
;             }
;         }
;         WSYNC();
	ds_read_b128 v[122:125], v147 offset:2048
	ds_read_b128 v[126:129], v147 offset:2112
	ds_read_b128 v[130:133], v147 offset:2176
	ds_read_b128 v[160:163], v147 offset:2240
	v_add_u32_e32 v114, v143, v141
	ds_read_b128 v[164:167], v147 offset:6400
	ds_read_b128 v[168:171], v147 offset:6464
	ds_read_b128 v[172:175], v147 offset:6528
	ds_read_b128 v[176:179], v147 offset:6592
	ds_read_b128 v[180:183], v114
	ds_read_b128 v[194:197], v114 offset:1024
	s_waitcnt lgkmcnt(0)
	v_mfma_f32_16x16x32_bf16 v[122:125], v[18:21], v[122:125], 0
	s_mov_b32 s21, 0x33800000
	s_add_i32 s20, s20, -1
	v_lshl_add_u64 v[102:103], v[102:103], 0, s[76:77]
	v_mfma_f32_16x16x32_bf16 v[164:167], v[18:21], v[164:167], 0
	v_lshl_add_u64 v[104:105], v[104:105], 0, s[76:77]
	s_cmp_lg_u32 s20, 0
	v_lshl_add_u64 v[106:107], v[106:107], 0, s[76:77]
	v_mfma_f32_16x16x32_bf16 v[122:125], v[26:29], v[126:129], v[122:125]
	v_mfma_f32_16x16x32_bf16 v[126:129], v[26:29], v[168:171], v[164:167]
	v_mfma_f32_16x16x32_bf16 v[122:125], v[30:33], v[130:133], v[122:125]
	s_nop 1
	v_lshl_add_u64 v[164:165], v[100:101], 0, s[94:95]
	v_add_co_u32_e32 v130, vcc, s21, v164
	v_mfma_f32_16x16x32_bf16 v[126:129], v[30:33], v[172:175], v[126:129]
	s_nop 0
	v_addc_co_u32_e32 v131, vcc, 0, v165, vcc
	v_add_co_u32_e32 v132, vcc, 0x33804000, v164
	v_mfma_f32_16x16x32_bf16 v[122:125], v[34:37], v[160:163], v[122:125]
	s_nop 0
	v_addc_co_u32_e32 v133, vcc, 0, v165, vcc
	v_lshl_add_u64 v[100:101], v[100:101], 0, s[96:97]
	v_mfma_f32_16x16x32_bf16 v[126:129], v[34:37], v[176:179], v[126:129]
	s_nop 3
	v_fma_f32 v124, v12, v182, v124
	v_fma_f32 v125, v13, v183, v125
	v_pk_fma_f32 v[122:123], v[10:11], v[180:181], v[122:123]
	v_mul_f32_e32 v160, 0x3d372713, v124
	v_mul_f32_e32 v121, 0x3d372713, v123
	v_pk_fma_f32 v[128:129], v[12:13], v[196:197], v[128:129]
	v_pk_fma_f32 v[126:127], v[10:11], v[194:195], v[126:127]
	v_mul_f32_e32 v87, 0x3d372713, v122
	v_mul_f32_e32 v161, 0x3d372713, v125
	v_mul_f32_e32 v121, v123, v121
	v_mul_f32_e32 v160, v124, v160
	v_mul_f32_e32 v162, 0x3d372713, v126
	v_mul_f32_e32 v163, 0x3d372713, v127
	v_mul_f32_e32 v164, 0x3d372713, v128
	v_mul_f32_e32 v165, 0x3d372713, v129
	v_mul_f32_e32 v87, v122, v87
	v_mul_f32_e32 v161, v125, v161
	v_fma_f32 v121, v123, v121, v123
	v_fma_f32 v160, v124, v160, v124
	v_mul_f32_e32 v162, v126, v162
	v_mul_f32_e32 v163, v127, v163
	v_mul_f32_e32 v164, v128, v164
	v_mul_f32_e32 v165, v129, v165
	v_fma_f32 v87, v122, v87, v122
	v_fma_f32 v161, v125, v161, v125
	v_mul_f32_e32 v121, 0xbfcc422a, v121
	v_mul_f32_e32 v160, 0xbfcc422a, v160
	v_fma_f32 v162, v126, v162, v126
	v_fma_f32 v163, v127, v163, v127
	v_fma_f32 v164, v128, v164, v128
	v_fma_f32 v165, v129, v165, v129
	v_mul_f32_e32 v87, 0xbfcc422a, v87
	v_mul_f32_e32 v161, 0xbfcc422a, v161
	v_mul_f32_e32 v121, 0x3fb8aa3b, v121
	v_mul_f32_e32 v160, 0x3fb8aa3b, v160
	v_mul_f32_e32 v162, 0xbfcc422a, v162
	v_mul_f32_e32 v163, 0xbfcc422a, v163
	v_mul_f32_e32 v164, 0xbfcc422a, v164
	v_mul_f32_e32 v165, 0xbfcc422a, v165
	v_mul_f32_e32 v87, 0x3fb8aa3b, v87
	v_mul_f32_e32 v161, 0x3fb8aa3b, v161
	v_exp_f32_e32 v121, v121
	v_exp_f32_e32 v160, v160
	v_mul_f32_e32 v162, 0x3fb8aa3b, v162
	v_mul_f32_e32 v163, 0x3fb8aa3b, v163
	v_mul_f32_e32 v164, 0x3fb8aa3b, v164
	v_mul_f32_e32 v165, 0x3fb8aa3b, v165
	v_exp_f32_e32 v87, v87
	v_exp_f32_e32 v161, v161
	v_exp_f32_e32 v162, v162
	v_exp_f32_e32 v163, v163
	v_exp_f32_e32 v164, v164
	v_exp_f32_e32 v165, v165
	v_add_f32_e32 v121, 1.0, v121
	v_add_f32_e32 v160, 1.0, v160
	v_add_f32_e32 v87, 1.0, v87
	v_add_f32_e32 v161, 1.0, v161
	v_rcp_f32_e32 v121, v121
	v_rcp_f32_e32 v160, v160
	v_add_f32_e32 v162, 1.0, v162
	v_add_f32_e32 v163, 1.0, v163
	v_add_f32_e32 v164, 1.0, v164
	v_add_f32_e32 v165, 1.0, v165
	v_rcp_f32_e32 v87, v87
	v_rcp_f32_e32 v161, v161
	v_rcp_f32_e32 v162, v162
	v_rcp_f32_e32 v163, v163
	v_rcp_f32_e32 v164, v164
	v_rcp_f32_e32 v165, v165
	v_mul_f32_e32 v121, v123, v121
	v_mul_f32_e32 v123, v124, v160
	v_mul_f32_e32 v87, v122, v87
	v_mul_f32_e32 v124, v125, v161
	v_cvt_pk_bf16_f32 v122, v87, v121
	v_cvt_pk_bf16_f32 v123, v123, v124
	v_mul_f32_e32 v125, v126, v162
	v_mul_f32_e32 v126, v127, v163
	v_mul_f32_e32 v127, v128, v164
	v_mul_f32_e32 v128, v129, v165
	global_store_dwordx2 v[130:131], v[122:123], off
	v_cvt_pk_bf16_f32 v122, v125, v126
	v_cvt_pk_bf16_f32 v123, v127, v128
	global_store_dwordx2 v[132:133], v[122:123], off
	s_waitcnt lgkmcnt(0)
	s_cbranch_scc1 .LBB0_744
; #define LAS __attribute__((address_space(3)))
; __device__ __forceinline__ float bflo(unsigned w) { return __uint_as_float(w << 16); }
; __device__ __forceinline__ float bfhi(unsigned w) { return __uint_as_float(w & 0xffff0000u); }
; #define WSYNC() asm volatile("s_waitcnt lgkmcnt(0)" ::: "memory")
; __device__ __forceinline__ void s5_unit(LAS unsigned char* lw, int b, int g, const float* lam_re, const float* lam_im, const float* log_step, ...
;     ...
;     for (int tc = 0; tc < SEQ / 32; ++tc) {
;         const int t0 = tc * 32;
;         u32x4 a0 = an0, a1 = an1; if (g4 >= 2) { a0 = (u32x4){0u, 0u, 0u, 0u}; a1 = a0; }
;         { const int tk = lane >> 1, hf = lane & 1; const u32x4 v = vnext;
;           if (tc + 1 < SEQ / 32) { vnext = *(const u32x4*)(zb + (size_t)(t0 + 32 + tk) * ZW + hf * 8);
;               an0 = *(const u32x4*)(zb + (size_t)(t0 + 32 + r) * ZW + g4c * 8); an1 = *(const u32x4*)(zb + (size_t)(t0 + 48 + r) * ZW + g4c * 8); }
;           f32x4 a, c2; a[0] = bflo(v.x); a[1] = bfhi(v.x); a[2] = bflo(v.y); a[3] = bfhi(v.y); c2[0] = bflo(v.z); c2[1] = bfhi(v.z); c2[2] = bflo(v.w); c2[3] = bfhi(v.w);
;           *(LAS f32x4*)(U + tk * 16 + hf * 8) = a; *(LAS f32x4*)(U + tk * 16 + hf * 8 + 4) = c2; }
; #pragma unroll
;         for (int rb = 0; rb < 2; ++rb) { const bf16x8 af = __builtin_bit_cast(bf16x8, rb ? a1 : a0);
; #pragma unroll
;             for (int nb = 0; nb < 8; ++nb) { const f32x4 xa = __builtin_amdgcn_mfma_f32_16x16x32_bf16(Bf[nb], af, (f32x4){0.f, 0.f, 0.f, 0.f}, 0, 0, 0);
;                 *(LAS f32x4*)(Xs + (rb * 16 + r) * 132 + nb * 16 + g4 * 4) = xa; } }
;         WSYNC();
;         {
;             float xrv[32], xiv[32]; unsigned hp[32];
; #pragma unroll
;             for (int t = 0; t < 32; ++t) { xrv[t] = Xs[t * 132 + n]; xiv[t] = Xs[t * 132 + 64 + n]; }
	s_waitcnt vmcnt(0)
	v_lshlrev_b32_e32 v96, 16, v62
	v_and_b32_e32 v97, 0xffff0000, v62
	v_lshlrev_b32_e32 v98, 16, v63
	v_and_b32_e32 v99, 0xffff0000, v63
	v_lshlrev_b32_e32 v62, 16, v64
	v_and_b32_e32 v63, 0xffff0000, v64
	v_lshlrev_b32_e32 v64, 16, v65
	v_and_b32_e32 v65, 0xffff0000, v65
	v_cndmask_b32_e64 v61, v61, 0, s[4:5]
	v_cndmask_b32_e64 v60, v60, 0, s[4:5]
	v_cndmask_b32_e64 v59, v59, 0, s[4:5]
	v_cndmask_b32_e64 v58, v58, 0, s[4:5]
	ds_write_b128 v142, v[96:99]
	ds_write_b128 v142, v[62:65] offset:16
	v_mfma_f32_16x16x32_bf16 v[62:65], v[6:9], v[58:61], 0
	v_cndmask_b32_e64 v57, v57, 0, s[4:5]
	v_cndmask_b32_e64 v56, v56, 0, s[4:5]
	v_cndmask_b32_e64 v55, v55, 0, s[4:5]
	v_cndmask_b32_e64 v54, v54, 0, s[4:5]
	s_add_u32 s18, s22, s18
	s_nop 2
	ds_write_b128 v146, v[62:65] offset:10752
	v_mfma_f32_16x16x32_bf16 v[62:65], v[2:5], v[58:61], 0
	s_addc_u32 s19, s23, s19
	s_lshl_b32 s20, s27, 1
	s_add_u32 s18, s18, s20
	v_mfma_f32_16x16x32_bf16 v[2:5], v[2:5], v[54:57], 0
	s_addc_u32 s19, s19, 0
	s_nop 2
	ds_write_b128 v146, v[62:65] offset:10816
	v_mov_b32_e32 v87, v1
	v_mfma_f32_16x16x32_bf16 v[62:65], v[22:25], v[58:61], 0
	v_lshl_add_u64 v[92:93], s[18:19], 0, v[86:87]
	ds_write_b128 v146, v[2:5] offset:19264
	v_mfma_f32_16x16x32_bf16 v[2:5], v[22:25], v[54:57], 0
	v_mfma_f32_16x16x32_bf16 v[6:9], v[6:9], v[54:57], 0
	s_nop 3
	ds_write_b128 v146, v[62:65] offset:10880
	s_nop 1
	ds_write_b128 v146, v[2:5] offset:19328
	v_mfma_f32_16x16x32_bf16 v[2:5], v[14:17], v[54:57], 0
	v_mfma_f32_16x16x32_bf16 v[62:65], v[14:17], v[58:61], 0
	ds_write_b128 v146, v[6:9] offset:19200
	s_nop 5
	ds_write_b128 v146, v[2:5] offset:19392
	v_mfma_f32_16x16x32_bf16 v[2:5], v[42:45], v[54:57], 0
	ds_write_b128 v146, v[62:65] offset:10944
	v_mfma_f32_16x16x32_bf16 v[62:65], v[42:45], v[58:61], 0
	s_nop 5
	ds_write_b128 v146, v[2:5] offset:19456
	v_mfma_f32_16x16x32_bf16 v[2:5], v[38:41], v[54:57], 0
	ds_write_b128 v146, v[62:65] offset:11008
	v_mfma_f32_16x16x32_bf16 v[62:65], v[38:41], v[58:61], 0
	s_nop 5
	ds_write_b128 v146, v[2:5] offset:19520
	v_mfma_f32_16x16x32_bf16 v[2:5], v[50:53], v[54:57], 0
	ds_write_b128 v146, v[62:65] offset:11072
	v_mfma_f32_16x16x32_bf16 v[62:65], v[50:53], v[58:61], 0
	s_nop 5
	ds_write_b128 v146, v[2:5] offset:19584
	v_mfma_f32_16x16x32_bf16 v[58:61], v[46:49], v[58:61], 0
	v_mfma_f32_16x16x32_bf16 v[2:5], v[46:49], v[54:57], 0
	ds_write_b128 v146, v[62:65] offset:11136
	s_nop 5
	ds_write_b128 v146, v[58:61] offset:11200
	ds_write_b128 v146, v[2:5] offset:19648
	s_waitcnt lgkmcnt(0)
	ds_read2st64_b32 v[16:17], v144 offset0:42 offset1:43
	ds_read2st64_b32 v[22:23], v158 offset0:44 offset1:45
	ds_read2st64_b32 v[24:25], v159 offset0:46 offset1:47
	ds_read2st64_b32 v[38:39], v156 offset0:48 offset1:49
	ds_read2st64_b32 v[40:41], v157 offset0:50 offset1:51
	ds_read2st64_b32 v[42:43], v154 offset0:52 offset1:53
	ds_read2st64_b32 v[44:45], v155 offset0:54 offset1:55
	ds_read2st64_b32 v[46:47], v152 offset0:56 offset1:57
	ds_read2st64_b32 v[48:49], v153 offset0:58 offset1:59
	ds_read2st64_b32 v[50:51], v150 offset0:60 offset1:61
	ds_read2st64_b32 v[52:53], v151 offset0:62 offset1:63
	ds_read2st64_b32 v[54:55], v148 offset0:64 offset1:65
	ds_read2st64_b32 v[56:57], v149 offset0:66 offset1:67
	ds_read2st64_b32 v[58:59], v85 offset0:68 offset1:69
	ds_read2st64_b32 v[60:61], v89 offset0:70 offset1:71
	ds_read2st64_b32 v[62:63], v83 offset0:72 offset1:73
	ds_read2st64_b32 v[64:65], v144 offset0:75 offset1:76
	ds_read2st64_b32 v[96:97], v158 offset0:77 offset1:78
	ds_read2st64_b32 v[98:99], v159 offset0:79 offset1:80
	ds_read2st64_b32 v[100:101], v156 offset0:81 offset1:82
	ds_read2st64_b32 v[102:103], v157 offset0:83 offset1:84
	ds_read2st64_b32 v[104:105], v154 offset0:85 offset1:86
	ds_read2st64_b32 v[106:107], v155 offset0:87 offset1:88
	ds_read2st64_b32 v[122:123], v152 offset0:89 offset1:90
	ds_read2st64_b32 v[124:125], v153 offset0:91 offset1:92
	ds_read2st64_b32 v[126:127], v150 offset0:93 offset1:94
	ds_read2st64_b32 v[128:129], v151 offset0:95 offset1:96
	ds_read2st64_b32 v[14:15], v148 offset0:97 offset1:98
	ds_read2st64_b32 v[8:9], v149 offset0:99 offset1:100
	ds_read2st64_b32 v[6:7], v85 offset0:101 offset1:102
	ds_read2st64_b32 v[4:5], v89 offset0:103 offset1:104
	ds_read2st64_b32 v[2:3], v83 offset0:105 offset1:106
	v_pk_mul_f32 v[130:131], v[90:91], v[94:95]
	s_nop 0
	v_sub_f32_e32 v83, v130, v131
	s_waitcnt lgkmcnt(0)
; __device__ __forceinline__ unsigned cvt_pk_bf16(float lo, float hi) { unsigned r; asm volatile("v_cvt_pk_bf16_f32 %0, %1, %2" : "=v"(r) : "v"(lo), "v"(hi)); return r; }
; __device__ __forceinline__ void s5_unit(LAS unsigned char* lw, int b, int g, const float* lam_re, const float* lam_im, const float* log_step, ...
;     ...
; #pragma unroll
;             for (int t = 0; t < 32; ++t) { const float nhr = are * hr - aim * hi + xrv[t], nhi = are * hi + aim * hr + xiv[t]; hr = nhr; hi = nhi; hp[t] = cvt_pk_bf16(hr, hi); }
	v_add_f32_e32 v16, v83, v16
	v_mul_f32_e32 v83, v90, v95
	v_fmac_f32_e32 v83, v91, v94
	v_add_f32_e32 v17, v83, v17
	v_cvt_pk_bf16_f32 v83, v16, v17
	v_mul_f32_e32 v85, v91, v17
	v_mul_f32_e32 v17, v90, v17
	v_fmac_f32_e32 v17, v91, v16
	v_fma_f32 v85, v90, v16, -v85
	v_add_f32_e32 v16, v23, v17
	v_add_f32_e32 v22, v22, v85
	v_mul_f32_e32 v23, v91, v16
	v_cvt_pk_bf16_f32 v17, v22, v16
	v_fma_f32 v23, v90, v22, -v23
	v_mul_f32_e32 v22, v91, v22
	v_fmac_f32_e32 v22, v90, v16
	v_add_f32_e32 v16, v25, v22
	v_add_f32_e32 v23, v24, v23
	v_mul_f32_e32 v24, v91, v16
	v_cvt_pk_bf16_f32 v22, v23, v16
	v_fma_f32 v24, v90, v23, -v24
	v_mul_f32_e32 v23, v91, v23
	v_fmac_f32_e32 v23, v90, v16
	v_add_f32_e32 v16, v39, v23
	v_add_f32_e32 v24, v38, v24
	v_mul_f32_e32 v25, v91, v16
	v_cvt_pk_bf16_f32 v23, v24, v16
	v_fma_f32 v25, v90, v24, -v25
	v_mul_f32_e32 v24, v91, v24
	v_fmac_f32_e32 v24, v90, v16
	v_add_f32_e32 v16, v41, v24
	v_add_f32_e32 v25, v40, v25
	v_mul_f32_e32 v38, v91, v16
	v_cvt_pk_bf16_f32 v24, v25, v16
	v_fma_f32 v38, v90, v25, -v38
	v_mul_f32_e32 v25, v91, v25
	v_fmac_f32_e32 v25, v90, v16
	v_add_f32_e32 v16, v43, v25
	v_add_f32_e32 v38, v42, v38
	v_mul_f32_e32 v39, v91, v16
	v_cvt_pk_bf16_f32 v25, v38, v16
	v_fma_f32 v39, v90, v38, -v39
	v_mul_f32_e32 v38, v91, v38
	v_fmac_f32_e32 v38, v90, v16
	v_add_f32_e32 v16, v45, v38
	v_add_f32_e32 v39, v44, v39
	v_mul_f32_e32 v40, v91, v16
	v_cvt_pk_bf16_f32 v38, v39, v16
	v_fma_f32 v40, v90, v39, -v40
	v_mul_f32_e32 v39, v91, v39
	v_fmac_f32_e32 v39, v90, v16
	v_add_f32_e32 v16, v47, v39
	v_add_f32_e32 v40, v46, v40
	v_mul_f32_e32 v41, v91, v16
	v_cvt_pk_bf16_f32 v39, v40, v16
	v_fma_f32 v41, v90, v40, -v41
	v_mul_f32_e32 v40, v91, v40
	v_fmac_f32_e32 v40, v90, v16
	v_add_f32_e32 v16, v49, v40
	v_add_f32_e32 v41, v48, v41
	v_mul_f32_e32 v42, v91, v16
	v_cvt_pk_bf16_f32 v40, v41, v16
	v_fma_f32 v42, v90, v41, -v42
	v_mul_f32_e32 v41, v91, v41
	v_fmac_f32_e32 v41, v90, v16
	v_add_f32_e32 v16, v51, v41
	v_add_f32_e32 v42, v50, v42
	v_mul_f32_e32 v43, v91, v16
	v_cvt_pk_bf16_f32 v41, v42, v16
	v_fma_f32 v43, v90, v42, -v43
	v_mul_f32_e32 v42, v91, v42
	v_fmac_f32_e32 v42, v90, v16
	v_add_f32_e32 v16, v53, v42
	v_add_f32_e32 v43, v52, v43
	v_mul_f32_e32 v44, v91, v16
	v_cvt_pk_bf16_f32 v42, v43, v16
	v_fma_f32 v44, v90, v43, -v44
	v_mul_f32_e32 v43, v91, v43
	v_fmac_f32_e32 v43, v90, v16
	v_add_f32_e32 v16, v55, v43
	v_add_f32_e32 v44, v54, v44
	v_mul_f32_e32 v45, v91, v16
	v_cvt_pk_bf16_f32 v43, v44, v16
	v_fma_f32 v45, v90, v44, -v45
	v_mul_f32_e32 v44, v91, v44
	v_fmac_f32_e32 v44, v90, v16
	v_add_f32_e32 v16, v57, v44
	v_add_f32_e32 v45, v56, v45
	v_mul_f32_e32 v46, v91, v16
	v_cvt_pk_bf16_f32 v44, v45, v16
	v_fma_f32 v46, v90, v45, -v46
	v_mul_f32_e32 v45, v91, v45
	v_fmac_f32_e32 v45, v90, v16
	v_add_f32_e32 v16, v59, v45
	v_add_f32_e32 v46, v58, v46
	v_mul_f32_e32 v47, v91, v16
	v_cvt_pk_bf16_f32 v45, v46, v16
	v_fma_f32 v47, v90, v46, -v47
	v_mul_f32_e32 v46, v91, v46
	v_fmac_f32_e32 v46, v90, v16
	v_add_f32_e32 v16, v61, v46
	v_add_f32_e32 v47, v60, v47
	v_mul_f32_e32 v48, v91, v16
	v_cvt_pk_bf16_f32 v46, v47, v16
	v_fma_f32 v48, v90, v47, -v48
	v_mul_f32_e32 v47, v91, v47
	v_fmac_f32_e32 v47, v90, v16
	v_add_f32_e32 v16, v63, v47
	v_add_f32_e32 v48, v62, v48
	v_mul_f32_e32 v49, v91, v16
	v_cvt_pk_bf16_f32 v47, v48, v16
	v_fma_f32 v49, v90, v48, -v49
	v_mul_f32_e32 v48, v91, v48
	v_fmac_f32_e32 v48, v90, v16
	v_add_f32_e32 v16, v65, v48
	v_add_f32_e32 v49, v64, v49
	v_mul_f32_e32 v50, v91, v16
	v_cvt_pk_bf16_f32 v48, v49, v16
	v_fma_f32 v50, v90, v49, -v50
	v_mul_f32_e32 v49, v91, v49
	v_fmac_f32_e32 v49, v90, v16
	v_add_f32_e32 v16, v97, v49
	v_add_f32_e32 v50, v96, v50
	v_mul_f32_e32 v51, v91, v16
	v_cvt_pk_bf16_f32 v49, v50, v16
	v_fma_f32 v51, v90, v50, -v51
	v_mul_f32_e32 v50, v91, v50
	v_fmac_f32_e32 v50, v90, v16
	v_add_f32_e32 v16, v99, v50
	v_add_f32_e32 v51, v98, v51
	v_mul_f32_e32 v52, v91, v16
	v_cvt_pk_bf16_f32 v50, v51, v16
	v_fma_f32 v52, v90, v51, -v52
	v_mul_f32_e32 v51, v91, v51
	v_fmac_f32_e32 v51, v90, v16
	v_add_f32_e32 v16, v101, v51
	v_add_f32_e32 v52, v100, v52
	v_mul_f32_e32 v53, v91, v16
	v_cvt_pk_bf16_f32 v51, v52, v16
	v_fma_f32 v53, v90, v52, -v53
	v_mul_f32_e32 v52, v91, v52
	v_fmac_f32_e32 v52, v90, v16
	v_add_f32_e32 v16, v103, v52
	v_add_f32_e32 v53, v102, v53
	v_mul_f32_e32 v54, v91, v16
	v_cvt_pk_bf16_f32 v52, v53, v16
	v_fma_f32 v54, v90, v53, -v54
	v_mul_f32_e32 v53, v91, v53
	v_fmac_f32_e32 v53, v90, v16
	v_add_f32_e32 v16, v105, v53
	v_add_f32_e32 v54, v104, v54
	v_mul_f32_e32 v55, v91, v16
	v_cvt_pk_bf16_f32 v53, v54, v16
	v_fma_f32 v55, v90, v54, -v55
	v_mul_f32_e32 v54, v91, v54
	v_fmac_f32_e32 v54, v90, v16
	v_add_f32_e32 v16, v107, v54
	v_add_f32_e32 v55, v106, v55
	v_mul_f32_e32 v56, v91, v16
	v_cvt_pk_bf16_f32 v54, v55, v16
	v_fma_f32 v56, v90, v55, -v56
	v_mul_f32_e32 v55, v91, v55
	v_fmac_f32_e32 v55, v90, v16
	v_add_f32_e32 v16, v123, v55
	v_add_f32_e32 v56, v122, v56
	v_mul_f32_e32 v57, v91, v16
	v_cvt_pk_bf16_f32 v55, v56, v16
	v_fma_f32 v57, v90, v56, -v57
	v_mul_f32_e32 v56, v91, v56
	v_fmac_f32_e32 v56, v90, v16
	v_add_f32_e32 v16, v125, v56
	v_add_f32_e32 v57, v124, v57
	v_mul_f32_e32 v58, v91, v16
	v_cvt_pk_bf16_f32 v56, v57, v16
	v_fma_f32 v58, v90, v57, -v58
	v_mul_f32_e32 v57, v91, v57
	v_fmac_f32_e32 v57, v90, v16
	v_add_f32_e32 v16, v127, v57
	v_add_f32_e32 v58, v126, v58
	v_mul_f32_e32 v59, v91, v16
	v_cvt_pk_bf16_f32 v57, v58, v16
	v_fma_f32 v59, v90, v58, -v59
	v_mul_f32_e32 v58, v91, v58
	v_fmac_f32_e32 v58, v90, v16
	v_add_f32_e32 v16, v129, v58
	v_add_f32_e32 v59, v128, v59
	v_mul_f32_e32 v60, v91, v16
	v_cvt_pk_bf16_f32 v58, v59, v16
; __device__ __forceinline__ unsigned cvt_pk_bf16(float lo, float hi) { unsigned r; asm volatile("v_cvt_pk_bf16_f32 %0, %1, %2" : "=v"(r) : "v"(lo), "v"(hi)); return r; }
; #define LAS __attribute__((address_space(3)))
; __device__ __forceinline__ float gelu_tanh(float x) { const float t = 1.5957691216057308f * (x + 0.044715f * x * x * x); return x * __builtin_amdgcn_rcpf(1.0f + __expf(-t)); }
; #define WSYNC() asm volatile("s_waitcnt lgkmcnt(0)" ::: "memory")
; __device__ __forceinline__ void s5_unit(LAS unsigned char* lw, int b, int g, const float* lam_re, const float* lam_im, const float* log_step, ...
;     ...
;             for (int t = 0; t < 32; ++t) { const float nhr = are * hr - aim * hi + xrv[t], nhi = are * hi + aim * hr + xiv[t]; hr = nhr; hi = nhi; hp[t] = cvt_pk_bf16(hr, hi); }
;             __builtin_amdgcn_sched_barrier(0);
; #pragma unroll
;             for (int t = 0; t < 32; ++t) *(LAS unsigned*)(H + t * 136 + 2 * n) = hp[t];
;         }
;         WSYNC();
;         {
;             bf16x8 hf[2][4]; f32x4 uu[2];
; #pragma unroll
;             for (int rb = 0; rb < 2; ++rb) {
; #pragma unroll
;                 for (int kk = 0; kk < 4; ++kk) hf[rb][kk] = *(const LAS bf16x8*)(H + (rb * 16 + r) * 136 + kk * 32 + g4 * 8);
;                 uu[rb] = *(const LAS f32x4*)(U + (rb * 16 + r) * 16 + g4 * 4); }
;             __builtin_amdgcn_sched_barrier(0);
; #pragma unroll
;             for (int rb = 0; rb < 2; ++rb) {
;                 f32x4 acc = __builtin_amdgcn_mfma_f32_16x16x32_bf16(CfT[0], hf[rb][0], (f32x4){0.f, 0.f, 0.f, 0.f}, 0, 0, 0);
; #pragma unroll
;                 for (int kk = 1; kk < 4; ++kk) acc = __builtin_amdgcn_mfma_f32_16x16x32_bf16(CfT[kk], hf[rb][kk], acc, 0, 0, 0);
;                 const f32x4 y = acc + dsk4 * uu[rb];
;                 u32x2 ow; ow.x = cvt_pk_bf16(gelu_tanh(y[0]), gelu_tanh(y[1])); ow.y = cvt_pk_bf16(gelu_tanh(y[2]), gelu_tanh(y[3]));
;                 *(u32x2*)(ob + (size_t)(t0 + rb * 16 + r) * 512 + g4 * 4) = ow;
;             }
;         }
;         WSYNC();
	v_fma_f32 v60, v90, v59, -v60
	v_mul_f32_e32 v59, v91, v59
	v_fmac_f32_e32 v59, v90, v16
	v_add_f32_e32 v15, v15, v59
	v_add_f32_e32 v14, v14, v60
	v_mul_f32_e32 v59, v91, v15
	v_cvt_pk_bf16_f32 v16, v14, v15
	v_fma_f32 v59, v90, v14, -v59
	v_mul_f32_e32 v14, v91, v14
	v_fmac_f32_e32 v14, v90, v15
	v_add_f32_e32 v9, v9, v14
	v_add_f32_e32 v8, v8, v59
	v_mul_f32_e32 v15, v91, v9
	v_cvt_pk_bf16_f32 v14, v8, v9
	v_fma_f32 v15, v90, v8, -v15
	v_mul_f32_e32 v8, v91, v8
	v_fmac_f32_e32 v8, v90, v9
	v_add_f32_e32 v7, v7, v8
	v_add_f32_e32 v6, v6, v15
	v_mul_f32_e32 v9, v91, v7
	v_cvt_pk_bf16_f32 v8, v6, v7
	v_fma_f32 v9, v90, v6, -v9
	v_mul_f32_e32 v6, v91, v6
	v_fmac_f32_e32 v6, v90, v7
	v_add_f32_e32 v5, v5, v6
	v_add_f32_e32 v4, v4, v9
	v_mul_f32_e32 v7, v91, v5
	v_cvt_pk_bf16_f32 v6, v4, v5
	v_fma_f32 v7, v90, v4, -v7
	v_mul_f32_e32 v4, v91, v4
	v_add_f32_e32 v2, v2, v7
	v_fmac_f32_e32 v4, v90, v5
	v_add_f32_e32 v3, v3, v4
	v_cvt_pk_bf16_f32 v2, v2, v3
	ds_write2_b32 v108, v83, v17 offset1:68
	ds_write2_b32 v108, v22, v23 offset0:136 offset1:204
	ds_write2_b32 v109, v24, v25 offset0:16 offset1:84
	ds_write2_b32 v109, v38, v39 offset0:152 offset1:220
	ds_write2_b32 v110, v40, v41 offset0:32 offset1:100
	ds_write2_b32 v110, v42, v43 offset0:168 offset1:236
	ds_write2_b32 v111, v44, v45 offset0:48 offset1:116
	ds_write2_b32 v111, v46, v47 offset0:184 offset1:252
	ds_write2_b32 v112, v48, v49 offset0:64 offset1:132
	ds_write2_b32 v113, v50, v51 offset0:72 offset1:140
	ds_write2_b32 v115, v52, v53 offset0:80 offset1:148
	ds_write2_b32 v116, v54, v55 offset0:88 offset1:156
	ds_write2_b32 v117, v56, v57 offset0:96 offset1:164
	ds_write2_b32 v118, v58, v16 offset0:104 offset1:172
	ds_write2_b32 v119, v14, v8 offset0:112 offset1:180
	ds_write2_b32 v120, v6, v2 offset0:120 offset1:188
	s_waitcnt lgkmcnt(0)
	ds_read_b128 v[2:5], v147 offset:2048
	ds_read_b128 v[6:9], v147 offset:2112
	ds_read_b128 v[14:17], v147 offset:2176
	ds_read_b128 v[22:25], v147 offset:2240
	ds_read_b128 v[38:41], v147 offset:6400
	ds_read_b128 v[42:45], v147 offset:6464
	ds_read_b128 v[46:49], v147 offset:6528
	ds_read_b128 v[50:53], v147 offset:6592
	ds_read_b128 v[54:57], v114
	ds_read_b128 v[58:61], v114 offset:1024
	s_waitcnt lgkmcnt(9)
	v_mfma_f32_16x16x32_bf16 v[2:5], v[18:21], v[2:5], 0
	v_mov_b32_e32 v89, v1
	s_mov_b32 s18, 0x1f8000
	s_add_i32 s1, s1, s24
	s_waitcnt lgkmcnt(8)
	v_mfma_f32_16x16x32_bf16 v[2:5], v[26:29], v[6:9], v[2:5]
	s_add_i32 s25, s25, s24
	s_cmpk_lt_i32 s1, 0x400
	s_waitcnt lgkmcnt(7)
	v_mfma_f32_16x16x32_bf16 v[2:5], v[30:33], v[14:17], v[2:5]
	s_waitcnt lgkmcnt(6)
	v_mfma_f32_16x16x32_bf16 v[2:5], v[34:37], v[22:25], v[2:5]
	s_waitcnt lgkmcnt(1)
	s_nop 6
	v_pk_fma_f32 v[2:3], v[10:11], v[54:55], v[2:3]
	v_pk_fma_f32 v[6:7], v[12:13], v[56:57], v[4:5]
	v_mul_f32_e32 v4, 0x3d372713, v2
	v_mul_f32_e32 v4, v2, v4
	v_fma_f32 v4, v2, v4, v2
	v_mul_f32_e32 v5, 0x3d372713, v3
	v_mul_f32_e32 v4, 0xbfcc422a, v4
	v_mul_f32_e32 v5, v3, v5
	v_mul_f32_e32 v4, 0x3fb8aa3b, v4
	v_fma_f32 v5, v3, v5, v3
	v_exp_f32_e32 v4, v4
	v_mul_f32_e32 v5, 0xbfcc422a, v5
	v_mul_f32_e32 v5, 0x3fb8aa3b, v5
	v_exp_f32_e32 v5, v5
	v_add_f32_e32 v4, 1.0, v4
	v_rcp_f32_e32 v4, v4
	v_mul_f32_e32 v9, 0x3d372713, v7
	v_add_f32_e32 v5, 1.0, v5
	v_mul_f32_e32 v9, v7, v9
	v_rcp_f32_e32 v5, v5
	v_mul_f32_e32 v14, v2, v4
	v_fma_f32 v2, v7, v9, v7
	v_mul_f32_e32 v2, 0xbfcc422a, v2
	v_mul_f32_e32 v2, 0x3fb8aa3b, v2
	v_mul_f32_e32 v15, v3, v5
	v_exp_f32_e32 v9, v2
	v_mfma_f32_16x16x32_bf16 v[2:5], v[18:21], v[38:41], 0
	v_mul_f32_e32 v8, 0x3d372713, v6
	v_mul_f32_e32 v8, v6, v8
	v_fma_f32 v8, v6, v8, v6
	v_mfma_f32_16x16x32_bf16 v[2:5], v[26:29], v[42:45], v[2:5]
	v_mul_f32_e32 v8, 0xbfcc422a, v8
	v_mul_f32_e32 v8, 0x3fb8aa3b, v8
	v_exp_f32_e32 v8, v8
	v_mfma_f32_16x16x32_bf16 v[2:5], v[30:33], v[46:49], v[2:5]
	v_add_f32_e32 v8, 1.0, v8
	v_mfma_f32_16x16x32_bf16 v[2:5], v[34:37], v[50:53], v[2:5]
	v_rcp_f32_e32 v16, v8
	v_add_f32_e32 v8, 1.0, v9
	v_rcp_f32_e32 v9, v8
	v_cvt_pk_bf16_f32 v8, v14, v15
	v_mul_f32_e32 v6, v6, v16
	s_waitcnt lgkmcnt(0)
	s_nop 2
	v_pk_fma_f32 v[2:3], v[10:11], v[58:59], v[2:3]
	v_mul_f32_e32 v7, v7, v9
	v_mul_f32_e32 v10, 0x3d372713, v2
	v_mul_f32_e32 v10, v2, v10
	v_fma_f32 v10, v2, v10, v2
	v_mul_f32_e32 v10, 0xbfcc422a, v10
	v_cvt_pk_bf16_f32 v9, v6, v7
	v_lshl_add_u64 v[6:7], v[92:93], 0, v[88:89]
	v_mul_f32_e32 v10, 0x3fb8aa3b, v10
	v_exp_f32_e32 v14, v10
	v_add_co_u32_e32 v10, vcc, s18, v6
	v_mul_f32_e32 v15, 0x3d372713, v3
	s_nop 0
	v_addc_co_u32_e32 v11, vcc, 0, v7, vcc
	v_pk_fma_f32 v[4:5], v[12:13], v[60:61], v[4:5]
	v_mul_f32_e32 v15, v3, v15
	global_store_dwordx2 v[10:11], v[8:9], off
	v_mul_f32_e32 v9, 0x3d372713, v4
	v_mul_f32_e32 v10, 0x3d372713, v5
	v_fma_f32 v15, v3, v15, v3
	v_mul_f32_e32 v9, v4, v9
	v_mul_f32_e32 v10, v5, v10
	v_mul_f32_e32 v15, 0xbfcc422a, v15
	v_fma_f32 v9, v4, v9, v4
	v_fma_f32 v10, v5, v10, v5
	v_mul_f32_e32 v15, 0x3fb8aa3b, v15
	v_mul_f32_e32 v9, 0xbfcc422a, v9
	v_mul_f32_e32 v10, 0xbfcc422a, v10
	v_exp_f32_e32 v15, v15
	v_mul_f32_e32 v9, 0x3fb8aa3b, v9
	v_mul_f32_e32 v10, 0x3fb8aa3b, v10
	v_exp_f32_e32 v9, v9
	v_exp_f32_e32 v10, v10
	v_add_f32_e32 v14, 1.0, v14
	v_add_f32_e32 v8, 1.0, v15
	v_rcp_f32_e32 v14, v14
	v_rcp_f32_e32 v8, v8
	v_add_f32_e32 v9, 1.0, v9
	v_add_f32_e32 v10, 1.0, v10
	v_rcp_f32_e32 v9, v9
	v_rcp_f32_e32 v10, v10
	v_mul_f32_e32 v2, v2, v14
	v_mul_f32_e32 v3, v3, v8
	v_cvt_pk_bf16_f32 v2, v2, v3
	v_mul_f32_e32 v3, v4, v9
	v_mul_f32_e32 v4, v5, v10
	v_cvt_pk_bf16_f32 v3, v3, v4
	v_add_co_u32_e32 v4, vcc, 0x1fc000, v6
	s_nop 1
	v_addc_co_u32_e32 v5, vcc, 0, v7, vcc
	global_store_dwordx2 v[4:5], v[2:3], off
	s_waitcnt lgkmcnt(0)
	s_cbranch_scc1 .LBB0_727
	v_readlane_b32 s54, v255, 22
	v_readlane_b32 s55, v255, 23
	s_mov_b32 s50, 0x800000
	v_readlane_b32 s46, v254, 1
	v_readlane_b32 s47, v254, 2

; __device__ __forceinline__ float xsum_rows(float v) { return xsum32(xsum16(v)); }
; __global__ void __launch_bounds__(512, 2) mega_fwd(Params P) {
;     ...
;                             float sm = 0.f;
; #pragma unroll
;                             for (int cb = 0; cb < 8; ++cb) sm += (o[0][cb][0] + o[0][cb][1]) + (o[0][cb][2] + o[0][cb][3]);
;                             sm = xsum_rows(sm);
;                             const float mean = sm * (1.0f / 128.0f); float sq = 0.f;
; #pragma unroll
;                             for (int cb = 0; cb < 8; ++cb) { o[0][cb] = o[0][cb] - mean; sq += (o[0][cb][0] * o[0][cb][0] + o[0][cb][1] * o[0][cb][1]) + (o[0][cb][2] * o[0][cb][2] + o[0][cb][3] * o[0][cb][3]); }
;                             sq = xsum_rows(sq);
;                             const float rstd = rsqrtf(sq * (1.0f / 128.0f) + LN_EPS);
;                             const size_t row = rb + q0 + wave * 16 + r;
;                             f32x4 ggv[8]; u32x2 gwv[8];
; #pragma unroll
;                             for (int cb = 0; cb < 8; ++cb) { const int col = cb * 16 + g4 * 4; ggv[cb] = *(const f32x4*)(rg + col); gwv[cb] = *(const u32x2*)(Z + row * ZW + 1536 + h * 128 + col); }
.LBB0_787:
	v_add_f32_e32 v0, v30, v31
	v_add_f32_e32 v34, v32, v33
	v_add_f32_e32 v0, v0, v34
	v_add_f32_e32 v34, v26, v27
	v_add_f32_e32 v35, v28, v29
	v_add_f32_e32 v0, 0, v0
	v_add_f32_e32 v34, v34, v35
	v_add_f32_e32 v0, v0, v34
	v_add_f32_e32 v34, v22, v23
	v_add_f32_e32 v35, v24, v25
	v_add_f32_e32 v34, v34, v35
	v_add_f32_e32 v0, v0, v34
	v_add_f32_e32 v34, v18, v19
	v_add_f32_e32 v35, v20, v21
	v_add_f32_e32 v34, v34, v35
	v_add_f32_e32 v0, v0, v34
	v_add_f32_e32 v34, v14, v15
	v_add_f32_e32 v35, v16, v17
	v_add_f32_e32 v34, v34, v35
	v_add_f32_e32 v0, v0, v34
	v_add_f32_e32 v34, v10, v11
	v_add_f32_e32 v35, v12, v13
	v_add_f32_e32 v34, v34, v35
	v_add_f32_e32 v0, v0, v34
	v_add_f32_e32 v34, v6, v7
	v_add_f32_e32 v35, v8, v9
	v_add_f32_e32 v34, v34, v35
	v_add_f32_e32 v0, v0, v34
	v_add_f32_e32 v34, v2, v3
	v_add_f32_e32 v35, v4, v5
	v_add_f32_e32 v34, v34, v35
	v_add_f32_e32 v0, v0, v34
	v_mov_b32_e32 v34, v0
	s_nop 1
	v_permlane16_swap_b32_e32 v0, v34
	v_add_f32_e32 v0, v0, v34
	v_mov_b32_e32 v34, v0
	s_nop 1
	v_permlane32_swap_b32_e32 v0, v34
	v_add_f32_e32 v38, v0, v34
	v_fmac_f32_e32 v33, 0xbc000000, v38
	v_fmac_f32_e32 v31, 0xbc000000, v38
	v_fmac_f32_e32 v32, 0xbc000000, v38
	v_fmac_f32_e32 v30, 0xbc000000, v38
	v_mul_f32_e32 v0, v31, v31
	v_mul_f32_e32 v34, v33, v33
	v_fmac_f32_e32 v0, v30, v30
	v_fmac_f32_e32 v34, v32, v32
	v_fmac_f32_e32 v29, 0xbc000000, v38
	v_fmac_f32_e32 v27, 0xbc000000, v38
	v_add_f32_e32 v0, v0, v34
	v_fmac_f32_e32 v28, 0xbc000000, v38
	v_fmac_f32_e32 v26, 0xbc000000, v38
	v_mul_f32_e32 v34, v27, v27
	v_mul_f32_e32 v35, v29, v29
	v_fmac_f32_e32 v34, v26, v26
	v_fmac_f32_e32 v35, v28, v28
	v_add_f32_e32 v34, v34, v35
	v_fmac_f32_e32 v25, 0xbc000000, v38
	v_fmac_f32_e32 v23, 0xbc000000, v38
	v_add_f32_e32 v0, v0, v34
	v_fmac_f32_e32 v24, 0xbc000000, v38
	v_fmac_f32_e32 v22, 0xbc000000, v38
	v_mul_f32_e32 v34, v23, v23
	v_mul_f32_e32 v35, v25, v25
	v_fmac_f32_e32 v34, v22, v22
	v_fmac_f32_e32 v35, v24, v24
	v_add_f32_e32 v34, v34, v35
	v_add_f32_e32 v39, v0, v34
	v_lshl_add_u64 v[86:87], s[6:7], 0, v[74:75]
	v_mov_b64_e32 v[34:35], s[4:5]
	v_mad_u64_u32 v[34:35], s[6:7], v86, s57, v[34:35]
	v_mov_b32_e32 v0, v35
	v_mad_u64_u32 v[36:37], s[6:7], v87, s57, v[0:1]
	v_mov_b32_e32 v35, v36
	s_lshl_b32 s94, s21, 1
	v_lshl_add_u64 v[34:35], v[34:35], 0, s[94:95]
	v_mov_b32_e32 v79, v1
	v_lshl_add_u64 v[66:67], v[34:35], 0, v[78:79]
	global_load_dwordx2 v[84:85], v[66:67], off offset:3072
	global_load_dwordx2 v[88:89], v[66:67], off offset:3104
	s_waitcnt lgkmcnt(0)
	global_load_dwordx4 v[58:61], v[76:77], off
	v_fmac_f32_e32 v21, 0xbc000000, v38
	v_fmac_f32_e32 v19, 0xbc000000, v38
	v_fmac_f32_e32 v20, 0xbc000000, v38
	v_fmac_f32_e32 v18, 0xbc000000, v38
	v_mul_f32_e32 v40, v19, v19
	v_mul_f32_e32 v0, v21, v21
	v_fmac_f32_e32 v17, 0xbc000000, v38
	v_fmac_f32_e32 v15, 0xbc000000, v38
	v_fmac_f32_e32 v40, v18, v18
	v_fmac_f32_e32 v0, v20, v20
	v_fmac_f32_e32 v16, 0xbc000000, v38
	v_fmac_f32_e32 v14, 0xbc000000, v38
	v_mul_f32_e32 v34, v15, v15
	v_mul_f32_e32 v35, v17, v17
	v_add_f32_e32 v0, v40, v0
	v_fmac_f32_e32 v34, v14, v14
	v_fmac_f32_e32 v35, v16, v16
	v_add_f32_e32 v0, v39, v0
	v_add_f32_e32 v34, v34, v35
	v_fmac_f32_e32 v13, 0xbc000000, v38
	v_fmac_f32_e32 v11, 0xbc000000, v38
	v_add_f32_e32 v0, v0, v34
	v_fmac_f32_e32 v12, 0xbc000000, v38
	v_fmac_f32_e32 v10, 0xbc000000, v38
	v_mul_f32_e32 v34, v11, v11
	v_mul_f32_e32 v35, v13, v13
	v_fmac_f32_e32 v34, v10, v10
	v_fmac_f32_e32 v35, v12, v12
	v_add_f32_e32 v34, v34, v35
	v_fmac_f32_e32 v9, 0xbc000000, v38
	v_fmac_f32_e32 v7, 0xbc000000, v38
	v_add_f32_e32 v0, v0, v34
	v_fmac_f32_e32 v8, 0xbc000000, v38
	v_fmac_f32_e32 v6, 0xbc000000, v38
	v_mul_f32_e32 v34, v7, v7
	v_mul_f32_e32 v35, v9, v9
	v_fmac_f32_e32 v34, v6, v6
	v_fmac_f32_e32 v35, v8, v8
	v_add_f32_e32 v34, v34, v35
	v_fmac_f32_e32 v5, 0xbc000000, v38
	v_fmac_f32_e32 v3, 0xbc000000, v38
	v_add_f32_e32 v0, v0, v34
	v_fmac_f32_e32 v4, 0xbc000000, v38
	v_fmac_f32_e32 v2, 0xbc000000, v38
	v_mul_f32_e32 v34, v3, v3
	v_mul_f32_e32 v35, v5, v5
	v_fmac_f32_e32 v34, v2, v2
	v_fmac_f32_e32 v35, v4, v4
	v_add_f32_e32 v34, v34, v35
	v_add_f32_e32 v0, v0, v34
	v_mov_b32_e32 v34, v0
	s_nop 1
	v_permlane16_swap_b32_e32 v0, v34
	v_add_f32_e32 v0, v0, v34
	v_mov_b32_e32 v34, v0
	s_nop 1
	v_permlane32_swap_b32_e32 v0, v34
	v_add_f32_e32 v0, v0, v34
	v_fmamk_f32 v0, v0, 0x3c000000, v220
	v_mul_f32_e32 v34, 0x4b800000, v0
	v_cmp_gt_f32_e32 vcc, s50, v0
	v_lshlrev_b64 v[86:87], 11, v[86:87]
	v_lshl_add_u64 v[86:87], s[2:3], 0, v[86:87]
	v_cndmask_b32_e32 v0, v0, v34, vcc
	global_load_dwordx4 v[62:65], v[76:77], off offset:64
	global_load_dwordx4 v[54:57], v[76:77], off offset:128
	global_load_dwordx4 v[50:53], v[76:77], off offset:192
	global_load_dwordx2 v[82:83], v[66:67], off offset:3136
	global_load_dwordx2 v[80:81], v[66:67], off offset:3168
	global_load_dwordx4 v[46:49], v[76:77], off offset:256
	global_load_dwordx4 v[42:45], v[76:77], off offset:320
	global_load_dwordx4 v[38:41], v[76:77], off offset:384
	global_load_dwordx4 v[34:37], v[76:77], off offset:448
	global_load_dwordx2 v[72:73], v[66:67], off offset:3200
	global_load_dwordx2 v[70:71], v[66:67], off offset:3232
	global_load_dwordx2 v[68:69], v[66:67], off offset:3264
	s_nop 0
	global_load_dwordx2 v[66:67], v[66:67], off offset:3296
	v_rsq_f32_e32 v0, v0
	v_lshl_add_u64 v[86:87], v[86:87], 0, s[94:95]
	s_mov_b64 s[6:7], 0x2b800400
	s_add_i32 s1, s1, s20
	v_mul_f32_e32 v90, 0x45800000, v0
	v_cndmask_b32_e32 v0, v0, v90, vcc
	s_cmpk_gt_i32 s1, 0x7ff
	s_waitcnt vmcnt(0)
; __device__ __forceinline__ unsigned cvt_pk_bf16(float lo, float hi) { unsigned r; asm volatile("v_cvt_pk_bf16_f32 %0, %1, %2" : "=v"(r) : "v"(lo), "v"(hi)); return r; }
; __device__ __forceinline__ float bflo(unsigned w) { return __uint_as_float(w << 16); }
; __device__ __forceinline__ float bfhi(unsigned w) { return __uint_as_float(w & 0xffff0000u); }
; __device__ __forceinline__ float silu_f(float x) { return x * __builtin_amdgcn_rcpf(1.0f + __expf(-x)); }
; __global__ void __launch_bounds__(512, 2) mega_fwd(Params P) {
;     ...
; #pragma unroll
;                             for (int cb = 0; cb < 8; ++cb) { const int col = cb * 16 + g4 * 4; const f32x4 gg = ggv[cb];
;                                 const u32x2 gw = gwv[cb];
;                                 f32x4 gt; gt[0] = bflo(gw.x); gt[1] = bfhi(gw.x); gt[2] = bflo(gw.y); gt[3] = bfhi(gw.y);
;                                 f32x4 v;
; #pragma unroll
;                                 for (int j = 0; j < 4; ++j) v[j] = silu_f(gt[j]) * o[0][cb][j] * rstd * gg[j];
;                                 u32x2 wv; wv.x = cvt_pk_bf16(v[0], v[1]); wv.y = cvt_pk_bf16(v[2], v[3]); *(u32x2*)(CAT + row * 1024 + 512 + h * 128 + col) = wv; }
	v_lshlrev_b32_e32 v90, 16, v84
	v_mul_f32_e32 v91, 0xbfb8aa3b, v90
	v_exp_f32_e32 v91, v91
	v_and_b32_e32 v84, 0xffff0000, v84
	v_mul_f32_e32 v93, 0xbfb8aa3b, v84
	v_exp_f32_e32 v93, v93
	v_add_f32_e32 v91, 1.0, v91
	v_rcp_f32_e32 v91, v91
	v_lshlrev_b32_e32 v92, 16, v85
	v_and_b32_e32 v85, 0xffff0000, v85
	v_mul_f32_e32 v90, v91, v90
	v_mul_f32_e32 v30, v30, v90
	v_add_f32_e32 v90, 1.0, v93
	v_rcp_f32_e32 v90, v90
	v_mul_f32_e32 v91, 0xbfb8aa3b, v92
	v_exp_f32_e32 v91, v91
	v_mul_f32_e32 v30, v0, v30
	v_mul_f32_e32 v30, v58, v30
	v_mul_f32_e32 v58, v90, v84
	v_mul_f32_e32 v84, 0xbfb8aa3b, v85
	v_exp_f32_e32 v84, v84
	v_mul_f32_e32 v31, v31, v58
	v_add_f32_e32 v58, 1.0, v91
	v_rcp_f32_e32 v58, v58
	v_mul_f32_e32 v31, v0, v31
	v_mul_f32_e32 v31, v59, v31
	v_add_f32_e32 v59, 1.0, v84
	v_rcp_f32_e32 v59, v59
	v_mul_f32_e32 v58, v58, v92
	v_mul_f32_e32 v32, v32, v58
	v_mul_f32_e32 v32, v0, v32
	v_mul_f32_e32 v58, v60, v32
	v_mul_f32_e32 v32, v59, v85
	v_mul_f32_e32 v32, v33, v32
	v_mul_f32_e32 v32, v0, v32
	v_lshlrev_b32_e32 v60, 16, v88
	v_mul_f32_e32 v33, v61, v32
	v_mul_f32_e32 v61, 0xbfb8aa3b, v60
	v_exp_f32_e32 v61, v61
	v_cvt_pk_bf16_f32 v32, v30, v31
	v_cvt_pk_bf16_f32 v33, v58, v33
	v_lshl_add_u64 v[58:59], v[86:87], 0, v[78:79]
	v_lshl_add_u64 v[30:31], v[58:59], 0, s[6:7]
	v_add_co_u32_e32 v58, vcc, s58, v58
	s_nop 1
	v_addc_co_u32_e32 v59, vcc, 0, v59, vcc
	global_store_dwordx2 v[58:59], v[32:33], off offset:1024
	v_and_b32_e32 v32, 0xffff0000, v88
	v_add_f32_e32 v58, 1.0, v61
	v_rcp_f32_e32 v58, v58
	v_mul_f32_e32 v61, 0xbfb8aa3b, v32
	v_exp_f32_e32 v61, v61
	v_lshlrev_b32_e32 v33, 16, v89
	v_mul_f32_e32 v58, v58, v60
	v_mul_f32_e32 v26, v26, v58
	v_add_f32_e32 v58, 1.0, v61
	v_rcp_f32_e32 v58, v58
	v_mul_f32_e32 v60, 0xbfb8aa3b, v33
	v_exp_f32_e32 v60, v60
	v_and_b32_e32 v59, 0xffff0000, v89
	v_mul_f32_e32 v32, v58, v32
	v_mul_f32_e32 v27, v27, v32
	v_add_f32_e32 v32, 1.0, v60
	v_mul_f32_e32 v58, 0xbfb8aa3b, v59
	v_rcp_f32_e32 v32, v32
	v_exp_f32_e32 v58, v58
	v_mul_f32_e32 v26, v0, v26
	v_mul_f32_e32 v27, v0, v27
	v_mul_f32_e32 v32, v32, v33
	v_add_f32_e32 v33, 1.0, v58
	v_rcp_f32_e32 v33, v33
	v_mul_f32_e32 v28, v28, v32
	v_mul_f32_e32 v28, v0, v28
	v_mul_f32_e32 v26, v62, v26
	v_mul_f32_e32 v32, v33, v59
	v_mul_f32_e32 v29, v29, v32
	v_mul_f32_e32 v27, v63, v27
	v_mul_f32_e32 v28, v64, v28
	v_mul_f32_e32 v29, v0, v29
	v_mul_f32_e32 v29, v65, v29
	v_cvt_pk_bf16_f32 v26, v26, v27
	v_cvt_pk_bf16_f32 v27, v28, v29
	s_waitcnt lgkmcnt(0)
	v_lshlrev_b32_e32 v28, 16, v82
	v_mul_f32_e32 v29, 0xbfb8aa3b, v28
	v_exp_f32_e32 v29, v29
	global_store_dwordx2 v[30:31], v[26:27], off offset:32
	v_and_b32_e32 v26, 0xffff0000, v82
	v_mul_f32_e32 v33, 0xbfb8aa3b, v26
	v_add_f32_e32 v29, 1.0, v29
	v_rcp_f32_e32 v29, v29
	v_exp_f32_e32 v33, v33
	v_lshlrev_b32_e32 v27, 16, v83
	v_and_b32_e32 v32, 0xffff0000, v83
	v_mul_f32_e32 v28, v29, v28
	v_mul_f32_e32 v22, v22, v28
	v_add_f32_e32 v28, 1.0, v33
	v_rcp_f32_e32 v28, v28
	v_mul_f32_e32 v29, 0xbfb8aa3b, v27
	v_exp_f32_e32 v29, v29
	v_mul_f32_e32 v22, v0, v22
	v_mul_f32_e32 v26, v28, v26
	v_mul_f32_e32 v23, v23, v26
	v_add_f32_e32 v26, 1.0, v29
	v_mul_f32_e32 v28, 0xbfb8aa3b, v32
	v_rcp_f32_e32 v26, v26
	v_exp_f32_e32 v28, v28
	v_mul_f32_e32 v23, v0, v23
	v_mul_f32_e32 v22, v54, v22
	v_mul_f32_e32 v26, v26, v27
	v_add_f32_e32 v27, 1.0, v28
	v_rcp_f32_e32 v27, v27
	v_mul_f32_e32 v24, v24, v26
	v_mul_f32_e32 v24, v0, v24
	v_mul_f32_e32 v23, v55, v23
	v_mul_f32_e32 v26, v27, v32
	v_mul_f32_e32 v25, v25, v26
	v_mul_f32_e32 v24, v56, v24
	v_mul_f32_e32 v25, v0, v25
	v_mul_f32_e32 v25, v57, v25
	v_cvt_pk_bf16_f32 v22, v22, v23
	v_cvt_pk_bf16_f32 v23, v24, v25
	v_lshlrev_b32_e32 v24, 16, v80
	v_mul_f32_e32 v25, 0xbfb8aa3b, v24
	v_exp_f32_e32 v25, v25
	global_store_dwordx2 v[30:31], v[22:23], off offset:64
	v_and_b32_e32 v22, 0xffff0000, v80
	v_mul_f32_e32 v27, 0xbfb8aa3b, v22
	v_add_f32_e32 v25, 1.0, v25
	v_rcp_f32_e32 v25, v25
	v_exp_f32_e32 v27, v27
	v_lshlrev_b32_e32 v23, 16, v81
	v_and_b32_e32 v26, 0xffff0000, v81
	v_mul_f32_e32 v24, v25, v24
	v_mul_f32_e32 v18, v18, v24
	v_add_f32_e32 v24, 1.0, v27
	v_rcp_f32_e32 v24, v24
	v_mul_f32_e32 v25, 0xbfb8aa3b, v23
	v_exp_f32_e32 v25, v25
	v_mul_f32_e32 v18, v0, v18
	v_mul_f32_e32 v22, v24, v22
	v_mul_f32_e32 v19, v19, v22
	v_add_f32_e32 v22, 1.0, v25
	v_mul_f32_e32 v24, 0xbfb8aa3b, v26
	v_rcp_f32_e32 v22, v22
	v_exp_f32_e32 v24, v24
	v_mul_f32_e32 v19, v0, v19
	v_mul_f32_e32 v18, v50, v18
	v_mul_f32_e32 v22, v22, v23
	v_add_f32_e32 v23, 1.0, v24
	v_rcp_f32_e32 v23, v23
	v_mul_f32_e32 v20, v20, v22
	v_mul_f32_e32 v20, v0, v20
	v_mul_f32_e32 v19, v51, v19
	v_mul_f32_e32 v22, v23, v26
	v_mul_f32_e32 v21, v21, v22
	v_mul_f32_e32 v20, v52, v20
	v_mul_f32_e32 v21, v0, v21
	v_mul_f32_e32 v21, v53, v21
	v_cvt_pk_bf16_f32 v18, v18, v19
	v_cvt_pk_bf16_f32 v19, v20, v21
	v_lshlrev_b32_e32 v20, 16, v72
	v_mul_f32_e32 v21, 0xbfb8aa3b, v20
	v_exp_f32_e32 v21, v21
	global_store_dwordx2 v[30:31], v[18:19], off offset:96
	v_and_b32_e32 v18, 0xffff0000, v72
	v_mul_f32_e32 v23, 0xbfb8aa3b, v18
	v_add_f32_e32 v21, 1.0, v21
	v_rcp_f32_e32 v21, v21
	v_exp_f32_e32 v23, v23
	v_lshlrev_b32_e32 v19, 16, v73
	v_and_b32_e32 v22, 0xffff0000, v73
	v_mul_f32_e32 v20, v21, v20
	v_mul_f32_e32 v14, v14, v20
	v_add_f32_e32 v20, 1.0, v23
	v_rcp_f32_e32 v20, v20
	v_mul_f32_e32 v21, 0xbfb8aa3b, v19
	v_exp_f32_e32 v21, v21
	v_mul_f32_e32 v14, v0, v14
	v_mul_f32_e32 v18, v20, v18
	v_mul_f32_e32 v15, v15, v18
	v_add_f32_e32 v18, 1.0, v21
	v_mul_f32_e32 v20, 0xbfb8aa3b, v22
	v_rcp_f32_e32 v18, v18
	v_exp_f32_e32 v20, v20
	v_mul_f32_e32 v15, v0, v15
	v_mul_f32_e32 v14, v46, v14
	v_mul_f32_e32 v18, v18, v19
; __device__ __forceinline__ unsigned cvt_pk_bf16(float lo, float hi) { unsigned r; asm volatile("v_cvt_pk_bf16_f32 %0, %1, %2" : "=v"(r) : "v"(lo), "v"(hi)); return r; }
; __device__ __forceinline__ float bflo(unsigned w) { return __uint_as_float(w << 16); }
; __device__ __forceinline__ float bfhi(unsigned w) { return __uint_as_float(w & 0xffff0000u); }
; __device__ __forceinline__ float silu_f(float x) { return x * __builtin_amdgcn_rcpf(1.0f + __expf(-x)); }
; __global__ void __launch_bounds__(512, 2) mega_fwd(Params P) {
;     ...
;                             const int bh = u & 127, b = bh >> 2, h = bh & 3, qi_ = u >> 7, ii_ = qi_ >> 1, hb_ = qi_ & 1, qt = (ii_ & 1) ? (ii_ - 1 + hb_) : (15 - hb_ - ii_), q0 = qt * 128, nkt = qt + 1;
;                             const size_t rb = (size_t)b * SEQ;
;                             const float l2g = log2f(1.0f - exp2f(-5.0f - (float)h));
;     ...
;                             for (int cb = 0; cb < 8; ++cb) { const int col = cb * 16 + g4 * 4; const f32x4 gg = ggv[cb];
;                                 const u32x2 gw = gwv[cb];
;                                 f32x4 gt; gt[0] = bflo(gw.x); gt[1] = bfhi(gw.x); gt[2] = bflo(gw.y); gt[3] = bfhi(gw.y);
;                                 f32x4 v;
; #pragma unroll
;                                 for (int j = 0; j < 4; ++j) v[j] = silu_f(gt[j]) * o[0][cb][j] * rstd * gg[j];
;                                 u32x2 wv; wv.x = cvt_pk_bf16(v[0], v[1]); wv.y = cvt_pk_bf16(v[2], v[3]); *(u32x2*)(CAT + row * 1024 + 512 + h * 128 + col) = wv; }
	v_add_f32_e32 v19, 1.0, v20
	v_rcp_f32_e32 v19, v19
	v_mul_f32_e32 v16, v16, v18
	v_mul_f32_e32 v16, v0, v16
	v_mul_f32_e32 v15, v47, v15
	v_mul_f32_e32 v18, v19, v22
	v_mul_f32_e32 v17, v17, v18
	v_mul_f32_e32 v16, v48, v16
	v_mul_f32_e32 v17, v0, v17
	v_mul_f32_e32 v17, v49, v17
	v_cvt_pk_bf16_f32 v14, v14, v15
	v_cvt_pk_bf16_f32 v15, v16, v17
	v_lshlrev_b32_e32 v16, 16, v70
	v_mul_f32_e32 v17, 0xbfb8aa3b, v16
	v_exp_f32_e32 v17, v17
	global_store_dwordx2 v[30:31], v[14:15], off offset:128
	v_and_b32_e32 v14, 0xffff0000, v70
	v_mul_f32_e32 v19, 0xbfb8aa3b, v14
	v_add_f32_e32 v17, 1.0, v17
	v_rcp_f32_e32 v17, v17
	v_exp_f32_e32 v19, v19
	v_lshlrev_b32_e32 v15, 16, v71
	v_and_b32_e32 v18, 0xffff0000, v71
	v_mul_f32_e32 v16, v17, v16
	v_mul_f32_e32 v10, v10, v16
	v_add_f32_e32 v16, 1.0, v19
	v_rcp_f32_e32 v16, v16
	v_mul_f32_e32 v17, 0xbfb8aa3b, v15
	v_exp_f32_e32 v17, v17
	v_mul_f32_e32 v10, v0, v10
	v_mul_f32_e32 v14, v16, v14
	v_mul_f32_e32 v11, v11, v14
	v_add_f32_e32 v14, 1.0, v17
	v_mul_f32_e32 v16, 0xbfb8aa3b, v18
	v_rcp_f32_e32 v14, v14
	v_exp_f32_e32 v16, v16
	v_mul_f32_e32 v11, v0, v11
	v_mul_f32_e32 v10, v42, v10
	v_mul_f32_e32 v14, v14, v15
	v_add_f32_e32 v15, 1.0, v16
	v_rcp_f32_e32 v15, v15
	v_mul_f32_e32 v12, v12, v14
	v_mul_f32_e32 v12, v0, v12
	v_mul_f32_e32 v11, v43, v11
	v_mul_f32_e32 v14, v15, v18
	v_mul_f32_e32 v13, v13, v14
	v_mul_f32_e32 v12, v44, v12
	v_mul_f32_e32 v13, v0, v13
	v_mul_f32_e32 v13, v45, v13
	v_cvt_pk_bf16_f32 v10, v10, v11
	v_cvt_pk_bf16_f32 v11, v12, v13
	v_lshlrev_b32_e32 v12, 16, v68
	v_mul_f32_e32 v13, 0xbfb8aa3b, v12
	v_exp_f32_e32 v13, v13
	global_store_dwordx2 v[30:31], v[10:11], off offset:160
	v_and_b32_e32 v10, 0xffff0000, v68
	v_mul_f32_e32 v15, 0xbfb8aa3b, v10
	v_add_f32_e32 v13, 1.0, v13
	v_rcp_f32_e32 v13, v13
	v_exp_f32_e32 v15, v15
	v_lshlrev_b32_e32 v11, 16, v69
	v_and_b32_e32 v14, 0xffff0000, v69
	v_mul_f32_e32 v12, v13, v12
	v_mul_f32_e32 v6, v6, v12
	v_add_f32_e32 v12, 1.0, v15
	v_rcp_f32_e32 v12, v12
	v_mul_f32_e32 v13, 0xbfb8aa3b, v11
	v_exp_f32_e32 v13, v13
	v_mul_f32_e32 v6, v0, v6
	v_mul_f32_e32 v10, v12, v10
	v_mul_f32_e32 v7, v7, v10
	v_add_f32_e32 v10, 1.0, v13
	v_mul_f32_e32 v12, 0xbfb8aa3b, v14
	v_rcp_f32_e32 v10, v10
	v_exp_f32_e32 v12, v12
	v_mul_f32_e32 v7, v0, v7
	v_mul_f32_e32 v6, v38, v6
	v_mul_f32_e32 v10, v10, v11
	v_add_f32_e32 v11, 1.0, v12
	v_rcp_f32_e32 v11, v11
	v_mul_f32_e32 v8, v8, v10
	v_mul_f32_e32 v8, v0, v8
	v_mul_f32_e32 v7, v39, v7
	v_mul_f32_e32 v10, v11, v14
	v_mul_f32_e32 v9, v9, v10
	v_mul_f32_e32 v8, v40, v8
	v_mul_f32_e32 v9, v0, v9
	v_mul_f32_e32 v9, v41, v9
	v_cvt_pk_bf16_f32 v6, v6, v7
	v_cvt_pk_bf16_f32 v7, v8, v9
	v_lshlrev_b32_e32 v8, 16, v66
	v_mul_f32_e32 v9, 0xbfb8aa3b, v8
	v_exp_f32_e32 v9, v9
	global_store_dwordx2 v[30:31], v[6:7], off offset:192
	v_and_b32_e32 v6, 0xffff0000, v66
	v_mul_f32_e32 v11, 0xbfb8aa3b, v6
	v_add_f32_e32 v9, 1.0, v9
	v_rcp_f32_e32 v9, v9
	v_exp_f32_e32 v11, v11
	v_lshlrev_b32_e32 v7, 16, v67
	v_and_b32_e32 v10, 0xffff0000, v67
	v_mul_f32_e32 v8, v9, v8
	v_mul_f32_e32 v2, v2, v8
	v_add_f32_e32 v8, 1.0, v11
	v_rcp_f32_e32 v8, v8
	v_mul_f32_e32 v9, 0xbfb8aa3b, v7
	v_exp_f32_e32 v9, v9
	v_mul_f32_e32 v2, v0, v2
	v_mul_f32_e32 v6, v8, v6
	v_mul_f32_e32 v3, v3, v6
	v_add_f32_e32 v6, 1.0, v9
	v_mul_f32_e32 v8, 0xbfb8aa3b, v10
	v_rcp_f32_e32 v6, v6
	v_exp_f32_e32 v8, v8
	v_mul_f32_e32 v3, v0, v3
	v_mul_f32_e32 v2, v34, v2
	v_mul_f32_e32 v6, v6, v7
	v_add_f32_e32 v7, 1.0, v8
	v_rcp_f32_e32 v7, v7
	v_mul_f32_e32 v4, v4, v6
	v_mul_f32_e32 v3, v35, v3
	v_mul_f32_e32 v4, v0, v4
	v_mul_f32_e32 v6, v7, v10
	v_mul_f32_e32 v5, v5, v6
	v_mul_f32_e32 v0, v0, v5
	v_mul_f32_e32 v4, v36, v4
	v_mul_f32_e32 v0, v37, v0
	v_cvt_pk_bf16_f32 v2, v2, v3
	v_cvt_pk_bf16_f32 v3, v4, v0
	global_store_dwordx2 v[30:31], v[2:3], off offset:224
	s_cbranch_scc1 .LBB0_799
.LBB0_788:
	s_ashr_i32 s6, s1, 8
	s_bfe_u32 s7, s1, 0x10007
	s_add_i32 s9, s6, s7
	s_xor_b32 s7, s7, 15
	s_and_b32 s12, s1, 3
	s_and_b32 s8, s1, 0x100
	s_add_i32 s9, s9, -1
	s_sub_i32 s6, s7, s6
	s_cmp_eq_u32 s8, 0
	s_cselect_b32 s22, s6, s9
	s_lshl_b32 s6, s1, 9
	v_cvt_f32_ubyte0_e32 v0, s12
	s_and_b32 s8, s6, 0xf800
	v_sub_f32_e32 v0, 0xc0a00000, v0
	s_mov_b32 s6, 0xc2fc0000
	v_cmp_gt_f32_e32 vcc, s6, v0
	v_mov_b32_e32 v2, 0x42800000
	s_lshl_b32 s31, s22, 7
	v_cndmask_b32_e32 v2, 0, v2, vcc
	v_add_f32_e32 v0, v0, v2
	v_exp_f32_e32 v0, v0
	s_and_b64 s[6:7], vcc, exec
	s_cselect_b32 s6, 0xffffffc0, 0
	v_mov_b32_e32 v11, v211
	v_ldexp_f32 v0, v0, s6
	v_sub_f32_e32 v10, 1.0, v0
	v_cmp_gt_f32_e32 vcc, s50, v10
	s_and_b64 s[6:7], vcc, exec
	s_cselect_b32 s43, 32, 0
	s_ashr_i32 s7, s31, 31
	s_add_u32 s6, s31, s8
	s_addc_u32 s7, s7, 0
	s_mul_i32 s9, s7, 0x1400
	s_mul_hi_u32 s10, s6, 0x1400
	s_add_i32 s10, s10, s9
	s_mul_i32 s9, s6, 0x1400
	s_add_u32 s9, s4, s9
	s_addc_u32 s11, s5, s10
	s_lshl_b32 s21, s12, 7
	s_add_u32 s10, s9, s21
	s_addc_u32 s11, s11, 0
	s_mulk_i32 s8, 0x1400
	s_add_u32 s13, s4, s8
	s_addc_u32 s15, s5, 0
	s_add_u32 s8, s13, s21
	s_addc_u32 s9, s15, 0
	s_lshl_b32 s12, s12, 8
	s_add_u32 s14, s13, s12
	s_addc_u32 s15, s15, 0
	v_readfirstlane_b32 s12, v11
	s_ashr_i32 s18, s12, 6
	v_and_b32_e32 v6, 15, v11
	s_lshl_b32 s33, s18, 4
	v_or_b32_e32 v0, s33, v6
	v_mov_b64_e32 v[2:3], s[10:11]
	v_mad_i64_i32 v[2:3], s[10:11], v0, s57, v[2:3]
	v_and_b32_e32 v0, 48, v11
	v_lshl_add_u64 v[2:3], v[2:3], 0, v[0:1]
	v_ashrrev_i32_e32 v0, 31, v11
	v_lshrrev_b32_e32 v0, 29, v0
	v_add_u32_e32 v0, v11, v0
	v_ashrrev_i32_e32 v8, 3, v0
	v_and_b32_e32 v0, -8, v0
	v_sub_u32_e32 v16, v11, v0
	global_load_dwordx4 v[34:37], v[2:3], off offset:1024
	global_load_dwordx4 v[38:41], v[2:3], off offset:1088
; template <int D, int DV, int MODE, int NMAP, int KT> ...
;     ...
;     AT_LOAD(0);
;     __syncthreads();
;     AT_STORE(0);
;     if (nkt > 1) AT_LOAD(1);
	v_mov_b64_e32 v[4:5], s[8:9]
	v_lshlrev_b32_e32 v2, 3, v16
	v_add_u32_e32 v0, 0x200, v11
	v_mad_i64_i32 v[12:13], s[10:11], v8, s57, v[4:5]
	v_ashrrev_i32_e32 v3, 31, v2
	v_ashrrev_i32_e32 v9, 31, v0
	v_lshl_add_u64 v[12:13], v[2:3], 1, v[12:13]
	v_lshrrev_b32_e32 v9, 29, v9
	global_load_dwordx4 v[42:45], v[12:13], off offset:1536
	v_add_u32_e32 v12, v0, v9
	v_ashrrev_i32_e32 v9, 3, v12
	v_and_b32_e32 v12, -8, v12
	v_sub_u32_e32 v17, v0, v12
	v_mad_i64_i32 v[12:13], s[10:11], v9, s57, v[4:5]
	s_ashr_i32 s10, s18, 31
	s_lshr_b32 s10, s10, 28
	v_lshlrev_b32_e32 v4, 3, v17
	s_add_i32 s10, s18, s10
	v_ashrrev_i32_e32 v5, 31, v4
	s_ashr_i32 s24, s10, 4
	s_add_i32 s12, s18, 8
	v_and_b32_e32 v7, 63, v11
	v_lshl_add_u64 v[12:13], v[4:5], 1, v[12:13]
	s_lshl_b32 s34, s24, 6
	s_ashr_i32 s13, s12, 31
	global_load_dwordx4 v[46:49], v[12:13], off offset:1536
	s_and_b32 s10, s10, -16
	v_or_b32_e32 v0, s34, v7
	v_mov_b64_e32 v[12:13], s[14:15]
	s_lshr_b32 s13, s13, 28
	s_sub_i32 s23, s18, s10
	v_mad_i64_i32 v[14:15], s[10:11], v0, s57, v[12:13]
	s_add_i32 s13, s12, s13
	s_lshl_b32 s10, s23, 3
	s_ashr_i32 s26, s13, 4
	s_add_i32 s16, s18, 16
	s_ashr_i32 s11, s10, 31
	s_lshl_b32 s40, s26, 6
	s_ashr_i32 s17, s16, 31
	s_add_i32 s18, s18, 24
	v_lshl_add_u64 v[14:15], s[10:11], 1, v[14:15]
	s_and_b32 s13, s13, -16
	v_or_b32_e32 v0, s40, v7
	s_lshr_b32 s17, s17, 28
	s_ashr_i32 s19, s18, 31
	global_load_dwordx4 v[50:53], v[14:15], off offset:2048
	s_sub_i32 s25, s12, s13
	v_mad_i64_i32 v[14:15], s[12:13], v0, s57, v[12:13]
	s_add_i32 s17, s16, s17
	s_lshr_b32 s19, s19, 28
	s_lshl_b32 s12, s25, 3
	s_ashr_i32 s28, s17, 4
	s_add_i32 s19, s18, s19
	s_ashr_i32 s13, s12, 31
	s_lshl_b32 s41, s28, 6
	s_ashr_i32 s30, s19, 4
	v_lshl_add_u64 v[14:15], s[12:13], 1, v[14:15]
	s_and_b32 s17, s17, -16
	v_or_b32_e32 v0, s41, v7
	s_lshl_b32 s42, s30, 6
	global_load_dwordx4 v[54:57], v[14:15], off offset:2048
	s_sub_i32 s27, s16, s17
	v_mad_i64_i32 v[14:15], s[16:17], v0, s57, v[12:13]
	s_and_b32 s19, s19, -16
	v_or_b32_e32 v0, s42, v7
	s_lshl_b32 s16, s27, 3
	s_sub_i32 s29, s18, s19
	v_mad_i64_i32 v[12:13], s[18:19], v0, s57, v[12:13]
	s_ashr_i32 s17, s16, 31
	s_lshl_b32 s18, s29, 3
	v_lshl_add_u64 v[14:15], s[16:17], 1, v[14:15]
	s_ashr_i32 s19, s18, 31
	global_load_dwordx4 v[58:61], v[14:15], off offset:2048
	v_lshl_add_u64 v[12:13], s[18:19], 1, v[12:13]
	global_load_dwordx4 v[62:65], v[12:13], off offset:2048
	s_movk_i32 s36, 0x90
	v_mul_lo_u32 v0, v8, s36
	v_lshlrev_b32_e32 v79, 4, v16
	s_mulk_i32 s23, 0x880
	v_add3_u32 v12, 0, v0, v79
	v_mul_lo_u32 v84, v9, s36
	v_lshlrev_b32_e32 v85, 4, v17
	s_add_i32 s44, s23, 0
	s_lshl_b32 s24, s24, 7
	s_waitcnt lgkmcnt(0)
	s_barrier
	s_waitcnt vmcnt(0)
	ds_write_b128 v12, v[42:45]
	v_add3_u32 v12, 0, v84, v85
	s_add_i32 s44, s44, s24
	v_lshlrev_b32_e32 v86, 1, v7
	s_mulk_i32 s25, 0x880
	s_lshl_b32 s26, s26, 7
	s_mulk_i32 s27, 0x880
	s_lshl_b32 s28, s28, 7
	s_mulk_i32 s29, 0x880
	s_lshl_b32 s30, s30, 7
	ds_write_b128 v12, v[46:49]
	v_add_u32_e32 v12, s44, v86
	s_add_i32 s44, s25, 0
	s_add_i32 s44, s44, s26
	ds_write_b16 v12, v50 offset:18432
	ds_write_b16_d16_hi v12, v50 offset:18704
	ds_write_b16 v12, v51 offset:18976
	ds_write_b16_d16_hi v12, v51 offset:19248
	ds_write_b16 v12, v52 offset:19520
	ds_write_b16_d16_hi v12, v52 offset:19792
	ds_write_b16 v12, v53 offset:20064
	ds_write_b16_d16_hi v12, v53 offset:20336
	v_add_u32_e32 v12, s44, v86
	s_add_i32 s44, s27, 0
	s_add_i32 s44, s44, s28
	ds_write_b16 v12, v54 offset:18432
	ds_write_b16_d16_hi v12, v54 offset:18704
	ds_write_b16 v12, v55 offset:18976
	ds_write_b16_d16_hi v12, v55 offset:19248
	ds_write_b16 v12, v56 offset:19520
	ds_write_b16_d16_hi v12, v56 offset:19792
	ds_write_b16 v12, v57 offset:20064
	ds_write_b16_d16_hi v12, v57 offset:20336
	v_add_u32_e32 v12, s44, v86
	s_add_i32 s44, s29, 0
	s_add_i32 s44, s44, s30
	ds_write_b16 v12, v58 offset:18432
	ds_write_b16_d16_hi v12, v58 offset:18704
	ds_write_b16 v12, v59 offset:18976
	ds_write_b16_d16_hi v12, v59 offset:19248
	ds_write_b16 v12, v60 offset:19520
	ds_write_b16_d16_hi v12, v60 offset:19792
	ds_write_b16 v12, v61 offset:20064
	ds_write_b16_d16_hi v12, v61 offset:20336
	v_add_u32_e32 v12, s44, v86
	s_cmp_lt_i32 s22, 1
	ds_write_b16 v12, v62 offset:18432
	ds_write_b16_d16_hi v12, v62 offset:18704
	ds_write_b16 v12, v63 offset:18976
	ds_write_b16_d16_hi v12, v63 offset:19248
	ds_write_b16 v12, v64 offset:19520
	ds_write_b16_d16_hi v12, v64 offset:19792
	ds_write_b16 v12, v65 offset:20064
	ds_write_b16_d16_hi v12, v65 offset:20336
	s_cbranch_scc1 .LBB0_790
	v_add_u32_e32 v14, 0x80, v8
	v_mov_b64_e32 v[12:13], s[8:9]
	v_add_u32_e32 v16, 0x80, v9
	v_mad_i64_i32 v[14:15], s[44:45], v14, s57, v[12:13]
	v_mad_i64_i32 v[12:13], s[44:45], v16, s57, v[12:13]
	v_lshl_add_u64 v[14:15], v[2:3], 1, v[14:15]
	v_lshl_add_u64 v[12:13], v[4:5], 1, v[12:13]
	v_or_b32_e32 v18, 0x80, v7
	global_load_dwordx4 v[42:45], v[14:15], off offset:1536
	global_load_dwordx4 v[46:49], v[12:13], off offset:1536
	v_add_u32_e32 v14, s34, v18
	v_mov_b64_e32 v[12:13], s[14:15]
	v_mad_i64_i32 v[14:15], s[44:45], v14, s57, v[12:13]
	v_add_u32_e32 v16, s40, v18
	v_lshl_add_u64 v[14:15], s[10:11], 1, v[14:15]
	v_mad_i64_i32 v[16:17], s[44:45], v16, s57, v[12:13]
	v_lshl_add_u64 v[16:17], s[12:13], 1, v[16:17]
	global_load_dwordx4 v[50:53], v[14:15], off offset:2048
	global_load_dwordx4 v[54:57], v[16:17], off offset:2048
	v_add_u32_e32 v14, s41, v18
	v_mad_i64_i32 v[14:15], s[44:45], v14, s57, v[12:13]
	v_add_u32_e32 v16, s42, v18
	v_lshl_add_u64 v[14:15], s[16:17], 1, v[14:15]
	v_mad_i64_i32 v[12:13], s[44:45], v16, s57, v[12:13]
	v_lshl_add_u64 v[12:13], s[18:19], 1, v[12:13]
	global_load_dwordx4 v[58:61], v[14:15], off offset:2048
	global_load_dwordx4 v[62:65], v[12:13], off offset:2048

; template <int D, int DV, int MODE, int NMAP, int KT> ...
;     ...
;     AT_LOAD(0);
;     __syncthreads();
;     AT_STORE(0);
;     if (nkt > 1) AT_LOAD(1);
;     for (int kt = 0; kt < nkt; ++kt) {
;         __syncthreads();
;         const int cur = (kt & 1) * BUF_BYTES;
;         if (kt + 1 < nkt) { AT_STORE(((kt + 1) & 1) * BUF_BYTES); if (kt + 2 < nkt) AT_LOAD(kt + 2); }
.LBB0_792:
	s_add_i32 s34, s16, 1
	s_cmp_ge_i32 s16, s22
	s_waitcnt lgkmcnt(0)
	s_barrier
	s_cbranch_scc1 .LBB0_795
	s_bitcmp1_b32 s34, 0
	s_cselect_b32 s17, 0xd000, 0
	s_add_i32 s17, s17, 0
	v_add3_u32 v66, s17, v0, v79
	s_add_i32 s40, s17, s23
	s_waitcnt vmcnt(0)
	ds_write_b128 v66, v[42:45]
	v_add3_u32 v66, s17, v84, v85
	s_add_i32 s40, s40, s24
	ds_write_b128 v66, v[46:49]
	v_add_u32_e32 v66, s40, v86
	s_add_i32 s40, s17, s25
	s_add_i32 s40, s40, s26
	ds_write_b16 v66, v50 offset:18432
	ds_write_b16_d16_hi v66, v50 offset:18704
	ds_write_b16 v66, v51 offset:18976
	ds_write_b16_d16_hi v66, v51 offset:19248
	ds_write_b16 v66, v52 offset:19520
	ds_write_b16_d16_hi v66, v52 offset:19792
	ds_write_b16 v66, v53 offset:20064
	ds_write_b16_d16_hi v66, v53 offset:20336
	v_add_u32_e32 v66, s40, v86
	s_add_i32 s40, s17, s27
	s_add_i32 s40, s40, s28
	s_add_i32 s17, s17, s29
	ds_write_b16 v66, v54 offset:18432
	ds_write_b16_d16_hi v66, v54 offset:18704
	ds_write_b16 v66, v55 offset:18976
	ds_write_b16_d16_hi v66, v55 offset:19248
	ds_write_b16 v66, v56 offset:19520
	ds_write_b16_d16_hi v66, v56 offset:19792
	ds_write_b16 v66, v57 offset:20064
	ds_write_b16_d16_hi v66, v57 offset:20336
	v_add_u32_e32 v66, s40, v86
	s_add_i32 s17, s17, s30
	ds_write_b16 v66, v58 offset:18432
	ds_write_b16_d16_hi v66, v58 offset:18704
	ds_write_b16 v66, v59 offset:18976
	ds_write_b16_d16_hi v66, v59 offset:19248
	ds_write_b16 v66, v60 offset:19520
	ds_write_b16_d16_hi v66, v60 offset:19792
	ds_write_b16 v66, v61 offset:20064
	ds_write_b16_d16_hi v66, v61 offset:20336
	v_add_u32_e32 v66, s17, v86
	s_add_i32 s17, s16, 2
	s_cmp_gt_i32 s17, s22
	ds_write_b16 v66, v62 offset:18432
	ds_write_b16_d16_hi v66, v62 offset:18704
	ds_write_b16 v66, v63 offset:18976
	ds_write_b16_d16_hi v66, v63 offset:19248
	ds_write_b16 v66, v64 offset:19520
	ds_write_b16_d16_hi v66, v64 offset:19792
	ds_write_b16 v66, v65 offset:20064
	ds_write_b16_d16_hi v66, v65 offset:20336
	s_cbranch_scc1 .LBB0_795
	v_add_u32_e32 v52, s19, v131
	v_mov_b64_e32 v[50:51], s[8:9]
	v_add_u32_e32 v60, s19, v129
	v_mov_b64_e32 v[58:59], s[12:13]
	v_add_u32_e32 v42, s19, v133
	v_add_u32_e32 v44, s19, v132
	v_mad_i64_i32 v[50:51], s[40:41], v52, s57, v[50:51]
	v_add_u32_e32 v54, s19, v130
	v_mov_b64_e32 v[52:53], s[10:11]
	v_mad_i64_i32 v[58:59], s[40:41], v60, s57, v[58:59]
	v_add_u32_e32 v62, s19, v128
	v_mov_b64_e32 v[60:61], s[14:15]
	v_mad_i64_i32 v[42:43], s[40:41], v42, s57, v[80:81]
	v_mad_i64_i32 v[46:47], s[40:41], v44, s57, v[82:83]
	v_mad_i64_i32 v[54:55], s[40:41], v54, s57, v[52:53]
	v_mad_i64_i32 v[62:63], s[40:41], v62, s57, v[60:61]
	global_load_dwordx4 v[42:45], v[42:43], off offset:1536
	s_nop 0
	global_load_dwordx4 v[46:49], v[46:47], off offset:1536
	s_nop 0
	global_load_dwordx4 v[50:53], v[50:51], off offset:2048
	s_nop 0
	global_load_dwordx4 v[54:57], v[54:55], off offset:2048
	s_nop 0
	global_load_dwordx4 v[58:61], v[58:59], off offset:2048
	s_nop 0
	global_load_dwordx4 v[62:65], v[62:63], off offset:2048

; #define PG8_STAGE(bufoff, gbase, voff) do { _Pragma("unroll") for (int _i = 0; _i < 2; ++_i) \
;         __builtin_amdgcn_global_load_lds((const unsigned*)((const char*)(gbase) + (voff)[_i]), (PG8_LAS unsigned*)(lds + (bufoff) + ldsw + _i * 8192), 16, 0, 0); } while (0)
; #define PG8_LDA(dst, b, h) do { _Pragma("unroll") for (int m = 0; m < 4; ++m) _Pragma("unroll") for (int k = 0; k < 2; ++k) dst[m][k] = *(const PG8_LAS bf16x8*)(lds + PG8_SA(b, h) + aoff + m * 2048 + k * 1024); } while (0)
; #define PG8_LDB(dst, b, h) do { _Pragma("unroll") for (int n = 0; n < 2; ++n) _Pragma("unroll") for (int k = 0; k < 2; ++k) dst[n][k] = *(const PG8_LAS bf16x8*)(lds + PG8_SB(b, h) + boff + n * 2048 + k * 1024); } while (0)
; #define PG8_MMA(ai, bj, At, Bt) do { __builtin_amdgcn_s_setprio(1); _Pragma("unroll") for (int m = 0; m < 4; ++m) _Pragma("unroll") for (int n = 0; n < 2; ++n) _Pragma("unroll") for (int k = 0; k < 2; ++k) \
;         acc[ai][bj][m][n] = __builtin_amdgcn_mfma_f32_16x16x32_bf16(Bt[n][k], At[m][k], acc[ai][bj][m][n], 0, 0, 0); __builtin_amdgcn_s_setprio(0); } while (0)
; #define PG8_WAIT_V(n) asm volatile("s_waitcnt vmcnt(" #n ")" ::: "memory")
; template <class Epi, class Sched, bool ALIGN_EPI = false, bool SP2 = false>
; __device__ __forceinline__ void gemm_phase(PG8_LAS unsigned char* lds, const Gemm g, const Sched& S, const Epi& E) {
;     ...
;             PG8_LDB(B0, 0, 0); PG8_LDB(B1, 0, 1); PG8_SCHED; PG8_LDA(At, 0, 0); PG8_STAGE(PG8_SA(1, 1), a1 + hstep, voffA);
;             PG8_WAIT_V(8); PG8_WAIT_L(0); PG8_BAR; PG8_MMA(0, 0, At, B0); PG8_MMA(0, 1, At, B1); PG8_BAR; PG8_SCHED;
;             PG8_LDA(At, 0, 1); PG8_STAGE(PG8_SB(0, 0), b2, voffB); PG8_STAGE(PG8_SB(0, 1), b2 + hstep, voffB); PG8_STAGE(PG8_SA(0, 0), a2, voffA);
;             PG8_WAIT_V(8); PG8_WAIT_L(0); PG8_BAR; PG8_MMA(1, 0, At, B0); PG8_MMA(1, 1, At, B1); PG8_BAR; PG8_SCHED;
;             PG8_LDB(B0, 1, 0); PG8_LDB(B1, 1, 1); PG8_SCHED; PG8_LDA(At, 1, 0); PG8_STAGE(PG8_SA(0, 1), a2 + hstep, voffA);
;             PG8_WAIT_V(8); PG8_WAIT_L(0); PG8_BAR; PG8_MMA(0, 0, At, B0); PG8_MMA(0, 1, At, B1); PG8_BAR; PG8_SCHED;
;             PG8_LDA(At, 1, 1); PG8_STAGE(PG8_SB(1, 0), b3, voffB); PG8_STAGE(PG8_SB(1, 1), b3 + hstep, voffB); PG8_STAGE(PG8_SA(1, 0), a3, voffA);
;             PG8_WAIT_V(8); PG8_WAIT_L(0); PG8_BAR; PG8_MMA(1, 0, At, B0); PG8_MMA(1, 1, At, B1); PG8_BAR; PG8_SCHED;
.LBB0_821:
	s_add_i32 s74, s30, 2
	s_add_u32 s75, s28, 0x80
	s_addc_u32 s31, s29, 0
	s_add_i32 s80, 0, 0x10000
	s_cmp_eq_u32 s49, s30
	s_cselect_b32 s31, s5, s31
	s_cselect_b32 s30, s4, s75
	v_add_u32_e32 v0, s80, v185
	s_cselect_b32 s77, s27, s67
	s_cselect_b32 s76, s26, s61
	s_add_i32 s75, 0, 0x14000
	ds_read_b128 v[90:93], v0
	ds_read_b128 v[102:105], v0 offset:1024
	ds_read_b128 v[110:113], v0 offset:2048
	ds_read_b128 v[126:129], v0 offset:3072
	v_add_u32_e32 v0, s75, v185
	ds_read_b128 v[134:137], v0
	ds_read_b128 v[150:153], v0 offset:1024
	ds_read_b128 v[154:157], v0 offset:2048
	ds_read_b128 v[158:161], v0 offset:3072
	v_lshl_add_u64 v[182:183], s[28:29], 0, v[176:177]
	s_add_i32 m0, s42, 0xc000
	ds_read_b128 v[162:165], v195
	ds_read_b128 v[178:181], v195 offset:1024
	ds_read_b128 v[196:199], v195 offset:2048
	ds_read_b128 v[200:203], v195 offset:3072
	ds_read_b128 v[204:207], v195 offset:4096
	ds_read_b128 v[226:229], v195 offset:5120
	ds_read_b128 v[230:233], v195 offset:6144
	ds_read_b128 v[234:237], v195 offset:7168
	global_load_lds_dwordx4 v[182:183], off
	v_lshl_add_u64 v[182:183], s[28:29], 0, v[174:175]
	s_add_i32 m0, s42, 0xe000
	s_nop 0
	global_load_lds_dwordx4 v[182:183], off
	s_waitcnt vmcnt(8)
	s_waitcnt lgkmcnt(0)
	s_barrier
	s_setprio 1
	v_mfma_f32_16x16x32_bf16 v[146:149], v[90:93], v[162:165], v[146:149]
	v_mfma_f32_16x16x32_bf16 v[142:145], v[110:113], v[162:165], v[142:145]
	v_mfma_f32_16x16x32_bf16 v[122:125], v[90:93], v[196:199], v[122:125]
	v_mfma_f32_16x16x32_bf16 v[118:121], v[110:113], v[196:199], v[118:121]
	v_mfma_f32_16x16x32_bf16 v[98:101], v[90:93], v[204:207], v[98:101]
	v_mfma_f32_16x16x32_bf16 v[94:97], v[110:113], v[204:207], v[94:97]
	v_mfma_f32_16x16x32_bf16 v[78:81], v[90:93], v[230:233], v[78:81]
	v_mfma_f32_16x16x32_bf16 v[74:77], v[110:113], v[230:233], v[74:77]
	v_mfma_f32_16x16x32_bf16 v[146:149], v[102:105], v[178:181], v[146:149]
	v_mfma_f32_16x16x32_bf16 v[142:145], v[126:129], v[178:181], v[142:145]
	v_mfma_f32_16x16x32_bf16 v[122:125], v[102:105], v[200:203], v[122:125]
	v_mfma_f32_16x16x32_bf16 v[118:121], v[126:129], v[200:203], v[118:121]
	v_mfma_f32_16x16x32_bf16 v[98:101], v[102:105], v[226:229], v[98:101]
	v_mfma_f32_16x16x32_bf16 v[94:97], v[126:129], v[226:229], v[94:97]
	v_mfma_f32_16x16x32_bf16 v[78:81], v[102:105], v[234:237], v[78:81]
	v_mfma_f32_16x16x32_bf16 v[74:77], v[126:129], v[234:237], v[74:77]
	s_setprio 0
	s_setprio 1
	v_mfma_f32_16x16x32_bf16 v[138:141], v[134:137], v[162:165], v[138:141]
	v_mfma_f32_16x16x32_bf16 v[130:133], v[154:157], v[162:165], v[130:133]
	v_mfma_f32_16x16x32_bf16 v[114:117], v[134:137], v[196:199], v[114:117]
	v_mfma_f32_16x16x32_bf16 v[106:109], v[154:157], v[196:199], v[106:109]
	v_mfma_f32_16x16x32_bf16 v[86:89], v[134:137], v[204:207], v[86:89]
	v_mfma_f32_16x16x32_bf16 v[82:85], v[154:157], v[204:207], v[82:85]
	v_mfma_f32_16x16x32_bf16 v[70:73], v[134:137], v[230:233], v[70:73]
	v_mfma_f32_16x16x32_bf16 v[66:69], v[154:157], v[230:233], v[66:69]
	v_mfma_f32_16x16x32_bf16 v[138:141], v[150:153], v[178:181], v[138:141]
	v_mfma_f32_16x16x32_bf16 v[130:133], v[158:161], v[178:181], v[130:133]
	v_mfma_f32_16x16x32_bf16 v[114:117], v[150:153], v[200:203], v[114:117]
	v_mfma_f32_16x16x32_bf16 v[106:109], v[158:161], v[200:203], v[106:109]
	v_mfma_f32_16x16x32_bf16 v[86:89], v[150:153], v[226:229], v[86:89]
	v_mfma_f32_16x16x32_bf16 v[82:85], v[158:161], v[226:229], v[82:85]
	v_mfma_f32_16x16x32_bf16 v[70:73], v[150:153], v[234:237], v[70:73]
	v_mfma_f32_16x16x32_bf16 v[66:69], v[158:161], v[234:237], v[66:69]
	s_setprio 0
	s_barrier
	s_add_i32 s80, s80, s41
	v_lshl_add_u64 v[182:183], s[76:77], 0, v[168:169]
	s_mov_b32 m0, s80
	ds_read_b128 v[162:165], v195 offset:16384
	ds_read_b128 v[178:181], v195 offset:17408
	ds_read_b128 v[196:199], v195 offset:18432
	ds_read_b128 v[200:203], v195 offset:19456
	ds_read_b128 v[204:207], v195 offset:20480
	ds_read_b128 v[226:229], v195 offset:21504
	ds_read_b128 v[230:233], v195 offset:22528
	ds_read_b128 v[234:237], v195 offset:23552
	global_load_lds_dwordx4 v[182:183], off
	s_add_i32 m0, s80, 0x2000
	v_lshl_add_u64 v[208:209], s[76:77], 0, v[172:173]
	s_add_u32 s76, s76, s12
	s_addc_u32 s77, s77, s13
	s_add_i32 s75, s75, s41
	global_load_lds_dwordx4 v[208:209], off
	v_lshl_add_u64 v[212:213], s[76:77], 0, v[168:169]
	s_mov_b32 m0, s75
	v_lshl_add_u64 v[214:215], s[76:77], 0, v[172:173]
	global_load_lds_dwordx4 v[212:213], off
	s_add_i32 m0, s75, 0x2000
	v_lshl_add_u64 v[216:217], s[30:31], 0, v[166:167]
	global_load_lds_dwordx4 v[214:215], off
	s_mov_b32 m0, s42
	v_lshl_add_u64 v[238:239], s[30:31], 0, v[170:171]
	global_load_lds_dwordx4 v[216:217], off
	s_mov_b32 m0, s43
	s_nop 0
	global_load_lds_dwordx4 v[238:239], off
	s_waitcnt vmcnt(8)
	s_waitcnt lgkmcnt(0)
	s_barrier
; #define PG8_STAGE(bufoff, gbase, voff) do { _Pragma("unroll") for (int _i = 0; _i < 2; ++_i) \
;         __builtin_amdgcn_global_load_lds((const unsigned*)((const char*)(gbase) + (voff)[_i]), (PG8_LAS unsigned*)(lds + (bufoff) + ldsw + _i * 8192), 16, 0, 0); } while (0)
; #define PG8_LDA(dst, b, h) do { _Pragma("unroll") for (int m = 0; m < 4; ++m) _Pragma("unroll") for (int k = 0; k < 2; ++k) dst[m][k] = *(const PG8_LAS bf16x8*)(lds + PG8_SA(b, h) + aoff + m * 2048 + k * 1024); } while (0)
; #define PG8_LDB(dst, b, h) do { _Pragma("unroll") for (int n = 0; n < 2; ++n) _Pragma("unroll") for (int k = 0; k < 2; ++k) dst[n][k] = *(const PG8_LAS bf16x8*)(lds + PG8_SB(b, h) + boff + n * 2048 + k * 1024); } while (0)
; #define PG8_MMA(ai, bj, At, Bt) do { __builtin_amdgcn_s_setprio(1); _Pragma("unroll") for (int m = 0; m < 4; ++m) _Pragma("unroll") for (int n = 0; n < 2; ++n) _Pragma("unroll") for (int k = 0; k < 2; ++k) \
;         acc[ai][bj][m][n] = __builtin_amdgcn_mfma_f32_16x16x32_bf16(Bt[n][k], At[m][k], acc[ai][bj][m][n], 0, 0, 0); __builtin_amdgcn_s_setprio(0); } while (0)
; #define PG8_WAIT_V(n) asm volatile("s_waitcnt vmcnt(" #n ")" ::: "memory")
; template <class Epi, class Sched, bool ALIGN_EPI = false, bool SP2 = false>
; __device__ __forceinline__ void gemm_phase(PG8_LAS unsigned char* lds, const Gemm g, const Sched& S, const Epi& E) {
;     ...
;             PG8_LDB(B0, 0, 0); PG8_LDB(B1, 0, 1); PG8_SCHED; PG8_LDA(At, 0, 0); PG8_STAGE(PG8_SA(1, 1), a1 + hstep, voffA);
;             PG8_WAIT_V(8); PG8_WAIT_L(0); PG8_BAR; PG8_MMA(0, 0, At, B0); PG8_MMA(0, 1, At, B1); PG8_BAR; PG8_SCHED;
;             PG8_LDA(At, 0, 1); PG8_STAGE(PG8_SB(0, 0), b2, voffB); PG8_STAGE(PG8_SB(0, 1), b2 + hstep, voffB); PG8_STAGE(PG8_SA(0, 0), a2, voffA);
;             PG8_WAIT_V(8); PG8_WAIT_L(0); PG8_BAR; PG8_MMA(1, 0, At, B0); PG8_MMA(1, 1, At, B1); PG8_BAR; PG8_SCHED;
;             PG8_LDB(B0, 1, 0); PG8_LDB(B1, 1, 1); PG8_SCHED; PG8_LDA(At, 1, 0); PG8_STAGE(PG8_SA(0, 1), a2 + hstep, voffA);
;             PG8_WAIT_V(8); PG8_WAIT_L(0); PG8_BAR; PG8_MMA(0, 0, At, B0); PG8_MMA(0, 1, At, B1); PG8_BAR; PG8_SCHED;
;             PG8_LDA(At, 1, 1); PG8_STAGE(PG8_SB(1, 0), b3, voffB); PG8_STAGE(PG8_SB(1, 1), b3 + hstep, voffB); PG8_STAGE(PG8_SA(1, 0), a3, voffA);
;             PG8_WAIT_V(8); PG8_WAIT_L(0); PG8_BAR; PG8_MMA(1, 0, At, B0); PG8_MMA(1, 1, At, B1); PG8_BAR; PG8_SCHED;
	s_setprio 1
	v_mfma_f32_16x16x32_bf16 v[62:65], v[90:93], v[162:165], v[62:65]
	v_mfma_f32_16x16x32_bf16 v[58:61], v[110:113], v[162:165], v[58:61]
	v_mfma_f32_16x16x32_bf16 v[46:49], v[90:93], v[196:199], v[46:49]
	v_mfma_f32_16x16x32_bf16 v[42:45], v[110:113], v[196:199], v[42:45]
	v_mfma_f32_16x16x32_bf16 v[30:33], v[90:93], v[204:207], v[30:33]
	v_mfma_f32_16x16x32_bf16 v[26:29], v[110:113], v[204:207], v[26:29]
	v_mfma_f32_16x16x32_bf16 v[14:17], v[90:93], v[230:233], v[14:17]
	v_mfma_f32_16x16x32_bf16 v[10:13], v[110:113], v[230:233], v[10:13]
	v_mfma_f32_16x16x32_bf16 v[62:65], v[102:105], v[178:181], v[62:65]
	v_mfma_f32_16x16x32_bf16 v[58:61], v[126:129], v[178:181], v[58:61]
	v_mfma_f32_16x16x32_bf16 v[46:49], v[102:105], v[200:203], v[46:49]
	v_mfma_f32_16x16x32_bf16 v[42:45], v[126:129], v[200:203], v[42:45]
	v_mfma_f32_16x16x32_bf16 v[30:33], v[102:105], v[226:229], v[30:33]
	v_mfma_f32_16x16x32_bf16 v[26:29], v[126:129], v[226:229], v[26:29]
	v_mfma_f32_16x16x32_bf16 v[14:17], v[102:105], v[234:237], v[14:17]
	v_mfma_f32_16x16x32_bf16 v[10:13], v[126:129], v[234:237], v[10:13]
	s_setprio 0
	s_setprio 1
	v_mfma_f32_16x16x32_bf16 v[54:57], v[134:137], v[162:165], v[54:57]
	v_mfma_f32_16x16x32_bf16 v[50:53], v[154:157], v[162:165], v[50:53]
	v_mfma_f32_16x16x32_bf16 v[38:41], v[134:137], v[196:199], v[38:41]
	v_mfma_f32_16x16x32_bf16 v[34:37], v[154:157], v[196:199], v[34:37]
	v_mfma_f32_16x16x32_bf16 v[22:25], v[134:137], v[204:207], v[22:25]
	v_mfma_f32_16x16x32_bf16 v[18:21], v[154:157], v[204:207], v[18:21]
	v_mfma_f32_16x16x32_bf16 v[6:9], v[134:137], v[230:233], v[6:9]
	v_mfma_f32_16x16x32_bf16 v[2:5], v[154:157], v[230:233], v[2:5]
	v_mfma_f32_16x16x32_bf16 v[54:57], v[150:153], v[178:181], v[54:57]
	v_mfma_f32_16x16x32_bf16 v[50:53], v[158:161], v[178:181], v[50:53]
	v_mfma_f32_16x16x32_bf16 v[38:41], v[150:153], v[200:203], v[38:41]
	v_mfma_f32_16x16x32_bf16 v[34:37], v[158:161], v[200:203], v[34:37]
	v_mfma_f32_16x16x32_bf16 v[22:25], v[150:153], v[226:229], v[22:25]
	v_mfma_f32_16x16x32_bf16 v[18:21], v[158:161], v[226:229], v[18:21]
	v_mfma_f32_16x16x32_bf16 v[6:9], v[150:153], v[234:237], v[6:9]
	v_mfma_f32_16x16x32_bf16 v[2:5], v[158:161], v[234:237], v[2:5]
	s_setprio 0
	s_barrier
	s_add_i32 s75, 0, 0x18000
	v_add_u32_e32 v0, s75, v185
	s_add_i32 s76, 0, 0x1c000
	ds_read_b128 v[90:93], v0
	ds_read_b128 v[102:105], v0 offset:1024
	ds_read_b128 v[110:113], v0 offset:2048
	ds_read_b128 v[126:129], v0 offset:3072
	v_add_u32_e32 v0, s76, v185
	ds_read_b128 v[134:137], v0
	ds_read_b128 v[150:153], v0 offset:1024
	ds_read_b128 v[154:157], v0 offset:2048
	ds_read_b128 v[158:161], v0 offset:3072
	s_add_u32 s30, s30, s12
	s_addc_u32 s31, s31, s13
	s_mov_b32 m0, s44
	v_lshl_add_u64 v[240:241], s[30:31], 0, v[166:167]
	ds_read_b128 v[162:165], v195 offset:32768
	ds_read_b128 v[178:181], v195 offset:33792
	ds_read_b128 v[196:199], v195 offset:34816
	ds_read_b128 v[200:203], v195 offset:35840
	ds_read_b128 v[204:207], v195 offset:36864
	ds_read_b128 v[226:229], v195 offset:37888
	ds_read_b128 v[230:233], v195 offset:38912
	ds_read_b128 v[234:237], v195 offset:39936
	global_load_lds_dwordx4 v[240:241], off
	v_lshl_add_u64 v[240:241], s[30:31], 0, v[170:171]
	s_mov_b32 m0, s45
	s_nop 0
	global_load_lds_dwordx4 v[240:241], off
	s_waitcnt vmcnt(8)
	s_waitcnt lgkmcnt(0)
	s_barrier
	s_setprio 1
	v_mfma_f32_16x16x32_bf16 v[146:149], v[90:93], v[162:165], v[146:149]
	v_mfma_f32_16x16x32_bf16 v[142:145], v[110:113], v[162:165], v[142:145]
	v_mfma_f32_16x16x32_bf16 v[122:125], v[90:93], v[196:199], v[122:125]
	v_mfma_f32_16x16x32_bf16 v[118:121], v[110:113], v[196:199], v[118:121]
	v_mfma_f32_16x16x32_bf16 v[98:101], v[90:93], v[204:207], v[98:101]
	v_mfma_f32_16x16x32_bf16 v[94:97], v[110:113], v[204:207], v[94:97]
	v_mfma_f32_16x16x32_bf16 v[78:81], v[90:93], v[230:233], v[78:81]
	v_mfma_f32_16x16x32_bf16 v[74:77], v[110:113], v[230:233], v[74:77]
	v_mfma_f32_16x16x32_bf16 v[146:149], v[102:105], v[178:181], v[146:149]
	v_mfma_f32_16x16x32_bf16 v[142:145], v[126:129], v[178:181], v[142:145]
	v_mfma_f32_16x16x32_bf16 v[122:125], v[102:105], v[200:203], v[122:125]
	v_mfma_f32_16x16x32_bf16 v[118:121], v[126:129], v[200:203], v[118:121]
	v_mfma_f32_16x16x32_bf16 v[98:101], v[102:105], v[226:229], v[98:101]
	v_mfma_f32_16x16x32_bf16 v[94:97], v[126:129], v[226:229], v[94:97]
	v_mfma_f32_16x16x32_bf16 v[78:81], v[102:105], v[234:237], v[78:81]
	v_mfma_f32_16x16x32_bf16 v[74:77], v[126:129], v[234:237], v[74:77]
	s_setprio 0
	s_setprio 1
	v_mfma_f32_16x16x32_bf16 v[138:141], v[134:137], v[162:165], v[138:141]
	v_mfma_f32_16x16x32_bf16 v[130:133], v[154:157], v[162:165], v[130:133]
	v_mfma_f32_16x16x32_bf16 v[114:117], v[134:137], v[196:199], v[114:117]
	v_mfma_f32_16x16x32_bf16 v[106:109], v[154:157], v[196:199], v[106:109]
	v_mfma_f32_16x16x32_bf16 v[86:89], v[134:137], v[204:207], v[86:89]
	v_mfma_f32_16x16x32_bf16 v[82:85], v[154:157], v[204:207], v[82:85]
	v_mfma_f32_16x16x32_bf16 v[70:73], v[134:137], v[230:233], v[70:73]
	v_mfma_f32_16x16x32_bf16 v[66:69], v[154:157], v[230:233], v[66:69]
	v_mfma_f32_16x16x32_bf16 v[138:141], v[150:153], v[178:181], v[138:141]
	v_mfma_f32_16x16x32_bf16 v[130:133], v[158:161], v[178:181], v[130:133]
	v_mfma_f32_16x16x32_bf16 v[114:117], v[150:153], v[200:203], v[114:117]
	v_mfma_f32_16x16x32_bf16 v[106:109], v[158:161], v[200:203], v[106:109]
	v_mfma_f32_16x16x32_bf16 v[86:89], v[150:153], v[226:229], v[86:89]
	v_mfma_f32_16x16x32_bf16 v[82:85], v[158:161], v[226:229], v[82:85]
	v_mfma_f32_16x16x32_bf16 v[70:73], v[150:153], v[234:237], v[70:73]
	v_mfma_f32_16x16x32_bf16 v[66:69], v[158:161], v[234:237], v[66:69]
	s_setprio 0
	s_barrier
; #define PG8_STAGE(bufoff, gbase, voff) do { _Pragma("unroll") for (int _i = 0; _i < 2; ++_i) \
;         __builtin_amdgcn_global_load_lds((const unsigned*)((const char*)(gbase) + (voff)[_i]), (PG8_LAS unsigned*)(lds + (bufoff) + ldsw + _i * 8192), 16, 0, 0); } while (0)
; #define PG8_LDA(dst, b, h) do { _Pragma("unroll") for (int m = 0; m < 4; ++m) _Pragma("unroll") for (int k = 0; k < 2; ++k) dst[m][k] = *(const PG8_LAS bf16x8*)(lds + PG8_SA(b, h) + aoff + m * 2048 + k * 1024); } while (0)
; #define PG8_LDB(dst, b, h) do { _Pragma("unroll") for (int n = 0; n < 2; ++n) _Pragma("unroll") for (int k = 0; k < 2; ++k) dst[n][k] = *(const PG8_LAS bf16x8*)(lds + PG8_SB(b, h) + boff + n * 2048 + k * 1024); } while (0)
; #define PG8_MMA(ai, bj, At, Bt) do { __builtin_amdgcn_s_setprio(1); _Pragma("unroll") for (int m = 0; m < 4; ++m) _Pragma("unroll") for (int n = 0; n < 2; ++n) _Pragma("unroll") for (int k = 0; k < 2; ++k) \
;         acc[ai][bj][m][n] = __builtin_amdgcn_mfma_f32_16x16x32_bf16(Bt[n][k], At[m][k], acc[ai][bj][m][n], 0, 0, 0); __builtin_amdgcn_s_setprio(0); } while (0)
; #define PG8_WAIT_V(n) asm volatile("s_waitcnt vmcnt(" #n ")" ::: "memory")
; template <class Epi, class Sched, bool ALIGN_EPI = false, bool SP2 = false>
; __device__ __forceinline__ void gemm_phase(PG8_LAS unsigned char* lds, const Gemm g, const Sched& S, const Epi& E) {
;     ...
;             PG8_LDB(B0, 0, 0); PG8_LDB(B1, 0, 1); PG8_SCHED; PG8_LDA(At, 0, 0); PG8_STAGE(PG8_SA(1, 1), a1 + hstep, voffA);
;             PG8_WAIT_V(8); PG8_WAIT_L(0); PG8_BAR; PG8_MMA(0, 0, At, B0); PG8_MMA(0, 1, At, B1); PG8_BAR; PG8_SCHED;
;             PG8_LDA(At, 0, 1); PG8_STAGE(PG8_SB(0, 0), b2, voffB); PG8_STAGE(PG8_SB(0, 1), b2 + hstep, voffB); PG8_STAGE(PG8_SA(0, 0), a2, voffA);
;             PG8_WAIT_V(8); PG8_WAIT_L(0); PG8_BAR; PG8_MMA(1, 0, At, B0); PG8_MMA(1, 1, At, B1); PG8_BAR; PG8_SCHED;
;             PG8_LDB(B0, 1, 0); PG8_LDB(B1, 1, 1); PG8_SCHED; PG8_LDA(At, 1, 0); PG8_STAGE(PG8_SA(0, 1), a2 + hstep, voffA);
;             PG8_WAIT_V(8); PG8_WAIT_L(0); PG8_BAR; PG8_MMA(0, 0, At, B0); PG8_MMA(0, 1, At, B1); PG8_BAR; PG8_SCHED;
;             PG8_LDA(At, 1, 1); PG8_STAGE(PG8_SB(1, 0), b3, voffB); PG8_STAGE(PG8_SB(1, 1), b3 + hstep, voffB); PG8_STAGE(PG8_SA(1, 0), a3, voffA);
;             PG8_WAIT_V(8); PG8_WAIT_L(0); PG8_BAR; PG8_MMA(1, 0, At, B0); PG8_MMA(1, 1, At, B1); PG8_BAR; PG8_SCHED;
	s_add_i32 s30, s75, s41
	v_lshl_add_u64 v[182:183], v[182:183], 0, s[38:39]
	s_mov_b32 m0, s30
	ds_read_b128 v[162:165], v195 offset:49152
	ds_read_b128 v[178:181], v195 offset:50176
	ds_read_b128 v[196:199], v195 offset:51200
	ds_read_b128 v[200:203], v195 offset:52224
	ds_read_b128 v[204:207], v195 offset:53248
	ds_read_b128 v[226:229], v195 offset:54272
	ds_read_b128 v[230:233], v195 offset:55296
	ds_read_b128 v[234:237], v195 offset:56320
	global_load_lds_dwordx4 v[182:183], off
	v_lshl_add_u64 v[182:183], v[208:209], 0, s[38:39]
	s_add_i32 m0, s30, 0x2000
	s_add_i32 s30, s76, s41
	global_load_lds_dwordx4 v[182:183], off
	v_lshl_add_u64 v[182:183], v[212:213], 0, s[38:39]
	s_mov_b32 m0, s30
	s_nop 0
	global_load_lds_dwordx4 v[182:183], off
	v_lshl_add_u64 v[182:183], v[214:215], 0, s[38:39]
	s_add_i32 m0, s30, 0x2000
	s_nop 0
	global_load_lds_dwordx4 v[182:183], off
	v_lshl_add_u64 v[182:183], v[216:217], 0, s[38:39]
	s_mov_b32 m0, s47
	s_nop 0
	global_load_lds_dwordx4 v[182:183], off
	v_lshl_add_u64 v[182:183], v[238:239], 0, s[38:39]
	s_mov_b32 m0, s48
	s_nop 0
	global_load_lds_dwordx4 v[182:183], off
	s_waitcnt vmcnt(8)
	s_waitcnt lgkmcnt(0)
	s_barrier
	s_setprio 1
	v_mfma_f32_16x16x32_bf16 v[62:65], v[90:93], v[162:165], v[62:65]
	v_mfma_f32_16x16x32_bf16 v[58:61], v[110:113], v[162:165], v[58:61]
	v_mfma_f32_16x16x32_bf16 v[46:49], v[90:93], v[196:199], v[46:49]
	v_mfma_f32_16x16x32_bf16 v[42:45], v[110:113], v[196:199], v[42:45]
	v_mfma_f32_16x16x32_bf16 v[30:33], v[90:93], v[204:207], v[30:33]
	v_mfma_f32_16x16x32_bf16 v[26:29], v[110:113], v[204:207], v[26:29]
	v_mfma_f32_16x16x32_bf16 v[14:17], v[90:93], v[230:233], v[14:17]
	v_mfma_f32_16x16x32_bf16 v[10:13], v[110:113], v[230:233], v[10:13]
	v_mfma_f32_16x16x32_bf16 v[62:65], v[102:105], v[178:181], v[62:65]
	v_mfma_f32_16x16x32_bf16 v[58:61], v[126:129], v[178:181], v[58:61]
	v_mfma_f32_16x16x32_bf16 v[46:49], v[102:105], v[200:203], v[46:49]
	v_mfma_f32_16x16x32_bf16 v[42:45], v[126:129], v[200:203], v[42:45]
	v_mfma_f32_16x16x32_bf16 v[30:33], v[102:105], v[226:229], v[30:33]
	v_mfma_f32_16x16x32_bf16 v[26:29], v[126:129], v[226:229], v[26:29]
	v_mfma_f32_16x16x32_bf16 v[14:17], v[102:105], v[234:237], v[14:17]
	v_mfma_f32_16x16x32_bf16 v[10:13], v[126:129], v[234:237], v[10:13]
	s_setprio 0
	s_setprio 1
	v_mfma_f32_16x16x32_bf16 v[54:57], v[134:137], v[162:165], v[54:57]
	v_mfma_f32_16x16x32_bf16 v[50:53], v[154:157], v[162:165], v[50:53]
	v_mfma_f32_16x16x32_bf16 v[38:41], v[134:137], v[196:199], v[38:41]
	v_mfma_f32_16x16x32_bf16 v[34:37], v[154:157], v[196:199], v[34:37]
	v_mfma_f32_16x16x32_bf16 v[22:25], v[134:137], v[204:207], v[22:25]
	v_mfma_f32_16x16x32_bf16 v[18:21], v[154:157], v[204:207], v[18:21]
	v_mfma_f32_16x16x32_bf16 v[6:9], v[134:137], v[230:233], v[6:9]
	v_mfma_f32_16x16x32_bf16 v[2:5], v[154:157], v[230:233], v[2:5]
	v_mfma_f32_16x16x32_bf16 v[54:57], v[150:153], v[178:181], v[54:57]
	v_mfma_f32_16x16x32_bf16 v[50:53], v[158:161], v[178:181], v[50:53]
	v_mfma_f32_16x16x32_bf16 v[38:41], v[150:153], v[200:203], v[38:41]
	v_mfma_f32_16x16x32_bf16 v[34:37], v[158:161], v[200:203], v[34:37]
	v_mfma_f32_16x16x32_bf16 v[22:25], v[150:153], v[226:229], v[22:25]
	v_mfma_f32_16x16x32_bf16 v[18:21], v[158:161], v[226:229], v[18:21]
	v_mfma_f32_16x16x32_bf16 v[6:9], v[150:153], v[234:237], v[6:9]
	v_mfma_f32_16x16x32_bf16 v[2:5], v[158:161], v[234:237], v[2:5]
	s_setprio 0
	s_barrier
	s_add_u32 s61, s61, 0x100
	s_addc_u32 s67, s67, 0
	s_add_u32 s28, s28, 0x100
	s_addc_u32 s29, s29, 0
	s_cmp_ge_i32 s74, s46
	s_mov_b32 s30, s74
	s_cbranch_scc0 .LBB0_821
	s_mov_b64 s[76:77], 0x28000

; __device__ __forceinline__ unsigned cvt_pk_bf16(float lo, float hi) { unsigned r; asm volatile("v_cvt_pk_bf16_f32 %0, %1, %2" : "=v"(r) : "v"(lo), "v"(hi)); return r; }
; __device__ __forceinline__ float fast_sigmoid(float x) { return __builtin_amdgcn_rcpf(1.0f + __expf(-x)); }
;     __device__ __forceinline__ void operator()(const f32x4 (&acc)[2][2][4][2], const Unit& u, int wr, int wc, int fr, int fq, PG8_LAS unsigned char* ldsb) const {
;     ...
;         for (int ai = 0; ai < 2; ++ai) {
;             u32x4 zv[4][2];
; #pragma unroll
;             for (int m = 0; m < 4; ++m)
; #pragma unroll
;                 for (int bj = 0; bj < 2; ++bj) zv[m][bj] = *(const u32x4*)(Zs + ((unsigned)(row0 + ai * HALF + m * 16) * 512u + (unsigned)(col0 + bj * HALF)));
; #pragma unroll
;             for (int m = 0; m < 4; ++m) {
;                 const int row = row0 + ai * HALF + m * 16;
; #pragma unroll
;                 for (int bj = 0; bj < 2; ++bj) {
;                     const int c = col0 + bj * HALF;
;                     const u32x4 zw = zv[m][bj];
;                     float v[8];
; #pragma unroll
;                     for (int n = 0; n < 2; ++n)
; #pragma unroll
;                         for (int i = 0; i < 4; ++i) { const int e = n * 4 + i; const unsigned wd = zw[e >> 1];
;                             const float z = __uint_as_float((e & 1) ? (wd & 0xffff0000u) : (wd << 16));
;                             v[e] = z * fast_sigmoid(acc[ai][bj][m][n][i] + bias[c + e]); }
;                     u32x4 w; w.x = cvt_pk_bf16(v[0], v[1]); w.y = cvt_pk_bf16(v[2], v[3]); w.z = cvt_pk_bf16(v[4], v[5]); w.w = cvt_pk_bf16(v[6], v[7]);
;                     *(u32x4*)(O + (size_t)row * ldo + c) = w;
;                 }
.LBB0_825:
	v_lshl_add_u32 v180, s1, 8, v184
	v_lshl_or_b32 v182, s56, 8, v194
	v_lshl_add_u32 v0, v180, 9, v182
	v_lshl_add_u64 v[90:91], v[0:1], 1, s[6:7]
	global_load_dwordx4 v[158:161], v[90:91], off
	v_or_b32_e32 v90, 0x80, v0
	v_mov_b32_e32 v91, v1
	v_lshl_add_u64 v[90:91], v[90:91], 1, s[6:7]
	global_load_dwordx4 v[154:157], v[90:91], off
	v_add_u32_e32 v90, 0x2000, v0
	v_mov_b32_e32 v91, v1
	v_lshl_add_u64 v[90:91], v[90:91], 1, s[6:7]
	global_load_dwordx4 v[150:153], v[90:91], off
	v_add_u32_e32 v90, 0x2080, v0
	v_mov_b32_e32 v91, v1
	v_lshl_add_u64 v[90:91], v[90:91], 1, s[6:7]
	global_load_dwordx4 v[134:137], v[90:91], off
	v_add_u32_e32 v90, 0x4000, v0
	v_mov_b32_e32 v91, v1
	v_lshl_add_u64 v[90:91], v[90:91], 1, s[6:7]
	global_load_dwordx4 v[126:129], v[90:91], off
	v_add_u32_e32 v90, 0x4080, v0
	v_mov_b32_e32 v91, v1
	v_lshl_add_u64 v[90:91], v[90:91], 1, s[6:7]
	global_load_dwordx4 v[110:113], v[90:91], off
	v_add_u32_e32 v90, 0x6000, v0
	v_mov_b32_e32 v91, v1
	v_lshl_add_u64 v[90:91], v[90:91], 1, s[6:7]
	global_load_dwordx4 v[102:105], v[90:91], off
	v_add_u32_e32 v90, 0x6080, v0
	v_mov_b32_e32 v91, v1
	v_ashrrev_i32_e32 v183, 31, v182
	v_lshl_add_u64 v[90:91], v[90:91], 1, s[6:7]
	v_lshl_add_u64 v[178:179], v[182:183], 2, s[20:21]
	global_load_dwordx4 v[90:93], v[90:91], off
	s_nop 0
	global_load_dwordx4 v[162:165], v[178:179], off offset:16
	global_load_dwordx4 v[196:199], v[178:179], off
	v_ashrrev_i32_e32 v181, 31, v180
	s_mov_b32 s1, 0x48000
	s_mov_b64 s[28:29], 0x48000
	s_waitcnt vmcnt(0) lgkmcnt(0)
	v_lshlrev_b32_e32 v200, 16, v158
	v_and_b32_e32 v158, 0xffff0000, v158
	v_add_f32_e32 v142, v142, v162
	v_add_f32_e32 v147, v147, v197
	v_mul_f32_e32 v147, 0xbfb8aa3b, v147
	v_add_f32_e32 v148, v148, v198
	v_exp_f32_e32 v147, v147
	v_mul_f32_e32 v148, 0xbfb8aa3b, v148
	v_add_f32_e32 v149, v149, v199
	v_exp_f32_e32 v148, v148
	v_mul_f32_e32 v149, 0xbfb8aa3b, v149
	v_exp_f32_e32 v149, v149
	v_mul_f32_e32 v142, 0xbfb8aa3b, v142
	v_add_f32_e32 v143, v143, v163
	v_exp_f32_e32 v142, v142
	v_mul_f32_e32 v143, 0xbfb8aa3b, v143
	v_add_f32_e32 v147, 1.0, v147
	v_exp_f32_e32 v143, v143
	v_rcp_f32_e32 v147, v147
	v_add_f32_e32 v148, 1.0, v148
	v_rcp_f32_e32 v148, v148
	v_add_f32_e32 v149, 1.0, v149
	v_rcp_f32_e32 v149, v149
	v_add_f32_e32 v142, 1.0, v142
	v_rcp_f32_e32 v142, v142
	v_add_f32_e32 v143, 1.0, v143
	v_mul_f32_e32 v147, v147, v158
	v_lshlrev_b32_e32 v158, 16, v159
	v_rcp_f32_e32 v143, v143
	v_mul_f32_e32 v148, v148, v158
	v_and_b32_e32 v158, 0xffff0000, v159
	v_mul_f32_e32 v149, v149, v158
	v_lshlrev_b32_e32 v158, 16, v160
	v_mul_f32_e32 v158, v142, v158
	v_and_b32_e32 v142, 0xffff0000, v160
	v_mul_f32_e32 v159, v143, v142
	v_add_f32_e32 v143, v144, v164
	v_mul_f32_e32 v143, 0xbfb8aa3b, v143
	v_exp_f32_e32 v143, v143
	v_add_f32_e32 v146, v146, v196
	v_lshlrev_b32_e32 v142, 16, v161
	v_mul_f32_e32 v146, 0xbfb8aa3b, v146
	v_add_f32_e32 v143, 1.0, v143
	v_rcp_f32_e32 v143, v143
	v_exp_f32_e32 v146, v146
	v_lshlrev_b32_e32 v162, 16, v154
	v_and_b32_e32 v154, 0xffff0000, v154
	v_mul_f32_e32 v160, v143, v142
	v_add_f32_e32 v143, v145, v165
	v_mul_f32_e32 v143, 0xbfb8aa3b, v143
	v_exp_f32_e32 v143, v143
	v_add_f32_e32 v146, 1.0, v146
	v_rcp_f32_e32 v146, v146
	v_and_b32_e32 v142, 0xffff0000, v161
	v_add_f32_e32 v143, 1.0, v143
	v_rcp_f32_e32 v143, v143
	v_mul_f32_e32 v146, v146, v200
	v_mul_f32_e32 v145, v143, v142
	v_cvt_pk_bf16_f32 v142, v146, v147
	v_lshlrev_b64 v[146:147], 11, v[180:181]
	v_cvt_pk_bf16_f32 v143, v148, v149
	v_lshl_add_u64 v[146:147], s[18:19], 0, v[146:147]
	v_lshlrev_b64 v[148:149], 1, v[182:183]
	v_lshl_add_u64 v[146:147], v[146:147], 0, v[148:149]
	v_cvt_pk_bf16_f32 v144, v158, v159
	v_cvt_pk_bf16_f32 v145, v160, v145
	global_store_dwordx4 v[146:147], v[142:145], off
	global_load_dwordx4 v[142:145], v[178:179], off offset:528
	s_nop 0
	global_load_dwordx4 v[158:161], v[178:179], off offset:512
	s_waitcnt vmcnt(0)
	v_add_f32_e32 v130, v130, v142
	v_add_f32_e32 v139, v139, v159
	v_mul_f32_e32 v139, 0xbfb8aa3b, v139
	v_add_f32_e32 v140, v140, v160
	v_exp_f32_e32 v139, v139
	v_mul_f32_e32 v140, 0xbfb8aa3b, v140
	v_add_f32_e32 v141, v141, v161
	v_exp_f32_e32 v140, v140
	v_mul_f32_e32 v141, 0xbfb8aa3b, v141
	v_exp_f32_e32 v141, v141
	v_mul_f32_e32 v130, 0xbfb8aa3b, v130
	v_add_f32_e32 v131, v131, v143
	v_exp_f32_e32 v130, v130
	v_mul_f32_e32 v131, 0xbfb8aa3b, v131
	v_add_f32_e32 v139, 1.0, v139
	v_exp_f32_e32 v131, v131
	v_rcp_f32_e32 v139, v139
	v_add_f32_e32 v140, 1.0, v140
	v_rcp_f32_e32 v140, v140
	v_add_f32_e32 v141, 1.0, v141
	v_rcp_f32_e32 v141, v141
	v_add_f32_e32 v130, 1.0, v130
	v_rcp_f32_e32 v130, v130
	v_add_f32_e32 v131, 1.0, v131
	v_mul_f32_e32 v139, v139, v154
	v_lshlrev_b32_e32 v154, 16, v155
	v_rcp_f32_e32 v131, v131
	v_mul_f32_e32 v140, v140, v154
	v_and_b32_e32 v154, 0xffff0000, v155
	v_mul_f32_e32 v141, v141, v154
	v_lshlrev_b32_e32 v154, 16, v156
	v_mul_f32_e32 v142, v130, v154
	v_and_b32_e32 v130, 0xffff0000, v156
	v_mul_f32_e32 v143, v131, v130
	v_add_f32_e32 v131, v132, v144
	v_mul_f32_e32 v131, 0xbfb8aa3b, v131
	v_exp_f32_e32 v131, v131
	v_lshlrev_b32_e32 v130, 16, v157
	v_add_f32_e32 v138, v138, v158
	v_mul_f32_e32 v138, 0xbfb8aa3b, v138
	v_add_f32_e32 v131, 1.0, v131
	v_rcp_f32_e32 v131, v131
	v_exp_f32_e32 v138, v138
	v_mul_f32_e32 v144, v131, v130
	v_add_f32_e32 v131, v133, v145
	v_mul_f32_e32 v131, 0xbfb8aa3b, v131
	v_exp_f32_e32 v131, v131
	v_add_f32_e32 v138, 1.0, v138
	v_rcp_f32_e32 v138, v138
	v_and_b32_e32 v130, 0xffff0000, v157
	v_add_f32_e32 v131, 1.0, v131
	v_rcp_f32_e32 v131, v131
	v_mul_f32_e32 v138, v138, v162
	v_mul_f32_e32 v133, v131, v130
	v_cvt_pk_bf16_f32 v130, v138, v139
	v_cvt_pk_bf16_f32 v131, v140, v141
	v_cvt_pk_bf16_f32 v132, v142, v143
	v_cvt_pk_bf16_f32 v133, v144, v133
	global_store_dwordx4 v[146:147], v[130:133], off offset:256
	global_load_dwordx4 v[138:141], v[178:179], off offset:16
	global_load_dwordx4 v[142:145], v[178:179], off
	v_lshlrev_b32_e32 v132, 16, v150
	v_or_b32_e32 v130, 16, v180
	v_ashrrev_i32_e32 v131, 31, v130
	s_waitcnt vmcnt(0)
; __device__ __forceinline__ unsigned cvt_pk_bf16(float lo, float hi) { unsigned r; asm volatile("v_cvt_pk_bf16_f32 %0, %1, %2" : "=v"(r) : "v"(lo), "v"(hi)); return r; }
; __device__ __forceinline__ float fast_sigmoid(float x) { return __builtin_amdgcn_rcpf(1.0f + __expf(-x)); }
;     __device__ __forceinline__ void operator()(const f32x4 (&acc)[2][2][4][2], const Unit& u, int wr, int wc, int fr, int fq, PG8_LAS unsigned char* ldsb) const {
;     ...
;         for (int ai = 0; ai < 2; ++ai) {
;             u32x4 zv[4][2];
; #pragma unroll
;             for (int m = 0; m < 4; ++m)
; #pragma unroll
;                 for (int bj = 0; bj < 2; ++bj) zv[m][bj] = *(const u32x4*)(Zs + ((unsigned)(row0 + ai * HALF + m * 16) * 512u + (unsigned)(col0 + bj * HALF)));
; #pragma unroll
;             for (int m = 0; m < 4; ++m) {
;                 const int row = row0 + ai * HALF + m * 16;
; #pragma unroll
;                 for (int bj = 0; bj < 2; ++bj) {
;                     const int c = col0 + bj * HALF;
;                     const u32x4 zw = zv[m][bj];
;                     float v[8];
; #pragma unroll
;                     for (int n = 0; n < 2; ++n)
; #pragma unroll
;                         for (int i = 0; i < 4; ++i) { const int e = n * 4 + i; const unsigned wd = zw[e >> 1];
;                             const float z = __uint_as_float((e & 1) ? (wd & 0xffff0000u) : (wd << 16));
;                             v[e] = z * fast_sigmoid(acc[ai][bj][m][n][i] + bias[c + e]); }
;                     u32x4 w; w.x = cvt_pk_bf16(v[0], v[1]); w.y = cvt_pk_bf16(v[2], v[3]); w.z = cvt_pk_bf16(v[4], v[5]); w.w = cvt_pk_bf16(v[6], v[7]);
;                     *(u32x4*)(O + (size_t)row * ldo + c) = w;
;                 }
	v_add_f32_e32 v118, v118, v138
	v_add_f32_e32 v122, v122, v142
	v_mul_f32_e32 v122, 0xbfb8aa3b, v122
	v_add_f32_e32 v123, v123, v143
	v_exp_f32_e32 v122, v122
	v_mul_f32_e32 v123, 0xbfb8aa3b, v123
	v_add_f32_e32 v124, v124, v144
	v_exp_f32_e32 v123, v123
	v_mul_f32_e32 v124, 0xbfb8aa3b, v124
	v_add_f32_e32 v125, v125, v145
	v_exp_f32_e32 v124, v124
	v_mul_f32_e32 v125, 0xbfb8aa3b, v125
	v_exp_f32_e32 v125, v125
	v_mul_f32_e32 v118, 0xbfb8aa3b, v118
	v_add_f32_e32 v119, v119, v139
	v_add_f32_e32 v122, 1.0, v122
	v_exp_f32_e32 v118, v118
	v_mul_f32_e32 v119, 0xbfb8aa3b, v119
	v_rcp_f32_e32 v122, v122
	v_add_f32_e32 v123, 1.0, v123
	v_exp_f32_e32 v119, v119
	v_rcp_f32_e32 v123, v123
	v_add_f32_e32 v124, 1.0, v124
	v_rcp_f32_e32 v124, v124
	v_add_f32_e32 v125, 1.0, v125
	v_rcp_f32_e32 v125, v125
	v_add_f32_e32 v118, 1.0, v118
	v_mul_f32_e32 v122, v122, v132
	v_and_b32_e32 v132, 0xffff0000, v150
	v_rcp_f32_e32 v118, v118
	v_add_f32_e32 v119, 1.0, v119
	v_mul_f32_e32 v123, v123, v132
	v_lshlrev_b32_e32 v132, 16, v151
	v_rcp_f32_e32 v119, v119
	v_mul_f32_e32 v124, v124, v132
	v_and_b32_e32 v132, 0xffff0000, v151
	v_mul_f32_e32 v125, v125, v132
	v_lshlrev_b32_e32 v132, 16, v152
	v_mul_f32_e32 v132, v118, v132
	v_and_b32_e32 v118, 0xffff0000, v152
	v_mul_f32_e32 v133, v119, v118
	v_add_f32_e32 v119, v120, v140
	v_mul_f32_e32 v119, 0xbfb8aa3b, v119
	v_exp_f32_e32 v119, v119
	v_lshlrev_b32_e32 v118, 16, v153
	v_add_f32_e32 v119, 1.0, v119
	v_rcp_f32_e32 v119, v119
	s_nop 0
	v_mul_f32_e32 v138, v119, v118
	v_add_f32_e32 v119, v121, v141
	v_mul_f32_e32 v119, 0xbfb8aa3b, v119
	v_exp_f32_e32 v119, v119
	v_and_b32_e32 v118, 0xffff0000, v153
	v_add_f32_e32 v119, 1.0, v119
	v_rcp_f32_e32 v119, v119
	s_nop 0
	v_mul_f32_e32 v121, v119, v118
	v_cvt_pk_bf16_f32 v118, v122, v123
	v_lshlrev_b64 v[122:123], 11, v[130:131]
	v_lshl_add_u64 v[122:123], s[18:19], 0, v[122:123]
	v_lshl_add_u64 v[122:123], v[122:123], 0, v[148:149]
	v_cvt_pk_bf16_f32 v119, v124, v125
	v_cvt_pk_bf16_f32 v120, v132, v133
	v_cvt_pk_bf16_f32 v121, v138, v121
	global_store_dwordx4 v[122:123], v[118:121], off
	global_load_dwordx4 v[118:121], v[178:179], off offset:528
	s_nop 0
	global_load_dwordx4 v[130:133], v[178:179], off offset:512
	v_lshlrev_b32_e32 v124, 16, v134
	s_waitcnt vmcnt(0)
	v_add_f32_e32 v106, v106, v118
	v_add_f32_e32 v114, v114, v130
	v_mul_f32_e32 v114, 0xbfb8aa3b, v114
	v_add_f32_e32 v115, v115, v131
	v_exp_f32_e32 v114, v114
	v_mul_f32_e32 v115, 0xbfb8aa3b, v115
	v_add_f32_e32 v116, v116, v132
	v_exp_f32_e32 v115, v115
	v_mul_f32_e32 v116, 0xbfb8aa3b, v116
	v_add_f32_e32 v117, v117, v133
	v_exp_f32_e32 v116, v116
	v_mul_f32_e32 v117, 0xbfb8aa3b, v117
	v_exp_f32_e32 v117, v117
	v_mul_f32_e32 v106, 0xbfb8aa3b, v106
	v_add_f32_e32 v107, v107, v119
	v_add_f32_e32 v114, 1.0, v114
	v_exp_f32_e32 v106, v106
	v_mul_f32_e32 v107, 0xbfb8aa3b, v107
	v_rcp_f32_e32 v114, v114
	v_add_f32_e32 v115, 1.0, v115
	v_exp_f32_e32 v107, v107
	v_rcp_f32_e32 v115, v115
	v_add_f32_e32 v116, 1.0, v116
	v_rcp_f32_e32 v116, v116
	v_add_f32_e32 v117, 1.0, v117
	v_rcp_f32_e32 v117, v117
	v_add_f32_e32 v106, 1.0, v106
	v_mul_f32_e32 v114, v114, v124
	v_and_b32_e32 v124, 0xffff0000, v134
	v_rcp_f32_e32 v106, v106
	v_add_f32_e32 v107, 1.0, v107
	v_mul_f32_e32 v115, v115, v124
	v_lshlrev_b32_e32 v124, 16, v135
	v_rcp_f32_e32 v107, v107
	v_mul_f32_e32 v116, v116, v124
	v_and_b32_e32 v124, 0xffff0000, v135
	v_mul_f32_e32 v117, v117, v124
	v_lshlrev_b32_e32 v124, 16, v136
	v_mul_f32_e32 v118, v106, v124
	v_and_b32_e32 v106, 0xffff0000, v136
	v_mul_f32_e32 v119, v107, v106
	v_add_f32_e32 v107, v108, v120
	v_mul_f32_e32 v107, 0xbfb8aa3b, v107
	v_exp_f32_e32 v107, v107
	v_lshlrev_b32_e32 v106, 16, v137
	v_add_f32_e32 v107, 1.0, v107
	v_rcp_f32_e32 v107, v107
	s_nop 0
	v_mul_f32_e32 v120, v107, v106
	v_add_f32_e32 v107, v109, v121
	v_mul_f32_e32 v107, 0xbfb8aa3b, v107
	v_exp_f32_e32 v107, v107
	v_and_b32_e32 v106, 0xffff0000, v137
	v_add_f32_e32 v107, 1.0, v107
	v_rcp_f32_e32 v107, v107
	s_nop 0
	v_mul_f32_e32 v109, v107, v106
	v_cvt_pk_bf16_f32 v106, v114, v115
	v_cvt_pk_bf16_f32 v107, v116, v117
	v_cvt_pk_bf16_f32 v108, v118, v119
	v_cvt_pk_bf16_f32 v109, v120, v109
	global_store_dwordx4 v[122:123], v[106:109], off offset:256
	global_load_dwordx4 v[114:117], v[178:179], off offset:16
	global_load_dwordx4 v[118:121], v[178:179], off
	v_lshlrev_b32_e32 v108, 16, v126
	v_or_b32_e32 v106, 32, v180
	v_ashrrev_i32_e32 v107, 31, v106
	s_waitcnt vmcnt(0)
	v_add_f32_e32 v94, v94, v114
	v_add_f32_e32 v98, v98, v118
	v_mul_f32_e32 v98, 0xbfb8aa3b, v98
	v_add_f32_e32 v99, v99, v119
	v_exp_f32_e32 v98, v98
	v_mul_f32_e32 v99, 0xbfb8aa3b, v99
	v_add_f32_e32 v100, v100, v120
	v_exp_f32_e32 v99, v99
	v_mul_f32_e32 v100, 0xbfb8aa3b, v100
	v_add_f32_e32 v101, v101, v121
	v_exp_f32_e32 v100, v100
	v_mul_f32_e32 v101, 0xbfb8aa3b, v101
	v_exp_f32_e32 v101, v101
	v_mul_f32_e32 v94, 0xbfb8aa3b, v94
	v_add_f32_e32 v95, v95, v115
	v_add_f32_e32 v98, 1.0, v98
	v_exp_f32_e32 v94, v94
	v_mul_f32_e32 v95, 0xbfb8aa3b, v95
	v_rcp_f32_e32 v98, v98
	v_add_f32_e32 v99, 1.0, v99
	v_exp_f32_e32 v95, v95
	v_rcp_f32_e32 v99, v99
	v_add_f32_e32 v100, 1.0, v100
	v_rcp_f32_e32 v100, v100
	v_add_f32_e32 v101, 1.0, v101
	v_rcp_f32_e32 v101, v101
	v_add_f32_e32 v94, 1.0, v94
	v_mul_f32_e32 v98, v98, v108
	v_and_b32_e32 v108, 0xffff0000, v126
	v_rcp_f32_e32 v94, v94
	v_add_f32_e32 v95, 1.0, v95
	v_mul_f32_e32 v99, v99, v108
	v_lshlrev_b32_e32 v108, 16, v127
	v_rcp_f32_e32 v95, v95
	v_mul_f32_e32 v100, v100, v108
	v_and_b32_e32 v108, 0xffff0000, v127
	v_mul_f32_e32 v101, v101, v108
	v_lshlrev_b32_e32 v108, 16, v128
	v_mul_f32_e32 v108, v94, v108
	v_and_b32_e32 v94, 0xffff0000, v128
	v_mul_f32_e32 v109, v95, v94
	v_add_f32_e32 v95, v96, v116
	v_mul_f32_e32 v95, 0xbfb8aa3b, v95
	v_exp_f32_e32 v95, v95
	v_lshlrev_b32_e32 v94, 16, v129
	v_add_f32_e32 v95, 1.0, v95
	v_rcp_f32_e32 v95, v95
	s_nop 0
	v_mul_f32_e32 v114, v95, v94
	v_add_f32_e32 v95, v97, v117
	v_mul_f32_e32 v95, 0xbfb8aa3b, v95
	v_exp_f32_e32 v95, v95
	v_and_b32_e32 v94, 0xffff0000, v129
	v_add_f32_e32 v95, 1.0, v95
	v_rcp_f32_e32 v95, v95
	s_nop 0
	v_mul_f32_e32 v97, v95, v94
	v_cvt_pk_bf16_f32 v94, v98, v99
	v_lshlrev_b64 v[98:99], 11, v[106:107]
	v_lshl_add_u64 v[98:99], s[18:19], 0, v[98:99]
	v_lshl_add_u64 v[98:99], v[98:99], 0, v[148:149]
	v_cvt_pk_bf16_f32 v95, v100, v101
	v_cvt_pk_bf16_f32 v96, v108, v109
	v_cvt_pk_bf16_f32 v97, v114, v97
	global_store_dwordx4 v[98:99], v[94:97], off
	global_load_dwordx4 v[94:97], v[178:179], off offset:528
	s_nop 0
	global_load_dwordx4 v[106:109], v[178:179], off offset:512
	v_lshlrev_b32_e32 v100, 16, v110
	s_waitcnt vmcnt(0)
; __device__ __forceinline__ unsigned cvt_pk_bf16(float lo, float hi) { unsigned r; asm volatile("v_cvt_pk_bf16_f32 %0, %1, %2" : "=v"(r) : "v"(lo), "v"(hi)); return r; }
; __device__ __forceinline__ float fast_sigmoid(float x) { return __builtin_amdgcn_rcpf(1.0f + __expf(-x)); }
;     __device__ __forceinline__ void operator()(const f32x4 (&acc)[2][2][4][2], const Unit& u, int wr, int wc, int fr, int fq, PG8_LAS unsigned char* ldsb) const {
;     ...
;         for (int ai = 0; ai < 2; ++ai) {
;             u32x4 zv[4][2];
; #pragma unroll
;             for (int m = 0; m < 4; ++m)
; #pragma unroll
;                 for (int bj = 0; bj < 2; ++bj) zv[m][bj] = *(const u32x4*)(Zs + ((unsigned)(row0 + ai * HALF + m * 16) * 512u + (unsigned)(col0 + bj * HALF)));
; #pragma unroll
;             for (int m = 0; m < 4; ++m) {
;                 const int row = row0 + ai * HALF + m * 16;
; #pragma unroll
;                 for (int bj = 0; bj < 2; ++bj) {
;                     const int c = col0 + bj * HALF;
;                     const u32x4 zw = zv[m][bj];
;                     float v[8];
; #pragma unroll
;                     for (int n = 0; n < 2; ++n)
; #pragma unroll
;                         for (int i = 0; i < 4; ++i) { const int e = n * 4 + i; const unsigned wd = zw[e >> 1];
;                             const float z = __uint_as_float((e & 1) ? (wd & 0xffff0000u) : (wd << 16));
;                             v[e] = z * fast_sigmoid(acc[ai][bj][m][n][i] + bias[c + e]); }
;                     u32x4 w; w.x = cvt_pk_bf16(v[0], v[1]); w.y = cvt_pk_bf16(v[2], v[3]); w.z = cvt_pk_bf16(v[4], v[5]); w.w = cvt_pk_bf16(v[6], v[7]);
;                     *(u32x4*)(O + (size_t)row * ldo + c) = w;
;                 }
	v_add_f32_e32 v82, v82, v94
	v_add_f32_e32 v86, v86, v106
	v_mul_f32_e32 v86, 0xbfb8aa3b, v86
	v_add_f32_e32 v87, v87, v107
	v_exp_f32_e32 v86, v86
	v_mul_f32_e32 v87, 0xbfb8aa3b, v87
	v_add_f32_e32 v88, v88, v108
	v_exp_f32_e32 v87, v87
	v_mul_f32_e32 v88, 0xbfb8aa3b, v88
	v_add_f32_e32 v89, v89, v109
	v_exp_f32_e32 v88, v88
	v_mul_f32_e32 v89, 0xbfb8aa3b, v89
	v_exp_f32_e32 v89, v89
	v_mul_f32_e32 v82, 0xbfb8aa3b, v82
	v_add_f32_e32 v83, v83, v95
	v_add_f32_e32 v86, 1.0, v86
	v_exp_f32_e32 v82, v82
	v_mul_f32_e32 v83, 0xbfb8aa3b, v83
	v_rcp_f32_e32 v86, v86
	v_add_f32_e32 v87, 1.0, v87
	v_exp_f32_e32 v83, v83
	v_rcp_f32_e32 v87, v87
	v_add_f32_e32 v88, 1.0, v88
	v_rcp_f32_e32 v88, v88
	v_add_f32_e32 v89, 1.0, v89
	v_rcp_f32_e32 v89, v89
	v_add_f32_e32 v82, 1.0, v82
	v_mul_f32_e32 v86, v86, v100
	v_and_b32_e32 v100, 0xffff0000, v110
	v_rcp_f32_e32 v82, v82
	v_add_f32_e32 v83, 1.0, v83
	v_mul_f32_e32 v87, v87, v100
	v_lshlrev_b32_e32 v100, 16, v111
	v_rcp_f32_e32 v83, v83
	v_mul_f32_e32 v88, v88, v100
	v_and_b32_e32 v100, 0xffff0000, v111
	v_mul_f32_e32 v89, v89, v100
	v_lshlrev_b32_e32 v100, 16, v112
	v_mul_f32_e32 v94, v82, v100
	v_and_b32_e32 v82, 0xffff0000, v112
	v_mul_f32_e32 v95, v83, v82
	v_add_f32_e32 v83, v84, v96
	v_mul_f32_e32 v83, 0xbfb8aa3b, v83
	v_exp_f32_e32 v83, v83
	v_lshlrev_b32_e32 v82, 16, v113
	v_add_f32_e32 v83, 1.0, v83
	v_rcp_f32_e32 v83, v83
	s_nop 0
	v_mul_f32_e32 v96, v83, v82
	v_add_f32_e32 v83, v85, v97
	v_mul_f32_e32 v83, 0xbfb8aa3b, v83
	v_exp_f32_e32 v83, v83
	v_and_b32_e32 v82, 0xffff0000, v113
	v_add_f32_e32 v83, 1.0, v83
	v_rcp_f32_e32 v83, v83
	s_nop 0
	v_mul_f32_e32 v85, v83, v82
	v_cvt_pk_bf16_f32 v82, v86, v87
	v_cvt_pk_bf16_f32 v83, v88, v89
	v_cvt_pk_bf16_f32 v84, v94, v95
	v_cvt_pk_bf16_f32 v85, v96, v85
	global_store_dwordx4 v[98:99], v[82:85], off offset:256
	global_load_dwordx4 v[84:87], v[178:179], off offset:16
	s_nop 0
	global_load_dwordx4 v[94:97], v[178:179], off
	v_lshlrev_b32_e32 v88, 16, v102
	v_or_b32_e32 v82, 48, v180
	v_ashrrev_i32_e32 v83, 31, v82
	s_waitcnt vmcnt(0)
	v_add_f32_e32 v74, v74, v84
	v_add_f32_e32 v78, v78, v94
	v_mul_f32_e32 v78, 0xbfb8aa3b, v78
	v_add_f32_e32 v79, v79, v95
	v_exp_f32_e32 v78, v78
	v_mul_f32_e32 v79, 0xbfb8aa3b, v79
	v_add_f32_e32 v80, v80, v96
	v_exp_f32_e32 v79, v79
	v_mul_f32_e32 v80, 0xbfb8aa3b, v80
	v_add_f32_e32 v81, v81, v97
	v_exp_f32_e32 v80, v80
	v_mul_f32_e32 v81, 0xbfb8aa3b, v81
	v_exp_f32_e32 v81, v81
	v_mul_f32_e32 v74, 0xbfb8aa3b, v74
	v_add_f32_e32 v75, v75, v85
	v_add_f32_e32 v78, 1.0, v78
	v_exp_f32_e32 v74, v74
	v_mul_f32_e32 v75, 0xbfb8aa3b, v75
	v_rcp_f32_e32 v78, v78
	v_add_f32_e32 v79, 1.0, v79
	v_exp_f32_e32 v75, v75
	v_rcp_f32_e32 v79, v79
	v_add_f32_e32 v80, 1.0, v80
	v_rcp_f32_e32 v80, v80
	v_add_f32_e32 v81, 1.0, v81
	v_rcp_f32_e32 v81, v81
	v_add_f32_e32 v74, 1.0, v74
	v_mul_f32_e32 v78, v78, v88
	v_and_b32_e32 v88, 0xffff0000, v102
	v_rcp_f32_e32 v74, v74
	v_add_f32_e32 v75, 1.0, v75
	v_mul_f32_e32 v79, v79, v88
	v_lshlrev_b32_e32 v88, 16, v103
	v_rcp_f32_e32 v75, v75
	v_mul_f32_e32 v80, v80, v88
	v_and_b32_e32 v88, 0xffff0000, v103
	v_mul_f32_e32 v81, v81, v88
	v_lshlrev_b32_e32 v88, 16, v104
	v_mul_f32_e32 v84, v74, v88
	v_and_b32_e32 v74, 0xffff0000, v104
	v_mul_f32_e32 v85, v75, v74
	v_add_f32_e32 v75, v76, v86
	v_mul_f32_e32 v75, 0xbfb8aa3b, v75
	v_exp_f32_e32 v75, v75
	v_lshlrev_b32_e32 v74, 16, v105
	v_add_f32_e32 v75, 1.0, v75
	v_rcp_f32_e32 v75, v75
	s_nop 0
	v_mul_f32_e32 v86, v75, v74
	v_add_f32_e32 v75, v77, v87
	v_mul_f32_e32 v75, 0xbfb8aa3b, v75
	v_exp_f32_e32 v75, v75
	v_and_b32_e32 v74, 0xffff0000, v105
	v_add_f32_e32 v75, 1.0, v75
	v_rcp_f32_e32 v75, v75
	s_nop 0
	v_mul_f32_e32 v77, v75, v74
	v_cvt_pk_bf16_f32 v74, v78, v79
	v_lshlrev_b64 v[78:79], 11, v[82:83]
	v_lshl_add_u64 v[78:79], s[18:19], 0, v[78:79]
	v_lshl_add_u64 v[78:79], v[78:79], 0, v[148:149]
	v_cvt_pk_bf16_f32 v75, v80, v81
	v_cvt_pk_bf16_f32 v76, v84, v85
	v_cvt_pk_bf16_f32 v77, v86, v77
	global_store_dwordx4 v[78:79], v[74:77], off
	global_load_dwordx4 v[74:77], v[178:179], off offset:528
	s_nop 0
	global_load_dwordx4 v[80:83], v[178:179], off offset:512
	v_lshlrev_b32_e32 v84, 16, v90
	s_waitcnt vmcnt(0)
	v_add_f32_e32 v66, v66, v74
	v_add_f32_e32 v71, v71, v81
	v_mul_f32_e32 v71, 0xbfb8aa3b, v71
	v_add_f32_e32 v72, v72, v82
	v_exp_f32_e32 v71, v71
	v_mul_f32_e32 v72, 0xbfb8aa3b, v72
	v_add_f32_e32 v73, v73, v83
	v_exp_f32_e32 v72, v72
	v_mul_f32_e32 v73, 0xbfb8aa3b, v73
	v_exp_f32_e32 v73, v73
	v_mul_f32_e32 v66, 0xbfb8aa3b, v66
	v_add_f32_e32 v67, v67, v75
	v_exp_f32_e32 v66, v66
	v_mul_f32_e32 v67, 0xbfb8aa3b, v67
	v_add_f32_e32 v71, 1.0, v71
	v_exp_f32_e32 v67, v67
	v_rcp_f32_e32 v71, v71
	v_add_f32_e32 v72, 1.0, v72
	v_rcp_f32_e32 v72, v72
	v_add_f32_e32 v73, 1.0, v73
	v_rcp_f32_e32 v73, v73
	v_add_f32_e32 v66, 1.0, v66
	v_add_f32_e32 v70, v70, v80
	v_and_b32_e32 v80, 0xffff0000, v90
	v_rcp_f32_e32 v66, v66
	v_add_f32_e32 v67, 1.0, v67
	v_mul_f32_e32 v71, v71, v80
	v_lshlrev_b32_e32 v80, 16, v91
	v_rcp_f32_e32 v67, v67
	v_mul_f32_e32 v72, v72, v80
	v_and_b32_e32 v80, 0xffff0000, v91
	v_mul_f32_e32 v73, v73, v80
	v_lshlrev_b32_e32 v80, 16, v92
	v_mul_f32_e32 v74, v66, v80
	v_and_b32_e32 v66, 0xffff0000, v92
	v_mul_f32_e32 v75, v67, v66
	v_add_f32_e32 v67, v68, v76
	v_mul_f32_e32 v67, 0xbfb8aa3b, v67
	v_exp_f32_e32 v67, v67
	v_lshlrev_b32_e32 v66, 16, v93
	v_mul_f32_e32 v70, 0xbfb8aa3b, v70
	v_exp_f32_e32 v70, v70
	v_add_f32_e32 v67, 1.0, v67
	v_rcp_f32_e32 v67, v67
	v_add_f32_e32 v70, 1.0, v70
	v_rcp_f32_e32 v70, v70
	v_mul_f32_e32 v76, v67, v66
	v_add_f32_e32 v67, v69, v77
	v_mul_f32_e32 v67, 0xbfb8aa3b, v67
	v_exp_f32_e32 v67, v67
; __device__ __forceinline__ unsigned cvt_pk_bf16(float lo, float hi) { unsigned r; asm volatile("v_cvt_pk_bf16_f32 %0, %1, %2" : "=v"(r) : "v"(lo), "v"(hi)); return r; }
; __device__ __forceinline__ float fast_sigmoid(float x) { return __builtin_amdgcn_rcpf(1.0f + __expf(-x)); }
;     __device__ __forceinline__ void operator()(const f32x4 (&acc)[2][2][4][2], const Unit& u, int wr, int wc, int fr, int fq, PG8_LAS unsigned char* ldsb) const {
;     ...
;         for (int ai = 0; ai < 2; ++ai) {
;             u32x4 zv[4][2];
; #pragma unroll
;             for (int m = 0; m < 4; ++m)
; #pragma unroll
;                 for (int bj = 0; bj < 2; ++bj) zv[m][bj] = *(const u32x4*)(Zs + ((unsigned)(row0 + ai * HALF + m * 16) * 512u + (unsigned)(col0 + bj * HALF)));
; #pragma unroll
;             for (int m = 0; m < 4; ++m) {
;                 const int row = row0 + ai * HALF + m * 16;
; #pragma unroll
;                 for (int bj = 0; bj < 2; ++bj) {
;                     const int c = col0 + bj * HALF;
;                     const u32x4 zw = zv[m][bj];
;                     float v[8];
; #pragma unroll
;                     for (int n = 0; n < 2; ++n)
; #pragma unroll
;                         for (int i = 0; i < 4; ++i) { const int e = n * 4 + i; const unsigned wd = zw[e >> 1];
;                             const float z = __uint_as_float((e & 1) ? (wd & 0xffff0000u) : (wd << 16));
;                             v[e] = z * fast_sigmoid(acc[ai][bj][m][n][i] + bias[c + e]); }
;                     u32x4 w; w.x = cvt_pk_bf16(v[0], v[1]); w.y = cvt_pk_bf16(v[2], v[3]); w.z = cvt_pk_bf16(v[4], v[5]); w.w = cvt_pk_bf16(v[6], v[7]);
;                     *(u32x4*)(O + (size_t)row * ldo + c) = w;
;                 }
	v_and_b32_e32 v66, 0xffff0000, v93
	v_mul_f32_e32 v70, v70, v84
	v_add_f32_e32 v67, 1.0, v67
	v_rcp_f32_e32 v67, v67
	s_nop 0
	v_mul_f32_e32 v69, v67, v66
	v_cvt_pk_bf16_f32 v66, v70, v71
	v_cvt_pk_bf16_f32 v67, v72, v73
	v_cvt_pk_bf16_f32 v68, v74, v75
	v_cvt_pk_bf16_f32 v69, v76, v69
	global_store_dwordx4 v[78:79], v[66:69], off offset:256
	s_nop 1
	v_add_u32_e32 v66, 0x10000, v0
	v_mov_b32_e32 v67, v1
	v_lshl_add_u64 v[66:67], v[66:67], 1, s[6:7]
	global_load_dwordx4 v[94:97], v[66:67], off
	v_add_u32_e32 v66, 0x10080, v0
	v_mov_b32_e32 v67, v1
	v_lshl_add_u64 v[66:67], v[66:67], 1, s[6:7]
	global_load_dwordx4 v[90:93], v[66:67], off
	v_add_u32_e32 v66, 0x12000, v0
	v_mov_b32_e32 v67, v1
	v_lshl_add_u64 v[66:67], v[66:67], 1, s[6:7]
	global_load_dwordx4 v[86:89], v[66:67], off
	v_add_u32_e32 v66, 0x12080, v0
	v_mov_b32_e32 v67, v1
	v_lshl_add_u64 v[66:67], v[66:67], 1, s[6:7]
	global_load_dwordx4 v[82:85], v[66:67], off
	v_add_u32_e32 v66, 0x14000, v0
	v_mov_b32_e32 v67, v1
	v_lshl_add_u64 v[66:67], v[66:67], 1, s[6:7]
	global_load_dwordx4 v[78:81], v[66:67], off
	v_add_u32_e32 v66, 0x14080, v0
	v_mov_b32_e32 v67, v1
	v_lshl_add_u64 v[66:67], v[66:67], 1, s[6:7]
	global_load_dwordx4 v[74:77], v[66:67], off
	v_add_u32_e32 v66, 0x16000, v0
	v_mov_b32_e32 v67, v1
	v_lshl_add_u64 v[66:67], v[66:67], 1, s[6:7]
	v_add_u32_e32 v0, 0x16080, v0
	global_load_dwordx4 v[70:73], v[66:67], off
	v_lshl_add_u64 v[66:67], v[0:1], 1, s[6:7]
	global_load_dwordx4 v[66:69], v[66:67], off
	s_nop 0
	global_load_dwordx4 v[98:101], v[178:179], off offset:16
	global_load_dwordx4 v[102:105], v[178:179], off
	s_waitcnt vmcnt(0) lgkmcnt(0)
	v_lshlrev_b32_e32 v0, 16, v94
	v_add_f32_e32 v58, v58, v98
	v_add_f32_e32 v62, v62, v102
	v_mul_f32_e32 v62, 0xbfb8aa3b, v62
	v_add_f32_e32 v63, v63, v103
	v_exp_f32_e32 v62, v62
	v_mul_f32_e32 v63, 0xbfb8aa3b, v63
	v_add_f32_e32 v64, v64, v104
	v_exp_f32_e32 v63, v63
	v_mul_f32_e32 v64, 0xbfb8aa3b, v64
	v_add_f32_e32 v65, v65, v105
	v_exp_f32_e32 v64, v64
	v_mul_f32_e32 v65, 0xbfb8aa3b, v65
	v_exp_f32_e32 v65, v65
	v_mul_f32_e32 v58, 0xbfb8aa3b, v58
	v_add_f32_e32 v59, v59, v99
	v_add_f32_e32 v62, 1.0, v62
	v_exp_f32_e32 v58, v58
	v_mul_f32_e32 v59, 0xbfb8aa3b, v59
	v_rcp_f32_e32 v62, v62
	v_add_f32_e32 v63, 1.0, v63
	v_exp_f32_e32 v59, v59
	v_rcp_f32_e32 v63, v63
	v_add_f32_e32 v64, 1.0, v64
	v_rcp_f32_e32 v64, v64
	v_add_f32_e32 v65, 1.0, v65
	v_rcp_f32_e32 v65, v65
	v_add_f32_e32 v58, 1.0, v58
	v_mul_f32_e32 v0, v62, v0
	v_and_b32_e32 v62, 0xffff0000, v94
	v_rcp_f32_e32 v58, v58
	v_add_f32_e32 v59, 1.0, v59
	v_mul_f32_e32 v62, v63, v62
	v_lshlrev_b32_e32 v63, 16, v95
	v_rcp_f32_e32 v59, v59
	v_mul_f32_e32 v63, v64, v63
	v_and_b32_e32 v64, 0xffff0000, v95
	v_mul_f32_e32 v64, v65, v64
	v_lshlrev_b32_e32 v65, 16, v96
	v_mul_f32_e32 v65, v58, v65
	v_and_b32_e32 v58, 0xffff0000, v96
	v_mul_f32_e32 v94, v59, v58
	v_add_f32_e32 v59, v60, v100
	v_mul_f32_e32 v59, 0xbfb8aa3b, v59
	v_exp_f32_e32 v59, v59
	v_lshlrev_b32_e32 v58, 16, v97
	v_add_f32_e32 v59, 1.0, v59
	v_rcp_f32_e32 v59, v59
	s_nop 0
	v_mul_f32_e32 v95, v59, v58
	v_add_f32_e32 v59, v61, v101
	v_mul_f32_e32 v59, 0xbfb8aa3b, v59
	v_exp_f32_e32 v59, v59
	v_and_b32_e32 v58, 0xffff0000, v97
	v_add_f32_e32 v59, 1.0, v59
	v_rcp_f32_e32 v59, v59
	s_nop 0
	v_mul_f32_e32 v61, v59, v58
	v_cvt_pk_bf16_f32 v58, v0, v62
	v_cvt_pk_bf16_f32 v59, v63, v64
	v_add_co_u32_e32 v64, vcc, s35, v146
	v_cvt_pk_bf16_f32 v60, v65, v94
	v_cvt_pk_bf16_f32 v61, v95, v61
	v_lshlrev_b32_e32 v0, 16, v90
	s_nop 0
	v_addc_co_u32_e32 v65, vcc, 0, v147, vcc
	global_store_dwordx4 v[64:65], v[58:61], off
	global_load_dwordx4 v[58:61], v[178:179], off offset:528
	s_nop 0
	global_load_dwordx4 v[94:97], v[178:179], off offset:512
	v_lshl_add_u64 v[62:63], v[146:147], 0, s[72:73]
	s_waitcnt vmcnt(0)
	v_add_f32_e32 v50, v50, v58
	v_add_f32_e32 v54, v54, v94
	v_mul_f32_e32 v54, 0xbfb8aa3b, v54
	v_add_f32_e32 v55, v55, v95
	v_exp_f32_e32 v54, v54
	v_mul_f32_e32 v55, 0xbfb8aa3b, v55
	v_add_f32_e32 v56, v56, v96
	v_exp_f32_e32 v55, v55
	v_mul_f32_e32 v56, 0xbfb8aa3b, v56
	v_add_f32_e32 v57, v57, v97
	v_exp_f32_e32 v56, v56
	v_mul_f32_e32 v57, 0xbfb8aa3b, v57
	v_exp_f32_e32 v57, v57
	v_mul_f32_e32 v50, 0xbfb8aa3b, v50
	v_add_f32_e32 v51, v51, v59
	v_add_f32_e32 v54, 1.0, v54
	v_exp_f32_e32 v50, v50
	v_mul_f32_e32 v51, 0xbfb8aa3b, v51
	v_rcp_f32_e32 v54, v54
	v_add_f32_e32 v55, 1.0, v55
	v_exp_f32_e32 v51, v51
	v_rcp_f32_e32 v55, v55
	v_add_f32_e32 v56, 1.0, v56
	v_rcp_f32_e32 v56, v56
	v_add_f32_e32 v57, 1.0, v57
	v_rcp_f32_e32 v57, v57
	v_add_f32_e32 v50, 1.0, v50
	v_mul_f32_e32 v0, v54, v0
	v_and_b32_e32 v54, 0xffff0000, v90
	v_rcp_f32_e32 v50, v50
	v_add_f32_e32 v51, 1.0, v51
	v_mul_f32_e32 v54, v55, v54
	v_lshlrev_b32_e32 v55, 16, v91
	v_rcp_f32_e32 v51, v51
	v_mul_f32_e32 v55, v56, v55
	v_and_b32_e32 v56, 0xffff0000, v91
	v_mul_f32_e32 v56, v57, v56
	v_lshlrev_b32_e32 v57, 16, v92
	v_mul_f32_e32 v57, v50, v57
	v_and_b32_e32 v50, 0xffff0000, v92
	v_mul_f32_e32 v58, v51, v50
	v_add_f32_e32 v51, v52, v60
	v_mul_f32_e32 v51, 0xbfb8aa3b, v51
	v_exp_f32_e32 v51, v51
	v_lshlrev_b32_e32 v50, 16, v93
	v_add_f32_e32 v51, 1.0, v51
	v_rcp_f32_e32 v51, v51
	s_nop 0
	v_mul_f32_e32 v59, v51, v50
	v_add_f32_e32 v51, v53, v61
	v_mul_f32_e32 v51, 0xbfb8aa3b, v51
	v_exp_f32_e32 v51, v51
	v_and_b32_e32 v50, 0xffff0000, v93
	v_add_f32_e32 v51, 1.0, v51
	v_rcp_f32_e32 v51, v51
	s_nop 0
	v_mul_f32_e32 v53, v51, v50
	v_cvt_pk_bf16_f32 v50, v0, v54
	v_cvt_pk_bf16_f32 v51, v55, v56
	v_cvt_pk_bf16_f32 v52, v57, v58
	v_cvt_pk_bf16_f32 v53, v59, v53
	global_store_dwordx4 v[62:63], v[50:53], off offset:256
	global_load_dwordx4 v[50:53], v[178:179], off offset:16
	s_nop 0
	global_load_dwordx4 v[54:57], v[178:179], off
	v_lshlrev_b32_e32 v0, 16, v86
	s_waitcnt vmcnt(0)
; __device__ __forceinline__ unsigned cvt_pk_bf16(float lo, float hi) { unsigned r; asm volatile("v_cvt_pk_bf16_f32 %0, %1, %2" : "=v"(r) : "v"(lo), "v"(hi)); return r; }
; __device__ __forceinline__ float fast_sigmoid(float x) { return __builtin_amdgcn_rcpf(1.0f + __expf(-x)); }
;     __device__ __forceinline__ void operator()(const f32x4 (&acc)[2][2][4][2], const Unit& u, int wr, int wc, int fr, int fq, PG8_LAS unsigned char* ldsb) const {
;     ...
;         for (int ai = 0; ai < 2; ++ai) {
;             u32x4 zv[4][2];
; #pragma unroll
;             for (int m = 0; m < 4; ++m)
; #pragma unroll
;                 for (int bj = 0; bj < 2; ++bj) zv[m][bj] = *(const u32x4*)(Zs + ((unsigned)(row0 + ai * HALF + m * 16) * 512u + (unsigned)(col0 + bj * HALF)));
; #pragma unroll
;             for (int m = 0; m < 4; ++m) {
;                 const int row = row0 + ai * HALF + m * 16;
; #pragma unroll
;                 for (int bj = 0; bj < 2; ++bj) {
;                     const int c = col0 + bj * HALF;
;                     const u32x4 zw = zv[m][bj];
;                     float v[8];
; #pragma unroll
;                     for (int n = 0; n < 2; ++n)
; #pragma unroll
;                         for (int i = 0; i < 4; ++i) { const int e = n * 4 + i; const unsigned wd = zw[e >> 1];
;                             const float z = __uint_as_float((e & 1) ? (wd & 0xffff0000u) : (wd << 16));
;                             v[e] = z * fast_sigmoid(acc[ai][bj][m][n][i] + bias[c + e]); }
;                     u32x4 w; w.x = cvt_pk_bf16(v[0], v[1]); w.y = cvt_pk_bf16(v[2], v[3]); w.z = cvt_pk_bf16(v[4], v[5]); w.w = cvt_pk_bf16(v[6], v[7]);
;                     *(u32x4*)(O + (size_t)row * ldo + c) = w;
;                 }
	v_add_f32_e32 v42, v42, v50
	v_add_f32_e32 v46, v46, v54
	v_mul_f32_e32 v46, 0xbfb8aa3b, v46
	v_add_f32_e32 v47, v47, v55
	v_exp_f32_e32 v46, v46
	v_mul_f32_e32 v47, 0xbfb8aa3b, v47
	v_add_f32_e32 v48, v48, v56
	v_exp_f32_e32 v47, v47
	v_mul_f32_e32 v48, 0xbfb8aa3b, v48
	v_add_f32_e32 v49, v49, v57
	v_exp_f32_e32 v48, v48
	v_mul_f32_e32 v49, 0xbfb8aa3b, v49
	v_exp_f32_e32 v49, v49
	v_mul_f32_e32 v42, 0xbfb8aa3b, v42
	v_add_f32_e32 v43, v43, v51
	v_add_f32_e32 v46, 1.0, v46
	v_exp_f32_e32 v42, v42
	v_mul_f32_e32 v43, 0xbfb8aa3b, v43
	v_rcp_f32_e32 v46, v46
	v_add_f32_e32 v47, 1.0, v47
	v_exp_f32_e32 v43, v43
	v_rcp_f32_e32 v47, v47
	v_add_f32_e32 v48, 1.0, v48
	v_rcp_f32_e32 v48, v48
	v_add_f32_e32 v49, 1.0, v49
	v_rcp_f32_e32 v49, v49
	v_add_f32_e32 v42, 1.0, v42
	v_mul_f32_e32 v0, v46, v0
	v_and_b32_e32 v46, 0xffff0000, v86
	v_rcp_f32_e32 v42, v42
	v_add_f32_e32 v43, 1.0, v43
	v_mul_f32_e32 v46, v47, v46
	v_lshlrev_b32_e32 v47, 16, v87
	v_rcp_f32_e32 v43, v43
	v_mul_f32_e32 v47, v48, v47
	v_and_b32_e32 v48, 0xffff0000, v87
	v_mul_f32_e32 v48, v49, v48
	v_lshlrev_b32_e32 v49, 16, v88
	v_mul_f32_e32 v49, v42, v49
	v_and_b32_e32 v42, 0xffff0000, v88
	v_mul_f32_e32 v50, v43, v42
	v_add_f32_e32 v43, v44, v52
	v_mul_f32_e32 v43, 0xbfb8aa3b, v43
	v_exp_f32_e32 v43, v43
	v_lshlrev_b32_e32 v42, 16, v89
	v_add_f32_e32 v43, 1.0, v43
	v_rcp_f32_e32 v43, v43
	s_nop 0
	v_mul_f32_e32 v51, v43, v42
	v_add_f32_e32 v43, v45, v53
	v_mul_f32_e32 v43, 0xbfb8aa3b, v43
	v_exp_f32_e32 v43, v43
	v_and_b32_e32 v42, 0xffff0000, v89
	v_add_f32_e32 v43, 1.0, v43
	v_rcp_f32_e32 v43, v43
	s_nop 0
	v_mul_f32_e32 v45, v43, v42
	v_cvt_pk_bf16_f32 v42, v0, v46
	v_cvt_pk_bf16_f32 v43, v47, v48
	v_add_co_u32_e32 v48, vcc, s1, v146
	v_cvt_pk_bf16_f32 v44, v49, v50
	v_cvt_pk_bf16_f32 v45, v51, v45
	v_lshlrev_b32_e32 v0, 16, v82
	s_nop 0
	v_addc_co_u32_e32 v49, vcc, 0, v147, vcc
	global_store_dwordx4 v[48:49], v[42:45], off
	global_load_dwordx4 v[42:45], v[178:179], off offset:528
	s_nop 0
	global_load_dwordx4 v[48:51], v[178:179], off offset:512
	v_lshl_add_u64 v[46:47], v[146:147], 0, s[28:29]
	s_mov_b32 s1, 0x50000
	s_mov_b64 s[28:29], 0x50000
	s_waitcnt vmcnt(0)
	v_add_f32_e32 v34, v34, v42
	v_add_f32_e32 v38, v38, v48
	v_mul_f32_e32 v38, 0xbfb8aa3b, v38
	v_add_f32_e32 v39, v39, v49
	v_exp_f32_e32 v38, v38
	v_mul_f32_e32 v39, 0xbfb8aa3b, v39
	v_add_f32_e32 v40, v40, v50
	v_exp_f32_e32 v39, v39
	v_mul_f32_e32 v40, 0xbfb8aa3b, v40
	v_add_f32_e32 v41, v41, v51
	v_exp_f32_e32 v40, v40
	v_mul_f32_e32 v41, 0xbfb8aa3b, v41
	v_exp_f32_e32 v41, v41
	v_mul_f32_e32 v34, 0xbfb8aa3b, v34
	v_add_f32_e32 v35, v35, v43
	v_add_f32_e32 v38, 1.0, v38
	v_exp_f32_e32 v34, v34
	v_mul_f32_e32 v35, 0xbfb8aa3b, v35
	v_rcp_f32_e32 v38, v38
	v_add_f32_e32 v39, 1.0, v39
	v_exp_f32_e32 v35, v35
	v_rcp_f32_e32 v39, v39
	v_add_f32_e32 v40, 1.0, v40
	v_rcp_f32_e32 v40, v40
	v_add_f32_e32 v41, 1.0, v41
	v_rcp_f32_e32 v41, v41
	v_add_f32_e32 v34, 1.0, v34
	v_mul_f32_e32 v0, v38, v0
	v_and_b32_e32 v38, 0xffff0000, v82
	v_rcp_f32_e32 v34, v34
	v_add_f32_e32 v35, 1.0, v35
	v_mul_f32_e32 v38, v39, v38
	v_lshlrev_b32_e32 v39, 16, v83
	v_rcp_f32_e32 v35, v35
	v_mul_f32_e32 v39, v40, v39
	v_and_b32_e32 v40, 0xffff0000, v83
	v_mul_f32_e32 v40, v41, v40
	v_lshlrev_b32_e32 v41, 16, v84
	v_mul_f32_e32 v41, v34, v41
	v_and_b32_e32 v34, 0xffff0000, v84
	v_mul_f32_e32 v42, v35, v34
	v_add_f32_e32 v35, v36, v44
	v_mul_f32_e32 v35, 0xbfb8aa3b, v35
	v_exp_f32_e32 v35, v35
	v_lshlrev_b32_e32 v34, 16, v85
	v_add_f32_e32 v35, 1.0, v35
	v_rcp_f32_e32 v35, v35
	s_nop 0
	v_mul_f32_e32 v43, v35, v34
	v_add_f32_e32 v35, v37, v45
	v_mul_f32_e32 v35, 0xbfb8aa3b, v35
	v_exp_f32_e32 v35, v35
	v_and_b32_e32 v34, 0xffff0000, v85
	v_add_f32_e32 v35, 1.0, v35
	v_rcp_f32_e32 v35, v35
	s_nop 0
	v_mul_f32_e32 v37, v35, v34
	v_cvt_pk_bf16_f32 v34, v0, v38
	v_cvt_pk_bf16_f32 v35, v39, v40
	v_cvt_pk_bf16_f32 v36, v41, v42
	v_cvt_pk_bf16_f32 v37, v43, v37
	global_store_dwordx4 v[46:47], v[34:37], off offset:256
	global_load_dwordx4 v[34:37], v[178:179], off offset:16
	s_nop 0
	global_load_dwordx4 v[38:41], v[178:179], off
	v_lshlrev_b32_e32 v0, 16, v78
	s_waitcnt vmcnt(0)
	v_add_f32_e32 v26, v26, v34
	v_add_f32_e32 v30, v30, v38
	v_mul_f32_e32 v30, 0xbfb8aa3b, v30
	v_add_f32_e32 v31, v31, v39
	v_exp_f32_e32 v30, v30
	v_mul_f32_e32 v31, 0xbfb8aa3b, v31
	v_add_f32_e32 v32, v32, v40
	v_exp_f32_e32 v31, v31
	v_mul_f32_e32 v32, 0xbfb8aa3b, v32
	v_add_f32_e32 v33, v33, v41
	v_exp_f32_e32 v32, v32
	v_mul_f32_e32 v33, 0xbfb8aa3b, v33
	v_exp_f32_e32 v33, v33
	v_mul_f32_e32 v26, 0xbfb8aa3b, v26
	v_add_f32_e32 v27, v27, v35
	v_add_f32_e32 v30, 1.0, v30
	v_exp_f32_e32 v26, v26
	v_mul_f32_e32 v27, 0xbfb8aa3b, v27
	v_rcp_f32_e32 v30, v30
	v_add_f32_e32 v31, 1.0, v31
	v_exp_f32_e32 v27, v27
	v_rcp_f32_e32 v31, v31
	v_add_f32_e32 v32, 1.0, v32
	v_rcp_f32_e32 v32, v32
	v_add_f32_e32 v33, 1.0, v33
	v_rcp_f32_e32 v33, v33
	v_add_f32_e32 v26, 1.0, v26
	v_mul_f32_e32 v0, v30, v0
	v_and_b32_e32 v30, 0xffff0000, v78
	v_rcp_f32_e32 v26, v26
	v_add_f32_e32 v27, 1.0, v27
	v_mul_f32_e32 v30, v31, v30
	v_lshlrev_b32_e32 v31, 16, v79
	v_rcp_f32_e32 v27, v27
	v_mul_f32_e32 v31, v32, v31
	v_and_b32_e32 v32, 0xffff0000, v79
	v_mul_f32_e32 v32, v33, v32
	v_lshlrev_b32_e32 v33, 16, v80
	v_mul_f32_e32 v33, v26, v33
	v_and_b32_e32 v26, 0xffff0000, v80
	v_mul_f32_e32 v34, v27, v26
	v_add_f32_e32 v27, v28, v36
	v_mul_f32_e32 v27, 0xbfb8aa3b, v27
	v_exp_f32_e32 v27, v27
	v_lshlrev_b32_e32 v26, 16, v81
	v_add_f32_e32 v27, 1.0, v27
	v_rcp_f32_e32 v27, v27
	s_nop 0
	v_mul_f32_e32 v35, v27, v26
	v_add_f32_e32 v27, v29, v37
	v_mul_f32_e32 v27, 0xbfb8aa3b, v27
	v_exp_f32_e32 v27, v27
	v_and_b32_e32 v26, 0xffff0000, v81
	v_add_f32_e32 v27, 1.0, v27
	v_rcp_f32_e32 v27, v27
	s_nop 0
	v_mul_f32_e32 v29, v27, v26
	v_cvt_pk_bf16_f32 v26, v0, v30
	v_cvt_pk_bf16_f32 v27, v31, v32
	v_add_co_u32_e32 v32, vcc, s1, v146
	v_cvt_pk_bf16_f32 v28, v33, v34
	v_cvt_pk_bf16_f32 v29, v35, v29
	v_lshlrev_b32_e32 v0, 16, v74
	s_nop 0
	v_addc_co_u32_e32 v33, vcc, 0, v147, vcc
	global_store_dwordx4 v[32:33], v[26:29], off
	global_load_dwordx4 v[26:29], v[178:179], off offset:528
	s_nop 0
	global_load_dwordx4 v[32:35], v[178:179], off offset:512
	v_lshl_add_u64 v[30:31], v[146:147], 0, s[28:29]
	s_mov_b32 s1, 0x58000
	s_mov_b64 s[28:29], 0x58000
	s_waitcnt vmcnt(0)
; __device__ __forceinline__ unsigned cvt_pk_bf16(float lo, float hi) { unsigned r; asm volatile("v_cvt_pk_bf16_f32 %0, %1, %2" : "=v"(r) : "v"(lo), "v"(hi)); return r; }
; __device__ __forceinline__ float fast_sigmoid(float x) { return __builtin_amdgcn_rcpf(1.0f + __expf(-x)); }
;     __device__ __forceinline__ void operator()(const f32x4 (&acc)[2][2][4][2], const Unit& u, int wr, int wc, int fr, int fq, PG8_LAS unsigned char* ldsb) const {
;     ...
;         for (int ai = 0; ai < 2; ++ai) {
;             u32x4 zv[4][2];
; #pragma unroll
;             for (int m = 0; m < 4; ++m)
; #pragma unroll
;                 for (int bj = 0; bj < 2; ++bj) zv[m][bj] = *(const u32x4*)(Zs + ((unsigned)(row0 + ai * HALF + m * 16) * 512u + (unsigned)(col0 + bj * HALF)));
; #pragma unroll
;             for (int m = 0; m < 4; ++m) {
;                 const int row = row0 + ai * HALF + m * 16;
; #pragma unroll
;                 for (int bj = 0; bj < 2; ++bj) {
;                     const int c = col0 + bj * HALF;
;                     const u32x4 zw = zv[m][bj];
;                     float v[8];
; #pragma unroll
;                     for (int n = 0; n < 2; ++n)
; #pragma unroll
;                         for (int i = 0; i < 4; ++i) { const int e = n * 4 + i; const unsigned wd = zw[e >> 1];
;                             const float z = __uint_as_float((e & 1) ? (wd & 0xffff0000u) : (wd << 16));
;                             v[e] = z * fast_sigmoid(acc[ai][bj][m][n][i] + bias[c + e]); }
;                     u32x4 w; w.x = cvt_pk_bf16(v[0], v[1]); w.y = cvt_pk_bf16(v[2], v[3]); w.z = cvt_pk_bf16(v[4], v[5]); w.w = cvt_pk_bf16(v[6], v[7]);
;                     *(u32x4*)(O + (size_t)row * ldo + c) = w;
;                 }
	v_add_f32_e32 v18, v18, v26
	v_add_f32_e32 v22, v22, v32
	v_mul_f32_e32 v22, 0xbfb8aa3b, v22
	v_add_f32_e32 v23, v23, v33
	v_exp_f32_e32 v22, v22
	v_mul_f32_e32 v23, 0xbfb8aa3b, v23
	v_add_f32_e32 v24, v24, v34
	v_exp_f32_e32 v23, v23
	v_mul_f32_e32 v24, 0xbfb8aa3b, v24
	v_add_f32_e32 v25, v25, v35
	v_exp_f32_e32 v24, v24
	v_mul_f32_e32 v25, 0xbfb8aa3b, v25
	v_exp_f32_e32 v25, v25
	v_mul_f32_e32 v18, 0xbfb8aa3b, v18
	v_add_f32_e32 v19, v19, v27
	v_add_f32_e32 v22, 1.0, v22
	v_exp_f32_e32 v18, v18
	v_mul_f32_e32 v19, 0xbfb8aa3b, v19
	v_rcp_f32_e32 v22, v22
	v_add_f32_e32 v23, 1.0, v23
	v_exp_f32_e32 v19, v19
	v_rcp_f32_e32 v23, v23
	v_add_f32_e32 v24, 1.0, v24
	v_rcp_f32_e32 v24, v24
	v_add_f32_e32 v25, 1.0, v25
	v_rcp_f32_e32 v25, v25
	v_add_f32_e32 v18, 1.0, v18
	v_mul_f32_e32 v0, v22, v0
	v_and_b32_e32 v22, 0xffff0000, v74
	v_rcp_f32_e32 v18, v18
	v_add_f32_e32 v19, 1.0, v19
	v_mul_f32_e32 v22, v23, v22
	v_lshlrev_b32_e32 v23, 16, v75
	v_rcp_f32_e32 v19, v19
	v_mul_f32_e32 v23, v24, v23
	v_and_b32_e32 v24, 0xffff0000, v75
	v_mul_f32_e32 v24, v25, v24
	v_lshlrev_b32_e32 v25, 16, v76
	v_mul_f32_e32 v25, v18, v25
	v_and_b32_e32 v18, 0xffff0000, v76
	v_mul_f32_e32 v26, v19, v18
	v_add_f32_e32 v19, v20, v28
	v_mul_f32_e32 v19, 0xbfb8aa3b, v19
	v_exp_f32_e32 v19, v19
	v_lshlrev_b32_e32 v18, 16, v77
	v_add_f32_e32 v19, 1.0, v19
	v_rcp_f32_e32 v19, v19
	s_nop 0
	v_mul_f32_e32 v27, v19, v18
	v_add_f32_e32 v19, v21, v29
	v_mul_f32_e32 v19, 0xbfb8aa3b, v19
	v_exp_f32_e32 v19, v19
	v_and_b32_e32 v18, 0xffff0000, v77
	v_add_f32_e32 v19, 1.0, v19
	v_rcp_f32_e32 v19, v19
	s_nop 0
	v_mul_f32_e32 v21, v19, v18
	v_cvt_pk_bf16_f32 v18, v0, v22
	v_cvt_pk_bf16_f32 v19, v23, v24
	v_cvt_pk_bf16_f32 v20, v25, v26
	v_cvt_pk_bf16_f32 v21, v27, v21
	global_store_dwordx4 v[30:31], v[18:21], off offset:256
	global_load_dwordx4 v[18:21], v[178:179], off offset:16
	s_nop 0
	global_load_dwordx4 v[22:25], v[178:179], off
	v_lshlrev_b32_e32 v0, 16, v70
	s_waitcnt vmcnt(0)
	v_add_f32_e32 v10, v10, v18
	v_add_f32_e32 v14, v14, v22
	v_mul_f32_e32 v14, 0xbfb8aa3b, v14
	v_add_f32_e32 v15, v15, v23
	v_exp_f32_e32 v14, v14
	v_mul_f32_e32 v15, 0xbfb8aa3b, v15
	v_add_f32_e32 v16, v16, v24
	v_exp_f32_e32 v15, v15
	v_mul_f32_e32 v16, 0xbfb8aa3b, v16
	v_add_f32_e32 v17, v17, v25
	v_exp_f32_e32 v16, v16
	v_mul_f32_e32 v17, 0xbfb8aa3b, v17
	v_exp_f32_e32 v17, v17
	v_mul_f32_e32 v10, 0xbfb8aa3b, v10
	v_add_f32_e32 v11, v11, v19
	v_add_f32_e32 v14, 1.0, v14
	v_exp_f32_e32 v10, v10
	v_mul_f32_e32 v11, 0xbfb8aa3b, v11
	v_rcp_f32_e32 v14, v14
	v_add_f32_e32 v15, 1.0, v15
	v_exp_f32_e32 v11, v11
	v_rcp_f32_e32 v15, v15
	v_add_f32_e32 v16, 1.0, v16
	v_rcp_f32_e32 v16, v16
	v_add_f32_e32 v17, 1.0, v17
	v_rcp_f32_e32 v17, v17
	v_add_f32_e32 v10, 1.0, v10
	v_mul_f32_e32 v0, v14, v0
	v_and_b32_e32 v14, 0xffff0000, v70
	v_rcp_f32_e32 v10, v10
	v_add_f32_e32 v11, 1.0, v11
	v_mul_f32_e32 v14, v15, v14
	v_lshlrev_b32_e32 v15, 16, v71
	v_rcp_f32_e32 v11, v11
	v_mul_f32_e32 v15, v16, v15
	v_and_b32_e32 v16, 0xffff0000, v71
	v_mul_f32_e32 v16, v17, v16
	v_lshlrev_b32_e32 v17, 16, v72
	v_mul_f32_e32 v17, v10, v17
	v_and_b32_e32 v10, 0xffff0000, v72
	v_mul_f32_e32 v18, v11, v10
	v_add_f32_e32 v11, v12, v20
	v_mul_f32_e32 v11, 0xbfb8aa3b, v11
	v_exp_f32_e32 v11, v11
	v_lshlrev_b32_e32 v10, 16, v73
	v_add_f32_e32 v11, 1.0, v11
	v_rcp_f32_e32 v11, v11
	s_nop 0
	v_mul_f32_e32 v19, v11, v10
	v_add_f32_e32 v11, v13, v21
	v_mul_f32_e32 v11, 0xbfb8aa3b, v11
	v_exp_f32_e32 v11, v11
	v_and_b32_e32 v10, 0xffff0000, v73
	v_add_f32_e32 v11, 1.0, v11
	v_rcp_f32_e32 v11, v11
	s_nop 0
	v_mul_f32_e32 v13, v11, v10
	v_cvt_pk_bf16_f32 v10, v0, v14
	v_cvt_pk_bf16_f32 v11, v15, v16
	v_add_co_u32_e32 v16, vcc, s1, v146
	v_cvt_pk_bf16_f32 v12, v17, v18
	v_cvt_pk_bf16_f32 v13, v19, v13
	v_lshlrev_b32_e32 v0, 16, v66
	s_nop 0
	v_addc_co_u32_e32 v17, vcc, 0, v147, vcc
	global_store_dwordx4 v[16:17], v[10:13], off
	global_load_dwordx4 v[10:13], v[178:179], off offset:528
	s_nop 0
	global_load_dwordx4 v[16:19], v[178:179], off offset:512
	v_lshl_add_u64 v[14:15], v[146:147], 0, s[28:29]
	s_mov_b64 s[28:29], -1
	s_and_b64 vcc, exec, s[2:3]
	s_waitcnt vmcnt(0)
	v_add_f32_e32 v2, v2, v10
	v_add_f32_e32 v6, v6, v16
	v_mul_f32_e32 v6, 0xbfb8aa3b, v6
	v_add_f32_e32 v7, v7, v17
	v_exp_f32_e32 v6, v6
	v_mul_f32_e32 v7, 0xbfb8aa3b, v7
	v_add_f32_e32 v8, v8, v18
	v_exp_f32_e32 v7, v7
	v_mul_f32_e32 v8, 0xbfb8aa3b, v8
	v_add_f32_e32 v9, v9, v19
	v_exp_f32_e32 v8, v8
	v_mul_f32_e32 v9, 0xbfb8aa3b, v9
	v_exp_f32_e32 v9, v9
	v_mul_f32_e32 v2, 0xbfb8aa3b, v2
	v_add_f32_e32 v3, v3, v11
	v_add_f32_e32 v6, 1.0, v6
	v_exp_f32_e32 v2, v2
	v_mul_f32_e32 v3, 0xbfb8aa3b, v3
	v_rcp_f32_e32 v6, v6
	v_add_f32_e32 v7, 1.0, v7
	v_exp_f32_e32 v3, v3
	v_rcp_f32_e32 v7, v7
	v_add_f32_e32 v8, 1.0, v8
	v_rcp_f32_e32 v8, v8
	v_add_f32_e32 v9, 1.0, v9
	v_rcp_f32_e32 v9, v9
	v_add_f32_e32 v2, 1.0, v2
	v_mul_f32_e32 v0, v6, v0
	v_and_b32_e32 v6, 0xffff0000, v66
	v_rcp_f32_e32 v2, v2
	v_add_f32_e32 v3, 1.0, v3
	v_mul_f32_e32 v6, v7, v6
	v_lshlrev_b32_e32 v7, 16, v67
	v_rcp_f32_e32 v3, v3
	v_mul_f32_e32 v7, v8, v7
	v_and_b32_e32 v8, 0xffff0000, v67
	v_mul_f32_e32 v8, v9, v8
	v_lshlrev_b32_e32 v9, 16, v68
	v_mul_f32_e32 v9, v2, v9
	v_and_b32_e32 v2, 0xffff0000, v68
	v_mul_f32_e32 v10, v3, v2
	v_add_f32_e32 v3, v4, v12
	v_mul_f32_e32 v3, 0xbfb8aa3b, v3
	v_exp_f32_e32 v3, v3
	v_lshlrev_b32_e32 v2, 16, v69
	v_add_f32_e32 v3, 1.0, v3
	v_rcp_f32_e32 v3, v3
	s_nop 0
	v_mul_f32_e32 v11, v3, v2
	v_add_f32_e32 v3, v5, v13
	v_mul_f32_e32 v3, 0xbfb8aa3b, v3
	v_exp_f32_e32 v3, v3
	v_and_b32_e32 v2, 0xffff0000, v69
	v_add_f32_e32 v3, 1.0, v3
	v_rcp_f32_e32 v3, v3
	s_nop 0
	v_mul_f32_e32 v5, v3, v2
	v_cvt_pk_bf16_f32 v2, v0, v6
	v_cvt_pk_bf16_f32 v3, v7, v8
	v_cvt_pk_bf16_f32 v4, v9, v10
	v_cvt_pk_bf16_f32 v5, v11, v5
	global_store_dwordx4 v[14:15], v[2:5], off offset:256
	s_cbranch_vccnz .LBB0_808
	s_andn2_b64 vcc, exec, s[16:17]
	s_cbranch_vccnz .LBB0_807
	s_barrier
	s_branch .LBB0_807

; __device__ __forceinline__ unsigned cvt_pk_bf16(float lo, float hi) { unsigned r; asm volatile("v_cvt_pk_bf16_f32 %0, %1, %2" : "=v"(r) : "v"(lo), "v"(hi)); return r; }
; __device__ __forceinline__ float bflo(unsigned w) { return __uint_as_float(w << 16); }
; __device__ __forceinline__ float bfhi(unsigned w) { return __uint_as_float(w & 0xffff0000u); }
; __global__ void __launch_bounds__(512, 2) mega_fwd(Params P) {
;     ...
;                     for (size_t idx0 = gtid; idx0 < (size_t)T_TOK * 16; idx0 += GT * 4) {
;                         u32x4 av[4], bv4[4]; f32x4 tv[4][4];
; #pragma unroll
;                         for (int q = 0; q < 4; ++q) { const size_t idx = idx0 + (size_t)q * GT; const bool ok = idx < (size_t)T_TOK * 16; const size_t ix = ok ? idx : 0;
;                             const int row = (int)(ix >> 4), sub = (int)(ix & 15), qk = sub >> 3, hm = sub & 7, pos = row & (SEQ - 1);
;                             const bf16_t* p = Z + (size_t)row * ZW + qk * 512 + hm * 64; av[q] = *(const u32x4*)p; bv4[q] = *(const u32x4*)(p + 8);
; #pragma unroll
;                             for (int e = 0; e < 4; ++e) tv[q][e] = ((const f32x4*)(ROPE_DA + pos * 8))[e]; }
; #pragma unroll
;                         for (int q = 0; q < 4; ++q) { const size_t idx = idx0 + (size_t)q * GT; if (idx < (size_t)T_TOK * 16) {
;                             const int row = (int)(idx >> 4), sub = (int)(idx & 15), qk = sub >> 3, hm = sub & 7;
;                             bf16_t* p = Z + (size_t)row * ZW + qk * 512 + hm * 64; float o1[8], o2[8];
; #pragma unroll
;                             for (int e = 0; e < 8; ++e) { const unsigned wa = av[q][e >> 1], wb = bv4[q][e >> 1]; const float x1 = (e & 1) ? bfhi(wa) : bflo(wa), x2 = (e & 1) ? bfhi(wb) : bflo(wb);
;                                 const float cs_ = tv[q][e >> 1][(e & 1) * 2], sn_ = tv[q][e >> 1][(e & 1) * 2 + 1]; o1[e] = x1 * cs_ - x2 * sn_; o2[e] = x1 * sn_ + x2 * cs_; }
;                             u32x4 wa, wb; wa.x = cvt_pk_bf16(o1[0], o1[1]); wa.y = cvt_pk_bf16(o1[2], o1[3]); wa.z = cvt_pk_bf16(o1[4], o1[5]); wa.w = cvt_pk_bf16(o1[6], o1[7]);
;                             wb.x = cvt_pk_bf16(o2[0], o2[1]); wb.y = cvt_pk_bf16(o2[2], o2[3]); wb.z = cvt_pk_bf16(o2[4], o2[5]); wb.w = cvt_pk_bf16(o2[6], o2[7]);
;                             *(u32x4*)p = wa; *(u32x4*)(p + 8) = wb; } }
.LBB0_871:
	v_lshl_add_u64 v[90:91], s[8:9], 0, v[82:83]
	v_cmp_gt_u64_e64 s[4:5], s[12:13], v[90:91]
	v_mov_b64_e32 v[104:105], s[10:11]
	v_lshl_add_u64 v[86:87], s[26:27], 0, v[82:83]
	v_cndmask_b32_e64 v0, 0, v91, s[4:5]
	v_cndmask_b32_e64 v4, 0, v90, s[4:5]
	v_alignbit_b32 v0, v0, v4, 4
	v_lshlrev_b32_e32 v5, 7, v4
	v_mad_i64_i32 v[2:3], s[2:3], v0, s57, v[104:105]
	v_and_b32_e32 v0, 0x400, v5
	v_lshl_add_u64 v[2:3], v[2:3], 0, v[0:1]
	v_and_b32_e32 v0, 0x380, v5
	v_lshl_add_u64 v[2:3], v[2:3], 0, v[0:1]
	v_lshlrev_b32_e32 v0, 2, v4
	v_and_b32_e32 v0, 0x1ffc0, v0
	v_cmp_gt_u64_e64 s[2:3], s[12:13], v[86:87]
	global_load_dwordx4 v[46:49], v[2:3], off
	global_load_dwordx4 v[50:53], v[2:3], off offset:16
	v_lshl_add_u64 v[2:3], s[20:21], 0, v[0:1]
	v_cndmask_b32_e64 v0, 0, v87, s[2:3]
	v_cndmask_b32_e64 v4, 0, v86, s[2:3]
	v_alignbit_b32 v0, v0, v4, 4
	v_lshlrev_b32_e32 v5, 7, v4
	global_load_dwordx4 v[70:73], v[2:3], off
	global_load_dwordx4 v[66:69], v[2:3], off offset:16
	global_load_dwordx4 v[62:65], v[2:3], off offset:32
	global_load_dwordx4 v[58:61], v[2:3], off offset:48
	v_mad_i64_i32 v[2:3], s[30:31], v0, s57, v[104:105]
	v_and_b32_e32 v0, 0x400, v5
	v_lshl_add_u64 v[2:3], v[2:3], 0, v[0:1]
	v_and_b32_e32 v0, 0x380, v5
	v_lshl_add_u64 v[2:3], v[2:3], 0, v[0:1]
	v_lshlrev_b32_e32 v0, 2, v4
	v_lshl_add_u64 v[84:85], s[36:37], 0, v[82:83]
	v_and_b32_e32 v0, 0x1ffc0, v0
	v_cmp_gt_u64_e32 vcc, s[12:13], v[84:85]
	global_load_dwordx4 v[22:25], v[2:3], off
	global_load_dwordx4 v[26:29], v[2:3], off offset:16
	v_lshl_add_u64 v[2:3], s[20:21], 0, v[0:1]
	v_cndmask_b32_e32 v0, 0, v85, vcc
	v_cndmask_b32_e32 v10, 0, v84, vcc
	v_alignbit_b32 v0, v0, v10, 4
	v_lshlrev_b32_e32 v4, 7, v10
	global_load_dwordx4 v[54:57], v[2:3], off
	global_load_dwordx4 v[42:45], v[2:3], off offset:16
	global_load_dwordx4 v[38:41], v[2:3], off offset:32
	global_load_dwordx4 v[34:37], v[2:3], off offset:48
	v_mad_i64_i32 v[2:3], s[30:31], v0, s57, v[104:105]
	v_and_b32_e32 v0, 0x400, v4
	v_lshl_add_u64 v[2:3], v[2:3], 0, v[0:1]
	v_and_b32_e32 v0, 0x380, v4
	v_lshl_add_u64 v[6:7], v[2:3], 0, v[0:1]
	v_lshlrev_b32_e32 v0, 2, v10
	v_and_b32_e32 v0, 0x1ffc0, v0
	v_lshlrev_b32_e32 v76, 1, v80
	v_lshl_add_u64 v[10:11], s[20:21], 0, v[0:1]
	v_and_b32_e32 v0, 0x400, v76
	v_alignbit_b32 v118, v83, v82, 4
	v_lshrrev_b32_e32 v110, 4, v83
	v_lshl_add_u64 v[74:75], s[10:11], 0, v[0:1]
	v_and_b32_e32 v108, 0x380, v76
	v_mov_b32_e32 v109, v1
	v_mad_u64_u32 v[104:105], s[30:31], v118, s57, v[104:105]
	v_mul_lo_u32 v119, v110, s57
	v_lshl_add_u64 v[88:89], v[74:75], 0, v[108:109]
	v_lshlrev_b32_e32 v74, 2, v82
	v_add_u32_e32 v105, v119, v105
	v_and_b32_e32 v74, 0x1ffc0, v74
	v_mov_b32_e32 v75, v1
	v_lshl_add_u64 v[104:105], v[104:105], 0, v[0:1]
	v_lshl_add_u64 v[100:101], s[20:21], 0, v[74:75]
	v_lshl_add_u64 v[104:105], v[104:105], 0, v[108:109]
	global_load_dwordx4 v[2:5], v[6:7], off
	s_nop 0
	global_load_dwordx4 v[6:9], v[6:7], off offset:16
	s_nop 0
	global_load_dwordx4 v[30:33], v[10:11], off
	global_load_dwordx4 v[18:21], v[10:11], off offset:16
	global_load_dwordx4 v[14:17], v[10:11], off offset:32
	s_nop 0
	global_load_dwordx4 v[10:13], v[10:11], off offset:48
	s_nop 0
	global_load_dwordx4 v[74:77], v[100:101], off offset:48
	global_load_dwordx4 v[92:95], v[100:101], off offset:32
	global_load_dwordx4 v[96:99], v[100:101], off offset:16
	s_nop 0
	global_load_dwordx4 v[100:103], v[100:101], off
	s_nop 0
	global_load_dwordx4 v[108:111], v[104:105], off offset:16
	global_load_dwordx4 v[112:115], v[104:105], off
	s_waitcnt vmcnt(0) lgkmcnt(0)
	v_lshlrev_b32_e32 v104, 16, v108
	v_lshlrev_b32_e32 v105, 16, v112
	v_pk_mul_f32 v[116:117], v[100:101], v[104:105] op_sel:[0,1] op_sel_hi:[1,0]
	v_pk_mul_f32 v[100:101], v[100:101], v[104:105]
	v_sub_f32_e32 v0, v116, v117
	v_add_f32_e32 v116, v101, v100
	v_and_b32_e32 v101, 0xffff0000, v112
	v_and_b32_e32 v100, 0xffff0000, v108
	v_pk_mul_f32 v[104:105], v[102:103], v[100:101] op_sel:[0,1] op_sel_hi:[1,0]
	v_pk_mul_f32 v[100:101], v[102:103], v[100:101]
	v_sub_f32_e32 v104, v104, v105
	v_add_f32_e32 v105, v101, v100
	v_lshlrev_b32_e32 v101, 16, v113
	v_lshlrev_b32_e32 v100, 16, v109
	v_pk_mul_f32 v[102:103], v[96:97], v[100:101] op_sel:[0,1] op_sel_hi:[1,0]
	v_pk_mul_f32 v[96:97], v[96:97], v[100:101]
	v_sub_f32_e32 v102, v102, v103
	v_add_f32_e32 v103, v97, v96
	v_and_b32_e32 v97, 0xffff0000, v113
	v_and_b32_e32 v96, 0xffff0000, v109
	v_pk_mul_f32 v[100:101], v[98:99], v[96:97] op_sel:[0,1] op_sel_hi:[1,0]
	v_pk_mul_f32 v[96:97], v[98:99], v[96:97]
	v_sub_f32_e32 v100, v100, v101
	v_add_f32_e32 v101, v97, v96
	v_lshlrev_b32_e32 v97, 16, v114
	v_lshlrev_b32_e32 v96, 16, v110
	v_pk_mul_f32 v[98:99], v[92:93], v[96:97] op_sel:[0,1] op_sel_hi:[1,0]
	v_pk_mul_f32 v[92:93], v[92:93], v[96:97]
	v_sub_f32_e32 v98, v98, v99
	v_add_f32_e32 v99, v93, v92
	v_and_b32_e32 v93, 0xffff0000, v114
	v_and_b32_e32 v92, 0xffff0000, v110
	v_pk_mul_f32 v[96:97], v[94:95], v[92:93] op_sel:[0,1] op_sel_hi:[1,0]
	v_pk_mul_f32 v[92:93], v[94:95], v[92:93]
	v_sub_f32_e32 v108, v96, v97
	v_add_f32_e32 v109, v93, v92
	v_lshlrev_b32_e32 v93, 16, v115
	v_lshlrev_b32_e32 v92, 16, v111
	v_pk_mul_f32 v[94:95], v[74:75], v[92:93] op_sel:[0,1] op_sel_hi:[1,0]
	v_pk_mul_f32 v[74:75], v[74:75], v[92:93]
	v_sub_f32_e32 v94, v94, v95
	v_add_f32_e32 v95, v75, v74
	v_and_b32_e32 v75, 0xffff0000, v115
	v_and_b32_e32 v74, 0xffff0000, v111
	v_pk_mul_f32 v[92:93], v[76:77], v[74:75] op_sel:[0,1] op_sel_hi:[1,0]
	v_pk_mul_f32 v[74:75], v[76:77], v[74:75]
	v_mad_u64_u32 v[96:97], s[30:31], v118, s57, v[88:89]
	v_sub_f32_e32 v92, v92, v93
	v_add_f32_e32 v110, v75, v74
	v_add_u32_e32 v97, v119, v97
	v_cvt_pk_bf16_f32 v74, v0, v104
	v_cvt_pk_bf16_f32 v75, v102, v100
	v_cvt_pk_bf16_f32 v76, v98, v108
	v_cvt_pk_bf16_f32 v77, v94, v92
	v_cvt_pk_bf16_f32 v92, v116, v105
	v_cvt_pk_bf16_f32 v93, v103, v101
	v_cvt_pk_bf16_f32 v94, v99, v109
	v_cvt_pk_bf16_f32 v95, v95, v110
	global_store_dwordx4 v[96:97], v[74:77], off
	global_store_dwordx4 v[96:97], v[92:95], off offset:16
	s_and_saveexec_b64 s[30:31], s[4:5]
	s_cbranch_execnz .LBB0_874
	s_or_b64 exec, exec, s[30:31]
	s_and_saveexec_b64 s[4:5], s[2:3]
	s_cbranch_execnz .LBB0_875

; __device__ __forceinline__ unsigned cvt_pk_bf16(float lo, float hi) { unsigned r; asm volatile("v_cvt_pk_bf16_f32 %0, %1, %2" : "=v"(r) : "v"(lo), "v"(hi)); return r; }
; __device__ __forceinline__ float bflo(unsigned w) { return __uint_as_float(w << 16); }
; __device__ __forceinline__ float bfhi(unsigned w) { return __uint_as_float(w & 0xffff0000u); }
; __global__ void __launch_bounds__(512, 2) mega_fwd(Params P) {
;     ...
;                         for (int q = 0; q < 4; ++q) { const size_t idx = idx0 + (size_t)q * GT; if (idx < (size_t)T_TOK * 16) {
;                             const int row = (int)(idx >> 4), sub = (int)(idx & 15), qk = sub >> 3, hm = sub & 7;
;                             bf16_t* p = Z + (size_t)row * ZW + qk * 512 + hm * 64; float o1[8], o2[8];
; #pragma unroll
;                             for (int e = 0; e < 8; ++e) { const unsigned wa = av[q][e >> 1], wb = bv4[q][e >> 1]; const float x1 = (e & 1) ? bfhi(wa) : bflo(wa), x2 = (e & 1) ? bfhi(wb) : bflo(wb);
;                                 const float cs_ = tv[q][e >> 1][(e & 1) * 2], sn_ = tv[q][e >> 1][(e & 1) * 2 + 1]; o1[e] = x1 * cs_ - x2 * sn_; o2[e] = x1 * sn_ + x2 * cs_; }
;                             u32x4 wa, wb; wa.x = cvt_pk_bf16(o1[0], o1[1]); wa.y = cvt_pk_bf16(o1[2], o1[3]); wa.z = cvt_pk_bf16(o1[4], o1[5]); wa.w = cvt_pk_bf16(o1[6], o1[7]);
;                             wb.x = cvt_pk_bf16(o2[0], o2[1]); wb.y = cvt_pk_bf16(o2[2], o2[3]); wb.z = cvt_pk_bf16(o2[4], o2[5]); wb.w = cvt_pk_bf16(o2[6], o2[7]);
;                             *(u32x4*)p = wa; *(u32x4*)(p + 8) = wb; } }
.LBB0_874:
	v_lshlrev_b32_e32 v75, 16, v46
	v_lshlrev_b32_e32 v74, 16, v50
	v_pk_mul_f32 v[76:77], v[70:71], v[74:75] op_sel:[0,1] op_sel_hi:[1,0]
	v_pk_mul_f32 v[70:71], v[70:71], v[74:75]
	v_sub_f32_e32 v76, v76, v77
	v_add_f32_e32 v77, v71, v70
	v_and_b32_e32 v71, 0xffff0000, v46
	v_and_b32_e32 v70, 0xffff0000, v50
	v_pk_mul_f32 v[74:75], v[72:73], v[70:71] op_sel:[0,1] op_sel_hi:[1,0]
	v_pk_mul_f32 v[70:71], v[72:73], v[70:71]
	v_sub_f32_e32 v74, v74, v75
	v_add_f32_e32 v75, v71, v70
	v_lshlrev_b32_e32 v71, 16, v47
	v_and_b32_e32 v47, 0xffff0000, v47
	v_and_b32_e32 v46, 0xffff0000, v51
	v_lshlrev_b32_e32 v70, 16, v51
	v_pk_mul_f32 v[50:51], v[68:69], v[46:47] op_sel:[0,1] op_sel_hi:[1,0]
	v_pk_mul_f32 v[46:47], v[68:69], v[46:47]
	v_pk_mul_f32 v[72:73], v[66:67], v[70:71] op_sel:[0,1] op_sel_hi:[1,0]
	v_pk_mul_f32 v[66:67], v[66:67], v[70:71]
	v_add_f32_e32 v68, v47, v46
	v_lshlrev_b32_e32 v47, 16, v48
	v_lshlrev_b32_e32 v46, 16, v52
	v_add_f32_e32 v66, v67, v66
	v_sub_f32_e32 v67, v50, v51
	v_pk_mul_f32 v[50:51], v[62:63], v[46:47] op_sel:[0,1] op_sel_hi:[1,0]
	v_pk_mul_f32 v[46:47], v[62:63], v[46:47]
	v_sub_f32_e32 v69, v50, v51
	v_add_f32_e32 v62, v47, v46
	v_and_b32_e32 v47, 0xffff0000, v48
	v_and_b32_e32 v46, 0xffff0000, v52
	v_pk_mul_f32 v[50:51], v[64:65], v[46:47] op_sel:[0,1] op_sel_hi:[1,0]
	v_pk_mul_f32 v[46:47], v[64:65], v[46:47]
	v_sub_f32_e32 v52, v50, v51
	v_add_f32_e32 v63, v47, v46
	v_lshlrev_b32_e32 v47, 16, v49
	v_lshlrev_b32_e32 v46, 16, v53
	v_pk_mul_f32 v[50:51], v[58:59], v[46:47] op_sel:[0,1] op_sel_hi:[1,0]
	v_pk_mul_f32 v[46:47], v[58:59], v[46:47]
	v_alignbit_b32 v0, v91, v90, 4
	v_add_f32_e32 v64, v47, v46
	v_and_b32_e32 v47, 0xffff0000, v49
	v_and_b32_e32 v46, 0xffff0000, v53
	v_pk_mul_f32 v[48:49], v[60:61], v[46:47] op_sel:[0,1] op_sel_hi:[1,0]
	v_pk_mul_f32 v[46:47], v[60:61], v[46:47]
	v_mad_u64_u32 v[58:59], s[4:5], v0, s57, v[88:89]
	v_add_f32_e32 v53, v47, v46
	v_mov_b32_e32 v0, v59
	v_lshrrev_b32_e32 v46, 4, v91
	v_sub_f32_e32 v49, v48, v49
	v_mad_u64_u32 v[46:47], s[4:5], v46, s57, v[0:1]
	v_sub_f32_e32 v72, v72, v73
	v_sub_f32_e32 v50, v50, v51
	v_mov_b32_e32 v59, v46
	v_cvt_pk_bf16_f32 v46, v76, v74
	v_cvt_pk_bf16_f32 v47, v72, v67
	v_cvt_pk_bf16_f32 v48, v69, v52
	v_cvt_pk_bf16_f32 v49, v50, v49
	v_cvt_pk_bf16_f32 v50, v77, v75
	v_cvt_pk_bf16_f32 v51, v66, v68
	v_cvt_pk_bf16_f32 v52, v62, v63
	v_cvt_pk_bf16_f32 v53, v64, v53
	global_store_dwordx4 v[58:59], v[46:49], off
	global_store_dwordx4 v[58:59], v[50:53], off offset:16
	s_or_b64 exec, exec, s[30:31]
	s_and_saveexec_b64 s[4:5], s[2:3]
	s_cbranch_execz .LBB0_873
; __device__ __forceinline__ unsigned cvt_pk_bf16(float lo, float hi) { unsigned r; asm volatile("v_cvt_pk_bf16_f32 %0, %1, %2" : "=v"(r) : "v"(lo), "v"(hi)); return r; }
; __device__ __forceinline__ float bflo(unsigned w) { return __uint_as_float(w << 16); }
; __device__ __forceinline__ float bfhi(unsigned w) { return __uint_as_float(w & 0xffff0000u); }
; __global__ void __launch_bounds__(512, 2) mega_fwd(Params P) {
;     ...
;                         for (int q = 0; q < 4; ++q) { const size_t idx = idx0 + (size_t)q * GT; if (idx < (size_t)T_TOK * 16) {
;                             const int row = (int)(idx >> 4), sub = (int)(idx & 15), qk = sub >> 3, hm = sub & 7;
;                             bf16_t* p = Z + (size_t)row * ZW + qk * 512 + hm * 64; float o1[8], o2[8];
; #pragma unroll
;                             for (int e = 0; e < 8; ++e) { const unsigned wa = av[q][e >> 1], wb = bv4[q][e >> 1]; const float x1 = (e & 1) ? bfhi(wa) : bflo(wa), x2 = (e & 1) ? bfhi(wb) : bflo(wb);
;                                 const float cs_ = tv[q][e >> 1][(e & 1) * 2], sn_ = tv[q][e >> 1][(e & 1) * 2 + 1]; o1[e] = x1 * cs_ - x2 * sn_; o2[e] = x1 * sn_ + x2 * cs_; }
;                             u32x4 wa, wb; wa.x = cvt_pk_bf16(o1[0], o1[1]); wa.y = cvt_pk_bf16(o1[2], o1[3]); wa.z = cvt_pk_bf16(o1[4], o1[5]); wa.w = cvt_pk_bf16(o1[6], o1[7]);
;                             wb.x = cvt_pk_bf16(o2[0], o2[1]); wb.y = cvt_pk_bf16(o2[2], o2[3]); wb.z = cvt_pk_bf16(o2[4], o2[5]); wb.w = cvt_pk_bf16(o2[6], o2[7]);
;                             *(u32x4*)p = wa; *(u32x4*)(p + 8) = wb; } }
.LBB0_875:
	v_lshlrev_b32_e32 v47, 16, v22
	v_lshlrev_b32_e32 v46, 16, v26
	v_pk_mul_f32 v[48:49], v[54:55], v[46:47] op_sel:[0,1] op_sel_hi:[1,0]
	v_pk_mul_f32 v[46:47], v[54:55], v[46:47]
	v_sub_f32_e32 v50, v48, v49
	v_add_f32_e32 v51, v47, v46
	v_and_b32_e32 v47, 0xffff0000, v22
	v_and_b32_e32 v46, 0xffff0000, v26
	v_pk_mul_f32 v[48:49], v[56:57], v[46:47] op_sel:[0,1] op_sel_hi:[1,0]
	v_pk_mul_f32 v[46:47], v[56:57], v[46:47]
	v_and_b32_e32 v22, 0xffff0000, v27
	v_add_f32_e32 v53, v47, v46
	v_lshlrev_b32_e32 v47, 16, v23
	v_and_b32_e32 v23, 0xffff0000, v23
	v_lshlrev_b32_e32 v46, 16, v27
	v_pk_mul_f32 v[26:27], v[44:45], v[22:23] op_sel:[0,1] op_sel_hi:[1,0]
	v_pk_mul_f32 v[22:23], v[44:45], v[22:23]
	v_sub_f32_e32 v52, v48, v49
	v_pk_mul_f32 v[48:49], v[42:43], v[46:47] op_sel:[0,1] op_sel_hi:[1,0]
	v_pk_mul_f32 v[42:43], v[42:43], v[46:47]
	v_add_f32_e32 v44, v23, v22
	v_lshlrev_b32_e32 v23, 16, v24
	v_lshlrev_b32_e32 v22, 16, v28
	v_add_f32_e32 v42, v43, v42
	v_sub_f32_e32 v43, v26, v27
	v_pk_mul_f32 v[26:27], v[38:39], v[22:23] op_sel:[0,1] op_sel_hi:[1,0]
	v_pk_mul_f32 v[22:23], v[38:39], v[22:23]
	v_sub_f32_e32 v45, v26, v27
	v_add_f32_e32 v38, v23, v22
	v_and_b32_e32 v23, 0xffff0000, v24
	v_and_b32_e32 v22, 0xffff0000, v28
	v_pk_mul_f32 v[26:27], v[40:41], v[22:23] op_sel:[0,1] op_sel_hi:[1,0]
	v_pk_mul_f32 v[22:23], v[40:41], v[22:23]
	v_sub_f32_e32 v28, v26, v27
	v_add_f32_e32 v39, v23, v22
	v_lshlrev_b32_e32 v23, 16, v25
	v_lshlrev_b32_e32 v22, 16, v29
	v_pk_mul_f32 v[26:27], v[34:35], v[22:23] op_sel:[0,1] op_sel_hi:[1,0]
	v_pk_mul_f32 v[22:23], v[34:35], v[22:23]
	v_alignbit_b32 v0, v87, v86, 4
	v_add_f32_e32 v40, v23, v22
	v_and_b32_e32 v23, 0xffff0000, v25
	v_and_b32_e32 v22, 0xffff0000, v29
	v_pk_mul_f32 v[24:25], v[36:37], v[22:23] op_sel:[0,1] op_sel_hi:[1,0]
	v_pk_mul_f32 v[22:23], v[36:37], v[22:23]
	v_mad_u64_u32 v[34:35], s[2:3], v0, s57, v[88:89]
	v_add_f32_e32 v29, v23, v22
	v_mov_b32_e32 v0, v35
	v_lshrrev_b32_e32 v22, 4, v87
	v_sub_f32_e32 v25, v24, v25
	v_mad_u64_u32 v[22:23], s[2:3], v22, s57, v[0:1]
	v_sub_f32_e32 v48, v48, v49
	v_sub_f32_e32 v26, v26, v27
	v_mov_b32_e32 v35, v22
	v_cvt_pk_bf16_f32 v22, v50, v52
	v_cvt_pk_bf16_f32 v23, v48, v43
	v_cvt_pk_bf16_f32 v24, v45, v28
	v_cvt_pk_bf16_f32 v25, v26, v25
	v_cvt_pk_bf16_f32 v26, v51, v53
	v_cvt_pk_bf16_f32 v27, v42, v44
	v_cvt_pk_bf16_f32 v28, v38, v39
	v_cvt_pk_bf16_f32 v29, v40, v29
	global_store_dwordx4 v[34:35], v[22:25], off
	global_store_dwordx4 v[34:35], v[26:29], off offset:16
	s_or_b64 exec, exec, s[4:5]
	s_and_saveexec_b64 s[2:3], vcc
	s_cbranch_execz .LBB0_870
.LBB0_876:
	v_lshlrev_b32_e32 v23, 16, v2
	v_lshlrev_b32_e32 v22, 16, v6
	v_pk_mul_f32 v[24:25], v[30:31], v[22:23] op_sel:[0,1] op_sel_hi:[1,0]
	v_pk_mul_f32 v[22:23], v[30:31], v[22:23]
	v_sub_f32_e32 v26, v24, v25
	v_add_f32_e32 v27, v23, v22
	v_and_b32_e32 v23, 0xffff0000, v2
	v_and_b32_e32 v22, 0xffff0000, v6
	v_pk_mul_f32 v[24:25], v[32:33], v[22:23] op_sel:[0,1] op_sel_hi:[1,0]
	v_pk_mul_f32 v[22:23], v[32:33], v[22:23]
	v_and_b32_e32 v2, 0xffff0000, v7
	v_add_f32_e32 v29, v23, v22
	v_lshlrev_b32_e32 v23, 16, v3
	v_and_b32_e32 v3, 0xffff0000, v3
	v_lshlrev_b32_e32 v22, 16, v7
	v_pk_mul_f32 v[6:7], v[20:21], v[2:3] op_sel:[0,1] op_sel_hi:[1,0]
	v_pk_mul_f32 v[2:3], v[20:21], v[2:3]
	v_sub_f32_e32 v28, v24, v25
	v_pk_mul_f32 v[24:25], v[18:19], v[22:23] op_sel:[0,1] op_sel_hi:[1,0]
	v_pk_mul_f32 v[18:19], v[18:19], v[22:23]
	v_add_f32_e32 v20, v3, v2
	v_lshlrev_b32_e32 v3, 16, v4
	v_lshlrev_b32_e32 v2, 16, v8
	v_add_f32_e32 v18, v19, v18
	v_sub_f32_e32 v19, v6, v7
	v_pk_mul_f32 v[6:7], v[14:15], v[2:3] op_sel:[0,1] op_sel_hi:[1,0]
	v_pk_mul_f32 v[2:3], v[14:15], v[2:3]
	v_sub_f32_e32 v21, v6, v7
	v_add_f32_e32 v14, v3, v2
	v_and_b32_e32 v3, 0xffff0000, v4
	v_and_b32_e32 v2, 0xffff0000, v8
	v_pk_mul_f32 v[6:7], v[16:17], v[2:3] op_sel:[0,1] op_sel_hi:[1,0]
	v_pk_mul_f32 v[2:3], v[16:17], v[2:3]
	v_sub_f32_e32 v8, v6, v7
	v_add_f32_e32 v15, v3, v2
	v_lshlrev_b32_e32 v3, 16, v5
	v_lshlrev_b32_e32 v2, 16, v9
	v_pk_mul_f32 v[6:7], v[10:11], v[2:3] op_sel:[0,1] op_sel_hi:[1,0]
	v_pk_mul_f32 v[2:3], v[10:11], v[2:3]
	v_alignbit_b32 v0, v85, v84, 4
	v_add_f32_e32 v16, v3, v2
	v_and_b32_e32 v3, 0xffff0000, v5
	v_and_b32_e32 v2, 0xffff0000, v9
	v_pk_mul_f32 v[4:5], v[12:13], v[2:3] op_sel:[0,1] op_sel_hi:[1,0]
	v_pk_mul_f32 v[2:3], v[12:13], v[2:3]
	v_mad_u64_u32 v[10:11], s[4:5], v0, s57, v[88:89]
	v_add_f32_e32 v9, v3, v2
	v_mov_b32_e32 v0, v11
	v_lshrrev_b32_e32 v2, 4, v85
	v_sub_f32_e32 v5, v4, v5
	v_mad_u64_u32 v[2:3], s[4:5], v2, s57, v[0:1]
	v_sub_f32_e32 v24, v24, v25
	v_sub_f32_e32 v6, v6, v7
	v_mov_b32_e32 v11, v2
	v_cvt_pk_bf16_f32 v2, v26, v28
	v_cvt_pk_bf16_f32 v3, v24, v19
	v_cvt_pk_bf16_f32 v4, v21, v8
	v_cvt_pk_bf16_f32 v5, v6, v5
	v_cvt_pk_bf16_f32 v6, v27, v29
	v_cvt_pk_bf16_f32 v7, v18, v20
	v_cvt_pk_bf16_f32 v8, v14, v15
	v_cvt_pk_bf16_f32 v9, v16, v9
	global_store_dwordx4 v[10:11], v[2:5], off
	global_store_dwordx4 v[10:11], v[6:9], off offset:16
	s_branch .LBB0_870

; __device__ __forceinline__ unsigned cvt_pk_bf16(float lo, float hi) { unsigned r; asm volatile("v_cvt_pk_bf16_f32 %0, %1, %2" : "=v"(r) : "v"(lo), "v"(hi)); return r; }
; #define LAS __attribute__((address_space(3)))
; __global__ void __launch_bounds__(512, 2) mega_fwd(Params P) {
;     ...
;                   { LAS unsigned* CV = (LAS unsigned*)(lds + 131072); for (int i = tid; i < 5632; i += 512) CV[i] = (cvt_pk_bf16(cvk[i], 0.f) & 0xffffu) | (cvt_pk_bf16(cvk[5632 + i], 0.f) << 16);
;                     if (tid < 2) ((volatile LAS int*)(lds + 155648))[tid] = -1; __syncthreads(); }
.LBB0_881:
	v_add_co_u32_e32 v6, vcc, 0xffffa800, v4
	v_add_u32_e32 v0, 0x200, v0
	s_nop 0
	v_addc_co_u32_e32 v7, vcc, -1, v5, vcc
	global_load_dword v6, v[6:7], off
	s_waitcnt vmcnt(0) lgkmcnt(0)
	v_cvt_pk_bf16_f32 v6, v6, v1
	global_load_dword v7, v[4:5], off
	s_movk_i32 s8, 0x13ff
	v_and_b32_e32 v6, 0xffff, v6
	v_cmp_lt_i32_e32 vcc, s8, v0
	s_waitcnt vmcnt(0) lgkmcnt(0)
	v_cvt_pk_bf16_f32 v7, v7, v1
	s_or_b64 s[6:7], vcc, s[6:7]
	v_lshl_or_b32 v6, v7, 16, v6
	v_lshl_add_u64 v[4:5], v[4:5], 0, s[42:43]
	ds_write_b32 v3, v6
	v_add_u32_e32 v3, 0x800, v3
	s_andn2_b64 exec, exec, s[6:7]
	s_cbranch_execnz .LBB0_881

; #define PG8_STAGE(bufoff, gbase, voff) do { _Pragma("unroll") for (int _i = 0; _i < 2; ++_i) \
;         __builtin_amdgcn_global_load_lds((const unsigned*)((const char*)(gbase) + (voff)[_i]), (PG8_LAS unsigned*)(lds + (bufoff) + ldsw + _i * 8192), 16, 0, 0); } while (0)
; #define PG8_LDA(dst, b, h) do { _Pragma("unroll") for (int m = 0; m < 4; ++m) _Pragma("unroll") for (int k = 0; k < 2; ++k) dst[m][k] = *(const PG8_LAS bf16x8*)(lds + PG8_SA(b, h) + aoff + m * 2048 + k * 1024); } while (0)
; #define PG8_LDB(dst, b, h) do { _Pragma("unroll") for (int n = 0; n < 2; ++n) _Pragma("unroll") for (int k = 0; k < 2; ++k) dst[n][k] = *(const PG8_LAS bf16x8*)(lds + PG8_SB(b, h) + boff + n * 2048 + k * 1024); } while (0)
; #define PG8_MMA(ai, bj, At, Bt) do { __builtin_amdgcn_s_setprio(1); _Pragma("unroll") for (int m = 0; m < 4; ++m) _Pragma("unroll") for (int n = 0; n < 2; ++n) _Pragma("unroll") for (int k = 0; k < 2; ++k) \
;         acc[ai][bj][m][n] = __builtin_amdgcn_mfma_f32_16x16x32_bf16(Bt[n][k], At[m][k], acc[ai][bj][m][n], 0, 0, 0); __builtin_amdgcn_s_setprio(0); } while (0)
; #define PG8_WAIT_V(n) asm volatile("s_waitcnt vmcnt(" #n ")" ::: "memory")
; template <class Epi, class Sched, bool ALIGN_EPI = false, bool SP2 = false>
; __device__ __forceinline__ void gemm_phase(PG8_LAS unsigned char* lds, const Gemm g, const Sched& S, const Epi& E) {
;     ...
;             PG8_LDB(B0, 0, 0); PG8_LDB(B1, 0, 1); PG8_SCHED; PG8_LDA(At, 0, 0); PG8_STAGE(PG8_SA(1, 1), a1 + hstep, voffA);
;             PG8_WAIT_V(8); PG8_WAIT_L(0); PG8_BAR; PG8_MMA(0, 0, At, B0); PG8_MMA(0, 1, At, B1); PG8_BAR; PG8_SCHED;
;             PG8_LDA(At, 0, 1); PG8_STAGE(PG8_SB(0, 0), b2, voffB); PG8_STAGE(PG8_SB(0, 1), b2 + hstep, voffB); PG8_STAGE(PG8_SA(0, 0), a2, voffA);
;             PG8_WAIT_V(8); PG8_WAIT_L(0); PG8_BAR; PG8_MMA(1, 0, At, B0); PG8_MMA(1, 1, At, B1); PG8_BAR; PG8_SCHED;
;             PG8_LDB(B0, 1, 0); PG8_LDB(B1, 1, 1); PG8_SCHED; PG8_LDA(At, 1, 0); PG8_STAGE(PG8_SA(0, 1), a2 + hstep, voffA);
;             PG8_WAIT_V(8); PG8_WAIT_L(0); PG8_BAR; PG8_MMA(0, 0, At, B0); PG8_MMA(0, 1, At, B1); PG8_BAR; PG8_SCHED;
;             PG8_LDA(At, 1, 1); PG8_STAGE(PG8_SB(1, 0), b3, voffB); PG8_STAGE(PG8_SB(1, 1), b3 + hstep, voffB); PG8_STAGE(PG8_SA(1, 0), a3, voffA);
;             PG8_WAIT_V(8); PG8_WAIT_L(0); PG8_BAR; PG8_MMA(1, 0, At, B0); PG8_MMA(1, 1, At, B1); PG8_BAR; PG8_SCHED;
.LBB0_898:
	s_add_i32 s67, s30, 2
	s_add_u32 s74, s28, 0x80
	s_addc_u32 s31, s29, 0
	s_add_i32 s76, 0, 0x10000
	s_cmp_eq_u32 s48, s30
	s_cselect_b32 s31, s5, s31
	s_cselect_b32 s30, s4, s74
	v_add_u32_e32 v0, s76, v185
	s_cselect_b32 s75, s27, s63
	s_cselect_b32 s74, s26, s62
	s_add_i32 s77, 0, 0x14000
	ds_read_b128 v[106:109], v0
	ds_read_b128 v[134:137], v0 offset:1024
	ds_read_b128 v[138:141], v0 offset:2048
	ds_read_b128 v[142:145], v0 offset:3072
	v_add_u32_e32 v0, s77, v185
	ds_read_b128 v[146:149], v0
	ds_read_b128 v[150:153], v0 offset:1024
	ds_read_b128 v[168:171], v0 offset:2048
	ds_read_b128 v[172:175], v0 offset:3072
	v_lshl_add_u64 v[208:209], s[28:29], 0, v[164:165]
	s_add_i32 m0, s41, 0xc000
	ds_read_b128 v[176:179], v203
	ds_read_b128 v[180:183], v203 offset:1024
	ds_read_b128 v[204:207], v203 offset:2048
	ds_read_b128 v[226:229], v203 offset:3072
	ds_read_b128 v[230:233], v203 offset:4096
	ds_read_b128 v[234:237], v203 offset:5120
	ds_read_b128 v[238:241], v203 offset:6144
	ds_read_b128 v[242:245], v203 offset:7168
	global_load_lds_dwordx4 v[208:209], off
	v_lshl_add_u64 v[208:209], s[28:29], 0, v[162:163]
	s_add_i32 m0, s41, 0xe000
	s_nop 0
	global_load_lds_dwordx4 v[208:209], off
	s_waitcnt vmcnt(8)
	s_waitcnt lgkmcnt(0)
	s_barrier
	s_setprio 1
	v_mfma_f32_16x16x32_bf16 v[126:129], v[106:109], v[176:179], v[126:129]
	v_mfma_f32_16x16x32_bf16 v[118:121], v[138:141], v[176:179], v[118:121]
	v_mfma_f32_16x16x32_bf16 v[110:113], v[106:109], v[204:207], v[110:113]
	v_mfma_f32_16x16x32_bf16 v[98:101], v[138:141], v[204:207], v[98:101]
	v_mfma_f32_16x16x32_bf16 v[90:93], v[106:109], v[230:233], v[90:93]
	v_mfma_f32_16x16x32_bf16 v[82:85], v[138:141], v[230:233], v[82:85]
	v_mfma_f32_16x16x32_bf16 v[74:77], v[106:109], v[238:241], v[74:77]
	v_mfma_f32_16x16x32_bf16 v[66:69], v[138:141], v[238:241], v[66:69]
	v_mfma_f32_16x16x32_bf16 v[126:129], v[134:137], v[180:183], v[126:129]
	v_mfma_f32_16x16x32_bf16 v[118:121], v[142:145], v[180:183], v[118:121]
	v_mfma_f32_16x16x32_bf16 v[110:113], v[134:137], v[226:229], v[110:113]
	v_mfma_f32_16x16x32_bf16 v[98:101], v[142:145], v[226:229], v[98:101]
	v_mfma_f32_16x16x32_bf16 v[90:93], v[134:137], v[234:237], v[90:93]
	v_mfma_f32_16x16x32_bf16 v[82:85], v[142:145], v[234:237], v[82:85]
	v_mfma_f32_16x16x32_bf16 v[74:77], v[134:137], v[242:245], v[74:77]
	v_mfma_f32_16x16x32_bf16 v[66:69], v[142:145], v[242:245], v[66:69]
	s_setprio 0
	s_setprio 1
	v_mfma_f32_16x16x32_bf16 v[130:133], v[146:149], v[176:179], v[130:133]
	v_mfma_f32_16x16x32_bf16 v[122:125], v[168:171], v[176:179], v[122:125]
	v_mfma_f32_16x16x32_bf16 v[114:117], v[146:149], v[204:207], v[114:117]
	v_mfma_f32_16x16x32_bf16 v[102:105], v[168:171], v[204:207], v[102:105]
	v_mfma_f32_16x16x32_bf16 v[94:97], v[146:149], v[230:233], v[94:97]
	v_mfma_f32_16x16x32_bf16 v[86:89], v[168:171], v[230:233], v[86:89]
	v_mfma_f32_16x16x32_bf16 v[78:81], v[146:149], v[238:241], v[78:81]
	v_mfma_f32_16x16x32_bf16 v[70:73], v[168:171], v[238:241], v[70:73]
	v_mfma_f32_16x16x32_bf16 v[130:133], v[150:153], v[180:183], v[130:133]
	v_mfma_f32_16x16x32_bf16 v[122:125], v[172:175], v[180:183], v[122:125]
	v_mfma_f32_16x16x32_bf16 v[114:117], v[150:153], v[226:229], v[114:117]
	v_mfma_f32_16x16x32_bf16 v[102:105], v[172:175], v[226:229], v[102:105]
	v_mfma_f32_16x16x32_bf16 v[94:97], v[150:153], v[234:237], v[94:97]
	v_mfma_f32_16x16x32_bf16 v[86:89], v[172:175], v[234:237], v[86:89]
	v_mfma_f32_16x16x32_bf16 v[78:81], v[150:153], v[242:245], v[78:81]
	v_mfma_f32_16x16x32_bf16 v[70:73], v[172:175], v[242:245], v[70:73]
	s_setprio 0
	s_barrier
	s_add_i32 s76, s76, s34
	v_lshl_add_u64 v[208:209], s[74:75], 0, v[158:159]
	s_mov_b32 m0, s76
	ds_read_b128 v[176:179], v203 offset:16384
	ds_read_b128 v[180:183], v203 offset:17408
	ds_read_b128 v[204:207], v203 offset:18432
	ds_read_b128 v[226:229], v203 offset:19456
	ds_read_b128 v[230:233], v203 offset:20480
	ds_read_b128 v[234:237], v203 offset:21504
	ds_read_b128 v[238:241], v203 offset:22528
	ds_read_b128 v[242:245], v203 offset:23552
	global_load_lds_dwordx4 v[208:209], off
	s_add_i32 m0, s76, 0x2000
	v_lshl_add_u64 v[212:213], s[74:75], 0, v[154:155]
	s_add_u32 s74, s74, s12
	s_addc_u32 s75, s75, s13
	s_add_i32 s76, s77, s34
	global_load_lds_dwordx4 v[212:213], off
	v_lshl_add_u64 v[214:215], s[74:75], 0, v[158:159]
	s_mov_b32 m0, s76
	v_lshl_add_u64 v[216:217], s[74:75], 0, v[154:155]
	global_load_lds_dwordx4 v[214:215], off
	s_add_i32 m0, s76, 0x2000
	v_lshl_add_u64 v[246:247], s[30:31], 0, v[160:161]
	global_load_lds_dwordx4 v[216:217], off
	s_mov_b32 m0, s41
	v_lshl_add_u64 v[248:249], s[30:31], 0, v[156:157]
	global_load_lds_dwordx4 v[246:247], off
	s_mov_b32 m0, s42
	s_nop 0
	global_load_lds_dwordx4 v[248:249], off
	s_waitcnt vmcnt(8)
	s_waitcnt lgkmcnt(0)
	s_barrier
; #define PG8_STAGE(bufoff, gbase, voff) do { _Pragma("unroll") for (int _i = 0; _i < 2; ++_i) \
;         __builtin_amdgcn_global_load_lds((const unsigned*)((const char*)(gbase) + (voff)[_i]), (PG8_LAS unsigned*)(lds + (bufoff) + ldsw + _i * 8192), 16, 0, 0); } while (0)
; #define PG8_LDA(dst, b, h) do { _Pragma("unroll") for (int m = 0; m < 4; ++m) _Pragma("unroll") for (int k = 0; k < 2; ++k) dst[m][k] = *(const PG8_LAS bf16x8*)(lds + PG8_SA(b, h) + aoff + m * 2048 + k * 1024); } while (0)
; #define PG8_LDB(dst, b, h) do { _Pragma("unroll") for (int n = 0; n < 2; ++n) _Pragma("unroll") for (int k = 0; k < 2; ++k) dst[n][k] = *(const PG8_LAS bf16x8*)(lds + PG8_SB(b, h) + boff + n * 2048 + k * 1024); } while (0)
; #define PG8_MMA(ai, bj, At, Bt) do { __builtin_amdgcn_s_setprio(1); _Pragma("unroll") for (int m = 0; m < 4; ++m) _Pragma("unroll") for (int n = 0; n < 2; ++n) _Pragma("unroll") for (int k = 0; k < 2; ++k) \
;         acc[ai][bj][m][n] = __builtin_amdgcn_mfma_f32_16x16x32_bf16(Bt[n][k], At[m][k], acc[ai][bj][m][n], 0, 0, 0); __builtin_amdgcn_s_setprio(0); } while (0)
; #define PG8_WAIT_V(n) asm volatile("s_waitcnt vmcnt(" #n ")" ::: "memory")
; template <class Epi, class Sched, bool ALIGN_EPI = false, bool SP2 = false>
; __device__ __forceinline__ void gemm_phase(PG8_LAS unsigned char* lds, const Gemm g, const Sched& S, const Epi& E) {
;     ...
;             PG8_LDB(B0, 0, 0); PG8_LDB(B1, 0, 1); PG8_SCHED; PG8_LDA(At, 0, 0); PG8_STAGE(PG8_SA(1, 1), a1 + hstep, voffA);
;             PG8_WAIT_V(8); PG8_WAIT_L(0); PG8_BAR; PG8_MMA(0, 0, At, B0); PG8_MMA(0, 1, At, B1); PG8_BAR; PG8_SCHED;
;             PG8_LDA(At, 0, 1); PG8_STAGE(PG8_SB(0, 0), b2, voffB); PG8_STAGE(PG8_SB(0, 1), b2 + hstep, voffB); PG8_STAGE(PG8_SA(0, 0), a2, voffA);
;             PG8_WAIT_V(8); PG8_WAIT_L(0); PG8_BAR; PG8_MMA(1, 0, At, B0); PG8_MMA(1, 1, At, B1); PG8_BAR; PG8_SCHED;
;             PG8_LDB(B0, 1, 0); PG8_LDB(B1, 1, 1); PG8_SCHED; PG8_LDA(At, 1, 0); PG8_STAGE(PG8_SA(0, 1), a2 + hstep, voffA);
;             PG8_WAIT_V(8); PG8_WAIT_L(0); PG8_BAR; PG8_MMA(0, 0, At, B0); PG8_MMA(0, 1, At, B1); PG8_BAR; PG8_SCHED;
;             PG8_LDA(At, 1, 1); PG8_STAGE(PG8_SB(1, 0), b3, voffB); PG8_STAGE(PG8_SB(1, 1), b3 + hstep, voffB); PG8_STAGE(PG8_SA(1, 0), a3, voffA);
;             PG8_WAIT_V(8); PG8_WAIT_L(0); PG8_BAR; PG8_MMA(1, 0, At, B0); PG8_MMA(1, 1, At, B1); PG8_BAR; PG8_SCHED;
	s_setprio 1
	v_mfma_f32_16x16x32_bf16 v[58:61], v[106:109], v[176:179], v[58:61]
	v_mfma_f32_16x16x32_bf16 v[50:53], v[138:141], v[176:179], v[50:53]
	v_mfma_f32_16x16x32_bf16 v[42:45], v[106:109], v[204:207], v[42:45]
	v_mfma_f32_16x16x32_bf16 v[34:37], v[138:141], v[204:207], v[34:37]
	v_mfma_f32_16x16x32_bf16 v[26:29], v[106:109], v[230:233], v[26:29]
	v_mfma_f32_16x16x32_bf16 v[18:21], v[138:141], v[230:233], v[18:21]
	v_mfma_f32_16x16x32_bf16 v[10:13], v[106:109], v[238:241], v[10:13]
	v_mfma_f32_16x16x32_bf16 v[6:9], v[138:141], v[238:241], v[6:9]
	v_mfma_f32_16x16x32_bf16 v[58:61], v[134:137], v[180:183], v[58:61]
	v_mfma_f32_16x16x32_bf16 v[50:53], v[142:145], v[180:183], v[50:53]
	v_mfma_f32_16x16x32_bf16 v[42:45], v[134:137], v[226:229], v[42:45]
	v_mfma_f32_16x16x32_bf16 v[34:37], v[142:145], v[226:229], v[34:37]
	v_mfma_f32_16x16x32_bf16 v[26:29], v[134:137], v[234:237], v[26:29]
	v_mfma_f32_16x16x32_bf16 v[18:21], v[142:145], v[234:237], v[18:21]
	v_mfma_f32_16x16x32_bf16 v[10:13], v[134:137], v[242:245], v[10:13]
	v_mfma_f32_16x16x32_bf16 v[6:9], v[142:145], v[242:245], v[6:9]
	s_setprio 0
	s_setprio 1
	v_mfma_f32_16x16x32_bf16 v[62:65], v[146:149], v[176:179], v[62:65]
	v_mfma_f32_16x16x32_bf16 v[54:57], v[168:171], v[176:179], v[54:57]
	v_mfma_f32_16x16x32_bf16 v[46:49], v[146:149], v[204:207], v[46:49]
	v_mfma_f32_16x16x32_bf16 v[38:41], v[168:171], v[204:207], v[38:41]
	v_mfma_f32_16x16x32_bf16 v[30:33], v[146:149], v[230:233], v[30:33]
	v_mfma_f32_16x16x32_bf16 v[22:25], v[168:171], v[230:233], v[22:25]
	v_mfma_f32_16x16x32_bf16 v[14:17], v[146:149], v[238:241], v[14:17]
	v_mfma_f32_16x16x32_bf16 v[2:5], v[168:171], v[238:241], v[2:5]
	v_mfma_f32_16x16x32_bf16 v[62:65], v[150:153], v[180:183], v[62:65]
	v_mfma_f32_16x16x32_bf16 v[54:57], v[172:175], v[180:183], v[54:57]
	v_mfma_f32_16x16x32_bf16 v[46:49], v[150:153], v[226:229], v[46:49]
	v_mfma_f32_16x16x32_bf16 v[38:41], v[172:175], v[226:229], v[38:41]
	v_mfma_f32_16x16x32_bf16 v[30:33], v[150:153], v[234:237], v[30:33]
	v_mfma_f32_16x16x32_bf16 v[22:25], v[172:175], v[234:237], v[22:25]
	v_mfma_f32_16x16x32_bf16 v[14:17], v[150:153], v[242:245], v[14:17]
	v_mfma_f32_16x16x32_bf16 v[2:5], v[172:175], v[242:245], v[2:5]
	s_setprio 0
	s_barrier
	s_add_i32 s74, 0, 0x18000
	v_add_u32_e32 v0, s74, v185
	s_add_i32 s75, 0, 0x1c000
	ds_read_b128 v[106:109], v0
	ds_read_b128 v[134:137], v0 offset:1024
	ds_read_b128 v[138:141], v0 offset:2048
	ds_read_b128 v[142:145], v0 offset:3072
	v_add_u32_e32 v0, s75, v185
	ds_read_b128 v[146:149], v0
	ds_read_b128 v[150:153], v0 offset:1024
	ds_read_b128 v[168:171], v0 offset:2048
	ds_read_b128 v[172:175], v0 offset:3072
	s_add_u32 s30, s30, s12
	s_addc_u32 s31, s31, s13
	s_mov_b32 m0, s43
	v_lshl_add_u64 v[250:251], s[30:31], 0, v[160:161]
	ds_read_b128 v[176:179], v203 offset:32768
	ds_read_b128 v[180:183], v203 offset:33792
	ds_read_b128 v[204:207], v203 offset:34816
	ds_read_b128 v[226:229], v203 offset:35840
	ds_read_b128 v[230:233], v203 offset:36864
	ds_read_b128 v[234:237], v203 offset:37888
	ds_read_b128 v[238:241], v203 offset:38912
	ds_read_b128 v[242:245], v203 offset:39936
	global_load_lds_dwordx4 v[250:251], off
	v_lshl_add_u64 v[250:251], s[30:31], 0, v[156:157]
	s_mov_b32 m0, s44
	s_nop 0
	global_load_lds_dwordx4 v[250:251], off
	s_waitcnt vmcnt(8)
	s_waitcnt lgkmcnt(0)
	s_barrier
	s_setprio 1
	v_mfma_f32_16x16x32_bf16 v[126:129], v[106:109], v[176:179], v[126:129]
	v_mfma_f32_16x16x32_bf16 v[118:121], v[138:141], v[176:179], v[118:121]
	v_mfma_f32_16x16x32_bf16 v[110:113], v[106:109], v[204:207], v[110:113]
	v_mfma_f32_16x16x32_bf16 v[98:101], v[138:141], v[204:207], v[98:101]
	v_mfma_f32_16x16x32_bf16 v[90:93], v[106:109], v[230:233], v[90:93]
	v_mfma_f32_16x16x32_bf16 v[82:85], v[138:141], v[230:233], v[82:85]
	v_mfma_f32_16x16x32_bf16 v[74:77], v[106:109], v[238:241], v[74:77]
	v_mfma_f32_16x16x32_bf16 v[66:69], v[138:141], v[238:241], v[66:69]
	v_mfma_f32_16x16x32_bf16 v[126:129], v[134:137], v[180:183], v[126:129]
	v_mfma_f32_16x16x32_bf16 v[118:121], v[142:145], v[180:183], v[118:121]
	v_mfma_f32_16x16x32_bf16 v[110:113], v[134:137], v[226:229], v[110:113]
	v_mfma_f32_16x16x32_bf16 v[98:101], v[142:145], v[226:229], v[98:101]
	v_mfma_f32_16x16x32_bf16 v[90:93], v[134:137], v[234:237], v[90:93]
	v_mfma_f32_16x16x32_bf16 v[82:85], v[142:145], v[234:237], v[82:85]
	v_mfma_f32_16x16x32_bf16 v[74:77], v[134:137], v[242:245], v[74:77]
	v_mfma_f32_16x16x32_bf16 v[66:69], v[142:145], v[242:245], v[66:69]
	s_setprio 0
	s_setprio 1
	v_mfma_f32_16x16x32_bf16 v[130:133], v[146:149], v[176:179], v[130:133]
	v_mfma_f32_16x16x32_bf16 v[122:125], v[168:171], v[176:179], v[122:125]
	v_mfma_f32_16x16x32_bf16 v[114:117], v[146:149], v[204:207], v[114:117]
	v_mfma_f32_16x16x32_bf16 v[102:105], v[168:171], v[204:207], v[102:105]
	v_mfma_f32_16x16x32_bf16 v[94:97], v[146:149], v[230:233], v[94:97]
	v_mfma_f32_16x16x32_bf16 v[86:89], v[168:171], v[230:233], v[86:89]
	v_mfma_f32_16x16x32_bf16 v[78:81], v[146:149], v[238:241], v[78:81]
	v_mfma_f32_16x16x32_bf16 v[70:73], v[168:171], v[238:241], v[70:73]
	v_mfma_f32_16x16x32_bf16 v[130:133], v[150:153], v[180:183], v[130:133]
	v_mfma_f32_16x16x32_bf16 v[122:125], v[172:175], v[180:183], v[122:125]
	v_mfma_f32_16x16x32_bf16 v[114:117], v[150:153], v[226:229], v[114:117]
	v_mfma_f32_16x16x32_bf16 v[102:105], v[172:175], v[226:229], v[102:105]
	v_mfma_f32_16x16x32_bf16 v[94:97], v[150:153], v[234:237], v[94:97]
	v_mfma_f32_16x16x32_bf16 v[86:89], v[172:175], v[234:237], v[86:89]
	v_mfma_f32_16x16x32_bf16 v[78:81], v[150:153], v[242:245], v[78:81]
	v_mfma_f32_16x16x32_bf16 v[70:73], v[172:175], v[242:245], v[70:73]
	s_setprio 0
	s_barrier
; #define PG8_STAGE(bufoff, gbase, voff) do { _Pragma("unroll") for (int _i = 0; _i < 2; ++_i) \
;         __builtin_amdgcn_global_load_lds((const unsigned*)((const char*)(gbase) + (voff)[_i]), (PG8_LAS unsigned*)(lds + (bufoff) + ldsw + _i * 8192), 16, 0, 0); } while (0)
; #define PG8_LDA(dst, b, h) do { _Pragma("unroll") for (int m = 0; m < 4; ++m) _Pragma("unroll") for (int k = 0; k < 2; ++k) dst[m][k] = *(const PG8_LAS bf16x8*)(lds + PG8_SA(b, h) + aoff + m * 2048 + k * 1024); } while (0)
; #define PG8_LDB(dst, b, h) do { _Pragma("unroll") for (int n = 0; n < 2; ++n) _Pragma("unroll") for (int k = 0; k < 2; ++k) dst[n][k] = *(const PG8_LAS bf16x8*)(lds + PG8_SB(b, h) + boff + n * 2048 + k * 1024); } while (0)
; #define PG8_MMA(ai, bj, At, Bt) do { __builtin_amdgcn_s_setprio(1); _Pragma("unroll") for (int m = 0; m < 4; ++m) _Pragma("unroll") for (int n = 0; n < 2; ++n) _Pragma("unroll") for (int k = 0; k < 2; ++k) \
;         acc[ai][bj][m][n] = __builtin_amdgcn_mfma_f32_16x16x32_bf16(Bt[n][k], At[m][k], acc[ai][bj][m][n], 0, 0, 0); __builtin_amdgcn_s_setprio(0); } while (0)
; #define PG8_WAIT_V(n) asm volatile("s_waitcnt vmcnt(" #n ")" ::: "memory")
; template <class Epi, class Sched, bool ALIGN_EPI = false, bool SP2 = false>
; __device__ __forceinline__ void gemm_phase(PG8_LAS unsigned char* lds, const Gemm g, const Sched& S, const Epi& E) {
;     ...
;             PG8_LDB(B0, 0, 0); PG8_LDB(B1, 0, 1); PG8_SCHED; PG8_LDA(At, 0, 0); PG8_STAGE(PG8_SA(1, 1), a1 + hstep, voffA);
;             PG8_WAIT_V(8); PG8_WAIT_L(0); PG8_BAR; PG8_MMA(0, 0, At, B0); PG8_MMA(0, 1, At, B1); PG8_BAR; PG8_SCHED;
;             PG8_LDA(At, 0, 1); PG8_STAGE(PG8_SB(0, 0), b2, voffB); PG8_STAGE(PG8_SB(0, 1), b2 + hstep, voffB); PG8_STAGE(PG8_SA(0, 0), a2, voffA);
;             PG8_WAIT_V(8); PG8_WAIT_L(0); PG8_BAR; PG8_MMA(1, 0, At, B0); PG8_MMA(1, 1, At, B1); PG8_BAR; PG8_SCHED;
;             PG8_LDB(B0, 1, 0); PG8_LDB(B1, 1, 1); PG8_SCHED; PG8_LDA(At, 1, 0); PG8_STAGE(PG8_SA(0, 1), a2 + hstep, voffA);
;             PG8_WAIT_V(8); PG8_WAIT_L(0); PG8_BAR; PG8_MMA(0, 0, At, B0); PG8_MMA(0, 1, At, B1); PG8_BAR; PG8_SCHED;
;             PG8_LDA(At, 1, 1); PG8_STAGE(PG8_SB(1, 0), b3, voffB); PG8_STAGE(PG8_SB(1, 1), b3 + hstep, voffB); PG8_STAGE(PG8_SA(1, 0), a3, voffA);
;             PG8_WAIT_V(8); PG8_WAIT_L(0); PG8_BAR; PG8_MMA(1, 0, At, B0); PG8_MMA(1, 1, At, B1); PG8_BAR; PG8_SCHED;
	s_add_i32 s30, s74, s34
	v_lshl_add_u64 v[208:209], v[208:209], 0, s[38:39]
	s_mov_b32 m0, s30
	ds_read_b128 v[176:179], v203 offset:49152
	ds_read_b128 v[180:183], v203 offset:50176
	ds_read_b128 v[204:207], v203 offset:51200
	ds_read_b128 v[226:229], v203 offset:52224
	ds_read_b128 v[230:233], v203 offset:53248
	ds_read_b128 v[234:237], v203 offset:54272
	ds_read_b128 v[238:241], v203 offset:55296
	ds_read_b128 v[242:245], v203 offset:56320
	global_load_lds_dwordx4 v[208:209], off
	v_lshl_add_u64 v[208:209], v[212:213], 0, s[38:39]
	s_add_i32 m0, s30, 0x2000
	s_add_i32 s30, s75, s34
	global_load_lds_dwordx4 v[208:209], off
	v_lshl_add_u64 v[208:209], v[214:215], 0, s[38:39]
	s_mov_b32 m0, s30
	s_nop 0
	global_load_lds_dwordx4 v[208:209], off
	v_lshl_add_u64 v[208:209], v[216:217], 0, s[38:39]
	s_add_i32 m0, s30, 0x2000
	s_nop 0
	global_load_lds_dwordx4 v[208:209], off
	v_lshl_add_u64 v[208:209], v[246:247], 0, s[38:39]
	s_mov_b32 m0, s46
	s_nop 0
	global_load_lds_dwordx4 v[208:209], off
	v_lshl_add_u64 v[208:209], v[248:249], 0, s[38:39]
	s_mov_b32 m0, s47
	s_nop 0
	global_load_lds_dwordx4 v[208:209], off
	s_waitcnt vmcnt(8)
	s_waitcnt lgkmcnt(0)
	s_barrier
	s_setprio 1
	v_mfma_f32_16x16x32_bf16 v[58:61], v[106:109], v[176:179], v[58:61]
	v_mfma_f32_16x16x32_bf16 v[50:53], v[138:141], v[176:179], v[50:53]
	v_mfma_f32_16x16x32_bf16 v[42:45], v[106:109], v[204:207], v[42:45]
	v_mfma_f32_16x16x32_bf16 v[34:37], v[138:141], v[204:207], v[34:37]
	v_mfma_f32_16x16x32_bf16 v[26:29], v[106:109], v[230:233], v[26:29]
	v_mfma_f32_16x16x32_bf16 v[18:21], v[138:141], v[230:233], v[18:21]
	v_mfma_f32_16x16x32_bf16 v[10:13], v[106:109], v[238:241], v[10:13]
	v_mfma_f32_16x16x32_bf16 v[6:9], v[138:141], v[238:241], v[6:9]
	v_mfma_f32_16x16x32_bf16 v[58:61], v[134:137], v[180:183], v[58:61]
	v_mfma_f32_16x16x32_bf16 v[50:53], v[142:145], v[180:183], v[50:53]
	v_mfma_f32_16x16x32_bf16 v[42:45], v[134:137], v[226:229], v[42:45]
	v_mfma_f32_16x16x32_bf16 v[34:37], v[142:145], v[226:229], v[34:37]
	v_mfma_f32_16x16x32_bf16 v[26:29], v[134:137], v[234:237], v[26:29]
	v_mfma_f32_16x16x32_bf16 v[18:21], v[142:145], v[234:237], v[18:21]
	v_mfma_f32_16x16x32_bf16 v[10:13], v[134:137], v[242:245], v[10:13]
	v_mfma_f32_16x16x32_bf16 v[6:9], v[142:145], v[242:245], v[6:9]
	s_setprio 0
	s_setprio 1
	v_mfma_f32_16x16x32_bf16 v[62:65], v[146:149], v[176:179], v[62:65]
	v_mfma_f32_16x16x32_bf16 v[54:57], v[168:171], v[176:179], v[54:57]
	v_mfma_f32_16x16x32_bf16 v[46:49], v[146:149], v[204:207], v[46:49]
	v_mfma_f32_16x16x32_bf16 v[38:41], v[168:171], v[204:207], v[38:41]
	v_mfma_f32_16x16x32_bf16 v[30:33], v[146:149], v[230:233], v[30:33]
	v_mfma_f32_16x16x32_bf16 v[22:25], v[168:171], v[230:233], v[22:25]
	v_mfma_f32_16x16x32_bf16 v[14:17], v[146:149], v[238:241], v[14:17]
	v_mfma_f32_16x16x32_bf16 v[2:5], v[168:171], v[238:241], v[2:5]
	v_mfma_f32_16x16x32_bf16 v[62:65], v[150:153], v[180:183], v[62:65]
	v_mfma_f32_16x16x32_bf16 v[54:57], v[172:175], v[180:183], v[54:57]
	v_mfma_f32_16x16x32_bf16 v[46:49], v[150:153], v[226:229], v[46:49]
	v_mfma_f32_16x16x32_bf16 v[38:41], v[172:175], v[226:229], v[38:41]
	v_mfma_f32_16x16x32_bf16 v[30:33], v[150:153], v[234:237], v[30:33]
	v_mfma_f32_16x16x32_bf16 v[22:25], v[172:175], v[234:237], v[22:25]
	v_mfma_f32_16x16x32_bf16 v[14:17], v[150:153], v[242:245], v[14:17]
	v_mfma_f32_16x16x32_bf16 v[2:5], v[172:175], v[242:245], v[2:5]
	s_setprio 0
	s_barrier
	s_add_u32 s62, s62, 0x100
	s_addc_u32 s63, s63, 0
	s_add_u32 s28, s28, 0x100
	s_addc_u32 s29, s29, 0
	s_cmp_ge_i32 s67, s45
	s_mov_b32 s30, s67
	s_cbranch_scc0 .LBB0_898
	s_mov_b64 s[76:77], 0x28000

; #define PG8_LAS __attribute__((address_space(3)))
;     __device__ __forceinline__ void operator()(const f32x4 (&acc)[2][2][4][2], const Unit& u, int wr, int wc, int fr, int fq, PG8_LAS unsigned char* ldsb) const {
;         const int row0 = u.pm * BM + wr * 64 + fr; const int col0 = u.pn * HALF + wc * 32 + 8 * fq;
;         const int brow = u.pn * BM + wc * 32 + 8 * fq;
;         const PG8_LAS unsigned* CV = (const PG8_LAS unsigned*)(ldsb + 131072);
;         PG8_LAS f32x2* ST = (PG8_LAS f32x2*)(ldsb + 153600);
;         volatile PG8_LAS int* TAG = (volatile PG8_LAS int*)(ldsb + 155648);
;         float rsv[2][4], msv[2][4];
;         if (TAG[wr] != u.pm) {
.LBB0_902:
	v_mov_b32_e32 v0, s49
	ds_read_b32 v0, v0
	v_lshl_add_u32 v168, s61, 8, v167
	s_mov_b64 s[28:29], -1
	v_or_b32_e32 v146, 16, v168
	v_or_b32_e32 v147, 32, v168
	s_waitcnt lgkmcnt(0)
	v_cmp_eq_u32_e32 vcc, s61, v0
	s_and_b64 vcc, exec, vcc
	v_or_b32_e32 v148, 48, v168
	v_add_u32_e32 v149, 0x80, v168
	v_add_u32_e32 v150, 0x90, v168
	v_add_u32_e32 v151, 0xa0, v168
	v_add_u32_e32 v152, 0xb0, v168
	s_cbranch_vccnz .LBB0_904
; __device__ __forceinline__ float xsum_rows(float v) { return xsum32(xsum16(v)); }
; __device__ __forceinline__ void ln_row(const float* st, int row, int fq, float& rs, float& ms) {
;     f32x2 v = *(const f32x2*)(st + (unsigned)(8 * row + 2 * fq));
;     v.x = xsum_rows(v.x); v.y = xsum_rows(v.y);
;     const float mean = v.x * (1.0f / 1024.0f); const float var = v.y * (1.0f / 1024.0f) - mean * mean;
;     rs = __builtin_amdgcn_rsqf(var + 1e-5f); ms = rs * mean;
; }
;     __device__ __forceinline__ void operator()(const f32x4 (&acc)[2][2][4][2], const Unit& u, int wr, int wc, int fr, int fq, PG8_LAS unsigned char* ldsb) const {
;     ...
;         if (TAG[wr] != u.pm) {
; #pragma unroll
;             for (int ai = 0; ai < 2; ++ai)
; #pragma unroll
;                 for (int m = 0; m < 4; ++m) { ln_row(ln.st, row0 + ai * HALF + m * 16, fq, rsv[ai][m], msv[ai][m]);
;                     f32x2 pr; pr.x = rsv[ai][m]; pr.y = msv[ai][m]; ST[ai * HALF + wr * 64 + m * 16 + fr] = pr; }
;             asm volatile("s_waitcnt lgkmcnt(0)" ::: "memory");
;             TAG[wr] = u.pm;
	v_lshl_or_b32 v0, v168, 3, v197
	v_lshl_add_u64 v[106:107], v[0:1], 2, s[20:21]
	global_load_dwordx2 v[106:107], v[106:107], off
	v_or_b32_e32 v217, 16, v168
	v_or_b32_e32 v216, 32, v168
	v_or_b32_e32 v214, 48, v168
	v_add_u32_e32 v212, 0x80, v168
	v_add_u32_e32 v210, 0x90, v168
	v_add_u32_e32 v209, 0xa0, v168
	v_add_u32_e32 v208, 0xb0, v168
	v_mov_b32_e32 v153, s61
	s_mov_b64 s[28:29], 0
	s_waitcnt vmcnt(0) lgkmcnt(0)
	v_mov_b32_e32 v0, v106
	s_nop 1
	v_permlane16_swap_b32_e32 v106, v0
	v_add_f32_e32 v109, v106, v0
	v_mov_b32_e32 v0, v107
	s_nop 1
	v_permlane16_swap_b32_e32 v107, v0
	v_add_f32_e32 v108, v107, v0
	v_mov_b32_e32 v135, v109
	v_mov_b32_e32 v134, v108
	s_nop 0
	v_permlane32_swap_b32_e32 v109, v135
	v_permlane32_swap_b32_e32 v108, v134
	v_pk_add_f32 v[106:107], v[108:109], v[134:135]
	s_nop 0
	v_pk_mul_f32 v[106:107], v[106:107], s[68:69] op_sel_hi:[1,0]
	s_nop 0
	v_fma_f32 v0, -v107, v107, v106
	v_add_f32_e32 v0, 0x3727c5ac, v0
	v_rsq_f32_e32 v142, v0
	v_lshl_or_b32 v0, v217, 3, v197
	v_mul_f32_e32 v143, v107, v142
	ds_write_b64 v199, v[142:143]
	v_lshl_add_u64 v[106:107], v[0:1], 2, s[20:21]
	global_load_dwordx2 v[106:107], v[106:107], off
	v_mov_b32_e32 v202, v143
	s_waitcnt vmcnt(0) lgkmcnt(0)
	v_mov_b32_e32 v0, v106
	s_nop 1
	v_permlane16_swap_b32_e32 v106, v0
	v_add_f32_e32 v109, v106, v0
	v_mov_b32_e32 v0, v107
	s_nop 1
	v_permlane16_swap_b32_e32 v107, v0
	v_add_f32_e32 v108, v107, v0
	v_mov_b32_e32 v135, v109
	v_mov_b32_e32 v134, v108
	s_nop 0
	v_permlane32_swap_b32_e32 v109, v135
	v_permlane32_swap_b32_e32 v108, v134
	v_pk_add_f32 v[106:107], v[108:109], v[134:135]
	s_nop 0
	v_pk_mul_f32 v[106:107], v[106:107], s[68:69] op_sel_hi:[1,0]
	s_nop 0
	v_fma_f32 v0, -v107, v107, v106
	v_add_f32_e32 v0, 0x3727c5ac, v0
	v_rsq_f32_e32 v144, v0
	v_lshl_or_b32 v0, v216, 3, v197
	v_mul_f32_e32 v145, v107, v144
	ds_write_b64 v199, v[144:145] offset:128
	v_lshl_add_u64 v[106:107], v[0:1], 2, s[20:21]
	global_load_dwordx2 v[106:107], v[106:107], off
	v_mov_b32_e32 v200, v145
	s_waitcnt vmcnt(0) lgkmcnt(0)
	v_mov_b32_e32 v0, v106
	s_nop 1
	v_permlane16_swap_b32_e32 v106, v0
	v_add_f32_e32 v109, v106, v0
	v_mov_b32_e32 v0, v107
	s_nop 1
	v_permlane16_swap_b32_e32 v107, v0
	v_add_f32_e32 v108, v107, v0
	v_mov_b32_e32 v135, v109
	v_mov_b32_e32 v134, v108
	s_nop 0
	v_permlane32_swap_b32_e32 v109, v135
	v_permlane32_swap_b32_e32 v108, v134
	v_pk_add_f32 v[106:107], v[108:109], v[134:135]
	s_nop 0
	v_pk_mul_f32 v[106:107], v[106:107], s[68:69] op_sel_hi:[1,0]
	s_nop 0
	v_fma_f32 v0, -v107, v107, v106
	v_add_f32_e32 v0, 0x3727c5ac, v0
	v_rsq_f32_e32 v138, v0
	v_lshl_or_b32 v0, v214, 3, v197
	v_mul_f32_e32 v139, v107, v138
	ds_write_b64 v199, v[138:139] offset:256
	v_lshl_add_u64 v[106:107], v[0:1], 2, s[20:21]
	global_load_dwordx2 v[106:107], v[106:107], off
	v_mov_b32_e32 v198, v139
	s_waitcnt vmcnt(0) lgkmcnt(0)
	v_mov_b32_e32 v0, v106
	s_nop 1
	v_permlane16_swap_b32_e32 v106, v0
	v_add_f32_e32 v109, v106, v0
	v_mov_b32_e32 v0, v107
	s_nop 1
	v_permlane16_swap_b32_e32 v107, v0
	v_add_f32_e32 v108, v107, v0
	v_mov_b32_e32 v135, v109
	v_mov_b32_e32 v134, v108
	s_nop 0
	v_permlane32_swap_b32_e32 v109, v135
	v_permlane32_swap_b32_e32 v108, v134
	v_pk_add_f32 v[106:107], v[108:109], v[134:135]
	s_nop 0
	v_pk_mul_f32 v[106:107], v[106:107], s[68:69] op_sel_hi:[1,0]
	s_nop 0
	v_fma_f32 v0, -v107, v107, v106
	v_add_f32_e32 v0, 0x3727c5ac, v0
	v_rsq_f32_e32 v140, v0
	v_lshl_or_b32 v0, v212, 3, v197
	v_mul_f32_e32 v141, v107, v140
	ds_write_b64 v199, v[140:141] offset:384
	v_lshl_add_u64 v[106:107], v[0:1], 2, s[20:21]
	global_load_dwordx2 v[106:107], v[106:107], off
	v_mov_b32_e32 v196, v141
	s_waitcnt vmcnt(0) lgkmcnt(0)
	v_mov_b32_e32 v0, v106
	s_nop 1
	v_permlane16_swap_b32_e32 v106, v0
	v_add_f32_e32 v109, v106, v0
	v_mov_b32_e32 v0, v107
	s_nop 1
	v_permlane16_swap_b32_e32 v107, v0
	v_add_f32_e32 v108, v107, v0
	v_mov_b32_e32 v135, v109
	v_mov_b32_e32 v134, v108
	s_nop 0
	v_permlane32_swap_b32_e32 v109, v135
	v_permlane32_swap_b32_e32 v108, v134
	v_pk_add_f32 v[106:107], v[108:109], v[134:135]
	s_nop 0
	v_pk_mul_f32 v[106:107], v[106:107], s[68:69] op_sel_hi:[1,0]
	s_nop 0
	v_fma_f32 v0, -v107, v107, v106
	v_add_f32_e32 v0, 0x3727c5ac, v0
	v_rsq_f32_e32 v134, v0
	v_lshl_or_b32 v0, v210, 3, v197
	v_mul_f32_e32 v135, v107, v134
	ds_write_b64 v199, v[134:135] offset:1024
	v_lshl_add_u64 v[106:107], v[0:1], 2, s[20:21]
	global_load_dwordx2 v[106:107], v[106:107], off
	v_mov_b32_e32 v194, v135
	s_waitcnt vmcnt(0) lgkmcnt(0)
	v_mov_b32_e32 v0, v106
	s_nop 1
	v_permlane16_swap_b32_e32 v106, v0
	v_add_f32_e32 v109, v106, v0
	v_mov_b32_e32 v0, v107
	s_nop 1
	v_permlane16_swap_b32_e32 v107, v0
	v_add_f32_e32 v108, v107, v0
	v_mov_b32_e32 v137, v109
	v_mov_b32_e32 v136, v108
	s_nop 0
	v_permlane32_swap_b32_e32 v109, v137
	v_permlane32_swap_b32_e32 v108, v136
	v_pk_add_f32 v[106:107], v[108:109], v[136:137]
	s_nop 0
	v_pk_mul_f32 v[106:107], v[106:107], s[68:69] op_sel_hi:[1,0]
	s_nop 0
	v_fma_f32 v0, -v107, v107, v106
	v_add_f32_e32 v0, 0x3727c5ac, v0
	v_rsq_f32_e32 v136, v0
	v_lshl_or_b32 v0, v209, 3, v197
	v_mul_f32_e32 v137, v107, v136
	ds_write_b64 v199, v[136:137] offset:1152
	v_lshl_add_u64 v[106:107], v[0:1], 2, s[20:21]
	global_load_dwordx2 v[106:107], v[106:107], off
	v_mov_b32_e32 v184, v137
	s_waitcnt vmcnt(0) lgkmcnt(0)
	v_mov_b32_e32 v0, v106
	s_nop 1
	v_permlane16_swap_b32_e32 v106, v0
	v_add_f32_e32 v109, v106, v0
	v_mov_b32_e32 v0, v107
	s_nop 1
	v_permlane16_swap_b32_e32 v107, v0
	v_add_f32_e32 v108, v107, v0
	v_mov_b32_e32 v171, v109
	v_mov_b32_e32 v170, v108
	s_nop 0
	v_permlane32_swap_b32_e32 v109, v171
	v_permlane32_swap_b32_e32 v108, v170
	v_pk_add_f32 v[106:107], v[108:109], v[170:171]
	s_nop 0
	v_pk_mul_f32 v[106:107], v[106:107], s[68:69] op_sel_hi:[1,0]
	s_nop 0
	v_fma_f32 v0, -v107, v107, v106
	v_add_f32_e32 v0, 0x3727c5ac, v0
	v_rsq_f32_e32 v106, v0
	v_lshl_or_b32 v0, v208, 3, v197
	v_lshl_add_u64 v[108:109], v[0:1], 2, s[20:21]
	v_mul_f32_e32 v107, v107, v106
	ds_write_b64 v199, v[106:107] offset:1280
	global_load_dwordx2 v[108:109], v[108:109], off
	v_mov_b32_e32 v166, v107
	s_waitcnt vmcnt(0) lgkmcnt(0)
	v_mov_b32_e32 v0, v108
	s_nop 1
	v_permlane16_swap_b32_e32 v108, v0
	v_add_f32_e32 v171, v108, v0
	v_mov_b32_e32 v0, v109
	s_nop 1
	v_permlane16_swap_b32_e32 v109, v0
	v_add_f32_e32 v170, v109, v0
	v_mov_b32_e32 v173, v171
	v_mov_b32_e32 v172, v170
	s_nop 0
	v_permlane32_swap_b32_e32 v171, v173
	v_permlane32_swap_b32_e32 v170, v172
	v_pk_add_f32 v[108:109], v[170:171], v[172:173]
	s_nop 0
	v_pk_mul_f32 v[108:109], v[108:109], s[68:69] op_sel_hi:[1,0]
	s_nop 0
	v_fma_f32 v0, -v109, v109, v108
	v_add_f32_e32 v0, 0x3727c5ac, v0
	v_rsq_f32_e32 v108, v0
	v_mov_b32_e32 v0, s49
	v_mul_f32_e32 v109, v109, v108
	ds_write_b64 v199, v[108:109] offset:1408
	s_waitcnt lgkmcnt(0)
	ds_write_b32 v0, v153
	v_mov_b32_e32 v0, v109

; #define PG8_LAS __attribute__((address_space(3)))
; __device__ __forceinline__ unsigned cvt_pk_bf16(float lo, float hi) { unsigned r; asm volatile("v_cvt_pk_bf16_f32 %0, %1, %2" : "=v"(r) : "v"(lo), "v"(hi)); return r; }
; __device__ __forceinline__ float fast_sigmoid(float x) { return __builtin_amdgcn_rcpf(1.0f + __expf(-x)); }
;     __device__ __forceinline__ void operator()(const f32x4 (&acc)[2][2][4][2], const Unit& u, int wr, int wc, int fr, int fq, PG8_LAS unsigned char* ldsb) const {
;     ...
;         { const u32x4 g0 = *(const PG8_LAS u32x4*)(CV + brow), g1 = *(const PG8_LAS u32x4*)(CV + brow + 4), u0 = *(const PG8_LAS u32x4*)(CV + brow + HALF), u1 = *(const PG8_LAS u32x4*)(CV + brow + HALF + 4);
; #pragma unroll
;           for (int i = 0; i < 4; ++i) { c1g[i] = __uint_as_float(g0[i] << 16); c2g[i] = __uint_as_float(g0[i] & 0xffff0000u); c1g[4 + i] = __uint_as_float(g1[i] << 16); c2g[4 + i] = __uint_as_float(g1[i] & 0xffff0000u);
;               c1u[i] = __uint_as_float(u0[i] << 16); c2u[i] = __uint_as_float(u0[i] & 0xffff0000u); c1u[4 + i] = __uint_as_float(u1[i] << 16); c2u[4 + i] = __uint_as_float(u1[i] & 0xffff0000u); } }
; #pragma unroll
;         for (int ai = 0; ai < 2; ++ai)
; #pragma unroll
;             for (int m = 0; m < 4; ++m) {
;                 bf16_t* p = O + (size_t)(row0 + ai * HALF + m * 16) * ldo + col0;
;                 const float rs = rsv[ai][m], ms = msv[ai][m];
;                 float v[8];
; #pragma unroll
;                 for (int n = 0; n < 2; ++n)
; #pragma unroll
;                     for (int i = 0; i < 4; ++i) { const int e = n * 4 + i; const float g = acc[ai][0][m][n][i] * rs - ms * c1g[e] + c2g[e], up = acc[ai][1][m][n][i] * rs - ms * c1u[e] + c2u[e]; v[e] = g * fast_sigmoid(g) * up; }
;                 u32x4 w; w.x = cvt_pk_bf16(v[0], v[1]); w.y = cvt_pk_bf16(v[2], v[3]); w.z = cvt_pk_bf16(v[4], v[5]); w.w = cvt_pk_bf16(v[6], v[7]);
;                 *(u32x4*)p = w;
.LBB0_906:
	v_lshl_add_u32 v150, s56, 10, v195
	ds_read_b128 v[178:181], v150
	ds_read_b128 v[146:149], v150 offset:16
	ds_read_b128 v[226:229], v150 offset:512
	ds_read_b128 v[150:153], v150 offset:528
	v_mov_b64_e32 v[172:173], s[18:19]
	v_mad_i64_i32 v[206:207], s[28:29], v168, s65, v[172:173]
	s_waitcnt lgkmcnt(0)
	v_lshlrev_b32_e32 v169, 16, v178
	v_lshlrev_b32_e32 v168, 16, v226
	v_mov_b32_e32 v174, v130
	v_mov_b32_e32 v175, v126
	v_pk_mul_f32 v[176:177], v[202:203], v[168:169] op_sel_hi:[0,1]
	v_and_b32_e32 v171, 0xffff0000, v178
	v_and_b32_e32 v170, 0xffff0000, v226
	v_pk_fma_f32 v[174:175], v[174:175], v[142:143], v[176:177] op_sel_hi:[1,0,1] neg_lo:[0,0,1] neg_hi:[0,0,1]
	v_and_b32_e32 v177, 0xffff0000, v179
	v_pk_add_f32 v[174:175], v[174:175], v[170:171]
	v_and_b32_e32 v176, 0xffff0000, v227
	v_mul_f32_e32 v126, 0xbfb8aa3b, v175
	v_exp_f32_e32 v126, v126
	v_mov_b32_e32 v178, v132
	v_lshl_or_b32 v204, s56, 7, v201
	v_ashrrev_i32_e32 v205, 31, v204
	v_add_f32_e32 v126, 1.0, v126
	v_rcp_f32_e32 v126, v126
	s_and_b64 vcc, exec, s[2:3]
	v_mul_f32_e32 v126, v175, v126
	v_mul_f32_e32 v213, v174, v126
	v_lshlrev_b32_e32 v175, 16, v179
	v_lshlrev_b32_e32 v174, 16, v227
	v_mov_b32_e32 v126, v131
	v_pk_mul_f32 v[130:131], v[202:203], v[174:175] op_sel_hi:[0,1]
	v_pk_fma_f32 v[126:127], v[126:127], v[142:143], v[130:131] op_sel_hi:[1,0,1] neg_lo:[0,0,1] neg_hi:[0,0,1]
	v_mov_b32_e32 v179, v128
	v_pk_add_f32 v[126:127], v[126:127], v[176:177]
	v_and_b32_e32 v131, 0xffff0000, v180
	v_mul_f32_e32 v130, 0xbfb8aa3b, v127
	v_exp_f32_e32 v130, v130
	s_nop 0
	v_add_f32_e32 v130, 1.0, v130
	v_rcp_f32_e32 v130, v130
	s_nop 0
	v_mul_f32_e32 v127, v127, v130
	v_mul_f32_e32 v215, v126, v127
	v_lshlrev_b32_e32 v127, 16, v180
	v_lshlrev_b32_e32 v126, 16, v228
	v_pk_mul_f32 v[182:183], v[202:203], v[126:127] op_sel_hi:[0,1]
	v_and_b32_e32 v130, 0xffff0000, v228
	v_pk_fma_f32 v[178:179], v[178:179], v[142:143], v[182:183] op_sel_hi:[1,0,1] neg_lo:[0,0,1] neg_hi:[0,0,1]
	v_and_b32_e32 v180, 0xffff0000, v229
	v_pk_add_f32 v[178:179], v[178:179], v[130:131]
	v_mov_b32_e32 v182, v122
	v_mul_f32_e32 v128, 0xbfb8aa3b, v179
	v_exp_f32_e32 v128, v128
	v_mov_b32_e32 v183, v118
	v_add_f32_e32 v128, 1.0, v128
	v_rcp_f32_e32 v128, v128
	s_nop 0
	v_mul_f32_e32 v128, v179, v128
	v_mul_f32_e32 v228, v178, v128
	v_lshlrev_b32_e32 v179, 16, v181
	v_lshlrev_b32_e32 v178, 16, v229
	v_mov_b32_e32 v128, v133
	v_pk_mul_f32 v[132:133], v[202:203], v[178:179] op_sel_hi:[0,1]
	v_and_b32_e32 v181, 0xffff0000, v181
	v_pk_fma_f32 v[128:129], v[128:129], v[142:143], v[132:133] op_sel_hi:[1,0,1] neg_lo:[0,0,1] neg_hi:[0,0,1]
	v_and_b32_e32 v133, 0xffff0000, v146
	v_pk_add_f32 v[128:129], v[128:129], v[180:181]
	s_nop 0
	v_mul_f32_e32 v132, 0xbfb8aa3b, v129
	v_exp_f32_e32 v132, v132
	s_nop 0
	v_add_f32_e32 v132, 1.0, v132
	v_rcp_f32_e32 v132, v132
	s_nop 0
	v_mul_f32_e32 v129, v129, v132
	v_mul_f32_e32 v229, v128, v129
	v_lshlrev_b32_e32 v129, 16, v146
	v_lshlrev_b32_e32 v128, 16, v150
	v_pk_mul_f32 v[226:227], v[202:203], v[128:129] op_sel_hi:[0,1]
	v_and_b32_e32 v132, 0xffff0000, v150
	v_pk_fma_f32 v[182:183], v[182:183], v[142:143], v[226:227] op_sel_hi:[1,0,1] neg_lo:[0,0,1] neg_hi:[0,0,1]
	v_and_b32_e32 v146, 0xffff0000, v151
	v_pk_add_f32 v[182:183], v[182:183], v[132:133]
	v_mov_b32_e32 v150, v124
	v_mul_f32_e32 v118, 0xbfb8aa3b, v183
	v_exp_f32_e32 v118, v118
	s_nop 0
	v_add_f32_e32 v118, 1.0, v118
	v_rcp_f32_e32 v118, v118
	s_nop 0
	v_mul_f32_e32 v118, v183, v118
	v_mul_f32_e32 v230, v182, v118
	v_lshlrev_b32_e32 v183, 16, v147
	v_lshlrev_b32_e32 v182, 16, v151
	v_mov_b32_e32 v118, v123
	v_pk_mul_f32 v[122:123], v[202:203], v[182:183] op_sel_hi:[0,1]
	v_and_b32_e32 v147, 0xffff0000, v147
	v_pk_fma_f32 v[118:119], v[118:119], v[142:143], v[122:123] op_sel_hi:[1,0,1] neg_lo:[0,0,1] neg_hi:[0,0,1]
	v_mov_b32_e32 v151, v120
	v_pk_add_f32 v[118:119], v[118:119], v[146:147]
	v_and_b32_e32 v123, 0xffff0000, v148
	v_mul_f32_e32 v122, 0xbfb8aa3b, v119
	v_exp_f32_e32 v122, v122
	s_nop 0
	v_add_f32_e32 v122, 1.0, v122
	v_rcp_f32_e32 v122, v122
	s_nop 0
	v_mul_f32_e32 v119, v119, v122
	v_mul_f32_e32 v231, v118, v119
	v_lshlrev_b32_e32 v119, 16, v148
	v_lshlrev_b32_e32 v118, 16, v152
	v_pk_mul_f32 v[226:227], v[202:203], v[118:119] op_sel_hi:[0,1]
	v_and_b32_e32 v122, 0xffff0000, v152
	v_pk_fma_f32 v[150:151], v[150:151], v[142:143], v[226:227] op_sel_hi:[1,0,1] neg_lo:[0,0,1] neg_hi:[0,0,1]
	v_and_b32_e32 v148, 0xffff0000, v153
	v_pk_add_f32 v[150:151], v[150:151], v[122:123]
	s_nop 0
	v_mul_f32_e32 v120, 0xbfb8aa3b, v151
	v_exp_f32_e32 v120, v120
	s_nop 0
	v_add_f32_e32 v120, 1.0, v120
	v_rcp_f32_e32 v120, v120
	s_nop 0
	v_mul_f32_e32 v120, v151, v120
	v_mul_f32_e32 v152, v150, v120
	v_lshlrev_b32_e32 v151, 16, v149
	v_lshlrev_b32_e32 v150, 16, v153
	v_mov_b32_e32 v120, v125
	v_pk_mul_f32 v[124:125], v[202:203], v[150:151] op_sel_hi:[0,1]
	v_and_b32_e32 v149, 0xffff0000, v149
	v_pk_fma_f32 v[120:121], v[120:121], v[142:143], v[124:125] op_sel_hi:[1,0,1] neg_lo:[0,0,1] neg_hi:[0,0,1]
	v_mov_b32_e32 v143, v110
	v_pk_add_f32 v[120:121], v[120:121], v[148:149]
	s_nop 0
	v_mul_f32_e32 v124, 0xbfb8aa3b, v121
	v_exp_f32_e32 v124, v124
	s_nop 0
	v_add_f32_e32 v124, 1.0, v124
	v_rcp_f32_e32 v124, v124
	s_nop 0
	v_mul_f32_e32 v121, v121, v124
	v_mul_f32_e32 v142, v120, v121
	v_lshlrev_b64 v[120:121], 1, v[204:205]
	v_lshl_add_u64 v[124:125], v[206:207], 0, v[120:121]
	v_cvt_pk_bf16_f32 v204, v213, v215
	v_cvt_pk_bf16_f32 v205, v228, v229
	v_cvt_pk_bf16_f32 v206, v230, v231
	v_cvt_pk_bf16_f32 v207, v152, v142
	v_mov_b32_e32 v142, v114
	v_pk_mul_f32 v[152:153], v[200:201], v[168:169] op_sel_hi:[0,1]
; #define PG8_LAS __attribute__((address_space(3)))
; __device__ __forceinline__ unsigned cvt_pk_bf16(float lo, float hi) { unsigned r; asm volatile("v_cvt_pk_bf16_f32 %0, %1, %2" : "=v"(r) : "v"(lo), "v"(hi)); return r; }
; __device__ __forceinline__ float fast_sigmoid(float x) { return __builtin_amdgcn_rcpf(1.0f + __expf(-x)); }
;     __device__ __forceinline__ void operator()(const f32x4 (&acc)[2][2][4][2], const Unit& u, int wr, int wc, int fr, int fq, PG8_LAS unsigned char* ldsb) const {
;     ...
;         { const u32x4 g0 = *(const PG8_LAS u32x4*)(CV + brow), g1 = *(const PG8_LAS u32x4*)(CV + brow + 4), u0 = *(const PG8_LAS u32x4*)(CV + brow + HALF), u1 = *(const PG8_LAS u32x4*)(CV + brow + HALF + 4);
; #pragma unroll
;           for (int i = 0; i < 4; ++i) { c1g[i] = __uint_as_float(g0[i] << 16); c2g[i] = __uint_as_float(g0[i] & 0xffff0000u); c1g[4 + i] = __uint_as_float(g1[i] << 16); c2g[4 + i] = __uint_as_float(g1[i] & 0xffff0000u);
;               c1u[i] = __uint_as_float(u0[i] << 16); c2u[i] = __uint_as_float(u0[i] & 0xffff0000u); c1u[4 + i] = __uint_as_float(u1[i] << 16); c2u[4 + i] = __uint_as_float(u1[i] & 0xffff0000u); } }
; #pragma unroll
;         for (int ai = 0; ai < 2; ++ai)
; #pragma unroll
;             for (int m = 0; m < 4; ++m) {
;                 bf16_t* p = O + (size_t)(row0 + ai * HALF + m * 16) * ldo + col0;
;                 const float rs = rsv[ai][m], ms = msv[ai][m];
;                 float v[8];
; #pragma unroll
;                 for (int n = 0; n < 2; ++n)
; #pragma unroll
;                     for (int i = 0; i < 4; ++i) { const int e = n * 4 + i; const float g = acc[ai][0][m][n][i] * rs - ms * c1g[e] + c2g[e], up = acc[ai][1][m][n][i] * rs - ms * c1u[e] + c2u[e]; v[e] = g * fast_sigmoid(g) * up; }
;                 u32x4 w; w.x = cvt_pk_bf16(v[0], v[1]); w.y = cvt_pk_bf16(v[2], v[3]); w.z = cvt_pk_bf16(v[4], v[5]); w.w = cvt_pk_bf16(v[6], v[7]);
;                 *(u32x4*)p = w;
	v_pk_fma_f32 v[142:143], v[142:143], v[144:145], v[152:153] op_sel_hi:[1,0,1] neg_lo:[0,0,1] neg_hi:[0,0,1]
	global_store_dwordx4 v[124:125], v[204:207], off
	v_pk_add_f32 v[142:143], v[142:143], v[170:171]
	v_mad_i64_i32 v[124:125], s[28:29], v217, s65, v[172:173]
	v_mul_f32_e32 v110, 0xbfb8aa3b, v143
	v_exp_f32_e32 v110, v110
	s_nop 0
	v_add_f32_e32 v110, 1.0, v110
	v_rcp_f32_e32 v110, v110
	s_nop 0
	v_mul_f32_e32 v110, v143, v110
	v_mul_f32_e32 v142, v142, v110
	v_mov_b32_e32 v110, v115
	v_pk_mul_f32 v[114:115], v[200:201], v[174:175] op_sel_hi:[0,1]
	v_pk_fma_f32 v[110:111], v[110:111], v[144:145], v[114:115] op_sel_hi:[1,0,1] neg_lo:[0,0,1] neg_hi:[0,0,1]
	s_nop 0
	v_pk_add_f32 v[110:111], v[110:111], v[176:177]
	s_nop 0
	v_mul_f32_e32 v114, 0xbfb8aa3b, v111
	v_exp_f32_e32 v114, v114
	s_nop 0
	v_add_f32_e32 v114, 1.0, v114
	v_rcp_f32_e32 v114, v114
	s_nop 0
	v_mul_f32_e32 v111, v111, v114
	v_mul_f32_e32 v143, v110, v111
	v_mov_b32_e32 v110, v116
	v_mov_b32_e32 v111, v112
	v_pk_mul_f32 v[114:115], v[200:201], v[126:127] op_sel_hi:[0,1]
	v_pk_fma_f32 v[110:111], v[110:111], v[144:145], v[114:115] op_sel_hi:[1,0,1] neg_lo:[0,0,1] neg_hi:[0,0,1]
	s_nop 0
	v_pk_add_f32 v[110:111], v[110:111], v[130:131]
	s_nop 0
	v_mul_f32_e32 v112, 0xbfb8aa3b, v111
	v_exp_f32_e32 v112, v112
	s_nop 0
	v_add_f32_e32 v112, 1.0, v112
	v_rcp_f32_e32 v112, v112
	s_nop 0
	v_mul_f32_e32 v111, v111, v112
	v_mul_f32_e32 v114, v110, v111
	v_mov_b32_e32 v112, v117
	v_pk_mul_f32 v[110:111], v[200:201], v[178:179] op_sel_hi:[0,1]
	v_pk_fma_f32 v[110:111], v[112:113], v[144:145], v[110:111] op_sel_hi:[1,0,1] neg_lo:[0,0,1] neg_hi:[0,0,1]
	s_nop 0
	v_pk_add_f32 v[110:111], v[110:111], v[180:181]
	s_nop 0
	v_mul_f32_e32 v112, 0xbfb8aa3b, v111
	v_exp_f32_e32 v112, v112
	s_nop 0
	v_add_f32_e32 v112, 1.0, v112
	v_rcp_f32_e32 v112, v112
	s_nop 0
	v_mul_f32_e32 v111, v111, v112
	v_mul_f32_e32 v115, v110, v111
	v_mov_b32_e32 v110, v102
	v_mov_b32_e32 v111, v98
	v_pk_mul_f32 v[112:113], v[200:201], v[128:129] op_sel_hi:[0,1]
	v_pk_fma_f32 v[110:111], v[110:111], v[144:145], v[112:113] op_sel_hi:[1,0,1] neg_lo:[0,0,1] neg_hi:[0,0,1]
	s_nop 0
	v_pk_add_f32 v[110:111], v[110:111], v[132:133]
	s_nop 0
	v_mul_f32_e32 v98, 0xbfb8aa3b, v111
	v_exp_f32_e32 v98, v98
	s_nop 0
	v_add_f32_e32 v98, 1.0, v98
	v_rcp_f32_e32 v98, v98
	s_nop 0
	v_mul_f32_e32 v98, v111, v98
	v_mul_f32_e32 v110, v110, v98
	v_mov_b32_e32 v98, v103
	v_pk_mul_f32 v[102:103], v[200:201], v[182:183] op_sel_hi:[0,1]
	v_pk_fma_f32 v[98:99], v[98:99], v[144:145], v[102:103] op_sel_hi:[1,0,1] neg_lo:[0,0,1] neg_hi:[0,0,1]
	s_nop 0
	v_pk_add_f32 v[98:99], v[98:99], v[146:147]
	s_nop 0
	v_mul_f32_e32 v102, 0xbfb8aa3b, v99
	v_exp_f32_e32 v102, v102
	s_nop 0
	v_add_f32_e32 v102, 1.0, v102
	v_rcp_f32_e32 v102, v102
	s_nop 0
	v_mul_f32_e32 v99, v99, v102
	v_mul_f32_e32 v111, v98, v99
	v_mov_b32_e32 v98, v104
	v_mov_b32_e32 v99, v100
	v_pk_mul_f32 v[102:103], v[200:201], v[118:119] op_sel_hi:[0,1]
	v_pk_fma_f32 v[98:99], v[98:99], v[144:145], v[102:103] op_sel_hi:[1,0,1] neg_lo:[0,0,1] neg_hi:[0,0,1]
	v_lshl_add_u64 v[102:103], v[124:125], 0, v[120:121]
	v_pk_add_f32 v[98:99], v[98:99], v[122:123]
	s_nop 0
	v_mul_f32_e32 v100, 0xbfb8aa3b, v99
	v_exp_f32_e32 v100, v100
	s_nop 0
	v_add_f32_e32 v100, 1.0, v100
	v_rcp_f32_e32 v100, v100
	s_nop 0
	v_mul_f32_e32 v99, v99, v100
	v_mul_f32_e32 v104, v98, v99
	v_mov_b32_e32 v100, v105
	v_pk_mul_f32 v[98:99], v[200:201], v[150:151] op_sel_hi:[0,1]
	v_pk_fma_f32 v[98:99], v[100:101], v[144:145], v[98:99] op_sel_hi:[1,0,1] neg_lo:[0,0,1] neg_hi:[0,0,1]
	s_nop 0
	v_pk_add_f32 v[98:99], v[98:99], v[148:149]
	s_nop 0
	v_mul_f32_e32 v100, 0xbfb8aa3b, v99
	v_exp_f32_e32 v100, v100
	s_nop 0
	v_add_f32_e32 v100, 1.0, v100
	v_rcp_f32_e32 v100, v100
	s_nop 0
	v_mul_f32_e32 v99, v99, v100
	v_mul_f32_e32 v101, v98, v99
	v_cvt_pk_bf16_f32 v98, v142, v143
	v_cvt_pk_bf16_f32 v99, v114, v115
	v_cvt_pk_bf16_f32 v100, v110, v111
	v_cvt_pk_bf16_f32 v101, v104, v101
	global_store_dwordx4 v[102:103], v[98:101], off
	v_pk_mul_f32 v[102:103], v[198:199], v[168:169] op_sel_hi:[0,1]
	s_nop 0
	v_mov_b32_e32 v100, v94
	v_mov_b32_e32 v101, v90
	v_pk_fma_f32 v[100:101], v[100:101], v[138:139], v[102:103] op_sel_hi:[1,0,1] neg_lo:[0,0,1] neg_hi:[0,0,1]
	v_mad_i64_i32 v[98:99], s[28:29], v216, s65, v[172:173]
	v_pk_add_f32 v[100:101], v[100:101], v[170:171]
	s_nop 0
	v_mul_f32_e32 v90, 0xbfb8aa3b, v101
	v_exp_f32_e32 v90, v90
	s_nop 0
	v_add_f32_e32 v90, 1.0, v90
	v_rcp_f32_e32 v90, v90
	s_nop 0
	v_mul_f32_e32 v90, v101, v90
	v_mul_f32_e32 v100, v100, v90
	v_mov_b32_e32 v90, v95
	v_pk_mul_f32 v[94:95], v[198:199], v[174:175] op_sel_hi:[0,1]
	v_pk_fma_f32 v[90:91], v[90:91], v[138:139], v[94:95] op_sel_hi:[1,0,1] neg_lo:[0,0,1] neg_hi:[0,0,1]
	s_nop 0
	v_pk_add_f32 v[90:91], v[90:91], v[176:177]
	s_nop 0
	v_mul_f32_e32 v94, 0xbfb8aa3b, v91
	v_exp_f32_e32 v94, v94
	s_nop 0
	v_add_f32_e32 v94, 1.0, v94
	v_rcp_f32_e32 v94, v94
	s_nop 0
	v_mul_f32_e32 v91, v91, v94
	v_mul_f32_e32 v101, v90, v91
	v_mov_b32_e32 v90, v96
	v_mov_b32_e32 v91, v92
	v_pk_mul_f32 v[94:95], v[198:199], v[126:127] op_sel_hi:[0,1]
	v_pk_fma_f32 v[90:91], v[90:91], v[138:139], v[94:95] op_sel_hi:[1,0,1] neg_lo:[0,0,1] neg_hi:[0,0,1]
	s_nop 0
	v_pk_add_f32 v[90:91], v[90:91], v[130:131]
	s_nop 0
	v_mul_f32_e32 v92, 0xbfb8aa3b, v91
	v_exp_f32_e32 v92, v92
	s_nop 0
	v_add_f32_e32 v92, 1.0, v92
	v_rcp_f32_e32 v92, v92
	s_nop 0
	v_mul_f32_e32 v91, v91, v92
	v_mul_f32_e32 v94, v90, v91
	v_mov_b32_e32 v92, v97
	v_pk_mul_f32 v[90:91], v[198:199], v[178:179] op_sel_hi:[0,1]
	v_pk_fma_f32 v[90:91], v[92:93], v[138:139], v[90:91] op_sel_hi:[1,0,1] neg_lo:[0,0,1] neg_hi:[0,0,1]
; #define PG8_LAS __attribute__((address_space(3)))
; __device__ __forceinline__ unsigned cvt_pk_bf16(float lo, float hi) { unsigned r; asm volatile("v_cvt_pk_bf16_f32 %0, %1, %2" : "=v"(r) : "v"(lo), "v"(hi)); return r; }
; __device__ __forceinline__ float fast_sigmoid(float x) { return __builtin_amdgcn_rcpf(1.0f + __expf(-x)); }
;     __device__ __forceinline__ void operator()(const f32x4 (&acc)[2][2][4][2], const Unit& u, int wr, int wc, int fr, int fq, PG8_LAS unsigned char* ldsb) const {
;     ...
;         { const u32x4 g0 = *(const PG8_LAS u32x4*)(CV + brow), g1 = *(const PG8_LAS u32x4*)(CV + brow + 4), u0 = *(const PG8_LAS u32x4*)(CV + brow + HALF), u1 = *(const PG8_LAS u32x4*)(CV + brow + HALF + 4);
; #pragma unroll
;           for (int i = 0; i < 4; ++i) { c1g[i] = __uint_as_float(g0[i] << 16); c2g[i] = __uint_as_float(g0[i] & 0xffff0000u); c1g[4 + i] = __uint_as_float(g1[i] << 16); c2g[4 + i] = __uint_as_float(g1[i] & 0xffff0000u);
;               c1u[i] = __uint_as_float(u0[i] << 16); c2u[i] = __uint_as_float(u0[i] & 0xffff0000u); c1u[4 + i] = __uint_as_float(u1[i] << 16); c2u[4 + i] = __uint_as_float(u1[i] & 0xffff0000u); } }
; #pragma unroll
;         for (int ai = 0; ai < 2; ++ai)
; #pragma unroll
;             for (int m = 0; m < 4; ++m) {
;                 bf16_t* p = O + (size_t)(row0 + ai * HALF + m * 16) * ldo + col0;
;                 const float rs = rsv[ai][m], ms = msv[ai][m];
;                 float v[8];
; #pragma unroll
;                 for (int n = 0; n < 2; ++n)
; #pragma unroll
;                     for (int i = 0; i < 4; ++i) { const int e = n * 4 + i; const float g = acc[ai][0][m][n][i] * rs - ms * c1g[e] + c2g[e], up = acc[ai][1][m][n][i] * rs - ms * c1u[e] + c2u[e]; v[e] = g * fast_sigmoid(g) * up; }
;                 u32x4 w; w.x = cvt_pk_bf16(v[0], v[1]); w.y = cvt_pk_bf16(v[2], v[3]); w.z = cvt_pk_bf16(v[4], v[5]); w.w = cvt_pk_bf16(v[6], v[7]);
;                 *(u32x4*)p = w;
	s_nop 0
	v_pk_add_f32 v[90:91], v[90:91], v[180:181]
	s_nop 0
	v_mul_f32_e32 v92, 0xbfb8aa3b, v91
	v_exp_f32_e32 v92, v92
	s_nop 0
	v_add_f32_e32 v92, 1.0, v92
	v_rcp_f32_e32 v92, v92
	s_nop 0
	v_mul_f32_e32 v91, v91, v92
	v_mul_f32_e32 v95, v90, v91
	v_mov_b32_e32 v90, v86
	v_mov_b32_e32 v91, v82
	v_pk_mul_f32 v[92:93], v[198:199], v[128:129] op_sel_hi:[0,1]
	v_pk_fma_f32 v[90:91], v[90:91], v[138:139], v[92:93] op_sel_hi:[1,0,1] neg_lo:[0,0,1] neg_hi:[0,0,1]
	s_nop 0
	v_pk_add_f32 v[90:91], v[90:91], v[132:133]
	s_nop 0
	v_mul_f32_e32 v82, 0xbfb8aa3b, v91
	v_exp_f32_e32 v82, v82
	s_nop 0
	v_add_f32_e32 v82, 1.0, v82
	v_rcp_f32_e32 v82, v82
	s_nop 0
	v_mul_f32_e32 v82, v91, v82
	v_mul_f32_e32 v90, v90, v82
	v_mov_b32_e32 v82, v87
	v_pk_mul_f32 v[86:87], v[198:199], v[182:183] op_sel_hi:[0,1]
	v_pk_fma_f32 v[82:83], v[82:83], v[138:139], v[86:87] op_sel_hi:[1,0,1] neg_lo:[0,0,1] neg_hi:[0,0,1]
	s_nop 0
	v_pk_add_f32 v[82:83], v[82:83], v[146:147]
	s_nop 0
	v_mul_f32_e32 v86, 0xbfb8aa3b, v83
	v_exp_f32_e32 v86, v86
	s_nop 0
	v_add_f32_e32 v86, 1.0, v86
	v_rcp_f32_e32 v86, v86
	s_nop 0
	v_mul_f32_e32 v83, v83, v86
	v_mul_f32_e32 v91, v82, v83
	v_mov_b32_e32 v82, v88
	v_mov_b32_e32 v83, v84
	v_pk_mul_f32 v[86:87], v[198:199], v[118:119] op_sel_hi:[0,1]
	v_pk_fma_f32 v[82:83], v[82:83], v[138:139], v[86:87] op_sel_hi:[1,0,1] neg_lo:[0,0,1] neg_hi:[0,0,1]
	v_lshl_add_u64 v[86:87], v[98:99], 0, v[120:121]
	v_pk_add_f32 v[82:83], v[82:83], v[122:123]
	s_nop 0
	v_mul_f32_e32 v84, 0xbfb8aa3b, v83
	v_exp_f32_e32 v84, v84
	s_nop 0
	v_add_f32_e32 v84, 1.0, v84
	v_rcp_f32_e32 v84, v84
	s_nop 0
	v_mul_f32_e32 v83, v83, v84
	v_mul_f32_e32 v88, v82, v83
	v_mov_b32_e32 v84, v89
	v_pk_mul_f32 v[82:83], v[198:199], v[150:151] op_sel_hi:[0,1]
	v_pk_fma_f32 v[82:83], v[84:85], v[138:139], v[82:83] op_sel_hi:[1,0,1] neg_lo:[0,0,1] neg_hi:[0,0,1]
	s_nop 0
	v_pk_add_f32 v[82:83], v[82:83], v[148:149]
	s_nop 0
	v_mul_f32_e32 v84, 0xbfb8aa3b, v83
	v_exp_f32_e32 v84, v84
	s_nop 0
	v_add_f32_e32 v84, 1.0, v84
	v_rcp_f32_e32 v84, v84
	s_nop 0
	v_mul_f32_e32 v83, v83, v84
	v_mul_f32_e32 v85, v82, v83
	v_cvt_pk_bf16_f32 v82, v100, v101
	v_cvt_pk_bf16_f32 v83, v94, v95
	v_cvt_pk_bf16_f32 v84, v90, v91
	v_cvt_pk_bf16_f32 v85, v88, v85
	global_store_dwordx4 v[86:87], v[82:85], off
	v_pk_mul_f32 v[86:87], v[196:197], v[168:169] op_sel_hi:[0,1]
	s_nop 0
	v_mov_b32_e32 v84, v78
	v_mov_b32_e32 v85, v74
	v_pk_fma_f32 v[84:85], v[84:85], v[140:141], v[86:87] op_sel_hi:[1,0,1] neg_lo:[0,0,1] neg_hi:[0,0,1]
	v_mad_i64_i32 v[82:83], s[28:29], v214, s65, v[172:173]
	v_pk_add_f32 v[84:85], v[84:85], v[170:171]
	s_nop 0
	v_mul_f32_e32 v74, 0xbfb8aa3b, v85
	v_exp_f32_e32 v74, v74
	s_nop 0
	v_add_f32_e32 v74, 1.0, v74
	v_rcp_f32_e32 v74, v74
	s_nop 0
	v_mul_f32_e32 v74, v85, v74
	v_mul_f32_e32 v84, v84, v74
	v_mov_b32_e32 v74, v79
	v_pk_mul_f32 v[78:79], v[196:197], v[174:175] op_sel_hi:[0,1]
	v_pk_fma_f32 v[74:75], v[74:75], v[140:141], v[78:79] op_sel_hi:[1,0,1] neg_lo:[0,0,1] neg_hi:[0,0,1]
	s_nop 0
	v_pk_add_f32 v[74:75], v[74:75], v[176:177]
	s_nop 0
	v_mul_f32_e32 v78, 0xbfb8aa3b, v75
	v_exp_f32_e32 v78, v78
	s_nop 0
	v_add_f32_e32 v78, 1.0, v78
	v_rcp_f32_e32 v78, v78
	s_nop 0
	v_mul_f32_e32 v75, v75, v78
	v_mul_f32_e32 v85, v74, v75
	v_mov_b32_e32 v74, v80
	v_mov_b32_e32 v75, v76
	v_pk_mul_f32 v[78:79], v[196:197], v[126:127] op_sel_hi:[0,1]
	v_pk_fma_f32 v[74:75], v[74:75], v[140:141], v[78:79] op_sel_hi:[1,0,1] neg_lo:[0,0,1] neg_hi:[0,0,1]
	s_nop 0
	v_pk_add_f32 v[74:75], v[74:75], v[130:131]
	s_nop 0
	v_mul_f32_e32 v76, 0xbfb8aa3b, v75
	v_exp_f32_e32 v76, v76
	s_nop 0
	v_add_f32_e32 v76, 1.0, v76
	v_rcp_f32_e32 v76, v76
	s_nop 0
	v_mul_f32_e32 v75, v75, v76
	v_mul_f32_e32 v78, v74, v75
	v_mov_b32_e32 v76, v81
	v_pk_mul_f32 v[74:75], v[196:197], v[178:179] op_sel_hi:[0,1]
	v_pk_fma_f32 v[74:75], v[76:77], v[140:141], v[74:75] op_sel_hi:[1,0,1] neg_lo:[0,0,1] neg_hi:[0,0,1]
	s_nop 0
	v_pk_add_f32 v[74:75], v[74:75], v[180:181]
	s_nop 0
	v_mul_f32_e32 v76, 0xbfb8aa3b, v75
	v_exp_f32_e32 v76, v76
	s_nop 0
	v_add_f32_e32 v76, 1.0, v76
	v_rcp_f32_e32 v76, v76
	s_nop 0
	v_mul_f32_e32 v75, v75, v76
	v_mul_f32_e32 v79, v74, v75
	v_mov_b32_e32 v74, v70
	v_mov_b32_e32 v75, v66
	v_pk_mul_f32 v[76:77], v[196:197], v[128:129] op_sel_hi:[0,1]
	v_pk_fma_f32 v[74:75], v[74:75], v[140:141], v[76:77] op_sel_hi:[1,0,1] neg_lo:[0,0,1] neg_hi:[0,0,1]
	s_nop 0
	v_pk_add_f32 v[74:75], v[74:75], v[132:133]
	s_nop 0
	v_mul_f32_e32 v66, 0xbfb8aa3b, v75
	v_exp_f32_e32 v66, v66
	s_nop 0
	v_add_f32_e32 v66, 1.0, v66
	v_rcp_f32_e32 v66, v66
	s_nop 0
	v_mul_f32_e32 v66, v75, v66
	v_mul_f32_e32 v74, v74, v66
	v_mov_b32_e32 v66, v71
	v_pk_mul_f32 v[70:71], v[196:197], v[182:183] op_sel_hi:[0,1]
	v_pk_fma_f32 v[66:67], v[66:67], v[140:141], v[70:71] op_sel_hi:[1,0,1] neg_lo:[0,0,1] neg_hi:[0,0,1]
	s_nop 0
	v_pk_add_f32 v[66:67], v[66:67], v[146:147]
	s_nop 0
	v_mul_f32_e32 v70, 0xbfb8aa3b, v67
	v_exp_f32_e32 v70, v70
	s_nop 0
	v_add_f32_e32 v70, 1.0, v70
	v_rcp_f32_e32 v70, v70
	s_nop 0
	v_mul_f32_e32 v67, v67, v70
	v_mul_f32_e32 v75, v66, v67
	v_mov_b32_e32 v66, v72
	v_mov_b32_e32 v67, v68
	v_pk_mul_f32 v[70:71], v[196:197], v[118:119] op_sel_hi:[0,1]
	v_pk_fma_f32 v[66:67], v[66:67], v[140:141], v[70:71] op_sel_hi:[1,0,1] neg_lo:[0,0,1] neg_hi:[0,0,1]
	v_lshl_add_u64 v[70:71], v[82:83], 0, v[120:121]
	v_pk_add_f32 v[66:67], v[66:67], v[122:123]
	s_nop 0
	v_mul_f32_e32 v68, 0xbfb8aa3b, v67
	v_exp_f32_e32 v68, v68
	s_nop 0
	v_add_f32_e32 v68, 1.0, v68
	v_rcp_f32_e32 v68, v68
	s_nop 0
	v_mul_f32_e32 v67, v67, v68
	v_mul_f32_e32 v72, v66, v67
	v_mov_b32_e32 v68, v73
	v_pk_mul_f32 v[66:67], v[196:197], v[150:151] op_sel_hi:[0,1]
; #define PG8_LAS __attribute__((address_space(3)))
; __device__ __forceinline__ unsigned cvt_pk_bf16(float lo, float hi) { unsigned r; asm volatile("v_cvt_pk_bf16_f32 %0, %1, %2" : "=v"(r) : "v"(lo), "v"(hi)); return r; }
; __device__ __forceinline__ float fast_sigmoid(float x) { return __builtin_amdgcn_rcpf(1.0f + __expf(-x)); }
;     __device__ __forceinline__ void operator()(const f32x4 (&acc)[2][2][4][2], const Unit& u, int wr, int wc, int fr, int fq, PG8_LAS unsigned char* ldsb) const {
;     ...
;         { const u32x4 g0 = *(const PG8_LAS u32x4*)(CV + brow), g1 = *(const PG8_LAS u32x4*)(CV + brow + 4), u0 = *(const PG8_LAS u32x4*)(CV + brow + HALF), u1 = *(const PG8_LAS u32x4*)(CV + brow + HALF + 4);
; #pragma unroll
;           for (int i = 0; i < 4; ++i) { c1g[i] = __uint_as_float(g0[i] << 16); c2g[i] = __uint_as_float(g0[i] & 0xffff0000u); c1g[4 + i] = __uint_as_float(g1[i] << 16); c2g[4 + i] = __uint_as_float(g1[i] & 0xffff0000u);
;               c1u[i] = __uint_as_float(u0[i] << 16); c2u[i] = __uint_as_float(u0[i] & 0xffff0000u); c1u[4 + i] = __uint_as_float(u1[i] << 16); c2u[4 + i] = __uint_as_float(u1[i] & 0xffff0000u); } }
; #pragma unroll
;         for (int ai = 0; ai < 2; ++ai)
; #pragma unroll
;             for (int m = 0; m < 4; ++m) {
;                 bf16_t* p = O + (size_t)(row0 + ai * HALF + m * 16) * ldo + col0;
;                 const float rs = rsv[ai][m], ms = msv[ai][m];
;                 float v[8];
; #pragma unroll
;                 for (int n = 0; n < 2; ++n)
; #pragma unroll
;                     for (int i = 0; i < 4; ++i) { const int e = n * 4 + i; const float g = acc[ai][0][m][n][i] * rs - ms * c1g[e] + c2g[e], up = acc[ai][1][m][n][i] * rs - ms * c1u[e] + c2u[e]; v[e] = g * fast_sigmoid(g) * up; }
;                 u32x4 w; w.x = cvt_pk_bf16(v[0], v[1]); w.y = cvt_pk_bf16(v[2], v[3]); w.z = cvt_pk_bf16(v[4], v[5]); w.w = cvt_pk_bf16(v[6], v[7]);
;                 *(u32x4*)p = w;
	v_pk_fma_f32 v[66:67], v[68:69], v[140:141], v[66:67] op_sel_hi:[1,0,1] neg_lo:[0,0,1] neg_hi:[0,0,1]
	s_nop 0
	v_pk_add_f32 v[66:67], v[66:67], v[148:149]
	s_nop 0
	v_mul_f32_e32 v68, 0xbfb8aa3b, v67
	v_exp_f32_e32 v68, v68
	s_nop 0
	v_add_f32_e32 v68, 1.0, v68
	v_rcp_f32_e32 v68, v68
	s_nop 0
	v_mul_f32_e32 v67, v67, v68
	v_mul_f32_e32 v69, v66, v67
	v_cvt_pk_bf16_f32 v66, v84, v85
	v_cvt_pk_bf16_f32 v67, v78, v79
	v_cvt_pk_bf16_f32 v68, v74, v75
	v_cvt_pk_bf16_f32 v69, v72, v69
	global_store_dwordx4 v[70:71], v[66:69], off
	v_pk_mul_f32 v[70:71], v[194:195], v[168:169] op_sel_hi:[0,1]
	s_nop 0
	v_mov_b32_e32 v68, v62
	v_mov_b32_e32 v69, v58
	v_pk_fma_f32 v[68:69], v[68:69], v[134:135], v[70:71] op_sel_hi:[1,0,1] neg_lo:[0,0,1] neg_hi:[0,0,1]
	v_mad_i64_i32 v[66:67], s[28:29], v212, s65, v[172:173]
	v_pk_add_f32 v[68:69], v[68:69], v[170:171]
	s_nop 0
	v_mul_f32_e32 v58, 0xbfb8aa3b, v69
	v_exp_f32_e32 v58, v58
	s_nop 0
	v_add_f32_e32 v58, 1.0, v58
	v_rcp_f32_e32 v58, v58
	s_nop 0
	v_mul_f32_e32 v58, v69, v58
	v_mul_f32_e32 v68, v68, v58
	v_mov_b32_e32 v58, v63
	v_pk_mul_f32 v[62:63], v[194:195], v[174:175] op_sel_hi:[0,1]
	v_pk_fma_f32 v[58:59], v[58:59], v[134:135], v[62:63] op_sel_hi:[1,0,1] neg_lo:[0,0,1] neg_hi:[0,0,1]
	s_nop 0
	v_pk_add_f32 v[58:59], v[58:59], v[176:177]
	s_nop 0
	v_mul_f32_e32 v62, 0xbfb8aa3b, v59
	v_exp_f32_e32 v62, v62
	s_nop 0
	v_add_f32_e32 v62, 1.0, v62
	v_rcp_f32_e32 v62, v62
	s_nop 0
	v_mul_f32_e32 v59, v59, v62
	v_mul_f32_e32 v69, v58, v59
	v_mov_b32_e32 v58, v64
	v_mov_b32_e32 v59, v60
	v_pk_mul_f32 v[62:63], v[194:195], v[126:127] op_sel_hi:[0,1]
	v_pk_fma_f32 v[58:59], v[58:59], v[134:135], v[62:63] op_sel_hi:[1,0,1] neg_lo:[0,0,1] neg_hi:[0,0,1]
	s_nop 0
	v_pk_add_f32 v[58:59], v[58:59], v[130:131]
	s_nop 0
	v_mul_f32_e32 v60, 0xbfb8aa3b, v59
	v_exp_f32_e32 v60, v60
	s_nop 0
	v_add_f32_e32 v60, 1.0, v60
	v_rcp_f32_e32 v60, v60
	s_nop 0
	v_mul_f32_e32 v59, v59, v60
	v_mul_f32_e32 v62, v58, v59
	v_mov_b32_e32 v60, v65
	v_pk_mul_f32 v[58:59], v[194:195], v[178:179] op_sel_hi:[0,1]
	v_pk_fma_f32 v[58:59], v[60:61], v[134:135], v[58:59] op_sel_hi:[1,0,1] neg_lo:[0,0,1] neg_hi:[0,0,1]
	s_nop 0
	v_pk_add_f32 v[58:59], v[58:59], v[180:181]
	s_nop 0
	v_mul_f32_e32 v60, 0xbfb8aa3b, v59
	v_exp_f32_e32 v60, v60
	s_nop 0
	v_add_f32_e32 v60, 1.0, v60
	v_rcp_f32_e32 v60, v60
	s_nop 0
	v_mul_f32_e32 v59, v59, v60
	v_mul_f32_e32 v63, v58, v59
	v_mov_b32_e32 v58, v54
	v_mov_b32_e32 v59, v50
	v_pk_mul_f32 v[60:61], v[194:195], v[128:129] op_sel_hi:[0,1]
	v_pk_fma_f32 v[58:59], v[58:59], v[134:135], v[60:61] op_sel_hi:[1,0,1] neg_lo:[0,0,1] neg_hi:[0,0,1]
	s_nop 0
	v_pk_add_f32 v[58:59], v[58:59], v[132:133]
	s_nop 0
	v_mul_f32_e32 v50, 0xbfb8aa3b, v59
	v_exp_f32_e32 v50, v50
	s_nop 0
	v_add_f32_e32 v50, 1.0, v50
	v_rcp_f32_e32 v50, v50
	s_nop 0
	v_mul_f32_e32 v50, v59, v50
	v_mul_f32_e32 v58, v58, v50
	v_mov_b32_e32 v50, v55
	v_pk_mul_f32 v[54:55], v[194:195], v[182:183] op_sel_hi:[0,1]
	v_pk_fma_f32 v[50:51], v[50:51], v[134:135], v[54:55] op_sel_hi:[1,0,1] neg_lo:[0,0,1] neg_hi:[0,0,1]
	s_nop 0
	v_pk_add_f32 v[50:51], v[50:51], v[146:147]
	s_nop 0
	v_mul_f32_e32 v54, 0xbfb8aa3b, v51
	v_exp_f32_e32 v54, v54
	s_nop 0
	v_add_f32_e32 v54, 1.0, v54
	v_rcp_f32_e32 v54, v54
	s_nop 0
	v_mul_f32_e32 v51, v51, v54
	v_mul_f32_e32 v59, v50, v51
	v_mov_b32_e32 v50, v56
	v_mov_b32_e32 v51, v52
	v_pk_mul_f32 v[54:55], v[194:195], v[118:119] op_sel_hi:[0,1]
	v_pk_fma_f32 v[50:51], v[50:51], v[134:135], v[54:55] op_sel_hi:[1,0,1] neg_lo:[0,0,1] neg_hi:[0,0,1]
	v_lshl_add_u64 v[54:55], v[66:67], 0, v[120:121]
	v_pk_add_f32 v[50:51], v[50:51], v[122:123]
	s_nop 0
	v_mul_f32_e32 v52, 0xbfb8aa3b, v51
	v_exp_f32_e32 v52, v52
	s_nop 0
	v_add_f32_e32 v52, 1.0, v52
	v_rcp_f32_e32 v52, v52
	s_nop 0
	v_mul_f32_e32 v51, v51, v52
	v_mul_f32_e32 v56, v50, v51
	v_mov_b32_e32 v52, v57
	v_pk_mul_f32 v[50:51], v[194:195], v[150:151] op_sel_hi:[0,1]
	v_pk_fma_f32 v[50:51], v[52:53], v[134:135], v[50:51] op_sel_hi:[1,0,1] neg_lo:[0,0,1] neg_hi:[0,0,1]
	s_nop 0
	v_pk_add_f32 v[50:51], v[50:51], v[148:149]
	s_nop 0
	v_mul_f32_e32 v52, 0xbfb8aa3b, v51
	v_exp_f32_e32 v52, v52
	s_nop 0
	v_add_f32_e32 v52, 1.0, v52
	v_rcp_f32_e32 v52, v52
	s_nop 0
	v_mul_f32_e32 v51, v51, v52
	v_mul_f32_e32 v53, v50, v51
	v_cvt_pk_bf16_f32 v50, v68, v69
	v_cvt_pk_bf16_f32 v51, v62, v63
	v_cvt_pk_bf16_f32 v52, v58, v59
	v_cvt_pk_bf16_f32 v53, v56, v53
	global_store_dwordx4 v[54:55], v[50:53], off
	v_pk_mul_f32 v[54:55], v[184:185], v[168:169] op_sel_hi:[0,1]
	s_nop 0
	v_mov_b32_e32 v52, v46
	v_mov_b32_e32 v53, v42
	v_pk_fma_f32 v[52:53], v[52:53], v[136:137], v[54:55] op_sel_hi:[1,0,1] neg_lo:[0,0,1] neg_hi:[0,0,1]
	v_mad_i64_i32 v[50:51], s[28:29], v210, s65, v[172:173]
	v_pk_add_f32 v[52:53], v[52:53], v[170:171]
	s_nop 0
	v_mul_f32_e32 v42, 0xbfb8aa3b, v53
	v_exp_f32_e32 v42, v42
	s_nop 0
	v_add_f32_e32 v42, 1.0, v42
	v_rcp_f32_e32 v42, v42
	s_nop 0
	v_mul_f32_e32 v42, v53, v42
	v_mul_f32_e32 v52, v52, v42
	v_mov_b32_e32 v42, v47
	v_pk_mul_f32 v[46:47], v[184:185], v[174:175] op_sel_hi:[0,1]
	v_pk_fma_f32 v[42:43], v[42:43], v[136:137], v[46:47] op_sel_hi:[1,0,1] neg_lo:[0,0,1] neg_hi:[0,0,1]
	s_nop 0
	v_pk_add_f32 v[42:43], v[42:43], v[176:177]
	s_nop 0
	v_mul_f32_e32 v46, 0xbfb8aa3b, v43
	v_exp_f32_e32 v46, v46
	s_nop 0
	v_add_f32_e32 v46, 1.0, v46
	v_rcp_f32_e32 v46, v46
	s_nop 0
	v_mul_f32_e32 v43, v43, v46
	v_mul_f32_e32 v53, v42, v43
	v_mov_b32_e32 v42, v48
	v_mov_b32_e32 v43, v44
	v_pk_mul_f32 v[46:47], v[184:185], v[126:127] op_sel_hi:[0,1]
	v_pk_fma_f32 v[42:43], v[42:43], v[136:137], v[46:47] op_sel_hi:[1,0,1] neg_lo:[0,0,1] neg_hi:[0,0,1]
	s_nop 0
; __device__ __forceinline__ unsigned cvt_pk_bf16(float lo, float hi) { unsigned r; asm volatile("v_cvt_pk_bf16_f32 %0, %1, %2" : "=v"(r) : "v"(lo), "v"(hi)); return r; }
; __device__ __forceinline__ float fast_sigmoid(float x) { return __builtin_amdgcn_rcpf(1.0f + __expf(-x)); }
;     __device__ __forceinline__ void operator()(const f32x4 (&acc)[2][2][4][2], const Unit& u, int wr, int wc, int fr, int fq, PG8_LAS unsigned char* ldsb) const {
;     ...
;                 bf16_t* p = O + (size_t)(row0 + ai * HALF + m * 16) * ldo + col0;
;                 const float rs = rsv[ai][m], ms = msv[ai][m];
;                 float v[8];
; #pragma unroll
;                 for (int n = 0; n < 2; ++n)
; #pragma unroll
;                     for (int i = 0; i < 4; ++i) { const int e = n * 4 + i; const float g = acc[ai][0][m][n][i] * rs - ms * c1g[e] + c2g[e], up = acc[ai][1][m][n][i] * rs - ms * c1u[e] + c2u[e]; v[e] = g * fast_sigmoid(g) * up; }
;                 u32x4 w; w.x = cvt_pk_bf16(v[0], v[1]); w.y = cvt_pk_bf16(v[2], v[3]); w.z = cvt_pk_bf16(v[4], v[5]); w.w = cvt_pk_bf16(v[6], v[7]);
;                 *(u32x4*)p = w;
	v_pk_add_f32 v[42:43], v[42:43], v[130:131]
	s_nop 0
	v_mul_f32_e32 v44, 0xbfb8aa3b, v43
	v_exp_f32_e32 v44, v44
	s_nop 0
	v_add_f32_e32 v44, 1.0, v44
	v_rcp_f32_e32 v44, v44
	s_nop 0
	v_mul_f32_e32 v43, v43, v44
	v_mul_f32_e32 v46, v42, v43
	v_mov_b32_e32 v44, v49
	v_pk_mul_f32 v[42:43], v[184:185], v[178:179] op_sel_hi:[0,1]
	v_pk_fma_f32 v[42:43], v[44:45], v[136:137], v[42:43] op_sel_hi:[1,0,1] neg_lo:[0,0,1] neg_hi:[0,0,1]
	s_nop 0
	v_pk_add_f32 v[42:43], v[42:43], v[180:181]
	s_nop 0
	v_mul_f32_e32 v44, 0xbfb8aa3b, v43
	v_exp_f32_e32 v44, v44
	s_nop 0
	v_add_f32_e32 v44, 1.0, v44
	v_rcp_f32_e32 v44, v44
	s_nop 0
	v_mul_f32_e32 v43, v43, v44
	v_mul_f32_e32 v47, v42, v43
	v_mov_b32_e32 v42, v38
	v_mov_b32_e32 v43, v34
	v_pk_mul_f32 v[44:45], v[184:185], v[128:129] op_sel_hi:[0,1]
	v_pk_fma_f32 v[42:43], v[42:43], v[136:137], v[44:45] op_sel_hi:[1,0,1] neg_lo:[0,0,1] neg_hi:[0,0,1]
	s_nop 0
	v_pk_add_f32 v[42:43], v[42:43], v[132:133]
	s_nop 0
	v_mul_f32_e32 v34, 0xbfb8aa3b, v43
	v_exp_f32_e32 v34, v34
	s_nop 0
	v_add_f32_e32 v34, 1.0, v34
	v_rcp_f32_e32 v34, v34
	s_nop 0
	v_mul_f32_e32 v34, v43, v34
	v_mul_f32_e32 v42, v42, v34
	v_mov_b32_e32 v34, v39
	v_pk_mul_f32 v[38:39], v[184:185], v[182:183] op_sel_hi:[0,1]
	v_pk_fma_f32 v[34:35], v[34:35], v[136:137], v[38:39] op_sel_hi:[1,0,1] neg_lo:[0,0,1] neg_hi:[0,0,1]
	s_nop 0
	v_pk_add_f32 v[34:35], v[34:35], v[146:147]
	s_nop 0
	v_mul_f32_e32 v38, 0xbfb8aa3b, v35
	v_exp_f32_e32 v38, v38
	s_nop 0
	v_add_f32_e32 v38, 1.0, v38
	v_rcp_f32_e32 v38, v38
	s_nop 0
	v_mul_f32_e32 v35, v35, v38
	v_mul_f32_e32 v43, v34, v35
	v_mov_b32_e32 v34, v40
	v_mov_b32_e32 v35, v36
	v_pk_mul_f32 v[38:39], v[184:185], v[118:119] op_sel_hi:[0,1]
	v_pk_fma_f32 v[34:35], v[34:35], v[136:137], v[38:39] op_sel_hi:[1,0,1] neg_lo:[0,0,1] neg_hi:[0,0,1]
	v_lshl_add_u64 v[38:39], v[50:51], 0, v[120:121]
	v_pk_add_f32 v[34:35], v[34:35], v[122:123]
	s_nop 0
	v_mul_f32_e32 v36, 0xbfb8aa3b, v35
	v_exp_f32_e32 v36, v36
	s_nop 0
	v_add_f32_e32 v36, 1.0, v36
	v_rcp_f32_e32 v36, v36
	s_nop 0
	v_mul_f32_e32 v35, v35, v36
	v_mul_f32_e32 v40, v34, v35
	v_mov_b32_e32 v36, v41
	v_pk_mul_f32 v[34:35], v[184:185], v[150:151] op_sel_hi:[0,1]
	v_pk_fma_f32 v[34:35], v[36:37], v[136:137], v[34:35] op_sel_hi:[1,0,1] neg_lo:[0,0,1] neg_hi:[0,0,1]
	s_nop 0
	v_pk_add_f32 v[34:35], v[34:35], v[148:149]
	s_nop 0
	v_mul_f32_e32 v36, 0xbfb8aa3b, v35
	v_exp_f32_e32 v36, v36
	s_nop 0
	v_add_f32_e32 v36, 1.0, v36
	v_rcp_f32_e32 v36, v36
	s_nop 0
	v_mul_f32_e32 v35, v35, v36
	v_mul_f32_e32 v37, v34, v35
	v_cvt_pk_bf16_f32 v34, v52, v53
	v_cvt_pk_bf16_f32 v35, v46, v47
	v_cvt_pk_bf16_f32 v36, v42, v43
	v_cvt_pk_bf16_f32 v37, v40, v37
	global_store_dwordx4 v[38:39], v[34:37], off
	v_pk_mul_f32 v[38:39], v[166:167], v[168:169] op_sel_hi:[0,1]
	s_nop 0
	v_mov_b32_e32 v36, v30
	v_mov_b32_e32 v37, v26
	v_pk_fma_f32 v[36:37], v[36:37], v[106:107], v[38:39] op_sel_hi:[1,0,1] neg_lo:[0,0,1] neg_hi:[0,0,1]
	v_mad_i64_i32 v[34:35], s[28:29], v209, s65, v[172:173]
	v_pk_add_f32 v[36:37], v[36:37], v[170:171]
	s_nop 0
	v_mul_f32_e32 v26, 0xbfb8aa3b, v37
	v_exp_f32_e32 v26, v26
	s_nop 0
	v_add_f32_e32 v26, 1.0, v26
	v_rcp_f32_e32 v26, v26
	s_nop 0
	v_mul_f32_e32 v26, v37, v26
	v_mul_f32_e32 v36, v36, v26
	v_mov_b32_e32 v26, v31
	v_pk_mul_f32 v[30:31], v[166:167], v[174:175] op_sel_hi:[0,1]
	v_pk_fma_f32 v[26:27], v[26:27], v[106:107], v[30:31] op_sel_hi:[1,0,1] neg_lo:[0,0,1] neg_hi:[0,0,1]
	s_nop 0
	v_pk_add_f32 v[26:27], v[26:27], v[176:177]
	s_nop 0
	v_mul_f32_e32 v30, 0xbfb8aa3b, v27
	v_exp_f32_e32 v30, v30
	s_nop 0
	v_add_f32_e32 v30, 1.0, v30
	v_rcp_f32_e32 v30, v30
	s_nop 0
	v_mul_f32_e32 v27, v27, v30
	v_mul_f32_e32 v37, v26, v27
	v_mov_b32_e32 v26, v32
	v_mov_b32_e32 v27, v28
	v_pk_mul_f32 v[30:31], v[166:167], v[126:127] op_sel_hi:[0,1]
	v_pk_fma_f32 v[26:27], v[26:27], v[106:107], v[30:31] op_sel_hi:[1,0,1] neg_lo:[0,0,1] neg_hi:[0,0,1]
	s_nop 0
	v_pk_add_f32 v[26:27], v[26:27], v[130:131]
	s_nop 0
	v_mul_f32_e32 v28, 0xbfb8aa3b, v27
	v_exp_f32_e32 v28, v28
	s_nop 0
	v_add_f32_e32 v28, 1.0, v28
	v_rcp_f32_e32 v28, v28
	s_nop 0
	v_mul_f32_e32 v27, v27, v28
	v_mul_f32_e32 v30, v26, v27
	v_mov_b32_e32 v28, v33
	v_pk_mul_f32 v[26:27], v[166:167], v[178:179] op_sel_hi:[0,1]
	v_pk_fma_f32 v[26:27], v[28:29], v[106:107], v[26:27] op_sel_hi:[1,0,1] neg_lo:[0,0,1] neg_hi:[0,0,1]
	s_nop 0
	v_pk_add_f32 v[26:27], v[26:27], v[180:181]
	s_nop 0
	v_mul_f32_e32 v28, 0xbfb8aa3b, v27
	v_exp_f32_e32 v28, v28
	s_nop 0
	v_add_f32_e32 v28, 1.0, v28
	v_rcp_f32_e32 v28, v28
	s_nop 0
	v_mul_f32_e32 v27, v27, v28
	v_mul_f32_e32 v31, v26, v27
	v_mov_b32_e32 v26, v22
	v_mov_b32_e32 v27, v18
	v_pk_mul_f32 v[28:29], v[166:167], v[128:129] op_sel_hi:[0,1]
	v_pk_fma_f32 v[26:27], v[26:27], v[106:107], v[28:29] op_sel_hi:[1,0,1] neg_lo:[0,0,1] neg_hi:[0,0,1]
	s_nop 0
	v_pk_add_f32 v[26:27], v[26:27], v[132:133]
	s_nop 0
	v_mul_f32_e32 v18, 0xbfb8aa3b, v27
	v_exp_f32_e32 v18, v18
	s_nop 0
	v_add_f32_e32 v18, 1.0, v18
	v_rcp_f32_e32 v18, v18
	s_nop 0
	v_mul_f32_e32 v18, v27, v18
	v_mul_f32_e32 v26, v26, v18
	v_mov_b32_e32 v18, v23
	v_pk_mul_f32 v[22:23], v[166:167], v[182:183] op_sel_hi:[0,1]
	v_pk_fma_f32 v[18:19], v[18:19], v[106:107], v[22:23] op_sel_hi:[1,0,1] neg_lo:[0,0,1] neg_hi:[0,0,1]
	s_nop 0
; __device__ __forceinline__ unsigned cvt_pk_bf16(float lo, float hi) { unsigned r; asm volatile("v_cvt_pk_bf16_f32 %0, %1, %2" : "=v"(r) : "v"(lo), "v"(hi)); return r; }
; __device__ __forceinline__ float fast_sigmoid(float x) { return __builtin_amdgcn_rcpf(1.0f + __expf(-x)); }
;     __device__ __forceinline__ void operator()(const f32x4 (&acc)[2][2][4][2], const Unit& u, int wr, int wc, int fr, int fq, PG8_LAS unsigned char* ldsb) const {
;     ...
;                 bf16_t* p = O + (size_t)(row0 + ai * HALF + m * 16) * ldo + col0;
;                 const float rs = rsv[ai][m], ms = msv[ai][m];
;                 float v[8];
; #pragma unroll
;                 for (int n = 0; n < 2; ++n)
; #pragma unroll
;                     for (int i = 0; i < 4; ++i) { const int e = n * 4 + i; const float g = acc[ai][0][m][n][i] * rs - ms * c1g[e] + c2g[e], up = acc[ai][1][m][n][i] * rs - ms * c1u[e] + c2u[e]; v[e] = g * fast_sigmoid(g) * up; }
;                 u32x4 w; w.x = cvt_pk_bf16(v[0], v[1]); w.y = cvt_pk_bf16(v[2], v[3]); w.z = cvt_pk_bf16(v[4], v[5]); w.w = cvt_pk_bf16(v[6], v[7]);
;                 *(u32x4*)p = w;
;             }
	v_pk_add_f32 v[18:19], v[18:19], v[146:147]
	s_nop 0
	v_mul_f32_e32 v22, 0xbfb8aa3b, v19
	v_exp_f32_e32 v22, v22
	s_nop 0
	v_add_f32_e32 v22, 1.0, v22
	v_rcp_f32_e32 v22, v22
	s_nop 0
	v_mul_f32_e32 v19, v19, v22
	v_mul_f32_e32 v27, v18, v19
	v_mov_b32_e32 v18, v24
	v_mov_b32_e32 v19, v20
	v_pk_mul_f32 v[22:23], v[166:167], v[118:119] op_sel_hi:[0,1]
	v_pk_fma_f32 v[18:19], v[18:19], v[106:107], v[22:23] op_sel_hi:[1,0,1] neg_lo:[0,0,1] neg_hi:[0,0,1]
	v_lshl_add_u64 v[22:23], v[34:35], 0, v[120:121]
	v_pk_add_f32 v[18:19], v[18:19], v[122:123]
	s_nop 0
	v_mul_f32_e32 v20, 0xbfb8aa3b, v19
	v_exp_f32_e32 v20, v20
	s_nop 0
	v_add_f32_e32 v20, 1.0, v20
	v_rcp_f32_e32 v20, v20
	s_nop 0
	v_mul_f32_e32 v19, v19, v20
	v_mul_f32_e32 v24, v18, v19
	v_mov_b32_e32 v20, v25
	v_pk_mul_f32 v[18:19], v[166:167], v[150:151] op_sel_hi:[0,1]
	v_pk_fma_f32 v[18:19], v[20:21], v[106:107], v[18:19] op_sel_hi:[1,0,1] neg_lo:[0,0,1] neg_hi:[0,0,1]
	s_nop 0
	v_pk_add_f32 v[18:19], v[18:19], v[148:149]
	s_nop 0
	v_mul_f32_e32 v20, 0xbfb8aa3b, v19
	v_exp_f32_e32 v20, v20
	s_nop 0
	v_add_f32_e32 v20, 1.0, v20
	v_rcp_f32_e32 v20, v20
	s_nop 0
	v_mul_f32_e32 v19, v19, v20
	v_mul_f32_e32 v21, v18, v19
	v_cvt_pk_bf16_f32 v18, v36, v37
	v_cvt_pk_bf16_f32 v19, v30, v31
	v_cvt_pk_bf16_f32 v20, v26, v27
	v_cvt_pk_bf16_f32 v21, v24, v21
	global_store_dwordx4 v[22:23], v[18:21], off
	v_pk_mul_f32 v[22:23], v[0:1], v[168:169] op_sel_hi:[0,1]
	s_nop 0
	v_mov_b32_e32 v20, v14
	v_mov_b32_e32 v21, v10
	v_pk_fma_f32 v[20:21], v[20:21], v[108:109], v[22:23] op_sel_hi:[1,0,1] neg_lo:[0,0,1] neg_hi:[0,0,1]
	v_mad_i64_i32 v[18:19], s[28:29], v208, s65, v[172:173]
	v_pk_add_f32 v[20:21], v[20:21], v[170:171]
	s_mov_b64 s[28:29], -1
	v_mul_f32_e32 v10, 0xbfb8aa3b, v21
	v_exp_f32_e32 v10, v10
	s_nop 0
	v_add_f32_e32 v10, 1.0, v10
	v_rcp_f32_e32 v10, v10
	s_nop 0
	v_mul_f32_e32 v10, v21, v10
	v_mul_f32_e32 v20, v20, v10
	v_mov_b32_e32 v10, v15
	v_pk_mul_f32 v[14:15], v[0:1], v[174:175] op_sel_hi:[0,1]
	v_pk_fma_f32 v[10:11], v[10:11], v[108:109], v[14:15] op_sel_hi:[1,0,1] neg_lo:[0,0,1] neg_hi:[0,0,1]
	s_nop 0
	v_pk_add_f32 v[10:11], v[10:11], v[176:177]
	s_nop 0
	v_mul_f32_e32 v14, 0xbfb8aa3b, v11
	v_exp_f32_e32 v14, v14
	s_nop 0
	v_add_f32_e32 v14, 1.0, v14
	v_rcp_f32_e32 v14, v14
	s_nop 0
	v_mul_f32_e32 v11, v11, v14
	v_mul_f32_e32 v21, v10, v11
	v_mov_b32_e32 v10, v16
	v_mov_b32_e32 v11, v12
	v_pk_mul_f32 v[14:15], v[0:1], v[126:127] op_sel_hi:[0,1]
	v_pk_fma_f32 v[10:11], v[10:11], v[108:109], v[14:15] op_sel_hi:[1,0,1] neg_lo:[0,0,1] neg_hi:[0,0,1]
	s_nop 0
	v_pk_add_f32 v[10:11], v[10:11], v[130:131]
	s_nop 0
	v_mul_f32_e32 v12, 0xbfb8aa3b, v11
	v_exp_f32_e32 v12, v12
	s_nop 0
	v_add_f32_e32 v12, 1.0, v12
	v_rcp_f32_e32 v12, v12
	s_nop 0
	v_mul_f32_e32 v11, v11, v12
	v_mul_f32_e32 v14, v10, v11
	v_mov_b32_e32 v12, v17
	v_pk_mul_f32 v[10:11], v[0:1], v[178:179] op_sel_hi:[0,1]
	v_pk_fma_f32 v[10:11], v[12:13], v[108:109], v[10:11] op_sel_hi:[1,0,1] neg_lo:[0,0,1] neg_hi:[0,0,1]
	s_nop 0
	v_pk_add_f32 v[10:11], v[10:11], v[180:181]
	s_nop 0
	v_mul_f32_e32 v12, 0xbfb8aa3b, v11
	v_exp_f32_e32 v12, v12
	s_nop 0
	v_add_f32_e32 v12, 1.0, v12
	v_rcp_f32_e32 v12, v12
	s_nop 0
	v_mul_f32_e32 v11, v11, v12
	v_mul_f32_e32 v15, v10, v11
	v_mov_b32_e32 v10, v2
	v_mov_b32_e32 v11, v6
	v_pk_mul_f32 v[12:13], v[0:1], v[128:129] op_sel_hi:[0,1]
	v_pk_fma_f32 v[10:11], v[10:11], v[108:109], v[12:13] op_sel_hi:[1,0,1] neg_lo:[0,0,1] neg_hi:[0,0,1]
	v_mov_b32_e32 v6, v3
	v_pk_add_f32 v[10:11], v[10:11], v[132:133]
	s_nop 0
	v_mul_f32_e32 v2, 0xbfb8aa3b, v11
	v_exp_f32_e32 v2, v2
	s_nop 0
	v_add_f32_e32 v2, 1.0, v2
	v_rcp_f32_e32 v2, v2
	s_nop 0
	v_mul_f32_e32 v2, v11, v2
	v_mul_f32_e32 v10, v10, v2
	v_pk_mul_f32 v[2:3], v[0:1], v[182:183] op_sel_hi:[0,1]
	v_pk_fma_f32 v[2:3], v[6:7], v[108:109], v[2:3] op_sel_hi:[1,0,1] neg_lo:[0,0,1] neg_hi:[0,0,1]
	s_nop 0
	v_pk_add_f32 v[2:3], v[2:3], v[146:147]
	s_nop 0
	v_mul_f32_e32 v6, 0xbfb8aa3b, v3
	v_exp_f32_e32 v6, v6
	s_nop 0
	v_add_f32_e32 v6, 1.0, v6
	v_rcp_f32_e32 v6, v6
	s_nop 0
	v_mul_f32_e32 v3, v3, v6
	v_mul_f32_e32 v11, v2, v3
	v_mov_b32_e32 v2, v4
	v_mov_b32_e32 v3, v8
	v_pk_mul_f32 v[6:7], v[0:1], v[118:119] op_sel_hi:[0,1]
	v_pk_fma_f32 v[2:3], v[2:3], v[108:109], v[6:7] op_sel_hi:[1,0,1] neg_lo:[0,0,1] neg_hi:[0,0,1]
	v_mov_b32_e32 v8, v5
	v_pk_add_f32 v[2:3], v[2:3], v[122:123]
	v_lshl_add_u64 v[6:7], v[18:19], 0, v[120:121]
	v_mul_f32_e32 v4, 0xbfb8aa3b, v3
	v_exp_f32_e32 v4, v4
	s_nop 0
	v_add_f32_e32 v4, 1.0, v4
	v_rcp_f32_e32 v4, v4
	s_nop 0
	v_mul_f32_e32 v3, v3, v4
	v_mul_f32_e32 v12, v2, v3
	v_pk_mul_f32 v[2:3], v[0:1], v[150:151] op_sel_hi:[0,1]
	v_pk_fma_f32 v[2:3], v[8:9], v[108:109], v[2:3] op_sel_hi:[1,0,1] neg_lo:[0,0,1] neg_hi:[0,0,1]
	s_nop 0
	v_pk_add_f32 v[2:3], v[2:3], v[148:149]
	s_nop 0
	v_mul_f32_e32 v0, 0xbfb8aa3b, v3
	v_exp_f32_e32 v0, v0
	s_nop 0
	v_add_f32_e32 v0, 1.0, v0
	v_rcp_f32_e32 v0, v0
	s_nop 0
	v_mul_f32_e32 v0, v3, v0
	v_mul_f32_e32 v0, v2, v0
	v_cvt_pk_bf16_f32 v2, v20, v21
	v_cvt_pk_bf16_f32 v3, v14, v15
	v_cvt_pk_bf16_f32 v4, v10, v11
	v_cvt_pk_bf16_f32 v5, v12, v0
	global_store_dwordx4 v[6:7], v[2:5], off
	s_cbranch_vccnz .LBB0_889
	s_andn2_b64 vcc, exec, s[16:17]
	s_cbranch_vccnz .LBB0_888
	s_barrier
	s_branch .LBB0_888

; __device__ __forceinline__ unsigned cvt_pk_bf16(float lo, float hi) { unsigned r; asm volatile("v_cvt_pk_bf16_f32 %0, %1, %2" : "=v"(r) : "v"(lo), "v"(hi)); return r; }
; __device__ __forceinline__ float bflo(unsigned w) { return __uint_as_float(w << 16); }
; __device__ __forceinline__ float bfhi(unsigned w) { return __uint_as_float(w & 0xffff0000u); }
; __global__ void __launch_bounds__(512, 2) mega_fwd(Params P) {
;     ...
;                       for (size_t idx0 = gtid; idx0 < (size_t)T_TOK * 64; idx0 += GT * 4) {
;                         u32x4 xv[4][4];
; #pragma unroll
;                         for (int q = 0; q < 4; ++q) { const size_t idx = idx0 + (size_t)q * GT; const bool ok = idx < (size_t)T_TOK * 64; const int row = ok ? (int)(idx >> 6) : 3, pos = row & (SEQ - 1);
; #pragma unroll
;                             for (int j = 0; j < 4; ++j) xv[q][j] = (pos - 3 + j >= 0) ? *(const u32x4*)(Z + (size_t)(row - 3 + j) * ZW + 2048 + c0) : (u32x4){0u, 0u, 0u, 0u}; }
; #pragma unroll
;                         for (int q = 0; q < 4; ++q) { const size_t idx = idx0 + (size_t)q * GT; if (idx < (size_t)T_TOK * 64) { const int row = (int)(idx >> 6);
;                             f32x4 a0 = bb[0], a1 = bb[1];
; #pragma unroll
;                             for (int j = 0; j < 4; ++j) { const u32x4 v = xv[q][j]; f32x4 x0, x1; x0[0] = bflo(v.x); x0[1] = bfhi(v.x); x0[2] = bflo(v.y); x0[3] = bfhi(v.y); x1[0] = bflo(v.z); x1[1] = bfhi(v.z); x1[2] = bflo(v.w); x1[3] = bfhi(v.w);
;                                 a0 += wv[j][0] * x0; a1 += wv[j][1] * x1; }
;                             u32x4 o; o.x = cvt_pk_bf16(a0[0], a0[1]); o.y = cvt_pk_bf16(a0[2], a0[3]); o.z = cvt_pk_bf16(a1[0], a1[1]); o.w = cvt_pk_bf16(a1[2], a1[3]);
;                             *(u32x4*)(XC + (size_t)row * 512 + c0) = o; } }
.LBB0_926:
	v_alignbit_b32 v0, v107, v106, 6
	v_and_b32_e32 v43, 0x7ff, v0
	v_lshrrev_b64 v[44:45], 6, v[106:107]
	v_cmp_lt_u32_e32 vcc, 2, v43
	v_mov_b32_e32 v46, 0
	v_lshlrev_b32_e32 v0, 1, v108
	v_mov_b32_e32 v54, 0
	v_mov_b32_e32 v55, 0
	v_mov_b32_e32 v56, 0
	v_mov_b32_e32 v57, 0
	s_and_saveexec_b64 s[2:3], vcc
	s_cbranch_execz .LBB0_928
	v_add_u32_e32 v42, -3, v44
	v_mov_b64_e32 v[48:49], s[10:11]
	v_mad_i64_i32 v[48:49], s[4:5], v42, s57, v[48:49]
	v_lshl_add_u64 v[48:49], v[48:49], 0, v[0:1]
	v_add_co_u32_e32 v48, vcc, 0x1000, v48
	s_nop 1
	v_addc_co_u32_e32 v49, vcc, 0, v49, vcc
	global_load_dwordx4 v[54:57], v[48:49], off
.LBB0_928:
	s_or_b64 exec, exec, s[2:3]
	v_cmp_lt_u32_e32 vcc, 1, v43
	v_mov_b32_e32 v47, 0
	v_mov_b32_e32 v48, 0
	v_mov_b32_e32 v49, 0
	s_and_saveexec_b64 s[2:3], vcc
	s_cbranch_execz .LBB0_930
	v_add_u32_e32 v42, -2, v44
	v_mov_b64_e32 v[46:47], s[10:11]
	v_mad_i64_i32 v[46:47], s[4:5], v42, s57, v[46:47]
	v_lshl_add_u64 v[46:47], v[46:47], 0, v[0:1]
	v_add_co_u32_e32 v46, vcc, 0x1000, v46
	s_nop 1
	v_addc_co_u32_e32 v47, vcc, 0, v47, vcc
	global_load_dwordx4 v[46:49], v[46:47], off
.LBB0_930:
	s_or_b64 exec, exec, s[2:3]
	v_mov_b32_e32 v42, 0
	v_cmp_ne_u32_e32 vcc, 0, v43
	v_mov_b32_e32 v70, 0
	v_mov_b32_e32 v71, 0
	v_mov_b32_e32 v72, 0
	v_mov_b32_e32 v73, 0
	s_and_saveexec_b64 s[2:3], vcc
	s_cbranch_execz .LBB0_932
	v_add_u32_e32 v43, -1, v44
	v_mov_b64_e32 v[50:51], s[10:11]
	v_mad_i64_i32 v[50:51], s[4:5], v43, s57, v[50:51]
	v_lshl_add_u64 v[50:51], v[50:51], 0, v[0:1]
	v_add_co_u32_e32 v50, vcc, 0x1000, v50
	s_nop 1
	v_addc_co_u32_e32 v51, vcc, 0, v51, vcc
	global_load_dwordx4 v[70:73], v[50:51], off
.LBB0_932:
	s_or_b64 exec, exec, s[2:3]
	v_mov_b64_e32 v[50:51], s[10:11]
	v_mad_u64_u32 v[50:51], s[2:3], v44, s57, v[50:51]
	v_mov_b32_e32 v44, v51
	v_mad_u64_u32 v[44:45], s[2:3], v45, s57, v[44:45]
	v_mov_b32_e32 v51, v44
	v_lshl_add_u64 v[44:45], v[50:51], 0, v[0:1]
	v_add_co_u32_e32 v44, vcc, s33, v44
	s_nop 1
	v_addc_co_u32_e32 v45, vcc, 0, v45, vcc
	global_load_dwordx4 v[86:89], v[44:45], off
	v_lshl_add_u64 v[44:45], s[8:9], 0, v[106:107]
	v_alignbit_b32 v43, v45, v44, 6
	v_cmp_gt_u64_e64 s[2:3], s[46:47], v[44:45]
	v_mov_b32_e32 v44, 0
	v_mov_b32_e32 v45, 0
	v_cndmask_b32_e64 v50, 3, v43, s[2:3]
	v_and_b32_e32 v51, 0x7ff, v50
	v_cmp_lt_u32_e32 vcc, 2, v51
	v_mov_b32_e32 v43, 0
	s_and_saveexec_b64 s[4:5], vcc
	s_cbranch_execz .LBB0_934
	v_add_u32_e32 v44, -3, v50
	v_mov_b64_e32 v[42:43], s[10:11]
	v_mad_i64_i32 v[42:43], s[6:7], v44, s57, v[42:43]
	v_lshl_add_u64 v[42:43], v[42:43], 0, v[0:1]
	v_add_co_u32_e32 v42, vcc, 0x1000, v42
	s_nop 1
	v_addc_co_u32_e32 v43, vcc, 0, v43, vcc
	global_load_dwordx4 v[42:45], v[42:43], off
.LBB0_934:
	s_or_b64 exec, exec, s[4:5]
	v_cmp_lt_u32_e32 vcc, 1, v51
	v_mov_b32_e32 v62, 0
	v_mov_b32_e32 v74, 0
	v_mov_b32_e32 v75, 0
	v_mov_b32_e32 v76, 0
	v_mov_b32_e32 v77, 0
	s_and_saveexec_b64 s[4:5], vcc
	s_cbranch_execz .LBB0_936
	v_add_u32_e32 v58, -2, v50
	v_mov_b64_e32 v[52:53], s[10:11]
	v_mad_i64_i32 v[52:53], s[6:7], v58, s57, v[52:53]
	v_lshl_add_u64 v[52:53], v[52:53], 0, v[0:1]
	v_add_co_u32_e32 v52, vcc, 0x1000, v52
	s_nop 1
	v_addc_co_u32_e32 v53, vcc, 0, v53, vcc
	global_load_dwordx4 v[74:77], v[52:53], off
.LBB0_936:
	s_or_b64 exec, exec, s[4:5]
	v_cmp_ne_u32_e32 vcc, 0, v51
	v_mov_b32_e32 v63, 0
	v_mov_b32_e32 v64, 0
	v_mov_b32_e32 v65, 0
	s_and_saveexec_b64 s[4:5], vcc
	s_cbranch_execz .LBB0_938
	v_add_u32_e32 v51, -1, v50
	v_mov_b64_e32 v[52:53], s[10:11]
	v_mad_i64_i32 v[52:53], s[6:7], v51, s57, v[52:53]
	v_lshl_add_u64 v[52:53], v[52:53], 0, v[0:1]
	v_add_co_u32_e32 v52, vcc, 0x1000, v52
	s_nop 1
	v_addc_co_u32_e32 v53, vcc, 0, v53, vcc
	global_load_dwordx4 v[62:65], v[52:53], off
.LBB0_938:
	s_or_b64 exec, exec, s[4:5]
	v_mov_b64_e32 v[52:53], s[10:11]
	v_mad_i64_i32 v[50:51], s[4:5], v50, s57, v[52:53]
	v_lshl_add_u64 v[50:51], v[50:51], 0, v[0:1]
	v_add_co_u32_e32 v50, vcc, 0x1000, v50
	v_mov_b32_e32 v58, 0
	s_nop 0
	v_addc_co_u32_e32 v51, vcc, 0, v51, vcc
	global_load_dwordx4 v[94:97], v[50:51], off
	v_lshl_add_u64 v[50:51], s[20:21], 0, v[106:107]
	v_alignbit_b32 v52, v51, v50, 6
	v_cmp_gt_u64_e64 s[4:5], s[46:47], v[50:51]
	v_mov_b32_e32 v78, 0
	v_mov_b32_e32 v79, 0
	v_cndmask_b32_e64 v51, 3, v52, s[4:5]
	v_and_b32_e32 v52, 0x7ff, v51
	v_cmp_lt_u32_e32 vcc, 2, v52
	v_mov_b32_e32 v80, 0
	v_mov_b32_e32 v81, 0
	s_and_saveexec_b64 s[6:7], vcc
	s_cbranch_execz .LBB0_940
	v_add_u32_e32 v50, -3, v51
	v_mov_b64_e32 v[60:61], s[10:11]
	v_mad_i64_i32 v[60:61], s[28:29], v50, s57, v[60:61]
	v_lshl_add_u64 v[60:61], v[60:61], 0, v[0:1]
	v_add_co_u32_e32 v60, vcc, 0x1000, v60
	s_nop 1
	v_addc_co_u32_e32 v61, vcc, 0, v61, vcc
	global_load_dwordx4 v[78:81], v[60:61], off
.LBB0_940:
	s_or_b64 exec, exec, s[6:7]
	v_cmp_lt_u32_e32 vcc, 1, v52
	v_mov_b32_e32 v59, 0
	v_mov_b32_e32 v60, 0
	v_mov_b32_e32 v61, 0
	s_and_saveexec_b64 s[6:7], vcc
	s_cbranch_execz .LBB0_942
	v_add_u32_e32 v50, -2, v51
	v_mov_b64_e32 v[58:59], s[10:11]
	v_mad_i64_i32 v[58:59], s[28:29], v50, s57, v[58:59]
	v_lshl_add_u64 v[58:59], v[58:59], 0, v[0:1]
	v_add_co_u32_e32 v58, vcc, 0x1000, v58
	s_nop 1
	v_addc_co_u32_e32 v59, vcc, 0, v59, vcc
	global_load_dwordx4 v[58:61], v[58:59], off
; __device__ __forceinline__ unsigned cvt_pk_bf16(float lo, float hi) { unsigned r; asm volatile("v_cvt_pk_bf16_f32 %0, %1, %2" : "=v"(r) : "v"(lo), "v"(hi)); return r; }
; __device__ __forceinline__ float bflo(unsigned w) { return __uint_as_float(w << 16); }
; __device__ __forceinline__ float bfhi(unsigned w) { return __uint_as_float(w & 0xffff0000u); }
; __global__ void __launch_bounds__(512, 2) mega_fwd(Params P) {
;     ...
;                         for (int q = 0; q < 4; ++q) { const size_t idx = idx0 + (size_t)q * GT; const bool ok = idx < (size_t)T_TOK * 64; const int row = ok ? (int)(idx >> 6) : 3, pos = row & (SEQ - 1);
; #pragma unroll
;                             for (int j = 0; j < 4; ++j) xv[q][j] = (pos - 3 + j >= 0) ? *(const u32x4*)(Z + (size_t)(row - 3 + j) * ZW + 2048 + c0) : (u32x4){0u, 0u, 0u, 0u}; }
; #pragma unroll
;                         for (int q = 0; q < 4; ++q) { const size_t idx = idx0 + (size_t)q * GT; if (idx < (size_t)T_TOK * 64) { const int row = (int)(idx >> 6);
;                             f32x4 a0 = bb[0], a1 = bb[1];
; #pragma unroll
;                             for (int j = 0; j < 4; ++j) { const u32x4 v = xv[q][j]; f32x4 x0, x1; x0[0] = bflo(v.x); x0[1] = bfhi(v.x); x0[2] = bflo(v.y); x0[3] = bfhi(v.y); x1[0] = bflo(v.z); x1[1] = bfhi(v.z); x1[2] = bflo(v.w); x1[3] = bfhi(v.w);
;                                 a0 += wv[j][0] * x0; a1 += wv[j][1] * x1; }
;                             u32x4 o; o.x = cvt_pk_bf16(a0[0], a0[1]); o.y = cvt_pk_bf16(a0[2], a0[3]); o.z = cvt_pk_bf16(a1[0], a1[1]); o.w = cvt_pk_bf16(a1[2], a1[3]);
;                             *(u32x4*)(XC + (size_t)row * 512 + c0) = o; } }
.LBB0_942:
	s_or_b64 exec, exec, s[6:7]
	v_mov_b32_e32 v50, 0
	v_cmp_ne_u32_e32 vcc, 0, v52
	v_mov_b32_e32 v90, 0
	v_mov_b32_e32 v91, 0
	v_mov_b32_e32 v92, 0
	v_mov_b32_e32 v93, 0
	s_and_saveexec_b64 s[6:7], vcc
	s_cbranch_execz .LBB0_944
	v_add_u32_e32 v66, -1, v51
	v_mov_b64_e32 v[52:53], s[10:11]
	v_mad_i64_i32 v[52:53], s[28:29], v66, s57, v[52:53]
	v_lshl_add_u64 v[52:53], v[52:53], 0, v[0:1]
	v_add_co_u32_e32 v52, vcc, 0x1000, v52
	s_nop 1
	v_addc_co_u32_e32 v53, vcc, 0, v53, vcc
	global_load_dwordx4 v[90:93], v[52:53], off
.LBB0_944:
	s_or_b64 exec, exec, s[6:7]
	v_mov_b64_e32 v[52:53], s[10:11]
	v_mad_i64_i32 v[52:53], s[6:7], v51, s57, v[52:53]
	v_lshl_add_u64 v[52:53], v[52:53], 0, v[0:1]
	v_add_co_u32_e32 v52, vcc, 0x1000, v52
	s_nop 1
	v_addc_co_u32_e32 v53, vcc, 0, v53, vcc
	global_load_dwordx4 v[98:101], v[52:53], off
	v_lshl_add_u64 v[52:53], s[36:37], 0, v[106:107]
	v_alignbit_b32 v51, v53, v52, 6
	v_cmp_gt_u64_e64 s[6:7], s[46:47], v[52:53]
	v_mov_b32_e32 v52, 0
	v_mov_b32_e32 v53, 0
	s_waitcnt vmcnt(0) lgkmcnt(0)
	v_cndmask_b32_e64 v102, 3, v51, s[6:7]
	v_and_b32_e32 v67, 0x7ff, v102
	v_cmp_lt_u32_e32 vcc, 2, v67
	v_mov_b32_e32 v51, 0
	s_and_saveexec_b64 s[28:29], vcc
	s_cbranch_execz .LBB0_946
	v_add_u32_e32 v52, -3, v102
	v_mov_b64_e32 v[50:51], s[10:11]
	v_mad_i64_i32 v[50:51], s[30:31], v52, s57, v[50:51]
	v_lshl_add_u64 v[50:51], v[50:51], 0, v[0:1]
	v_add_co_u32_e32 v50, vcc, 0x1000, v50
	s_nop 1
	v_addc_co_u32_e32 v51, vcc, 0, v51, vcc
	global_load_dwordx4 v[50:53], v[50:51], off
.LBB0_946:
	s_or_b64 exec, exec, s[28:29]
	v_cmp_lt_u32_e32 vcc, 1, v67
	v_mov_b32_e32 v66, 0
	v_mov_b32_e32 v82, 0
	v_mov_b32_e32 v83, 0
	v_mov_b32_e32 v84, 0
	v_mov_b32_e32 v85, 0
	s_and_saveexec_b64 s[28:29], vcc
	s_cbranch_execz .LBB0_948
	v_add_u32_e32 v82, -2, v102
	v_mov_b64_e32 v[68:69], s[10:11]
	v_mad_i64_i32 v[68:69], s[30:31], v82, s57, v[68:69]
	v_lshl_add_u64 v[68:69], v[68:69], 0, v[0:1]
	v_add_co_u32_e32 v68, vcc, 0x1000, v68
	s_nop 1
	v_addc_co_u32_e32 v69, vcc, 0, v69, vcc
	global_load_dwordx4 v[82:85], v[68:69], off
.LBB0_948:
	s_or_b64 exec, exec, s[28:29]
	v_cmp_ne_u32_e32 vcc, 0, v67
	v_mov_b32_e32 v67, 0
	v_mov_b32_e32 v68, 0
	v_mov_b32_e32 v69, 0
	s_and_saveexec_b64 s[28:29], vcc
	s_cbranch_execz .LBB0_950
	v_add_u32_e32 v68, -1, v102
	v_mov_b64_e32 v[66:67], s[10:11]
	v_mad_i64_i32 v[66:67], s[30:31], v68, s57, v[66:67]
	v_lshl_add_u64 v[66:67], v[66:67], 0, v[0:1]
	v_add_co_u32_e32 v66, vcc, 0x1000, v66
	s_nop 1
	v_addc_co_u32_e32 v67, vcc, 0, v67, vcc
	global_load_dwordx4 v[66:69], v[66:67], off
.LBB0_950:
	s_or_b64 exec, exec, s[28:29]
	v_mov_b64_e32 v[104:105], s[10:11]
	v_mad_i64_i32 v[102:103], s[28:29], v102, s57, v[104:105]
	v_lshl_add_u64 v[102:103], v[102:103], 0, v[0:1]
	v_add_co_u32_e32 v102, vcc, 0x1000, v102
	s_waitcnt vmcnt(0) lgkmcnt(0)
	v_lshlrev_b32_e32 v114, 16, v54
	v_addc_co_u32_e32 v103, vcc, 0, v103, vcc
	global_load_dwordx4 v[102:105], v[102:103], off
	v_and_b32_e32 v115, 0xffff0000, v54
	v_lshlrev_b32_e32 v54, 16, v55
	v_and_b32_e32 v55, 0xffff0000, v55
	v_lshlrev_b32_e32 v116, 16, v56
	v_and_b32_e32 v117, 0xffff0000, v56
	v_lshlrev_b32_e32 v56, 16, v57
	v_and_b32_e32 v57, 0xffff0000, v57
	v_pk_fma_f32 v[114:115], v[6:7], v[114:115], v[38:39]
	v_pk_fma_f32 v[54:55], v[8:9], v[54:55], v[40:41]
	v_pk_fma_f32 v[116:117], v[2:3], v[116:117], v[34:35]
	v_pk_fma_f32 v[56:57], v[4:5], v[56:57], v[36:37]
	v_lshlrev_b32_e32 v118, 16, v46
	v_and_b32_e32 v119, 0xffff0000, v46
	v_lshlrev_b32_e32 v46, 16, v47
	v_and_b32_e32 v47, 0xffff0000, v47
	v_lshlrev_b32_e32 v120, 16, v48
	v_and_b32_e32 v121, 0xffff0000, v48
	v_lshlrev_b32_e32 v48, 16, v49
	v_and_b32_e32 v49, 0xffff0000, v49
	v_pk_fma_f32 v[46:47], v[16:17], v[46:47], v[54:55]
	v_pk_fma_f32 v[54:55], v[14:15], v[118:119], v[114:115]
	v_pk_fma_f32 v[48:49], v[12:13], v[48:49], v[56:57]
	v_pk_fma_f32 v[56:57], v[10:11], v[120:121], v[116:117]
	v_lshlrev_b32_e32 v114, 16, v70
	v_and_b32_e32 v115, 0xffff0000, v70
	v_lshlrev_b32_e32 v70, 16, v71
	v_and_b32_e32 v71, 0xffff0000, v71
	v_lshlrev_b32_e32 v116, 16, v72
	v_and_b32_e32 v117, 0xffff0000, v72
	v_lshlrev_b32_e32 v72, 16, v73
	v_and_b32_e32 v73, 0xffff0000, v73
	v_pk_fma_f32 v[54:55], v[18:19], v[114:115], v[54:55]
	v_pk_fma_f32 v[46:47], v[20:21], v[70:71], v[46:47]
	v_pk_fma_f32 v[56:57], v[22:23], v[116:117], v[56:57]
	v_pk_fma_f32 v[48:49], v[24:25], v[72:73], v[48:49]
	v_lshlrev_b32_e32 v70, 16, v86
	v_and_b32_e32 v71, 0xffff0000, v86
	v_lshlrev_b32_e32 v72, 16, v87
	v_and_b32_e32 v73, 0xffff0000, v87
	v_lshlrev_b32_e32 v86, 16, v88
	v_and_b32_e32 v87, 0xffff0000, v88
	v_lshlrev_b32_e32 v88, 16, v89
	v_and_b32_e32 v89, 0xffff0000, v89
	v_and_b32_e32 v0, 0x1fffe00, v112
	v_pk_fma_f32 v[72:73], v[28:29], v[72:73], v[46:47]
	v_pk_fma_f32 v[46:47], v[26:27], v[70:71], v[54:55]
	v_pk_fma_f32 v[54:55], v[32:33], v[88:89], v[48:49]
	v_pk_fma_f32 v[48:49], v[30:31], v[86:87], v[56:57]
	v_lshlrev_b32_e32 v0, 1, v0
	v_cvt_pk_bf16_f32 v46, v46, v47
	v_cvt_pk_bf16_f32 v47, v72, v73
	v_cvt_pk_bf16_f32 v48, v48, v49
	v_cvt_pk_bf16_f32 v49, v54, v55
	v_lshl_add_u64 v[54:55], v[110:111], 0, v[0:1]
	global_store_dwordx4 v[54:55], v[46:49], off
	s_and_saveexec_b64 s[28:29], s[2:3]
	s_cbranch_execnz .LBB0_953
	s_or_b64 exec, exec, s[28:29]
	s_and_saveexec_b64 s[2:3], s[4:5]
	s_cbranch_execnz .LBB0_954

; __device__ __forceinline__ unsigned cvt_pk_bf16(float lo, float hi) { unsigned r; asm volatile("v_cvt_pk_bf16_f32 %0, %1, %2" : "=v"(r) : "v"(lo), "v"(hi)); return r; }
; __device__ __forceinline__ float bflo(unsigned w) { return __uint_as_float(w << 16); }
; __device__ __forceinline__ float bfhi(unsigned w) { return __uint_as_float(w & 0xffff0000u); }
; __global__ void __launch_bounds__(512, 2) mega_fwd(Params P) {
;     ...
;                         for (int q = 0; q < 4; ++q) { const size_t idx = idx0 + (size_t)q * GT; if (idx < (size_t)T_TOK * 64) { const int row = (int)(idx >> 6);
;                             f32x4 a0 = bb[0], a1 = bb[1];
; #pragma unroll
;                             for (int j = 0; j < 4; ++j) { const u32x4 v = xv[q][j]; f32x4 x0, x1; x0[0] = bflo(v.x); x0[1] = bfhi(v.x); x0[2] = bflo(v.y); x0[3] = bfhi(v.y); x1[0] = bflo(v.z); x1[1] = bfhi(v.z); x1[2] = bflo(v.w); x1[3] = bfhi(v.w);
;                                 a0 += wv[j][0] * x0; a1 += wv[j][1] * x1; }
;                             u32x4 o; o.x = cvt_pk_bf16(a0[0], a0[1]); o.y = cvt_pk_bf16(a0[2], a0[3]); o.z = cvt_pk_bf16(a1[0], a1[1]); o.w = cvt_pk_bf16(a1[2], a1[3]);
;                             *(u32x4*)(XC + (size_t)row * 512 + c0) = o; } }
.LBB0_953:
	v_lshlrev_b32_e32 v46, 16, v42
	v_and_b32_e32 v47, 0xffff0000, v42
	v_lshlrev_b32_e32 v42, 16, v43
	v_and_b32_e32 v43, 0xffff0000, v43
	v_lshlrev_b32_e32 v48, 16, v44
	v_and_b32_e32 v49, 0xffff0000, v44
	v_lshlrev_b32_e32 v44, 16, v45
	v_and_b32_e32 v45, 0xffff0000, v45
	v_pk_fma_f32 v[46:47], v[6:7], v[46:47], v[38:39]
	v_pk_fma_f32 v[42:43], v[8:9], v[42:43], v[40:41]
	v_pk_fma_f32 v[48:49], v[2:3], v[48:49], v[34:35]
	v_pk_fma_f32 v[44:45], v[4:5], v[44:45], v[36:37]
	v_lshlrev_b32_e32 v54, 16, v74
	v_and_b32_e32 v55, 0xffff0000, v74
	v_lshlrev_b32_e32 v56, 16, v75
	v_and_b32_e32 v57, 0xffff0000, v75
	v_lshlrev_b32_e32 v70, 16, v76
	v_and_b32_e32 v71, 0xffff0000, v76
	v_lshlrev_b32_e32 v72, 16, v77
	v_and_b32_e32 v73, 0xffff0000, v77
	v_pk_fma_f32 v[42:43], v[16:17], v[56:57], v[42:43]
	v_pk_fma_f32 v[46:47], v[14:15], v[54:55], v[46:47]
	v_pk_fma_f32 v[44:45], v[12:13], v[72:73], v[44:45]
	v_pk_fma_f32 v[48:49], v[10:11], v[70:71], v[48:49]
	v_lshlrev_b32_e32 v54, 16, v62
	v_and_b32_e32 v55, 0xffff0000, v62
	v_lshlrev_b32_e32 v56, 16, v63
	v_and_b32_e32 v57, 0xffff0000, v63
	v_lshlrev_b32_e32 v62, 16, v64
	v_and_b32_e32 v63, 0xffff0000, v64
	v_lshlrev_b32_e32 v64, 16, v65
	v_and_b32_e32 v65, 0xffff0000, v65
	v_add_u32_e32 v0, s24, v112
	v_pk_fma_f32 v[46:47], v[18:19], v[54:55], v[46:47]
	v_pk_fma_f32 v[42:43], v[20:21], v[56:57], v[42:43]
	v_pk_fma_f32 v[48:49], v[22:23], v[62:63], v[48:49]
	v_pk_fma_f32 v[44:45], v[24:25], v[64:65], v[44:45]
	v_lshlrev_b32_e32 v54, 16, v94
	v_and_b32_e32 v55, 0xffff0000, v94
	v_lshlrev_b32_e32 v56, 16, v95
	v_and_b32_e32 v57, 0xffff0000, v95
	v_lshlrev_b32_e32 v62, 16, v96
	v_and_b32_e32 v63, 0xffff0000, v96
	v_lshlrev_b32_e32 v64, 16, v97
	v_and_b32_e32 v65, 0xffff0000, v97
	v_and_b32_e32 v0, 0x1fffe00, v0
	v_pk_fma_f32 v[56:57], v[28:29], v[56:57], v[42:43]
	v_pk_fma_f32 v[42:43], v[26:27], v[54:55], v[46:47]
	v_pk_fma_f32 v[46:47], v[32:33], v[64:65], v[44:45]
	v_pk_fma_f32 v[44:45], v[30:31], v[62:63], v[48:49]
	v_lshlrev_b32_e32 v0, 1, v0
	v_cvt_pk_bf16_f32 v42, v42, v43
	v_cvt_pk_bf16_f32 v43, v56, v57
	v_cvt_pk_bf16_f32 v44, v44, v45
	v_cvt_pk_bf16_f32 v45, v46, v47
	v_lshl_add_u64 v[46:47], v[110:111], 0, v[0:1]
	global_store_dwordx4 v[46:47], v[42:45], off
	s_or_b64 exec, exec, s[28:29]
	s_and_saveexec_b64 s[2:3], s[4:5]
	s_cbranch_execz .LBB0_952
.LBB0_954:
	v_lshlrev_b32_e32 v42, 16, v78
	v_and_b32_e32 v43, 0xffff0000, v78
	v_lshlrev_b32_e32 v44, 16, v79
	v_and_b32_e32 v45, 0xffff0000, v79
	v_lshlrev_b32_e32 v46, 16, v80
	v_and_b32_e32 v47, 0xffff0000, v80
	v_pk_fma_f32 v[42:43], v[6:7], v[42:43], v[38:39]
	v_pk_fma_f32 v[44:45], v[8:9], v[44:45], v[40:41]
	v_pk_fma_f32 v[46:47], v[2:3], v[46:47], v[34:35]
	v_lshlrev_b32_e32 v54, 16, v58
	v_and_b32_e32 v55, 0xffff0000, v58
	v_lshlrev_b32_e32 v56, 16, v59
	v_and_b32_e32 v57, 0xffff0000, v59
	v_lshlrev_b32_e32 v58, 16, v60
	v_and_b32_e32 v59, 0xffff0000, v60
	v_lshlrev_b32_e32 v48, 16, v81
	v_and_b32_e32 v49, 0xffff0000, v81
	v_pk_fma_f32 v[44:45], v[16:17], v[56:57], v[44:45]
	v_pk_fma_f32 v[42:43], v[14:15], v[54:55], v[42:43]
	v_pk_fma_f32 v[46:47], v[10:11], v[58:59], v[46:47]
	v_lshlrev_b32_e32 v54, 16, v90
	v_and_b32_e32 v55, 0xffff0000, v90
	v_lshlrev_b32_e32 v56, 16, v91
	v_and_b32_e32 v57, 0xffff0000, v91
	v_lshlrev_b32_e32 v58, 16, v92
	v_and_b32_e32 v59, 0xffff0000, v92
	v_add_u32_e32 v0, s22, v112
	v_pk_fma_f32 v[48:49], v[4:5], v[48:49], v[36:37]
	v_lshlrev_b32_e32 v60, 16, v61
	v_and_b32_e32 v61, 0xffff0000, v61
	v_pk_fma_f32 v[42:43], v[18:19], v[54:55], v[42:43]
	v_pk_fma_f32 v[44:45], v[20:21], v[56:57], v[44:45]
	v_pk_fma_f32 v[46:47], v[22:23], v[58:59], v[46:47]
	v_lshlrev_b32_e32 v54, 16, v98
	v_and_b32_e32 v55, 0xffff0000, v98
	v_lshlrev_b32_e32 v56, 16, v99
	v_and_b32_e32 v57, 0xffff0000, v99
	v_lshlrev_b32_e32 v58, 16, v100
	v_and_b32_e32 v59, 0xffff0000, v100
	v_and_b32_e32 v0, 0x1fffe00, v0
	v_pk_fma_f32 v[48:49], v[12:13], v[60:61], v[48:49]
	v_lshlrev_b32_e32 v60, 16, v93
	v_and_b32_e32 v61, 0xffff0000, v93
	v_pk_fma_f32 v[44:45], v[28:29], v[56:57], v[44:45]
	v_pk_fma_f32 v[42:43], v[26:27], v[54:55], v[42:43]
	v_pk_fma_f32 v[46:47], v[30:31], v[58:59], v[46:47]
	v_lshlrev_b32_e32 v0, 1, v0
	v_pk_fma_f32 v[48:49], v[24:25], v[60:61], v[48:49]
	v_lshlrev_b32_e32 v60, 16, v101
	v_and_b32_e32 v61, 0xffff0000, v101
	v_cvt_pk_bf16_f32 v42, v42, v43
	v_cvt_pk_bf16_f32 v43, v44, v45
	v_cvt_pk_bf16_f32 v44, v46, v47
	v_lshl_add_u64 v[46:47], v[110:111], 0, v[0:1]
	v_pk_fma_f32 v[48:49], v[32:33], v[60:61], v[48:49]
	s_nop 0
	v_cvt_pk_bf16_f32 v45, v48, v49
	global_store_dwordx4 v[46:47], v[42:45], off
	s_or_b64 exec, exec, s[2:3]
	s_and_saveexec_b64 s[2:3], s[6:7]
	s_cbranch_execz .LBB0_925
.LBB0_955:
	v_lshlrev_b32_e32 v42, 16, v50
	v_and_b32_e32 v43, 0xffff0000, v50
	v_lshlrev_b32_e32 v44, 16, v51
	v_and_b32_e32 v45, 0xffff0000, v51
	v_lshlrev_b32_e32 v46, 16, v52
	v_and_b32_e32 v47, 0xffff0000, v52
	v_lshlrev_b32_e32 v48, 16, v53
	v_and_b32_e32 v49, 0xffff0000, v53
	v_pk_fma_f32 v[42:43], v[6:7], v[42:43], v[38:39]
	v_pk_fma_f32 v[44:45], v[8:9], v[44:45], v[40:41]
	v_pk_fma_f32 v[46:47], v[2:3], v[46:47], v[34:35]
	v_lshlrev_b32_e32 v50, 16, v82
	v_and_b32_e32 v51, 0xffff0000, v82
	v_lshlrev_b32_e32 v52, 16, v83
	v_and_b32_e32 v53, 0xffff0000, v83
	v_lshlrev_b32_e32 v54, 16, v84
	v_and_b32_e32 v55, 0xffff0000, v84
	v_pk_fma_f32 v[44:45], v[16:17], v[52:53], v[44:45]
	v_pk_fma_f32 v[42:43], v[14:15], v[50:51], v[42:43]
	v_pk_fma_f32 v[46:47], v[10:11], v[54:55], v[46:47]
	v_lshlrev_b32_e32 v50, 16, v66
	v_and_b32_e32 v51, 0xffff0000, v66
	v_lshlrev_b32_e32 v52, 16, v67
	v_and_b32_e32 v53, 0xffff0000, v67
	v_lshlrev_b32_e32 v54, 16, v68
	v_and_b32_e32 v55, 0xffff0000, v68
	v_add_u32_e32 v0, s1, v112
	v_pk_fma_f32 v[48:49], v[4:5], v[48:49], v[36:37]
	v_lshlrev_b32_e32 v56, 16, v85
	v_and_b32_e32 v57, 0xffff0000, v85
	v_pk_fma_f32 v[42:43], v[18:19], v[50:51], v[42:43]
	v_pk_fma_f32 v[44:45], v[20:21], v[52:53], v[44:45]
	v_pk_fma_f32 v[46:47], v[22:23], v[54:55], v[46:47]
	s_waitcnt vmcnt(0) lgkmcnt(0)
	v_lshlrev_b32_e32 v50, 16, v102
	v_and_b32_e32 v51, 0xffff0000, v102
	v_lshlrev_b32_e32 v52, 16, v103
	v_and_b32_e32 v53, 0xffff0000, v103
	v_lshlrev_b32_e32 v54, 16, v104
	v_and_b32_e32 v55, 0xffff0000, v104
	v_and_b32_e32 v0, 0x1fffe00, v0
	v_pk_fma_f32 v[48:49], v[12:13], v[56:57], v[48:49]
	v_lshlrev_b32_e32 v56, 16, v69
	v_and_b32_e32 v57, 0xffff0000, v69
	v_pk_fma_f32 v[44:45], v[28:29], v[52:53], v[44:45]
	v_pk_fma_f32 v[42:43], v[26:27], v[50:51], v[42:43]
	v_pk_fma_f32 v[46:47], v[30:31], v[54:55], v[46:47]
	v_lshlrev_b32_e32 v0, 1, v0
	v_pk_fma_f32 v[48:49], v[24:25], v[56:57], v[48:49]
	v_lshlrev_b32_e32 v56, 16, v105
	v_and_b32_e32 v57, 0xffff0000, v105
	v_cvt_pk_bf16_f32 v42, v42, v43
	v_cvt_pk_bf16_f32 v43, v44, v45
	v_cvt_pk_bf16_f32 v44, v46, v47
	v_lshl_add_u64 v[46:47], v[110:111], 0, v[0:1]
	v_pk_fma_f32 v[48:49], v[32:33], v[56:57], v[48:49]
	s_nop 0
	v_cvt_pk_bf16_f32 v45, v48, v49
	global_store_dwordx4 v[46:47], v[42:45], off
	s_branch .LBB0_925

; #define PG8_STAGE(bufoff, gbase, voff) do { _Pragma("unroll") for (int _i = 0; _i < 2; ++_i) \
;         __builtin_amdgcn_global_load_lds((const unsigned*)((const char*)(gbase) + (voff)[_i]), (PG8_LAS unsigned*)(lds + (bufoff) + ldsw + _i * 8192), 16, 0, 0); } while (0)
; #define PG8_LDA(dst, b, h) do { _Pragma("unroll") for (int m = 0; m < 4; ++m) _Pragma("unroll") for (int k = 0; k < 2; ++k) dst[m][k] = *(const PG8_LAS bf16x8*)(lds + PG8_SA(b, h) + aoff + m * 2048 + k * 1024); } while (0)
; #define PG8_LDB(dst, b, h) do { _Pragma("unroll") for (int n = 0; n < 2; ++n) _Pragma("unroll") for (int k = 0; k < 2; ++k) dst[n][k] = *(const PG8_LAS bf16x8*)(lds + PG8_SB(b, h) + boff + n * 2048 + k * 1024); } while (0)
; template <class Epi, class Sched, bool ALIGN_EPI = false, bool SP2 = false>
; __device__ __forceinline__ void gemm_phase(PG8_LAS unsigned char* lds, const Gemm g, const Sched& S, const Epi& E) {
;     ...
;         for (int t = 0; t < nt; t += 2) {
;             const bool last = (t == nt - 2);
;             const char* a1 = cA + (size_t)(t + 1) * kstep;
;             const char* a2 = last ? nA : cA + (size_t)(t + 2) * kstep; const char* b2 = last ? nB : cB + (size_t)(t + 2) * kstep;
;             const char* a3 = a2 + kstep; const char* b3 = b2 + kstep;
;             if (last && has_next) S.a_ready(nxt);
;             if constexpr (SP2) {
;             PG8_LDB(B0, 0, 0); PG8_LDB(B1, 0, 1); PG8_SCHED; PG8_LDA(At, 0, 0); PG8_STAGE(PG8_SA(1, 1), a1 + hstep, voffA);
;             PG8_WAIT_V(8); PG8_WAIT_L(0); PG8_BAR; PG8_MMA(0, 0, At, B0); PG8_MMA(0, 1, At, B1); PG8_BAR; PG8_SCHED;
;             PG8_LDA(At, 0, 1); PG8_STAGE(PG8_SB(0, 0), b2, voffB); PG8_STAGE(PG8_SB(0, 1), b2 + hstep, voffB); PG8_STAGE(PG8_SA(0, 0), a2, voffA);
;             PG8_WAIT_V(8); PG8_WAIT_L(0); PG8_BAR; PG8_MMA(1, 0, At, B0); PG8_MMA(1, 1, At, B1); PG8_BAR; PG8_SCHED;
;             PG8_LDB(B0, 1, 0); PG8_LDB(B1, 1, 1); PG8_SCHED; PG8_LDA(At, 1, 0); PG8_STAGE(PG8_SA(0, 1), a2 + hstep, voffA);
;             PG8_WAIT_V(8); PG8_WAIT_L(0); PG8_BAR; PG8_MMA(0, 0, At, B0); PG8_MMA(0, 1, At, B1); PG8_BAR; PG8_SCHED;
;             PG8_LDA(At, 1, 1); PG8_STAGE(PG8_SB(1, 0), b3, voffB); PG8_STAGE(PG8_SB(1, 1), b3 + hstep, voffB); PG8_STAGE(PG8_SA(1, 0), a3, voffA);
;             PG8_WAIT_V(8); PG8_WAIT_L(0); PG8_BAR; PG8_MMA(1, 0, At, B0); PG8_MMA(1, 1, At, B1); PG8_BAR; PG8_SCHED;
.LBB0_1040:
	s_add_i32 s48, s46, 2
	s_add_u32 s49, s4, 0x80
	s_addc_u32 s47, s5, 0
	s_add_i32 s76, 0, 0x10000
	s_cmp_eq_u32 s42, s46
	s_cselect_b32 s47, s29, s47
	s_cselect_b32 s46, s28, s49
	v_add_u32_e32 v0, s76, v212
	s_cselect_b32 s75, s31, s61
	s_cselect_b32 s74, s30, s56
	s_add_i32 s49, 0, 0x14000
	ds_read_b128 v[18:21], v0
	ds_read_b128 v[22:25], v0 offset:1024
	ds_read_b128 v[26:29], v0 offset:2048
	ds_read_b128 v[38:41], v0 offset:3072
	v_add_u32_e32 v0, s49, v212
	ds_read_b128 v[42:45], v0
	ds_read_b128 v[46:49], v0 offset:1024
	ds_read_b128 v[50:53], v0 offset:2048
	ds_read_b128 v[70:73], v0 offset:3072
	v_lshl_add_u64 v[230:231], s[4:5], 0, v[204:205]
	s_add_i32 m0, s94, 0xc000
	ds_read_b128 v[90:93], v216
	ds_read_b128 v[110:113], v216 offset:1024
	ds_read_b128 v[130:133], v216 offset:2048
	ds_read_b128 v[150:153], v216 offset:3072
	ds_read_b128 v[170:173], v216 offset:4096
	ds_read_b128 v[182:185], v216 offset:5120
	ds_read_b128 v[206:209], v216 offset:6144
	ds_read_b128 v[226:229], v216 offset:7168
	global_load_lds_dwordx4 v[230:231], off
	v_lshl_add_u64 v[230:231], s[4:5], 0, v[202:203]
	s_add_i32 m0, s94, 0xe000
	s_nop 0
	global_load_lds_dwordx4 v[230:231], off
	s_waitcnt vmcnt(8)
	s_waitcnt lgkmcnt(0)
	s_barrier
	s_setprio 1
	v_mfma_f32_16x16x32_bf16 v[178:181], v[18:21], v[90:93], v[178:181]
	v_mfma_f32_16x16x32_bf16 v[166:169], v[26:29], v[90:93], v[166:169]
	v_mfma_f32_16x16x32_bf16 v[158:161], v[18:21], v[130:133], v[158:161]
	v_mfma_f32_16x16x32_bf16 v[146:149], v[26:29], v[130:133], v[146:149]
	v_mfma_f32_16x16x32_bf16 v[138:141], v[18:21], v[170:173], v[138:141]
	v_mfma_f32_16x16x32_bf16 v[126:129], v[26:29], v[170:173], v[126:129]
	v_mfma_f32_16x16x32_bf16 v[118:121], v[18:21], v[206:209], v[118:121]
	v_mfma_f32_16x16x32_bf16 v[106:109], v[26:29], v[206:209], v[106:109]
	v_mfma_f32_16x16x32_bf16 v[178:181], v[22:25], v[110:113], v[178:181]
	v_mfma_f32_16x16x32_bf16 v[166:169], v[38:41], v[110:113], v[166:169]
	v_mfma_f32_16x16x32_bf16 v[158:161], v[22:25], v[150:153], v[158:161]
	v_mfma_f32_16x16x32_bf16 v[146:149], v[38:41], v[150:153], v[146:149]
	v_mfma_f32_16x16x32_bf16 v[138:141], v[22:25], v[182:185], v[138:141]
	v_mfma_f32_16x16x32_bf16 v[126:129], v[38:41], v[182:185], v[126:129]
	v_mfma_f32_16x16x32_bf16 v[118:121], v[22:25], v[226:229], v[118:121]
	v_mfma_f32_16x16x32_bf16 v[106:109], v[38:41], v[226:229], v[106:109]
	s_setprio 0
	s_setprio 1
	v_mfma_f32_16x16x32_bf16 v[174:177], v[42:45], v[90:93], v[174:177]
	v_mfma_f32_16x16x32_bf16 v[90:93], v[50:53], v[90:93], v[162:165]
	v_mfma_f32_16x16x32_bf16 v[134:137], v[42:45], v[170:173], v[134:137]
	v_mfma_f32_16x16x32_bf16 v[122:125], v[50:53], v[170:173], v[122:125]
	v_mfma_f32_16x16x32_bf16 v[114:117], v[42:45], v[206:209], v[114:117]
	v_mfma_f32_16x16x32_bf16 v[102:105], v[50:53], v[206:209], v[102:105]
	v_mfma_f32_16x16x32_bf16 v[174:177], v[46:49], v[110:113], v[174:177]
	v_mfma_f32_16x16x32_bf16 v[90:93], v[70:73], v[110:113], v[90:93]
	v_mfma_f32_16x16x32_bf16 v[110:113], v[42:45], v[130:133], v[154:157]
	v_mfma_f32_16x16x32_bf16 v[130:133], v[50:53], v[130:133], v[142:145]
	v_mfma_f32_16x16x32_bf16 v[134:137], v[46:49], v[182:185], v[134:137]
	v_mfma_f32_16x16x32_bf16 v[122:125], v[70:73], v[182:185], v[122:125]
	v_mfma_f32_16x16x32_bf16 v[114:117], v[46:49], v[226:229], v[114:117]
	v_mfma_f32_16x16x32_bf16 v[102:105], v[70:73], v[226:229], v[102:105]
	v_mfma_f32_16x16x32_bf16 v[110:113], v[46:49], v[150:153], v[110:113]
	v_mfma_f32_16x16x32_bf16 v[130:133], v[70:73], v[150:153], v[130:133]
	s_setprio 0
	s_barrier
	s_add_i32 s76, s76, s53
	v_lshl_add_u64 v[238:239], s[74:75], 0, v[196:197]
	s_mov_b32 m0, s76
	ds_read_b128 v[142:145], v216 offset:16384
	ds_read_b128 v[150:153], v216 offset:17408
	ds_read_b128 v[154:157], v216 offset:18432
	ds_read_b128 v[162:165], v216 offset:19456
	ds_read_b128 v[170:173], v216 offset:20480
	ds_read_b128 v[182:185], v216 offset:21504
	ds_read_b128 v[206:209], v216 offset:22528
	ds_read_b128 v[226:229], v216 offset:23552
	global_load_lds_dwordx4 v[238:239], off
	s_add_i32 m0, s76, 0x2000
	v_lshl_add_u64 v[240:241], s[74:75], 0, v[200:201]
	s_add_u32 s74, s74, s12
	s_addc_u32 s75, s75, s13
	s_add_i32 s49, s49, s53
	global_load_lds_dwordx4 v[240:241], off
	v_lshl_add_u64 v[242:243], s[74:75], 0, v[196:197]
	s_mov_b32 m0, s49
	v_lshl_add_u64 v[244:245], s[74:75], 0, v[200:201]
	global_load_lds_dwordx4 v[242:243], off
	s_add_i32 m0, s49, 0x2000
	v_lshl_add_u64 v[246:247], s[46:47], 0, v[194:195]
	global_load_lds_dwordx4 v[244:245], off
	s_mov_b32 m0, s94
	v_lshl_add_u64 v[248:249], s[46:47], 0, v[198:199]
	global_load_lds_dwordx4 v[246:247], off
	s_mov_b32 m0, s92
	s_nop 0
	global_load_lds_dwordx4 v[248:249], off
	s_waitcnt vmcnt(8)
	s_waitcnt lgkmcnt(0)
	s_barrier
; #define PG8_STAGE(bufoff, gbase, voff) do { _Pragma("unroll") for (int _i = 0; _i < 2; ++_i) \
;         __builtin_amdgcn_global_load_lds((const unsigned*)((const char*)(gbase) + (voff)[_i]), (PG8_LAS unsigned*)(lds + (bufoff) + ldsw + _i * 8192), 16, 0, 0); } while (0)
; #define PG8_LDA(dst, b, h) do { _Pragma("unroll") for (int m = 0; m < 4; ++m) _Pragma("unroll") for (int k = 0; k < 2; ++k) dst[m][k] = *(const PG8_LAS bf16x8*)(lds + PG8_SA(b, h) + aoff + m * 2048 + k * 1024); } while (0)
; #define PG8_LDB(dst, b, h) do { _Pragma("unroll") for (int n = 0; n < 2; ++n) _Pragma("unroll") for (int k = 0; k < 2; ++k) dst[n][k] = *(const PG8_LAS bf16x8*)(lds + PG8_SB(b, h) + boff + n * 2048 + k * 1024); } while (0)
; #define PG8_MMA(ai, bj, At, Bt) do { __builtin_amdgcn_s_setprio(1); _Pragma("unroll") for (int m = 0; m < 4; ++m) _Pragma("unroll") for (int n = 0; n < 2; ++n) _Pragma("unroll") for (int k = 0; k < 2; ++k) \
;         acc[ai][bj][m][n] = __builtin_amdgcn_mfma_f32_16x16x32_bf16(Bt[n][k], At[m][k], acc[ai][bj][m][n], 0, 0, 0); __builtin_amdgcn_s_setprio(0); } while (0)
; #define PG8_WAIT_V(n) asm volatile("s_waitcnt vmcnt(" #n ")" ::: "memory")
; #define PG8_WAIT_L(n) asm volatile("s_waitcnt lgkmcnt(" #n ")" ::: "memory")
; #define PG8_BAR __builtin_amdgcn_s_barrier()
; #define PG8_SCHED __builtin_amdgcn_sched_barrier(0)
; template <class Epi, class Sched, bool ALIGN_EPI = false, bool SP2 = false>
; __device__ __forceinline__ void gemm_phase(PG8_LAS unsigned char* lds, const Gemm g, const Sched& S, const Epi& E) {
;     ...
;             PG8_LDB(B0, 0, 0); PG8_LDB(B1, 0, 1); PG8_SCHED; PG8_LDA(At, 0, 0); PG8_STAGE(PG8_SA(1, 1), a1 + hstep, voffA);
;             PG8_WAIT_V(8); PG8_WAIT_L(0); PG8_BAR; PG8_MMA(0, 0, At, B0); PG8_MMA(0, 1, At, B1); PG8_BAR; PG8_SCHED;
;             PG8_LDA(At, 0, 1); PG8_STAGE(PG8_SB(0, 0), b2, voffB); PG8_STAGE(PG8_SB(0, 1), b2 + hstep, voffB); PG8_STAGE(PG8_SA(0, 0), a2, voffA);
;             PG8_WAIT_V(8); PG8_WAIT_L(0); PG8_BAR; PG8_MMA(1, 0, At, B0); PG8_MMA(1, 1, At, B1); PG8_BAR; PG8_SCHED;
;             PG8_LDB(B0, 1, 0); PG8_LDB(B1, 1, 1); PG8_SCHED; PG8_LDA(At, 1, 0); PG8_STAGE(PG8_SA(0, 1), a2 + hstep, voffA);
;             PG8_WAIT_V(8); PG8_WAIT_L(0); PG8_BAR; PG8_MMA(0, 0, At, B0); PG8_MMA(0, 1, At, B1); PG8_BAR; PG8_SCHED;
	s_setprio 1
	v_mfma_f32_16x16x32_bf16 v[98:101], v[18:21], v[142:145], v[98:101]
	v_mfma_f32_16x16x32_bf16 v[86:89], v[26:29], v[142:145], v[86:89]
	v_mfma_f32_16x16x32_bf16 v[78:81], v[18:21], v[154:157], v[78:81]
	v_mfma_f32_16x16x32_bf16 v[66:69], v[26:29], v[154:157], v[66:69]
	v_mfma_f32_16x16x32_bf16 v[58:61], v[18:21], v[170:173], v[58:61]
	v_mfma_f32_16x16x32_bf16 v[34:37], v[26:29], v[170:173], v[34:37]
	v_mfma_f32_16x16x32_bf16 v[14:17], v[18:21], v[206:209], v[14:17]
	v_mfma_f32_16x16x32_bf16 v[6:9], v[26:29], v[206:209], v[6:9]
	v_mfma_f32_16x16x32_bf16 v[98:101], v[22:25], v[150:153], v[98:101]
	v_mfma_f32_16x16x32_bf16 v[86:89], v[38:41], v[150:153], v[86:89]
	v_mfma_f32_16x16x32_bf16 v[78:81], v[22:25], v[162:165], v[78:81]
	v_mfma_f32_16x16x32_bf16 v[66:69], v[38:41], v[162:165], v[66:69]
	v_mfma_f32_16x16x32_bf16 v[58:61], v[22:25], v[182:185], v[58:61]
	v_mfma_f32_16x16x32_bf16 v[34:37], v[38:41], v[182:185], v[34:37]
	v_mfma_f32_16x16x32_bf16 v[14:17], v[22:25], v[226:229], v[14:17]
	v_mfma_f32_16x16x32_bf16 v[6:9], v[38:41], v[226:229], v[6:9]
	s_setprio 0
	s_setprio 1
	v_mfma_f32_16x16x32_bf16 v[54:57], v[42:45], v[170:173], v[54:57]
	v_mfma_f32_16x16x32_bf16 v[30:33], v[50:53], v[170:173], v[30:33]
	v_mfma_f32_16x16x32_bf16 v[10:13], v[42:45], v[206:209], v[10:13]
	v_mfma_f32_16x16x32_bf16 v[2:5], v[50:53], v[206:209], v[2:5]
	v_mfma_f32_16x16x32_bf16 v[18:21], v[42:45], v[142:145], v[94:97]
	v_mfma_f32_16x16x32_bf16 v[22:25], v[50:53], v[142:145], v[82:85]
	v_mfma_f32_16x16x32_bf16 v[26:29], v[42:45], v[154:157], v[74:77]
	v_mfma_f32_16x16x32_bf16 v[38:41], v[50:53], v[154:157], v[62:65]
	v_mfma_f32_16x16x32_bf16 v[54:57], v[46:49], v[182:185], v[54:57]
	v_mfma_f32_16x16x32_bf16 v[30:33], v[70:73], v[182:185], v[30:33]
	v_mfma_f32_16x16x32_bf16 v[10:13], v[46:49], v[226:229], v[10:13]
	v_mfma_f32_16x16x32_bf16 v[2:5], v[70:73], v[226:229], v[2:5]
	v_mfma_f32_16x16x32_bf16 v[18:21], v[46:49], v[150:153], v[18:21]
	v_mfma_f32_16x16x32_bf16 v[22:25], v[70:73], v[150:153], v[22:25]
	v_mfma_f32_16x16x32_bf16 v[26:29], v[46:49], v[162:165], v[26:29]
	v_mfma_f32_16x16x32_bf16 v[38:41], v[70:73], v[162:165], v[38:41]
	s_setprio 0
	s_barrier
	s_add_i32 s49, 0, 0x18000
	v_add_u32_e32 v0, s49, v212
	s_add_i32 s74, 0, 0x1c000
	ds_read_b128 v[42:45], v0
	ds_read_b128 v[46:49], v0 offset:1024
	ds_read_b128 v[50:53], v0 offset:2048
	ds_read_b128 v[62:65], v0 offset:3072
	v_add_u32_e32 v0, s74, v212
	ds_read_b128 v[70:73], v0
	ds_read_b128 v[150:153], v0 offset:1024
	ds_read_b128 v[170:173], v0 offset:2048
	ds_read_b128 v[182:185], v0 offset:3072
	s_add_u32 s46, s46, s12
	s_addc_u32 s47, s47, s13
	s_mov_b32 m0, s93
	v_lshl_add_u64 v[154:155], s[46:47], 0, v[194:195]
	ds_read_b128 v[74:77], v216 offset:32768
	ds_read_b128 v[82:85], v216 offset:33792
	ds_read_b128 v[94:97], v216 offset:34816
	ds_read_b128 v[142:145], v216 offset:35840
	ds_read_b128 v[206:209], v216 offset:36864
	ds_read_b128 v[226:229], v216 offset:37888
	ds_read_b128 v[230:233], v216 offset:38912
	ds_read_b128 v[234:237], v216 offset:39936
	global_load_lds_dwordx4 v[154:155], off
	v_lshl_add_u64 v[154:155], s[46:47], 0, v[198:199]
	s_mov_b32 m0, s33
	s_nop 0
	global_load_lds_dwordx4 v[154:155], off
	s_waitcnt vmcnt(8)
	s_waitcnt lgkmcnt(0)
	s_barrier
	s_setprio 1
	v_mfma_f32_16x16x32_bf16 v[154:157], v[42:45], v[74:77], v[178:181]
	v_mfma_f32_16x16x32_bf16 v[178:181], v[46:49], v[82:85], v[154:157]
	v_mfma_f32_16x16x32_bf16 v[154:157], v[50:53], v[74:77], v[166:169]
	v_mfma_f32_16x16x32_bf16 v[166:169], v[62:65], v[82:85], v[154:157]
	v_mfma_f32_16x16x32_bf16 v[154:157], v[42:45], v[94:97], v[158:161]
	v_mfma_f32_16x16x32_bf16 v[146:149], v[50:53], v[94:97], v[146:149]
	v_mfma_f32_16x16x32_bf16 v[138:141], v[42:45], v[206:209], v[138:141]
	v_mfma_f32_16x16x32_bf16 v[126:129], v[50:53], v[206:209], v[126:129]
	v_mfma_f32_16x16x32_bf16 v[118:121], v[42:45], v[230:233], v[118:121]
	v_mfma_f32_16x16x32_bf16 v[106:109], v[50:53], v[230:233], v[106:109]
	v_mfma_f32_16x16x32_bf16 v[158:161], v[46:49], v[142:145], v[154:157]
	v_mfma_f32_16x16x32_bf16 v[146:149], v[62:65], v[142:145], v[146:149]
	v_mfma_f32_16x16x32_bf16 v[138:141], v[46:49], v[226:229], v[138:141]
	v_mfma_f32_16x16x32_bf16 v[126:129], v[62:65], v[226:229], v[126:129]
	v_mfma_f32_16x16x32_bf16 v[118:121], v[46:49], v[234:237], v[118:121]
	v_mfma_f32_16x16x32_bf16 v[106:109], v[62:65], v[234:237], v[106:109]
	s_setprio 0
	s_setprio 1
	v_mfma_f32_16x16x32_bf16 v[154:157], v[70:73], v[74:77], v[174:177]
	v_mfma_f32_16x16x32_bf16 v[74:77], v[170:173], v[74:77], v[90:93]
	v_mfma_f32_16x16x32_bf16 v[162:165], v[182:185], v[82:85], v[74:77]
	v_mfma_f32_16x16x32_bf16 v[74:77], v[70:73], v[94:97], v[110:113]
	v_mfma_f32_16x16x32_bf16 v[174:177], v[150:153], v[82:85], v[154:157]
	v_mfma_f32_16x16x32_bf16 v[154:157], v[150:153], v[142:145], v[74:77]
	v_mfma_f32_16x16x32_bf16 v[74:77], v[170:173], v[94:97], v[130:133]
	v_mfma_f32_16x16x32_bf16 v[142:145], v[182:185], v[142:145], v[74:77]
	v_mfma_f32_16x16x32_bf16 v[74:77], v[70:73], v[206:209], v[134:137]
	v_mfma_f32_16x16x32_bf16 v[134:137], v[150:153], v[226:229], v[74:77]
	v_mfma_f32_16x16x32_bf16 v[74:77], v[170:173], v[206:209], v[122:125]
	v_mfma_f32_16x16x32_bf16 v[122:125], v[182:185], v[226:229], v[74:77]
	v_mfma_f32_16x16x32_bf16 v[74:77], v[70:73], v[230:233], v[114:117]
	v_mfma_f32_16x16x32_bf16 v[114:117], v[150:153], v[234:237], v[74:77]
	v_mfma_f32_16x16x32_bf16 v[74:77], v[170:173], v[230:233], v[102:105]
	v_mfma_f32_16x16x32_bf16 v[102:105], v[182:185], v[234:237], v[74:77]
	s_setprio 0
	s_barrier
; #define PG8_STAGE(bufoff, gbase, voff) do { _Pragma("unroll") for (int _i = 0; _i < 2; ++_i) \
;         __builtin_amdgcn_global_load_lds((const unsigned*)((const char*)(gbase) + (voff)[_i]), (PG8_LAS unsigned*)(lds + (bufoff) + ldsw + _i * 8192), 16, 0, 0); } while (0)
; #define PG8_LDA(dst, b, h) do { _Pragma("unroll") for (int m = 0; m < 4; ++m) _Pragma("unroll") for (int k = 0; k < 2; ++k) dst[m][k] = *(const PG8_LAS bf16x8*)(lds + PG8_SA(b, h) + aoff + m * 2048 + k * 1024); } while (0)
; #define PG8_LDB(dst, b, h) do { _Pragma("unroll") for (int n = 0; n < 2; ++n) _Pragma("unroll") for (int k = 0; k < 2; ++k) dst[n][k] = *(const PG8_LAS bf16x8*)(lds + PG8_SB(b, h) + boff + n * 2048 + k * 1024); } while (0)
; template <class Epi, class Sched, bool ALIGN_EPI = false, bool SP2 = false>
; __device__ __forceinline__ void gemm_phase(PG8_LAS unsigned char* lds, const Gemm g, const Sched& S, const Epi& E) {
;     ...
;         for (int t = 0; t < nt; t += 2) {
;             const bool last = (t == nt - 2);
;             const char* a1 = cA + (size_t)(t + 1) * kstep;
;             const char* a2 = last ? nA : cA + (size_t)(t + 2) * kstep; const char* b2 = last ? nB : cB + (size_t)(t + 2) * kstep;
;             const char* a3 = a2 + kstep; const char* b3 = b2 + kstep;
;             if (last && has_next) S.a_ready(nxt);
;             if constexpr (SP2) {
;             PG8_LDB(B0, 0, 0); PG8_LDB(B1, 0, 1); PG8_SCHED; PG8_LDA(At, 0, 0); PG8_STAGE(PG8_SA(1, 1), a1 + hstep, voffA);
;             PG8_WAIT_V(8); PG8_WAIT_L(0); PG8_BAR; PG8_MMA(0, 0, At, B0); PG8_MMA(0, 1, At, B1); PG8_BAR; PG8_SCHED;
;             PG8_LDA(At, 0, 1); PG8_STAGE(PG8_SB(0, 0), b2, voffB); PG8_STAGE(PG8_SB(0, 1), b2 + hstep, voffB); PG8_STAGE(PG8_SA(0, 0), a2, voffA);
;             PG8_WAIT_V(8); PG8_WAIT_L(0); PG8_BAR; PG8_MMA(1, 0, At, B0); PG8_MMA(1, 1, At, B1); PG8_BAR; PG8_SCHED;
;             PG8_LDB(B0, 1, 0); PG8_LDB(B1, 1, 1); PG8_SCHED; PG8_LDA(At, 1, 0); PG8_STAGE(PG8_SA(0, 1), a2 + hstep, voffA);
;             PG8_WAIT_V(8); PG8_WAIT_L(0); PG8_BAR; PG8_MMA(0, 0, At, B0); PG8_MMA(0, 1, At, B1); PG8_BAR; PG8_SCHED;
;             PG8_LDA(At, 1, 1); PG8_STAGE(PG8_SB(1, 0), b3, voffB); PG8_STAGE(PG8_SB(1, 1), b3 + hstep, voffB); PG8_STAGE(PG8_SA(1, 0), a3, voffA);
;             PG8_WAIT_V(8); PG8_WAIT_L(0); PG8_BAR; PG8_MMA(1, 0, At, B0); PG8_MMA(1, 1, At, B1); PG8_BAR; PG8_SCHED;
	s_add_i32 s46, s49, s53
	v_lshl_add_u64 v[94:95], v[238:239], 0, s[38:39]
	s_mov_b32 m0, s46
	s_nop 1
	ds_read_b128 v[74:77], v216 offset:49152
	ds_read_b128 v[82:85], v216 offset:50176
	ds_read_b128 v[90:93], v216 offset:51200
	ds_read_b128 v[110:113], v216 offset:52224
	ds_read_b128 v[130:133], v216 offset:53248
	ds_read_b128 v[206:209], v216 offset:54272
	ds_read_b128 v[226:229], v216 offset:55296
	ds_read_b128 v[230:233], v216 offset:56320
	global_load_lds_dwordx4 v[94:95], off
	v_lshl_add_u64 v[94:95], v[240:241], 0, s[38:39]
	s_add_i32 m0, s46, 0x2000
	s_add_i32 s46, s74, s53
	global_load_lds_dwordx4 v[94:95], off
	v_lshl_add_u64 v[94:95], v[242:243], 0, s[38:39]
	s_mov_b32 m0, s46
	s_nop 0
	global_load_lds_dwordx4 v[94:95], off
	v_lshl_add_u64 v[94:95], v[244:245], 0, s[38:39]
	s_add_i32 m0, s46, 0x2000
	s_nop 0
	global_load_lds_dwordx4 v[94:95], off
	v_lshl_add_u64 v[94:95], v[246:247], 0, s[38:39]
	s_mov_b32 m0, s40
	s_nop 0
	global_load_lds_dwordx4 v[94:95], off
	v_lshl_add_u64 v[94:95], v[248:249], 0, s[38:39]
	s_mov_b32 m0, s41
	s_nop 0
	global_load_lds_dwordx4 v[94:95], off
	s_waitcnt vmcnt(8)
	s_waitcnt lgkmcnt(0)
	s_barrier
	s_setprio 1
	v_mfma_f32_16x16x32_bf16 v[94:97], v[42:45], v[74:77], v[98:101]
	v_mfma_f32_16x16x32_bf16 v[86:89], v[50:53], v[74:77], v[86:89]
	v_mfma_f32_16x16x32_bf16 v[78:81], v[42:45], v[90:93], v[78:81]
	v_mfma_f32_16x16x32_bf16 v[66:69], v[50:53], v[90:93], v[66:69]
	v_mfma_f32_16x16x32_bf16 v[58:61], v[42:45], v[130:133], v[58:61]
	v_mfma_f32_16x16x32_bf16 v[34:37], v[50:53], v[130:133], v[34:37]
	v_mfma_f32_16x16x32_bf16 v[14:17], v[42:45], v[226:229], v[14:17]
	v_mfma_f32_16x16x32_bf16 v[6:9], v[50:53], v[226:229], v[6:9]
	v_mfma_f32_16x16x32_bf16 v[98:101], v[46:49], v[82:85], v[94:97]
	v_mfma_f32_16x16x32_bf16 v[86:89], v[62:65], v[82:85], v[86:89]
	v_mfma_f32_16x16x32_bf16 v[78:81], v[46:49], v[110:113], v[78:81]
	v_mfma_f32_16x16x32_bf16 v[66:69], v[62:65], v[110:113], v[66:69]
	v_mfma_f32_16x16x32_bf16 v[58:61], v[46:49], v[206:209], v[58:61]
	v_mfma_f32_16x16x32_bf16 v[34:37], v[62:65], v[206:209], v[34:37]
	v_mfma_f32_16x16x32_bf16 v[14:17], v[46:49], v[230:233], v[14:17]
	v_mfma_f32_16x16x32_bf16 v[6:9], v[62:65], v[230:233], v[6:9]
	s_setprio 0
	s_setprio 1
	v_mfma_f32_16x16x32_bf16 v[18:21], v[70:73], v[74:77], v[18:21]
	v_mfma_f32_16x16x32_bf16 v[94:97], v[150:153], v[82:85], v[18:21]
	v_mfma_f32_16x16x32_bf16 v[18:21], v[170:173], v[74:77], v[22:25]
	v_mfma_f32_16x16x32_bf16 v[82:85], v[182:185], v[82:85], v[18:21]
	v_mfma_f32_16x16x32_bf16 v[18:21], v[70:73], v[90:93], v[26:29]
	v_mfma_f32_16x16x32_bf16 v[74:77], v[150:153], v[110:113], v[18:21]
	v_mfma_f32_16x16x32_bf16 v[18:21], v[170:173], v[90:93], v[38:41]
	v_mfma_f32_16x16x32_bf16 v[62:65], v[182:185], v[110:113], v[18:21]
	v_mfma_f32_16x16x32_bf16 v[18:21], v[70:73], v[130:133], v[54:57]
	v_mfma_f32_16x16x32_bf16 v[54:57], v[150:153], v[206:209], v[18:21]
	v_mfma_f32_16x16x32_bf16 v[18:21], v[170:173], v[130:133], v[30:33]
	v_mfma_f32_16x16x32_bf16 v[10:13], v[70:73], v[226:229], v[10:13]
	v_mfma_f32_16x16x32_bf16 v[2:5], v[170:173], v[226:229], v[2:5]
	v_mfma_f32_16x16x32_bf16 v[30:33], v[182:185], v[206:209], v[18:21]
	v_mfma_f32_16x16x32_bf16 v[10:13], v[150:153], v[230:233], v[10:13]
	v_mfma_f32_16x16x32_bf16 v[2:5], v[182:185], v[230:233], v[2:5]
	s_setprio 0
	s_barrier
	s_add_u32 s56, s56, 0x100
	s_addc_u32 s61, s61, 0
	s_add_u32 s4, s4, 0x100
	s_addc_u32 s5, s5, 0
	s_cmp_ge_i32 s48, s34
	s_mov_b32 s46, s48
	s_cbranch_scc0 .LBB0_1040
	s_mov_b64 s[76:77], 0x28000

; __device__ __forceinline__ unsigned cvt_pk_bf16(float lo, float hi) { unsigned r; asm volatile("v_cvt_pk_bf16_f32 %0, %1, %2" : "=v"(r) : "v"(lo), "v"(hi)); return r; }
; __device__ __forceinline__ float fast_sigmoid(float x) { return __builtin_amdgcn_rcpf(1.0f + __expf(-x)); }
;     __device__ __forceinline__ void operator()(const f32x4 (&acc)[2][2][4][2], const Unit& u, int wr, int wc, int fr, int fq, PG8_LAS unsigned char* ldsb) const {
;         const int row0 = u.pm * BM + wr * 64 + fr; const int ch0 = u.pn * HALF + wc * 32 + 8 * fq;
;         float sp[8], br[8], bi[8];
; #pragma unroll
;         for (int i = 0; i < 8; ++i) { sp[i] = lam[ch0 + i]; br[i] = gb[ch0 + i]; bi[i] = gb[512 + ch0 + i]; }
;         u32x4 xwv[2][4];
; #pragma unroll
;         for (int ai = 0; ai < 2; ++ai)
; #pragma unroll
;             for (int m = 0; m < 4; ++m) xwv[ai][m] = *(const u32x4*)(XC + ((unsigned)(row0 + ai * HALF + m * 16) * 512u + (unsigned)ch0));
; #pragma unroll
;         for (int ai = 0; ai < 2; ++ai)
; #pragma unroll
;             for (int m = 0; m < 4; ++m) {
;                 const size_t ro = (size_t)(row0 + ai * HALF + m * 16) * 512 + ch0;
;                 const u32x4 xw = xwv[ai][m];
;                 unsigned ow[8];
; #pragma unroll
;                 for (int n = 0; n < 2; ++n)
; #pragma unroll
;                     for (int i = 0; i < 4; ++i) { const int e = n * 4 + i;
;                         const unsigned wd = xw[e >> 1]; const float xc = __uint_as_float((e & 1) ? (wd & 0xffff0000u) : (wd << 16));
;                         const float r = fast_sigmoid(acc[ai][0][m][n][i] + br[e]), ig = fast_sigmoid(acc[ai][1][m][n][i] + bi[e]);
;                         const float la = sp[e] * r;
;                         const float bb = __builtin_sqrtf(fmaxf(1.0f - __expf(2.0f * la), 0.f)) * (ig * xc);
;                         ow[e] = cvt_pk_bf16(la * 1.4426950408889634f, bb); }
.LBB0_1044:
	v_lshl_or_b32 v38, s45, 7, v214
	v_ashrrev_i32_e32 v39, 31, v38
	v_lshlrev_b64 v[206:207], 2, v[38:39]
	v_lshl_add_u64 v[18:19], s[22:23], 0, v[206:207]
	v_lshl_add_u64 v[20:21], s[20:21], 0, v[206:207]
	global_load_dwordx4 v[42:45], v[18:19], off
	global_load_dwordx4 v[26:29], v[20:21], off offset:16
	global_load_dwordx4 v[50:53], v[20:21], off
	global_load_dwordx4 v[22:25], v[20:21], off offset:2064
	global_load_dwordx4 v[46:49], v[20:21], off offset:2048
	s_nop 0
	global_load_dwordx4 v[18:21], v[18:19], off offset:16
	v_lshl_add_u32 v208, s1, 8, v210
	v_lshl_add_u32 v0, v208, 9, v38
	v_lshl_add_u64 v[38:39], v[0:1], 1, s[6:7]
	global_load_dwordx4 v[182:185], v[38:39], off
	v_add_u32_e32 v38, 0x2000, v0
	v_mov_b32_e32 v39, v1
	v_lshl_add_u64 v[38:39], v[38:39], 1, s[6:7]
	global_load_dwordx4 v[170:173], v[38:39], off
	v_add_u32_e32 v38, 0x4000, v0
	v_mov_b32_e32 v39, v1
	v_lshl_add_u64 v[38:39], v[38:39], 1, s[6:7]
	global_load_dwordx4 v[150:153], v[38:39], off
	v_add_u32_e32 v38, 0x6000, v0
	v_mov_b32_e32 v39, v1
	v_lshl_add_u64 v[38:39], v[38:39], 1, s[6:7]
	global_load_dwordx4 v[130:133], v[38:39], off
	v_add_u32_e32 v38, 0x10000, v0
	v_mov_b32_e32 v39, v1
	v_lshl_add_u64 v[38:39], v[38:39], 1, s[6:7]
	global_load_dwordx4 v[110:113], v[38:39], off
	v_add_u32_e32 v38, 0x12000, v0
	v_mov_b32_e32 v39, v1
	v_lshl_add_u64 v[38:39], v[38:39], 1, s[6:7]
	global_load_dwordx4 v[90:93], v[38:39], off
	v_add_u32_e32 v38, 0x14000, v0
	v_mov_b32_e32 v39, v1
	v_lshl_add_u64 v[38:39], v[38:39], 1, s[6:7]
	v_add_u32_e32 v0, 0x16000, v0
	global_load_dwordx4 v[70:73], v[38:39], off
	v_lshl_add_u64 v[38:39], v[0:1], 1, s[6:7]
	global_load_dwordx4 v[38:41], v[38:39], off
	v_ashrrev_i32_e32 v209, 31, v208
	s_mov_b32 s1, 0x48000
	s_waitcnt vmcnt(0)
	v_add_f32_e32 v166, v166, v26
	v_add_f32_e32 v178, v178, v50
	v_mul_f32_e32 v178, 0xbfb8aa3b, v178
	v_exp_f32_e32 v178, v178
	v_add_f32_e32 v174, v174, v46
	v_mul_f32_e32 v174, 0xbfb8aa3b, v174
	v_exp_f32_e32 v174, v174
	v_add_f32_e32 v178, 1.0, v178
	v_rcp_f32_e32 v178, v178
	s_waitcnt lgkmcnt(0)
	v_lshlrev_b32_e32 v0, 16, v182
	v_add_f32_e32 v174, 1.0, v174
	v_rcp_f32_e32 v174, v174
	v_mul_f32_e32 v178, v42, v178
	v_add_f32_e32 v213, v178, v178
	v_mul_f32_e32 v213, 0x3fb8aa3b, v213
	v_exp_f32_e32 v213, v213
	v_mul_f32_e32 v0, v174, v0
	v_mul_f32_e32 v174, 0x3fb8aa3b, v178
	v_add_f32_e32 v178, v179, v51
	v_mul_f32_e32 v178, 0xbfb8aa3b, v178
	v_sub_f32_e32 v213, 1.0, v213
	v_exp_f32_e32 v178, v178
	v_max_f32_e32 v213, 0, v213
	v_cmp_gt_f32_e32 vcc, s59, v213
	v_mul_f32_e32 v215, 0x4f800000, v213
	v_add_f32_e32 v178, 1.0, v178
	v_cndmask_b32_e32 v213, v213, v215, vcc
	v_sqrt_f32_e32 v215, v213
	v_rcp_f32_e32 v178, v178
	v_add_f32_e32 v175, v175, v47
	v_mul_f32_e32 v175, 0xbfb8aa3b, v175
	v_add_u32_e32 v217, -1, v215
	v_fma_f32 v226, -v217, v215, v213
	v_mul_f32_e32 v178, v43, v178
	v_cmp_ge_f32_e64 s[4:5], 0, v226
	v_add_u32_e32 v226, 1, v215
	v_add_f32_e32 v179, v178, v178
	v_cndmask_b32_e64 v217, v215, v217, s[4:5]
	v_fma_f32 v215, -v226, v215, v213
	v_mul_f32_e32 v179, 0x3fb8aa3b, v179
	v_cmp_lt_f32_e64 s[4:5], 0, v215
	v_exp_f32_e32 v175, v175
	v_exp_f32_e32 v179, v179
	v_cndmask_b32_e64 v215, v217, v226, s[4:5]
	v_mul_f32_e32 v217, 0x37800000, v215
	v_cndmask_b32_e32 v215, v215, v217, vcc
	v_cmp_class_f32_e32 vcc, v213, v221
	v_add_f32_e32 v175, 1.0, v175
	v_sub_f32_e32 v179, 1.0, v179
	v_cndmask_b32_e32 v213, v215, v213, vcc
	v_mul_f32_e32 v0, v213, v0
	v_rcp_f32_e32 v175, v175
	v_max_f32_e32 v179, 0, v179
	v_cvt_pk_bf16_f32 v174, v174, v0
	v_and_b32_e32 v0, 0xffff0000, v182
	v_cmp_gt_f32_e32 vcc, s59, v179
	v_mul_f32_e32 v182, 0x4f800000, v179
	v_mul_f32_e32 v0, v175, v0
	v_cndmask_b32_e32 v179, v179, v182, vcc
	v_sqrt_f32_e32 v182, v179
	v_mul_f32_e32 v175, 0x3fb8aa3b, v178
	v_add_f32_e32 v178, v180, v52
	v_mul_f32_e32 v178, 0xbfb8aa3b, v178
	v_exp_f32_e32 v178, v178
	v_add_u32_e32 v213, -1, v182
	v_fma_f32 v215, -v213, v182, v179
	v_cmp_ge_f32_e64 s[4:5], 0, v215
	v_add_u32_e32 v215, 1, v182
	v_add_f32_e32 v178, 1.0, v178
	v_cndmask_b32_e64 v213, v182, v213, s[4:5]
	v_fma_f32 v182, -v215, v182, v179
	v_cmp_lt_f32_e64 s[4:5], 0, v182
	v_rcp_f32_e32 v178, v178
	v_add_f32_e32 v176, v176, v48
	v_cndmask_b32_e64 v182, v213, v215, s[4:5]
	v_mul_f32_e32 v213, 0x37800000, v182
	v_cndmask_b32_e32 v182, v182, v213, vcc
	v_cmp_class_f32_e32 vcc, v179, v221
	v_mul_f32_e32 v178, v44, v178
	v_mul_f32_e32 v176, 0xbfb8aa3b, v176
	v_cndmask_b32_e32 v179, v182, v179, vcc
	v_mul_f32_e32 v0, v179, v0
	v_add_f32_e32 v179, v178, v178
	v_mul_f32_e32 v179, 0x3fb8aa3b, v179
	v_exp_f32_e32 v176, v176
	v_exp_f32_e32 v179, v179
	v_cvt_pk_bf16_f32 v175, v175, v0
	v_lshlrev_b32_e32 v0, 16, v183
	v_add_f32_e32 v176, 1.0, v176
	v_sub_f32_e32 v179, 1.0, v179
	v_rcp_f32_e32 v176, v176
	v_max_f32_e32 v179, 0, v179
	v_cmp_gt_f32_e32 vcc, s59, v179
	v_mul_f32_e32 v180, 0x4f800000, v179
	v_mul_f32_e32 v0, v176, v0
	v_cndmask_b32_e32 v179, v179, v180, vcc
	v_sqrt_f32_e32 v180, v179
	v_mul_f32_e32 v176, 0x3fb8aa3b, v178
	v_add_f32_e32 v178, v181, v53
	v_mul_f32_e32 v178, 0xbfb8aa3b, v178
	v_exp_f32_e32 v178, v178
	v_add_u32_e32 v182, -1, v180
	v_fma_f32 v213, -v182, v180, v179
	v_cmp_ge_f32_e64 s[4:5], 0, v213
	v_add_u32_e32 v213, 1, v180
	v_add_f32_e32 v178, 1.0, v178
	v_cndmask_b32_e64 v182, v180, v182, s[4:5]
	v_fma_f32 v180, -v213, v180, v179
	v_cmp_lt_f32_e64 s[4:5], 0, v180
	v_rcp_f32_e32 v178, v178
	v_add_f32_e32 v177, v177, v49
	v_cndmask_b32_e64 v180, v182, v213, s[4:5]
	v_mul_f32_e32 v182, 0x37800000, v180
	v_cndmask_b32_e32 v180, v180, v182, vcc
	v_cmp_class_f32_e32 vcc, v179, v221
	v_mul_f32_e32 v178, v45, v178
; __device__ __forceinline__ unsigned cvt_pk_bf16(float lo, float hi) { unsigned r; asm volatile("v_cvt_pk_bf16_f32 %0, %1, %2" : "=v"(r) : "v"(lo), "v"(hi)); return r; }
; __device__ __forceinline__ float fast_sigmoid(float x) { return __builtin_amdgcn_rcpf(1.0f + __expf(-x)); }
;     __device__ __forceinline__ void operator()(const f32x4 (&acc)[2][2][4][2], const Unit& u, int wr, int wc, int fr, int fq, PG8_LAS unsigned char* ldsb) const {
;     ...
;                     for (int i = 0; i < 4; ++i) { const int e = n * 4 + i;
;                         const unsigned wd = xw[e >> 1]; const float xc = __uint_as_float((e & 1) ? (wd & 0xffff0000u) : (wd << 16));
;                         const float r = fast_sigmoid(acc[ai][0][m][n][i] + br[e]), ig = fast_sigmoid(acc[ai][1][m][n][i] + bi[e]);
;                         const float la = sp[e] * r;
;                         const float bb = __builtin_sqrtf(fmaxf(1.0f - __expf(2.0f * la), 0.f)) * (ig * xc);
;                         ow[e] = cvt_pk_bf16(la * 1.4426950408889634f, bb); }
	v_mul_f32_e32 v166, 0xbfb8aa3b, v166
	v_cndmask_b32_e32 v179, v180, v179, vcc
	v_mul_f32_e32 v0, v179, v0
	v_add_f32_e32 v179, v178, v178
	v_mul_f32_e32 v179, 0x3fb8aa3b, v179
	v_exp_f32_e32 v179, v179
	v_mul_f32_e32 v177, 0xbfb8aa3b, v177
	v_exp_f32_e32 v166, v166
	v_exp_f32_e32 v177, v177
	v_sub_f32_e32 v179, 1.0, v179
	v_max_f32_e32 v179, 0, v179
	v_cmp_gt_f32_e32 vcc, s59, v179
	v_mul_f32_e32 v180, 0x4f800000, v179
	v_add_f32_e32 v162, v162, v22
	v_cndmask_b32_e32 v179, v179, v180, vcc
	v_sqrt_f32_e32 v180, v179
	v_mul_f32_e32 v162, 0xbfb8aa3b, v162
	v_add_f32_e32 v166, 1.0, v166
	v_exp_f32_e32 v162, v162
	v_add_u32_e32 v181, -1, v180
	v_fma_f32 v182, -v181, v180, v179
	v_cmp_ge_f32_e64 s[4:5], 0, v182
	v_add_u32_e32 v182, 1, v180
	v_add_f32_e32 v177, 1.0, v177
	v_cndmask_b32_e64 v181, v180, v181, s[4:5]
	v_fma_f32 v180, -v182, v180, v179
	v_rcp_f32_e32 v166, v166
	v_rcp_f32_e32 v177, v177
	v_cmp_lt_f32_e64 s[4:5], 0, v180
	v_add_f32_e32 v162, 1.0, v162
	v_cvt_pk_bf16_f32 v176, v176, v0
	v_and_b32_e32 v0, 0xffff0000, v183
	v_cndmask_b32_e64 v180, v181, v182, s[4:5]
	v_mul_f32_e32 v181, 0x37800000, v180
	v_cndmask_b32_e32 v180, v180, v181, vcc
	v_cmp_class_f32_e32 vcc, v179, v221
	v_rcp_f32_e32 v162, v162
	v_mul_f32_e32 v166, v18, v166
	v_cndmask_b32_e32 v179, v180, v179, vcc
	v_mul_f32_e32 v0, v177, v0
	v_mul_f32_e32 v177, 0x3fb8aa3b, v178
	v_add_f32_e32 v178, v166, v166
	v_mul_f32_e32 v0, v179, v0
	v_mul_f32_e32 v178, 0x3fb8aa3b, v178
	v_cvt_pk_bf16_f32 v177, v177, v0
	v_lshlrev_b32_e32 v0, 16, v184
	v_exp_f32_e32 v178, v178
	v_mul_f32_e32 v0, v162, v0
	v_mul_f32_e32 v162, 0x3fb8aa3b, v166
	v_add_f32_e32 v166, v167, v27
	v_mul_f32_e32 v166, 0xbfb8aa3b, v166
	v_exp_f32_e32 v166, v166
	v_sub_f32_e32 v178, 1.0, v178
	v_max_f32_e32 v178, 0, v178
	v_cmp_gt_f32_e32 vcc, s59, v178
	v_mul_f32_e32 v179, 0x4f800000, v178
	v_add_f32_e32 v166, 1.0, v166
	v_cndmask_b32_e32 v178, v178, v179, vcc
	v_sqrt_f32_e32 v179, v178
	v_rcp_f32_e32 v166, v166
	v_add_f32_e32 v163, v163, v23
	v_mul_f32_e32 v163, 0xbfb8aa3b, v163
	v_add_u32_e32 v180, -1, v179
	v_mul_f32_e32 v166, v19, v166
	v_fma_f32 v181, -v180, v179, v178
	v_add_f32_e32 v167, v166, v166
	v_cmp_ge_f32_e64 s[4:5], 0, v181
	v_add_u32_e32 v181, 1, v179
	v_mul_f32_e32 v167, 0x3fb8aa3b, v167
	v_cndmask_b32_e64 v180, v179, v180, s[4:5]
	v_fma_f32 v179, -v181, v179, v178
	v_exp_f32_e32 v163, v163
	v_exp_f32_e32 v167, v167
	v_cmp_lt_f32_e64 s[4:5], 0, v179
	v_add_f32_e32 v164, v164, v24
	v_add_f32_e32 v163, 1.0, v163
	v_cndmask_b32_e64 v179, v180, v181, s[4:5]
	v_mul_f32_e32 v180, 0x37800000, v179
	v_cndmask_b32_e32 v179, v179, v180, vcc
	v_cmp_class_f32_e32 vcc, v178, v221
	v_sub_f32_e32 v167, 1.0, v167
	v_rcp_f32_e32 v163, v163
	v_cndmask_b32_e32 v178, v179, v178, vcc
	v_max_f32_e32 v167, 0, v167
	v_mul_f32_e32 v0, v178, v0
	v_cmp_gt_f32_e32 vcc, s59, v167
	v_mul_f32_e32 v178, 0x4f800000, v167
	v_cvt_pk_bf16_f32 v162, v162, v0
	v_and_b32_e32 v0, 0xffff0000, v184
	v_cndmask_b32_e32 v167, v167, v178, vcc
	v_sqrt_f32_e32 v178, v167
	v_mul_f32_e32 v0, v163, v0
	v_mul_f32_e32 v163, 0x3fb8aa3b, v166
	v_add_f32_e32 v166, v168, v28
	v_mul_f32_e32 v166, 0xbfb8aa3b, v166
	v_exp_f32_e32 v166, v166
	v_add_u32_e32 v179, -1, v178
	v_fma_f32 v180, -v179, v178, v167
	v_cmp_ge_f32_e64 s[4:5], 0, v180
	v_add_u32_e32 v180, 1, v178
	v_add_f32_e32 v166, 1.0, v166
	v_cndmask_b32_e64 v179, v178, v179, s[4:5]
	v_fma_f32 v178, -v180, v178, v167
	v_cmp_lt_f32_e64 s[4:5], 0, v178
	v_rcp_f32_e32 v166, v166
	v_mul_f32_e32 v164, 0xbfb8aa3b, v164
	v_cndmask_b32_e64 v178, v179, v180, s[4:5]
	v_mul_f32_e32 v179, 0x37800000, v178
	v_cndmask_b32_e32 v178, v178, v179, vcc
	v_cmp_class_f32_e32 vcc, v167, v221
	v_mul_f32_e32 v166, v20, v166
	v_exp_f32_e32 v164, v164
	v_cndmask_b32_e32 v167, v178, v167, vcc
	v_mul_f32_e32 v0, v0, v167
	v_add_f32_e32 v167, v166, v166
	v_mul_f32_e32 v167, 0x3fb8aa3b, v167
	v_exp_f32_e32 v167, v167
	v_add_f32_e32 v164, 1.0, v164
	v_rcp_f32_e32 v164, v164
	v_cvt_pk_bf16_f32 v163, v163, v0
	v_sub_f32_e32 v167, 1.0, v167
	v_max_f32_e32 v167, 0, v167
	v_cmp_gt_f32_e32 vcc, s59, v167
	v_mul_f32_e32 v168, 0x4f800000, v167
	v_lshlrev_b32_e32 v0, 16, v185
	v_cndmask_b32_e32 v167, v167, v168, vcc
	v_sqrt_f32_e32 v168, v167
	v_mul_f32_e32 v0, v164, v0
	v_mul_f32_e32 v164, 0x3fb8aa3b, v166
	v_add_f32_e32 v166, v169, v29
	v_mul_f32_e32 v166, 0xbfb8aa3b, v166
	v_exp_f32_e32 v166, v166
	v_add_u32_e32 v178, -1, v168
	v_fma_f32 v179, -v178, v168, v167
	v_cmp_ge_f32_e64 s[4:5], 0, v179
	v_add_u32_e32 v179, 1, v168
	v_add_f32_e32 v166, 1.0, v166
	v_cndmask_b32_e64 v178, v168, v178, s[4:5]
	v_fma_f32 v168, -v179, v168, v167
	v_cmp_lt_f32_e64 s[4:5], 0, v168
	v_rcp_f32_e32 v166, v166
	v_add_f32_e32 v165, v165, v25
	v_cndmask_b32_e64 v168, v178, v179, s[4:5]
	v_mul_f32_e32 v178, 0x37800000, v168
	v_cndmask_b32_e32 v168, v168, v178, vcc
	v_cmp_class_f32_e32 vcc, v167, v221
	v_mul_f32_e32 v166, v21, v166
	v_mul_f32_e32 v165, 0xbfb8aa3b, v165
	v_cndmask_b32_e32 v167, v168, v167, vcc
	v_mul_f32_e32 v0, v0, v167
	v_add_f32_e32 v167, v166, v166
	v_mul_f32_e32 v167, 0x3fb8aa3b, v167
	v_exp_f32_e32 v167, v167
	v_exp_f32_e32 v165, v165
	v_add_f32_e32 v158, v158, v50
	v_mul_f32_e32 v158, 0xbfb8aa3b, v158
	v_sub_f32_e32 v167, 1.0, v167
	v_max_f32_e32 v167, 0, v167
	v_cmp_gt_f32_e32 vcc, s59, v167
	v_mul_f32_e32 v168, 0x4f800000, v167
	v_exp_f32_e32 v158, v158
	v_cndmask_b32_e32 v167, v167, v168, vcc
	v_sqrt_f32_e32 v168, v167
	v_add_f32_e32 v165, 1.0, v165
	v_rcp_f32_e32 v165, v165
	v_add_f32_e32 v154, v154, v46
	v_add_u32_e32 v169, -1, v168
	v_fma_f32 v178, -v169, v168, v167
	v_cmp_ge_f32_e64 s[4:5], 0, v178
	v_add_u32_e32 v178, 1, v168
; __device__ __forceinline__ unsigned cvt_pk_bf16(float lo, float hi) { unsigned r; asm volatile("v_cvt_pk_bf16_f32 %0, %1, %2" : "=v"(r) : "v"(lo), "v"(hi)); return r; }
; __device__ __forceinline__ float fast_sigmoid(float x) { return __builtin_amdgcn_rcpf(1.0f + __expf(-x)); }
;     __device__ __forceinline__ void operator()(const f32x4 (&acc)[2][2][4][2], const Unit& u, int wr, int wc, int fr, int fq, PG8_LAS unsigned char* ldsb) const {
;     ...
;             for (int m = 0; m < 4; ++m) {
;                 const size_t ro = (size_t)(row0 + ai * HALF + m * 16) * 512 + ch0;
;                 const u32x4 xw = xwv[ai][m];
;                 unsigned ow[8];
; #pragma unroll
;                 for (int n = 0; n < 2; ++n)
; #pragma unroll
;                     for (int i = 0; i < 4; ++i) { const int e = n * 4 + i;
;                         const unsigned wd = xw[e >> 1]; const float xc = __uint_as_float((e & 1) ? (wd & 0xffff0000u) : (wd << 16));
;                         const float r = fast_sigmoid(acc[ai][0][m][n][i] + br[e]), ig = fast_sigmoid(acc[ai][1][m][n][i] + bi[e]);
;                         const float la = sp[e] * r;
;                         const float bb = __builtin_sqrtf(fmaxf(1.0f - __expf(2.0f * la), 0.f)) * (ig * xc);
;                         ow[e] = cvt_pk_bf16(la * 1.4426950408889634f, bb); }
;                 u32x4 w0, w1; w0.x = ow[0]; w0.y = ow[1]; w0.z = ow[2]; w0.w = ow[3]; w1.x = ow[4]; w1.y = ow[5]; w1.z = ow[6]; w1.w = ow[7];
;                 *(u32x4*)(AB + ro) = w0; *(u32x4*)(AB + ro + 4) = w1;
	v_mul_f32_e32 v154, 0xbfb8aa3b, v154
	v_cndmask_b32_e64 v169, v168, v169, s[4:5]
	v_fma_f32 v168, -v178, v168, v167
	v_cmp_lt_f32_e64 s[4:5], 0, v168
	v_add_f32_e32 v158, 1.0, v158
	v_exp_f32_e32 v154, v154
	v_cndmask_b32_e64 v168, v169, v178, s[4:5]
	v_mul_f32_e32 v169, 0x37800000, v168
	v_cvt_pk_bf16_f32 v164, v164, v0
	v_and_b32_e32 v0, 0xffff0000, v185
	v_cndmask_b32_e32 v168, v168, v169, vcc
	v_cmp_class_f32_e32 vcc, v167, v221
	v_rcp_f32_e32 v158, v158
	v_mul_f32_e32 v0, v165, v0
	v_cndmask_b32_e32 v167, v168, v167, vcc
	v_mul_f32_e32 v0, v0, v167
	v_mul_f32_e32 v165, 0x3fb8aa3b, v166
	v_lshlrev_b64 v[166:167], 11, v[208:209]
	v_lshl_add_u64 v[166:167], s[18:19], 0, v[166:167]
	v_add_f32_e32 v154, 1.0, v154
	v_lshl_add_u64 v[166:167], v[166:167], 0, v[206:207]
	v_rcp_f32_e32 v154, v154
	v_mul_f32_e32 v158, v42, v158
	v_cvt_pk_bf16_f32 v165, v165, v0
	global_store_dwordx4 v[166:167], v[174:177], off
	global_store_dwordx4 v[166:167], v[162:165], off offset:16
	v_lshlrev_b32_e32 v0, 16, v170
	v_mul_f32_e32 v0, v154, v0
	v_add_f32_e32 v164, v158, v158
	v_mul_f32_e32 v164, 0x3fb8aa3b, v164
	v_exp_f32_e32 v164, v164
	v_mul_f32_e32 v154, 0x3fb8aa3b, v158
	v_add_f32_e32 v158, v159, v51
	v_mul_f32_e32 v158, 0xbfb8aa3b, v158
	v_exp_f32_e32 v158, v158
	v_sub_f32_e32 v164, 1.0, v164
	v_max_f32_e32 v164, 0, v164
	v_cmp_gt_f32_e32 vcc, s59, v164
	v_mul_f32_e32 v165, 0x4f800000, v164
	v_add_f32_e32 v158, 1.0, v158
	v_cndmask_b32_e32 v164, v164, v165, vcc
	v_sqrt_f32_e32 v165, v164
	v_rcp_f32_e32 v158, v158
	v_add_f32_e32 v155, v155, v47
	v_mul_f32_e32 v155, 0xbfb8aa3b, v155
	v_add_u32_e32 v168, -1, v165
	v_mul_f32_e32 v158, v43, v158
	v_fma_f32 v169, -v168, v165, v164
	v_add_f32_e32 v159, v158, v158
	v_cmp_ge_f32_e64 s[4:5], 0, v169
	v_add_u32_e32 v169, 1, v165
	v_mul_f32_e32 v159, 0x3fb8aa3b, v159
	v_cndmask_b32_e64 v168, v165, v168, s[4:5]
	v_fma_f32 v165, -v169, v165, v164
	v_exp_f32_e32 v155, v155
	v_exp_f32_e32 v159, v159
	v_cmp_lt_f32_e64 s[4:5], 0, v165
	v_add_f32_e32 v156, v156, v48
	v_add_f32_e32 v155, 1.0, v155
	v_cndmask_b32_e64 v165, v168, v169, s[4:5]
	v_mul_f32_e32 v168, 0x37800000, v165
	v_cndmask_b32_e32 v165, v165, v168, vcc
	v_cmp_class_f32_e32 vcc, v164, v221
	v_sub_f32_e32 v159, 1.0, v159
	v_rcp_f32_e32 v155, v155
	v_cndmask_b32_e32 v164, v165, v164, vcc
	v_max_f32_e32 v159, 0, v159
	v_mul_f32_e32 v0, v164, v0
	v_cmp_gt_f32_e32 vcc, s59, v159
	v_mul_f32_e32 v164, 0x4f800000, v159
	v_cvt_pk_bf16_f32 v154, v154, v0
	v_and_b32_e32 v0, 0xffff0000, v170
	v_cndmask_b32_e32 v159, v159, v164, vcc
	v_sqrt_f32_e32 v164, v159
	v_mul_f32_e32 v0, v155, v0
	v_mul_f32_e32 v155, 0x3fb8aa3b, v158
	v_add_f32_e32 v158, v160, v52
	v_mul_f32_e32 v158, 0xbfb8aa3b, v158
	v_exp_f32_e32 v158, v158
	v_add_u32_e32 v165, -1, v164
	v_fma_f32 v168, -v165, v164, v159
	v_cmp_ge_f32_e64 s[4:5], 0, v168
	v_add_u32_e32 v168, 1, v164
	v_add_f32_e32 v158, 1.0, v158
	v_cndmask_b32_e64 v165, v164, v165, s[4:5]
	v_fma_f32 v164, -v168, v164, v159
	v_cmp_lt_f32_e64 s[4:5], 0, v164
	v_rcp_f32_e32 v158, v158
	v_mul_f32_e32 v156, 0xbfb8aa3b, v156
	v_cndmask_b32_e64 v164, v165, v168, s[4:5]
	v_mul_f32_e32 v165, 0x37800000, v164
	v_cndmask_b32_e32 v164, v164, v165, vcc
	v_cmp_class_f32_e32 vcc, v159, v221
	v_mul_f32_e32 v158, v44, v158
	v_exp_f32_e32 v156, v156
	v_cndmask_b32_e32 v159, v164, v159, vcc
	v_mul_f32_e32 v0, v159, v0
	v_add_f32_e32 v159, v158, v158
	v_mul_f32_e32 v159, 0x3fb8aa3b, v159
	v_exp_f32_e32 v159, v159
	v_add_f32_e32 v156, 1.0, v156
	v_rcp_f32_e32 v156, v156
	v_cvt_pk_bf16_f32 v155, v155, v0
	v_sub_f32_e32 v159, 1.0, v159
	v_max_f32_e32 v159, 0, v159
	v_cmp_gt_f32_e32 vcc, s59, v159
	v_mul_f32_e32 v160, 0x4f800000, v159
	v_lshlrev_b32_e32 v0, 16, v171
	v_cndmask_b32_e32 v159, v159, v160, vcc
	v_sqrt_f32_e32 v160, v159
	v_mul_f32_e32 v0, v156, v0
	v_mul_f32_e32 v156, 0x3fb8aa3b, v158
	v_add_f32_e32 v158, v161, v53
	v_mul_f32_e32 v158, 0xbfb8aa3b, v158
	v_exp_f32_e32 v158, v158
	v_add_u32_e32 v164, -1, v160
	v_fma_f32 v165, -v164, v160, v159
	v_cmp_ge_f32_e64 s[4:5], 0, v165
	v_add_u32_e32 v165, 1, v160
	v_add_f32_e32 v158, 1.0, v158
	v_cndmask_b32_e64 v164, v160, v164, s[4:5]
	v_fma_f32 v160, -v165, v160, v159
	v_cmp_lt_f32_e64 s[4:5], 0, v160
	v_rcp_f32_e32 v158, v158
	v_add_f32_e32 v146, v146, v26
	v_cndmask_b32_e64 v160, v164, v165, s[4:5]
	v_mul_f32_e32 v164, 0x37800000, v160
	v_cndmask_b32_e32 v160, v160, v164, vcc
	v_cmp_class_f32_e32 vcc, v159, v221
	v_mul_f32_e32 v158, v45, v158
	v_add_f32_e32 v157, v157, v49
	v_cndmask_b32_e32 v159, v160, v159, vcc
	v_mul_f32_e32 v0, v159, v0
	v_add_f32_e32 v159, v158, v158
	v_mul_f32_e32 v159, 0x3fb8aa3b, v159
	v_exp_f32_e32 v159, v159
	v_mul_f32_e32 v146, 0xbfb8aa3b, v146
	v_mul_f32_e32 v157, 0xbfb8aa3b, v157
	v_exp_f32_e32 v146, v146
	v_sub_f32_e32 v159, 1.0, v159
	v_max_f32_e32 v159, 0, v159
	v_cmp_gt_f32_e32 vcc, s59, v159
	v_mul_f32_e32 v160, 0x4f800000, v159
	v_exp_f32_e32 v157, v157
	v_cndmask_b32_e32 v159, v159, v160, vcc
	v_sqrt_f32_e32 v160, v159
	v_add_f32_e32 v142, v142, v22
	v_mul_f32_e32 v142, 0xbfb8aa3b, v142
	v_add_f32_e32 v146, 1.0, v146
	v_add_u32_e32 v161, -1, v160
	v_fma_f32 v164, -v161, v160, v159
	v_cmp_ge_f32_e64 s[4:5], 0, v164
	v_add_u32_e32 v164, 1, v160
	v_exp_f32_e32 v142, v142
	v_add_f32_e32 v157, 1.0, v157
	v_cndmask_b32_e64 v161, v160, v161, s[4:5]
	v_fma_f32 v160, -v164, v160, v159
	v_rcp_f32_e32 v146, v146
	v_rcp_f32_e32 v157, v157
	v_cmp_lt_f32_e64 s[4:5], 0, v160
	v_add_f32_e32 v142, 1.0, v142
	v_cvt_pk_bf16_f32 v156, v156, v0
	v_and_b32_e32 v0, 0xffff0000, v171
	v_cndmask_b32_e64 v160, v161, v164, s[4:5]
	v_mul_f32_e32 v161, 0x37800000, v160
	v_cndmask_b32_e32 v160, v160, v161, vcc
; __device__ __forceinline__ unsigned cvt_pk_bf16(float lo, float hi) { unsigned r; asm volatile("v_cvt_pk_bf16_f32 %0, %1, %2" : "=v"(r) : "v"(lo), "v"(hi)); return r; }
; __device__ __forceinline__ float fast_sigmoid(float x) { return __builtin_amdgcn_rcpf(1.0f + __expf(-x)); }
;     __device__ __forceinline__ void operator()(const f32x4 (&acc)[2][2][4][2], const Unit& u, int wr, int wc, int fr, int fq, PG8_LAS unsigned char* ldsb) const {
;     ...
;             for (int m = 0; m < 4; ++m) {
;                 const size_t ro = (size_t)(row0 + ai * HALF + m * 16) * 512 + ch0;
;                 const u32x4 xw = xwv[ai][m];
;                 unsigned ow[8];
; #pragma unroll
;                 for (int n = 0; n < 2; ++n)
; #pragma unroll
;                     for (int i = 0; i < 4; ++i) { const int e = n * 4 + i;
;                         const unsigned wd = xw[e >> 1]; const float xc = __uint_as_float((e & 1) ? (wd & 0xffff0000u) : (wd << 16));
;                         const float r = fast_sigmoid(acc[ai][0][m][n][i] + br[e]), ig = fast_sigmoid(acc[ai][1][m][n][i] + bi[e]);
;                         const float la = sp[e] * r;
;                         const float bb = __builtin_sqrtf(fmaxf(1.0f - __expf(2.0f * la), 0.f)) * (ig * xc);
;                         ow[e] = cvt_pk_bf16(la * 1.4426950408889634f, bb); }
;                 u32x4 w0, w1; w0.x = ow[0]; w0.y = ow[1]; w0.z = ow[2]; w0.w = ow[3]; w1.x = ow[4]; w1.y = ow[5]; w1.z = ow[6]; w1.w = ow[7];
;                 *(u32x4*)(AB + ro) = w0; *(u32x4*)(AB + ro + 4) = w1;
	v_cmp_class_f32_e32 vcc, v159, v221
	v_rcp_f32_e32 v142, v142
	v_mul_f32_e32 v146, v18, v146
	v_cndmask_b32_e32 v159, v160, v159, vcc
	v_mul_f32_e32 v0, v157, v0
	v_mul_f32_e32 v157, 0x3fb8aa3b, v158
	v_add_f32_e32 v158, v146, v146
	v_mul_f32_e32 v0, v159, v0
	v_mul_f32_e32 v158, 0x3fb8aa3b, v158
	v_cvt_pk_bf16_f32 v157, v157, v0
	v_lshlrev_b32_e32 v0, 16, v172
	v_exp_f32_e32 v158, v158
	v_mul_f32_e32 v0, v142, v0
	v_mul_f32_e32 v142, 0x3fb8aa3b, v146
	v_add_f32_e32 v146, v147, v27
	v_mul_f32_e32 v146, 0xbfb8aa3b, v146
	v_exp_f32_e32 v146, v146
	v_sub_f32_e32 v158, 1.0, v158
	v_max_f32_e32 v158, 0, v158
	v_cmp_gt_f32_e32 vcc, s59, v158
	v_mul_f32_e32 v159, 0x4f800000, v158
	v_add_f32_e32 v146, 1.0, v146
	v_cndmask_b32_e32 v158, v158, v159, vcc
	v_sqrt_f32_e32 v159, v158
	v_rcp_f32_e32 v146, v146
	v_add_f32_e32 v143, v143, v23
	v_mul_f32_e32 v143, 0xbfb8aa3b, v143
	v_add_u32_e32 v160, -1, v159
	v_mul_f32_e32 v146, v19, v146
	v_fma_f32 v161, -v160, v159, v158
	v_add_f32_e32 v147, v146, v146
	v_cmp_ge_f32_e64 s[4:5], 0, v161
	v_add_u32_e32 v161, 1, v159
	v_mul_f32_e32 v147, 0x3fb8aa3b, v147
	v_cndmask_b32_e64 v160, v159, v160, s[4:5]
	v_fma_f32 v159, -v161, v159, v158
	v_exp_f32_e32 v143, v143
	v_exp_f32_e32 v147, v147
	v_cmp_lt_f32_e64 s[4:5], 0, v159
	v_add_f32_e32 v144, v144, v24
	v_add_f32_e32 v143, 1.0, v143
	v_cndmask_b32_e64 v159, v160, v161, s[4:5]
	v_mul_f32_e32 v160, 0x37800000, v159
	v_cndmask_b32_e32 v159, v159, v160, vcc
	v_cmp_class_f32_e32 vcc, v158, v221
	v_sub_f32_e32 v147, 1.0, v147
	v_rcp_f32_e32 v143, v143
	v_cndmask_b32_e32 v158, v159, v158, vcc
	v_max_f32_e32 v147, 0, v147
	v_mul_f32_e32 v0, v158, v0
	v_cmp_gt_f32_e32 vcc, s59, v147
	v_mul_f32_e32 v158, 0x4f800000, v147
	v_cvt_pk_bf16_f32 v142, v142, v0
	v_and_b32_e32 v0, 0xffff0000, v172
	v_cndmask_b32_e32 v147, v147, v158, vcc
	v_sqrt_f32_e32 v158, v147
	v_mul_f32_e32 v0, v143, v0
	v_mul_f32_e32 v143, 0x3fb8aa3b, v146
	v_add_f32_e32 v146, v148, v28
	v_mul_f32_e32 v146, 0xbfb8aa3b, v146
	v_exp_f32_e32 v146, v146
	v_add_u32_e32 v159, -1, v158
	v_fma_f32 v160, -v159, v158, v147
	v_cmp_ge_f32_e64 s[4:5], 0, v160
	v_add_u32_e32 v160, 1, v158
	v_add_f32_e32 v146, 1.0, v146
	v_cndmask_b32_e64 v159, v158, v159, s[4:5]
	v_fma_f32 v158, -v160, v158, v147
	v_cmp_lt_f32_e64 s[4:5], 0, v158
	v_rcp_f32_e32 v146, v146
	v_mul_f32_e32 v144, 0xbfb8aa3b, v144
	v_cndmask_b32_e64 v158, v159, v160, s[4:5]
	v_mul_f32_e32 v159, 0x37800000, v158
	v_cndmask_b32_e32 v158, v158, v159, vcc
	v_cmp_class_f32_e32 vcc, v147, v221
	v_mul_f32_e32 v146, v20, v146
	v_exp_f32_e32 v144, v144
	v_cndmask_b32_e32 v147, v158, v147, vcc
	v_mul_f32_e32 v0, v147, v0
	v_add_f32_e32 v147, v146, v146
	v_mul_f32_e32 v147, 0x3fb8aa3b, v147
	v_exp_f32_e32 v147, v147
	v_add_f32_e32 v144, 1.0, v144
	v_rcp_f32_e32 v144, v144
	v_cvt_pk_bf16_f32 v143, v143, v0
	v_sub_f32_e32 v147, 1.0, v147
	v_max_f32_e32 v147, 0, v147
	v_cmp_gt_f32_e32 vcc, s59, v147
	v_mul_f32_e32 v148, 0x4f800000, v147
	v_lshlrev_b32_e32 v0, 16, v173
	v_cndmask_b32_e32 v147, v147, v148, vcc
	v_sqrt_f32_e32 v148, v147
	v_mul_f32_e32 v0, v144, v0
	v_mul_f32_e32 v144, 0x3fb8aa3b, v146
	v_add_f32_e32 v146, v149, v29
	v_mul_f32_e32 v146, 0xbfb8aa3b, v146
	v_exp_f32_e32 v146, v146
	v_add_u32_e32 v158, -1, v148
	v_fma_f32 v159, -v158, v148, v147
	v_cmp_ge_f32_e64 s[4:5], 0, v159
	v_add_u32_e32 v159, 1, v148
	v_add_f32_e32 v146, 1.0, v146
	v_cndmask_b32_e64 v158, v148, v158, s[4:5]
	v_fma_f32 v148, -v159, v148, v147
	v_cmp_lt_f32_e64 s[4:5], 0, v148
	v_rcp_f32_e32 v146, v146
	v_add_f32_e32 v145, v145, v25
	v_cndmask_b32_e64 v148, v158, v159, s[4:5]
	v_mul_f32_e32 v158, 0x37800000, v148
	v_cndmask_b32_e32 v148, v148, v158, vcc
	v_cmp_class_f32_e32 vcc, v147, v221
	v_mul_f32_e32 v146, v21, v146
	v_mul_f32_e32 v145, 0xbfb8aa3b, v145
	v_cndmask_b32_e32 v147, v148, v147, vcc
	v_mul_f32_e32 v0, v0, v147
	v_add_f32_e32 v147, v146, v146
	v_mul_f32_e32 v147, 0x3fb8aa3b, v147
	v_exp_f32_e32 v147, v147
	v_exp_f32_e32 v145, v145
	v_add_f32_e32 v138, v138, v50
	v_mul_f32_e32 v138, 0xbfb8aa3b, v138
	v_sub_f32_e32 v147, 1.0, v147
	v_max_f32_e32 v147, 0, v147
	v_cmp_gt_f32_e32 vcc, s59, v147
	v_mul_f32_e32 v148, 0x4f800000, v147
	v_exp_f32_e32 v138, v138
	v_cndmask_b32_e32 v147, v147, v148, vcc
	v_sqrt_f32_e32 v148, v147
	v_add_f32_e32 v145, 1.0, v145
	v_rcp_f32_e32 v145, v145
	v_add_f32_e32 v134, v134, v46
	v_add_u32_e32 v149, -1, v148
	v_fma_f32 v158, -v149, v148, v147
	v_cmp_ge_f32_e64 s[4:5], 0, v158
	v_add_u32_e32 v158, 1, v148
	v_mul_f32_e32 v134, 0xbfb8aa3b, v134
	v_cndmask_b32_e64 v149, v148, v149, s[4:5]
	v_fma_f32 v148, -v158, v148, v147
	v_cmp_lt_f32_e64 s[4:5], 0, v148
	v_add_f32_e32 v138, 1.0, v138
	v_exp_f32_e32 v134, v134
	v_cndmask_b32_e64 v148, v149, v158, s[4:5]
	v_mul_f32_e32 v149, 0x37800000, v148
	v_or_b32_e32 v162, 16, v208
	v_cvt_pk_bf16_f32 v144, v144, v0
	v_and_b32_e32 v0, 0xffff0000, v173
	v_cndmask_b32_e32 v148, v148, v149, vcc
	v_cmp_class_f32_e32 vcc, v147, v221
	v_rcp_f32_e32 v138, v138
	v_ashrrev_i32_e32 v163, 31, v162
	v_cndmask_b32_e32 v147, v148, v147, vcc
	v_mul_f32_e32 v0, v145, v0
	v_mul_f32_e32 v0, v0, v147
	v_mul_f32_e32 v145, 0x3fb8aa3b, v146
	v_lshlrev_b64 v[146:147], 11, v[162:163]
	v_lshl_add_u64 v[146:147], s[18:19], 0, v[146:147]
	v_add_f32_e32 v134, 1.0, v134
	v_lshl_add_u64 v[146:147], v[146:147], 0, v[206:207]
	v_rcp_f32_e32 v134, v134
	v_mul_f32_e32 v138, v42, v138
	v_cvt_pk_bf16_f32 v145, v145, v0
	global_store_dwordx4 v[146:147], v[154:157], off
	global_store_dwordx4 v[146:147], v[142:145], off offset:16
	v_lshlrev_b32_e32 v0, 16, v150
	v_mul_f32_e32 v0, v134, v0
	v_add_f32_e32 v144, v138, v138
	v_mul_f32_e32 v144, 0x3fb8aa3b, v144
; __device__ __forceinline__ unsigned cvt_pk_bf16(float lo, float hi) { unsigned r; asm volatile("v_cvt_pk_bf16_f32 %0, %1, %2" : "=v"(r) : "v"(lo), "v"(hi)); return r; }
; __device__ __forceinline__ float fast_sigmoid(float x) { return __builtin_amdgcn_rcpf(1.0f + __expf(-x)); }
;     __device__ __forceinline__ void operator()(const f32x4 (&acc)[2][2][4][2], const Unit& u, int wr, int wc, int fr, int fq, PG8_LAS unsigned char* ldsb) const {
;     ...
;                     for (int i = 0; i < 4; ++i) { const int e = n * 4 + i;
;                         const unsigned wd = xw[e >> 1]; const float xc = __uint_as_float((e & 1) ? (wd & 0xffff0000u) : (wd << 16));
;                         const float r = fast_sigmoid(acc[ai][0][m][n][i] + br[e]), ig = fast_sigmoid(acc[ai][1][m][n][i] + bi[e]);
;                         const float la = sp[e] * r;
;                         const float bb = __builtin_sqrtf(fmaxf(1.0f - __expf(2.0f * la), 0.f)) * (ig * xc);
;                         ow[e] = cvt_pk_bf16(la * 1.4426950408889634f, bb); }
	v_exp_f32_e32 v144, v144
	v_mul_f32_e32 v134, 0x3fb8aa3b, v138
	v_add_f32_e32 v138, v139, v51
	v_mul_f32_e32 v138, 0xbfb8aa3b, v138
	v_exp_f32_e32 v138, v138
	v_sub_f32_e32 v144, 1.0, v144
	v_max_f32_e32 v144, 0, v144
	v_cmp_gt_f32_e32 vcc, s59, v144
	v_mul_f32_e32 v145, 0x4f800000, v144
	v_add_f32_e32 v138, 1.0, v138
	v_cndmask_b32_e32 v144, v144, v145, vcc
	v_sqrt_f32_e32 v145, v144
	v_rcp_f32_e32 v138, v138
	v_add_f32_e32 v135, v135, v47
	v_mul_f32_e32 v135, 0xbfb8aa3b, v135
	v_add_u32_e32 v146, -1, v145
	v_mul_f32_e32 v138, v43, v138
	v_fma_f32 v147, -v146, v145, v144
	v_add_f32_e32 v139, v138, v138
	v_cmp_ge_f32_e64 s[4:5], 0, v147
	v_add_u32_e32 v147, 1, v145
	v_mul_f32_e32 v139, 0x3fb8aa3b, v139
	v_cndmask_b32_e64 v146, v145, v146, s[4:5]
	v_fma_f32 v145, -v147, v145, v144
	v_exp_f32_e32 v135, v135
	v_exp_f32_e32 v139, v139
	v_cmp_lt_f32_e64 s[4:5], 0, v145
	v_add_f32_e32 v136, v136, v48
	v_add_f32_e32 v135, 1.0, v135
	v_cndmask_b32_e64 v145, v146, v147, s[4:5]
	v_mul_f32_e32 v146, 0x37800000, v145
	v_cndmask_b32_e32 v145, v145, v146, vcc
	v_cmp_class_f32_e32 vcc, v144, v221
	v_sub_f32_e32 v139, 1.0, v139
	v_rcp_f32_e32 v135, v135
	v_cndmask_b32_e32 v144, v145, v144, vcc
	v_max_f32_e32 v139, 0, v139
	v_mul_f32_e32 v0, v144, v0
	v_cmp_gt_f32_e32 vcc, s59, v139
	v_mul_f32_e32 v144, 0x4f800000, v139
	v_cvt_pk_bf16_f32 v134, v134, v0
	v_and_b32_e32 v0, 0xffff0000, v150
	v_cndmask_b32_e32 v139, v139, v144, vcc
	v_sqrt_f32_e32 v144, v139
	v_mul_f32_e32 v0, v135, v0
	v_mul_f32_e32 v135, 0x3fb8aa3b, v138
	v_add_f32_e32 v138, v140, v52
	v_mul_f32_e32 v138, 0xbfb8aa3b, v138
	v_exp_f32_e32 v138, v138
	v_add_u32_e32 v145, -1, v144
	v_fma_f32 v146, -v145, v144, v139
	v_cmp_ge_f32_e64 s[4:5], 0, v146
	v_add_u32_e32 v146, 1, v144
	v_add_f32_e32 v138, 1.0, v138
	v_cndmask_b32_e64 v145, v144, v145, s[4:5]
	v_fma_f32 v144, -v146, v144, v139
	v_cmp_lt_f32_e64 s[4:5], 0, v144
	v_rcp_f32_e32 v138, v138
	v_mul_f32_e32 v136, 0xbfb8aa3b, v136
	v_cndmask_b32_e64 v144, v145, v146, s[4:5]
	v_mul_f32_e32 v145, 0x37800000, v144
	v_cndmask_b32_e32 v144, v144, v145, vcc
	v_cmp_class_f32_e32 vcc, v139, v221
	v_mul_f32_e32 v138, v44, v138
	v_exp_f32_e32 v136, v136
	v_cndmask_b32_e32 v139, v144, v139, vcc
	v_mul_f32_e32 v0, v139, v0
	v_add_f32_e32 v139, v138, v138
	v_mul_f32_e32 v139, 0x3fb8aa3b, v139
	v_exp_f32_e32 v139, v139
	v_add_f32_e32 v136, 1.0, v136
	v_rcp_f32_e32 v136, v136
	v_cvt_pk_bf16_f32 v135, v135, v0
	v_sub_f32_e32 v139, 1.0, v139
	v_max_f32_e32 v139, 0, v139
	v_cmp_gt_f32_e32 vcc, s59, v139
	v_mul_f32_e32 v140, 0x4f800000, v139
	v_lshlrev_b32_e32 v0, 16, v151
	v_cndmask_b32_e32 v139, v139, v140, vcc
	v_sqrt_f32_e32 v140, v139
	v_mul_f32_e32 v0, v136, v0
	v_mul_f32_e32 v136, 0x3fb8aa3b, v138
	v_add_f32_e32 v138, v141, v53
	v_mul_f32_e32 v138, 0xbfb8aa3b, v138
	v_exp_f32_e32 v138, v138
	v_add_u32_e32 v144, -1, v140
	v_fma_f32 v145, -v144, v140, v139
	v_cmp_ge_f32_e64 s[4:5], 0, v145
	v_add_u32_e32 v145, 1, v140
	v_add_f32_e32 v138, 1.0, v138
	v_cndmask_b32_e64 v144, v140, v144, s[4:5]
	v_fma_f32 v140, -v145, v140, v139
	v_cmp_lt_f32_e64 s[4:5], 0, v140
	v_rcp_f32_e32 v138, v138
	v_add_f32_e32 v126, v126, v26
	v_cndmask_b32_e64 v140, v144, v145, s[4:5]
	v_mul_f32_e32 v144, 0x37800000, v140
	v_cndmask_b32_e32 v140, v140, v144, vcc
	v_cmp_class_f32_e32 vcc, v139, v221
	v_mul_f32_e32 v138, v45, v138
	v_add_f32_e32 v137, v137, v49
	v_cndmask_b32_e32 v139, v140, v139, vcc
	v_mul_f32_e32 v0, v139, v0
	v_add_f32_e32 v139, v138, v138
	v_mul_f32_e32 v139, 0x3fb8aa3b, v139
	v_exp_f32_e32 v139, v139
	v_mul_f32_e32 v126, 0xbfb8aa3b, v126
	v_mul_f32_e32 v137, 0xbfb8aa3b, v137
	v_exp_f32_e32 v126, v126
	v_sub_f32_e32 v139, 1.0, v139
	v_max_f32_e32 v139, 0, v139
	v_cmp_gt_f32_e32 vcc, s59, v139
	v_mul_f32_e32 v140, 0x4f800000, v139
	v_exp_f32_e32 v137, v137
	v_cndmask_b32_e32 v139, v139, v140, vcc
	v_sqrt_f32_e32 v140, v139
	v_add_f32_e32 v122, v122, v22
	v_mul_f32_e32 v122, 0xbfb8aa3b, v122
	v_add_f32_e32 v126, 1.0, v126
	v_add_u32_e32 v141, -1, v140
	v_fma_f32 v144, -v141, v140, v139
	v_cmp_ge_f32_e64 s[4:5], 0, v144
	v_add_u32_e32 v144, 1, v140
	v_exp_f32_e32 v122, v122
	v_add_f32_e32 v137, 1.0, v137
	v_cndmask_b32_e64 v141, v140, v141, s[4:5]
	v_fma_f32 v140, -v144, v140, v139
	v_rcp_f32_e32 v126, v126
	v_rcp_f32_e32 v137, v137
	v_cmp_lt_f32_e64 s[4:5], 0, v140
	v_add_f32_e32 v122, 1.0, v122
	v_cvt_pk_bf16_f32 v136, v136, v0
	v_and_b32_e32 v0, 0xffff0000, v151
	v_cndmask_b32_e64 v140, v141, v144, s[4:5]
	v_mul_f32_e32 v141, 0x37800000, v140
	v_cndmask_b32_e32 v140, v140, v141, vcc
	v_cmp_class_f32_e32 vcc, v139, v221
	v_rcp_f32_e32 v122, v122
	v_mul_f32_e32 v126, v18, v126
	v_cndmask_b32_e32 v139, v140, v139, vcc
	v_mul_f32_e32 v0, v137, v0
	v_mul_f32_e32 v137, 0x3fb8aa3b, v138
	v_add_f32_e32 v138, v126, v126
	v_mul_f32_e32 v0, v139, v0
	v_mul_f32_e32 v138, 0x3fb8aa3b, v138
	v_cvt_pk_bf16_f32 v137, v137, v0
	v_lshlrev_b32_e32 v0, 16, v152
	v_exp_f32_e32 v138, v138
	v_mul_f32_e32 v0, v122, v0
	v_mul_f32_e32 v122, 0x3fb8aa3b, v126
	v_add_f32_e32 v126, v127, v27
	v_mul_f32_e32 v126, 0xbfb8aa3b, v126
	v_exp_f32_e32 v126, v126
	v_sub_f32_e32 v138, 1.0, v138
	v_max_f32_e32 v138, 0, v138
	v_cmp_gt_f32_e32 vcc, s59, v138
	v_mul_f32_e32 v139, 0x4f800000, v138
	v_add_f32_e32 v126, 1.0, v126
	v_cndmask_b32_e32 v138, v138, v139, vcc
	v_sqrt_f32_e32 v139, v138
	v_rcp_f32_e32 v126, v126
	v_add_f32_e32 v123, v123, v23
	v_mul_f32_e32 v123, 0xbfb8aa3b, v123
	v_add_u32_e32 v140, -1, v139
	v_mul_f32_e32 v126, v19, v126
	v_fma_f32 v141, -v140, v139, v138
	v_add_f32_e32 v127, v126, v126
	v_cmp_ge_f32_e64 s[4:5], 0, v141
	v_add_u32_e32 v141, 1, v139
	v_mul_f32_e32 v127, 0x3fb8aa3b, v127
; __device__ __forceinline__ unsigned cvt_pk_bf16(float lo, float hi) { unsigned r; asm volatile("v_cvt_pk_bf16_f32 %0, %1, %2" : "=v"(r) : "v"(lo), "v"(hi)); return r; }
; __device__ __forceinline__ float fast_sigmoid(float x) { return __builtin_amdgcn_rcpf(1.0f + __expf(-x)); }
;     __device__ __forceinline__ void operator()(const f32x4 (&acc)[2][2][4][2], const Unit& u, int wr, int wc, int fr, int fq, PG8_LAS unsigned char* ldsb) const {
;     ...
;             for (int m = 0; m < 4; ++m) {
;                 const size_t ro = (size_t)(row0 + ai * HALF + m * 16) * 512 + ch0;
;                 const u32x4 xw = xwv[ai][m];
;                 unsigned ow[8];
; #pragma unroll
;                 for (int n = 0; n < 2; ++n)
; #pragma unroll
;                     for (int i = 0; i < 4; ++i) { const int e = n * 4 + i;
;                         const unsigned wd = xw[e >> 1]; const float xc = __uint_as_float((e & 1) ? (wd & 0xffff0000u) : (wd << 16));
;                         const float r = fast_sigmoid(acc[ai][0][m][n][i] + br[e]), ig = fast_sigmoid(acc[ai][1][m][n][i] + bi[e]);
;                         const float la = sp[e] * r;
;                         const float bb = __builtin_sqrtf(fmaxf(1.0f - __expf(2.0f * la), 0.f)) * (ig * xc);
;                         ow[e] = cvt_pk_bf16(la * 1.4426950408889634f, bb); }
;                 u32x4 w0, w1; w0.x = ow[0]; w0.y = ow[1]; w0.z = ow[2]; w0.w = ow[3]; w1.x = ow[4]; w1.y = ow[5]; w1.z = ow[6]; w1.w = ow[7];
;                 *(u32x4*)(AB + ro) = w0; *(u32x4*)(AB + ro + 4) = w1;
	v_cndmask_b32_e64 v140, v139, v140, s[4:5]
	v_fma_f32 v139, -v141, v139, v138
	v_exp_f32_e32 v123, v123
	v_exp_f32_e32 v127, v127
	v_cmp_lt_f32_e64 s[4:5], 0, v139
	v_add_f32_e32 v124, v124, v24
	v_add_f32_e32 v123, 1.0, v123
	v_cndmask_b32_e64 v139, v140, v141, s[4:5]
	v_mul_f32_e32 v140, 0x37800000, v139
	v_cndmask_b32_e32 v139, v139, v140, vcc
	v_cmp_class_f32_e32 vcc, v138, v221
	v_sub_f32_e32 v127, 1.0, v127
	v_rcp_f32_e32 v123, v123
	v_cndmask_b32_e32 v138, v139, v138, vcc
	v_max_f32_e32 v127, 0, v127
	v_mul_f32_e32 v0, v138, v0
	v_cmp_gt_f32_e32 vcc, s59, v127
	v_mul_f32_e32 v138, 0x4f800000, v127
	v_cvt_pk_bf16_f32 v122, v122, v0
	v_and_b32_e32 v0, 0xffff0000, v152
	v_cndmask_b32_e32 v127, v127, v138, vcc
	v_sqrt_f32_e32 v138, v127
	v_mul_f32_e32 v0, v123, v0
	v_mul_f32_e32 v123, 0x3fb8aa3b, v126
	v_add_f32_e32 v126, v128, v28
	v_mul_f32_e32 v126, 0xbfb8aa3b, v126
	v_exp_f32_e32 v126, v126
	v_add_u32_e32 v139, -1, v138
	v_fma_f32 v140, -v139, v138, v127
	v_cmp_ge_f32_e64 s[4:5], 0, v140
	v_add_u32_e32 v140, 1, v138
	v_add_f32_e32 v126, 1.0, v126
	v_cndmask_b32_e64 v139, v138, v139, s[4:5]
	v_fma_f32 v138, -v140, v138, v127
	v_cmp_lt_f32_e64 s[4:5], 0, v138
	v_rcp_f32_e32 v126, v126
	v_mul_f32_e32 v124, 0xbfb8aa3b, v124
	v_cndmask_b32_e64 v138, v139, v140, s[4:5]
	v_mul_f32_e32 v139, 0x37800000, v138
	v_cndmask_b32_e32 v138, v138, v139, vcc
	v_cmp_class_f32_e32 vcc, v127, v221
	v_mul_f32_e32 v126, v20, v126
	v_exp_f32_e32 v124, v124
	v_cndmask_b32_e32 v127, v138, v127, vcc
	v_mul_f32_e32 v0, v127, v0
	v_add_f32_e32 v127, v126, v126
	v_mul_f32_e32 v127, 0x3fb8aa3b, v127
	v_exp_f32_e32 v127, v127
	v_add_f32_e32 v124, 1.0, v124
	v_rcp_f32_e32 v124, v124
	v_cvt_pk_bf16_f32 v123, v123, v0
	v_sub_f32_e32 v127, 1.0, v127
	v_max_f32_e32 v127, 0, v127
	v_cmp_gt_f32_e32 vcc, s59, v127
	v_mul_f32_e32 v128, 0x4f800000, v127
	v_lshlrev_b32_e32 v0, 16, v153
	v_cndmask_b32_e32 v127, v127, v128, vcc
	v_sqrt_f32_e32 v128, v127
	v_mul_f32_e32 v0, v124, v0
	v_mul_f32_e32 v124, 0x3fb8aa3b, v126
	v_add_f32_e32 v126, v129, v29
	v_mul_f32_e32 v126, 0xbfb8aa3b, v126
	v_exp_f32_e32 v126, v126
	v_add_u32_e32 v138, -1, v128
	v_fma_f32 v139, -v138, v128, v127
	v_cmp_ge_f32_e64 s[4:5], 0, v139
	v_add_u32_e32 v139, 1, v128
	v_add_f32_e32 v126, 1.0, v126
	v_cndmask_b32_e64 v138, v128, v138, s[4:5]
	v_fma_f32 v128, -v139, v128, v127
	v_cmp_lt_f32_e64 s[4:5], 0, v128
	v_rcp_f32_e32 v126, v126
	v_add_f32_e32 v125, v125, v25
	v_cndmask_b32_e64 v128, v138, v139, s[4:5]
	v_mul_f32_e32 v138, 0x37800000, v128
	v_cndmask_b32_e32 v128, v128, v138, vcc
	v_cmp_class_f32_e32 vcc, v127, v221
	v_mul_f32_e32 v126, v21, v126
	v_mul_f32_e32 v125, 0xbfb8aa3b, v125
	v_cndmask_b32_e32 v127, v128, v127, vcc
	v_mul_f32_e32 v0, v0, v127
	v_add_f32_e32 v127, v126, v126
	v_mul_f32_e32 v127, 0x3fb8aa3b, v127
	v_exp_f32_e32 v127, v127
	v_exp_f32_e32 v125, v125
	v_add_f32_e32 v118, v118, v50
	v_mul_f32_e32 v118, 0xbfb8aa3b, v118
	v_sub_f32_e32 v127, 1.0, v127
	v_max_f32_e32 v127, 0, v127
	v_cmp_gt_f32_e32 vcc, s59, v127
	v_mul_f32_e32 v128, 0x4f800000, v127
	v_exp_f32_e32 v118, v118
	v_cndmask_b32_e32 v127, v127, v128, vcc
	v_sqrt_f32_e32 v128, v127
	v_add_f32_e32 v125, 1.0, v125
	v_rcp_f32_e32 v125, v125
	v_add_f32_e32 v114, v114, v46
	v_add_u32_e32 v129, -1, v128
	v_fma_f32 v138, -v129, v128, v127
	v_cmp_ge_f32_e64 s[4:5], 0, v138
	v_add_u32_e32 v138, 1, v128
	v_mul_f32_e32 v114, 0xbfb8aa3b, v114
	v_cndmask_b32_e64 v129, v128, v129, s[4:5]
	v_fma_f32 v128, -v138, v128, v127
	v_cmp_lt_f32_e64 s[4:5], 0, v128
	v_add_f32_e32 v118, 1.0, v118
	v_exp_f32_e32 v114, v114
	v_cndmask_b32_e64 v128, v129, v138, s[4:5]
	v_mul_f32_e32 v129, 0x37800000, v128
	v_or_b32_e32 v142, 32, v208
	v_cvt_pk_bf16_f32 v124, v124, v0
	v_and_b32_e32 v0, 0xffff0000, v153
	v_cndmask_b32_e32 v128, v128, v129, vcc
	v_cmp_class_f32_e32 vcc, v127, v221
	v_rcp_f32_e32 v118, v118
	v_ashrrev_i32_e32 v143, 31, v142
	v_cndmask_b32_e32 v127, v128, v127, vcc
	v_mul_f32_e32 v0, v125, v0
	v_mul_f32_e32 v0, v0, v127
	v_mul_f32_e32 v125, 0x3fb8aa3b, v126
	v_lshlrev_b64 v[126:127], 11, v[142:143]
	v_lshl_add_u64 v[126:127], s[18:19], 0, v[126:127]
	v_add_f32_e32 v114, 1.0, v114
	v_lshl_add_u64 v[126:127], v[126:127], 0, v[206:207]
	v_rcp_f32_e32 v114, v114
	v_mul_f32_e32 v118, v42, v118
	v_cvt_pk_bf16_f32 v125, v125, v0
	global_store_dwordx4 v[126:127], v[134:137], off
	global_store_dwordx4 v[126:127], v[122:125], off offset:16
	v_lshlrev_b32_e32 v0, 16, v130
	v_mul_f32_e32 v0, v114, v0
	v_add_f32_e32 v124, v118, v118
	v_mul_f32_e32 v124, 0x3fb8aa3b, v124
	v_exp_f32_e32 v124, v124
	v_mul_f32_e32 v114, 0x3fb8aa3b, v118
	v_add_f32_e32 v118, v119, v51
	v_mul_f32_e32 v118, 0xbfb8aa3b, v118
	v_exp_f32_e32 v118, v118
	v_sub_f32_e32 v124, 1.0, v124
	v_max_f32_e32 v124, 0, v124
	v_cmp_gt_f32_e32 vcc, s59, v124
	v_mul_f32_e32 v125, 0x4f800000, v124
	v_add_f32_e32 v118, 1.0, v118
	v_cndmask_b32_e32 v124, v124, v125, vcc
	v_sqrt_f32_e32 v125, v124
	v_rcp_f32_e32 v118, v118
	v_add_f32_e32 v115, v115, v47
	v_mul_f32_e32 v115, 0xbfb8aa3b, v115
	v_add_u32_e32 v126, -1, v125
	v_mul_f32_e32 v118, v43, v118
	v_fma_f32 v127, -v126, v125, v124
	v_add_f32_e32 v119, v118, v118
	v_cmp_ge_f32_e64 s[4:5], 0, v127
	v_add_u32_e32 v127, 1, v125
	v_mul_f32_e32 v119, 0x3fb8aa3b, v119
	v_cndmask_b32_e64 v126, v125, v126, s[4:5]
	v_fma_f32 v125, -v127, v125, v124
	v_exp_f32_e32 v115, v115
	v_exp_f32_e32 v119, v119
	v_cmp_lt_f32_e64 s[4:5], 0, v125
	v_add_f32_e32 v116, v116, v48
	v_add_f32_e32 v115, 1.0, v115
	v_cndmask_b32_e64 v125, v126, v127, s[4:5]
	v_mul_f32_e32 v126, 0x37800000, v125
	v_cndmask_b32_e32 v125, v125, v126, vcc
	v_cmp_class_f32_e32 vcc, v124, v221
; __device__ __forceinline__ unsigned cvt_pk_bf16(float lo, float hi) { unsigned r; asm volatile("v_cvt_pk_bf16_f32 %0, %1, %2" : "=v"(r) : "v"(lo), "v"(hi)); return r; }
; __device__ __forceinline__ float fast_sigmoid(float x) { return __builtin_amdgcn_rcpf(1.0f + __expf(-x)); }
;     __device__ __forceinline__ void operator()(const f32x4 (&acc)[2][2][4][2], const Unit& u, int wr, int wc, int fr, int fq, PG8_LAS unsigned char* ldsb) const {
;     ...
;                     for (int i = 0; i < 4; ++i) { const int e = n * 4 + i;
;                         const unsigned wd = xw[e >> 1]; const float xc = __uint_as_float((e & 1) ? (wd & 0xffff0000u) : (wd << 16));
;                         const float r = fast_sigmoid(acc[ai][0][m][n][i] + br[e]), ig = fast_sigmoid(acc[ai][1][m][n][i] + bi[e]);
;                         const float la = sp[e] * r;
;                         const float bb = __builtin_sqrtf(fmaxf(1.0f - __expf(2.0f * la), 0.f)) * (ig * xc);
;                         ow[e] = cvt_pk_bf16(la * 1.4426950408889634f, bb); }
	v_sub_f32_e32 v119, 1.0, v119
	v_rcp_f32_e32 v115, v115
	v_cndmask_b32_e32 v124, v125, v124, vcc
	v_max_f32_e32 v119, 0, v119
	v_mul_f32_e32 v0, v124, v0
	v_cmp_gt_f32_e32 vcc, s59, v119
	v_mul_f32_e32 v124, 0x4f800000, v119
	v_cvt_pk_bf16_f32 v114, v114, v0
	v_and_b32_e32 v0, 0xffff0000, v130
	v_cndmask_b32_e32 v119, v119, v124, vcc
	v_sqrt_f32_e32 v124, v119
	v_mul_f32_e32 v0, v115, v0
	v_mul_f32_e32 v115, 0x3fb8aa3b, v118
	v_add_f32_e32 v118, v120, v52
	v_mul_f32_e32 v118, 0xbfb8aa3b, v118
	v_exp_f32_e32 v118, v118
	v_add_u32_e32 v125, -1, v124
	v_fma_f32 v126, -v125, v124, v119
	v_cmp_ge_f32_e64 s[4:5], 0, v126
	v_add_u32_e32 v126, 1, v124
	v_add_f32_e32 v118, 1.0, v118
	v_cndmask_b32_e64 v125, v124, v125, s[4:5]
	v_fma_f32 v124, -v126, v124, v119
	v_cmp_lt_f32_e64 s[4:5], 0, v124
	v_rcp_f32_e32 v118, v118
	v_mul_f32_e32 v116, 0xbfb8aa3b, v116
	v_cndmask_b32_e64 v124, v125, v126, s[4:5]
	v_mul_f32_e32 v125, 0x37800000, v124
	v_cndmask_b32_e32 v124, v124, v125, vcc
	v_cmp_class_f32_e32 vcc, v119, v221
	v_mul_f32_e32 v118, v44, v118
	v_exp_f32_e32 v116, v116
	v_cndmask_b32_e32 v119, v124, v119, vcc
	v_mul_f32_e32 v0, v119, v0
	v_add_f32_e32 v119, v118, v118
	v_mul_f32_e32 v119, 0x3fb8aa3b, v119
	v_exp_f32_e32 v119, v119
	v_add_f32_e32 v116, 1.0, v116
	v_rcp_f32_e32 v116, v116
	v_cvt_pk_bf16_f32 v115, v115, v0
	v_sub_f32_e32 v119, 1.0, v119
	v_max_f32_e32 v119, 0, v119
	v_cmp_gt_f32_e32 vcc, s59, v119
	v_mul_f32_e32 v120, 0x4f800000, v119
	v_lshlrev_b32_e32 v0, 16, v131
	v_cndmask_b32_e32 v119, v119, v120, vcc
	v_sqrt_f32_e32 v120, v119
	v_mul_f32_e32 v0, v116, v0
	v_mul_f32_e32 v116, 0x3fb8aa3b, v118
	v_add_f32_e32 v118, v121, v53
	v_mul_f32_e32 v118, 0xbfb8aa3b, v118
	v_exp_f32_e32 v118, v118
	v_add_u32_e32 v124, -1, v120
	v_fma_f32 v125, -v124, v120, v119
	v_cmp_ge_f32_e64 s[4:5], 0, v125
	v_add_u32_e32 v125, 1, v120
	v_add_f32_e32 v118, 1.0, v118
	v_cndmask_b32_e64 v124, v120, v124, s[4:5]
	v_fma_f32 v120, -v125, v120, v119
	v_cmp_lt_f32_e64 s[4:5], 0, v120
	v_rcp_f32_e32 v118, v118
	v_add_f32_e32 v106, v106, v26
	v_cndmask_b32_e64 v120, v124, v125, s[4:5]
	v_mul_f32_e32 v124, 0x37800000, v120
	v_cndmask_b32_e32 v120, v120, v124, vcc
	v_cmp_class_f32_e32 vcc, v119, v221
	v_mul_f32_e32 v118, v45, v118
	v_add_f32_e32 v117, v117, v49
	v_cndmask_b32_e32 v119, v120, v119, vcc
	v_mul_f32_e32 v0, v119, v0
	v_add_f32_e32 v119, v118, v118
	v_mul_f32_e32 v119, 0x3fb8aa3b, v119
	v_exp_f32_e32 v119, v119
	v_mul_f32_e32 v106, 0xbfb8aa3b, v106
	v_mul_f32_e32 v117, 0xbfb8aa3b, v117
	v_exp_f32_e32 v106, v106
	v_sub_f32_e32 v119, 1.0, v119
	v_max_f32_e32 v119, 0, v119
	v_cmp_gt_f32_e32 vcc, s59, v119
	v_mul_f32_e32 v120, 0x4f800000, v119
	v_exp_f32_e32 v117, v117
	v_cndmask_b32_e32 v119, v119, v120, vcc
	v_sqrt_f32_e32 v120, v119
	v_add_f32_e32 v102, v102, v22
	v_mul_f32_e32 v102, 0xbfb8aa3b, v102
	v_add_f32_e32 v106, 1.0, v106
	v_add_u32_e32 v121, -1, v120
	v_fma_f32 v124, -v121, v120, v119
	v_cmp_ge_f32_e64 s[4:5], 0, v124
	v_add_u32_e32 v124, 1, v120
	v_exp_f32_e32 v102, v102
	v_add_f32_e32 v117, 1.0, v117
	v_cndmask_b32_e64 v121, v120, v121, s[4:5]
	v_fma_f32 v120, -v124, v120, v119
	v_rcp_f32_e32 v106, v106
	v_rcp_f32_e32 v117, v117
	v_cmp_lt_f32_e64 s[4:5], 0, v120
	v_add_f32_e32 v102, 1.0, v102
	v_cvt_pk_bf16_f32 v116, v116, v0
	v_and_b32_e32 v0, 0xffff0000, v131
	v_cndmask_b32_e64 v120, v121, v124, s[4:5]
	v_mul_f32_e32 v121, 0x37800000, v120
	v_cndmask_b32_e32 v120, v120, v121, vcc
	v_cmp_class_f32_e32 vcc, v119, v221
	v_rcp_f32_e32 v102, v102
	v_mul_f32_e32 v106, v18, v106
	v_cndmask_b32_e32 v119, v120, v119, vcc
	v_mul_f32_e32 v0, v117, v0
	v_mul_f32_e32 v117, 0x3fb8aa3b, v118
	v_add_f32_e32 v118, v106, v106
	v_mul_f32_e32 v0, v119, v0
	v_mul_f32_e32 v118, 0x3fb8aa3b, v118
	v_cvt_pk_bf16_f32 v117, v117, v0
	v_lshlrev_b32_e32 v0, 16, v132
	v_exp_f32_e32 v118, v118
	v_mul_f32_e32 v0, v102, v0
	v_mul_f32_e32 v102, 0x3fb8aa3b, v106
	v_add_f32_e32 v106, v107, v27
	v_mul_f32_e32 v106, 0xbfb8aa3b, v106
	v_exp_f32_e32 v106, v106
	v_sub_f32_e32 v118, 1.0, v118
	v_max_f32_e32 v118, 0, v118
	v_cmp_gt_f32_e32 vcc, s59, v118
	v_mul_f32_e32 v119, 0x4f800000, v118
	v_add_f32_e32 v106, 1.0, v106
	v_cndmask_b32_e32 v118, v118, v119, vcc
	v_sqrt_f32_e32 v119, v118
	v_rcp_f32_e32 v106, v106
	v_add_f32_e32 v103, v103, v23
	v_mul_f32_e32 v103, 0xbfb8aa3b, v103
	v_add_u32_e32 v120, -1, v119
	v_mul_f32_e32 v106, v19, v106
	v_fma_f32 v121, -v120, v119, v118
	v_add_f32_e32 v107, v106, v106
	v_cmp_ge_f32_e64 s[4:5], 0, v121
	v_add_u32_e32 v121, 1, v119
	v_mul_f32_e32 v107, 0x3fb8aa3b, v107
	v_cndmask_b32_e64 v120, v119, v120, s[4:5]
	v_fma_f32 v119, -v121, v119, v118
	v_exp_f32_e32 v103, v103
	v_exp_f32_e32 v107, v107
	v_cmp_lt_f32_e64 s[4:5], 0, v119
	v_add_f32_e32 v104, v104, v24
	v_add_f32_e32 v103, 1.0, v103
	v_cndmask_b32_e64 v119, v120, v121, s[4:5]
	v_mul_f32_e32 v120, 0x37800000, v119
	v_cndmask_b32_e32 v119, v119, v120, vcc
	v_cmp_class_f32_e32 vcc, v118, v221
	v_sub_f32_e32 v107, 1.0, v107
	v_rcp_f32_e32 v103, v103
	v_cndmask_b32_e32 v118, v119, v118, vcc
	v_max_f32_e32 v107, 0, v107
	v_mul_f32_e32 v0, v118, v0
	v_cmp_gt_f32_e32 vcc, s59, v107
	v_mul_f32_e32 v118, 0x4f800000, v107
	v_cvt_pk_bf16_f32 v102, v102, v0
	v_and_b32_e32 v0, 0xffff0000, v132
	v_cndmask_b32_e32 v107, v107, v118, vcc
	v_sqrt_f32_e32 v118, v107
	v_mul_f32_e32 v0, v103, v0
	v_mul_f32_e32 v103, 0x3fb8aa3b, v106
	v_add_f32_e32 v106, v108, v28
	v_mul_f32_e32 v106, 0xbfb8aa3b, v106
	v_exp_f32_e32 v106, v106
	v_add_u32_e32 v119, -1, v118
	v_fma_f32 v120, -v119, v118, v107
	v_cmp_ge_f32_e64 s[4:5], 0, v120
	v_add_u32_e32 v120, 1, v118
	v_add_f32_e32 v106, 1.0, v106
; __device__ __forceinline__ unsigned cvt_pk_bf16(float lo, float hi) { unsigned r; asm volatile("v_cvt_pk_bf16_f32 %0, %1, %2" : "=v"(r) : "v"(lo), "v"(hi)); return r; }
; __device__ __forceinline__ float fast_sigmoid(float x) { return __builtin_amdgcn_rcpf(1.0f + __expf(-x)); }
;     __device__ __forceinline__ void operator()(const f32x4 (&acc)[2][2][4][2], const Unit& u, int wr, int wc, int fr, int fq, PG8_LAS unsigned char* ldsb) const {
;     ...
;             for (int m = 0; m < 4; ++m) {
;                 const size_t ro = (size_t)(row0 + ai * HALF + m * 16) * 512 + ch0;
;                 const u32x4 xw = xwv[ai][m];
;                 unsigned ow[8];
; #pragma unroll
;                 for (int n = 0; n < 2; ++n)
; #pragma unroll
;                     for (int i = 0; i < 4; ++i) { const int e = n * 4 + i;
;                         const unsigned wd = xw[e >> 1]; const float xc = __uint_as_float((e & 1) ? (wd & 0xffff0000u) : (wd << 16));
;                         const float r = fast_sigmoid(acc[ai][0][m][n][i] + br[e]), ig = fast_sigmoid(acc[ai][1][m][n][i] + bi[e]);
;                         const float la = sp[e] * r;
;                         const float bb = __builtin_sqrtf(fmaxf(1.0f - __expf(2.0f * la), 0.f)) * (ig * xc);
;                         ow[e] = cvt_pk_bf16(la * 1.4426950408889634f, bb); }
;                 u32x4 w0, w1; w0.x = ow[0]; w0.y = ow[1]; w0.z = ow[2]; w0.w = ow[3]; w1.x = ow[4]; w1.y = ow[5]; w1.z = ow[6]; w1.w = ow[7];
;                 *(u32x4*)(AB + ro) = w0; *(u32x4*)(AB + ro + 4) = w1;
	v_cndmask_b32_e64 v119, v118, v119, s[4:5]
	v_fma_f32 v118, -v120, v118, v107
	v_cmp_lt_f32_e64 s[4:5], 0, v118
	v_rcp_f32_e32 v106, v106
	v_mul_f32_e32 v104, 0xbfb8aa3b, v104
	v_cndmask_b32_e64 v118, v119, v120, s[4:5]
	v_mul_f32_e32 v119, 0x37800000, v118
	v_cndmask_b32_e32 v118, v118, v119, vcc
	v_cmp_class_f32_e32 vcc, v107, v221
	v_mul_f32_e32 v106, v20, v106
	v_exp_f32_e32 v104, v104
	v_cndmask_b32_e32 v107, v118, v107, vcc
	v_mul_f32_e32 v0, v107, v0
	v_add_f32_e32 v107, v106, v106
	v_mul_f32_e32 v107, 0x3fb8aa3b, v107
	v_exp_f32_e32 v107, v107
	v_add_f32_e32 v104, 1.0, v104
	v_rcp_f32_e32 v104, v104
	v_cvt_pk_bf16_f32 v103, v103, v0
	v_sub_f32_e32 v107, 1.0, v107
	v_max_f32_e32 v107, 0, v107
	v_cmp_gt_f32_e32 vcc, s59, v107
	v_mul_f32_e32 v108, 0x4f800000, v107
	v_lshlrev_b32_e32 v0, 16, v133
	v_cndmask_b32_e32 v107, v107, v108, vcc
	v_sqrt_f32_e32 v108, v107
	v_mul_f32_e32 v0, v104, v0
	v_mul_f32_e32 v104, 0x3fb8aa3b, v106
	v_add_f32_e32 v106, v109, v29
	v_mul_f32_e32 v106, 0xbfb8aa3b, v106
	v_exp_f32_e32 v106, v106
	v_add_u32_e32 v118, -1, v108
	v_fma_f32 v119, -v118, v108, v107
	v_cmp_ge_f32_e64 s[4:5], 0, v119
	v_add_u32_e32 v119, 1, v108
	v_add_f32_e32 v106, 1.0, v106
	v_cndmask_b32_e64 v118, v108, v118, s[4:5]
	v_fma_f32 v108, -v119, v108, v107
	v_cmp_lt_f32_e64 s[4:5], 0, v108
	v_rcp_f32_e32 v106, v106
	v_add_f32_e32 v105, v105, v25
	v_cndmask_b32_e64 v108, v118, v119, s[4:5]
	v_mul_f32_e32 v118, 0x37800000, v108
	v_cndmask_b32_e32 v108, v108, v118, vcc
	v_cmp_class_f32_e32 vcc, v107, v221
	v_mul_f32_e32 v106, v21, v106
	v_mul_f32_e32 v105, 0xbfb8aa3b, v105
	v_cndmask_b32_e32 v107, v108, v107, vcc
	v_mul_f32_e32 v0, v0, v107
	v_add_f32_e32 v107, v106, v106
	v_mul_f32_e32 v107, 0x3fb8aa3b, v107
	v_exp_f32_e32 v107, v107
	v_exp_f32_e32 v105, v105
	v_add_f32_e32 v98, v98, v50
	v_mul_f32_e32 v98, 0xbfb8aa3b, v98
	v_sub_f32_e32 v107, 1.0, v107
	v_max_f32_e32 v107, 0, v107
	v_cmp_gt_f32_e32 vcc, s59, v107
	v_mul_f32_e32 v108, 0x4f800000, v107
	v_exp_f32_e32 v98, v98
	v_cndmask_b32_e32 v107, v107, v108, vcc
	v_sqrt_f32_e32 v108, v107
	v_add_f32_e32 v105, 1.0, v105
	v_rcp_f32_e32 v105, v105
	v_add_f32_e32 v94, v94, v46
	v_add_u32_e32 v109, -1, v108
	v_fma_f32 v118, -v109, v108, v107
	v_cmp_ge_f32_e64 s[4:5], 0, v118
	v_add_u32_e32 v118, 1, v108
	v_mul_f32_e32 v94, 0xbfb8aa3b, v94
	v_cndmask_b32_e64 v109, v108, v109, s[4:5]
	v_fma_f32 v108, -v118, v108, v107
	v_cmp_lt_f32_e64 s[4:5], 0, v108
	v_add_f32_e32 v98, 1.0, v98
	v_exp_f32_e32 v94, v94
	v_cndmask_b32_e64 v108, v109, v118, s[4:5]
	v_mul_f32_e32 v109, 0x37800000, v108
	v_or_b32_e32 v122, 48, v208
	v_cvt_pk_bf16_f32 v104, v104, v0
	v_and_b32_e32 v0, 0xffff0000, v133
	v_cndmask_b32_e32 v108, v108, v109, vcc
	v_cmp_class_f32_e32 vcc, v107, v221
	v_rcp_f32_e32 v98, v98
	v_ashrrev_i32_e32 v123, 31, v122
	v_cndmask_b32_e32 v107, v108, v107, vcc
	v_mul_f32_e32 v0, v105, v0
	v_mul_f32_e32 v0, v0, v107
	v_mul_f32_e32 v105, 0x3fb8aa3b, v106
	v_lshlrev_b64 v[106:107], 11, v[122:123]
	v_lshl_add_u64 v[106:107], s[18:19], 0, v[106:107]
	v_add_f32_e32 v94, 1.0, v94
	v_lshl_add_u64 v[106:107], v[106:107], 0, v[206:207]
	v_rcp_f32_e32 v94, v94
	v_mul_f32_e32 v98, v42, v98
	v_cvt_pk_bf16_f32 v105, v105, v0
	global_store_dwordx4 v[106:107], v[114:117], off
	global_store_dwordx4 v[106:107], v[102:105], off offset:16
	v_lshlrev_b32_e32 v0, 16, v110
	v_mul_f32_e32 v0, v94, v0
	v_add_f32_e32 v102, v98, v98
	v_mul_f32_e32 v102, 0x3fb8aa3b, v102
	v_exp_f32_e32 v102, v102
	v_mul_f32_e32 v94, 0x3fb8aa3b, v98
	v_add_f32_e32 v98, v99, v51
	v_mul_f32_e32 v98, 0xbfb8aa3b, v98
	v_exp_f32_e32 v98, v98
	v_sub_f32_e32 v102, 1.0, v102
	v_max_f32_e32 v102, 0, v102
	v_cmp_gt_f32_e32 vcc, s59, v102
	v_mul_f32_e32 v103, 0x4f800000, v102
	v_add_f32_e32 v98, 1.0, v98
	v_cndmask_b32_e32 v102, v102, v103, vcc
	v_sqrt_f32_e32 v103, v102
	v_rcp_f32_e32 v98, v98
	v_add_f32_e32 v95, v95, v47
	v_mul_f32_e32 v95, 0xbfb8aa3b, v95
	v_add_u32_e32 v104, -1, v103
	v_mul_f32_e32 v98, v43, v98
	v_fma_f32 v105, -v104, v103, v102
	v_add_f32_e32 v99, v98, v98
	v_cmp_ge_f32_e64 s[4:5], 0, v105
	v_add_u32_e32 v105, 1, v103
	v_mul_f32_e32 v99, 0x3fb8aa3b, v99
	v_cndmask_b32_e64 v104, v103, v104, s[4:5]
	v_fma_f32 v103, -v105, v103, v102
	v_exp_f32_e32 v95, v95
	v_exp_f32_e32 v99, v99
	v_cmp_lt_f32_e64 s[4:5], 0, v103
	v_add_f32_e32 v96, v96, v48
	v_add_f32_e32 v95, 1.0, v95
	v_cndmask_b32_e64 v103, v104, v105, s[4:5]
	v_mul_f32_e32 v104, 0x37800000, v103
	v_cndmask_b32_e32 v103, v103, v104, vcc
	v_cmp_class_f32_e32 vcc, v102, v221
	v_sub_f32_e32 v99, 1.0, v99
	v_rcp_f32_e32 v95, v95
	v_cndmask_b32_e32 v102, v103, v102, vcc
	v_max_f32_e32 v99, 0, v99
	v_mul_f32_e32 v0, v102, v0
	v_cmp_gt_f32_e32 vcc, s59, v99
	v_mul_f32_e32 v102, 0x4f800000, v99
	v_cvt_pk_bf16_f32 v94, v94, v0
	v_and_b32_e32 v0, 0xffff0000, v110
	v_cndmask_b32_e32 v99, v99, v102, vcc
	v_sqrt_f32_e32 v102, v99
	v_mul_f32_e32 v0, v95, v0
	v_mul_f32_e32 v95, 0x3fb8aa3b, v98
	v_add_f32_e32 v98, v100, v52
	v_mul_f32_e32 v98, 0xbfb8aa3b, v98
	v_exp_f32_e32 v98, v98
	v_add_u32_e32 v103, -1, v102
	v_fma_f32 v104, -v103, v102, v99
	v_cmp_ge_f32_e64 s[4:5], 0, v104
	v_add_u32_e32 v104, 1, v102
	v_add_f32_e32 v98, 1.0, v98
	v_cndmask_b32_e64 v103, v102, v103, s[4:5]
	v_fma_f32 v102, -v104, v102, v99
	v_cmp_lt_f32_e64 s[4:5], 0, v102
	v_rcp_f32_e32 v98, v98
	v_mul_f32_e32 v96, 0xbfb8aa3b, v96
	v_cndmask_b32_e64 v102, v103, v104, s[4:5]
	v_mul_f32_e32 v103, 0x37800000, v102
	v_cndmask_b32_e32 v102, v102, v103, vcc
	v_cmp_class_f32_e32 vcc, v99, v221
	v_mul_f32_e32 v98, v44, v98
	v_exp_f32_e32 v96, v96
	v_cndmask_b32_e32 v99, v102, v99, vcc
	v_mul_f32_e32 v0, v99, v0
; __device__ __forceinline__ unsigned cvt_pk_bf16(float lo, float hi) { unsigned r; asm volatile("v_cvt_pk_bf16_f32 %0, %1, %2" : "=v"(r) : "v"(lo), "v"(hi)); return r; }
; __device__ __forceinline__ float fast_sigmoid(float x) { return __builtin_amdgcn_rcpf(1.0f + __expf(-x)); }
;     __device__ __forceinline__ void operator()(const f32x4 (&acc)[2][2][4][2], const Unit& u, int wr, int wc, int fr, int fq, PG8_LAS unsigned char* ldsb) const {
;     ...
;                     for (int i = 0; i < 4; ++i) { const int e = n * 4 + i;
;                         const unsigned wd = xw[e >> 1]; const float xc = __uint_as_float((e & 1) ? (wd & 0xffff0000u) : (wd << 16));
;                         const float r = fast_sigmoid(acc[ai][0][m][n][i] + br[e]), ig = fast_sigmoid(acc[ai][1][m][n][i] + bi[e]);
;                         const float la = sp[e] * r;
;                         const float bb = __builtin_sqrtf(fmaxf(1.0f - __expf(2.0f * la), 0.f)) * (ig * xc);
;                         ow[e] = cvt_pk_bf16(la * 1.4426950408889634f, bb); }
	v_add_f32_e32 v99, v98, v98
	v_mul_f32_e32 v99, 0x3fb8aa3b, v99
	v_exp_f32_e32 v99, v99
	v_add_f32_e32 v96, 1.0, v96
	v_rcp_f32_e32 v96, v96
	v_cvt_pk_bf16_f32 v95, v95, v0
	v_sub_f32_e32 v99, 1.0, v99
	v_max_f32_e32 v99, 0, v99
	v_cmp_gt_f32_e32 vcc, s59, v99
	v_mul_f32_e32 v100, 0x4f800000, v99
	v_lshlrev_b32_e32 v0, 16, v111
	v_cndmask_b32_e32 v99, v99, v100, vcc
	v_sqrt_f32_e32 v100, v99
	v_mul_f32_e32 v0, v96, v0
	v_mul_f32_e32 v96, 0x3fb8aa3b, v98
	v_add_f32_e32 v98, v101, v53
	v_mul_f32_e32 v98, 0xbfb8aa3b, v98
	v_exp_f32_e32 v98, v98
	v_add_u32_e32 v102, -1, v100
	v_fma_f32 v103, -v102, v100, v99
	v_cmp_ge_f32_e64 s[4:5], 0, v103
	v_add_u32_e32 v103, 1, v100
	v_add_f32_e32 v98, 1.0, v98
	v_cndmask_b32_e64 v102, v100, v102, s[4:5]
	v_fma_f32 v100, -v103, v100, v99
	v_cmp_lt_f32_e64 s[4:5], 0, v100
	v_rcp_f32_e32 v98, v98
	v_add_f32_e32 v86, v86, v26
	v_cndmask_b32_e64 v100, v102, v103, s[4:5]
	v_mul_f32_e32 v102, 0x37800000, v100
	v_cndmask_b32_e32 v100, v100, v102, vcc
	v_cmp_class_f32_e32 vcc, v99, v221
	v_mul_f32_e32 v98, v45, v98
	v_add_f32_e32 v97, v97, v49
	v_cndmask_b32_e32 v99, v100, v99, vcc
	v_mul_f32_e32 v0, v99, v0
	v_add_f32_e32 v99, v98, v98
	v_mul_f32_e32 v99, 0x3fb8aa3b, v99
	v_exp_f32_e32 v99, v99
	v_mul_f32_e32 v86, 0xbfb8aa3b, v86
	v_mul_f32_e32 v97, 0xbfb8aa3b, v97
	v_exp_f32_e32 v86, v86
	v_sub_f32_e32 v99, 1.0, v99
	v_max_f32_e32 v99, 0, v99
	v_cmp_gt_f32_e32 vcc, s59, v99
	v_mul_f32_e32 v100, 0x4f800000, v99
	v_exp_f32_e32 v97, v97
	v_cndmask_b32_e32 v99, v99, v100, vcc
	v_sqrt_f32_e32 v100, v99
	v_add_f32_e32 v82, v82, v22
	v_mul_f32_e32 v82, 0xbfb8aa3b, v82
	v_add_f32_e32 v86, 1.0, v86
	v_add_u32_e32 v101, -1, v100
	v_fma_f32 v102, -v101, v100, v99
	v_cmp_ge_f32_e64 s[4:5], 0, v102
	v_add_u32_e32 v102, 1, v100
	v_exp_f32_e32 v82, v82
	v_add_f32_e32 v97, 1.0, v97
	v_cndmask_b32_e64 v101, v100, v101, s[4:5]
	v_fma_f32 v100, -v102, v100, v99
	v_rcp_f32_e32 v86, v86
	v_rcp_f32_e32 v97, v97
	v_cmp_lt_f32_e64 s[4:5], 0, v100
	v_add_f32_e32 v82, 1.0, v82
	v_cvt_pk_bf16_f32 v96, v96, v0
	v_and_b32_e32 v0, 0xffff0000, v111
	v_cndmask_b32_e64 v100, v101, v102, s[4:5]
	v_mul_f32_e32 v101, 0x37800000, v100
	v_cndmask_b32_e32 v100, v100, v101, vcc
	v_cmp_class_f32_e32 vcc, v99, v221
	v_rcp_f32_e32 v82, v82
	v_mul_f32_e32 v86, v18, v86
	v_cndmask_b32_e32 v99, v100, v99, vcc
	v_mul_f32_e32 v0, v97, v0
	v_mul_f32_e32 v97, 0x3fb8aa3b, v98
	v_add_f32_e32 v98, v86, v86
	v_mul_f32_e32 v0, v99, v0
	v_mul_f32_e32 v98, 0x3fb8aa3b, v98
	v_cvt_pk_bf16_f32 v97, v97, v0
	v_lshlrev_b32_e32 v0, 16, v112
	v_exp_f32_e32 v98, v98
	v_mul_f32_e32 v0, v82, v0
	v_mul_f32_e32 v82, 0x3fb8aa3b, v86
	v_add_f32_e32 v86, v87, v27
	v_mul_f32_e32 v86, 0xbfb8aa3b, v86
	v_exp_f32_e32 v86, v86
	v_sub_f32_e32 v98, 1.0, v98
	v_max_f32_e32 v98, 0, v98
	v_cmp_gt_f32_e32 vcc, s59, v98
	v_mul_f32_e32 v99, 0x4f800000, v98
	v_add_f32_e32 v86, 1.0, v86
	v_cndmask_b32_e32 v98, v98, v99, vcc
	v_sqrt_f32_e32 v99, v98
	v_rcp_f32_e32 v86, v86
	v_add_f32_e32 v83, v83, v23
	v_mul_f32_e32 v83, 0xbfb8aa3b, v83
	v_add_u32_e32 v100, -1, v99
	v_mul_f32_e32 v86, v19, v86
	v_fma_f32 v101, -v100, v99, v98
	v_add_f32_e32 v87, v86, v86
	v_cmp_ge_f32_e64 s[4:5], 0, v101
	v_add_u32_e32 v101, 1, v99
	v_mul_f32_e32 v87, 0x3fb8aa3b, v87
	v_cndmask_b32_e64 v100, v99, v100, s[4:5]
	v_fma_f32 v99, -v101, v99, v98
	v_exp_f32_e32 v83, v83
	v_exp_f32_e32 v87, v87
	v_cmp_lt_f32_e64 s[4:5], 0, v99
	v_add_f32_e32 v84, v84, v24
	v_add_f32_e32 v83, 1.0, v83
	v_cndmask_b32_e64 v99, v100, v101, s[4:5]
	v_mul_f32_e32 v100, 0x37800000, v99
	v_cndmask_b32_e32 v99, v99, v100, vcc
	v_cmp_class_f32_e32 vcc, v98, v221
	v_sub_f32_e32 v87, 1.0, v87
	v_rcp_f32_e32 v83, v83
	v_cndmask_b32_e32 v98, v99, v98, vcc
	v_max_f32_e32 v87, 0, v87
	v_mul_f32_e32 v0, v98, v0
	v_cmp_gt_f32_e32 vcc, s59, v87
	v_mul_f32_e32 v98, 0x4f800000, v87
	v_cvt_pk_bf16_f32 v82, v82, v0
	v_and_b32_e32 v0, 0xffff0000, v112
	v_cndmask_b32_e32 v87, v87, v98, vcc
	v_sqrt_f32_e32 v98, v87
	v_mul_f32_e32 v0, v83, v0
	v_mul_f32_e32 v83, 0x3fb8aa3b, v86
	v_add_f32_e32 v86, v88, v28
	v_mul_f32_e32 v86, 0xbfb8aa3b, v86
	v_exp_f32_e32 v86, v86
	v_add_u32_e32 v99, -1, v98
	v_fma_f32 v100, -v99, v98, v87
	v_cmp_ge_f32_e64 s[4:5], 0, v100
	v_add_u32_e32 v100, 1, v98
	v_add_f32_e32 v86, 1.0, v86
	v_cndmask_b32_e64 v99, v98, v99, s[4:5]
	v_fma_f32 v98, -v100, v98, v87
	v_cmp_lt_f32_e64 s[4:5], 0, v98
	v_rcp_f32_e32 v86, v86
	v_mul_f32_e32 v84, 0xbfb8aa3b, v84
	v_cndmask_b32_e64 v98, v99, v100, s[4:5]
	v_mul_f32_e32 v99, 0x37800000, v98
	v_cndmask_b32_e32 v98, v98, v99, vcc
	v_cmp_class_f32_e32 vcc, v87, v221
	v_mul_f32_e32 v86, v20, v86
	v_exp_f32_e32 v84, v84
	v_cndmask_b32_e32 v87, v98, v87, vcc
	v_mul_f32_e32 v0, v87, v0
	v_add_f32_e32 v87, v86, v86
	v_mul_f32_e32 v87, 0x3fb8aa3b, v87
	v_exp_f32_e32 v87, v87
	v_add_f32_e32 v84, 1.0, v84
	v_rcp_f32_e32 v84, v84
	v_cvt_pk_bf16_f32 v83, v83, v0
	v_sub_f32_e32 v87, 1.0, v87
	v_max_f32_e32 v87, 0, v87
	v_cmp_gt_f32_e32 vcc, s59, v87
	v_mul_f32_e32 v88, 0x4f800000, v87
	v_lshlrev_b32_e32 v0, 16, v113
	v_cndmask_b32_e32 v87, v87, v88, vcc
	v_sqrt_f32_e32 v88, v87
	v_mul_f32_e32 v0, v84, v0
	v_mul_f32_e32 v84, 0x3fb8aa3b, v86
	v_add_f32_e32 v86, v89, v29
	v_mul_f32_e32 v86, 0xbfb8aa3b, v86
	v_exp_f32_e32 v86, v86
	v_add_u32_e32 v98, -1, v88
	v_fma_f32 v99, -v98, v88, v87
	v_cmp_ge_f32_e64 s[4:5], 0, v99
	v_add_u32_e32 v99, 1, v88
	v_add_f32_e32 v86, 1.0, v86
	v_cndmask_b32_e64 v98, v88, v98, s[4:5]
	v_fma_f32 v88, -v99, v88, v87
	v_cmp_lt_f32_e64 s[4:5], 0, v88
	v_rcp_f32_e32 v86, v86
	v_add_f32_e32 v85, v85, v25
	v_cndmask_b32_e64 v88, v98, v99, s[4:5]
	v_mul_f32_e32 v98, 0x37800000, v88
; __device__ __forceinline__ unsigned cvt_pk_bf16(float lo, float hi) { unsigned r; asm volatile("v_cvt_pk_bf16_f32 %0, %1, %2" : "=v"(r) : "v"(lo), "v"(hi)); return r; }
; __device__ __forceinline__ float fast_sigmoid(float x) { return __builtin_amdgcn_rcpf(1.0f + __expf(-x)); }
;     __device__ __forceinline__ void operator()(const f32x4 (&acc)[2][2][4][2], const Unit& u, int wr, int wc, int fr, int fq, PG8_LAS unsigned char* ldsb) const {
;     ...
;             for (int m = 0; m < 4; ++m) {
;                 const size_t ro = (size_t)(row0 + ai * HALF + m * 16) * 512 + ch0;
;                 const u32x4 xw = xwv[ai][m];
;                 unsigned ow[8];
; #pragma unroll
;                 for (int n = 0; n < 2; ++n)
; #pragma unroll
;                     for (int i = 0; i < 4; ++i) { const int e = n * 4 + i;
;                         const unsigned wd = xw[e >> 1]; const float xc = __uint_as_float((e & 1) ? (wd & 0xffff0000u) : (wd << 16));
;                         const float r = fast_sigmoid(acc[ai][0][m][n][i] + br[e]), ig = fast_sigmoid(acc[ai][1][m][n][i] + bi[e]);
;                         const float la = sp[e] * r;
;                         const float bb = __builtin_sqrtf(fmaxf(1.0f - __expf(2.0f * la), 0.f)) * (ig * xc);
;                         ow[e] = cvt_pk_bf16(la * 1.4426950408889634f, bb); }
;                 u32x4 w0, w1; w0.x = ow[0]; w0.y = ow[1]; w0.z = ow[2]; w0.w = ow[3]; w1.x = ow[4]; w1.y = ow[5]; w1.z = ow[6]; w1.w = ow[7];
;                 *(u32x4*)(AB + ro) = w0; *(u32x4*)(AB + ro + 4) = w1;
	v_cndmask_b32_e32 v88, v88, v98, vcc
	v_cmp_class_f32_e32 vcc, v87, v221
	v_mul_f32_e32 v86, v21, v86
	v_add_f32_e32 v78, v78, v50
	v_cndmask_b32_e32 v87, v88, v87, vcc
	v_mul_f32_e32 v0, v87, v0
	v_add_f32_e32 v87, v86, v86
	v_mul_f32_e32 v87, 0x3fb8aa3b, v87
	v_exp_f32_e32 v87, v87
	v_mul_f32_e32 v85, 0xbfb8aa3b, v85
	v_mul_f32_e32 v78, 0xbfb8aa3b, v78
	v_exp_f32_e32 v85, v85
	v_sub_f32_e32 v87, 1.0, v87
	v_max_f32_e32 v87, 0, v87
	v_cmp_gt_f32_e32 vcc, s59, v87
	v_mul_f32_e32 v88, 0x4f800000, v87
	v_exp_f32_e32 v78, v78
	v_cndmask_b32_e32 v87, v87, v88, vcc
	v_sqrt_f32_e32 v88, v87
	v_add_f32_e32 v74, v74, v46
	v_mul_f32_e32 v74, 0xbfb8aa3b, v74
	v_add_f32_e32 v85, 1.0, v85
	v_add_u32_e32 v89, -1, v88
	v_fma_f32 v98, -v89, v88, v87
	v_cmp_ge_f32_e64 s[4:5], 0, v98
	v_add_u32_e32 v98, 1, v88
	v_add_f32_e32 v78, 1.0, v78
	v_cndmask_b32_e64 v89, v88, v89, s[4:5]
	v_fma_f32 v88, -v98, v88, v87
	v_cmp_lt_f32_e64 s[4:5], 0, v88
	v_exp_f32_e32 v74, v74
	v_rcp_f32_e32 v85, v85
	v_cndmask_b32_e64 v88, v89, v98, s[4:5]
	v_rcp_f32_e32 v78, v78
	v_mul_f32_e32 v89, 0x37800000, v88
	v_cndmask_b32_e32 v88, v88, v89, vcc
	v_cmp_class_f32_e32 vcc, v87, v221
	v_cvt_pk_bf16_f32 v84, v84, v0
	v_and_b32_e32 v0, 0xffff0000, v113
	v_add_f32_e32 v74, 1.0, v74
	v_cndmask_b32_e32 v87, v88, v87, vcc
	v_add_co_u32_e32 v88, vcc, s35, v166
	v_mul_f32_e32 v0, v85, v0
	v_mul_f32_e32 v85, 0x3fb8aa3b, v86
	v_addc_co_u32_e32 v89, vcc, 0, v167, vcc
	v_rcp_f32_e32 v74, v74
	v_mul_f32_e32 v78, v42, v78
	v_mul_f32_e32 v0, v0, v87
	v_cvt_pk_bf16_f32 v85, v85, v0
	v_lshl_add_u64 v[86:87], v[166:167], 0, s[72:73]
	global_store_dwordx4 v[88:89], v[94:97], off
	global_store_dwordx4 v[86:87], v[82:85], off offset:16
	v_lshlrev_b32_e32 v0, 16, v90
	v_mul_f32_e32 v0, v74, v0
	v_add_f32_e32 v82, v78, v78
	v_mul_f32_e32 v82, 0x3fb8aa3b, v82
	v_exp_f32_e32 v82, v82
	v_mul_f32_e32 v74, 0x3fb8aa3b, v78
	v_add_f32_e32 v78, v79, v51
	v_mul_f32_e32 v78, 0xbfb8aa3b, v78
	v_exp_f32_e32 v78, v78
	v_sub_f32_e32 v82, 1.0, v82
	v_max_f32_e32 v82, 0, v82
	v_cmp_gt_f32_e32 vcc, s59, v82
	v_mul_f32_e32 v83, 0x4f800000, v82
	v_add_f32_e32 v78, 1.0, v78
	v_cndmask_b32_e32 v82, v82, v83, vcc
	v_sqrt_f32_e32 v83, v82
	v_rcp_f32_e32 v78, v78
	v_add_f32_e32 v75, v75, v47
	v_mul_f32_e32 v75, 0xbfb8aa3b, v75
	v_add_u32_e32 v84, -1, v83
	v_mul_f32_e32 v78, v43, v78
	v_fma_f32 v85, -v84, v83, v82
	v_add_f32_e32 v79, v78, v78
	v_cmp_ge_f32_e64 s[4:5], 0, v85
	v_add_u32_e32 v85, 1, v83
	v_mul_f32_e32 v79, 0x3fb8aa3b, v79
	v_cndmask_b32_e64 v84, v83, v84, s[4:5]
	v_fma_f32 v83, -v85, v83, v82
	v_exp_f32_e32 v75, v75
	v_exp_f32_e32 v79, v79
	v_cmp_lt_f32_e64 s[4:5], 0, v83
	v_add_f32_e32 v76, v76, v48
	v_add_f32_e32 v75, 1.0, v75
	v_cndmask_b32_e64 v83, v84, v85, s[4:5]
	v_mul_f32_e32 v84, 0x37800000, v83
	v_cndmask_b32_e32 v83, v83, v84, vcc
	v_cmp_class_f32_e32 vcc, v82, v221
	v_sub_f32_e32 v79, 1.0, v79
	v_rcp_f32_e32 v75, v75
	v_cndmask_b32_e32 v82, v83, v82, vcc
	v_max_f32_e32 v79, 0, v79
	v_mul_f32_e32 v0, v82, v0
	v_cmp_gt_f32_e32 vcc, s59, v79
	v_mul_f32_e32 v82, 0x4f800000, v79
	v_cvt_pk_bf16_f32 v74, v74, v0
	v_and_b32_e32 v0, 0xffff0000, v90
	v_cndmask_b32_e32 v79, v79, v82, vcc
	v_sqrt_f32_e32 v82, v79
	v_mul_f32_e32 v0, v75, v0
	v_mul_f32_e32 v75, 0x3fb8aa3b, v78
	v_add_f32_e32 v78, v80, v52
	v_mul_f32_e32 v78, 0xbfb8aa3b, v78
	v_exp_f32_e32 v78, v78
	v_add_u32_e32 v83, -1, v82
	v_fma_f32 v84, -v83, v82, v79
	v_cmp_ge_f32_e64 s[4:5], 0, v84
	v_add_u32_e32 v84, 1, v82
	v_add_f32_e32 v78, 1.0, v78
	v_cndmask_b32_e64 v83, v82, v83, s[4:5]
	v_fma_f32 v82, -v84, v82, v79
	v_cmp_lt_f32_e64 s[4:5], 0, v82
	v_rcp_f32_e32 v78, v78
	v_mul_f32_e32 v76, 0xbfb8aa3b, v76
	v_cndmask_b32_e64 v82, v83, v84, s[4:5]
	v_mul_f32_e32 v83, 0x37800000, v82
	v_cndmask_b32_e32 v82, v82, v83, vcc
	v_cmp_class_f32_e32 vcc, v79, v221
	v_mul_f32_e32 v78, v44, v78
	v_exp_f32_e32 v76, v76
	v_cndmask_b32_e32 v79, v82, v79, vcc
	v_mul_f32_e32 v0, v79, v0
	v_add_f32_e32 v79, v78, v78
	v_mul_f32_e32 v79, 0x3fb8aa3b, v79
	v_exp_f32_e32 v79, v79
	v_add_f32_e32 v76, 1.0, v76
	v_rcp_f32_e32 v76, v76
	v_cvt_pk_bf16_f32 v75, v75, v0
	v_sub_f32_e32 v79, 1.0, v79
	v_max_f32_e32 v79, 0, v79
	v_cmp_gt_f32_e32 vcc, s59, v79
	v_mul_f32_e32 v80, 0x4f800000, v79
	v_lshlrev_b32_e32 v0, 16, v91
	v_cndmask_b32_e32 v79, v79, v80, vcc
	v_sqrt_f32_e32 v80, v79
	v_mul_f32_e32 v0, v76, v0
	v_mul_f32_e32 v76, 0x3fb8aa3b, v78
	v_add_f32_e32 v78, v81, v53
	v_mul_f32_e32 v78, 0xbfb8aa3b, v78
	v_exp_f32_e32 v78, v78
	v_add_u32_e32 v82, -1, v80
	v_fma_f32 v83, -v82, v80, v79
	v_cmp_ge_f32_e64 s[4:5], 0, v83
	v_add_u32_e32 v83, 1, v80
	v_add_f32_e32 v78, 1.0, v78
	v_cndmask_b32_e64 v82, v80, v82, s[4:5]
	v_fma_f32 v80, -v83, v80, v79
	v_cmp_lt_f32_e64 s[4:5], 0, v80
	v_rcp_f32_e32 v78, v78
	v_add_f32_e32 v66, v66, v26
	v_cndmask_b32_e64 v80, v82, v83, s[4:5]
	v_mul_f32_e32 v82, 0x37800000, v80
	v_cndmask_b32_e32 v80, v80, v82, vcc
	v_cmp_class_f32_e32 vcc, v79, v221
	v_mul_f32_e32 v78, v45, v78
	v_add_f32_e32 v77, v77, v49
	v_cndmask_b32_e32 v79, v80, v79, vcc
	v_mul_f32_e32 v0, v79, v0
	v_add_f32_e32 v79, v78, v78
	v_mul_f32_e32 v79, 0x3fb8aa3b, v79
	v_exp_f32_e32 v79, v79
	v_mul_f32_e32 v66, 0xbfb8aa3b, v66
	v_mul_f32_e32 v77, 0xbfb8aa3b, v77
	v_exp_f32_e32 v66, v66
	v_sub_f32_e32 v79, 1.0, v79
	v_max_f32_e32 v79, 0, v79
	v_cmp_gt_f32_e32 vcc, s59, v79
	v_mul_f32_e32 v80, 0x4f800000, v79
	v_exp_f32_e32 v77, v77
	v_cndmask_b32_e32 v79, v79, v80, vcc
	v_sqrt_f32_e32 v80, v79
	v_add_f32_e32 v62, v62, v22
	v_mul_f32_e32 v62, 0xbfb8aa3b, v62
	v_add_f32_e32 v66, 1.0, v66
	v_add_u32_e32 v81, -1, v80
	v_fma_f32 v82, -v81, v80, v79
	v_cmp_ge_f32_e64 s[4:5], 0, v82
; __device__ __forceinline__ unsigned cvt_pk_bf16(float lo, float hi) { unsigned r; asm volatile("v_cvt_pk_bf16_f32 %0, %1, %2" : "=v"(r) : "v"(lo), "v"(hi)); return r; }
; __device__ __forceinline__ float fast_sigmoid(float x) { return __builtin_amdgcn_rcpf(1.0f + __expf(-x)); }
;     __device__ __forceinline__ void operator()(const f32x4 (&acc)[2][2][4][2], const Unit& u, int wr, int wc, int fr, int fq, PG8_LAS unsigned char* ldsb) const {
;     ...
;             for (int m = 0; m < 4; ++m) {
;                 const size_t ro = (size_t)(row0 + ai * HALF + m * 16) * 512 + ch0;
;                 const u32x4 xw = xwv[ai][m];
;                 unsigned ow[8];
; #pragma unroll
;                 for (int n = 0; n < 2; ++n)
; #pragma unroll
;                     for (int i = 0; i < 4; ++i) { const int e = n * 4 + i;
;                         const unsigned wd = xw[e >> 1]; const float xc = __uint_as_float((e & 1) ? (wd & 0xffff0000u) : (wd << 16));
;                         const float r = fast_sigmoid(acc[ai][0][m][n][i] + br[e]), ig = fast_sigmoid(acc[ai][1][m][n][i] + bi[e]);
;                         const float la = sp[e] * r;
;                         const float bb = __builtin_sqrtf(fmaxf(1.0f - __expf(2.0f * la), 0.f)) * (ig * xc);
;                         ow[e] = cvt_pk_bf16(la * 1.4426950408889634f, bb); }
;                 u32x4 w0, w1; w0.x = ow[0]; w0.y = ow[1]; w0.z = ow[2]; w0.w = ow[3]; w1.x = ow[4]; w1.y = ow[5]; w1.z = ow[6]; w1.w = ow[7];
;                 *(u32x4*)(AB + ro) = w0; *(u32x4*)(AB + ro + 4) = w1;
	v_add_u32_e32 v82, 1, v80
	v_exp_f32_e32 v62, v62
	v_add_f32_e32 v77, 1.0, v77
	v_cndmask_b32_e64 v81, v80, v81, s[4:5]
	v_fma_f32 v80, -v82, v80, v79
	v_rcp_f32_e32 v66, v66
	v_rcp_f32_e32 v77, v77
	v_cmp_lt_f32_e64 s[4:5], 0, v80
	v_add_f32_e32 v62, 1.0, v62
	v_cvt_pk_bf16_f32 v76, v76, v0
	v_and_b32_e32 v0, 0xffff0000, v91
	v_cndmask_b32_e64 v80, v81, v82, s[4:5]
	v_mul_f32_e32 v81, 0x37800000, v80
	v_cndmask_b32_e32 v80, v80, v81, vcc
	v_cmp_class_f32_e32 vcc, v79, v221
	v_rcp_f32_e32 v62, v62
	v_mul_f32_e32 v66, v18, v66
	v_cndmask_b32_e32 v79, v80, v79, vcc
	v_mul_f32_e32 v0, v77, v0
	v_mul_f32_e32 v77, 0x3fb8aa3b, v78
	v_add_f32_e32 v78, v66, v66
	v_mul_f32_e32 v0, v79, v0
	v_mul_f32_e32 v78, 0x3fb8aa3b, v78
	v_cvt_pk_bf16_f32 v77, v77, v0
	v_lshlrev_b32_e32 v0, 16, v92
	v_exp_f32_e32 v78, v78
	v_mul_f32_e32 v0, v62, v0
	v_mul_f32_e32 v62, 0x3fb8aa3b, v66
	v_add_f32_e32 v66, v67, v27
	v_mul_f32_e32 v66, 0xbfb8aa3b, v66
	v_exp_f32_e32 v66, v66
	v_sub_f32_e32 v78, 1.0, v78
	v_max_f32_e32 v78, 0, v78
	v_cmp_gt_f32_e32 vcc, s59, v78
	v_mul_f32_e32 v79, 0x4f800000, v78
	v_add_f32_e32 v66, 1.0, v66
	v_cndmask_b32_e32 v78, v78, v79, vcc
	v_sqrt_f32_e32 v79, v78
	v_rcp_f32_e32 v66, v66
	v_add_f32_e32 v63, v63, v23
	v_mul_f32_e32 v63, 0xbfb8aa3b, v63
	v_add_u32_e32 v80, -1, v79
	v_mul_f32_e32 v66, v19, v66
	v_fma_f32 v81, -v80, v79, v78
	v_add_f32_e32 v67, v66, v66
	v_cmp_ge_f32_e64 s[4:5], 0, v81
	v_add_u32_e32 v81, 1, v79
	v_mul_f32_e32 v67, 0x3fb8aa3b, v67
	v_cndmask_b32_e64 v80, v79, v80, s[4:5]
	v_fma_f32 v79, -v81, v79, v78
	v_exp_f32_e32 v63, v63
	v_exp_f32_e32 v67, v67
	v_cmp_lt_f32_e64 s[4:5], 0, v79
	v_add_f32_e32 v64, v64, v24
	v_add_f32_e32 v63, 1.0, v63
	v_cndmask_b32_e64 v79, v80, v81, s[4:5]
	v_mul_f32_e32 v80, 0x37800000, v79
	v_cndmask_b32_e32 v79, v79, v80, vcc
	v_cmp_class_f32_e32 vcc, v78, v221
	v_sub_f32_e32 v67, 1.0, v67
	v_rcp_f32_e32 v63, v63
	v_cndmask_b32_e32 v78, v79, v78, vcc
	v_max_f32_e32 v67, 0, v67
	v_mul_f32_e32 v0, v78, v0
	v_cmp_gt_f32_e32 vcc, s59, v67
	v_mul_f32_e32 v78, 0x4f800000, v67
	v_cvt_pk_bf16_f32 v62, v62, v0
	v_and_b32_e32 v0, 0xffff0000, v92
	v_cndmask_b32_e32 v67, v67, v78, vcc
	v_sqrt_f32_e32 v78, v67
	v_mul_f32_e32 v0, v63, v0
	v_mul_f32_e32 v63, 0x3fb8aa3b, v66
	v_add_f32_e32 v66, v68, v28
	v_mul_f32_e32 v66, 0xbfb8aa3b, v66
	v_exp_f32_e32 v66, v66
	v_add_u32_e32 v79, -1, v78
	v_fma_f32 v80, -v79, v78, v67
	v_cmp_ge_f32_e64 s[4:5], 0, v80
	v_add_u32_e32 v80, 1, v78
	v_add_f32_e32 v66, 1.0, v66
	v_cndmask_b32_e64 v79, v78, v79, s[4:5]
	v_fma_f32 v78, -v80, v78, v67
	v_cmp_lt_f32_e64 s[4:5], 0, v78
	v_rcp_f32_e32 v66, v66
	v_mul_f32_e32 v64, 0xbfb8aa3b, v64
	v_cndmask_b32_e64 v78, v79, v80, s[4:5]
	v_mul_f32_e32 v79, 0x37800000, v78
	v_cndmask_b32_e32 v78, v78, v79, vcc
	v_cmp_class_f32_e32 vcc, v67, v221
	v_mul_f32_e32 v66, v20, v66
	v_exp_f32_e32 v64, v64
	v_cndmask_b32_e32 v67, v78, v67, vcc
	v_mul_f32_e32 v0, v67, v0
	v_add_f32_e32 v67, v66, v66
	v_mul_f32_e32 v67, 0x3fb8aa3b, v67
	v_exp_f32_e32 v67, v67
	v_add_f32_e32 v64, 1.0, v64
	v_rcp_f32_e32 v64, v64
	v_cvt_pk_bf16_f32 v63, v63, v0
	v_sub_f32_e32 v67, 1.0, v67
	v_max_f32_e32 v67, 0, v67
	v_cmp_gt_f32_e32 vcc, s59, v67
	v_mul_f32_e32 v68, 0x4f800000, v67
	v_lshlrev_b32_e32 v0, 16, v93
	v_cndmask_b32_e32 v67, v67, v68, vcc
	v_sqrt_f32_e32 v68, v67
	v_mul_f32_e32 v0, v64, v0
	v_mul_f32_e32 v64, 0x3fb8aa3b, v66
	v_add_f32_e32 v66, v69, v29
	v_mul_f32_e32 v66, 0xbfb8aa3b, v66
	v_exp_f32_e32 v66, v66
	v_add_u32_e32 v78, -1, v68
	v_fma_f32 v79, -v78, v68, v67
	v_cmp_ge_f32_e64 s[4:5], 0, v79
	v_add_u32_e32 v79, 1, v68
	v_add_f32_e32 v66, 1.0, v66
	v_cndmask_b32_e64 v78, v68, v78, s[4:5]
	v_fma_f32 v68, -v79, v68, v67
	v_cmp_lt_f32_e64 s[4:5], 0, v68
	v_rcp_f32_e32 v66, v66
	v_add_f32_e32 v65, v65, v25
	v_cndmask_b32_e64 v68, v78, v79, s[4:5]
	v_mul_f32_e32 v78, 0x37800000, v68
	v_cndmask_b32_e32 v68, v68, v78, vcc
	v_cmp_class_f32_e32 vcc, v67, v221
	v_mul_f32_e32 v66, v21, v66
	v_add_f32_e32 v58, v58, v50
	v_cndmask_b32_e32 v67, v68, v67, vcc
	v_mul_f32_e32 v0, v67, v0
	v_add_f32_e32 v67, v66, v66
	v_mul_f32_e32 v67, 0x3fb8aa3b, v67
	v_exp_f32_e32 v67, v67
	v_mul_f32_e32 v65, 0xbfb8aa3b, v65
	v_mul_f32_e32 v58, 0xbfb8aa3b, v58
	v_exp_f32_e32 v65, v65
	v_sub_f32_e32 v67, 1.0, v67
	v_max_f32_e32 v67, 0, v67
	v_cmp_gt_f32_e32 vcc, s59, v67
	v_mul_f32_e32 v68, 0x4f800000, v67
	v_exp_f32_e32 v58, v58
	v_cndmask_b32_e32 v67, v67, v68, vcc
	v_sqrt_f32_e32 v68, v67
	v_add_f32_e32 v54, v54, v46
	v_mul_f32_e32 v54, 0xbfb8aa3b, v54
	v_add_f32_e32 v65, 1.0, v65
	v_add_u32_e32 v69, -1, v68
	v_fma_f32 v78, -v69, v68, v67
	v_cmp_ge_f32_e64 s[4:5], 0, v78
	v_add_u32_e32 v78, 1, v68
	v_add_f32_e32 v58, 1.0, v58
	v_cndmask_b32_e64 v69, v68, v69, s[4:5]
	v_fma_f32 v68, -v78, v68, v67
	v_cmp_lt_f32_e64 s[4:5], 0, v68
	v_exp_f32_e32 v54, v54
	v_rcp_f32_e32 v65, v65
	v_cndmask_b32_e64 v68, v69, v78, s[4:5]
	v_rcp_f32_e32 v58, v58
	v_mul_f32_e32 v69, 0x37800000, v68
	v_cndmask_b32_e32 v68, v68, v69, vcc
	v_cmp_class_f32_e32 vcc, v67, v221
	v_cvt_pk_bf16_f32 v64, v64, v0
	v_and_b32_e32 v0, 0xffff0000, v93
	v_add_f32_e32 v54, 1.0, v54
	v_cndmask_b32_e32 v67, v68, v67, vcc
	v_add_co_u32_e32 v68, vcc, s1, v166
	v_mul_f32_e32 v0, v65, v0
	v_mul_f32_e32 v65, 0x3fb8aa3b, v66
	s_mov_b64 s[4:5], 0x48000
	v_addc_co_u32_e32 v69, vcc, 0, v167, vcc
	v_rcp_f32_e32 v54, v54
	v_mul_f32_e32 v58, v42, v58
	v_mul_f32_e32 v0, v0, v67
	v_cvt_pk_bf16_f32 v65, v65, v0
	v_lshl_add_u64 v[66:67], v[166:167], 0, s[4:5]
	global_store_dwordx4 v[68:69], v[74:77], off
	global_store_dwordx4 v[66:67], v[62:65], off offset:16
	v_lshlrev_b32_e32 v0, 16, v70
	v_mul_f32_e32 v0, v54, v0
; __device__ __forceinline__ unsigned cvt_pk_bf16(float lo, float hi) { unsigned r; asm volatile("v_cvt_pk_bf16_f32 %0, %1, %2" : "=v"(r) : "v"(lo), "v"(hi)); return r; }
; __device__ __forceinline__ float fast_sigmoid(float x) { return __builtin_amdgcn_rcpf(1.0f + __expf(-x)); }
;     __device__ __forceinline__ void operator()(const f32x4 (&acc)[2][2][4][2], const Unit& u, int wr, int wc, int fr, int fq, PG8_LAS unsigned char* ldsb) const {
;     ...
;                     for (int i = 0; i < 4; ++i) { const int e = n * 4 + i;
;                         const unsigned wd = xw[e >> 1]; const float xc = __uint_as_float((e & 1) ? (wd & 0xffff0000u) : (wd << 16));
;                         const float r = fast_sigmoid(acc[ai][0][m][n][i] + br[e]), ig = fast_sigmoid(acc[ai][1][m][n][i] + bi[e]);
;                         const float la = sp[e] * r;
;                         const float bb = __builtin_sqrtf(fmaxf(1.0f - __expf(2.0f * la), 0.f)) * (ig * xc);
;                         ow[e] = cvt_pk_bf16(la * 1.4426950408889634f, bb); }
	v_add_f32_e32 v62, v58, v58
	v_mul_f32_e32 v62, 0x3fb8aa3b, v62
	v_exp_f32_e32 v62, v62
	v_mul_f32_e32 v54, 0x3fb8aa3b, v58
	v_add_f32_e32 v58, v59, v51
	v_mul_f32_e32 v58, 0xbfb8aa3b, v58
	v_exp_f32_e32 v58, v58
	v_sub_f32_e32 v62, 1.0, v62
	v_max_f32_e32 v62, 0, v62
	v_cmp_gt_f32_e32 vcc, s59, v62
	v_mul_f32_e32 v63, 0x4f800000, v62
	v_add_f32_e32 v58, 1.0, v58
	v_cndmask_b32_e32 v62, v62, v63, vcc
	v_sqrt_f32_e32 v63, v62
	v_rcp_f32_e32 v58, v58
	v_add_f32_e32 v55, v55, v47
	v_mul_f32_e32 v55, 0xbfb8aa3b, v55
	v_add_u32_e32 v64, -1, v63
	v_mul_f32_e32 v58, v43, v58
	v_fma_f32 v65, -v64, v63, v62
	v_add_f32_e32 v59, v58, v58
	v_cmp_ge_f32_e64 s[4:5], 0, v65
	v_add_u32_e32 v65, 1, v63
	v_mul_f32_e32 v59, 0x3fb8aa3b, v59
	v_cndmask_b32_e64 v64, v63, v64, s[4:5]
	v_fma_f32 v63, -v65, v63, v62
	v_exp_f32_e32 v55, v55
	v_exp_f32_e32 v59, v59
	v_cmp_lt_f32_e64 s[4:5], 0, v63
	v_add_f32_e32 v56, v56, v48
	v_add_f32_e32 v55, 1.0, v55
	v_cndmask_b32_e64 v63, v64, v65, s[4:5]
	v_mul_f32_e32 v64, 0x37800000, v63
	v_cndmask_b32_e32 v63, v63, v64, vcc
	v_cmp_class_f32_e32 vcc, v62, v221
	v_sub_f32_e32 v59, 1.0, v59
	v_rcp_f32_e32 v55, v55
	v_cndmask_b32_e32 v62, v63, v62, vcc
	v_max_f32_e32 v59, 0, v59
	v_mul_f32_e32 v0, v62, v0
	v_cmp_gt_f32_e32 vcc, s59, v59
	v_mul_f32_e32 v62, 0x4f800000, v59
	v_cvt_pk_bf16_f32 v54, v54, v0
	v_and_b32_e32 v0, 0xffff0000, v70
	v_cndmask_b32_e32 v59, v59, v62, vcc
	v_sqrt_f32_e32 v62, v59
	v_mul_f32_e32 v0, v55, v0
	v_mul_f32_e32 v55, 0x3fb8aa3b, v58
	v_add_f32_e32 v58, v60, v52
	v_mul_f32_e32 v58, 0xbfb8aa3b, v58
	v_exp_f32_e32 v58, v58
	v_add_u32_e32 v63, -1, v62
	v_fma_f32 v64, -v63, v62, v59
	v_cmp_ge_f32_e64 s[4:5], 0, v64
	v_add_u32_e32 v64, 1, v62
	v_add_f32_e32 v58, 1.0, v58
	v_cndmask_b32_e64 v63, v62, v63, s[4:5]
	v_fma_f32 v62, -v64, v62, v59
	v_cmp_lt_f32_e64 s[4:5], 0, v62
	v_rcp_f32_e32 v58, v58
	v_mul_f32_e32 v56, 0xbfb8aa3b, v56
	v_cndmask_b32_e64 v62, v63, v64, s[4:5]
	v_mul_f32_e32 v63, 0x37800000, v62
	v_cndmask_b32_e32 v62, v62, v63, vcc
	v_cmp_class_f32_e32 vcc, v59, v221
	v_mul_f32_e32 v58, v44, v58
	v_exp_f32_e32 v56, v56
	v_cndmask_b32_e32 v59, v62, v59, vcc
	v_mul_f32_e32 v0, v59, v0
	v_add_f32_e32 v59, v58, v58
	v_mul_f32_e32 v59, 0x3fb8aa3b, v59
	v_exp_f32_e32 v59, v59
	v_add_f32_e32 v56, 1.0, v56
	v_rcp_f32_e32 v56, v56
	v_cvt_pk_bf16_f32 v55, v55, v0
	v_sub_f32_e32 v59, 1.0, v59
	v_max_f32_e32 v59, 0, v59
	v_cmp_gt_f32_e32 vcc, s59, v59
	v_mul_f32_e32 v60, 0x4f800000, v59
	v_lshlrev_b32_e32 v0, 16, v71
	v_cndmask_b32_e32 v59, v59, v60, vcc
	v_sqrt_f32_e32 v60, v59
	v_mul_f32_e32 v0, v56, v0
	v_mul_f32_e32 v56, 0x3fb8aa3b, v58
	v_add_f32_e32 v58, v61, v53
	v_mul_f32_e32 v58, 0xbfb8aa3b, v58
	v_exp_f32_e32 v58, v58
	v_add_u32_e32 v62, -1, v60
	v_fma_f32 v63, -v62, v60, v59
	v_cmp_ge_f32_e64 s[4:5], 0, v63
	v_add_u32_e32 v63, 1, v60
	v_add_f32_e32 v58, 1.0, v58
	v_cndmask_b32_e64 v62, v60, v62, s[4:5]
	v_fma_f32 v60, -v63, v60, v59
	v_cmp_lt_f32_e64 s[4:5], 0, v60
	v_rcp_f32_e32 v58, v58
	v_add_f32_e32 v34, v34, v26
	v_cndmask_b32_e64 v60, v62, v63, s[4:5]
	v_mul_f32_e32 v62, 0x37800000, v60
	v_cndmask_b32_e32 v60, v60, v62, vcc
	v_cmp_class_f32_e32 vcc, v59, v221
	v_mul_f32_e32 v58, v45, v58
	v_add_f32_e32 v57, v57, v49
	v_cndmask_b32_e32 v59, v60, v59, vcc
	v_mul_f32_e32 v0, v59, v0
	v_add_f32_e32 v59, v58, v58
	v_mul_f32_e32 v59, 0x3fb8aa3b, v59
	v_exp_f32_e32 v59, v59
	v_mul_f32_e32 v34, 0xbfb8aa3b, v34
	v_mul_f32_e32 v57, 0xbfb8aa3b, v57
	v_exp_f32_e32 v34, v34
	v_sub_f32_e32 v59, 1.0, v59
	v_max_f32_e32 v59, 0, v59
	v_cmp_gt_f32_e32 vcc, s59, v59
	v_mul_f32_e32 v60, 0x4f800000, v59
	v_exp_f32_e32 v57, v57
	v_cndmask_b32_e32 v59, v59, v60, vcc
	v_sqrt_f32_e32 v60, v59
	v_add_f32_e32 v30, v30, v22
	v_mul_f32_e32 v30, 0xbfb8aa3b, v30
	v_add_f32_e32 v34, 1.0, v34
	v_add_u32_e32 v61, -1, v60
	v_fma_f32 v62, -v61, v60, v59
	v_cmp_ge_f32_e64 s[4:5], 0, v62
	v_add_u32_e32 v62, 1, v60
	v_exp_f32_e32 v30, v30
	v_add_f32_e32 v57, 1.0, v57
	v_cndmask_b32_e64 v61, v60, v61, s[4:5]
	v_fma_f32 v60, -v62, v60, v59
	v_rcp_f32_e32 v34, v34
	v_rcp_f32_e32 v57, v57
	v_cmp_lt_f32_e64 s[4:5], 0, v60
	v_add_f32_e32 v30, 1.0, v30
	v_cvt_pk_bf16_f32 v56, v56, v0
	v_and_b32_e32 v0, 0xffff0000, v71
	v_cndmask_b32_e64 v60, v61, v62, s[4:5]
	v_mul_f32_e32 v61, 0x37800000, v60
	v_cndmask_b32_e32 v60, v60, v61, vcc
	v_cmp_class_f32_e32 vcc, v59, v221
	v_rcp_f32_e32 v30, v30
	v_mul_f32_e32 v34, v18, v34
	v_cndmask_b32_e32 v59, v60, v59, vcc
	v_mul_f32_e32 v0, v57, v0
	v_mul_f32_e32 v57, 0x3fb8aa3b, v58
	v_add_f32_e32 v58, v34, v34
	v_mul_f32_e32 v0, v59, v0
	v_mul_f32_e32 v58, 0x3fb8aa3b, v58
	v_cvt_pk_bf16_f32 v57, v57, v0
	v_lshlrev_b32_e32 v0, 16, v72
	v_exp_f32_e32 v58, v58
	v_mul_f32_e32 v0, v30, v0
	v_mul_f32_e32 v30, 0x3fb8aa3b, v34
	v_add_f32_e32 v34, v35, v27
	v_mul_f32_e32 v34, 0xbfb8aa3b, v34
	v_exp_f32_e32 v34, v34
	v_sub_f32_e32 v58, 1.0, v58
	v_max_f32_e32 v58, 0, v58
	v_cmp_gt_f32_e32 vcc, s59, v58
	v_mul_f32_e32 v59, 0x4f800000, v58
	v_add_f32_e32 v34, 1.0, v34
	v_cndmask_b32_e32 v58, v58, v59, vcc
	v_sqrt_f32_e32 v59, v58
	v_rcp_f32_e32 v34, v34
	v_add_f32_e32 v31, v31, v23
	v_mul_f32_e32 v31, 0xbfb8aa3b, v31
	v_add_u32_e32 v60, -1, v59
	v_mul_f32_e32 v34, v19, v34
	v_fma_f32 v61, -v60, v59, v58
	v_add_f32_e32 v35, v34, v34
	v_cmp_ge_f32_e64 s[4:5], 0, v61
	v_add_u32_e32 v61, 1, v59
	v_mul_f32_e32 v35, 0x3fb8aa3b, v35
	v_cndmask_b32_e64 v60, v59, v60, s[4:5]
	v_fma_f32 v59, -v61, v59, v58
	v_exp_f32_e32 v31, v31
	v_exp_f32_e32 v35, v35
	v_cmp_lt_f32_e64 s[4:5], 0, v59
	v_add_f32_e32 v32, v32, v24
	v_add_f32_e32 v31, 1.0, v31
	v_cndmask_b32_e64 v59, v60, v61, s[4:5]
	v_mul_f32_e32 v60, 0x37800000, v59
; __device__ __forceinline__ unsigned cvt_pk_bf16(float lo, float hi) { unsigned r; asm volatile("v_cvt_pk_bf16_f32 %0, %1, %2" : "=v"(r) : "v"(lo), "v"(hi)); return r; }
; __device__ __forceinline__ float fast_sigmoid(float x) { return __builtin_amdgcn_rcpf(1.0f + __expf(-x)); }
;     __device__ __forceinline__ void operator()(const f32x4 (&acc)[2][2][4][2], const Unit& u, int wr, int wc, int fr, int fq, PG8_LAS unsigned char* ldsb) const {
;     ...
;             for (int m = 0; m < 4; ++m) {
;                 const size_t ro = (size_t)(row0 + ai * HALF + m * 16) * 512 + ch0;
;                 const u32x4 xw = xwv[ai][m];
;                 unsigned ow[8];
; #pragma unroll
;                 for (int n = 0; n < 2; ++n)
; #pragma unroll
;                     for (int i = 0; i < 4; ++i) { const int e = n * 4 + i;
;                         const unsigned wd = xw[e >> 1]; const float xc = __uint_as_float((e & 1) ? (wd & 0xffff0000u) : (wd << 16));
;                         const float r = fast_sigmoid(acc[ai][0][m][n][i] + br[e]), ig = fast_sigmoid(acc[ai][1][m][n][i] + bi[e]);
;                         const float la = sp[e] * r;
;                         const float bb = __builtin_sqrtf(fmaxf(1.0f - __expf(2.0f * la), 0.f)) * (ig * xc);
;                         ow[e] = cvt_pk_bf16(la * 1.4426950408889634f, bb); }
;                 u32x4 w0, w1; w0.x = ow[0]; w0.y = ow[1]; w0.z = ow[2]; w0.w = ow[3]; w1.x = ow[4]; w1.y = ow[5]; w1.z = ow[6]; w1.w = ow[7];
;                 *(u32x4*)(AB + ro) = w0; *(u32x4*)(AB + ro + 4) = w1;
	v_cndmask_b32_e32 v59, v59, v60, vcc
	v_cmp_class_f32_e32 vcc, v58, v221
	v_sub_f32_e32 v35, 1.0, v35
	v_rcp_f32_e32 v31, v31
	v_cndmask_b32_e32 v58, v59, v58, vcc
	v_max_f32_e32 v35, 0, v35
	v_mul_f32_e32 v0, v58, v0
	v_cmp_gt_f32_e32 vcc, s59, v35
	v_mul_f32_e32 v58, 0x4f800000, v35
	v_cvt_pk_bf16_f32 v30, v30, v0
	v_and_b32_e32 v0, 0xffff0000, v72
	v_cndmask_b32_e32 v35, v35, v58, vcc
	v_sqrt_f32_e32 v58, v35
	v_mul_f32_e32 v0, v31, v0
	v_mul_f32_e32 v31, 0x3fb8aa3b, v34
	v_add_f32_e32 v34, v36, v28
	v_mul_f32_e32 v34, 0xbfb8aa3b, v34
	v_exp_f32_e32 v34, v34
	v_add_u32_e32 v59, -1, v58
	v_fma_f32 v60, -v59, v58, v35
	v_cmp_ge_f32_e64 s[4:5], 0, v60
	v_add_u32_e32 v60, 1, v58
	v_add_f32_e32 v34, 1.0, v34
	v_cndmask_b32_e64 v59, v58, v59, s[4:5]
	v_fma_f32 v58, -v60, v58, v35
	v_cmp_lt_f32_e64 s[4:5], 0, v58
	v_rcp_f32_e32 v34, v34
	v_mul_f32_e32 v32, 0xbfb8aa3b, v32
	v_cndmask_b32_e64 v58, v59, v60, s[4:5]
	v_mul_f32_e32 v59, 0x37800000, v58
	v_cndmask_b32_e32 v58, v58, v59, vcc
	v_cmp_class_f32_e32 vcc, v35, v221
	v_mul_f32_e32 v34, v20, v34
	v_exp_f32_e32 v32, v32
	v_cndmask_b32_e32 v35, v58, v35, vcc
	v_mul_f32_e32 v0, v35, v0
	v_add_f32_e32 v35, v34, v34
	v_mul_f32_e32 v35, 0x3fb8aa3b, v35
	v_exp_f32_e32 v35, v35
	v_add_f32_e32 v32, 1.0, v32
	v_rcp_f32_e32 v32, v32
	v_cvt_pk_bf16_f32 v31, v31, v0
	v_sub_f32_e32 v35, 1.0, v35
	v_max_f32_e32 v35, 0, v35
	v_cmp_gt_f32_e32 vcc, s59, v35
	v_mul_f32_e32 v36, 0x4f800000, v35
	v_lshlrev_b32_e32 v0, 16, v73
	v_cndmask_b32_e32 v35, v35, v36, vcc
	v_sqrt_f32_e32 v36, v35
	v_mul_f32_e32 v0, v32, v0
	v_mul_f32_e32 v32, 0x3fb8aa3b, v34
	v_add_f32_e32 v34, v37, v29
	v_mul_f32_e32 v34, 0xbfb8aa3b, v34
	v_exp_f32_e32 v34, v34
	v_add_u32_e32 v58, -1, v36
	v_fma_f32 v59, -v58, v36, v35
	v_cmp_ge_f32_e64 s[4:5], 0, v59
	v_add_u32_e32 v59, 1, v36
	v_add_f32_e32 v34, 1.0, v34
	v_cndmask_b32_e64 v58, v36, v58, s[4:5]
	v_fma_f32 v36, -v59, v36, v35
	v_cmp_lt_f32_e64 s[4:5], 0, v36
	v_rcp_f32_e32 v34, v34
	v_add_f32_e32 v33, v33, v25
	v_cndmask_b32_e64 v36, v58, v59, s[4:5]
	v_mul_f32_e32 v58, 0x37800000, v36
	v_cndmask_b32_e32 v36, v36, v58, vcc
	v_cmp_class_f32_e32 vcc, v35, v221
	v_mul_f32_e32 v34, v21, v34
	v_add_f32_e32 v14, v14, v50
	v_cndmask_b32_e32 v35, v36, v35, vcc
	v_mul_f32_e32 v0, v35, v0
	v_add_f32_e32 v35, v34, v34
	v_mul_f32_e32 v35, 0x3fb8aa3b, v35
	v_exp_f32_e32 v35, v35
	v_mul_f32_e32 v33, 0xbfb8aa3b, v33
	v_mul_f32_e32 v14, 0xbfb8aa3b, v14
	v_exp_f32_e32 v33, v33
	v_sub_f32_e32 v35, 1.0, v35
	v_max_f32_e32 v35, 0, v35
	v_cmp_gt_f32_e32 vcc, s59, v35
	v_mul_f32_e32 v36, 0x4f800000, v35
	v_exp_f32_e32 v14, v14
	v_cndmask_b32_e32 v35, v35, v36, vcc
	v_sqrt_f32_e32 v36, v35
	v_add_f32_e32 v10, v10, v46
	v_mul_f32_e32 v10, 0xbfb8aa3b, v10
	v_add_f32_e32 v33, 1.0, v33
	v_add_u32_e32 v37, -1, v36
	v_fma_f32 v58, -v37, v36, v35
	v_cmp_ge_f32_e64 s[4:5], 0, v58
	v_add_u32_e32 v58, 1, v36
	v_add_f32_e32 v14, 1.0, v14
	v_cndmask_b32_e64 v37, v36, v37, s[4:5]
	v_fma_f32 v36, -v58, v36, v35
	v_cmp_lt_f32_e64 s[4:5], 0, v36
	v_exp_f32_e32 v10, v10
	v_rcp_f32_e32 v33, v33
	v_cndmask_b32_e64 v36, v37, v58, s[4:5]
	v_rcp_f32_e32 v14, v14
	v_mul_f32_e32 v37, 0x37800000, v36
	v_cndmask_b32_e32 v36, v36, v37, vcc
	v_cmp_class_f32_e32 vcc, v35, v221
	s_mov_b32 s1, 0x50000
	v_cvt_pk_bf16_f32 v32, v32, v0
	v_and_b32_e32 v0, 0xffff0000, v73
	v_cndmask_b32_e32 v35, v36, v35, vcc
	v_add_co_u32_e32 v36, vcc, s1, v166
	v_add_f32_e32 v10, 1.0, v10
	v_mul_f32_e32 v0, v33, v0
	v_mul_f32_e32 v33, 0x3fb8aa3b, v34
	s_mov_b64 s[4:5], 0x50000
	v_addc_co_u32_e32 v37, vcc, 0, v167, vcc
	v_rcp_f32_e32 v10, v10
	v_mul_f32_e32 v14, v42, v14
	v_mul_f32_e32 v0, v0, v35
	v_cvt_pk_bf16_f32 v33, v33, v0
	v_lshl_add_u64 v[34:35], v[166:167], 0, s[4:5]
	global_store_dwordx4 v[36:37], v[54:57], off
	global_store_dwordx4 v[34:35], v[30:33], off offset:16
	v_lshlrev_b32_e32 v0, 16, v38
	v_mul_f32_e32 v0, v10, v0
	v_add_f32_e32 v30, v14, v14
	v_mul_f32_e32 v30, 0x3fb8aa3b, v30
	v_exp_f32_e32 v30, v30
	v_mul_f32_e32 v10, 0x3fb8aa3b, v14
	v_add_f32_e32 v14, v15, v51
	v_mul_f32_e32 v14, 0xbfb8aa3b, v14
	v_exp_f32_e32 v14, v14
	v_sub_f32_e32 v30, 1.0, v30
	v_max_f32_e32 v30, 0, v30
	v_cmp_gt_f32_e32 vcc, s59, v30
	v_mul_f32_e32 v31, 0x4f800000, v30
	v_add_f32_e32 v14, 1.0, v14
	v_cndmask_b32_e32 v30, v30, v31, vcc
	v_sqrt_f32_e32 v31, v30
	v_rcp_f32_e32 v14, v14
	v_add_f32_e32 v11, v11, v47
	v_mul_f32_e32 v11, 0xbfb8aa3b, v11
	v_add_u32_e32 v32, -1, v31
	v_mul_f32_e32 v14, v43, v14
	v_fma_f32 v33, -v32, v31, v30
	v_add_f32_e32 v15, v14, v14
	v_cmp_ge_f32_e64 s[4:5], 0, v33
	v_add_u32_e32 v33, 1, v31
	v_mul_f32_e32 v15, 0x3fb8aa3b, v15
	v_cndmask_b32_e64 v32, v31, v32, s[4:5]
	v_fma_f32 v31, -v33, v31, v30
	v_exp_f32_e32 v11, v11
	v_exp_f32_e32 v15, v15
	v_cmp_lt_f32_e64 s[4:5], 0, v31
	v_add_f32_e32 v12, v12, v48
	v_add_f32_e32 v11, 1.0, v11
	v_cndmask_b32_e64 v31, v32, v33, s[4:5]
	v_mul_f32_e32 v32, 0x37800000, v31
	v_cndmask_b32_e32 v31, v31, v32, vcc
	v_cmp_class_f32_e32 vcc, v30, v221
	v_sub_f32_e32 v15, 1.0, v15
	v_rcp_f32_e32 v11, v11
	v_cndmask_b32_e32 v30, v31, v30, vcc
	v_max_f32_e32 v15, 0, v15
	v_mul_f32_e32 v0, v30, v0
	v_cmp_gt_f32_e32 vcc, s59, v15
	v_mul_f32_e32 v30, 0x4f800000, v15
	v_cvt_pk_bf16_f32 v10, v10, v0
	v_and_b32_e32 v0, 0xffff0000, v38
	v_cndmask_b32_e32 v15, v15, v30, vcc
	v_sqrt_f32_e32 v30, v15
	v_mul_f32_e32 v0, v11, v0
	v_mul_f32_e32 v11, 0x3fb8aa3b, v14
	v_add_f32_e32 v14, v16, v52
	v_mul_f32_e32 v14, 0xbfb8aa3b, v14
	v_exp_f32_e32 v14, v14
	v_add_u32_e32 v31, -1, v30
	v_fma_f32 v32, -v31, v30, v15
	v_cmp_ge_f32_e64 s[4:5], 0, v32
	v_add_u32_e32 v32, 1, v30
	v_add_f32_e32 v14, 1.0, v14
; __device__ __forceinline__ unsigned cvt_pk_bf16(float lo, float hi) { unsigned r; asm volatile("v_cvt_pk_bf16_f32 %0, %1, %2" : "=v"(r) : "v"(lo), "v"(hi)); return r; }
; __device__ __forceinline__ float fast_sigmoid(float x) { return __builtin_amdgcn_rcpf(1.0f + __expf(-x)); }
;     __device__ __forceinline__ void operator()(const f32x4 (&acc)[2][2][4][2], const Unit& u, int wr, int wc, int fr, int fq, PG8_LAS unsigned char* ldsb) const {
;     ...
;                     for (int i = 0; i < 4; ++i) { const int e = n * 4 + i;
;                         const unsigned wd = xw[e >> 1]; const float xc = __uint_as_float((e & 1) ? (wd & 0xffff0000u) : (wd << 16));
;                         const float r = fast_sigmoid(acc[ai][0][m][n][i] + br[e]), ig = fast_sigmoid(acc[ai][1][m][n][i] + bi[e]);
;                         const float la = sp[e] * r;
;                         const float bb = __builtin_sqrtf(fmaxf(1.0f - __expf(2.0f * la), 0.f)) * (ig * xc);
;                         ow[e] = cvt_pk_bf16(la * 1.4426950408889634f, bb); }
	v_cndmask_b32_e64 v31, v30, v31, s[4:5]
	v_fma_f32 v30, -v32, v30, v15
	v_cmp_lt_f32_e64 s[4:5], 0, v30
	v_rcp_f32_e32 v14, v14
	v_mul_f32_e32 v12, 0xbfb8aa3b, v12
	v_cndmask_b32_e64 v30, v31, v32, s[4:5]
	v_mul_f32_e32 v31, 0x37800000, v30
	v_cndmask_b32_e32 v30, v30, v31, vcc
	v_cmp_class_f32_e32 vcc, v15, v221
	v_mul_f32_e32 v14, v44, v14
	v_exp_f32_e32 v12, v12
	v_cndmask_b32_e32 v15, v30, v15, vcc
	v_mul_f32_e32 v0, v15, v0
	v_add_f32_e32 v15, v14, v14
	v_mul_f32_e32 v15, 0x3fb8aa3b, v15
	v_exp_f32_e32 v15, v15
	v_add_f32_e32 v12, 1.0, v12
	v_rcp_f32_e32 v12, v12
	v_cvt_pk_bf16_f32 v11, v11, v0
	v_sub_f32_e32 v15, 1.0, v15
	v_max_f32_e32 v15, 0, v15
	v_cmp_gt_f32_e32 vcc, s59, v15
	v_mul_f32_e32 v16, 0x4f800000, v15
	v_lshlrev_b32_e32 v0, 16, v39
	v_cndmask_b32_e32 v15, v15, v16, vcc
	v_sqrt_f32_e32 v16, v15
	v_mul_f32_e32 v0, v12, v0
	v_mul_f32_e32 v12, 0x3fb8aa3b, v14
	v_add_f32_e32 v14, v17, v53
	v_mul_f32_e32 v14, 0xbfb8aa3b, v14
	v_exp_f32_e32 v14, v14
	v_add_u32_e32 v30, -1, v16
	v_fma_f32 v31, -v30, v16, v15
	v_cmp_ge_f32_e64 s[4:5], 0, v31
	v_add_u32_e32 v31, 1, v16
	v_add_f32_e32 v14, 1.0, v14
	v_cndmask_b32_e64 v30, v16, v30, s[4:5]
	v_fma_f32 v16, -v31, v16, v15
	v_cmp_lt_f32_e64 s[4:5], 0, v16
	v_rcp_f32_e32 v14, v14
	v_add_f32_e32 v6, v6, v26
	v_cndmask_b32_e64 v16, v30, v31, s[4:5]
	v_mul_f32_e32 v30, 0x37800000, v16
	v_cndmask_b32_e32 v16, v16, v30, vcc
	v_cmp_class_f32_e32 vcc, v15, v221
	v_mul_f32_e32 v14, v45, v14
	v_add_f32_e32 v13, v13, v49
	v_cndmask_b32_e32 v15, v16, v15, vcc
	v_mul_f32_e32 v0, v15, v0
	v_add_f32_e32 v15, v14, v14
	v_mul_f32_e32 v15, 0x3fb8aa3b, v15
	v_exp_f32_e32 v15, v15
	v_mul_f32_e32 v6, 0xbfb8aa3b, v6
	v_mul_f32_e32 v13, 0xbfb8aa3b, v13
	v_exp_f32_e32 v6, v6
	v_sub_f32_e32 v15, 1.0, v15
	v_max_f32_e32 v15, 0, v15
	v_cmp_gt_f32_e32 vcc, s59, v15
	v_mul_f32_e32 v16, 0x4f800000, v15
	v_exp_f32_e32 v13, v13
	v_cndmask_b32_e32 v15, v15, v16, vcc
	v_sqrt_f32_e32 v16, v15
	v_add_f32_e32 v2, v2, v22
	v_mul_f32_e32 v2, 0xbfb8aa3b, v2
	v_add_f32_e32 v6, 1.0, v6
	v_add_u32_e32 v17, -1, v16
	v_fma_f32 v30, -v17, v16, v15
	v_cmp_ge_f32_e64 s[4:5], 0, v30
	v_add_u32_e32 v30, 1, v16
	v_exp_f32_e32 v2, v2
	v_add_f32_e32 v13, 1.0, v13
	v_cndmask_b32_e64 v17, v16, v17, s[4:5]
	v_fma_f32 v16, -v30, v16, v15
	v_rcp_f32_e32 v6, v6
	v_rcp_f32_e32 v13, v13
	v_cmp_lt_f32_e64 s[4:5], 0, v16
	v_add_f32_e32 v2, 1.0, v2
	v_cvt_pk_bf16_f32 v12, v12, v0
	v_and_b32_e32 v0, 0xffff0000, v39
	v_cndmask_b32_e64 v16, v17, v30, s[4:5]
	v_mul_f32_e32 v17, 0x37800000, v16
	v_cndmask_b32_e32 v16, v16, v17, vcc
	v_cmp_class_f32_e32 vcc, v15, v221
	v_rcp_f32_e32 v2, v2
	v_mul_f32_e32 v6, v18, v6
	v_cndmask_b32_e32 v15, v16, v15, vcc
	v_mul_f32_e32 v0, v13, v0
	v_mul_f32_e32 v13, 0x3fb8aa3b, v14
	v_add_f32_e32 v14, v6, v6
	v_mul_f32_e32 v0, v15, v0
	v_mul_f32_e32 v14, 0x3fb8aa3b, v14
	v_cvt_pk_bf16_f32 v13, v13, v0
	v_lshlrev_b32_e32 v0, 16, v40
	v_exp_f32_e32 v14, v14
	v_mul_f32_e32 v0, v2, v0
	v_mul_f32_e32 v2, 0x3fb8aa3b, v6
	v_add_f32_e32 v6, v7, v27
	v_mul_f32_e32 v6, 0xbfb8aa3b, v6
	v_exp_f32_e32 v6, v6
	v_sub_f32_e32 v14, 1.0, v14
	v_max_f32_e32 v14, 0, v14
	v_cmp_gt_f32_e32 vcc, s59, v14
	v_mul_f32_e32 v15, 0x4f800000, v14
	v_add_f32_e32 v6, 1.0, v6
	v_cndmask_b32_e32 v14, v14, v15, vcc
	v_sqrt_f32_e32 v15, v14
	v_rcp_f32_e32 v6, v6
	v_add_f32_e32 v3, v3, v23
	v_mul_f32_e32 v3, 0xbfb8aa3b, v3
	v_add_u32_e32 v16, -1, v15
	v_mul_f32_e32 v6, v19, v6
	v_fma_f32 v17, -v16, v15, v14
	v_add_f32_e32 v7, v6, v6
	v_cmp_ge_f32_e64 s[4:5], 0, v17
	v_add_u32_e32 v17, 1, v15
	v_mul_f32_e32 v7, 0x3fb8aa3b, v7
	v_cndmask_b32_e64 v16, v15, v16, s[4:5]
	v_fma_f32 v15, -v17, v15, v14
	v_exp_f32_e32 v3, v3
	v_exp_f32_e32 v7, v7
; __device__ __forceinline__ unsigned cvt_pk_bf16(float lo, float hi) { unsigned r; asm volatile("v_cvt_pk_bf16_f32 %0, %1, %2" : "=v"(r) : "v"(lo), "v"(hi)); return r; }
; __device__ __forceinline__ float fast_sigmoid(float x) { return __builtin_amdgcn_rcpf(1.0f + __expf(-x)); }
;     __device__ __forceinline__ void operator()(const f32x4 (&acc)[2][2][4][2], const Unit& u, int wr, int wc, int fr, int fq, PG8_LAS unsigned char* ldsb) const {
;     ...
;                     for (int i = 0; i < 4; ++i) { const int e = n * 4 + i;
;                         const unsigned wd = xw[e >> 1]; const float xc = __uint_as_float((e & 1) ? (wd & 0xffff0000u) : (wd << 16));
;                         const float r = fast_sigmoid(acc[ai][0][m][n][i] + br[e]), ig = fast_sigmoid(acc[ai][1][m][n][i] + bi[e]);
;                         const float la = sp[e] * r;
;                         const float bb = __builtin_sqrtf(fmaxf(1.0f - __expf(2.0f * la), 0.f)) * (ig * xc);
;                         ow[e] = cvt_pk_bf16(la * 1.4426950408889634f, bb); }
;                 u32x4 w0, w1; w0.x = ow[0]; w0.y = ow[1]; w0.z = ow[2]; w0.w = ow[3]; w1.x = ow[4]; w1.y = ow[5]; w1.z = ow[6]; w1.w = ow[7];
;                 *(u32x4*)(AB + ro) = w0; *(u32x4*)(AB + ro + 4) = w1;
	v_cmp_lt_f32_e64 s[4:5], 0, v15
	v_add_f32_e32 v4, v4, v24
	v_add_f32_e32 v3, 1.0, v3
	v_cndmask_b32_e64 v15, v16, v17, s[4:5]
	v_mul_f32_e32 v16, 0x37800000, v15
	v_cndmask_b32_e32 v15, v15, v16, vcc
	v_cmp_class_f32_e32 vcc, v14, v221
	v_sub_f32_e32 v7, 1.0, v7
	v_rcp_f32_e32 v3, v3
	v_cndmask_b32_e32 v14, v15, v14, vcc
	v_max_f32_e32 v7, 0, v7
	v_mul_f32_e32 v0, v14, v0
	v_cmp_gt_f32_e32 vcc, s59, v7
	v_mul_f32_e32 v14, 0x4f800000, v7
	v_cvt_pk_bf16_f32 v2, v2, v0
	v_and_b32_e32 v0, 0xffff0000, v40
	v_cndmask_b32_e32 v7, v7, v14, vcc
	v_sqrt_f32_e32 v14, v7
	v_mul_f32_e32 v0, v3, v0
	v_mul_f32_e32 v3, 0x3fb8aa3b, v6
	v_add_f32_e32 v6, v8, v28
	v_mul_f32_e32 v6, 0xbfb8aa3b, v6
	v_exp_f32_e32 v6, v6
	v_add_u32_e32 v15, -1, v14
	v_fma_f32 v16, -v15, v14, v7
	v_cmp_ge_f32_e64 s[4:5], 0, v16
	v_add_u32_e32 v16, 1, v14
	v_add_f32_e32 v6, 1.0, v6
	v_cndmask_b32_e64 v15, v14, v15, s[4:5]
	v_fma_f32 v14, -v16, v14, v7
	v_cmp_lt_f32_e64 s[4:5], 0, v14
	v_rcp_f32_e32 v6, v6
	v_mul_f32_e32 v4, 0xbfb8aa3b, v4
	v_cndmask_b32_e64 v14, v15, v16, s[4:5]
	v_mul_f32_e32 v15, 0x37800000, v14
	v_cndmask_b32_e32 v14, v14, v15, vcc
	v_cmp_class_f32_e32 vcc, v7, v221
	v_mul_f32_e32 v6, v20, v6
	v_exp_f32_e32 v4, v4
	v_cndmask_b32_e32 v7, v14, v7, vcc
	v_mul_f32_e32 v0, v7, v0
	v_add_f32_e32 v7, v6, v6
	v_mul_f32_e32 v7, 0x3fb8aa3b, v7
	v_exp_f32_e32 v7, v7
	v_add_f32_e32 v4, 1.0, v4
	v_rcp_f32_e32 v4, v4
	v_cvt_pk_bf16_f32 v3, v3, v0
	v_sub_f32_e32 v7, 1.0, v7
	v_max_f32_e32 v7, 0, v7
	v_cmp_gt_f32_e32 vcc, s59, v7
	v_mul_f32_e32 v8, 0x4f800000, v7
	v_lshlrev_b32_e32 v0, 16, v41
	v_cndmask_b32_e32 v7, v7, v8, vcc
	v_sqrt_f32_e32 v8, v7
	v_mul_f32_e32 v0, v4, v0
	v_mul_f32_e32 v4, 0x3fb8aa3b, v6
	v_add_f32_e32 v6, v9, v29
	v_mul_f32_e32 v6, 0xbfb8aa3b, v6
	v_exp_f32_e32 v6, v6
	v_add_u32_e32 v14, -1, v8
	v_fma_f32 v15, -v14, v8, v7
	v_cmp_ge_f32_e64 s[4:5], 0, v15
	v_add_u32_e32 v15, 1, v8
	v_add_f32_e32 v6, 1.0, v6
	v_cndmask_b32_e64 v14, v8, v14, s[4:5]
	v_fma_f32 v8, -v15, v8, v7
	v_cmp_lt_f32_e64 s[4:5], 0, v8
	v_rcp_f32_e32 v6, v6
	v_add_f32_e32 v5, v5, v25
	v_cndmask_b32_e64 v8, v14, v15, s[4:5]
	v_mul_f32_e32 v14, 0x37800000, v8
	v_cndmask_b32_e32 v8, v8, v14, vcc
	v_cmp_class_f32_e32 vcc, v7, v221
	v_mul_f32_e32 v6, v21, v6
	v_mul_f32_e32 v5, 0xbfb8aa3b, v5
	v_cndmask_b32_e32 v7, v8, v7, vcc
	v_mul_f32_e32 v0, v7, v0
	v_add_f32_e32 v7, v6, v6
	v_mul_f32_e32 v7, 0x3fb8aa3b, v7
	v_exp_f32_e32 v7, v7
	v_exp_f32_e32 v5, v5
	v_cvt_pk_bf16_f32 v4, v4, v0
	v_and_b32_e32 v0, 0xffff0000, v41
	v_sub_f32_e32 v7, 1.0, v7
	v_max_f32_e32 v7, 0, v7
	v_cmp_gt_f32_e32 vcc, s59, v7
	v_mul_f32_e32 v8, 0x4f800000, v7
	v_add_f32_e32 v5, 1.0, v5
	v_cndmask_b32_e32 v7, v7, v8, vcc
	v_sqrt_f32_e32 v8, v7
	v_rcp_f32_e32 v5, v5
	v_add_u32_e32 v9, -1, v8
	v_fma_f32 v14, -v9, v8, v7
	v_cmp_ge_f32_e64 s[4:5], 0, v14
	v_add_u32_e32 v14, 1, v8
	v_mul_f32_e32 v0, v5, v0
	v_cndmask_b32_e64 v9, v8, v9, s[4:5]
	v_fma_f32 v8, -v14, v8, v7
	v_cmp_lt_f32_e64 s[4:5], 0, v8
	v_mul_f32_e32 v5, 0x3fb8aa3b, v6
	s_nop 0
	v_cndmask_b32_e64 v8, v9, v14, s[4:5]
	v_mul_f32_e32 v9, 0x37800000, v8
	v_cndmask_b32_e32 v8, v8, v9, vcc
	v_cmp_class_f32_e32 vcc, v7, v221
	s_mov_b64 s[4:5], 0x58000
	s_nop 0
	v_cndmask_b32_e32 v7, v8, v7, vcc
	v_add_co_u32_e32 v8, vcc, 0x58000, v166
	v_mul_f32_e32 v0, v7, v0
	s_nop 0
	v_addc_co_u32_e32 v9, vcc, 0, v167, vcc
	v_lshl_add_u64 v[6:7], v[166:167], 0, s[4:5]
	s_mov_b64 s[4:5], -1
	s_and_b64 vcc, exec, s[2:3]
	v_cvt_pk_bf16_f32 v5, v5, v0
	global_store_dwordx4 v[8:9], v[10:13], off
	global_store_dwordx4 v[6:7], v[2:5], off offset:16
	s_cbranch_vccnz .LBB0_1027
	s_andn2_b64 vcc, exec, s[16:17]
	s_cbranch_vccnz .LBB0_1026
	s_barrier
	s_branch .LBB0_1026

; __device__ __forceinline__ float xsum_rows(float v) { return xsum32(xsum16(v)); }
; __global__ void __launch_bounds__(512, 2) mega_fwd(Params P) {
;     ...
;                             const float iv0 = 1.0f / ll[0], f1 = lmb / ll[1]; float ss = 0.f;
; #pragma unroll
;                             for (int cb = 0; cb < 8; ++cb)
; #pragma unroll
;                                 for (int j = 0; j < 4; ++j) { const float v = o[0][cb][j] * iv0 - f1 * o[1][cb][j]; o[0][cb][j] = v; ss += v * v; }
;                             ss = xsum_rows(ss);
;                             const float rs = rsqrtf(ss * (1.0f / 128.0f) + LN_EPS) * (1.0f - lam_init);
;                             const size_t row = rb + q0 + wave * 16 + r;
;                             f32x4 ggv[8];
; #pragma unroll
;                             for (int cb = 0; cb < 8; ++cb) ggv[cb] = *(const f32x4*)(ng + cb * 16 + g4 * 4);
; #pragma unroll
;                             for (int cb = 0; cb < 8; ++cb) { const f32x4 gg = ggv[cb]; const f32x4 v = o[0][cb] * rs * gg;
.LBB0_1088:
	v_mov_b32_e32 v0, v136
	s_nop 1
	v_permlane16_swap_b32_e32 v136, v0
	v_add_f32_e32 v0, v136, v0
	v_mov_b32_e32 v2, v0
	s_nop 1
	v_permlane32_swap_b32_e32 v0, v2
	v_add_f32_e32 v0, v0, v2
	v_mov_b32_e32 v2, v137
	s_nop 1
	v_permlane16_swap_b32_e32 v137, v2
	v_add_f32_e32 v2, v137, v2
	v_mov_b32_e32 v3, v2
	s_nop 1
	v_permlane32_swap_b32_e32 v2, v3
	v_add_f32_e32 v2, v2, v3
	v_div_scale_f32 v3, s[2:3], v0, v0, 1.0
	v_rcp_f32_e32 v4, v3
	v_mov_b32_e32 v135, v1
	v_fma_f32 v5, -v3, v4, 1.0
	v_fmac_f32_e32 v4, v5, v4
	v_div_scale_f32 v5, vcc, 1.0, v0, 1.0
	v_mul_f32_e32 v6, v5, v4
	v_fma_f32 v7, -v3, v6, v5
	v_fmac_f32_e32 v6, v7, v4
	v_fma_f32 v3, -v3, v6, v5
	v_div_fmas_f32 v3, v3, v4, v6
	v_div_fixup_f32 v0, v3, v0, 1.0
	v_div_scale_f32 v3, s[2:3], v2, v2, v142
	v_rcp_f32_e32 v4, v3
	s_add_u32 s2, s41, s43
	s_addc_u32 s3, s42, 0
	s_add_i32 s1, s1, s33
	v_fma_f32 v5, -v3, v4, 1.0
	v_fmac_f32_e32 v4, v5, v4
	v_div_scale_f32 v5, vcc, v142, v2, v142
	v_mul_f32_e32 v6, v5, v4
	v_fma_f32 v7, -v3, v6, v5
	v_fmac_f32_e32 v6, v7, v4
	v_fma_f32 v3, -v3, v6, v5
	v_div_fmas_f32 v3, v3, v4, v6
	v_div_fixup_f32 v2, v3, v2, v142
	v_pk_mul_f32 v[4:5], v[2:3], v[94:95] op_sel_hi:[0,1]
	v_pk_fma_f32 v[16:17], v[0:1], v[90:91], v[4:5] op_sel_hi:[0,1,1] neg_lo:[0,0,1] neg_hi:[0,0,1]
	v_mul_f32_e32 v4, v17, v17
	v_pk_mul_f32 v[6:7], v[2:3], v[96:97] op_sel_hi:[0,1]
	v_pk_fma_f32 v[4:5], v[16:17], v[16:17], v[4:5] op_sel_hi:[1,1,0]
	s_waitcnt vmcnt(0) lgkmcnt(0)
	v_pk_fma_f32 v[58:59], v[0:1], v[92:93], v[6:7] op_sel_hi:[0,1,1] neg_lo:[0,0,1] neg_hi:[0,0,1]
	v_pk_fma_f32 v[4:5], v[58:59], v[58:59], v[4:5]
	v_mul_f32_e32 v6, v59, v59
	v_pk_add_f32 v[4:5], v[4:5], v[6:7] op_sel_hi:[1,0]
	v_pk_mul_f32 v[6:7], v[2:3], v[86:87] op_sel_hi:[0,1]
	v_pk_fma_f32 v[18:19], v[0:1], v[82:83], v[6:7] op_sel_hi:[0,1,1] neg_lo:[0,0,1] neg_hi:[0,0,1]
	v_pk_fma_f32 v[4:5], v[18:19], v[18:19], v[4:5]
	v_mul_f32_e32 v6, v19, v19
	v_pk_add_f32 v[4:5], v[4:5], v[6:7] op_sel_hi:[1,0]
	v_pk_mul_f32 v[6:7], v[2:3], v[88:89] op_sel_hi:[0,1]
	v_pk_fma_f32 v[60:61], v[0:1], v[84:85], v[6:7] op_sel_hi:[0,1,1] neg_lo:[0,0,1] neg_hi:[0,0,1]
	v_pk_fma_f32 v[4:5], v[60:61], v[60:61], v[4:5]
	v_mul_f32_e32 v6, v61, v61
	v_pk_add_f32 v[4:5], v[4:5], v[6:7] op_sel_hi:[1,0]
	v_pk_mul_f32 v[6:7], v[2:3], v[78:79] op_sel_hi:[0,1]
	v_pk_fma_f32 v[20:21], v[0:1], v[74:75], v[6:7] op_sel_hi:[0,1,1] neg_lo:[0,0,1] neg_hi:[0,0,1]
	v_pk_fma_f32 v[4:5], v[20:21], v[20:21], v[4:5]
	v_mul_f32_e32 v6, v21, v21
	v_pk_add_f32 v[4:5], v[4:5], v[6:7] op_sel_hi:[1,0]
	v_pk_mul_f32 v[6:7], v[2:3], v[80:81] op_sel_hi:[0,1]
	v_pk_fma_f32 v[62:63], v[0:1], v[76:77], v[6:7] op_sel_hi:[0,1,1] neg_lo:[0,0,1] neg_hi:[0,0,1]
	v_pk_fma_f32 v[4:5], v[62:63], v[62:63], v[4:5]
	v_mul_f32_e32 v6, v63, v63
	v_pk_add_f32 v[4:5], v[4:5], v[6:7] op_sel_hi:[1,0]
	v_pk_mul_f32 v[6:7], v[2:3], v[70:71] op_sel_hi:[0,1]
	v_pk_fma_f32 v[32:33], v[0:1], v[66:67], v[6:7] op_sel_hi:[0,1,1] neg_lo:[0,0,1] neg_hi:[0,0,1]
	v_pk_fma_f32 v[4:5], v[32:33], v[32:33], v[4:5]
	v_mul_f32_e32 v6, v33, v33
	v_pk_add_f32 v[4:5], v[4:5], v[6:7] op_sel_hi:[1,0]
	v_pk_mul_f32 v[6:7], v[2:3], v[72:73] op_sel_hi:[0,1]
	v_pk_fma_f32 v[64:65], v[0:1], v[68:69], v[6:7] op_sel_hi:[0,1,1] neg_lo:[0,0,1] neg_hi:[0,0,1]
	v_pk_fma_f32 v[4:5], v[64:65], v[64:65], v[4:5]
	v_mul_f32_e32 v6, v65, v65
	v_pk_add_f32 v[4:5], v[4:5], v[6:7] op_sel_hi:[1,0]
	v_pk_mul_f32 v[6:7], v[2:3], v[54:55] op_sel_hi:[0,1]
	v_pk_fma_f32 v[50:51], v[0:1], v[50:51], v[6:7] op_sel_hi:[0,1,1] neg_lo:[0,0,1] neg_hi:[0,0,1]
	v_pk_fma_f32 v[4:5], v[50:51], v[50:51], v[4:5]
	v_mul_f32_e32 v6, v51, v51
	v_pk_add_f32 v[4:5], v[4:5], v[6:7] op_sel_hi:[1,0]
	v_pk_mul_f32 v[6:7], v[2:3], v[56:57] op_sel_hi:[0,1]
	v_pk_fma_f32 v[52:53], v[0:1], v[52:53], v[6:7] op_sel_hi:[0,1,1] neg_lo:[0,0,1] neg_hi:[0,0,1]
	v_pk_fma_f32 v[4:5], v[52:53], v[52:53], v[4:5]
	v_mul_f32_e32 v6, v53, v53
	v_pk_add_f32 v[4:5], v[4:5], v[6:7] op_sel_hi:[1,0]
	v_pk_mul_f32 v[6:7], v[2:3], v[46:47] op_sel_hi:[0,1]
	v_pk_fma_f32 v[14:15], v[0:1], v[42:43], v[6:7] op_sel_hi:[0,1,1] neg_lo:[0,0,1] neg_hi:[0,0,1]
	v_pk_fma_f32 v[4:5], v[14:15], v[14:15], v[4:5]
	v_mul_f32_e32 v6, v15, v15
	v_pk_add_f32 v[4:5], v[4:5], v[6:7] op_sel_hi:[1,0]
	v_pk_mul_f32 v[6:7], v[2:3], v[48:49] op_sel_hi:[0,1]
	v_pk_fma_f32 v[30:31], v[0:1], v[44:45], v[6:7] op_sel_hi:[0,1,1] neg_lo:[0,0,1] neg_hi:[0,0,1]
	v_pk_fma_f32 v[4:5], v[30:31], v[30:31], v[4:5]
	v_mul_f32_e32 v6, v31, v31
	v_pk_add_f32 v[4:5], v[4:5], v[6:7] op_sel_hi:[1,0]
	v_pk_mul_f32 v[6:7], v[2:3], v[38:39] op_sel_hi:[0,1]
	v_pk_fma_f32 v[10:11], v[0:1], v[34:35], v[6:7] op_sel_hi:[0,1,1] neg_lo:[0,0,1] neg_hi:[0,0,1]
	v_pk_fma_f32 v[4:5], v[10:11], v[10:11], v[4:5]
	v_mul_f32_e32 v6, v11, v11
	v_pk_add_f32 v[4:5], v[4:5], v[6:7] op_sel_hi:[1,0]
	v_pk_mul_f32 v[6:7], v[2:3], v[40:41] op_sel_hi:[0,1]
	v_pk_fma_f32 v[12:13], v[0:1], v[36:37], v[6:7] op_sel_hi:[0,1,1] neg_lo:[0,0,1] neg_hi:[0,0,1]
	v_pk_fma_f32 v[4:5], v[12:13], v[12:13], v[4:5]
	v_mul_f32_e32 v6, v13, v13
	v_pk_add_f32 v[4:5], v[4:5], v[6:7] op_sel_hi:[1,0]
	v_pk_mul_f32 v[6:7], v[2:3], v[26:27] op_sel_hi:[0,1]
	v_pk_fma_f32 v[6:7], v[0:1], v[22:23], v[6:7] op_sel_hi:[0,1,1] neg_lo:[0,0,1] neg_hi:[0,0,1]
	v_pk_fma_f32 v[4:5], v[6:7], v[6:7], v[4:5]
	v_mul_f32_e32 v8, v7, v7
	v_pk_mul_f32 v[2:3], v[2:3], v[28:29] op_sel_hi:[0,1]
	v_pk_add_f32 v[4:5], v[4:5], v[8:9] op_sel_hi:[1,0]
	v_pk_fma_f32 v[8:9], v[0:1], v[24:25], v[2:3] op_sel_hi:[0,1,1] neg_lo:[0,0,1] neg_hi:[0,0,1]
	v_pk_fma_f32 v[2:3], v[8:9], v[8:9], v[4:5]
	v_mul_f32_e32 v0, v9, v9
	v_pk_add_f32 v[2:3], v[2:3], v[0:1] op_sel_hi:[1,0]
	v_lshl_add_u64 v[66:67], s[46:47], 0, v[130:131]
	v_mov_b32_e32 v0, v2
	s_nop 1
	v_permlane16_swap_b32_e32 v2, v0
	v_add_f32_e32 v0, v2, v0
	v_mov_b32_e32 v2, v0
	s_nop 1
	v_permlane32_swap_b32_e32 v0, v2
	v_add_f32_e32 v0, v0, v2
	v_fmamk_f32 v0, v0, 0x3c000000, v220
	v_cmp_gt_f32_e32 vcc, s50, v0
	v_mul_f32_e32 v2, 0x4b800000, v0
	v_lshlrev_b64 v[66:67], 11, v[66:67]
	v_cndmask_b32_e32 v0, v0, v2, vcc
	v_rsq_f32_e32 v0, v0
	v_lshl_add_u64 v[66:67], s[2:3], 0, v[66:67]
	v_lshl_add_u64 v[66:67], v[66:67], 0, v[134:135]
	s_cmpk_gt_i32 s1, 0x7ff
	v_mul_f32_e32 v2, 0x45800000, v0
	v_cndmask_b32_e32 v0, v0, v2, vcc
	global_load_dwordx4 v[2:5], v[132:133], off
	global_load_dwordx4 v[22:25], v[132:133], off offset:64
	global_load_dwordx4 v[26:29], v[132:133], off offset:128
	global_load_dwordx4 v[34:37], v[132:133], off offset:192
	global_load_dwordx4 v[38:41], v[132:133], off offset:256
	global_load_dwordx4 v[42:45], v[132:133], off offset:320
	global_load_dwordx4 v[46:49], v[132:133], off offset:384
	global_load_dwordx4 v[54:57], v[132:133], off offset:448
	v_mul_f32_e32 v0, v143, v0
	v_pk_mul_f32 v[16:17], v[0:1], v[16:17] op_sel_hi:[0,1]
	v_pk_mul_f32 v[58:59], v[0:1], v[58:59] op_sel_hi:[0,1]
	s_waitcnt vmcnt(7)
; __device__ __forceinline__ unsigned cvt_pk_bf16(float lo, float hi) { unsigned r; asm volatile("v_cvt_pk_bf16_f32 %0, %1, %2" : "=v"(r) : "v"(lo), "v"(hi)); return r; }
; __global__ void __launch_bounds__(512, 2) mega_fwd(Params P) {
;     ...
;                             for (int cb = 0; cb < 8; ++cb) { const f32x4 gg = ggv[cb]; const f32x4 v = o[0][cb] * rs * gg;
;                                 u32x2 wv; wv.x = cvt_pk_bf16(v[0], v[1]); wv.y = cvt_pk_bf16(v[2], v[3]); *(u32x2*)(CAT + row * 1024 + h * 128 + cb * 16 + g4 * 4) = wv; }
	v_pk_mul_f32 v[2:3], v[2:3], v[16:17]
	v_pk_mul_f32 v[4:5], v[4:5], v[58:59]
	v_cvt_pk_bf16_f32 v2, v2, v3
	s_nop 0
	v_cvt_pk_bf16_f32 v3, v4, v5
	global_store_dwordx2 v[66:67], v[2:3], off
	v_pk_mul_f32 v[2:3], v[0:1], v[18:19] op_sel_hi:[0,1]
	v_pk_mul_f32 v[4:5], v[0:1], v[60:61] op_sel_hi:[0,1]
	s_waitcnt vmcnt(0)
	v_pk_mul_f32 v[2:3], v[22:23], v[2:3]
	v_pk_mul_f32 v[4:5], v[24:25], v[4:5]
	v_cvt_pk_bf16_f32 v2, v2, v3
	s_nop 0
	v_cvt_pk_bf16_f32 v3, v4, v5
	global_store_dwordx2 v[66:67], v[2:3], off offset:32
	v_pk_mul_f32 v[2:3], v[0:1], v[20:21] op_sel_hi:[0,1]
	v_pk_mul_f32 v[4:5], v[0:1], v[62:63] op_sel_hi:[0,1]
	v_pk_mul_f32 v[2:3], v[26:27], v[2:3]
	v_pk_mul_f32 v[4:5], v[28:29], v[4:5]
	v_cvt_pk_bf16_f32 v2, v2, v3
	s_nop 0
	v_cvt_pk_bf16_f32 v3, v4, v5
	global_store_dwordx2 v[66:67], v[2:3], off offset:64
	v_pk_mul_f32 v[2:3], v[0:1], v[32:33] op_sel_hi:[0,1]
	v_pk_mul_f32 v[4:5], v[0:1], v[64:65] op_sel_hi:[0,1]
	v_pk_mul_f32 v[2:3], v[34:35], v[2:3]
	v_pk_mul_f32 v[4:5], v[36:37], v[4:5]
	v_cvt_pk_bf16_f32 v2, v2, v3
	s_nop 0
	v_cvt_pk_bf16_f32 v3, v4, v5
	global_store_dwordx2 v[66:67], v[2:3], off offset:96
	v_pk_mul_f32 v[2:3], v[0:1], v[50:51] op_sel_hi:[0,1]
	v_pk_mul_f32 v[4:5], v[0:1], v[52:53] op_sel_hi:[0,1]
	v_pk_mul_f32 v[2:3], v[38:39], v[2:3]
	v_pk_mul_f32 v[4:5], v[40:41], v[4:5]
	v_cvt_pk_bf16_f32 v2, v2, v3
	s_nop 0
	v_cvt_pk_bf16_f32 v3, v4, v5
	global_store_dwordx2 v[66:67], v[2:3], off offset:128
	v_pk_mul_f32 v[2:3], v[0:1], v[14:15] op_sel_hi:[0,1]
	v_pk_mul_f32 v[4:5], v[0:1], v[30:31] op_sel_hi:[0,1]
	v_pk_mul_f32 v[2:3], v[42:43], v[2:3]
	v_pk_mul_f32 v[4:5], v[44:45], v[4:5]
	v_cvt_pk_bf16_f32 v2, v2, v3
	s_nop 0
	v_cvt_pk_bf16_f32 v3, v4, v5
	global_store_dwordx2 v[66:67], v[2:3], off offset:160
	v_pk_mul_f32 v[2:3], v[0:1], v[10:11] op_sel_hi:[0,1]
	v_pk_mul_f32 v[4:5], v[0:1], v[12:13] op_sel_hi:[0,1]
	v_pk_mul_f32 v[2:3], v[46:47], v[2:3]
	v_pk_mul_f32 v[4:5], v[48:49], v[4:5]
	v_cvt_pk_bf16_f32 v2, v2, v3
	s_nop 0
	v_cvt_pk_bf16_f32 v3, v4, v5
	global_store_dwordx2 v[66:67], v[2:3], off offset:192
	v_pk_mul_f32 v[2:3], v[0:1], v[6:7] op_sel_hi:[0,1]
	v_pk_mul_f32 v[4:5], v[0:1], v[8:9] op_sel_hi:[0,1]
	v_pk_mul_f32 v[2:3], v[54:55], v[2:3]
	v_pk_mul_f32 v[4:5], v[56:57], v[4:5]
	v_cvt_pk_bf16_f32 v2, v2, v3
	s_nop 0
	v_cvt_pk_bf16_f32 v3, v4, v5
	global_store_dwordx2 v[66:67], v[2:3], off offset:224
	s_cbranch_scc1 .LBB0_1109
; template <int D, int DV, int MODE, int NMAP, int KT> ...
;     ...
;     { const bf16_t* qr = Qp + (size_t)(w * 16 + r) * ldq + g4 * 8;
; #pragma unroll
;       for (int mp = 0; mp < NMAP; ++mp)
; #pragma unroll
;         for (int kk = 0; kk < D / 32; ++kk) qf[mp][kk] = *(const bf16x8*)(qr + mp * D + kk * 32); }
;     float m[NMAP];
; #pragma unroll
;     for (int mp = 0; mp < NMAP; ++mp) { m[mp] = -INFINITY; l[mp] = 0.f;
; #pragma unroll
;         for (int cb = 0; cb < DV / 16; ++cb) o[mp][cb] = (f32x4){0.f, 0.f, 0.f, 0.f}; }
;     const int rowmin = q0 + w * 16, myrow = rowmin + r;
;     float ck[NB][4];
;     if (MODE == 2) {
; #pragma unroll
;         for (int nb = 0; nb < NB; ++nb)
; #pragma unroll
;             for (int j = 0; j < 4; ++j) ck[nb][j] = __builtin_amdgcn_exp2f(-l2g * (float)(nb * 16 + g4 * 4 + j));
;     }
;     u32x4 kreg[KN], vreg[VN];
;     ...
;     AT_LOAD(0);
;     __syncthreads();
;     AT_STORE(0);
;     if (nkt > 1) AT_LOAD(1);
; __global__ void __launch_bounds__(512, 2) mega_fwd(Params P) {
;     ...
;                             const int bh = u & 127, b = bh >> 2, h = bh & 3, qi_ = u >> 7, ii_ = qi_ >> 1, hb_ = qi_ & 1, qt = (ii_ & 1) ? (ii_ - 1 + hb_) : (15 - hb_ - ii_), q0 = qt * 128, nkt = (q0 + 128) / 64;
;                             const size_t rb = (size_t)b * SEQ;
;                             f32x4 o[2][8]; float ll[2];
;                             attn_core3<64, 128, 1, 2, 64>(lds, Z + (rb + q0) * ZW + h * 128, ZW, Z + rb * ZW + 512 + h * 128, ZW, Z + rb * ZW + 1024 + h * 128, ZW, q0, nkt, 0.125f * LOG2E, 0.f, o, ll);
.LBB0_1089:
	s_ashr_i32 s2, s1, 8
	s_bfe_u32 s3, s1, 0x10007
	s_add_i32 s5, s2, s3
	s_xor_b32 s3, s3, 15
	s_and_b32 s4, s1, 0x100
	s_add_i32 s5, s5, -1
	s_sub_i32 s2, s3, s2
	s_cmp_eq_u32 s4, 0
	s_cselect_b32 s2, s2, s5
	s_lshl_b32 s8, s2, 7
	s_add_i32 s2, s8, 0x80
	s_ashr_i32 s44, s2, 6
	s_lshl_b32 s2, s1, 9
	s_and_b32 s2, s2, 0xf800
	s_ashr_i32 s3, s8, 31
	s_add_u32 s46, s8, s2
	s_addc_u32 s47, s3, 0
	s_mul_i32 s3, s47, 0x1400
	s_mul_hi_u32 s4, s46, 0x1400
	s_add_i32 s4, s4, s3
	s_mul_i32 s3, s46, 0x1400
	s_add_u32 s3, s34, s3
	s_addc_u32 s5, s40, s4
	s_lshl_b32 s4, s1, 7
	s_and_b32 s4, s4, 0x180
	s_lshl_b32 s43, s4, 1
	s_add_u32 s4, s3, s43
	s_addc_u32 s5, s5, 0
	s_mulk_i32 s2, 0x1400
	s_add_u32 s2, s34, s2
	s_addc_u32 s3, s40, 0
	v_mov_b32_e32 v28, v211
	s_add_u32 s2, s2, s43
	s_addc_u32 s3, s3, 0
	v_readfirstlane_b32 s6, v28
	s_ashr_i32 s6, s6, 6
	v_and_b32_e32 v27, 15, v28
	s_lshl_b32 s74, s6, 4
	v_or_b32_e32 v0, s74, v27
	v_mov_b64_e32 v[2:3], s[4:5]
	v_mad_i64_i32 v[2:3], s[4:5], v0, s57, v[2:3]
	v_and_b32_e32 v0, 48, v28
	v_add_u32_e32 v24, 0x200, v28
	v_lshl_add_u64 v[14:15], v[2:3], 0, v[0:1]
	v_ashrrev_i32_e32 v0, 31, v28
	v_ashrrev_i32_e32 v25, 31, v24
	v_lshrrev_b32_e32 v0, 28, v0
	v_lshrrev_b32_e32 v25, 28, v25
	v_add_u32_e32 v18, v28, v0
	v_add_u32_e32 v25, v24, v25
	v_ashrrev_i32_e32 v0, 4, v18
	v_and_b32_e32 v18, -16, v18
	v_mov_b64_e32 v[34:35], s[2:3]
	v_ashrrev_i32_e32 v29, 4, v25
	v_sub_u32_e32 v38, v28, v18
	v_mad_i64_i32 v[18:19], s[4:5], v0, s57, v[34:35]
	v_mad_i64_i32 v[30:31], s[4:5], v29, s57, v[34:35]
	s_ashr_i32 s4, s6, 31
	s_lshr_b32 s4, s4, 28
	s_add_i32 s4, s6, s4
	s_ashr_i32 s11, s4, 4
	s_and_b32 s4, s4, -16
	v_and_b32_e32 v26, 63, v28
	s_sub_i32 s45, s6, s4
	s_lshl_b32 s9, s11, 6
	s_add_i32 s6, s6, 8
	v_or_b32_e32 v36, s9, v26
	s_ashr_i32 s7, s6, 31
	v_mad_i64_i32 v[36:37], s[4:5], v36, s57, v[34:35]
	s_lshr_b32 s7, s7, 28
	s_lshl_b32 s4, s45, 3
	s_add_i32 s7, s6, s7
	v_and_b32_e32 v25, -16, v25
	s_ashr_i32 s5, s4, 31
	s_ashr_i32 s12, s7, 4
	v_lshlrev_b32_e32 v22, 3, v38
	v_sub_u32_e32 v39, v24, v25
	v_lshl_add_u64 v[36:37], s[4:5], 1, v[36:37]
	s_lshl_b32 s10, s12, 6
	global_load_dwordx4 v[2:5], v[14:15], off
	global_load_dwordx4 v[6:9], v[14:15], off offset:64
	global_load_dwordx4 v[10:13], v[14:15], off offset:128
	s_nop 0
	global_load_dwordx4 v[14:17], v[14:15], off offset:192
	v_ashrrev_i32_e32 v23, 31, v22
	v_lshlrev_b32_e32 v24, 3, v39
	global_load_dwordx4 v[58:61], v[36:37], off offset:2048
	s_and_b32 s7, s7, -16
	v_or_b32_e32 v36, s10, v26
	v_lshl_add_u64 v[18:19], v[22:23], 1, v[18:19]
	v_ashrrev_i32_e32 v25, 31, v24
	s_sub_i32 s61, s6, s7
	v_mad_i64_i32 v[34:35], s[6:7], v36, s57, v[34:35]
	global_load_dwordx4 v[18:21], v[18:19], off offset:1024
	v_lshl_add_u64 v[30:31], v[24:25], 1, v[30:31]
	s_lshl_b32 s6, s61, 3
	global_load_dwordx4 v[30:33], v[30:31], off offset:1024
	s_ashr_i32 s7, s6, 31
	v_lshl_add_u64 v[34:35], s[6:7], 1, v[34:35]
	global_load_dwordx4 v[62:65], v[34:35], off offset:2048
	s_movk_i32 s13, 0x110
	v_mul_lo_u32 v135, v0, s13
	v_lshlrev_b32_e32 v144, 4, v38
	s_mulk_i32 s45, 0x480
	v_add3_u32 v34, 0, v135, v144
	v_mul_lo_u32 v145, v29, s13
	v_lshlrev_b32_e32 v146, 4, v39
	s_add_i32 s13, s45, 0
	s_lshl_b32 s56, s11, 7
	s_mulk_i32 s61, 0x480
	s_waitcnt lgkmcnt(0)
	s_barrier
	s_add_i32 s13, s13, s56
	v_lshlrev_b32_e32 v147, 1, v26
	s_add_i32 s11, s61, 0
	s_lshl_b32 s67, s12, 7
	s_add_i32 s11, s11, s67
	s_cmp_lt_i32 s44, 2
	s_waitcnt vmcnt(0)
	ds_write_b128 v34, v[18:21]
	v_add3_u32 v34, 0, v145, v146
	ds_write_b128 v34, v[30:33]
	v_add_u32_e32 v34, s13, v147
	ds_write_b16 v34, v58 offset:17408
	ds_write_b16_d16_hi v34, v58 offset:17552
	ds_write_b16 v34, v59 offset:17696
	ds_write_b16_d16_hi v34, v59 offset:17840
	ds_write_b16 v34, v60 offset:17984
	ds_write_b16_d16_hi v34, v60 offset:18128
	ds_write_b16 v34, v61 offset:18272
	ds_write_b16_d16_hi v34, v61 offset:18416
	v_add_u32_e32 v34, s11, v147
	ds_write_b16 v34, v62 offset:17408
	ds_write_b16_d16_hi v34, v62 offset:17552
	ds_write_b16 v34, v63 offset:17696
	ds_write_b16_d16_hi v34, v63 offset:17840
	ds_write_b16 v34, v64 offset:17984
	ds_write_b16_d16_hi v34, v64 offset:18128
	ds_write_b16 v34, v65 offset:18272
	ds_write_b16_d16_hi v34, v65 offset:18416
	s_cbranch_scc1 .LBB0_1091
	v_or_b32_e32 v38, 64, v26
	v_add_u32_e32 v18, 64, v0
	v_mov_b64_e32 v[34:35], s[2:3]
	v_add_u32_e32 v20, 64, v29
	v_add_u32_e32 v36, s9, v38
	v_mad_i64_i32 v[18:19], s[12:13], v18, s57, v[34:35]
	v_mad_i64_i32 v[20:21], s[12:13], v20, s57, v[34:35]
	v_mad_i64_i32 v[36:37], s[12:13], v36, s57, v[34:35]
	v_add_u32_e32 v38, s10, v38
	v_lshl_add_u64 v[18:19], v[22:23], 1, v[18:19]
	v_lshl_add_u64 v[30:31], v[24:25], 1, v[20:21]
	v_lshl_add_u64 v[36:37], s[4:5], 1, v[36:37]
	v_mad_i64_i32 v[34:35], s[12:13], v38, s57, v[34:35]
	global_load_dwordx4 v[18:21], v[18:19], off offset:1024
	s_nop 0
	global_load_dwordx4 v[30:33], v[30:31], off offset:1024
	v_lshl_add_u64 v[34:35], s[6:7], 1, v[34:35]
	global_load_dwordx4 v[58:61], v[36:37], off offset:2048
	global_load_dwordx4 v[62:65], v[34:35], off offset:2048

; template <int D, int DV, int MODE, int NMAP, int KT> ...
;     ...
;     AT_LOAD(0);
;     __syncthreads();
;     AT_STORE(0);
;     if (nkt > 1) AT_LOAD(1);
;     for (int kt = 0; kt < nkt; ++kt) {
;         __syncthreads();
;         const int cur = (kt & 1) * BUF_BYTES;
;         if (kt + 1 < nkt) { AT_STORE(((kt + 1) & 1) * BUF_BYTES); if (kt + 2 < nkt) AT_LOAD(kt + 2); }
.LBB0_1093:
	s_add_i32 s77, s2, 1
	s_cmp_ge_i32 s77, s44
	s_waitcnt lgkmcnt(0)
	s_barrier
	s_cbranch_scc1 .LBB0_1096
	s_bitcmp1_b32 s77, 0
	s_cselect_b32 s3, 0x8c00, 0
	s_add_i32 s3, s3, 0
	v_add3_u32 v98, s3, v135, v144
	s_add_i32 s4, s3, s45
	s_waitcnt vmcnt(0)
	ds_write_b128 v98, v[18:21]
	v_add3_u32 v98, s3, v145, v146
	s_add_i32 s4, s4, s56
	s_add_i32 s3, s3, s61
	ds_write_b128 v98, v[30:33]
	v_add_u32_e32 v98, s4, v147
	s_add_i32 s3, s3, s67
	ds_write_b16 v98, v58 offset:17408
	ds_write_b16_d16_hi v98, v58 offset:17552
	ds_write_b16 v98, v59 offset:17696
	ds_write_b16_d16_hi v98, v59 offset:17840
	ds_write_b16 v98, v60 offset:17984
	ds_write_b16_d16_hi v98, v60 offset:18128
	ds_write_b16 v98, v61 offset:18272
	ds_write_b16_d16_hi v98, v61 offset:18416
	v_add_u32_e32 v98, s3, v147
	s_add_i32 s3, s2, 2
	s_cmp_ge_i32 s3, s44
	ds_write_b16 v98, v62 offset:17408
	ds_write_b16_d16_hi v98, v62 offset:17552
	ds_write_b16 v98, v63 offset:17696
	ds_write_b16_d16_hi v98, v63 offset:17840
	ds_write_b16 v98, v64 offset:17984
	ds_write_b16_d16_hi v98, v64 offset:18128
	ds_write_b16 v98, v65 offset:18272
	ds_write_b16_d16_hi v98, v65 offset:18416
	s_cbranch_scc1 .LBB0_1096
	v_add_u32_e32 v60, s76, v155
	v_mov_b64_e32 v[58:59], s[48:49]
	v_add_u32_e32 v18, s76, v154
	v_add_u32_e32 v20, s76, v153
	v_mad_i64_i32 v[58:59], s[4:5], v60, s57, v[58:59]
	v_add_u32_e32 v62, s76, v156
	v_mov_b64_e32 v[60:61], s[50:51]
	v_mad_i64_i32 v[18:19], s[4:5], v18, s57, v[138:139]
	v_mad_i64_i32 v[30:31], s[4:5], v20, s57, v[140:141]
	v_mad_i64_i32 v[62:63], s[4:5], v62, s57, v[60:61]
	global_load_dwordx4 v[18:21], v[18:19], off offset:1024
	s_nop 0
	global_load_dwordx4 v[30:33], v[30:31], off offset:1024
	s_nop 0
	global_load_dwordx4 v[58:61], v[58:59], off offset:2048
	s_nop 0
	global_load_dwordx4 v[62:65], v[62:63], off offset:2048

; __device__ __forceinline__ float bflo(unsigned w) { return __uint_as_float(w << 16); }
; __device__ __forceinline__ float bfhi(unsigned w) { return __uint_as_float(w & 0xffff0000u); }
; __global__ void __launch_bounds__(512, 2) mega_fwd(Params P) {
;     ...
;                             for (int t0 = 0; t0 < 64; t0 += 16) {
;                                 u32x4 wv[16];
; #pragma unroll
;                                 for (int i = 0; i < 16; ++i) wv[i] = *(const u32x4*)(ab + (size_t)(t0 + i) * 512);
; #pragma unroll
;                                 for (int i = 0; i < 16; ++i)
; #pragma unroll
;                                     for (int k = 0; k < 4; ++k) { const float la = bflo(wv[i][k]), bb = bfhi(wv[i][k]); h[k] = __builtin_amdgcn_exp2f(la) * h[k] + bb; sl[k] += la; }
.LBB0_1112:
	v_add_co_u32_e32 v10, vcc, 0xffff8800, v80
	s_movk_i32 s5, 0xa800
	s_nop 0
	v_addc_co_u32_e32 v11, vcc, -1, v81, vcc
	v_add_co_u32_e32 v12, vcc, 0xffff9000, v80
	s_add_i32 s1, s1, 16
	s_nop 0
	v_addc_co_u32_e32 v13, vcc, -1, v81, vcc
	v_add_co_u32_e32 v14, vcc, 0xffff9800, v80
	global_load_dwordx4 v[58:61], v[10:11], off
	global_load_dwordx4 v[46:49], v[12:13], off
	v_addc_co_u32_e32 v15, vcc, -1, v81, vcc
	v_add_co_u32_e32 v10, vcc, 0xffffa000, v80
	s_cmp_gt_u32 s1, 47
	s_nop 0
	v_addc_co_u32_e32 v11, vcc, -1, v81, vcc
	v_add_co_u32_e32 v12, vcc, s5, v80
	s_movk_i32 s5, 0xb000
	s_nop 0
	v_addc_co_u32_e32 v13, vcc, -1, v81, vcc
	global_load_dwordx4 v[62:65], v[14:15], off
	global_load_dwordx4 v[50:53], v[10:11], off
	v_add_co_u32_e32 v10, vcc, s5, v80
	s_movk_i32 s5, 0xb800
	s_nop 0
	v_addc_co_u32_e32 v11, vcc, -1, v81, vcc
	v_add_co_u32_e32 v14, vcc, s5, v80
	s_movk_i32 s5, 0xc000
	s_nop 0
	v_addc_co_u32_e32 v15, vcc, -1, v81, vcc
	global_load_dwordx4 v[54:57], v[12:13], off
	global_load_dwordx4 v[38:41], v[10:11], off
	v_add_co_u32_e32 v10, vcc, s5, v80
	s_movk_i32 s5, 0xc800
	s_nop 0
	v_addc_co_u32_e32 v11, vcc, -1, v81, vcc
	v_add_co_u32_e32 v12, vcc, s5, v80
	s_movk_i32 s5, 0xd000
	s_nop 0
	v_addc_co_u32_e32 v13, vcc, -1, v81, vcc
	global_load_dwordx4 v[42:45], v[14:15], off
	global_load_dwordx4 v[30:33], v[10:11], off
	v_add_co_u32_e32 v10, vcc, s5, v80
	s_movk_i32 s5, 0xd800
	s_nop 0
	v_addc_co_u32_e32 v11, vcc, -1, v81, vcc
	v_add_co_u32_e32 v14, vcc, s5, v80
	s_movk_i32 s5, 0xe000
	s_nop 0
	v_addc_co_u32_e32 v15, vcc, -1, v81, vcc
	global_load_dwordx4 v[34:37], v[12:13], off
	global_load_dwordx4 v[22:25], v[10:11], off
	v_add_co_u32_e32 v10, vcc, s5, v80
	s_movk_i32 s5, 0xe800
	s_nop 0
	v_addc_co_u32_e32 v11, vcc, -1, v81, vcc
	v_add_co_u32_e32 v12, vcc, s5, v80
	s_movk_i32 s5, 0xf000
	s_nop 0
	v_addc_co_u32_e32 v13, vcc, -1, v81, vcc
	global_load_dwordx4 v[26:29], v[14:15], off
	global_load_dwordx4 v[18:21], v[10:11], off
	v_add_co_u32_e32 v10, vcc, s5, v80
	s_movk_i32 s5, 0xf800
	s_nop 0
	v_addc_co_u32_e32 v11, vcc, -1, v81, vcc
	v_add_co_u32_e32 v14, vcc, s5, v80
	global_load_dwordx4 v[70:73], v[12:13], off
	global_load_dwordx4 v[66:69], v[10:11], off
	v_addc_co_u32_e32 v15, vcc, -1, v81, vcc
	global_load_dwordx4 v[10:13], v[14:15], off
	s_nop 0
	global_load_dwordx4 v[14:17], v[80:81], off
	v_lshl_add_u64 v[80:81], v[80:81], 0, s[96:97]
	s_waitcnt vmcnt(0) lgkmcnt(0)
	v_lshlrev_b32_e32 v85, 16, v59
	v_lshlrev_b32_e32 v84, 16, v58
	v_lshlrev_b32_e32 v87, 16, v61
	v_lshlrev_b32_e32 v86, 16, v60
	v_exp_f32_e32 v88, v84
	v_exp_f32_e32 v89, v85
	v_pk_add_f32 v[6:7], v[6:7], v[84:85]
	v_lshlrev_b32_e32 v85, 16, v47
	v_lshlrev_b32_e32 v84, 16, v46
	v_exp_f32_e32 v90, v86
	v_exp_f32_e32 v91, v87
	v_pk_add_f32 v[8:9], v[8:9], v[86:87]
	v_lshlrev_b32_e32 v87, 16, v49
	v_lshlrev_b32_e32 v86, 16, v48
	v_exp_f32_e32 v92, v84
	v_exp_f32_e32 v93, v85
	v_pk_add_f32 v[6:7], v[6:7], v[84:85]
	v_lshlrev_b32_e32 v85, 16, v63
	v_lshlrev_b32_e32 v84, 16, v62
	v_exp_f32_e32 v94, v86
	v_exp_f32_e32 v95, v87
	v_pk_add_f32 v[8:9], v[8:9], v[86:87]
	v_lshlrev_b32_e32 v87, 16, v65
	v_lshlrev_b32_e32 v86, 16, v64
	v_exp_f32_e32 v96, v84
	v_exp_f32_e32 v97, v85
	v_pk_add_f32 v[6:7], v[6:7], v[84:85]
	v_lshlrev_b32_e32 v85, 16, v51
	v_lshlrev_b32_e32 v84, 16, v50
	v_exp_f32_e32 v98, v86
	v_exp_f32_e32 v99, v87
	v_pk_add_f32 v[8:9], v[8:9], v[86:87]
	v_lshlrev_b32_e32 v87, 16, v53
	v_lshlrev_b32_e32 v86, 16, v52
	v_and_b32_e32 v59, 0xffff0000, v59
	v_and_b32_e32 v58, 0xffff0000, v58
	v_and_b32_e32 v61, 0xffff0000, v61
	v_and_b32_e32 v60, 0xffff0000, v60
	v_exp_f32_e32 v100, v84
	v_exp_f32_e32 v101, v85
	v_pk_add_f32 v[6:7], v[6:7], v[84:85]
	v_lshlrev_b32_e32 v85, 16, v55
	v_lshlrev_b32_e32 v84, 16, v54
	v_exp_f32_e32 v102, v86
	v_exp_f32_e32 v103, v87
	v_pk_add_f32 v[8:9], v[8:9], v[86:87]
	v_lshlrev_b32_e32 v87, 16, v57
	v_lshlrev_b32_e32 v86, 16, v56
	v_and_b32_e32 v47, 0xffff0000, v47
	v_and_b32_e32 v46, 0xffff0000, v46
	v_and_b32_e32 v49, 0xffff0000, v49
	v_and_b32_e32 v48, 0xffff0000, v48
	v_exp_f32_e32 v104, v84
	v_exp_f32_e32 v105, v85
	v_pk_fma_f32 v[2:3], v[2:3], v[88:89], v[58:59]
	v_pk_add_f32 v[6:7], v[6:7], v[84:85]
	v_exp_f32_e32 v58, v86
	v_exp_f32_e32 v59, v87
	v_pk_fma_f32 v[4:5], v[4:5], v[90:91], v[60:61]
	v_pk_add_f32 v[8:9], v[8:9], v[86:87]
	v_lshlrev_b32_e32 v85, 16, v39
	v_lshlrev_b32_e32 v84, 16, v38
	v_lshlrev_b32_e32 v87, 16, v41
	v_lshlrev_b32_e32 v86, 16, v40
	v_and_b32_e32 v63, 0xffff0000, v63
	v_and_b32_e32 v62, 0xffff0000, v62
	v_and_b32_e32 v65, 0xffff0000, v65
	v_and_b32_e32 v64, 0xffff0000, v64
	v_and_b32_e32 v60, 0xffff0000, v38
	v_and_b32_e32 v61, 0xffff0000, v39
	v_and_b32_e32 v38, 0xffff0000, v40
	v_and_b32_e32 v39, 0xffff0000, v41
	v_pk_fma_f32 v[2:3], v[2:3], v[92:93], v[46:47]
	v_pk_fma_f32 v[4:5], v[4:5], v[94:95], v[48:49]
	v_exp_f32_e32 v46, v84
	v_exp_f32_e32 v47, v85
	v_exp_f32_e32 v48, v86
	v_exp_f32_e32 v49, v87
	v_lshlrev_b32_e32 v40, 16, v42
	v_lshlrev_b32_e32 v41, 16, v43
	v_lshlrev_b32_e32 v88, 16, v44
	v_lshlrev_b32_e32 v89, 16, v45
	v_pk_add_f32 v[6:7], v[6:7], v[84:85]
	v_pk_add_f32 v[8:9], v[8:9], v[86:87]
	v_and_b32_e32 v51, 0xffff0000, v51
	v_and_b32_e32 v50, 0xffff0000, v50
	v_and_b32_e32 v53, 0xffff0000, v53
	v_and_b32_e32 v52, 0xffff0000, v52
	v_and_b32_e32 v85, 0xffff0000, v43
	v_and_b32_e32 v84, 0xffff0000, v42
	v_pk_fma_f32 v[2:3], v[2:3], v[96:97], v[62:63]
	v_pk_fma_f32 v[4:5], v[4:5], v[98:99], v[64:65]
	v_exp_f32_e32 v62, v40
	v_exp_f32_e32 v63, v41
	v_pk_add_f32 v[6:7], v[6:7], v[40:41]
	v_lshlrev_b32_e32 v41, 16, v31
	v_lshlrev_b32_e32 v40, 16, v30
	v_exp_f32_e32 v64, v88
; #define LAS __attribute__((address_space(3)))
; __device__ __forceinline__ float bflo(unsigned w) { return __uint_as_float(w << 16); }
; __device__ __forceinline__ float bfhi(unsigned w) { return __uint_as_float(w & 0xffff0000u); }
; __global__ void __launch_bounds__(512, 2) mega_fwd(Params P) {
;     ...
;                                 for (int i = 0; i < 16; ++i)
; #pragma unroll
;                                     for (int k = 0; k < 4; ++k) { const float la = bflo(wv[i][k]), bb = bfhi(wv[i][k]); h[k] = __builtin_amdgcn_exp2f(la) * h[k] + bb; sl[k] += la; }
;                             }
;                             __syncthreads();
;                             *(LAS f32x4*)(sA + jc * 64 + q * 4) = (f32x4){sl[0], sl[1], sl[2], sl[3]}; *(LAS f32x4*)(sB + jc * 64 + q * 4) = (f32x4){h[0], h[1], h[2], h[3]};
;                             __syncthreads();
;                             float hin[4] = {0.f, 0.f, 0.f, 0.f};
	v_exp_f32_e32 v65, v89
	v_pk_add_f32 v[8:9], v[8:9], v[88:89]
	v_lshlrev_b32_e32 v43, 16, v33
	v_lshlrev_b32_e32 v42, 16, v32
	v_and_b32_e32 v55, 0xffff0000, v55
	v_and_b32_e32 v54, 0xffff0000, v54
	v_and_b32_e32 v57, 0xffff0000, v57
	v_and_b32_e32 v56, 0xffff0000, v56
	v_pk_fma_f32 v[2:3], v[2:3], v[100:101], v[50:51]
	v_pk_fma_f32 v[4:5], v[4:5], v[102:103], v[52:53]
	v_exp_f32_e32 v50, v40
	v_exp_f32_e32 v51, v41
	v_pk_add_f32 v[6:7], v[6:7], v[40:41]
	v_lshlrev_b32_e32 v41, 16, v35
	v_lshlrev_b32_e32 v40, 16, v34
	v_exp_f32_e32 v52, v42
	v_exp_f32_e32 v53, v43
	v_pk_add_f32 v[8:9], v[8:9], v[42:43]
	v_lshlrev_b32_e32 v43, 16, v37
	v_lshlrev_b32_e32 v42, 16, v36
	v_pk_fma_f32 v[54:55], v[2:3], v[104:105], v[54:55]
	v_pk_fma_f32 v[4:5], v[4:5], v[58:59], v[56:57]
	v_exp_f32_e32 v56, v40
	v_exp_f32_e32 v57, v41
	v_pk_add_f32 v[6:7], v[6:7], v[40:41]
	v_lshlrev_b32_e32 v59, 16, v23
	v_lshlrev_b32_e32 v58, 16, v22
	v_and_b32_e32 v89, 0xffff0000, v23
	v_and_b32_e32 v88, 0xffff0000, v22
	v_exp_f32_e32 v90, v42
	v_exp_f32_e32 v91, v43
	v_pk_add_f32 v[8:9], v[8:9], v[42:43]
	v_lshlrev_b32_e32 v23, 16, v25
	v_lshlrev_b32_e32 v22, 16, v24
	v_and_b32_e32 v45, 0xffff0000, v45
	v_and_b32_e32 v44, 0xffff0000, v44
	v_and_b32_e32 v87, 0xffff0000, v37
	v_and_b32_e32 v86, 0xffff0000, v36
	v_and_b32_e32 v41, 0xffff0000, v25
	v_and_b32_e32 v40, 0xffff0000, v24
	v_and_b32_e32 v37, 0xffff0000, v27
	v_and_b32_e32 v36, 0xffff0000, v26
	v_and_b32_e32 v3, 0xffff0000, v29
	v_and_b32_e32 v2, 0xffff0000, v28
	v_exp_f32_e32 v92, v58
	v_exp_f32_e32 v93, v59
	v_pk_add_f32 v[6:7], v[6:7], v[58:59]
	v_lshlrev_b32_e32 v25, 16, v27
	v_lshlrev_b32_e32 v24, 16, v26
	v_pk_fma_f32 v[26:27], v[54:55], v[46:47], v[60:61]
	v_exp_f32_e32 v42, v22
	v_exp_f32_e32 v43, v23
	v_pk_add_f32 v[8:9], v[8:9], v[22:23]
	v_lshlrev_b32_e32 v23, 16, v29
	v_lshlrev_b32_e32 v22, 16, v28
	v_pk_fma_f32 v[28:29], v[4:5], v[48:49], v[38:39]
	v_and_b32_e32 v31, 0xffff0000, v31
	v_and_b32_e32 v30, 0xffff0000, v30
	v_and_b32_e32 v33, 0xffff0000, v33
	v_and_b32_e32 v32, 0xffff0000, v32
	v_exp_f32_e32 v38, v24
	v_exp_f32_e32 v39, v25
	v_pk_fma_f32 v[26:27], v[26:27], v[62:63], v[84:85]
	v_pk_add_f32 v[24:25], v[6:7], v[24:25]
	v_lshlrev_b32_e32 v47, 16, v19
	v_lshlrev_b32_e32 v46, 16, v18
	v_exp_f32_e32 v6, v22
	v_exp_f32_e32 v7, v23
	v_pk_fma_f32 v[28:29], v[28:29], v[64:65], v[44:45]
	v_pk_add_f32 v[44:45], v[8:9], v[22:23]
	v_lshlrev_b32_e32 v49, 16, v21
	v_lshlrev_b32_e32 v48, 16, v20
	v_and_b32_e32 v35, 0xffff0000, v35
	v_and_b32_e32 v34, 0xffff0000, v34
	v_and_b32_e32 v5, 0xffff0000, v19
	v_and_b32_e32 v4, 0xffff0000, v18
	v_pk_fma_f32 v[26:27], v[26:27], v[50:51], v[30:31]
	v_exp_f32_e32 v18, v46
	v_exp_f32_e32 v19, v47
	v_pk_add_f32 v[30:31], v[24:25], v[46:47]
	v_lshlrev_b32_e32 v47, 16, v71
	v_lshlrev_b32_e32 v46, 16, v70
	v_pk_fma_f32 v[32:33], v[28:29], v[52:53], v[32:33]
	v_exp_f32_e32 v22, v48
	v_exp_f32_e32 v23, v49
	v_pk_add_f32 v[44:45], v[44:45], v[48:49]
	v_lshlrev_b32_e32 v49, 16, v73
	v_lshlrev_b32_e32 v48, 16, v72
	v_pk_fma_f32 v[34:35], v[26:27], v[56:57], v[34:35]
	v_exp_f32_e32 v26, v46
	v_exp_f32_e32 v27, v47
	v_pk_add_f32 v[46:47], v[30:31], v[46:47]
	v_lshlrev_b32_e32 v53, 16, v67
	v_lshlrev_b32_e32 v52, 16, v66
	v_pk_fma_f32 v[54:55], v[32:33], v[90:91], v[86:87]
	v_exp_f32_e32 v30, v48
	v_exp_f32_e32 v31, v49
	v_pk_add_f32 v[48:49], v[44:45], v[48:49]
	v_lshlrev_b32_e32 v57, 16, v69
	v_lshlrev_b32_e32 v56, 16, v68
	v_pk_fma_f32 v[50:51], v[34:35], v[92:93], v[88:89]
	v_exp_f32_e32 v34, v52
	v_exp_f32_e32 v35, v53
	v_lshlrev_b32_e32 v59, 16, v11
	v_lshlrev_b32_e32 v58, 16, v10
	v_pk_fma_f32 v[42:43], v[54:55], v[42:43], v[40:41]
	v_exp_f32_e32 v40, v56
	v_exp_f32_e32 v41, v57
	v_pk_add_f32 v[54:55], v[48:49], v[56:57]
	v_lshlrev_b32_e32 v57, 16, v13
	v_lshlrev_b32_e32 v56, 16, v12
	v_and_b32_e32 v9, 0xffff0000, v21
	v_and_b32_e32 v8, 0xffff0000, v20
	v_pk_add_f32 v[52:53], v[46:47], v[52:53]
	v_lshlrev_b32_e32 v45, 16, v15
	v_lshlrev_b32_e32 v44, 16, v14
	v_lshlrev_b32_e32 v47, 16, v17
	v_lshlrev_b32_e32 v46, 16, v16
	v_exp_f32_e32 v48, v58
	v_exp_f32_e32 v49, v59
	v_pk_fma_f32 v[36:37], v[50:51], v[38:39], v[36:37]
	v_exp_f32_e32 v38, v56
	v_exp_f32_e32 v39, v57
	v_pk_fma_f32 v[2:3], v[42:43], v[6:7], v[2:3]
	v_and_b32_e32 v21, 0xffff0000, v71
	v_and_b32_e32 v20, 0xffff0000, v70
	v_and_b32_e32 v25, 0xffff0000, v73
	v_and_b32_e32 v24, 0xffff0000, v72
	v_pk_add_f32 v[52:53], v[52:53], v[58:59]
	v_exp_f32_e32 v58, v44
	v_exp_f32_e32 v59, v45
	v_pk_add_f32 v[50:51], v[54:55], v[56:57]
	v_exp_f32_e32 v54, v46
	v_exp_f32_e32 v55, v47
	v_pk_fma_f32 v[4:5], v[36:37], v[18:19], v[4:5]
	v_pk_fma_f32 v[2:3], v[2:3], v[22:23], v[8:9]
	v_and_b32_e32 v29, 0xffff0000, v67
	v_and_b32_e32 v28, 0xffff0000, v66
	v_and_b32_e32 v33, 0xffff0000, v69
	v_and_b32_e32 v32, 0xffff0000, v68
	v_pk_fma_f32 v[4:5], v[4:5], v[26:27], v[20:21]
	v_pk_fma_f32 v[2:3], v[2:3], v[30:31], v[24:25]
	v_and_b32_e32 v11, 0xffff0000, v11
	v_and_b32_e32 v10, 0xffff0000, v10
	v_and_b32_e32 v13, 0xffff0000, v13
	v_and_b32_e32 v12, 0xffff0000, v12
	v_pk_fma_f32 v[4:5], v[4:5], v[34:35], v[28:29]
	v_pk_fma_f32 v[2:3], v[2:3], v[40:41], v[32:33]
	v_and_b32_e32 v15, 0xffff0000, v15
	v_and_b32_e32 v14, 0xffff0000, v14
	v_and_b32_e32 v17, 0xffff0000, v17
	v_and_b32_e32 v16, 0xffff0000, v16
	v_pk_fma_f32 v[4:5], v[4:5], v[48:49], v[10:11]
	v_pk_fma_f32 v[10:11], v[2:3], v[38:39], v[12:13]
	v_pk_add_f32 v[6:7], v[52:53], v[44:45]
	v_pk_add_f32 v[8:9], v[50:51], v[46:47]
	v_pk_fma_f32 v[2:3], v[4:5], v[58:59], v[14:15]
	v_pk_fma_f32 v[4:5], v[10:11], v[54:55], v[16:17]
	s_cbranch_scc0 .LBB0_1112
	s_barrier
	ds_write_b128 v121, v[6:9]
	ds_write_b128 v121, v[2:5] offset:8192
	s_mov_b32 s1, 0
	v_mov_b32_e32 v2, 0
	v_mov_b32_e32 v10, v120
	v_mov_b32_e32 v3, 0
	v_mov_b32_e32 v5, 0
	v_mov_b32_e32 v4, 0
	s_waitcnt lgkmcnt(0)
	s_barrier
	s_branch .LBB0_1115

; __device__ __forceinline__ unsigned cvt_pk_bf16(float lo, float hi) { unsigned r; asm volatile("v_cvt_pk_bf16_f32 %0, %1, %2" : "=v"(r) : "v"(lo), "v"(hi)); return r; }
; __device__ __forceinline__ float bflo(unsigned w) { return __uint_as_float(w << 16); }
; __device__ __forceinline__ float bfhi(unsigned w) { return __uint_as_float(w & 0xffff0000u); }
; __device__ __forceinline__ float gelu_tanh(float x) { const float t = 1.5957691216057308f * (x + 0.044715f * x * x * x); return x * __builtin_amdgcn_rcpf(1.0f + __expf(-t)); }
; __global__ void __launch_bounds__(512, 2) mega_fwd(Params P) {
;     ...
;                             for (int t0 = 0; t0 < 64; t0 += 16) {
;                                 u32x4 wv[16]; u32x2 gv2[16];
; #pragma unroll
;                                 for (int i = 0; i < 16; ++i) { wv[i] = *(const u32x4*)(ab + (size_t)(t0 + i) * 512); gv2[i] = *(const u32x2*)(gp + (size_t)(t0 + i) * ZW); }
; #pragma unroll
;                                 for (int i = 0; i < 16; ++i) { float o4[4];
; #pragma unroll
;                                     for (int k = 0; k < 4; ++k) { const float la = bflo(wv[i][k]), bb = bfhi(wv[i][k]); h[k] = __builtin_amdgcn_exp2f(la) * h[k] + bb;
;                                         const unsigned gw = gv2[i][k >> 1]; const float gt = (k & 1) ? bfhi(gw) : bflo(gw); o4[k] = gelu_tanh(gt) * h[k]; }
;                                     u32x2 ow; ow.x = cvt_pk_bf16(o4[0], o4[1]); ow.y = cvt_pk_bf16(o4[2], o4[3]); *(u32x2*)(op + (size_t)(t0 + i) * 1024) = ow; }
.LBB0_1118:
	v_lshl_add_u64 v[2:3], s[2:3], 0, v[70:71]
	v_add_co_u32_e32 v4, vcc, 0x33800000, v2
	v_lshl_add_u64 v[82:83], s[2:3], 0, v[68:69]
	s_nop 0
	v_addc_co_u32_e32 v5, vcc, 0, v3, vcc
	v_add_co_u32_e32 v6, vcc, 0x15800000, v82
	global_load_dwordx4 v[54:57], v[4:5], off
	s_nop 0
	v_addc_co_u32_e32 v7, vcc, 0, v83, vcc
	global_load_dwordx2 v[94:95], v[6:7], off offset:3072
	global_load_dwordx4 v[58:61], v[4:5], off offset:2048
	v_add_co_u32_e32 v4, vcc, 0x15802000, v82
	s_mov_b32 s1, 0x33804000
	s_nop 0
	v_addc_co_u32_e32 v5, vcc, 0, v83, vcc
	global_load_dwordx2 v[114:115], v[4:5], off
	v_add_co_u32_e32 v4, vcc, 0x33801000, v2
	s_add_i32 s4, s4, 16
	s_nop 0
	v_addc_co_u32_e32 v5, vcc, 0, v3, vcc
	v_add_co_u32_e32 v6, vcc, 0x15803000, v82
	global_load_dwordx4 v[62:65], v[4:5], off
	s_nop 0
	v_addc_co_u32_e32 v7, vcc, 0, v83, vcc
	global_load_dwordx2 v[110:111], v[6:7], off offset:1024
	global_load_dwordx4 v[46:49], v[4:5], off offset:2048
	v_add_co_u32_e32 v4, vcc, 0x15804000, v82
	s_mov_b64 s[6:7], 0x14000
	s_nop 0
	v_addc_co_u32_e32 v5, vcc, 0, v83, vcc
	global_load_dwordx2 v[108:109], v[4:5], off offset:2048
	v_add_co_u32_e32 v4, vcc, 0x33802000, v2
	v_lshl_add_u64 v[68:69], v[68:69], 0, s[6:7]
	s_nop 0
	v_addc_co_u32_e32 v5, vcc, 0, v3, vcc
	v_add_co_u32_e32 v6, vcc, 0x15805000, v82
	global_load_dwordx4 v[50:53], v[4:5], off
	s_nop 0
	v_addc_co_u32_e32 v7, vcc, 0, v83, vcc
	global_load_dwordx2 v[106:107], v[6:7], off offset:3072
	global_load_dwordx4 v[42:45], v[4:5], off offset:2048
	v_add_co_u32_e32 v4, vcc, 0x15807000, v82
	v_lshl_add_u64 v[70:71], v[70:71], 0, s[96:97]
	s_nop 0
	v_addc_co_u32_e32 v5, vcc, 0, v83, vcc
	global_load_dwordx2 v[104:105], v[4:5], off
	v_add_co_u32_e32 v4, vcc, 0x33803000, v2
	s_cmp_gt_u32 s4, 47
	s_nop 0
	v_addc_co_u32_e32 v5, vcc, 0, v3, vcc
	v_add_co_u32_e32 v6, vcc, 0x15808000, v82
	global_load_dwordx4 v[34:37], v[4:5], off
	s_nop 0
	v_addc_co_u32_e32 v7, vcc, 0, v83, vcc
	global_load_dwordx2 v[102:103], v[6:7], off offset:1024
	global_load_dwordx4 v[22:25], v[4:5], off offset:2048
	v_add_co_u32_e32 v4, vcc, 0x15809000, v82
	s_waitcnt vmcnt(0) lgkmcnt(0)
	v_lshlrev_b32_e32 v0, 16, v54
	v_exp_f32_e32 v116, v0
	v_lshlrev_b32_e32 v0, 16, v94
	v_lshlrev_b32_e32 v125, 16, v58
	v_exp_f32_e32 v126, v125
	v_mul_f32_e32 v112, 0x3d372713, v0
	v_mul_f32_e32 v112, v112, v0
	v_fma_f32 v112, v112, v0, v0
	v_mul_f32_e32 v112, 0xbfcc422a, v112
	v_lshlrev_b32_e32 v125, 16, v114
	v_and_b32_e32 v114, 0xffff0000, v114
	v_mul_f32_e32 v128, 0x3d372713, v114
	v_mul_f32_e32 v128, v128, v114
	v_fma_f32 v128, v128, v114, v114
	v_mul_f32_e32 v128, 0xbfcc422a, v128
	v_mul_f32_e32 v128, 0x3fb8aa3b, v128
	v_exp_f32_e32 v128, v128
	v_mul_f32_e32 v112, 0x3fb8aa3b, v112
	v_exp_f32_e32 v112, v112
	v_mul_f32_e32 v127, 0x3d372713, v125
	v_add_f32_e32 v128, 1.0, v128
	v_rcp_f32_e32 v128, v128
	v_add_f32_e32 v112, 1.0, v112
	v_rcp_f32_e32 v112, v112
	v_mul_f32_e32 v127, v127, v125
	v_mul_f32_e32 v134, v128, v114
	v_lshlrev_b32_e32 v114, 16, v60
	v_exp_f32_e32 v128, v114
	v_lshlrev_b32_e32 v114, 16, v115
	v_mul_f32_e32 v129, 0x3d372713, v114
	v_mul_f32_e32 v129, v129, v114
	v_fma_f32 v129, v129, v114, v114
	v_mul_f32_e32 v129, 0xbfcc422a, v129
	v_mul_f32_e32 v129, 0x3fb8aa3b, v129
	v_exp_f32_e32 v129, v129
	v_mul_f32_e32 v123, v112, v0
	v_lshlrev_b32_e32 v0, 16, v55
	v_fma_f32 v127, v127, v125, v125
	v_add_f32_e32 v129, 1.0, v129
	v_rcp_f32_e32 v129, v129
	v_exp_f32_e32 v117, v0
	v_and_b32_e32 v0, 0xffff0000, v94
	v_mul_f32_e32 v127, 0xbfcc422a, v127
	v_mul_f32_e32 v135, v129, v114
	v_lshlrev_b32_e32 v114, 16, v61
	v_exp_f32_e32 v129, v114
	v_and_b32_e32 v114, 0xffff0000, v115
	v_mul_f32_e32 v115, 0x3d372713, v114
	v_mul_f32_e32 v115, v115, v114
	v_fma_f32 v115, v115, v114, v114
	v_mul_f32_e32 v115, 0xbfcc422a, v115
	v_mul_f32_e32 v115, 0x3fb8aa3b, v115
	v_exp_f32_e32 v115, v115
	v_mul_f32_e32 v94, 0x3d372713, v0
	v_mul_f32_e32 v127, 0x3fb8aa3b, v127
	v_mul_f32_e32 v94, v94, v0
	v_add_f32_e32 v115, 1.0, v115
	v_rcp_f32_e32 v115, v115
	v_exp_f32_e32 v127, v127
	v_fma_f32 v94, v94, v0, v0
	v_mul_f32_e32 v94, 0xbfcc422a, v94
	v_mul_f32_e32 v136, v115, v114
	v_lshlrev_b32_e32 v115, 16, v110
	v_mul_f32_e32 v130, 0x3d372713, v115
	v_mul_f32_e32 v130, v130, v115
	v_fma_f32 v130, v130, v115, v115
	v_mul_f32_e32 v130, 0xbfcc422a, v130
	v_mul_f32_e32 v130, 0x3fb8aa3b, v130
	v_exp_f32_e32 v130, v130
	v_and_b32_e32 v110, 0xffff0000, v110
	v_mul_f32_e32 v94, 0x3fb8aa3b, v94
	v_exp_f32_e32 v94, v94
	v_add_f32_e32 v130, 1.0, v130
	v_rcp_f32_e32 v130, v130
	v_add_f32_e32 v127, 1.0, v127
	v_rcp_f32_e32 v127, v127
	v_add_f32_e32 v94, 1.0, v94
	v_mul_f32_e32 v137, v130, v115
	v_mul_f32_e32 v130, 0x3d372713, v110
	v_mul_f32_e32 v130, v130, v110
	v_fma_f32 v130, v130, v110, v110
	v_mul_f32_e32 v130, 0xbfcc422a, v130
	v_mul_f32_e32 v130, 0x3fb8aa3b, v130
	v_exp_f32_e32 v130, v130
	v_rcp_f32_e32 v94, v94
	v_mul_f32_e32 v125, v127, v125
	v_lshlrev_b32_e32 v127, 16, v59
	v_add_f32_e32 v130, 1.0, v130
	v_rcp_f32_e32 v130, v130
	v_exp_f32_e32 v127, v127
	v_lshlrev_b32_e32 v114, 16, v62
	v_lshlrev_b32_e32 v115, 16, v63
	v_mul_f32_e32 v138, v130, v110
	v_lshlrev_b32_e32 v110, 16, v64
	v_exp_f32_e32 v130, v110
	v_lshlrev_b32_e32 v110, 16, v111
	v_mul_f32_e32 v131, 0x3d372713, v110
	v_mul_f32_e32 v131, v131, v110
	v_fma_f32 v131, v131, v110, v110
	v_mul_f32_e32 v131, 0xbfcc422a, v131
	v_mul_f32_e32 v131, 0x3fb8aa3b, v131
	v_exp_f32_e32 v131, v131
	v_exp_f32_e32 v114, v114
	v_exp_f32_e32 v115, v115
	v_and_b32_e32 v55, 0xffff0000, v55
	v_add_f32_e32 v131, 1.0, v131
	v_rcp_f32_e32 v131, v131
	v_and_b32_e32 v54, 0xffff0000, v54
	v_mul_f32_e32 v124, v94, v0
; __device__ __forceinline__ unsigned cvt_pk_bf16(float lo, float hi) { unsigned r; asm volatile("v_cvt_pk_bf16_f32 %0, %1, %2" : "=v"(r) : "v"(lo), "v"(hi)); return r; }
; __device__ __forceinline__ float bflo(unsigned w) { return __uint_as_float(w << 16); }
; __device__ __forceinline__ float bfhi(unsigned w) { return __uint_as_float(w & 0xffff0000u); }
; __device__ __forceinline__ float gelu_tanh(float x) { const float t = 1.5957691216057308f * (x + 0.044715f * x * x * x); return x * __builtin_amdgcn_rcpf(1.0f + __expf(-t)); }
; __global__ void __launch_bounds__(512, 2) mega_fwd(Params P) {
;     ...
;                             for (int t0 = 0; t0 < 64; t0 += 16) {
;                                 u32x4 wv[16]; u32x2 gv2[16];
; #pragma unroll
;                                 for (int i = 0; i < 16; ++i) { wv[i] = *(const u32x4*)(ab + (size_t)(t0 + i) * 512); gv2[i] = *(const u32x2*)(gp + (size_t)(t0 + i) * ZW); }
; #pragma unroll
;                                 for (int i = 0; i < 16; ++i) { float o4[4];
; #pragma unroll
;                                     for (int k = 0; k < 4; ++k) { const float la = bflo(wv[i][k]), bb = bfhi(wv[i][k]); h[k] = __builtin_amdgcn_exp2f(la) * h[k] + bb;
;                                         const unsigned gw = gv2[i][k >> 1]; const float gt = (k & 1) ? bfhi(gw) : bflo(gw); o4[k] = gelu_tanh(gt) * h[k]; }
;                                     u32x2 ow; ow.x = cvt_pk_bf16(o4[0], o4[1]); ow.y = cvt_pk_bf16(o4[2], o4[3]); *(u32x2*)(op + (size_t)(t0 + i) * 1024) = ow; }
	v_pk_fma_f32 v[54:55], v[72:73], v[116:117], v[54:55]
	v_mul_f32_e32 v139, v131, v110
	v_lshlrev_b32_e32 v110, 16, v65
	v_exp_f32_e32 v131, v110
	v_and_b32_e32 v110, 0xffff0000, v111
	v_mul_f32_e32 v111, 0x3d372713, v110
	v_mul_f32_e32 v111, v111, v110
	v_fma_f32 v111, v111, v110, v110
	v_mul_f32_e32 v111, 0xbfcc422a, v111
	v_mul_f32_e32 v111, 0x3fb8aa3b, v111
	v_exp_f32_e32 v111, v111
	v_and_b32_e32 v59, 0xffff0000, v59
	v_and_b32_e32 v58, 0xffff0000, v58
	v_mul_f32_e32 v72, v54, v123
	v_add_f32_e32 v111, 1.0, v111
	v_rcp_f32_e32 v111, v111
	v_mul_f32_e32 v73, v55, v124
	v_pk_fma_f32 v[54:55], v[54:55], v[126:127], v[58:59]
	v_and_b32_e32 v59, 0xffff0000, v63
	v_mul_f32_e32 v140, v111, v110
	v_lshlrev_b32_e32 v110, 16, v46
	v_exp_f32_e32 v132, v110
	v_lshlrev_b32_e32 v110, 16, v108
	v_mul_f32_e32 v111, 0x3d372713, v110
	v_mul_f32_e32 v111, v111, v110
	v_fma_f32 v111, v111, v110, v110
	v_mul_f32_e32 v111, 0xbfcc422a, v111
	v_mul_f32_e32 v111, 0x3fb8aa3b, v111
	v_exp_f32_e32 v111, v111
	v_and_b32_e32 v108, 0xffff0000, v108
	v_and_b32_e32 v58, 0xffff0000, v62
	v_mul_f32_e32 v116, v54, v125
	v_add_f32_e32 v111, 1.0, v111
	v_rcp_f32_e32 v111, v111
	v_mul_f32_e32 v117, v55, v134
	v_pk_fma_f32 v[54:55], v[54:55], v[114:115], v[58:59]
	v_and_b32_e32 v46, 0xffff0000, v46
	v_mul_f32_e32 v141, v111, v110
	v_lshlrev_b32_e32 v110, 16, v47
	v_exp_f32_e32 v133, v110
	v_mul_f32_e32 v110, 0x3d372713, v108
	v_mul_f32_e32 v110, v110, v108
	v_fma_f32 v110, v110, v108, v108
	v_mul_f32_e32 v110, 0xbfcc422a, v110
	v_mul_f32_e32 v110, 0x3fb8aa3b, v110
	v_exp_f32_e32 v110, v110
	v_and_b32_e32 v47, 0xffff0000, v47
	v_lshlrev_b32_e32 v0, 16, v56
	v_pk_fma_f32 v[46:47], v[54:55], v[132:133], v[46:47]
	v_add_f32_e32 v110, 1.0, v110
	v_rcp_f32_e32 v110, v110
	v_exp_f32_e32 v112, v0
	v_lshlrev_b32_e32 v0, 16, v95
	v_mul_f32_e32 v114, v46, v141
	v_mul_f32_e32 v142, v110, v108
	v_lshlrev_b32_e32 v108, 16, v48
	v_exp_f32_e32 v110, v108
	v_lshlrev_b32_e32 v108, 16, v109
	v_mul_f32_e32 v111, 0x3d372713, v108
	v_mul_f32_e32 v111, v111, v108
	v_fma_f32 v111, v111, v108, v108
	v_mul_f32_e32 v111, 0xbfcc422a, v111
	v_mul_f32_e32 v111, 0x3fb8aa3b, v111
	v_exp_f32_e32 v111, v111
	v_mul_f32_e32 v115, v47, v142
	v_mul_f32_e32 v94, 0x3d372713, v0
	v_mul_f32_e32 v94, v94, v0
	v_add_f32_e32 v111, 1.0, v111
	v_rcp_f32_e32 v111, v111
	v_fma_f32 v94, v94, v0, v0
	v_mul_f32_e32 v94, 0xbfcc422a, v94
	v_mul_f32_e32 v94, 0x3fb8aa3b, v94
	v_mul_f32_e32 v143, v111, v108
	v_lshlrev_b32_e32 v108, 16, v49
	v_exp_f32_e32 v111, v108
	v_and_b32_e32 v108, 0xffff0000, v109
	v_mul_f32_e32 v109, 0x3d372713, v108
	v_mul_f32_e32 v109, v109, v108
	v_fma_f32 v109, v109, v108, v108
	v_mul_f32_e32 v109, 0xbfcc422a, v109
	v_mul_f32_e32 v109, 0x3fb8aa3b, v109
	v_exp_f32_e32 v109, v109
	v_exp_f32_e32 v94, v94
	v_addc_co_u32_e32 v5, vcc, 0, v83, vcc
	v_add_f32_e32 v109, 1.0, v109
	v_rcp_f32_e32 v109, v109
	global_load_dwordx2 v[98:99], v[4:5], off offset:2048
	v_add_co_u32_e32 v4, vcc, s1, v2
	v_mul_f32_e32 v144, v109, v108
	v_lshlrev_b32_e32 v109, 16, v106
	v_mul_f32_e32 v145, 0x3d372713, v109
	v_mul_f32_e32 v145, v145, v109
	v_fma_f32 v145, v145, v109, v109
	v_mul_f32_e32 v145, 0xbfcc422a, v145
	v_mul_f32_e32 v145, 0x3fb8aa3b, v145
	v_exp_f32_e32 v145, v145
	v_lshlrev_b32_e32 v108, 16, v50
	v_exp_f32_e32 v108, v108
	v_and_b32_e32 v50, 0xffff0000, v50
	v_add_f32_e32 v145, 1.0, v145
	v_rcp_f32_e32 v145, v145
	v_addc_co_u32_e32 v5, vcc, 0, v3, vcc
	v_add_f32_e32 v94, 1.0, v94
	v_mul_f32_e32 v145, v145, v109
	v_lshlrev_b32_e32 v109, 16, v51
	v_exp_f32_e32 v109, v109
	v_and_b32_e32 v51, 0xffff0000, v51
	v_add_co_u32_e32 v6, vcc, 0x1580a000, v82
	v_pk_fma_f32 v[46:47], v[46:47], v[108:109], v[50:51]
	v_and_b32_e32 v50, 0xffff0000, v106
	v_mul_f32_e32 v51, 0x3d372713, v50
	v_mul_f32_e32 v51, v51, v50
	v_fma_f32 v51, v51, v50, v50
	v_mul_f32_e32 v51, 0xbfcc422a, v51
	v_mul_f32_e32 v51, 0x3fb8aa3b, v51
	v_exp_f32_e32 v51, v51
	v_rcp_f32_e32 v94, v94
	v_addc_co_u32_e32 v7, vcc, 0, v83, vcc
	v_add_f32_e32 v51, 1.0, v51
	v_rcp_f32_e32 v51, v51
	global_load_dwordx4 v[30:33], v[4:5], off
	global_load_dwordx2 v[100:101], v[6:7], off offset:3072
	global_load_dwordx4 v[26:29], v[4:5], off offset:2048
	v_add_co_u32_e32 v4, vcc, 0x1580c000, v82
	v_mul_f32_e32 v0, v94, v0
	s_nop 0
	v_addc_co_u32_e32 v5, vcc, 0, v83, vcc
	global_load_dwordx2 v[96:97], v[4:5], off
	v_add_co_u32_e32 v4, vcc, 0x33805000, v2
	v_lshlrev_b32_e32 v94, 16, v57
	v_mul_f32_e32 v50, v51, v50
	v_lshlrev_b32_e32 v51, 16, v107
	v_addc_co_u32_e32 v5, vcc, 0, v3, vcc
	v_exp_f32_e32 v113, v94
	v_and_b32_e32 v94, 0xffff0000, v95
	v_mul_f32_e32 v62, v54, v137
	v_mul_f32_e32 v54, 0x3d372713, v51
	v_add_co_u32_e32 v6, vcc, 0x1580d000, v82
	v_mul_f32_e32 v95, 0x3d372713, v94
	v_mul_f32_e32 v54, v54, v51
	v_addc_co_u32_e32 v7, vcc, 0, v83, vcc
	v_mul_f32_e32 v95, v95, v94
	v_fma_f32 v54, v54, v51, v51
	global_load_dwordx4 v[38:41], v[4:5], off
	global_load_dwordx2 v[92:93], v[6:7], off offset:1024
	s_nop 0
	global_load_dwordx4 v[6:9], v[4:5], off offset:2048
	v_add_co_u32_e32 v4, vcc, 0x1580e000, v82
	v_fma_f32 v95, v95, v94, v94
	v_mul_f32_e32 v54, 0xbfcc422a, v54
	v_addc_co_u32_e32 v5, vcc, 0, v83, vcc
	v_mul_f32_e32 v95, 0xbfcc422a, v95
	v_mul_f32_e32 v54, 0x3fb8aa3b, v54
	global_load_dwordx2 v[90:91], v[4:5], off offset:2048
	v_add_co_u32_e32 v4, vcc, 0x33806000, v2
	v_mul_f32_e32 v95, 0x3fb8aa3b, v95
	v_exp_f32_e32 v54, v54
	v_addc_co_u32_e32 v5, vcc, 0, v3, vcc
	v_exp_f32_e32 v95, v95
	v_add_co_u32_e32 v14, vcc, 0x1580f000, v82
	global_load_dwordx4 v[10:13], v[4:5], off
	s_nop 0
	v_addc_co_u32_e32 v15, vcc, 0, v83, vcc
	global_load_dwordx2 v[88:89], v[14:15], off offset:3072
; __device__ __forceinline__ unsigned cvt_pk_bf16(float lo, float hi) { unsigned r; asm volatile("v_cvt_pk_bf16_f32 %0, %1, %2" : "=v"(r) : "v"(lo), "v"(hi)); return r; }
; __device__ __forceinline__ float bflo(unsigned w) { return __uint_as_float(w << 16); }
; __device__ __forceinline__ float bfhi(unsigned w) { return __uint_as_float(w & 0xffff0000u); }
; __device__ __forceinline__ float gelu_tanh(float x) { const float t = 1.5957691216057308f * (x + 0.044715f * x * x * x); return x * __builtin_amdgcn_rcpf(1.0f + __expf(-t)); }
; __global__ void __launch_bounds__(512, 2) mega_fwd(Params P) {
;     ...
;                             for (int t0 = 0; t0 < 64; t0 += 16) {
;                                 u32x4 wv[16]; u32x2 gv2[16];
; #pragma unroll
;                                 for (int i = 0; i < 16; ++i) { wv[i] = *(const u32x4*)(ab + (size_t)(t0 + i) * 512); gv2[i] = *(const u32x2*)(gp + (size_t)(t0 + i) * ZW); }
; #pragma unroll
;                                 for (int i = 0; i < 16; ++i) { float o4[4];
; #pragma unroll
;                                     for (int k = 0; k < 4; ++k) { const float la = bflo(wv[i][k]), bb = bfhi(wv[i][k]); h[k] = __builtin_amdgcn_exp2f(la) * h[k] + bb;
;                                         const unsigned gw = gv2[i][k >> 1]; const float gt = (k & 1) ? bfhi(gw) : bflo(gw); o4[k] = gelu_tanh(gt) * h[k]; }
;                                     u32x2 ow; ow.x = cvt_pk_bf16(o4[0], o4[1]); ow.y = cvt_pk_bf16(o4[2], o4[3]); *(u32x2*)(op + (size_t)(t0 + i) * 1024) = ow; }
	s_nop 0
	global_load_dwordx4 v[14:17], v[4:5], off offset:2048
	v_add_co_u32_e32 v4, vcc, 0x15811000, v82
	v_add_f32_e32 v54, 1.0, v54
	s_nop 0
	v_addc_co_u32_e32 v5, vcc, 0, v83, vcc
	v_add_f32_e32 v95, 1.0, v95
	v_rcp_f32_e32 v54, v54
	v_add_co_u32_e32 v2, vcc, 0x33807000, v2
	v_rcp_f32_e32 v95, v95
	s_nop 0
	v_addc_co_u32_e32 v3, vcc, 0, v3, vcc
	global_load_dwordx2 v[86:87], v[4:5], off
	global_load_dwordx4 v[18:21], v[2:3], off
	v_add_co_u32_e32 v4, vcc, 0x15812000, v82
	v_mul_f32_e32 v63, v55, v138
	s_nop 0
	v_addc_co_u32_e32 v5, vcc, 0, v83, vcc
	v_mul_f32_e32 v109, v54, v51
	v_and_b32_e32 v55, 0xffff0000, v57
	v_and_b32_e32 v54, 0xffff0000, v56
	v_add_co_u32_e32 v82, vcc, 0x15813000, v82
	v_mul_f32_e32 v122, v95, v94
	v_pk_fma_f32 v[54:55], v[80:81], v[112:113], v[54:55]
	v_addc_co_u32_e32 v83, vcc, 0, v83, vcc
	v_lshl_add_u64 v[94:95], s[2:3], 0, v[66:67]
	v_mul_f32_e32 v56, v55, v122
	v_and_b32_e32 v59, 0xffff0000, v61
	v_and_b32_e32 v58, 0xffff0000, v60
	global_load_dwordx2 v[84:85], v[4:5], off offset:1024
	s_nop 0
	global_load_dwordx4 v[2:5], v[2:3], off offset:2048
	v_mul_f32_e32 v106, v47, v50
	global_load_dwordx2 v[82:83], v[82:83], off offset:2048
	v_cvt_pk_bf16_f32 v72, v72, v73
	v_lshlrev_b32_e32 v50, 16, v52
	v_lshlrev_b32_e32 v51, 16, v53
	v_mul_f32_e32 v0, v54, v0
	v_cvt_pk_bf16_f32 v73, v0, v56
	v_add_co_u32_e32 v56, vcc, s58, v94
	v_pk_fma_f32 v[54:55], v[54:55], v[128:129], v[58:59]
	v_exp_f32_e32 v50, v50
	v_exp_f32_e32 v51, v51
	v_addc_co_u32_e32 v57, vcc, 0, v95, vcc
	v_mul_f32_e32 v59, v55, v136
	global_store_dwordx2 v[56:57], v[72:73], off offset:1024
	v_mul_f32_e32 v0, v54, v135
	v_cvt_pk_bf16_f32 v58, v116, v117
	v_cvt_pk_bf16_f32 v59, v0, v59
	global_store_dwordx2 v[56:57], v[58:59], off offset:3072
	v_and_b32_e32 v57, 0xffff0000, v65
	v_and_b32_e32 v56, 0xffff0000, v64
	v_pk_fma_f32 v[54:55], v[54:55], v[130:131], v[56:57]
	v_and_b32_e32 v49, 0xffff0000, v49
	v_and_b32_e32 v48, 0xffff0000, v48
	v_mul_f32_e32 v0, v54, v139
	v_mul_f32_e32 v57, v55, v140
	v_pk_fma_f32 v[48:49], v[54:55], v[110:111], v[48:49]
	v_and_b32_e32 v53, 0xffff0000, v53
	v_and_b32_e32 v52, 0xffff0000, v52
	v_cvt_pk_bf16_f32 v56, v62, v63
	v_cvt_pk_bf16_f32 v57, v0, v57
	v_mul_f32_e32 v0, v48, v143
	v_pk_fma_f32 v[52:53], v[48:49], v[50:51], v[52:53]
	v_and_b32_e32 v48, 0xffff0000, v107
	v_mul_f32_e32 v55, v49, v144
	v_mul_f32_e32 v49, 0x3d372713, v48
	v_mul_f32_e32 v49, v49, v48
	v_fma_f32 v49, v49, v48, v48
	v_mul_f32_e32 v49, 0xbfcc422a, v49
	v_mul_f32_e32 v49, 0x3fb8aa3b, v49
	v_exp_f32_e32 v49, v49
	s_mov_b32 s1, 0x2b801000
	v_add_co_u32_e32 v58, vcc, s1, v94
	v_add_f32_e32 v49, 1.0, v49
	v_rcp_f32_e32 v49, v49
	v_addc_co_u32_e32 v59, vcc, 0, v95, vcc
	global_store_dwordx2 v[58:59], v[56:57], off offset:1024
	v_mul_f32_e32 v48, v49, v48
	v_cvt_pk_bf16_f32 v54, v114, v115
	v_cvt_pk_bf16_f32 v55, v0, v55
	v_mul_f32_e32 v0, v52, v109
	v_mul_f32_e32 v49, v53, v48
	v_mul_f32_e32 v108, v46, v145
	global_store_dwordx2 v[58:59], v[54:55], off offset:3072
	v_cvt_pk_bf16_f32 v48, v108, v106
	v_cvt_pk_bf16_f32 v49, v0, v49
	v_lshlrev_b32_e32 v0, 16, v42
	v_exp_f32_e32 v62, v0
	v_lshlrev_b32_e32 v0, 16, v104
	v_and_b32_e32 v60, 0xffff0000, v42
	v_mul_f32_e32 v42, 0x3d372713, v0
	v_mul_f32_e32 v42, v42, v0
	v_fma_f32 v42, v42, v0, v0
	v_mul_f32_e32 v42, 0xbfcc422a, v42
	v_mul_f32_e32 v42, 0x3fb8aa3b, v42
	v_exp_f32_e32 v42, v42
	v_and_b32_e32 v61, 0xffff0000, v43
	v_and_b32_e32 v56, 0xffff0000, v44
	v_and_b32_e32 v57, 0xffff0000, v45
	v_add_f32_e32 v42, 1.0, v42
	v_rcp_f32_e32 v42, v42
	s_mov_b32 s1, 0x2b802000
	v_add_co_u32_e32 v54, vcc, s1, v94
	v_mul_f32_e32 v0, v42, v0
	v_lshlrev_b32_e32 v42, 16, v43
	v_exp_f32_e32 v63, v42
	v_and_b32_e32 v42, 0xffff0000, v104
	v_mul_f32_e32 v43, 0x3d372713, v42
	v_mul_f32_e32 v43, v43, v42
	v_fma_f32 v43, v43, v42, v42
	v_mul_f32_e32 v43, 0xbfcc422a, v43
	v_mul_f32_e32 v43, 0x3fb8aa3b, v43
	v_exp_f32_e32 v43, v43
	v_addc_co_u32_e32 v55, vcc, 0, v95, vcc
	global_store_dwordx2 v[54:55], v[48:49], off offset:1024
	v_add_f32_e32 v43, 1.0, v43
	v_rcp_f32_e32 v43, v43
	v_pk_fma_f32 v[46:47], v[46:47], v[62:63], v[60:61]
	s_mov_b32 s1, 0x2b803000
	v_mul_f32_e32 v0, v46, v0
	v_mul_f32_e32 v104, v43, v42
	v_lshlrev_b32_e32 v42, 16, v44
	v_exp_f32_e32 v58, v42
	v_lshlrev_b32_e32 v42, 16, v105
	v_mul_f32_e32 v43, 0x3d372713, v42
	v_mul_f32_e32 v43, v43, v42
	v_fma_f32 v43, v43, v42, v42
	v_mul_f32_e32 v43, 0xbfcc422a, v43
	v_mul_f32_e32 v43, 0x3fb8aa3b, v43
	v_exp_f32_e32 v43, v43
	v_mul_f32_e32 v60, v47, v104
	v_cvt_pk_bf16_f32 v60, v0, v60
	s_waitcnt vmcnt(0) lgkmcnt(0)
; __device__ __forceinline__ unsigned cvt_pk_bf16(float lo, float hi) { unsigned r; asm volatile("v_cvt_pk_bf16_f32 %0, %1, %2" : "=v"(r) : "v"(lo), "v"(hi)); return r; }
; __device__ __forceinline__ float bflo(unsigned w) { return __uint_as_float(w << 16); }
; __device__ __forceinline__ float bfhi(unsigned w) { return __uint_as_float(w & 0xffff0000u); }
; __device__ __forceinline__ float gelu_tanh(float x) { const float t = 1.5957691216057308f * (x + 0.044715f * x * x * x); return x * __builtin_amdgcn_rcpf(1.0f + __expf(-t)); }
; __global__ void __launch_bounds__(512, 2) mega_fwd(Params P) {
;     ...
;                             for (int t0 = 0; t0 < 64; t0 += 16) {
;                                 u32x4 wv[16]; u32x2 gv2[16];
; #pragma unroll
;                                 for (int i = 0; i < 16; ++i) { wv[i] = *(const u32x4*)(ab + (size_t)(t0 + i) * 512); gv2[i] = *(const u32x2*)(gp + (size_t)(t0 + i) * ZW); }
; #pragma unroll
;                                 for (int i = 0; i < 16; ++i) { float o4[4];
; #pragma unroll
;                                     for (int k = 0; k < 4; ++k) { const float la = bflo(wv[i][k]), bb = bfhi(wv[i][k]); h[k] = __builtin_amdgcn_exp2f(la) * h[k] + bb;
;                                         const unsigned gw = gv2[i][k >> 1]; const float gt = (k & 1) ? bfhi(gw) : bflo(gw); o4[k] = gelu_tanh(gt) * h[k]; }
;                                     u32x2 ow; ow.x = cvt_pk_bf16(o4[0], o4[1]); ow.y = cvt_pk_bf16(o4[2], o4[3]); *(u32x2*)(op + (size_t)(t0 + i) * 1024) = ow; }
	v_and_b32_e32 v0, 0xffff0000, v92
	v_add_f32_e32 v43, 1.0, v43
	v_rcp_f32_e32 v43, v43
	v_lshl_add_u64 v[66:67], v[66:67], 0, s[96:97]
	v_mul_f32_e32 v106, v43, v42
	v_lshlrev_b32_e32 v42, 16, v45
	v_exp_f32_e32 v59, v42
	v_and_b32_e32 v42, 0xffff0000, v105
	v_mul_f32_e32 v43, 0x3d372713, v42
	v_mul_f32_e32 v43, v43, v42
	v_fma_f32 v43, v43, v42, v42
	v_mul_f32_e32 v43, 0xbfcc422a, v43
	v_mul_f32_e32 v43, 0x3fb8aa3b, v43
	v_exp_f32_e32 v43, v43
	s_nop 0
	v_add_f32_e32 v43, 1.0, v43
	v_rcp_f32_e32 v43, v43
	s_nop 0
	v_mul_f32_e32 v105, v43, v42
	v_lshlrev_b32_e32 v42, 16, v34
	v_exp_f32_e32 v72, v42
	v_lshlrev_b32_e32 v42, 16, v102
	v_mul_f32_e32 v43, 0x3d372713, v42
	v_mul_f32_e32 v43, v43, v42
	v_fma_f32 v43, v43, v42, v42
	v_mul_f32_e32 v43, 0xbfcc422a, v43
	v_mul_f32_e32 v43, 0x3fb8aa3b, v43
	v_exp_f32_e32 v43, v43
	v_and_b32_e32 v34, 0xffff0000, v34
	v_add_f32_e32 v43, 1.0, v43
	v_rcp_f32_e32 v43, v43
	s_nop 0
	v_mul_f32_e32 v107, v43, v42
	v_lshlrev_b32_e32 v42, 16, v35
	v_exp_f32_e32 v73, v42
	v_and_b32_e32 v42, 0xffff0000, v102
	v_mul_f32_e32 v43, 0x3d372713, v42
	v_mul_f32_e32 v43, v43, v42
	v_fma_f32 v43, v43, v42, v42
	v_mul_f32_e32 v43, 0xbfcc422a, v43
	v_mul_f32_e32 v43, 0x3fb8aa3b, v43
	v_exp_f32_e32 v43, v43
	v_and_b32_e32 v35, 0xffff0000, v35
	v_pk_fma_f32 v[34:35], v[46:47], v[72:73], v[34:35]
	v_add_f32_e32 v43, 1.0, v43
	v_rcp_f32_e32 v43, v43
	v_mul_f32_e32 v47, v34, v107
	v_mul_f32_e32 v108, v43, v42
	v_lshlrev_b32_e32 v42, 16, v36
	v_exp_f32_e32 v80, v42
	v_lshlrev_b32_e32 v42, 16, v103
	v_mul_f32_e32 v43, 0x3d372713, v42
	v_mul_f32_e32 v43, v43, v42
	v_fma_f32 v43, v43, v42, v42
	v_mul_f32_e32 v43, 0xbfcc422a, v43
	v_mul_f32_e32 v43, 0x3fb8aa3b, v43
	v_exp_f32_e32 v43, v43
	v_mul_f32_e32 v62, v35, v108
	v_and_b32_e32 v36, 0xffff0000, v36
	v_add_f32_e32 v43, 1.0, v43
	v_rcp_f32_e32 v43, v43
	s_nop 0
	v_mul_f32_e32 v109, v43, v42
	v_lshlrev_b32_e32 v42, 16, v37
	v_exp_f32_e32 v81, v42
	v_and_b32_e32 v42, 0xffff0000, v103
	v_mul_f32_e32 v43, 0x3d372713, v42
	v_mul_f32_e32 v43, v43, v42
	v_fma_f32 v43, v43, v42, v42
	v_mul_f32_e32 v43, 0xbfcc422a, v43
	v_mul_f32_e32 v43, 0x3fb8aa3b, v43
	v_exp_f32_e32 v43, v43
	v_and_b32_e32 v37, 0xffff0000, v37
	v_add_f32_e32 v43, 1.0, v43
	v_rcp_f32_e32 v43, v43
	s_nop 0
	v_mul_f32_e32 v110, v43, v42
	v_lshlrev_b32_e32 v42, 16, v22
	v_exp_f32_e32 v102, v42
	v_lshlrev_b32_e32 v42, 16, v98
	v_mul_f32_e32 v43, 0x3d372713, v42
	v_mul_f32_e32 v43, v43, v42
	v_fma_f32 v43, v43, v42, v42
	v_mul_f32_e32 v43, 0xbfcc422a, v43
	v_mul_f32_e32 v43, 0x3fb8aa3b, v43
	v_exp_f32_e32 v43, v43
	v_and_b32_e32 v22, 0xffff0000, v22
	v_add_f32_e32 v43, 1.0, v43
	v_rcp_f32_e32 v43, v43
	s_nop 0
	v_mul_f32_e32 v111, v43, v42
	v_lshlrev_b32_e32 v42, 16, v23
	v_exp_f32_e32 v103, v42
	v_and_b32_e32 v42, 0xffff0000, v98
	v_mul_f32_e32 v43, 0x3d372713, v42
	v_mul_f32_e32 v43, v43, v42
	v_fma_f32 v43, v43, v42, v42
	v_mul_f32_e32 v43, 0xbfcc422a, v43
	v_mul_f32_e32 v43, 0x3fb8aa3b, v43
	v_exp_f32_e32 v43, v43
	v_and_b32_e32 v23, 0xffff0000, v23
	v_pk_fma_f32 v[22:23], v[34:35], v[102:103], v[22:23]
	v_pk_fma_f32 v[34:35], v[52:53], v[58:59], v[56:57]
	v_add_f32_e32 v43, 1.0, v43
	v_rcp_f32_e32 v43, v43
	v_mul_f32_e32 v63, v22, v111
	v_mul_f32_e32 v112, v43, v42
	v_lshlrev_b32_e32 v42, 16, v24
	v_exp_f32_e32 v44, v42
	v_lshlrev_b32_e32 v42, 16, v99
	v_mul_f32_e32 v43, 0x3d372713, v42
	v_mul_f32_e32 v43, v43, v42
	v_fma_f32 v43, v43, v42, v42
	v_mul_f32_e32 v43, 0xbfcc422a, v43
	v_mul_f32_e32 v43, 0x3fb8aa3b, v43
	v_exp_f32_e32 v43, v43
	v_mul_f32_e32 v72, v23, v112
	v_and_b32_e32 v24, 0xffff0000, v24
	v_add_f32_e32 v43, 1.0, v43
	v_rcp_f32_e32 v43, v43
	s_nop 0
	v_mul_f32_e32 v65, v43, v42
	v_lshlrev_b32_e32 v42, 16, v25
	v_exp_f32_e32 v45, v42
	v_and_b32_e32 v42, 0xffff0000, v99
	v_mul_f32_e32 v43, 0x3d372713, v42
	v_mul_f32_e32 v43, v43, v42
	v_fma_f32 v43, v43, v42, v42
	v_mul_f32_e32 v43, 0xbfcc422a, v43
	v_mul_f32_e32 v43, 0x3fb8aa3b, v43
	v_exp_f32_e32 v43, v43
	v_and_b32_e32 v25, 0xffff0000, v25
	v_add_f32_e32 v43, 1.0, v43
	v_rcp_f32_e32 v43, v43
	s_nop 0
	v_mul_f32_e32 v113, v43, v42
	v_lshlrev_b32_e32 v42, 16, v30
	v_exp_f32_e32 v98, v42
	v_lshlrev_b32_e32 v42, 16, v100
	v_mul_f32_e32 v43, 0x3d372713, v42
	v_mul_f32_e32 v43, v43, v42
	v_fma_f32 v43, v43, v42, v42
	v_mul_f32_e32 v43, 0xbfcc422a, v43
	v_mul_f32_e32 v43, 0x3fb8aa3b, v43
	v_exp_f32_e32 v43, v43
	v_and_b32_e32 v30, 0xffff0000, v30
	v_add_f32_e32 v43, 1.0, v43
	v_rcp_f32_e32 v43, v43
	s_nop 0
	v_mul_f32_e32 v114, v43, v42
	v_lshlrev_b32_e32 v42, 16, v31
	v_exp_f32_e32 v99, v42
	v_and_b32_e32 v42, 0xffff0000, v100
	v_mul_f32_e32 v43, 0x3d372713, v42
	v_mul_f32_e32 v43, v43, v42
	v_fma_f32 v43, v43, v42, v42
	v_mul_f32_e32 v43, 0xbfcc422a, v43
	v_mul_f32_e32 v43, 0x3fb8aa3b, v43
	v_exp_f32_e32 v43, v43
	v_and_b32_e32 v31, 0xffff0000, v31
	v_pk_fma_f32 v[22:23], v[22:23], v[98:99], v[30:31]
	v_add_f32_e32 v43, 1.0, v43
	v_rcp_f32_e32 v43, v43
	v_mul_f32_e32 v73, v22, v114
	v_mul_f32_e32 v115, v43, v42
	v_lshlrev_b32_e32 v42, 16, v32
	v_exp_f32_e32 v48, v42
	v_lshlrev_b32_e32 v42, 16, v101
	v_mul_f32_e32 v43, 0x3d372713, v42
	v_mul_f32_e32 v43, v43, v42
	v_fma_f32 v43, v43, v42, v42
	v_mul_f32_e32 v43, 0xbfcc422a, v43
	v_mul_f32_e32 v43, 0x3fb8aa3b, v43
	v_exp_f32_e32 v43, v43
	v_mul_f32_e32 v98, v23, v115
	v_and_b32_e32 v32, 0xffff0000, v32
	v_add_f32_e32 v43, 1.0, v43
	v_rcp_f32_e32 v43, v43
	s_nop 0
	v_mul_f32_e32 v116, v43, v42
	v_lshlrev_b32_e32 v42, 16, v33
	v_exp_f32_e32 v49, v42
	v_and_b32_e32 v42, 0xffff0000, v101
	v_mul_f32_e32 v43, 0x3d372713, v42
	v_mul_f32_e32 v43, v43, v42
	v_fma_f32 v43, v43, v42, v42
	v_mul_f32_e32 v43, 0xbfcc422a, v43
; __device__ __forceinline__ unsigned cvt_pk_bf16(float lo, float hi) { unsigned r; asm volatile("v_cvt_pk_bf16_f32 %0, %1, %2" : "=v"(r) : "v"(lo), "v"(hi)); return r; }
; __device__ __forceinline__ float bflo(unsigned w) { return __uint_as_float(w << 16); }
; __device__ __forceinline__ float bfhi(unsigned w) { return __uint_as_float(w & 0xffff0000u); }
; __device__ __forceinline__ float gelu_tanh(float x) { const float t = 1.5957691216057308f * (x + 0.044715f * x * x * x); return x * __builtin_amdgcn_rcpf(1.0f + __expf(-t)); }
; __global__ void __launch_bounds__(512, 2) mega_fwd(Params P) {
;     ...
;                             for (int t0 = 0; t0 < 64; t0 += 16) {
;                                 u32x4 wv[16]; u32x2 gv2[16];
; #pragma unroll
;                                 for (int i = 0; i < 16; ++i) { wv[i] = *(const u32x4*)(ab + (size_t)(t0 + i) * 512); gv2[i] = *(const u32x2*)(gp + (size_t)(t0 + i) * ZW); }
; #pragma unroll
;                                 for (int i = 0; i < 16; ++i) { float o4[4];
; #pragma unroll
;                                     for (int k = 0; k < 4; ++k) { const float la = bflo(wv[i][k]), bb = bfhi(wv[i][k]); h[k] = __builtin_amdgcn_exp2f(la) * h[k] + bb;
;                                         const unsigned gw = gv2[i][k >> 1]; const float gt = (k & 1) ? bfhi(gw) : bflo(gw); o4[k] = gelu_tanh(gt) * h[k]; }
;                                     u32x2 ow; ow.x = cvt_pk_bf16(o4[0], o4[1]); ow.y = cvt_pk_bf16(o4[2], o4[3]); *(u32x2*)(op + (size_t)(t0 + i) * 1024) = ow; }
	v_mul_f32_e32 v43, 0x3fb8aa3b, v43
	v_exp_f32_e32 v43, v43
	v_and_b32_e32 v33, 0xffff0000, v33
	v_add_f32_e32 v43, 1.0, v43
	v_rcp_f32_e32 v43, v43
	s_nop 0
	v_mul_f32_e32 v117, v43, v42
	v_lshlrev_b32_e32 v42, 16, v26
	v_exp_f32_e32 v100, v42
	v_lshlrev_b32_e32 v42, 16, v96
	v_mul_f32_e32 v43, 0x3d372713, v42
	v_mul_f32_e32 v43, v43, v42
	v_fma_f32 v43, v43, v42, v42
	v_mul_f32_e32 v43, 0xbfcc422a, v43
	v_mul_f32_e32 v43, 0x3fb8aa3b, v43
	v_exp_f32_e32 v43, v43
	v_and_b32_e32 v26, 0xffff0000, v26
	v_add_f32_e32 v43, 1.0, v43
	v_rcp_f32_e32 v43, v43
	s_nop 0
	v_mul_f32_e32 v122, v43, v42
	v_lshlrev_b32_e32 v42, 16, v27
	v_exp_f32_e32 v101, v42
	v_and_b32_e32 v42, 0xffff0000, v96
	v_mul_f32_e32 v43, 0x3d372713, v42
	v_mul_f32_e32 v43, v43, v42
	v_fma_f32 v43, v43, v42, v42
	v_mul_f32_e32 v43, 0xbfcc422a, v43
	v_mul_f32_e32 v43, 0x3fb8aa3b, v43
	v_exp_f32_e32 v43, v43
	v_and_b32_e32 v27, 0xffff0000, v27
	v_pk_fma_f32 v[30:31], v[22:23], v[100:101], v[26:27]
	v_mul_f32_e32 v22, 0x3d372713, v0
	v_add_f32_e32 v43, 1.0, v43
	v_mul_f32_e32 v22, v22, v0
	v_rcp_f32_e32 v43, v43
	v_fma_f32 v22, v22, v0, v0
	v_mul_f32_e32 v22, 0xbfcc422a, v22
	v_mul_f32_e32 v22, 0x3fb8aa3b, v22
	v_exp_f32_e32 v22, v22
	v_mul_f32_e32 v96, v43, v42
	v_lshlrev_b32_e32 v42, 16, v28
	v_exp_f32_e32 v50, v42
	v_lshlrev_b32_e32 v42, 16, v97
	v_mul_f32_e32 v43, 0x3d372713, v42
	v_mul_f32_e32 v43, v43, v42
	v_add_f32_e32 v22, 1.0, v22
	v_fma_f32 v43, v43, v42, v42
	v_rcp_f32_e32 v22, v22
	v_mul_f32_e32 v43, 0xbfcc422a, v43
	v_mul_f32_e32 v43, 0x3fb8aa3b, v43
	v_exp_f32_e32 v43, v43
	v_mul_f32_e32 v46, v22, v0
	v_lshlrev_b32_e32 v0, 16, v40
	v_exp_f32_e32 v22, v0
	v_lshlrev_b32_e32 v0, 16, v93
	v_mul_f32_e32 v23, 0x3d372713, v0
	v_add_f32_e32 v43, 1.0, v43
	v_mul_f32_e32 v23, v23, v0
	v_rcp_f32_e32 v43, v43
	v_fma_f32 v23, v23, v0, v0
	v_mul_f32_e32 v23, 0xbfcc422a, v23
	v_mul_f32_e32 v23, 0x3fb8aa3b, v23
	v_exp_f32_e32 v23, v23
	v_mul_f32_e32 v123, v43, v42
	v_lshlrev_b32_e32 v42, 16, v29
	v_exp_f32_e32 v51, v42
	v_and_b32_e32 v42, 0xffff0000, v97
	v_mul_f32_e32 v43, 0x3d372713, v42
	v_mul_f32_e32 v43, v43, v42
	v_add_f32_e32 v23, 1.0, v23
	v_fma_f32 v43, v43, v42, v42
	v_rcp_f32_e32 v23, v23
	v_mul_f32_e32 v43, 0xbfcc422a, v43
	v_mul_f32_e32 v43, 0x3fb8aa3b, v43
	v_exp_f32_e32 v43, v43
	v_mul_f32_e32 v0, v23, v0
	v_lshlrev_b32_e32 v23, 16, v41
	v_and_b32_e32 v27, 0xffff0000, v41
	v_and_b32_e32 v26, 0xffff0000, v40
	v_mul_f32_e32 v40, v34, v106
	v_mul_f32_e32 v41, v35, v105
	v_pk_fma_f32 v[34:35], v[34:35], v[80:81], v[36:37]
	v_cvt_pk_bf16_f32 v61, v40, v41
	global_store_dwordx2 v[54:55], v[60:61], off offset:3072
	v_mul_f32_e32 v37, v34, v109
	v_mul_f32_e32 v40, v35, v110
	v_cvt_pk_bf16_f32 v36, v47, v62
	v_cvt_pk_bf16_f32 v37, v37, v40
	v_add_co_u32_e32 v40, vcc, s1, v94
	v_add_f32_e32 v43, 1.0, v43
	s_nop 0
	v_addc_co_u32_e32 v41, vcc, 0, v95, vcc
	v_pk_fma_f32 v[24:25], v[34:35], v[44:45], v[24:25]
	v_rcp_f32_e32 v43, v43
	global_store_dwordx2 v[40:41], v[36:37], off offset:1024
	v_mul_f32_e32 v35, v24, v65
	v_mul_f32_e32 v36, v25, v113
	v_cvt_pk_bf16_f32 v34, v63, v72
	v_pk_fma_f32 v[24:25], v[24:25], v[48:49], v[32:33]
	v_cvt_pk_bf16_f32 v35, v35, v36
	global_store_dwordx2 v[40:41], v[34:35], off offset:3072
	v_mul_f32_e32 v33, v24, v116
	v_mul_f32_e32 v34, v25, v117
	s_mov_b32 s1, 0x2b804000
	v_cvt_pk_bf16_f32 v32, v73, v98
	v_cvt_pk_bf16_f32 v33, v33, v34
	v_add_co_u32_e32 v34, vcc, s1, v94
	v_and_b32_e32 v29, 0xffff0000, v29
	v_and_b32_e32 v28, 0xffff0000, v28
	v_addc_co_u32_e32 v35, vcc, 0, v95, vcc
	v_pk_fma_f32 v[28:29], v[24:25], v[50:51], v[28:29]
	v_mul_f32_e32 v97, v43, v42
	v_mul_f32_e32 v99, v30, v122
	v_mul_f32_e32 v96, v31, v96
	global_store_dwordx2 v[34:35], v[32:33], off offset:1024
	v_mul_f32_e32 v25, v28, v123
	v_cvt_pk_bf16_f32 v24, v99, v96
	v_mul_f32_e32 v32, v29, v97
	v_cvt_pk_bf16_f32 v25, v25, v32
	global_store_dwordx2 v[34:35], v[24:25], off offset:3072
	v_and_b32_e32 v24, 0xffff0000, v93
	v_mul_f32_e32 v25, 0x3d372713, v24
	v_mul_f32_e32 v25, v25, v24
	v_fma_f32 v25, v25, v24, v24
	v_mul_f32_e32 v25, 0xbfcc422a, v25
	v_mul_f32_e32 v25, 0x3fb8aa3b, v25
	v_exp_f32_e32 v25, v25
	v_lshlrev_b32_e32 v43, 16, v92
	v_mul_f32_e32 v64, 0x3d372713, v43
	v_mul_f32_e32 v64, v64, v43
	v_add_f32_e32 v25, 1.0, v25
	v_rcp_f32_e32 v25, v25
	v_fma_f32 v64, v64, v43, v43
	v_mul_f32_e32 v64, 0xbfcc422a, v64
	v_mul_f32_e32 v64, 0x3fb8aa3b, v64
	v_mul_f32_e32 v25, v25, v24
	v_lshlrev_b32_e32 v24, 16, v6
	v_exp_f32_e32 v32, v24
	v_lshlrev_b32_e32 v24, 16, v90
	v_mul_f32_e32 v33, 0x3d372713, v24
	v_mul_f32_e32 v33, v33, v24
	v_fma_f32 v33, v33, v24, v24
	v_mul_f32_e32 v33, 0xbfcc422a, v33
	v_mul_f32_e32 v33, 0x3fb8aa3b, v33
	v_exp_f32_e32 v33, v33
	v_exp_f32_e32 v64, v64
	v_lshlrev_b32_e32 v42, 16, v38
	v_exp_f32_e32 v42, v42
	v_add_f32_e32 v33, 1.0, v33
	v_rcp_f32_e32 v33, v33
	v_add_f32_e32 v64, 1.0, v64
	v_rcp_f32_e32 v64, v64
	v_and_b32_e32 v38, 0xffff0000, v38
	v_mul_f32_e32 v47, v33, v24
	v_lshlrev_b32_e32 v24, 16, v7
	v_exp_f32_e32 v33, v24
	v_and_b32_e32 v24, 0xffff0000, v90
	v_mul_f32_e32 v34, 0x3d372713, v24
	v_mul_f32_e32 v34, v34, v24
	v_fma_f32 v34, v34, v24, v24
	v_mul_f32_e32 v34, 0xbfcc422a, v34
	v_mul_f32_e32 v34, 0x3fb8aa3b, v34
	v_exp_f32_e32 v34, v34
	v_mul_f32_e32 v64, v64, v43
	v_lshlrev_b32_e32 v43, 16, v39
	v_exp_f32_e32 v43, v43
	v_add_f32_e32 v34, 1.0, v34
	v_rcp_f32_e32 v34, v34
	v_and_b32_e32 v39, 0xffff0000, v39
	v_pk_fma_f32 v[30:31], v[30:31], v[42:43], v[38:39]
	v_and_b32_e32 v7, 0xffff0000, v7
	v_mul_f32_e32 v56, v34, v24
	v_lshlrev_b32_e32 v24, 16, v8
	v_exp_f32_e32 v34, v24
	v_lshlrev_b32_e32 v24, 16, v91
	v_mul_f32_e32 v35, 0x3d372713, v24
; __device__ __forceinline__ unsigned cvt_pk_bf16(float lo, float hi) { unsigned r; asm volatile("v_cvt_pk_bf16_f32 %0, %1, %2" : "=v"(r) : "v"(lo), "v"(hi)); return r; }
; __device__ __forceinline__ float bflo(unsigned w) { return __uint_as_float(w << 16); }
; __device__ __forceinline__ float bfhi(unsigned w) { return __uint_as_float(w & 0xffff0000u); }
; __device__ __forceinline__ float gelu_tanh(float x) { const float t = 1.5957691216057308f * (x + 0.044715f * x * x * x); return x * __builtin_amdgcn_rcpf(1.0f + __expf(-t)); }
; __global__ void __launch_bounds__(512, 2) mega_fwd(Params P) {
;     ...
;                             for (int t0 = 0; t0 < 64; t0 += 16) {
;                                 u32x4 wv[16]; u32x2 gv2[16];
; #pragma unroll
;                                 for (int i = 0; i < 16; ++i) { wv[i] = *(const u32x4*)(ab + (size_t)(t0 + i) * 512); gv2[i] = *(const u32x2*)(gp + (size_t)(t0 + i) * ZW); }
; #pragma unroll
;                                 for (int i = 0; i < 16; ++i) { float o4[4];
; #pragma unroll
;                                     for (int k = 0; k < 4; ++k) { const float la = bflo(wv[i][k]), bb = bfhi(wv[i][k]); h[k] = __builtin_amdgcn_exp2f(la) * h[k] + bb;
;                                         const unsigned gw = gv2[i][k >> 1]; const float gt = (k & 1) ? bfhi(gw) : bflo(gw); o4[k] = gelu_tanh(gt) * h[k]; }
;                                     u32x2 ow; ow.x = cvt_pk_bf16(o4[0], o4[1]); ow.y = cvt_pk_bf16(o4[2], o4[3]); *(u32x2*)(op + (size_t)(t0 + i) * 1024) = ow; }
	v_mul_f32_e32 v35, v35, v24
	v_fma_f32 v35, v35, v24, v24
	v_mul_f32_e32 v35, 0xbfcc422a, v35
	v_mul_f32_e32 v35, 0x3fb8aa3b, v35
	v_exp_f32_e32 v35, v35
	v_and_b32_e32 v6, 0xffff0000, v6
	v_pk_fma_f32 v[6:7], v[30:31], v[32:33], v[6:7]
	v_mul_f32_e32 v38, v31, v46
	v_add_f32_e32 v35, 1.0, v35
	v_rcp_f32_e32 v35, v35
	v_mul_f32_e32 v31, v7, v56
	v_exp_f32_e32 v23, v23
	v_and_b32_e32 v8, 0xffff0000, v8
	v_mul_f32_e32 v57, v35, v24
	v_lshlrev_b32_e32 v24, 16, v9
	v_exp_f32_e32 v35, v24
	v_and_b32_e32 v24, 0xffff0000, v91
	v_mul_f32_e32 v36, 0x3d372713, v24
	v_mul_f32_e32 v36, v36, v24
	v_fma_f32 v36, v36, v24, v24
	v_mul_f32_e32 v36, 0xbfcc422a, v36
	v_mul_f32_e32 v36, 0x3fb8aa3b, v36
	v_exp_f32_e32 v36, v36
	v_and_b32_e32 v9, 0xffff0000, v9
	s_mov_b32 s1, 0x2b805000
	v_add_f32_e32 v36, 1.0, v36
	v_rcp_f32_e32 v36, v36
	s_nop 0
	v_mul_f32_e32 v58, v36, v24
	v_lshlrev_b32_e32 v24, 16, v10
	v_exp_f32_e32 v36, v24
	v_lshlrev_b32_e32 v24, 16, v88
	v_mul_f32_e32 v37, 0x3d372713, v24
	v_mul_f32_e32 v37, v37, v24
	v_fma_f32 v37, v37, v24, v24
	v_mul_f32_e32 v37, 0xbfcc422a, v37
	v_mul_f32_e32 v37, 0x3fb8aa3b, v37
	v_exp_f32_e32 v37, v37
	v_and_b32_e32 v10, 0xffff0000, v10
	v_add_f32_e32 v37, 1.0, v37
	v_rcp_f32_e32 v37, v37
	s_nop 0
	v_mul_f32_e32 v59, v37, v24
	v_lshlrev_b32_e32 v24, 16, v11
	v_exp_f32_e32 v37, v24
	v_and_b32_e32 v24, 0xffff0000, v88
	v_mul_f32_e32 v40, 0x3d372713, v24
	v_mul_f32_e32 v40, v40, v24
	v_fma_f32 v40, v40, v24, v24
	v_mul_f32_e32 v40, 0xbfcc422a, v40
	v_mul_f32_e32 v40, 0x3fb8aa3b, v40
	v_exp_f32_e32 v40, v40
	v_and_b32_e32 v11, 0xffff0000, v11
	v_add_f32_e32 v40, 1.0, v40
	v_rcp_f32_e32 v40, v40
	s_nop 0
	v_mul_f32_e32 v60, v40, v24
	v_lshlrev_b32_e32 v24, 16, v12
	v_exp_f32_e32 v40, v24
	v_lshlrev_b32_e32 v24, 16, v89
	v_mul_f32_e32 v41, 0x3d372713, v24
	v_mul_f32_e32 v41, v41, v24
	v_fma_f32 v41, v41, v24, v24
	v_mul_f32_e32 v41, 0xbfcc422a, v41
	v_mul_f32_e32 v41, 0x3fb8aa3b, v41
	v_exp_f32_e32 v41, v41
	s_nop 0
	v_add_f32_e32 v41, 1.0, v41
	v_rcp_f32_e32 v41, v41
	s_nop 0
	v_mul_f32_e32 v61, v41, v24
	v_lshlrev_b32_e32 v24, 16, v13
	v_exp_f32_e32 v41, v24
	v_and_b32_e32 v24, 0xffff0000, v89
	v_mul_f32_e32 v44, 0x3d372713, v24
	v_mul_f32_e32 v44, v44, v24
	v_fma_f32 v44, v44, v24, v24
	v_mul_f32_e32 v44, 0xbfcc422a, v44
	v_mul_f32_e32 v44, 0x3fb8aa3b, v44
	v_exp_f32_e32 v44, v44
	s_nop 0
	v_add_f32_e32 v44, 1.0, v44
	v_rcp_f32_e32 v44, v44
	s_nop 0
	v_mul_f32_e32 v62, v44, v24
	v_lshlrev_b32_e32 v24, 16, v14
	v_exp_f32_e32 v44, v24
	v_lshlrev_b32_e32 v24, 16, v86
	v_mul_f32_e32 v45, 0x3d372713, v24
	v_mul_f32_e32 v45, v45, v24
	v_fma_f32 v45, v45, v24, v24
	v_mul_f32_e32 v45, 0xbfcc422a, v45
	v_mul_f32_e32 v45, 0x3fb8aa3b, v45
	v_exp_f32_e32 v45, v45
	s_nop 0
	v_add_f32_e32 v45, 1.0, v45
	v_rcp_f32_e32 v45, v45
	s_nop 0
	v_mul_f32_e32 v63, v45, v24
	v_lshlrev_b32_e32 v24, 16, v15
	v_exp_f32_e32 v45, v24
	v_and_b32_e32 v24, 0xffff0000, v86
	v_mul_f32_e32 v48, 0x3d372713, v24
	v_mul_f32_e32 v48, v48, v24
	v_fma_f32 v48, v48, v24, v24
	v_mul_f32_e32 v48, 0xbfcc422a, v48
	v_mul_f32_e32 v48, 0x3fb8aa3b, v48
	v_exp_f32_e32 v48, v48
	s_nop 0
	v_add_f32_e32 v48, 1.0, v48
	v_rcp_f32_e32 v48, v48
	s_nop 0
	v_mul_f32_e32 v65, v48, v24
	v_lshlrev_b32_e32 v24, 16, v16
	v_exp_f32_e32 v48, v24
	v_lshlrev_b32_e32 v24, 16, v87
	v_mul_f32_e32 v49, 0x3d372713, v24
	v_mul_f32_e32 v49, v49, v24
	v_fma_f32 v49, v49, v24, v24
	v_mul_f32_e32 v49, 0xbfcc422a, v49
	v_mul_f32_e32 v49, 0x3fb8aa3b, v49
	v_exp_f32_e32 v49, v49
	s_nop 0
	v_add_f32_e32 v49, 1.0, v49
	v_rcp_f32_e32 v49, v49
	s_nop 0
	v_mul_f32_e32 v80, v49, v24
	v_lshlrev_b32_e32 v24, 16, v17
	v_exp_f32_e32 v49, v24
	v_and_b32_e32 v24, 0xffff0000, v87
	v_mul_f32_e32 v50, 0x3d372713, v24
	v_mul_f32_e32 v50, v50, v24
	v_fma_f32 v50, v50, v24, v24
	v_mul_f32_e32 v50, 0xbfcc422a, v50
	v_mul_f32_e32 v50, 0x3fb8aa3b, v50
	v_exp_f32_e32 v50, v50
	s_nop 0
	v_add_f32_e32 v50, 1.0, v50
	v_rcp_f32_e32 v50, v50
	s_nop 0
	v_mul_f32_e32 v81, v50, v24
	v_lshlrev_b32_e32 v24, 16, v18
	v_exp_f32_e32 v50, v24
	v_lshlrev_b32_e32 v24, 16, v84
	v_mul_f32_e32 v51, 0x3d372713, v24
	v_mul_f32_e32 v51, v51, v24
	v_fma_f32 v51, v51, v24, v24
	v_mul_f32_e32 v51, 0xbfcc422a, v51
	v_mul_f32_e32 v51, 0x3fb8aa3b, v51
	v_exp_f32_e32 v51, v51
	s_nop 0
	v_add_f32_e32 v51, 1.0, v51
	v_rcp_f32_e32 v51, v51
	s_nop 0
	v_mul_f32_e32 v72, v51, v24
	v_lshlrev_b32_e32 v24, 16, v19
	v_exp_f32_e32 v51, v24
	v_and_b32_e32 v24, 0xffff0000, v84
	v_mul_f32_e32 v52, 0x3d372713, v24
	v_mul_f32_e32 v52, v52, v24
	v_fma_f32 v52, v52, v24, v24
	v_mul_f32_e32 v52, 0xbfcc422a, v52
	v_mul_f32_e32 v52, 0x3fb8aa3b, v52
	v_exp_f32_e32 v52, v52
	s_nop 0
	v_add_f32_e32 v52, 1.0, v52
	v_rcp_f32_e32 v52, v52
	s_nop 0
	v_mul_f32_e32 v73, v52, v24
	v_lshlrev_b32_e32 v24, 16, v20
	v_exp_f32_e32 v52, v24
	v_lshlrev_b32_e32 v24, 16, v85
; __device__ __forceinline__ unsigned cvt_pk_bf16(float lo, float hi) { unsigned r; asm volatile("v_cvt_pk_bf16_f32 %0, %1, %2" : "=v"(r) : "v"(lo), "v"(hi)); return r; }
; __device__ __forceinline__ float bflo(unsigned w) { return __uint_as_float(w << 16); }
; __device__ __forceinline__ float bfhi(unsigned w) { return __uint_as_float(w & 0xffff0000u); }
; __device__ __forceinline__ float gelu_tanh(float x) { const float t = 1.5957691216057308f * (x + 0.044715f * x * x * x); return x * __builtin_amdgcn_rcpf(1.0f + __expf(-t)); }
; __global__ void __launch_bounds__(512, 2) mega_fwd(Params P) {
;     ...
;                             for (int t0 = 0; t0 < 64; t0 += 16) {
;                                 u32x4 wv[16]; u32x2 gv2[16];
; #pragma unroll
;                                 for (int i = 0; i < 16; ++i) { wv[i] = *(const u32x4*)(ab + (size_t)(t0 + i) * 512); gv2[i] = *(const u32x2*)(gp + (size_t)(t0 + i) * ZW); }
; #pragma unroll
;                                 for (int i = 0; i < 16; ++i) { float o4[4];
; #pragma unroll
;                                     for (int k = 0; k < 4; ++k) { const float la = bflo(wv[i][k]), bb = bfhi(wv[i][k]); h[k] = __builtin_amdgcn_exp2f(la) * h[k] + bb;
;                                         const unsigned gw = gv2[i][k >> 1]; const float gt = (k & 1) ? bfhi(gw) : bflo(gw); o4[k] = gelu_tanh(gt) * h[k]; }
;                                     u32x2 ow; ow.x = cvt_pk_bf16(o4[0], o4[1]); ow.y = cvt_pk_bf16(o4[2], o4[3]); *(u32x2*)(op + (size_t)(t0 + i) * 1024) = ow; }
	v_mul_f32_e32 v53, 0x3d372713, v24
	v_mul_f32_e32 v53, v53, v24
	v_fma_f32 v53, v53, v24, v24
	v_mul_f32_e32 v53, 0xbfcc422a, v53
	v_mul_f32_e32 v53, 0x3fb8aa3b, v53
	v_exp_f32_e32 v53, v53
	s_nop 0
	v_add_f32_e32 v53, 1.0, v53
	v_rcp_f32_e32 v53, v53
	s_nop 0
	v_mul_f32_e32 v84, v53, v24
	v_lshlrev_b32_e32 v24, 16, v21
	v_exp_f32_e32 v53, v24
	v_and_b32_e32 v24, 0xffff0000, v85
	v_mul_f32_e32 v54, 0x3d372713, v24
	v_mul_f32_e32 v54, v54, v24
	v_fma_f32 v54, v54, v24, v24
	v_mul_f32_e32 v54, 0xbfcc422a, v54
	v_mul_f32_e32 v54, 0x3fb8aa3b, v54
	v_exp_f32_e32 v54, v54
	s_nop 0
	v_add_f32_e32 v54, 1.0, v54
	v_rcp_f32_e32 v54, v54
	s_nop 0
	v_mul_f32_e32 v85, v54, v24
	v_lshlrev_b32_e32 v24, 16, v2
	v_exp_f32_e32 v54, v24
	v_lshlrev_b32_e32 v24, 16, v82
	v_mul_f32_e32 v55, 0x3d372713, v24
	v_mul_f32_e32 v55, v55, v24
	v_fma_f32 v55, v55, v24, v24
	v_mul_f32_e32 v55, 0xbfcc422a, v55
	v_mul_f32_e32 v55, 0x3fb8aa3b, v55
	v_exp_f32_e32 v55, v55
	v_and_b32_e32 v2, 0xffff0000, v2
	v_add_f32_e32 v55, 1.0, v55
	v_rcp_f32_e32 v55, v55
	s_nop 0
	v_mul_f32_e32 v86, v55, v24
	v_lshlrev_b32_e32 v24, 16, v3
	v_exp_f32_e32 v55, v24
	v_mul_f32_e32 v24, v30, v64
	v_mul_f32_e32 v30, v6, v47
	v_pk_fma_f32 v[6:7], v[6:7], v[36:37], v[10:11]
	v_and_b32_e32 v11, 0xffff0000, v15
	v_and_b32_e32 v10, 0xffff0000, v14
	v_mul_f32_e32 v32, v6, v59
	v_mul_f32_e32 v33, v7, v60
	v_pk_fma_f32 v[6:7], v[6:7], v[44:45], v[10:11]
	v_and_b32_e32 v11, 0xffff0000, v19
	v_and_b32_e32 v10, 0xffff0000, v18
	v_mul_f32_e32 v14, v6, v63
	v_mul_f32_e32 v15, v7, v65
	v_pk_fma_f32 v[6:7], v[6:7], v[50:51], v[10:11]
	v_and_b32_e32 v3, 0xffff0000, v3
	v_mul_f32_e32 v18, v6, v72
	v_mul_f32_e32 v19, v7, v73
	v_pk_fma_f32 v[72:73], v[6:7], v[54:55], v[2:3]
	v_and_b32_e32 v2, 0xffff0000, v82
	v_mul_f32_e32 v3, 0x3d372713, v2
	v_mul_f32_e32 v3, v3, v2
	v_fma_f32 v3, v3, v2, v2
	v_mul_f32_e32 v3, 0xbfcc422a, v3
	v_mul_f32_e32 v3, 0x3fb8aa3b, v3
	v_exp_f32_e32 v3, v3
	v_cvt_pk_bf16_f32 v24, v24, v38
	v_mul_f32_e32 v36, v72, v86
	v_add_f32_e32 v3, 1.0, v3
	v_rcp_f32_e32 v3, v3
	s_nop 0
	v_mul_f32_e32 v2, v3, v2
	v_lshlrev_b32_e32 v3, 16, v83
	v_mul_f32_e32 v6, 0x3d372713, v3
	v_mul_f32_e32 v6, v6, v3
	v_fma_f32 v6, v6, v3, v3
	v_mul_f32_e32 v6, 0xbfcc422a, v6
	v_mul_f32_e32 v6, 0x3fb8aa3b, v6
	v_exp_f32_e32 v6, v6
	v_mul_f32_e32 v37, v73, v2
	v_lshlrev_b32_e32 v2, 16, v4
	v_exp_f32_e32 v2, v2
	v_add_f32_e32 v6, 1.0, v6
	v_rcp_f32_e32 v6, v6
	v_and_b32_e32 v4, 0xffff0000, v4
	v_mul_f32_e32 v38, v6, v3
	v_lshlrev_b32_e32 v3, 16, v5
	v_pk_fma_f32 v[6:7], v[28:29], v[22:23], v[26:27]
	v_exp_f32_e32 v3, v3
	v_mul_f32_e32 v0, v6, v0
	v_mul_f32_e32 v10, v7, v25
	v_pk_fma_f32 v[6:7], v[6:7], v[34:35], v[8:9]
	v_and_b32_e32 v9, 0xffff0000, v13
	v_and_b32_e32 v8, 0xffff0000, v12
	v_mul_f32_e32 v11, v6, v57
	v_mul_f32_e32 v22, v7, v58
	v_pk_fma_f32 v[6:7], v[6:7], v[40:41], v[8:9]
	v_and_b32_e32 v9, 0xffff0000, v17
	v_and_b32_e32 v8, 0xffff0000, v16
	v_mul_f32_e32 v12, v6, v61
	v_mul_f32_e32 v13, v7, v62
	v_pk_fma_f32 v[6:7], v[6:7], v[48:49], v[8:9]
	v_and_b32_e32 v9, 0xffff0000, v21
	v_and_b32_e32 v8, 0xffff0000, v20
	v_mul_f32_e32 v16, v6, v80
	v_mul_f32_e32 v17, v7, v81
	v_pk_fma_f32 v[6:7], v[6:7], v[52:53], v[8:9]
	v_and_b32_e32 v5, 0xffff0000, v5
	v_pk_fma_f32 v[80:81], v[6:7], v[2:3], v[4:5]
	v_and_b32_e32 v2, 0xffff0000, v83
	v_mul_f32_e32 v3, 0x3d372713, v2
	v_mul_f32_e32 v3, v3, v2
	v_fma_f32 v3, v3, v2, v2
	v_mul_f32_e32 v3, 0xbfcc422a, v3
	v_mul_f32_e32 v3, 0x3fb8aa3b, v3
	v_exp_f32_e32 v3, v3
	v_add_co_u32_e32 v8, vcc, s1, v94
	v_cvt_pk_bf16_f32 v25, v0, v10
	v_add_f32_e32 v3, 1.0, v3
	s_nop 0
	v_addc_co_u32_e32 v9, vcc, 0, v95, vcc
	v_rcp_f32_e32 v3, v3
	global_store_dwordx2 v[8:9], v[24:25], off offset:1024
	v_cvt_pk_bf16_f32 v10, v30, v31
	s_mov_b32 s1, 0x2b806000
	v_cvt_pk_bf16_f32 v11, v11, v22
	global_store_dwordx2 v[8:9], v[10:11], off offset:3072
	v_add_co_u32_e32 v10, vcc, s1, v94
	v_cvt_pk_bf16_f32 v8, v32, v33
	v_cvt_pk_bf16_f32 v9, v12, v13
	s_mov_b32 s1, 0x2b807000
	s_nop 0
	v_addc_co_u32_e32 v11, vcc, 0, v95, vcc
	global_store_dwordx2 v[10:11], v[8:9], off offset:1024
	v_cvt_pk_bf16_f32 v8, v14, v15
	v_cvt_pk_bf16_f32 v9, v16, v17
	global_store_dwordx2 v[10:11], v[8:9], off offset:3072
	v_add_co_u32_e32 v10, vcc, s1, v94
	v_mul_f32_e32 v2, v3, v2
	s_nop 0
	v_addc_co_u32_e32 v11, vcc, 0, v95, vcc
	v_mul_f32_e32 v3, v81, v2
	v_mul_f32_e32 v20, v6, v84
	v_mul_f32_e32 v21, v7, v85
	v_cvt_pk_bf16_f32 v8, v18, v19
	v_cvt_pk_bf16_f32 v9, v20, v21
	global_store_dwordx2 v[10:11], v[8:9], off offset:1024
	v_mul_f32_e32 v0, v80, v38
	v_cvt_pk_bf16_f32 v2, v36, v37
	v_cvt_pk_bf16_f32 v3, v0, v3
	global_store_dwordx2 v[10:11], v[2:3], off offset:3072
	s_cbranch_scc0 .LBB0_1118
	s_add_i32 s11, s11, s10
	s_add_i32 s12, s12, s13
	s_cmpk_gt_i32 s11, 0xff
	s_cbranch_scc0 .LBB0_1111

; #define LAS __attribute__((address_space(3)))
; __global__ void __launch_bounds__(512, 2) mega_fwd(Params P) {
;     ...
;               { LAS float* gl = (LAS float*)(lds + 147456); for (int i = tid; i < 1024; i += 512) { gl[i] = gpv[i]; gl[1024 + i] = bpv[i]; } __syncthreads(); }
.LBB0_1167:
	global_load_dword v3, v[6:7], off
	v_add_u32_e32 v8, 0xfffff000, v2
	v_add_u32_e32 v0, 0x200, v0
	v_cmp_lt_i32_e32 vcc, s69, v0
	v_lshl_add_u64 v[6:7], v[6:7], 0, s[42:43]
	s_or_b64 s[14:15], vcc, s[14:15]
	s_waitcnt vmcnt(0) lgkmcnt(0)
	ds_write_b32 v8, v3
	global_load_dword v3, v[4:5], off
	v_lshl_add_u64 v[4:5], v[4:5], 0, s[42:43]
	s_waitcnt vmcnt(0) lgkmcnt(0)
	ds_write_b32 v2, v3
	v_add_u32_e32 v2, 0x800, v2
	s_andn2_b64 exec, exec, s[14:15]
	s_cbranch_execnz .LBB0_1167

; #define PG8_STAGE(bufoff, gbase, voff) do { _Pragma("unroll") for (int _i = 0; _i < 2; ++_i) \
;         __builtin_amdgcn_global_load_lds((const unsigned*)((const char*)(gbase) + (voff)[_i]), (PG8_LAS unsigned*)(lds + (bufoff) + ldsw + _i * 8192), 16, 0, 0); } while (0)
; #define PG8_LDA(dst, b, h) do { _Pragma("unroll") for (int m = 0; m < 4; ++m) _Pragma("unroll") for (int k = 0; k < 2; ++k) dst[m][k] = *(const PG8_LAS bf16x8*)(lds + PG8_SA(b, h) + aoff + m * 2048 + k * 1024); } while (0)
; #define PG8_LDB(dst, b, h) do { _Pragma("unroll") for (int n = 0; n < 2; ++n) _Pragma("unroll") for (int k = 0; k < 2; ++k) dst[n][k] = *(const PG8_LAS bf16x8*)(lds + PG8_SB(b, h) + boff + n * 2048 + k * 1024); } while (0)
; #define PG8_MMA(ai, bj, At, Bt) do { __builtin_amdgcn_s_setprio(1); _Pragma("unroll") for (int m = 0; m < 4; ++m) _Pragma("unroll") for (int n = 0; n < 2; ++n) _Pragma("unroll") for (int k = 0; k < 2; ++k) \
;         acc[ai][bj][m][n] = __builtin_amdgcn_mfma_f32_16x16x32_bf16(Bt[n][k], At[m][k], acc[ai][bj][m][n], 0, 0, 0); __builtin_amdgcn_s_setprio(0); } while (0)
; #define PG8_WAIT_V(n) asm volatile("s_waitcnt vmcnt(" #n ")" ::: "memory")
; #define PG8_WAIT_L(n) asm volatile("s_waitcnt lgkmcnt(" #n ")" ::: "memory")
; #define PG8_BAR __builtin_amdgcn_s_barrier()
; #define PG8_SCHED __builtin_amdgcn_sched_barrier(0)
; template <class Epi, class Sched, bool ALIGN_EPI = false, bool SP2 = false>
; __device__ __forceinline__ void gemm_phase(PG8_LAS unsigned char* lds, const Gemm g, const Sched& S, const Epi& E) {
;     ...
;             PG8_LDB(B0, 0, 0); PG8_LDB(B1, 0, 1); PG8_SCHED; PG8_LDA(At, 0, 0); PG8_STAGE(PG8_SA(1, 1), a1 + hstep, voffA);
;             PG8_WAIT_V(8); PG8_WAIT_L(0); PG8_BAR; PG8_MMA(0, 0, At, B0); PG8_MMA(0, 1, At, B1); PG8_BAR; PG8_SCHED;
;             PG8_LDA(At, 0, 1); PG8_STAGE(PG8_SB(0, 0), b2, voffB); PG8_STAGE(PG8_SB(0, 1), b2 + hstep, voffB); PG8_STAGE(PG8_SA(0, 0), a2, voffA);
;             PG8_WAIT_V(8); PG8_WAIT_L(0); PG8_BAR; PG8_MMA(1, 0, At, B0); PG8_MMA(1, 1, At, B1); PG8_BAR; PG8_SCHED;
.LBB0_1192:
	s_add_i32 vcc_hi, s52, 2
	s_add_u32 s80, s50, 0x80
	s_addc_u32 s53, s51, 0
	s_add_i32 s36, 0, 0x10000
	s_cmp_eq_u32 s93, s52
	s_cselect_b32 s53, s9, s53
	s_cselect_b32 s52, s8, s80
	v_add_u32_e32 v0, s36, v171
	s_cselect_b32 s81, s49, vcc_lo
	s_cselect_b32 s80, s48, s77
	s_add_i32 s37, 0, 0x14000
	ds_read_b128 v[138:141], v0
	ds_read_b128 v[142:145], v0 offset:1024
	ds_read_b128 v[146:149], v0 offset:2048
	ds_read_b128 v[150:153], v0 offset:3072
	v_add_u32_e32 v0, s37, v171
	ds_read_b128 v[154:157], v0
	ds_read_b128 v[158:161], v0 offset:1024
	ds_read_b128 v[166:169], v0 offset:2048
	ds_read_b128 v[180:183], v0 offset:3072
	v_lshl_add_u64 v[162:163], s[50:51], 0, v[136:137]
	s_add_i32 m0, s42, 0xc000
	ds_read_b128 v[194:197], v176
	ds_read_b128 v[198:201], v176 offset:1024
	ds_read_b128 v[202:205], v176 offset:2048
	ds_read_b128 v[206:209], v176 offset:3072
	ds_read_b128 v[212:215], v176 offset:4096
	ds_read_b128 v[226:229], v176 offset:5120
	ds_read_b128 v[230:233], v176 offset:6144
	ds_read_b128 v[234:237], v176 offset:7168
	global_load_lds_dwordx4 v[162:163], off
	v_lshl_add_u64 v[162:163], s[50:51], 0, v[134:135]
	s_add_i32 m0, s42, 0xe000
	s_nop 0
	global_load_lds_dwordx4 v[162:163], off
	s_waitcnt vmcnt(8)
	s_waitcnt lgkmcnt(0)
	s_barrier
	s_setprio 1
	v_mfma_f32_16x16x32_bf16 v[126:129], v[138:141], v[194:197], v[126:129]
	v_mfma_f32_16x16x32_bf16 v[122:125], v[146:149], v[194:197], v[122:125]
	v_mfma_f32_16x16x32_bf16 v[110:113], v[138:141], v[202:205], v[110:113]
	v_mfma_f32_16x16x32_bf16 v[106:109], v[146:149], v[202:205], v[106:109]
	v_mfma_f32_16x16x32_bf16 v[94:97], v[138:141], v[212:215], v[94:97]
	v_mfma_f32_16x16x32_bf16 v[90:93], v[146:149], v[212:215], v[90:93]
	v_mfma_f32_16x16x32_bf16 v[78:81], v[138:141], v[230:233], v[78:81]
	v_mfma_f32_16x16x32_bf16 v[74:77], v[146:149], v[230:233], v[74:77]
	v_mfma_f32_16x16x32_bf16 v[126:129], v[142:145], v[198:201], v[126:129]
	v_mfma_f32_16x16x32_bf16 v[122:125], v[150:153], v[198:201], v[122:125]
	v_mfma_f32_16x16x32_bf16 v[110:113], v[142:145], v[206:209], v[110:113]
	v_mfma_f32_16x16x32_bf16 v[106:109], v[150:153], v[206:209], v[106:109]
	v_mfma_f32_16x16x32_bf16 v[94:97], v[142:145], v[226:229], v[94:97]
	v_mfma_f32_16x16x32_bf16 v[90:93], v[150:153], v[226:229], v[90:93]
	v_mfma_f32_16x16x32_bf16 v[78:81], v[142:145], v[234:237], v[78:81]
	v_mfma_f32_16x16x32_bf16 v[74:77], v[150:153], v[234:237], v[74:77]
	s_setprio 0
	s_setprio 1
	v_mfma_f32_16x16x32_bf16 v[118:121], v[154:157], v[194:197], v[118:121]
	v_mfma_f32_16x16x32_bf16 v[114:117], v[166:169], v[194:197], v[114:117]
	v_mfma_f32_16x16x32_bf16 v[102:105], v[154:157], v[202:205], v[102:105]
	v_mfma_f32_16x16x32_bf16 v[98:101], v[166:169], v[202:205], v[98:101]
	v_mfma_f32_16x16x32_bf16 v[86:89], v[154:157], v[212:215], v[86:89]
	v_mfma_f32_16x16x32_bf16 v[82:85], v[166:169], v[212:215], v[82:85]
	v_mfma_f32_16x16x32_bf16 v[70:73], v[154:157], v[230:233], v[70:73]
	v_mfma_f32_16x16x32_bf16 v[66:69], v[166:169], v[230:233], v[66:69]
	v_mfma_f32_16x16x32_bf16 v[118:121], v[158:161], v[198:201], v[118:121]
	v_mfma_f32_16x16x32_bf16 v[114:117], v[180:183], v[198:201], v[114:117]
	v_mfma_f32_16x16x32_bf16 v[102:105], v[158:161], v[206:209], v[102:105]
	v_mfma_f32_16x16x32_bf16 v[98:101], v[180:183], v[206:209], v[98:101]
	v_mfma_f32_16x16x32_bf16 v[86:89], v[158:161], v[226:229], v[86:89]
	v_mfma_f32_16x16x32_bf16 v[82:85], v[180:183], v[226:229], v[82:85]
	v_mfma_f32_16x16x32_bf16 v[70:73], v[158:161], v[234:237], v[70:73]
	v_mfma_f32_16x16x32_bf16 v[66:69], v[180:183], v[234:237], v[66:69]
	s_setprio 0
	s_barrier
	s_add_i32 s36, s36, s41
	v_lshl_add_u64 v[162:163], s[80:81], 0, v[130:131]
	s_mov_b32 m0, s36
	ds_read_b128 v[194:197], v176 offset:16384
	ds_read_b128 v[198:201], v176 offset:17408
	ds_read_b128 v[202:205], v176 offset:18432
	ds_read_b128 v[206:209], v176 offset:19456
	ds_read_b128 v[212:215], v176 offset:20480
	ds_read_b128 v[226:229], v176 offset:21504
	ds_read_b128 v[230:233], v176 offset:22528
	ds_read_b128 v[234:237], v176 offset:23552
	global_load_lds_dwordx4 v[162:163], off
	s_add_i32 m0, s36, 0x2000
	v_lshl_add_u64 v[184:185], s[80:81], 0, v[132:133]
	s_add_u32 s80, s80, s18
	s_addc_u32 s81, s81, s19
	s_add_i32 s36, s37, s41
	global_load_lds_dwordx4 v[184:185], off
	v_lshl_add_u64 v[216:217], s[80:81], 0, v[130:131]
	s_mov_b32 m0, s36
	v_lshl_add_u64 v[238:239], s[80:81], 0, v[132:133]
	global_load_lds_dwordx4 v[216:217], off
	s_add_i32 m0, s36, 0x2000
	v_lshl_add_u64 v[240:241], s[52:53], 0, v[130:131]
	global_load_lds_dwordx4 v[238:239], off
	s_mov_b32 m0, s42
	v_lshl_add_u64 v[242:243], s[52:53], 0, v[132:133]
	global_load_lds_dwordx4 v[240:241], off
	s_mov_b32 m0, s43
	s_nop 0
	global_load_lds_dwordx4 v[242:243], off
	s_waitcnt vmcnt(8)
	s_waitcnt lgkmcnt(0)
	s_barrier
; #define PG8_STAGE(bufoff, gbase, voff) do { _Pragma("unroll") for (int _i = 0; _i < 2; ++_i) \
;         __builtin_amdgcn_global_load_lds((const unsigned*)((const char*)(gbase) + (voff)[_i]), (PG8_LAS unsigned*)(lds + (bufoff) + ldsw + _i * 8192), 16, 0, 0); } while (0)
; #define PG8_LDA(dst, b, h) do { _Pragma("unroll") for (int m = 0; m < 4; ++m) _Pragma("unroll") for (int k = 0; k < 2; ++k) dst[m][k] = *(const PG8_LAS bf16x8*)(lds + PG8_SA(b, h) + aoff + m * 2048 + k * 1024); } while (0)
; #define PG8_LDB(dst, b, h) do { _Pragma("unroll") for (int n = 0; n < 2; ++n) _Pragma("unroll") for (int k = 0; k < 2; ++k) dst[n][k] = *(const PG8_LAS bf16x8*)(lds + PG8_SB(b, h) + boff + n * 2048 + k * 1024); } while (0)
; #define PG8_MMA(ai, bj, At, Bt) do { __builtin_amdgcn_s_setprio(1); _Pragma("unroll") for (int m = 0; m < 4; ++m) _Pragma("unroll") for (int n = 0; n < 2; ++n) _Pragma("unroll") for (int k = 0; k < 2; ++k) \
;         acc[ai][bj][m][n] = __builtin_amdgcn_mfma_f32_16x16x32_bf16(Bt[n][k], At[m][k], acc[ai][bj][m][n], 0, 0, 0); __builtin_amdgcn_s_setprio(0); } while (0)
; #define PG8_WAIT_V(n) asm volatile("s_waitcnt vmcnt(" #n ")" ::: "memory")
; #define PG8_WAIT_L(n) asm volatile("s_waitcnt lgkmcnt(" #n ")" ::: "memory")
; #define PG8_BAR __builtin_amdgcn_s_barrier()
; #define PG8_SCHED __builtin_amdgcn_sched_barrier(0)
; template <class Epi, class Sched, bool ALIGN_EPI = false, bool SP2 = false>
; __device__ __forceinline__ void gemm_phase(PG8_LAS unsigned char* lds, const Gemm g, const Sched& S, const Epi& E) {
;     ...
;             PG8_WAIT_V(8); PG8_WAIT_L(0); PG8_BAR; PG8_MMA(1, 0, At, B0); PG8_MMA(1, 1, At, B1); PG8_BAR; PG8_SCHED;
;             PG8_LDB(B0, 1, 0); PG8_LDB(B1, 1, 1); PG8_SCHED; PG8_LDA(At, 1, 0); PG8_STAGE(PG8_SA(0, 1), a2 + hstep, voffA);
;             PG8_WAIT_V(8); PG8_WAIT_L(0); PG8_BAR; PG8_MMA(0, 0, At, B0); PG8_MMA(0, 1, At, B1); PG8_BAR; PG8_SCHED;
	s_setprio 1
	v_mfma_f32_16x16x32_bf16 v[62:65], v[138:141], v[194:197], v[62:65]
	v_mfma_f32_16x16x32_bf16 v[58:61], v[146:149], v[194:197], v[58:61]
	v_mfma_f32_16x16x32_bf16 v[46:49], v[138:141], v[202:205], v[46:49]
	v_mfma_f32_16x16x32_bf16 v[42:45], v[146:149], v[202:205], v[42:45]
	v_mfma_f32_16x16x32_bf16 v[30:33], v[138:141], v[212:215], v[30:33]
	v_mfma_f32_16x16x32_bf16 v[26:29], v[146:149], v[212:215], v[26:29]
	v_mfma_f32_16x16x32_bf16 v[14:17], v[138:141], v[230:233], v[14:17]
	v_mfma_f32_16x16x32_bf16 v[10:13], v[146:149], v[230:233], v[10:13]
	v_mfma_f32_16x16x32_bf16 v[62:65], v[142:145], v[198:201], v[62:65]
	v_mfma_f32_16x16x32_bf16 v[58:61], v[150:153], v[198:201], v[58:61]
	v_mfma_f32_16x16x32_bf16 v[46:49], v[142:145], v[206:209], v[46:49]
	v_mfma_f32_16x16x32_bf16 v[42:45], v[150:153], v[206:209], v[42:45]
	v_mfma_f32_16x16x32_bf16 v[30:33], v[142:145], v[226:229], v[30:33]
	v_mfma_f32_16x16x32_bf16 v[26:29], v[150:153], v[226:229], v[26:29]
	v_mfma_f32_16x16x32_bf16 v[14:17], v[142:145], v[234:237], v[14:17]
	v_mfma_f32_16x16x32_bf16 v[10:13], v[150:153], v[234:237], v[10:13]
	s_setprio 0
	s_setprio 1
	v_mfma_f32_16x16x32_bf16 v[54:57], v[154:157], v[194:197], v[54:57]
	v_mfma_f32_16x16x32_bf16 v[50:53], v[166:169], v[194:197], v[50:53]
	v_mfma_f32_16x16x32_bf16 v[38:41], v[154:157], v[202:205], v[38:41]
	v_mfma_f32_16x16x32_bf16 v[34:37], v[166:169], v[202:205], v[34:37]
	v_mfma_f32_16x16x32_bf16 v[22:25], v[154:157], v[212:215], v[22:25]
	v_mfma_f32_16x16x32_bf16 v[18:21], v[166:169], v[212:215], v[18:21]
	v_mfma_f32_16x16x32_bf16 v[6:9], v[154:157], v[230:233], v[6:9]
	v_mfma_f32_16x16x32_bf16 v[2:5], v[166:169], v[230:233], v[2:5]
	v_mfma_f32_16x16x32_bf16 v[54:57], v[158:161], v[198:201], v[54:57]
	v_mfma_f32_16x16x32_bf16 v[50:53], v[180:183], v[198:201], v[50:53]
	v_mfma_f32_16x16x32_bf16 v[38:41], v[158:161], v[206:209], v[38:41]
	v_mfma_f32_16x16x32_bf16 v[34:37], v[180:183], v[206:209], v[34:37]
	v_mfma_f32_16x16x32_bf16 v[22:25], v[158:161], v[226:229], v[22:25]
	v_mfma_f32_16x16x32_bf16 v[18:21], v[180:183], v[226:229], v[18:21]
	v_mfma_f32_16x16x32_bf16 v[6:9], v[158:161], v[234:237], v[6:9]
	v_mfma_f32_16x16x32_bf16 v[2:5], v[180:183], v[234:237], v[2:5]
	s_setprio 0
	s_barrier
	s_add_i32 s36, 0, 0x18000
	v_add_u32_e32 v0, s36, v171
	s_add_i32 s37, 0, 0x1c000
	ds_read_b128 v[138:141], v0
	ds_read_b128 v[142:145], v0 offset:1024
	ds_read_b128 v[146:149], v0 offset:2048
	ds_read_b128 v[150:153], v0 offset:3072
	v_add_u32_e32 v0, s37, v171
	ds_read_b128 v[154:157], v0
	ds_read_b128 v[158:161], v0 offset:1024
	ds_read_b128 v[166:169], v0 offset:2048
	ds_read_b128 v[180:183], v0 offset:3072
	s_add_u32 s52, s52, s18
	s_addc_u32 s53, s53, s19
	s_mov_b32 m0, s44
	v_lshl_add_u64 v[244:245], s[52:53], 0, v[130:131]
	ds_read_b128 v[194:197], v176 offset:32768
	ds_read_b128 v[198:201], v176 offset:33792
	ds_read_b128 v[202:205], v176 offset:34816
	ds_read_b128 v[206:209], v176 offset:35840
	ds_read_b128 v[212:215], v176 offset:36864
	ds_read_b128 v[226:229], v176 offset:37888
	ds_read_b128 v[230:233], v176 offset:38912
	ds_read_b128 v[234:237], v176 offset:39936
	global_load_lds_dwordx4 v[244:245], off
	v_lshl_add_u64 v[244:245], s[52:53], 0, v[132:133]
	s_mov_b32 m0, s45
	s_nop 0
	global_load_lds_dwordx4 v[244:245], off
	s_waitcnt vmcnt(8)
	s_waitcnt lgkmcnt(0)
	s_barrier
	s_setprio 1
	v_mfma_f32_16x16x32_bf16 v[126:129], v[138:141], v[194:197], v[126:129]
	v_mfma_f32_16x16x32_bf16 v[122:125], v[146:149], v[194:197], v[122:125]
	v_mfma_f32_16x16x32_bf16 v[110:113], v[138:141], v[202:205], v[110:113]
	v_mfma_f32_16x16x32_bf16 v[106:109], v[146:149], v[202:205], v[106:109]
	v_mfma_f32_16x16x32_bf16 v[94:97], v[138:141], v[212:215], v[94:97]
	v_mfma_f32_16x16x32_bf16 v[90:93], v[146:149], v[212:215], v[90:93]
	v_mfma_f32_16x16x32_bf16 v[78:81], v[138:141], v[230:233], v[78:81]
	v_mfma_f32_16x16x32_bf16 v[74:77], v[146:149], v[230:233], v[74:77]
	v_mfma_f32_16x16x32_bf16 v[126:129], v[142:145], v[198:201], v[126:129]
	v_mfma_f32_16x16x32_bf16 v[122:125], v[150:153], v[198:201], v[122:125]
	v_mfma_f32_16x16x32_bf16 v[110:113], v[142:145], v[206:209], v[110:113]
	v_mfma_f32_16x16x32_bf16 v[106:109], v[150:153], v[206:209], v[106:109]
	v_mfma_f32_16x16x32_bf16 v[94:97], v[142:145], v[226:229], v[94:97]
	v_mfma_f32_16x16x32_bf16 v[90:93], v[150:153], v[226:229], v[90:93]
	v_mfma_f32_16x16x32_bf16 v[78:81], v[142:145], v[234:237], v[78:81]
	v_mfma_f32_16x16x32_bf16 v[74:77], v[150:153], v[234:237], v[74:77]
	s_setprio 0
	s_setprio 1
	v_mfma_f32_16x16x32_bf16 v[118:121], v[154:157], v[194:197], v[118:121]
	v_mfma_f32_16x16x32_bf16 v[114:117], v[166:169], v[194:197], v[114:117]
	v_mfma_f32_16x16x32_bf16 v[102:105], v[154:157], v[202:205], v[102:105]
	v_mfma_f32_16x16x32_bf16 v[98:101], v[166:169], v[202:205], v[98:101]
	v_mfma_f32_16x16x32_bf16 v[86:89], v[154:157], v[212:215], v[86:89]
	v_mfma_f32_16x16x32_bf16 v[82:85], v[166:169], v[212:215], v[82:85]
	v_mfma_f32_16x16x32_bf16 v[70:73], v[154:157], v[230:233], v[70:73]
	v_mfma_f32_16x16x32_bf16 v[66:69], v[166:169], v[230:233], v[66:69]
	v_mfma_f32_16x16x32_bf16 v[118:121], v[158:161], v[198:201], v[118:121]
	v_mfma_f32_16x16x32_bf16 v[114:117], v[180:183], v[198:201], v[114:117]
	v_mfma_f32_16x16x32_bf16 v[102:105], v[158:161], v[206:209], v[102:105]
	v_mfma_f32_16x16x32_bf16 v[98:101], v[180:183], v[206:209], v[98:101]
	v_mfma_f32_16x16x32_bf16 v[86:89], v[158:161], v[226:229], v[86:89]
	v_mfma_f32_16x16x32_bf16 v[82:85], v[180:183], v[226:229], v[82:85]
	v_mfma_f32_16x16x32_bf16 v[70:73], v[158:161], v[234:237], v[70:73]
	v_mfma_f32_16x16x32_bf16 v[66:69], v[180:183], v[234:237], v[66:69]
	s_setprio 0
	s_barrier
; #define PG8_STAGE(bufoff, gbase, voff) do { _Pragma("unroll") for (int _i = 0; _i < 2; ++_i) \
;         __builtin_amdgcn_global_load_lds((const unsigned*)((const char*)(gbase) + (voff)[_i]), (PG8_LAS unsigned*)(lds + (bufoff) + ldsw + _i * 8192), 16, 0, 0); } while (0)
; #define PG8_LDA(dst, b, h) do { _Pragma("unroll") for (int m = 0; m < 4; ++m) _Pragma("unroll") for (int k = 0; k < 2; ++k) dst[m][k] = *(const PG8_LAS bf16x8*)(lds + PG8_SA(b, h) + aoff + m * 2048 + k * 1024); } while (0)
; #define PG8_MMA(ai, bj, At, Bt) do { __builtin_amdgcn_s_setprio(1); _Pragma("unroll") for (int m = 0; m < 4; ++m) _Pragma("unroll") for (int n = 0; n < 2; ++n) _Pragma("unroll") for (int k = 0; k < 2; ++k) \
;         acc[ai][bj][m][n] = __builtin_amdgcn_mfma_f32_16x16x32_bf16(Bt[n][k], At[m][k], acc[ai][bj][m][n], 0, 0, 0); __builtin_amdgcn_s_setprio(0); } while (0)
; #define PG8_WAIT_V(n) asm volatile("s_waitcnt vmcnt(" #n ")" ::: "memory")
; #define PG8_WAIT_L(n) asm volatile("s_waitcnt lgkmcnt(" #n ")" ::: "memory")
; #define PG8_BAR __builtin_amdgcn_s_barrier()
; #define PG8_SCHED __builtin_amdgcn_sched_barrier(0)
; template <class Epi, class Sched, bool ALIGN_EPI = false, bool SP2 = false>
; __device__ __forceinline__ void gemm_phase(PG8_LAS unsigned char* lds, const Gemm g, const Sched& S, const Epi& E) {
;     ...
;         for (int t = 0; t < nt; t += 2) {
;             const bool last = (t == nt - 2);
;             const char* a1 = cA + (size_t)(t + 1) * kstep;
;             const char* a2 = last ? nA : cA + (size_t)(t + 2) * kstep; const char* b2 = last ? nB : cB + (size_t)(t + 2) * kstep;
;             const char* a3 = a2 + kstep; const char* b3 = b2 + kstep;
;     ...
;             PG8_LDA(At, 1, 1); PG8_STAGE(PG8_SB(1, 0), b3, voffB); PG8_STAGE(PG8_SB(1, 1), b3 + hstep, voffB); PG8_STAGE(PG8_SA(1, 0), a3, voffA);
;             PG8_WAIT_V(8); PG8_WAIT_L(0); PG8_BAR; PG8_MMA(1, 0, At, B0); PG8_MMA(1, 1, At, B1); PG8_BAR; PG8_SCHED;
	s_add_i32 s36, s36, s41
	v_lshl_add_u64 v[162:163], v[162:163], 0, s[38:39]
	s_mov_b32 m0, s36
	ds_read_b128 v[194:197], v176 offset:49152
	ds_read_b128 v[198:201], v176 offset:50176
	ds_read_b128 v[202:205], v176 offset:51200
	ds_read_b128 v[206:209], v176 offset:52224
	ds_read_b128 v[212:215], v176 offset:53248
	ds_read_b128 v[226:229], v176 offset:54272
	ds_read_b128 v[230:233], v176 offset:55296
	ds_read_b128 v[234:237], v176 offset:56320
	global_load_lds_dwordx4 v[162:163], off
	v_lshl_add_u64 v[162:163], v[184:185], 0, s[38:39]
	s_add_i32 m0, s36, 0x2000
	s_add_i32 s36, s37, s41
	global_load_lds_dwordx4 v[162:163], off
	v_lshl_add_u64 v[162:163], v[216:217], 0, s[38:39]
	s_mov_b32 m0, s36
	s_nop 0
	global_load_lds_dwordx4 v[162:163], off
	v_lshl_add_u64 v[162:163], v[238:239], 0, s[38:39]
	s_add_i32 m0, s36, 0x2000
	s_nop 0
	global_load_lds_dwordx4 v[162:163], off
	v_lshl_add_u64 v[162:163], v[240:241], 0, s[38:39]
	s_mov_b32 m0, s83
	s_nop 0
	global_load_lds_dwordx4 v[162:163], off
	v_lshl_add_u64 v[162:163], v[242:243], 0, s[38:39]
	s_mov_b32 m0, s92
	s_nop 0
	global_load_lds_dwordx4 v[162:163], off
	s_waitcnt vmcnt(8)
	s_waitcnt lgkmcnt(0)
	s_barrier
	s_setprio 1
	v_mfma_f32_16x16x32_bf16 v[62:65], v[138:141], v[194:197], v[62:65]
	v_mfma_f32_16x16x32_bf16 v[58:61], v[146:149], v[194:197], v[58:61]
	v_mfma_f32_16x16x32_bf16 v[46:49], v[138:141], v[202:205], v[46:49]
	v_mfma_f32_16x16x32_bf16 v[42:45], v[146:149], v[202:205], v[42:45]
	v_mfma_f32_16x16x32_bf16 v[30:33], v[138:141], v[212:215], v[30:33]
	v_mfma_f32_16x16x32_bf16 v[26:29], v[146:149], v[212:215], v[26:29]
	v_mfma_f32_16x16x32_bf16 v[14:17], v[138:141], v[230:233], v[14:17]
	v_mfma_f32_16x16x32_bf16 v[10:13], v[146:149], v[230:233], v[10:13]
	v_mfma_f32_16x16x32_bf16 v[62:65], v[142:145], v[198:201], v[62:65]
	v_mfma_f32_16x16x32_bf16 v[58:61], v[150:153], v[198:201], v[58:61]
	v_mfma_f32_16x16x32_bf16 v[46:49], v[142:145], v[206:209], v[46:49]
	v_mfma_f32_16x16x32_bf16 v[42:45], v[150:153], v[206:209], v[42:45]
	v_mfma_f32_16x16x32_bf16 v[30:33], v[142:145], v[226:229], v[30:33]
	v_mfma_f32_16x16x32_bf16 v[26:29], v[150:153], v[226:229], v[26:29]
	v_mfma_f32_16x16x32_bf16 v[14:17], v[142:145], v[234:237], v[14:17]
	v_mfma_f32_16x16x32_bf16 v[10:13], v[150:153], v[234:237], v[10:13]
	s_setprio 0
	s_setprio 1
	v_mfma_f32_16x16x32_bf16 v[54:57], v[154:157], v[194:197], v[54:57]
	v_mfma_f32_16x16x32_bf16 v[50:53], v[166:169], v[194:197], v[50:53]
	v_mfma_f32_16x16x32_bf16 v[38:41], v[154:157], v[202:205], v[38:41]
	v_mfma_f32_16x16x32_bf16 v[34:37], v[166:169], v[202:205], v[34:37]
	v_mfma_f32_16x16x32_bf16 v[22:25], v[154:157], v[212:215], v[22:25]
	v_mfma_f32_16x16x32_bf16 v[18:21], v[166:169], v[212:215], v[18:21]
	v_mfma_f32_16x16x32_bf16 v[6:9], v[154:157], v[230:233], v[6:9]
	v_mfma_f32_16x16x32_bf16 v[2:5], v[166:169], v[230:233], v[2:5]
	v_mfma_f32_16x16x32_bf16 v[54:57], v[158:161], v[198:201], v[54:57]
	v_mfma_f32_16x16x32_bf16 v[50:53], v[180:183], v[198:201], v[50:53]
	v_mfma_f32_16x16x32_bf16 v[38:41], v[158:161], v[206:209], v[38:41]
	v_mfma_f32_16x16x32_bf16 v[34:37], v[180:183], v[206:209], v[34:37]
	v_mfma_f32_16x16x32_bf16 v[22:25], v[158:161], v[226:229], v[22:25]
	v_mfma_f32_16x16x32_bf16 v[18:21], v[180:183], v[226:229], v[18:21]
	v_mfma_f32_16x16x32_bf16 v[6:9], v[158:161], v[234:237], v[6:9]
	v_mfma_f32_16x16x32_bf16 v[2:5], v[180:183], v[234:237], v[2:5]
	s_setprio 0
	s_barrier
	s_add_u32 s77, s77, 0x100
	s_addc_u32 vcc_lo, vcc_lo, 0
	s_add_u32 s50, s50, 0x100
	s_addc_u32 s51, s51, 0
	s_cmp_ge_i32 vcc_hi, s67
	s_mov_b32 s52, vcc_hi
	s_cbranch_scc0 .LBB0_1192

; __device__ __forceinline__ float xsum_rows(float v) { return xsum32(xsum16(v)); }
;     template <int AI, int M0, int NR>
;     __device__ __forceinline__ void batch(const f32x4 (&acc)[2][2][4][2], int row0, int col0, int wr, int wc, int fr, int fq, PG8_LAS float* red, const PG8_LAS float* gl) const {
;     ...
;         for (int mm = 0; mm < NR; ++mm) { const unsigned rr_ = (unsigned)(row0 + AI * HALF + (M0 + mm) * 16); stv[mm] = *(const f32x2*)(stp + (8u * rr_ + 2u * (unsigned)fq));
; #pragma unroll
;             for (int bj = 0; bj < 2; ++bj)
; #pragma unroll
;                 for (int n = 0; n < 2; ++n) { const unsigned cc_ = (unsigned)(col0 + bj * HALF + n * 16);
;                     xh[mm][bj][n] = *(const f32x2*)(PB + (rr_ * 1024u + cc_)); xl[mm][bj][n] = *(const f32x2*)((const bf16_t*)X + (rr_ * 2048u + 1024u + cc_)); } }
; #pragma unroll
;         for (int mm = 0; mm < NR; ++mm) { const int m = M0 + mm; const int row = row0 + AI * HALF + m * 16;
;             float rs, ms; { f32x2 v = stv[mm]; v.x = xsum_rows(v.x); v.y = xsum_rows(v.y);
;               const float mean = v.x * (1.0f / 1024.0f); const float var = v.y * (1.0f / 1024.0f) - mean * mean; rs = __builtin_amdgcn_rsqf(var + 1e-5f); ms = rs * mean; }
;             const unsigned ro = (unsigned)row * 1024u + (unsigned)col0;
;             float sm = 0.f, sq = 0.f;
; #pragma unroll
;             for (int bj = 0; bj < 2; ++bj)
; #pragma unroll
;                 for (int n = 0; n < 2; ++n) { const unsigned hw0 = __float_as_uint(xh[mm][bj][n].x), hw1 = __float_as_uint(xh[mm][bj][n].y), lw0 = __float_as_uint(xl[mm][bj][n].x), lw1 = __float_as_uint(xl[mm][bj][n].y);
;                     f32x4 x; x[0] = __uint_as_float(hw0 << 16) + __uint_as_float(lw0 << 16); x[1] = __uint_as_float(hw0 & 0xffff0000u) + __uint_as_float(lw0 & 0xffff0000u);
;                     x[2] = __uint_as_float(hw1 << 16) + __uint_as_float(lw1 << 16); x[3] = __uint_as_float(hw1 & 0xffff0000u) + __uint_as_float(lw1 & 0xffff0000u);
;                     const f32x4 gvv = *(const PG8_LAS f32x4*)(gl + bj * HALF + n * 16), bvv = *(const PG8_LAS f32x4*)(gl + 1024 + bj * HALF + n * 16);
;                     const f32x4 xn = (x * rs - ms) * gvv + bvv; const f32x4 y = xn * alpha + acc[AI][bj][m][n] * s;
;                     const unsigned nh0 = cvt_pk_bf16(y[0], y[1]), nh1 = cvt_pk_bf16(y[2], y[3]);
.LBB0_1195:
	s_lshl_b32 s52, s75, 8
	v_lshl_or_b32 v182, s40, 8, v172
	v_add_u32_e32 v183, s52, v165
	v_lshl_add_u32 v0, v182, 2, 0
	v_add_u32_e32 v179, 0x24000, v0
	v_lshl_or_b32 v0, v183, 3, v173
	v_lshl_add_u64 v[138:139], v[0:1], 2, s[28:29]
	global_load_dwordx2 v[196:197], v[138:139], off
	v_lshlrev_b32_e32 v140, 10, v183
	v_lshlrev_b32_e32 v170, 11, v183
	v_add_u32_e32 v0, v140, v182
	v_or_b32_e32 v141, 0x400, v170
	v_lshl_add_u64 v[204:205], v[0:1], 1, s[26:27]
	global_load_dwordx2 v[198:199], v[204:205], off
	v_add_u32_e32 v138, v141, v182
	v_mov_b32_e32 v139, v1
	v_lshl_add_u64 v[138:139], v[138:139], 1, s[12:13]
	global_load_dwordx2 v[200:201], v[138:139], off
	v_or_b32_e32 v184, 16, v182
	v_add_u32_e32 v138, v140, v184
	v_mov_b32_e32 v139, v1
	v_lshl_add_u64 v[138:139], v[138:139], 1, s[26:27]
	global_load_dwordx2 v[206:207], v[138:139], off
	v_add_u32_e32 v138, v141, v184
	v_mov_b32_e32 v139, v1
	v_lshl_add_u64 v[138:139], v[138:139], 1, s[12:13]
	global_load_dwordx2 v[208:209], v[138:139], off
	v_or_b32_e32 v181, 0x80, v182
	v_add_u32_e32 v138, v140, v181
	v_mov_b32_e32 v139, v1
	v_lshl_add_u64 v[138:139], v[138:139], 1, s[26:27]
	global_load_dwordx2 v[166:167], v[138:139], off
	v_add_u32_e32 v138, v141, v181
	v_mov_b32_e32 v139, v1
	v_lshl_add_u64 v[138:139], v[138:139], 1, s[12:13]
	global_load_dwordx2 v[168:169], v[138:139], off
	v_or_b32_e32 v185, 0x90, v182
	v_add_u32_e32 v138, v140, v185
	v_mov_b32_e32 v139, v1
	v_lshl_add_u64 v[138:139], v[138:139], 1, s[26:27]
	global_load_dwordx2 v[160:161], v[138:139], off
	v_add_u32_e32 v138, v141, v185
	v_mov_b32_e32 v139, v1
	v_lshl_add_u64 v[138:139], v[138:139], 1, s[12:13]
	global_load_dwordx2 v[162:163], v[138:139], off
	v_or_b32_e32 v140, 16, v183
	v_lshlrev_b32_e32 v194, 11, v140
	v_or_b32_e32 v143, 0x400, v194
	v_lshl_or_b32 v138, v140, 3, v173
	v_mov_b32_e32 v139, v1
	v_lshlrev_b32_e32 v142, 10, v140
	v_add_u32_e32 v140, v143, v182
	v_mov_b32_e32 v141, v1
	v_lshl_add_u64 v[138:139], v[138:139], 2, s[28:29]
	v_lshl_add_u64 v[140:141], v[140:141], 1, s[12:13]
	global_load_dwordx2 v[158:159], v[138:139], off
	v_add_u32_e32 v138, v142, v182
	v_mov_b32_e32 v139, v1
	global_load_dwordx2 v[156:157], v[140:141], off
	v_add_u32_e32 v140, v142, v184
	v_mov_b32_e32 v141, v1
	v_lshl_add_u64 v[152:153], v[138:139], 1, s[26:27]
	v_lshl_add_u64 v[140:141], v[140:141], 1, s[26:27]
	global_load_dwordx2 v[154:155], v[152:153], off
	global_load_dwordx2 v[148:149], v[140:141], off
	v_add_u32_e32 v140, v143, v184
	v_mov_b32_e32 v141, v1
	v_lshl_add_u64 v[140:141], v[140:141], 1, s[12:13]
	global_load_dwordx2 v[150:151], v[140:141], off
	v_add_u32_e32 v140, v142, v181
	v_mov_b32_e32 v141, v1
	v_lshl_add_u64 v[140:141], v[140:141], 1, s[26:27]
	global_load_dwordx2 v[144:145], v[140:141], off
	v_add_u32_e32 v140, v143, v181
	v_mov_b32_e32 v141, v1
	v_lshl_add_u64 v[140:141], v[140:141], 1, s[12:13]
	global_load_dwordx2 v[146:147], v[140:141], off
	v_add_u32_e32 v140, v142, v185
	v_mov_b32_e32 v141, v1
	v_add_u32_e32 v142, v143, v185
	v_mov_b32_e32 v143, v1
	v_lshl_add_u64 v[140:141], v[140:141], 1, s[26:27]
	v_lshl_add_u64 v[142:143], v[142:143], 1, s[12:13]
	global_load_dwordx2 v[140:141], v[140:141], off
	v_add_u32_e32 v180, 0x400, v182
	global_load_dwordx2 v[142:143], v[142:143], off
	s_waitcnt vmcnt(0) lgkmcnt(0)
	v_mov_b32_e32 v139, v196
	s_nop 1
	v_permlane16_swap_b32_e32 v196, v139
	v_add_f32_e32 v203, v196, v139
	v_mov_b32_e32 v139, v197
	s_nop 1
	v_permlane16_swap_b32_e32 v197, v139
	v_add_f32_e32 v202, v197, v139
	v_mov_b32_e32 v213, v203
	v_mov_b32_e32 v212, v202
	s_nop 0
	v_permlane32_swap_b32_e32 v203, v213
	v_permlane32_swap_b32_e32 v202, v212
	v_pk_add_f32 v[196:197], v[202:203], v[212:213]
	v_lshlrev_b32_e32 v202, 16, v200
	v_pk_mul_f32 v[212:213], v[196:197], s[68:69] op_sel_hi:[1,0]
	v_lshlrev_b32_e32 v196, 16, v198
	v_fma_f32 v139, -v213, v213, v212
	v_add_f32_e32 v139, 0x3727c5ac, v139
	v_and_b32_e32 v197, 0xffff0000, v198
	v_and_b32_e32 v203, 0xffff0000, v200
	v_rsq_f32_e32 v164, v139
	v_pk_add_f32 v[214:215], v[196:197], v[202:203]
	v_lshlrev_b32_e32 v196, 16, v199
	v_and_b32_e32 v197, 0xffff0000, v199
	v_lshlrev_b32_e32 v198, 16, v201
	v_and_b32_e32 v199, 0xffff0000, v201
	v_pk_add_f32 v[216:217], v[196:197], v[198:199]
	ds_read_b128 v[196:199], v179
	ds_read_b128 v[200:203], v179 offset:4096
	v_add_u32_e32 v212, v170, v180
	v_mul_f32_e64 v170, v213, -v164
	v_pk_fma_f32 v[214:215], v[214:215], v[164:165], v[170:171] op_sel_hi:[1,0,0]
	v_pk_fma_f32 v[216:217], v[216:217], v[164:165], v[170:171] op_sel_hi:[1,0,0]
	s_waitcnt lgkmcnt(0)
	v_pk_fma_f32 v[196:197], v[196:197], v[214:215], v[200:201]
	v_pk_fma_f32 v[198:199], v[198:199], v[216:217], v[202:203]
	v_pk_mul_f32 v[196:197], v[196:197], s[60:61] op_sel_hi:[1,0]
	v_pk_mul_f32 v[198:199], v[198:199], s[60:61] op_sel_hi:[1,0]
	v_pk_fma_f32 v[196:197], s[10:11], v[126:127], v[196:197]
	v_pk_fma_f32 v[128:129], s[24:25], v[128:129], v[198:199]
	v_cvt_pk_bf16_f32 v126, v196, v197
	v_mov_b32_e32 v213, v1
	v_cvt_pk_bf16_f32 v127, v128, v129
	global_store_dwordx2 v[204:205], v[126:127], off
	v_lshlrev_b32_e32 v139, 16, v126
	v_and_b32_e32 v126, 0xffff0000, v126
	v_sub_f32_e32 v139, v196, v139
	v_sub_f32_e32 v126, v197, v126
	v_cvt_pk_bf16_f32 v198, v139, v126
	v_lshlrev_b32_e32 v126, 16, v127
	v_and_b32_e32 v127, 0xffff0000, v127
	v_add_f32_e32 v139, v196, v197
	v_add_f32_e32 v195, v128, v129
	v_sub_f32_e32 v127, v129, v127
	v_add_f32_e32 v139, v139, v195
	v_mul_f32_e32 v195, v197, v197
	v_mul_f32_e32 v129, v129, v129
	v_sub_f32_e32 v126, v128, v126
	v_fmac_f32_e32 v195, v196, v196
	v_fmac_f32_e32 v129, v128, v128
	v_cvt_pk_bf16_f32 v199, v126, v127
	v_lshl_add_u64 v[126:127], v[212:213], 1, s[12:13]
	v_add_f32_e32 v195, v195, v129
	v_lshlrev_b32_e32 v128, 16, v206
	v_and_b32_e32 v129, 0xffff0000, v206
	v_lshlrev_b32_e32 v196, 16, v208
	v_and_b32_e32 v197, 0xffff0000, v208
	global_store_dwordx2 v[126:127], v[198:199], off
	v_pk_add_f32 v[128:129], v[128:129], v[196:197]
	v_lshlrev_b32_e32 v196, 16, v207
	v_and_b32_e32 v197, 0xffff0000, v207
	v_lshlrev_b32_e32 v198, 16, v209
	v_and_b32_e32 v199, 0xffff0000, v209
	v_pk_add_f32 v[204:205], v[196:197], v[198:199]
	ds_read_b128 v[196:199], v179 offset:64
	ds_read_b128 v[200:203], v179 offset:4160
	v_pk_fma_f32 v[204:205], v[204:205], v[164:165], v[170:171] op_sel_hi:[1,0,0]
	v_pk_fma_f32 v[128:129], v[128:129], v[164:165], v[170:171] op_sel_hi:[1,0,0]
	v_add_f32_e32 v139, 0, v139
	s_waitcnt lgkmcnt(0)
; __device__ __forceinline__ float xsum_rows(float v) { return xsum32(xsum16(v)); }
; #define PG8_LAS __attribute__((address_space(3)))
; __device__ __forceinline__ unsigned cvt_pk_bf16(float lo, float hi) { unsigned r; asm volatile("v_cvt_pk_bf16_f32 %0, %1, %2" : "=v"(r) : "v"(lo), "v"(hi)); return r; }
;     template <int AI, int M0, int NR>
;     __device__ __forceinline__ void batch(const f32x4 (&acc)[2][2][4][2], int row0, int col0, int wr, int wc, int fr, int fq, PG8_LAS float* red, const PG8_LAS float* gl) const {
;     ...
;                 for (int n = 0; n < 2; ++n) { const unsigned hw0 = __float_as_uint(xh[mm][bj][n].x), hw1 = __float_as_uint(xh[mm][bj][n].y), lw0 = __float_as_uint(xl[mm][bj][n].x), lw1 = __float_as_uint(xl[mm][bj][n].y);
;                     f32x4 x; x[0] = __uint_as_float(hw0 << 16) + __uint_as_float(lw0 << 16); x[1] = __uint_as_float(hw0 & 0xffff0000u) + __uint_as_float(lw0 & 0xffff0000u);
;                     x[2] = __uint_as_float(hw1 << 16) + __uint_as_float(lw1 << 16); x[3] = __uint_as_float(hw1 & 0xffff0000u) + __uint_as_float(lw1 & 0xffff0000u);
;                     const f32x4 gvv = *(const PG8_LAS f32x4*)(gl + bj * HALF + n * 16), bvv = *(const PG8_LAS f32x4*)(gl + 1024 + bj * HALF + n * 16);
;                     const f32x4 xn = (x * rs - ms) * gvv + bvv; const f32x4 y = xn * alpha + acc[AI][bj][m][n] * s;
;                     const unsigned nh0 = cvt_pk_bf16(y[0], y[1]), nh1 = cvt_pk_bf16(y[2], y[3]);
;                     f32x2 w; w.x = __uint_as_float(nh0); w.y = __uint_as_float(nh1); *(f32x2*)(PB + (ro + (unsigned)(bj * HALF + n * 16))) = w;
;                     f32x2 wl; wl.x = __uint_as_float(cvt_pk_bf16(y[0] - __uint_as_float(nh0 << 16), y[1] - __uint_as_float(nh0 & 0xffff0000u))); wl.y = __uint_as_float(cvt_pk_bf16(y[2] - __uint_as_float(nh1 << 16), y[3] - __uint_as_float(nh1 & 0xffff0000u)));
;                     *(f32x2*)((bf16_t*)X + ((unsigned)row * 2048u + 1024u + (unsigned)(col0 + bj * HALF + n * 16))) = wl;
;                     sm += (y[0] + y[1]) + (y[2] + y[3]); sq += (y[0] * y[0] + y[1] * y[1]) + (y[2] * y[2] + y[3] * y[3]); }
;             sm = xsum_rows(sm); sq = xsum_rows(sq);
;             if (fq == 0) { f32x2 pr; pr.x = sm; pr.y = sq; *(PG8_LAS f32x2*)(red + ((AI * HALF + wr * 64 + m * 16 + fr) * 4 + wc) * 2) = pr; }
	v_pk_fma_f32 v[198:199], v[198:199], v[204:205], v[202:203]
	v_pk_fma_f32 v[128:129], v[196:197], v[128:129], v[200:201]
	v_pk_mul_f32 v[196:197], v[198:199], s[60:61] op_sel_hi:[1,0]
	v_pk_mul_f32 v[128:129], v[128:129], s[60:61] op_sel_hi:[1,0]
	v_pk_fma_f32 v[124:125], s[24:25], v[124:125], v[196:197]
	v_or_b32_e32 v196, 16, v0
	v_mov_b32_e32 v197, v1
	v_pk_fma_f32 v[122:123], s[10:11], v[122:123], v[128:129]
	v_lshl_add_u64 v[196:197], v[196:197], 1, s[26:27]
	v_cvt_pk_bf16_f32 v128, v122, v123
	v_cvt_pk_bf16_f32 v129, v124, v125
	global_store_dwordx2 v[196:197], v[128:129], off
	v_lshlrev_b32_e32 v196, 16, v128
	v_and_b32_e32 v128, 0xffff0000, v128
	v_sub_f32_e32 v196, v122, v196
	v_sub_f32_e32 v128, v123, v128
	v_cvt_pk_bf16_f32 v128, v196, v128
	v_lshlrev_b32_e32 v196, 16, v129
	v_and_b32_e32 v129, 0xffff0000, v129
	v_sub_f32_e32 v129, v125, v129
	v_sub_f32_e32 v196, v124, v196
	v_cvt_pk_bf16_f32 v129, v196, v129
	global_store_dwordx2 v[126:127], v[128:129], off offset:32
	v_add_f32_e32 v128, v122, v123
	v_mul_f32_e32 v123, v123, v123
	v_fmac_f32_e32 v123, v122, v122
	v_mul_f32_e32 v122, v125, v125
	v_fmac_f32_e32 v122, v124, v124
	v_add_f32_e32 v122, v123, v122
	v_add_f32_e32 v129, v124, v125
	v_add_f32_e32 v195, v195, v122
	v_lshlrev_b32_e32 v122, 16, v166
	v_and_b32_e32 v123, 0xffff0000, v166
	v_lshlrev_b32_e32 v124, 16, v168
	v_and_b32_e32 v125, 0xffff0000, v168
	v_pk_add_f32 v[196:197], v[122:123], v[124:125]
	v_lshlrev_b32_e32 v122, 16, v167
	v_and_b32_e32 v123, 0xffff0000, v167
	v_lshlrev_b32_e32 v124, 16, v169
	v_and_b32_e32 v125, 0xffff0000, v169
	v_pk_add_f32 v[198:199], v[122:123], v[124:125]
	ds_read_b128 v[122:125], v179 offset:512
	ds_read_b128 v[166:169], v179 offset:4608
	v_pk_fma_f32 v[196:197], v[196:197], v[164:165], v[170:171] op_sel_hi:[1,0,0]
	v_pk_fma_f32 v[198:199], v[198:199], v[164:165], v[170:171] op_sel_hi:[1,0,0]
	v_add_f32_e32 v128, v128, v129
	v_add_f32_e32 v139, v128, v139
	s_waitcnt lgkmcnt(0)
	v_pk_fma_f32 v[124:125], v[198:199], v[124:125], v[168:169]
	v_pk_fma_f32 v[122:123], v[196:197], v[122:123], v[166:167]
	v_or_b32_e32 v128, 0x80, v0
	v_pk_mul_f32 v[122:123], v[122:123], s[60:61] op_sel_hi:[1,0]
	v_pk_mul_f32 v[124:125], v[124:125], s[60:61] op_sel_hi:[1,0]
	v_mov_b32_e32 v129, v1
	v_pk_fma_f32 v[120:121], s[24:25], v[120:121], v[124:125]
	v_pk_fma_f32 v[118:119], s[10:11], v[118:119], v[122:123]
	v_lshl_add_u64 v[124:125], v[128:129], 1, s[26:27]
	v_cvt_pk_bf16_f32 v122, v118, v119
	v_cvt_pk_bf16_f32 v123, v120, v121
	global_store_dwordx2 v[124:125], v[122:123], off
	v_lshlrev_b32_e32 v124, 16, v122
	v_and_b32_e32 v122, 0xffff0000, v122
	v_sub_f32_e32 v124, v118, v124
	v_sub_f32_e32 v122, v119, v122
	v_cvt_pk_bf16_f32 v122, v124, v122
	v_lshlrev_b32_e32 v124, 16, v123
	v_and_b32_e32 v123, 0xffff0000, v123
	v_sub_f32_e32 v123, v121, v123
	v_sub_f32_e32 v124, v120, v124
	v_cvt_pk_bf16_f32 v123, v124, v123
	global_store_dwordx2 v[126:127], v[122:123], off offset:256
	v_add_f32_e32 v122, v118, v119
	v_mul_f32_e32 v119, v119, v119
	v_fmac_f32_e32 v119, v118, v118
	v_mul_f32_e32 v118, v121, v121
	v_fmac_f32_e32 v118, v120, v120
	v_add_f32_e32 v118, v119, v118
	v_add_f32_e32 v123, v120, v121
	v_add_f32_e32 v166, v195, v118
	v_lshlrev_b32_e32 v118, 16, v160
	v_and_b32_e32 v119, 0xffff0000, v160
	v_lshlrev_b32_e32 v120, 16, v162
	v_and_b32_e32 v121, 0xffff0000, v162
	v_add_f32_e32 v122, v122, v123
	v_pk_add_f32 v[128:129], v[118:119], v[120:121]
	v_lshlrev_b32_e32 v118, 16, v161
	v_and_b32_e32 v119, 0xffff0000, v161
	v_lshlrev_b32_e32 v120, 16, v163
	v_and_b32_e32 v121, 0xffff0000, v163
	v_add_f32_e32 v139, v139, v122
	v_pk_add_f32 v[160:161], v[118:119], v[120:121]
	ds_read_b128 v[118:121], v179 offset:576
	ds_read_b128 v[122:125], v179 offset:4672
	v_pk_fma_f32 v[128:129], v[128:129], v[164:165], v[170:171] op_sel_hi:[1,0,0]
	v_pk_fma_f32 v[160:161], v[160:161], v[164:165], v[170:171] op_sel_hi:[1,0,0]
	v_or_b32_e32 v0, 0x90, v0
	s_waitcnt lgkmcnt(0)
	v_pk_fma_f32 v[120:121], v[160:161], v[120:121], v[124:125]
	v_pk_fma_f32 v[118:119], v[128:129], v[118:119], v[122:123]
	v_pk_mul_f32 v[120:121], v[120:121], s[60:61] op_sel_hi:[1,0]
	v_pk_mul_f32 v[118:119], v[118:119], s[60:61] op_sel_hi:[1,0]
	v_pk_fma_f32 v[116:117], s[24:25], v[116:117], v[120:121]
	v_pk_fma_f32 v[114:115], s[10:11], v[114:115], v[118:119]
	v_lshl_add_u64 v[120:121], v[0:1], 1, s[26:27]
	v_cvt_pk_bf16_f32 v118, v114, v115
	v_cvt_pk_bf16_f32 v119, v116, v117
	global_store_dwordx2 v[120:121], v[118:119], off
	v_lshlrev_b32_e32 v0, 16, v118
	v_and_b32_e32 v118, 0xffff0000, v118
	v_sub_f32_e32 v0, v114, v0
	v_sub_f32_e32 v118, v115, v118
	v_cvt_pk_bf16_f32 v118, v0, v118
	v_lshlrev_b32_e32 v0, 16, v119
	v_and_b32_e32 v119, 0xffff0000, v119
	v_sub_f32_e32 v0, v116, v0
	v_sub_f32_e32 v119, v117, v119
	v_cvt_pk_bf16_f32 v119, v0, v119
	v_add_f32_e32 v0, v114, v115
	v_mul_f32_e32 v115, v115, v115
	global_store_dwordx2 v[126:127], v[118:119], off offset:288
	v_add_f32_e32 v118, v116, v117
	v_fmac_f32_e32 v115, v114, v114
	v_mul_f32_e32 v114, v117, v117
	v_add_f32_e32 v0, v0, v118
	v_fmac_f32_e32 v114, v116, v116
	v_add_f32_e32 v0, v139, v0
	v_add_f32_e32 v114, v115, v114
	v_add_f32_e32 v115, v166, v114
	v_mov_b32_e32 v114, v0
	s_nop 1
	v_permlane16_swap_b32_e32 v0, v114
	v_add_f32_e32 v114, v0, v114
	v_mov_b32_e32 v0, v115
	s_nop 1
	v_permlane16_swap_b32_e32 v115, v0
	v_add_f32_e32 v115, v115, v0
	v_mov_b32_e32 v116, v114
	v_mov_b32_e32 v117, v115
	s_nop 0
	v_permlane32_swap_b32_e32 v114, v116
	v_permlane32_swap_b32_e32 v115, v117
	v_add_u32_e32 v160, s61, v174
	s_and_saveexec_b64 s[50:51], s[2:3]
	v_pk_add_f32 v[114:115], v[114:115], v[116:117]
	ds_write_b64 v160, v[114:115]
	s_or_b64 exec, exec, s[50:51]
	v_mov_b32_e32 v0, v158
	s_nop 1
	v_permlane16_swap_b32_e32 v158, v0
	v_add_f32_e32 v115, v158, v0
	v_mov_b32_e32 v0, v159
	s_nop 1
	v_permlane16_swap_b32_e32 v159, v0
	v_add_f32_e32 v114, v159, v0
	v_mov_b32_e32 v117, v115
	v_mov_b32_e32 v116, v114
	s_nop 0
	v_permlane32_swap_b32_e32 v115, v117
	v_permlane32_swap_b32_e32 v114, v116
	v_pk_add_f32 v[114:115], v[114:115], v[116:117]
	v_lshlrev_b32_e32 v116, 16, v154
	v_pk_mul_f32 v[114:115], v[114:115], s[68:69] op_sel_hi:[1,0]
	v_and_b32_e32 v117, 0xffff0000, v154
	v_fma_f32 v0, -v115, v115, v114
	v_add_f32_e32 v0, 0x3727c5ac, v0
	v_lshlrev_b32_e32 v118, 16, v156
	v_and_b32_e32 v119, 0xffff0000, v156
	v_rsq_f32_e32 v114, v0
	v_pk_add_f32 v[126:127], v[116:117], v[118:119]
	v_lshlrev_b32_e32 v116, 16, v155
	v_and_b32_e32 v117, 0xffff0000, v155
	v_lshlrev_b32_e32 v118, 16, v157
	v_and_b32_e32 v119, 0xffff0000, v157
	v_pk_add_f32 v[128:129], v[116:117], v[118:119]
	ds_read_b128 v[118:121], v179
	ds_read_b128 v[122:125], v179 offset:4096
	v_mul_f32_e64 v116, v115, -v114
	v_pk_fma_f32 v[126:127], v[126:127], v[114:115], v[116:117] op_sel_hi:[1,0,0]
	v_pk_fma_f32 v[128:129], v[128:129], v[114:115], v[116:117] op_sel_hi:[1,0,0]
	v_add_u32_e32 v0, v194, v180
	s_waitcnt lgkmcnt(0)
; #define PG8_LAS __attribute__((address_space(3)))
; __device__ __forceinline__ unsigned cvt_pk_bf16(float lo, float hi) { unsigned r; asm volatile("v_cvt_pk_bf16_f32 %0, %1, %2" : "=v"(r) : "v"(lo), "v"(hi)); return r; }
;     template <int AI, int M0, int NR>
;     __device__ __forceinline__ void batch(const f32x4 (&acc)[2][2][4][2], int row0, int col0, int wr, int wc, int fr, int fq, PG8_LAS float* red, const PG8_LAS float* gl) const {
;     ...
;                 for (int n = 0; n < 2; ++n) { const unsigned hw0 = __float_as_uint(xh[mm][bj][n].x), hw1 = __float_as_uint(xh[mm][bj][n].y), lw0 = __float_as_uint(xl[mm][bj][n].x), lw1 = __float_as_uint(xl[mm][bj][n].y);
;                     f32x4 x; x[0] = __uint_as_float(hw0 << 16) + __uint_as_float(lw0 << 16); x[1] = __uint_as_float(hw0 & 0xffff0000u) + __uint_as_float(lw0 & 0xffff0000u);
;                     x[2] = __uint_as_float(hw1 << 16) + __uint_as_float(lw1 << 16); x[3] = __uint_as_float(hw1 & 0xffff0000u) + __uint_as_float(lw1 & 0xffff0000u);
;                     const f32x4 gvv = *(const PG8_LAS f32x4*)(gl + bj * HALF + n * 16), bvv = *(const PG8_LAS f32x4*)(gl + 1024 + bj * HALF + n * 16);
;                     const f32x4 xn = (x * rs - ms) * gvv + bvv; const f32x4 y = xn * alpha + acc[AI][bj][m][n] * s;
;                     const unsigned nh0 = cvt_pk_bf16(y[0], y[1]), nh1 = cvt_pk_bf16(y[2], y[3]);
;                     f32x2 w; w.x = __uint_as_float(nh0); w.y = __uint_as_float(nh1); *(f32x2*)(PB + (ro + (unsigned)(bj * HALF + n * 16))) = w;
;                     f32x2 wl; wl.x = __uint_as_float(cvt_pk_bf16(y[0] - __uint_as_float(nh0 << 16), y[1] - __uint_as_float(nh0 & 0xffff0000u))); wl.y = __uint_as_float(cvt_pk_bf16(y[2] - __uint_as_float(nh1 << 16), y[3] - __uint_as_float(nh1 & 0xffff0000u)));
;                     *(f32x2*)((bf16_t*)X + ((unsigned)row * 2048u + 1024u + (unsigned)(col0 + bj * HALF + n * 16))) = wl;
;                     sm += (y[0] + y[1]) + (y[2] + y[3]); sq += (y[0] * y[0] + y[1] * y[1]) + (y[2] * y[2] + y[3] * y[3]); }
	v_pk_fma_f32 v[118:119], v[118:119], v[126:127], v[122:123]
	v_pk_fma_f32 v[120:121], v[120:121], v[128:129], v[124:125]
	v_pk_mul_f32 v[118:119], v[118:119], s[60:61] op_sel_hi:[1,0]
	v_pk_mul_f32 v[120:121], v[120:121], s[60:61] op_sel_hi:[1,0]
	v_pk_fma_f32 v[118:119], s[10:11], v[110:111], v[118:119]
	v_pk_fma_f32 v[112:113], s[24:25], v[112:113], v[120:121]
	v_cvt_pk_bf16_f32 v110, v118, v119
	s_nop 0
	v_cvt_pk_bf16_f32 v111, v112, v113
	global_store_dwordx2 v[152:153], v[110:111], off
	v_lshlrev_b32_e32 v115, 16, v110
	v_and_b32_e32 v110, 0xffff0000, v110
	v_sub_f32_e32 v110, v119, v110
	v_sub_f32_e32 v115, v118, v115
	v_cvt_pk_bf16_f32 v120, v115, v110
	v_lshlrev_b32_e32 v110, 16, v111
	v_and_b32_e32 v111, 0xffff0000, v111
	v_sub_f32_e32 v110, v112, v110
	v_sub_f32_e32 v111, v113, v111
	v_cvt_pk_bf16_f32 v121, v110, v111
	v_lshl_add_u64 v[110:111], v[0:1], 1, s[12:13]
	v_add_f32_e32 v0, v118, v119
	v_add_f32_e32 v115, v112, v113
	v_add_f32_e32 v0, v0, v115
	v_add_f32_e32 v115, 0, v0
	v_mul_f32_e32 v0, v119, v119
	v_mul_f32_e32 v113, v113, v113
	v_fmac_f32_e32 v0, v118, v118
	v_fmac_f32_e32 v113, v112, v112
	v_add_f32_e32 v117, v0, v113
	v_lshlrev_b32_e32 v112, 16, v148
	v_and_b32_e32 v113, 0xffff0000, v148
	v_lshlrev_b32_e32 v118, 16, v150
	v_and_b32_e32 v119, 0xffff0000, v150
	global_store_dwordx2 v[110:111], v[120:121], off
	v_pk_add_f32 v[112:113], v[112:113], v[118:119]
	v_lshlrev_b32_e32 v118, 16, v149
	v_and_b32_e32 v119, 0xffff0000, v149
	v_lshlrev_b32_e32 v120, 16, v151
	v_and_b32_e32 v121, 0xffff0000, v151
	v_pk_add_f32 v[126:127], v[118:119], v[120:121]
	ds_read_b128 v[118:121], v179 offset:64
	ds_read_b128 v[122:125], v179 offset:4160
	v_pk_fma_f32 v[112:113], v[112:113], v[114:115], v[116:117] op_sel_hi:[1,0,0]
	v_pk_fma_f32 v[126:127], v[126:127], v[114:115], v[116:117] op_sel_hi:[1,0,0]
	v_or_b32_e32 v0, 16, v138
	s_waitcnt lgkmcnt(0)
	v_pk_fma_f32 v[120:121], v[120:121], v[126:127], v[124:125]
	v_pk_fma_f32 v[112:113], v[118:119], v[112:113], v[122:123]
	v_pk_mul_f32 v[118:119], v[120:121], s[60:61] op_sel_hi:[1,0]
	v_pk_mul_f32 v[112:113], v[112:113], s[60:61] op_sel_hi:[1,0]
	v_pk_fma_f32 v[108:109], s[24:25], v[108:109], v[118:119]
	v_pk_fma_f32 v[106:107], s[10:11], v[106:107], v[112:113]
	v_lshl_add_u64 v[118:119], v[0:1], 1, s[26:27]
	v_cvt_pk_bf16_f32 v112, v106, v107
	v_cvt_pk_bf16_f32 v113, v108, v109
	global_store_dwordx2 v[118:119], v[112:113], off
	v_lshlrev_b32_e32 v0, 16, v112
	v_and_b32_e32 v112, 0xffff0000, v112
	v_sub_f32_e32 v0, v106, v0
	v_sub_f32_e32 v112, v107, v112
	v_cvt_pk_bf16_f32 v112, v0, v112
	v_lshlrev_b32_e32 v0, 16, v113
	v_and_b32_e32 v113, 0xffff0000, v113
	v_sub_f32_e32 v0, v108, v0
	v_sub_f32_e32 v113, v109, v113
	v_cvt_pk_bf16_f32 v113, v0, v113
	global_store_dwordx2 v[110:111], v[112:113], off offset:32
	v_add_f32_e32 v0, v106, v107
	v_add_f32_e32 v112, v108, v109
	v_add_f32_e32 v0, v0, v112
	v_add_f32_e32 v115, v0, v115
	v_mul_f32_e32 v0, v107, v107
	v_fmac_f32_e32 v0, v106, v106
	v_mul_f32_e32 v106, v109, v109
	v_fmac_f32_e32 v106, v108, v108
	v_add_f32_e32 v0, v0, v106
	v_lshlrev_b32_e32 v106, 16, v144
	v_and_b32_e32 v107, 0xffff0000, v144
	v_lshlrev_b32_e32 v108, 16, v146
	v_and_b32_e32 v109, 0xffff0000, v146
	v_pk_add_f32 v[112:113], v[106:107], v[108:109]
	v_lshlrev_b32_e32 v106, 16, v145
	v_and_b32_e32 v107, 0xffff0000, v145
	v_lshlrev_b32_e32 v108, 16, v147
	v_and_b32_e32 v109, 0xffff0000, v147
	v_pk_add_f32 v[122:123], v[106:107], v[108:109]
	ds_read_b128 v[106:109], v179 offset:512
	ds_read_b128 v[118:121], v179 offset:4608
	v_add_f32_e32 v117, v117, v0
	v_pk_fma_f32 v[112:113], v[112:113], v[114:115], v[116:117] op_sel_hi:[1,0,0]
	v_pk_fma_f32 v[122:123], v[122:123], v[114:115], v[116:117] op_sel_hi:[1,0,0]
	v_or_b32_e32 v0, 0x80, v138
	s_waitcnt lgkmcnt(0)
	v_pk_fma_f32 v[108:109], v[122:123], v[108:109], v[120:121]
	v_pk_fma_f32 v[106:107], v[112:113], v[106:107], v[118:119]
	v_pk_mul_f32 v[108:109], v[108:109], s[60:61] op_sel_hi:[1,0]
	v_pk_mul_f32 v[106:107], v[106:107], s[60:61] op_sel_hi:[1,0]
	v_pk_fma_f32 v[104:105], s[24:25], v[104:105], v[108:109]
	v_pk_fma_f32 v[102:103], s[10:11], v[102:103], v[106:107]
	v_lshl_add_u64 v[108:109], v[0:1], 1, s[26:27]
	v_cvt_pk_bf16_f32 v106, v102, v103
	v_cvt_pk_bf16_f32 v107, v104, v105
	global_store_dwordx2 v[108:109], v[106:107], off
	v_lshlrev_b32_e32 v0, 16, v106
	v_and_b32_e32 v106, 0xffff0000, v106
	v_sub_f32_e32 v0, v102, v0
	v_sub_f32_e32 v106, v103, v106
	v_cvt_pk_bf16_f32 v106, v0, v106
	v_lshlrev_b32_e32 v0, 16, v107
	v_and_b32_e32 v107, 0xffff0000, v107
	v_sub_f32_e32 v0, v104, v0
	v_sub_f32_e32 v107, v105, v107
	v_cvt_pk_bf16_f32 v107, v0, v107
	global_store_dwordx2 v[110:111], v[106:107], off offset:256
	v_add_f32_e32 v0, v102, v103
	v_add_f32_e32 v106, v104, v105
	v_add_f32_e32 v0, v0, v106
	v_add_f32_e32 v120, v115, v0
	v_mul_f32_e32 v0, v103, v103
	v_fmac_f32_e32 v0, v102, v102
	v_mul_f32_e32 v102, v105, v105
	v_fmac_f32_e32 v102, v104, v104
	v_add_f32_e32 v0, v0, v102
	v_lshlrev_b32_e32 v102, 16, v140
	v_and_b32_e32 v103, 0xffff0000, v140
	v_lshlrev_b32_e32 v104, 16, v142
	v_and_b32_e32 v105, 0xffff0000, v142
	v_pk_add_f32 v[112:113], v[102:103], v[104:105]
	v_lshlrev_b32_e32 v102, 16, v141
	v_and_b32_e32 v103, 0xffff0000, v141
	v_lshlrev_b32_e32 v104, 16, v143
	v_and_b32_e32 v105, 0xffff0000, v143
	v_pk_add_f32 v[118:119], v[102:103], v[104:105]
	ds_read_b128 v[102:105], v179 offset:576
	ds_read_b128 v[106:109], v179 offset:4672
	v_add_f32_e32 v117, v117, v0
	v_pk_fma_f32 v[112:113], v[112:113], v[114:115], v[116:117] op_sel_hi:[1,0,0]
	v_pk_fma_f32 v[114:115], v[118:119], v[114:115], v[116:117] op_sel_hi:[1,0,0]
	v_or_b32_e32 v0, 0x90, v138
	s_waitcnt lgkmcnt(0)
;     template <int AI, int M0, int NR>
;     __device__ __forceinline__ void batch(const f32x4 (&acc)[2][2][4][2], int row0, int col0, int wr, int wc, int fr, int fq, PG8_LAS float* red, const PG8_LAS float* gl) const {
;     ...
;         for (int mm = 0; mm < NR; ++mm) { const unsigned rr_ = (unsigned)(row0 + AI * HALF + (M0 + mm) * 16); stv[mm] = *(const f32x2*)(stp + (8u * rr_ + 2u * (unsigned)fq));
; #pragma unroll
;             for (int bj = 0; bj < 2; ++bj)
; #pragma unroll
;                 for (int n = 0; n < 2; ++n) { const unsigned cc_ = (unsigned)(col0 + bj * HALF + n * 16);
;     ...
;                 for (int n = 0; n < 2; ++n) { const unsigned hw0 = __float_as_uint(xh[mm][bj][n].x), hw1 = __float_as_uint(xh[mm][bj][n].y), lw0 = __float_as_uint(xl[mm][bj][n].x), lw1 = __float_as_uint(xl[mm][bj][n].y);
;                     f32x4 x; x[0] = __uint_as_float(hw0 << 16) + __uint_as_float(lw0 << 16); x[1] = __uint_as_float(hw0 & 0xffff0000u) + __uint_as_float(lw0 & 0xffff0000u);
;                     x[2] = __uint_as_float(hw1 << 16) + __uint_as_float(lw1 << 16); x[3] = __uint_as_float(hw1 & 0xffff0000u) + __uint_as_float(lw1 & 0xffff0000u);
;                     const f32x4 gvv = *(const PG8_LAS f32x4*)(gl + bj * HALF + n * 16), bvv = *(const PG8_LAS f32x4*)(gl + 1024 + bj * HALF + n * 16);
;                     const f32x4 xn = (x * rs - ms) * gvv + bvv; const f32x4 y = xn * alpha + acc[AI][bj][m][n] * s;
;                     const unsigned nh0 = cvt_pk_bf16(y[0], y[1]), nh1 = cvt_pk_bf16(y[2], y[3]);
;                     f32x2 w; w.x = __uint_as_float(nh0); w.y = __uint_as_float(nh1); *(f32x2*)(PB + (ro + (unsigned)(bj * HALF + n * 16))) = w;
;                     f32x2 wl; wl.x = __uint_as_float(cvt_pk_bf16(y[0] - __uint_as_float(nh0 << 16), y[1] - __uint_as_float(nh0 & 0xffff0000u))); wl.y = __uint_as_float(cvt_pk_bf16(y[2] - __uint_as_float(nh1 << 16), y[3] - __uint_as_float(nh1 & 0xffff0000u)));
;                     *(f32x2*)((bf16_t*)X + ((unsigned)row * 2048u + 1024u + (unsigned)(col0 + bj * HALF + n * 16))) = wl;
;                     sm += (y[0] + y[1]) + (y[2] + y[3]); sq += (y[0] * y[0] + y[1] * y[1]) + (y[2] * y[2] + y[3] * y[3]); }
;             sm = xsum_rows(sm); sq = xsum_rows(sq);
;             if (fq == 0) { f32x2 pr; pr.x = sm; pr.y = sq; *(PG8_LAS f32x2*)(red + ((AI * HALF + wr * 64 + m * 16 + fr) * 4 + wc) * 2) = pr; }
	v_pk_fma_f32 v[104:105], v[114:115], v[104:105], v[108:109]
	v_pk_fma_f32 v[102:103], v[112:113], v[102:103], v[106:107]
	v_pk_mul_f32 v[104:105], v[104:105], s[60:61] op_sel_hi:[1,0]
	v_pk_mul_f32 v[102:103], v[102:103], s[60:61] op_sel_hi:[1,0]
	v_pk_fma_f32 v[100:101], s[24:25], v[100:101], v[104:105]
	v_pk_fma_f32 v[98:99], s[10:11], v[98:99], v[102:103]
	v_lshl_add_u64 v[104:105], v[0:1], 1, s[26:27]
	v_cvt_pk_bf16_f32 v102, v98, v99
	v_cvt_pk_bf16_f32 v103, v100, v101
	global_store_dwordx2 v[104:105], v[102:103], off
	v_lshlrev_b32_e32 v0, 16, v102
	v_and_b32_e32 v102, 0xffff0000, v102
	v_sub_f32_e32 v0, v98, v0
	v_sub_f32_e32 v102, v99, v102
	v_cvt_pk_bf16_f32 v102, v0, v102
	v_lshlrev_b32_e32 v0, 16, v103
	v_and_b32_e32 v103, 0xffff0000, v103
	v_sub_f32_e32 v0, v100, v0
	v_sub_f32_e32 v103, v101, v103
	v_cvt_pk_bf16_f32 v103, v0, v103
	v_add_f32_e32 v0, v98, v99
	v_mul_f32_e32 v99, v99, v99
	global_store_dwordx2 v[110:111], v[102:103], off offset:288
	v_add_f32_e32 v102, v100, v101
	v_fmac_f32_e32 v99, v98, v98
	v_mul_f32_e32 v98, v101, v101
	v_add_f32_e32 v0, v0, v102
	v_fmac_f32_e32 v98, v100, v100
	v_add_f32_e32 v0, v120, v0
	v_add_f32_e32 v98, v99, v98
	v_add_f32_e32 v99, v117, v98
	v_mov_b32_e32 v98, v0
	s_nop 1
	v_permlane16_swap_b32_e32 v0, v98
	v_add_f32_e32 v98, v0, v98
	v_mov_b32_e32 v0, v99
	s_nop 1
	v_permlane16_swap_b32_e32 v99, v0
	v_add_f32_e32 v99, v99, v0
	v_mov_b32_e32 v100, v98
	v_mov_b32_e32 v101, v99
	s_nop 0
	v_permlane32_swap_b32_e32 v98, v100
	v_permlane32_swap_b32_e32 v99, v101
	s_and_saveexec_b64 s[50:51], s[2:3]
	v_pk_add_f32 v[98:99], v[98:99], v[100:101]
	ds_write_b64 v160, v[98:99] offset:512
	s_or_b64 exec, exec, s[50:51]
	v_or_b32_e32 v100, 32, v183
	v_lshl_or_b32 v0, v100, 3, v173
	v_lshl_add_u64 v[98:99], v[0:1], 2, s[28:29]
	global_load_dwordx2 v[144:145], v[98:99], off
	v_lshlrev_b32_e32 v101, 10, v100
	v_lshlrev_b32_e32 v149, 11, v100
	v_add_u32_e32 v0, v101, v182
	v_or_b32_e32 v100, 0x400, v149
	v_lshl_add_u64 v[128:129], v[0:1], 1, s[26:27]
	global_load_dwordx2 v[142:143], v[128:129], off
	v_add_u32_e32 v98, v100, v182
	v_mov_b32_e32 v99, v1
	v_lshl_add_u64 v[98:99], v[98:99], 1, s[12:13]
	global_load_dwordx2 v[146:147], v[98:99], off
	v_add_u32_e32 v98, v101, v184
	v_mov_b32_e32 v99, v1
	v_lshl_add_u64 v[98:99], v[98:99], 1, s[26:27]
	global_load_dwordx2 v[138:139], v[98:99], off
	v_add_u32_e32 v98, v100, v184
	v_mov_b32_e32 v99, v1
	v_lshl_add_u64 v[98:99], v[98:99], 1, s[12:13]
	global_load_dwordx2 v[140:141], v[98:99], off
	v_add_u32_e32 v98, v101, v181
	v_mov_b32_e32 v99, v1
	v_lshl_add_u64 v[98:99], v[98:99], 1, s[26:27]
	global_load_dwordx2 v[124:125], v[98:99], off
	v_add_u32_e32 v98, v100, v181
	v_mov_b32_e32 v99, v1
	v_lshl_add_u64 v[98:99], v[98:99], 1, s[12:13]
	global_load_dwordx2 v[126:127], v[98:99], off
	v_add_u32_e32 v98, v101, v185
	v_mov_b32_e32 v99, v1
	v_lshl_add_u64 v[98:99], v[98:99], 1, s[26:27]
	global_load_dwordx2 v[120:121], v[98:99], off
	v_add_u32_e32 v98, v100, v185
	v_mov_b32_e32 v99, v1
	v_lshl_add_u64 v[98:99], v[98:99], 1, s[12:13]
	global_load_dwordx2 v[122:123], v[98:99], off
	v_or_b32_e32 v100, 48, v183
	v_lshlrev_b32_e32 v148, 11, v100
	v_lshl_or_b32 v98, v100, 3, v173
	v_mov_b32_e32 v99, v1
	v_or_b32_e32 v119, 0x400, v148
	v_lshl_add_u64 v[98:99], v[98:99], 2, s[28:29]
	v_lshlrev_b32_e32 v118, 10, v100
	v_add_u32_e32 v100, v119, v182
	v_mov_b32_e32 v101, v1
	global_load_dwordx2 v[112:113], v[98:99], off
	v_add_u32_e32 v98, v118, v182
	v_mov_b32_e32 v99, v1
	v_lshl_add_u64 v[100:101], v[100:101], 1, s[12:13]
	v_lshl_add_u64 v[108:109], v[98:99], 1, s[26:27]
	global_load_dwordx2 v[116:117], v[100:101], off
	v_add_u32_e32 v100, v118, v184
	v_mov_b32_e32 v101, v1
	v_lshl_add_u64 v[100:101], v[100:101], 1, s[26:27]
	global_load_dwordx2 v[114:115], v[108:109], off
	global_load_dwordx2 v[106:107], v[100:101], off
	v_add_u32_e32 v100, v119, v184
	v_mov_b32_e32 v101, v1
	v_lshl_add_u64 v[100:101], v[100:101], 1, s[12:13]
	global_load_dwordx2 v[110:111], v[100:101], off
	v_add_u32_e32 v100, v118, v181
	v_mov_b32_e32 v101, v1
	v_lshl_add_u64 v[100:101], v[100:101], 1, s[26:27]
	global_load_dwordx2 v[102:103], v[100:101], off
	v_add_u32_e32 v100, v119, v181
	v_mov_b32_e32 v101, v1
	v_lshl_add_u64 v[100:101], v[100:101], 1, s[12:13]
	global_load_dwordx2 v[104:105], v[100:101], off
	v_add_u32_e32 v100, v118, v185
	v_mov_b32_e32 v101, v1
	v_add_u32_e32 v118, v119, v185
	v_mov_b32_e32 v119, v1
	v_lshl_add_u64 v[100:101], v[100:101], 1, s[26:27]
	v_lshl_add_u64 v[118:119], v[118:119], 1, s[12:13]
	global_load_dwordx2 v[100:101], v[100:101], off
	v_add_u32_e32 v158, v149, v180
	global_load_dwordx2 v[118:119], v[118:119], off
	v_mov_b32_e32 v159, v1
	s_waitcnt vmcnt(0) lgkmcnt(0)
	v_mov_b32_e32 v99, v144
	s_nop 1
	v_permlane16_swap_b32_e32 v144, v99
	v_add_f32_e32 v151, v144, v99
	v_mov_b32_e32 v99, v145
	s_nop 1
	v_permlane16_swap_b32_e32 v145, v99
	v_add_f32_e32 v150, v145, v99
	v_mov_b32_e32 v153, v151
	v_mov_b32_e32 v152, v150
	s_nop 0
	v_permlane32_swap_b32_e32 v151, v153
	v_permlane32_swap_b32_e32 v150, v152
	v_pk_add_f32 v[144:145], v[150:151], v[152:153]
	v_lshlrev_b32_e32 v150, 16, v142
	v_pk_mul_f32 v[144:145], v[144:145], s[68:69] op_sel_hi:[1,0]
	v_and_b32_e32 v151, 0xffff0000, v142
	v_fma_f32 v99, -v145, v145, v144
	v_add_f32_e32 v99, 0x3727c5ac, v99
	v_rsq_f32_e32 v144, v99
	v_lshlrev_b32_e32 v152, 16, v146
	v_and_b32_e32 v153, 0xffff0000, v146
	v_pk_add_f32 v[162:163], v[150:151], v[152:153]
	ds_read_b128 v[150:153], v179
	ds_read_b128 v[154:157], v179 offset:4096
	v_lshlrev_b32_e32 v142, 16, v143
	v_and_b32_e32 v143, 0xffff0000, v143
	v_lshlrev_b32_e32 v146, 16, v147
	v_and_b32_e32 v147, 0xffff0000, v147
	v_pk_add_f32 v[146:147], v[142:143], v[146:147]
	v_mul_f32_e64 v142, v145, -v144
	v_pk_fma_f32 v[162:163], v[162:163], v[144:145], v[142:143] op_sel_hi:[1,0,0]
	v_pk_fma_f32 v[146:147], v[146:147], v[144:145], v[142:143] op_sel_hi:[1,0,0]
	s_waitcnt lgkmcnt(0)
; #define PG8_LAS __attribute__((address_space(3)))
; __device__ __forceinline__ unsigned cvt_pk_bf16(float lo, float hi) { unsigned r; asm volatile("v_cvt_pk_bf16_f32 %0, %1, %2" : "=v"(r) : "v"(lo), "v"(hi)); return r; }
;     template <int AI, int M0, int NR>
;     __device__ __forceinline__ void batch(const f32x4 (&acc)[2][2][4][2], int row0, int col0, int wr, int wc, int fr, int fq, PG8_LAS float* red, const PG8_LAS float* gl) const {
;     ...
;                 for (int n = 0; n < 2; ++n) { const unsigned hw0 = __float_as_uint(xh[mm][bj][n].x), hw1 = __float_as_uint(xh[mm][bj][n].y), lw0 = __float_as_uint(xl[mm][bj][n].x), lw1 = __float_as_uint(xl[mm][bj][n].y);
;                     f32x4 x; x[0] = __uint_as_float(hw0 << 16) + __uint_as_float(lw0 << 16); x[1] = __uint_as_float(hw0 & 0xffff0000u) + __uint_as_float(lw0 & 0xffff0000u);
;                     x[2] = __uint_as_float(hw1 << 16) + __uint_as_float(lw1 << 16); x[3] = __uint_as_float(hw1 & 0xffff0000u) + __uint_as_float(lw1 & 0xffff0000u);
;                     const f32x4 gvv = *(const PG8_LAS f32x4*)(gl + bj * HALF + n * 16), bvv = *(const PG8_LAS f32x4*)(gl + 1024 + bj * HALF + n * 16);
;                     const f32x4 xn = (x * rs - ms) * gvv + bvv; const f32x4 y = xn * alpha + acc[AI][bj][m][n] * s;
;                     const unsigned nh0 = cvt_pk_bf16(y[0], y[1]), nh1 = cvt_pk_bf16(y[2], y[3]);
;                     f32x2 w; w.x = __uint_as_float(nh0); w.y = __uint_as_float(nh1); *(f32x2*)(PB + (ro + (unsigned)(bj * HALF + n * 16))) = w;
;                     f32x2 wl; wl.x = __uint_as_float(cvt_pk_bf16(y[0] - __uint_as_float(nh0 << 16), y[1] - __uint_as_float(nh0 & 0xffff0000u))); wl.y = __uint_as_float(cvt_pk_bf16(y[2] - __uint_as_float(nh1 << 16), y[3] - __uint_as_float(nh1 & 0xffff0000u)));
;                     *(f32x2*)((bf16_t*)X + ((unsigned)row * 2048u + 1024u + (unsigned)(col0 + bj * HALF + n * 16))) = wl;
;                     sm += (y[0] + y[1]) + (y[2] + y[3]); sq += (y[0] * y[0] + y[1] * y[1]) + (y[2] * y[2] + y[3] * y[3]); }
	v_pk_fma_f32 v[150:151], v[150:151], v[162:163], v[154:155]
	v_pk_fma_f32 v[146:147], v[152:153], v[146:147], v[156:157]
	v_pk_mul_f32 v[150:151], v[150:151], s[60:61] op_sel_hi:[1,0]
	v_pk_mul_f32 v[146:147], v[146:147], s[60:61] op_sel_hi:[1,0]
	s_nop 0
	v_pk_fma_f32 v[96:97], s[24:25], v[96:97], v[146:147]
	v_pk_fma_f32 v[146:147], s[10:11], v[94:95], v[150:151]
	s_nop 0
	v_cvt_pk_bf16_f32 v94, v146, v147
	v_cvt_pk_bf16_f32 v95, v96, v97
	global_store_dwordx2 v[128:129], v[94:95], off
	v_lshlrev_b32_e32 v99, 16, v94
	v_and_b32_e32 v94, 0xffff0000, v94
	v_sub_f32_e32 v94, v147, v94
	v_sub_f32_e32 v99, v146, v99
	v_cvt_pk_bf16_f32 v128, v99, v94
	v_lshlrev_b32_e32 v94, 16, v95
	v_and_b32_e32 v95, 0xffff0000, v95
	v_sub_f32_e32 v94, v96, v94
	v_sub_f32_e32 v95, v97, v95
	v_cvt_pk_bf16_f32 v129, v94, v95
	v_lshl_add_u64 v[94:95], v[158:159], 1, s[12:13]
	global_store_dwordx2 v[94:95], v[128:129], off
	v_add_f32_e32 v99, v146, v147
	v_add_f32_e32 v128, v96, v97
	v_add_f32_e32 v99, v99, v128
	v_mul_f32_e32 v128, v147, v147
	v_mul_f32_e32 v97, v97, v97
	v_fmac_f32_e32 v128, v146, v146
	v_fmac_f32_e32 v97, v96, v96
	v_add_f32_e32 v143, v128, v97
	v_lshlrev_b32_e32 v96, 16, v138
	v_and_b32_e32 v97, 0xffff0000, v138
	v_lshlrev_b32_e32 v128, 16, v140
	v_and_b32_e32 v129, 0xffff0000, v140
	v_pk_add_f32 v[96:97], v[96:97], v[128:129]
	v_lshlrev_b32_e32 v128, 16, v139
	v_and_b32_e32 v129, 0xffff0000, v139
	v_lshlrev_b32_e32 v138, 16, v141
	v_and_b32_e32 v139, 0xffff0000, v141
	v_pk_add_f32 v[128:129], v[128:129], v[138:139]
	ds_read_b128 v[138:141], v179 offset:64
	ds_read_b128 v[150:153], v179 offset:4160
	v_pk_fma_f32 v[128:129], v[128:129], v[144:145], v[142:143] op_sel_hi:[1,0,0]
	v_pk_fma_f32 v[96:97], v[96:97], v[144:145], v[142:143] op_sel_hi:[1,0,0]
	v_add_f32_e32 v99, 0, v99
	s_waitcnt lgkmcnt(0)
	v_pk_fma_f32 v[128:129], v[140:141], v[128:129], v[152:153]
	v_pk_fma_f32 v[96:97], v[138:139], v[96:97], v[150:151]
	v_pk_mul_f32 v[128:129], v[128:129], s[60:61] op_sel_hi:[1,0]
	v_pk_mul_f32 v[96:97], v[96:97], s[60:61] op_sel_hi:[1,0]
	v_pk_fma_f32 v[92:93], s[24:25], v[92:93], v[128:129]
	v_or_b32_e32 v128, 16, v0
	v_mov_b32_e32 v129, v1
	v_pk_fma_f32 v[90:91], s[10:11], v[90:91], v[96:97]
	v_lshl_add_u64 v[128:129], v[128:129], 1, s[26:27]
	v_cvt_pk_bf16_f32 v96, v90, v91
	v_cvt_pk_bf16_f32 v97, v92, v93
	global_store_dwordx2 v[128:129], v[96:97], off
	v_lshlrev_b32_e32 v128, 16, v96
	v_and_b32_e32 v96, 0xffff0000, v96
	v_sub_f32_e32 v128, v90, v128
	v_sub_f32_e32 v96, v91, v96
	v_cvt_pk_bf16_f32 v96, v128, v96
	v_lshlrev_b32_e32 v128, 16, v97
	v_and_b32_e32 v97, 0xffff0000, v97
	v_sub_f32_e32 v97, v93, v97
	v_sub_f32_e32 v128, v92, v128
	v_cvt_pk_bf16_f32 v97, v128, v97
	global_store_dwordx2 v[94:95], v[96:97], off offset:32
	v_add_f32_e32 v96, v90, v91
	v_mul_f32_e32 v91, v91, v91
	v_fmac_f32_e32 v91, v90, v90
	v_mul_f32_e32 v90, v93, v93
	v_fmac_f32_e32 v90, v92, v92
	v_add_f32_e32 v90, v91, v90
	v_add_f32_e32 v97, v92, v93
	v_add_f32_e32 v140, v143, v90
	v_lshlrev_b32_e32 v90, 16, v124
	v_and_b32_e32 v91, 0xffff0000, v124
	v_lshlrev_b32_e32 v92, 16, v126
	v_and_b32_e32 v93, 0xffff0000, v126
	v_pk_add_f32 v[128:129], v[90:91], v[92:93]
	v_lshlrev_b32_e32 v90, 16, v125
	v_and_b32_e32 v91, 0xffff0000, v125
	v_lshlrev_b32_e32 v92, 16, v127
	v_and_b32_e32 v93, 0xffff0000, v127
	v_pk_add_f32 v[138:139], v[90:91], v[92:93]
	ds_read_b128 v[90:93], v179 offset:512
	ds_read_b128 v[124:127], v179 offset:4608
	v_pk_fma_f32 v[128:129], v[128:129], v[144:145], v[142:143] op_sel_hi:[1,0,0]
	v_pk_fma_f32 v[138:139], v[138:139], v[144:145], v[142:143] op_sel_hi:[1,0,0]
	v_add_f32_e32 v96, v96, v97
	v_add_f32_e32 v99, v96, v99
	s_waitcnt lgkmcnt(0)
	v_pk_fma_f32 v[92:93], v[138:139], v[92:93], v[126:127]
	v_pk_fma_f32 v[90:91], v[128:129], v[90:91], v[124:125]
	v_or_b32_e32 v96, 0x80, v0
	v_pk_mul_f32 v[90:91], v[90:91], s[60:61] op_sel_hi:[1,0]
	v_pk_mul_f32 v[92:93], v[92:93], s[60:61] op_sel_hi:[1,0]
	v_mov_b32_e32 v97, v1
	v_pk_fma_f32 v[88:89], s[24:25], v[88:89], v[92:93]
	v_pk_fma_f32 v[86:87], s[10:11], v[86:87], v[90:91]
	v_lshl_add_u64 v[92:93], v[96:97], 1, s[26:27]
	v_cvt_pk_bf16_f32 v90, v86, v87
	v_cvt_pk_bf16_f32 v91, v88, v89
	global_store_dwordx2 v[92:93], v[90:91], off
	v_lshlrev_b32_e32 v92, 16, v90
	v_and_b32_e32 v90, 0xffff0000, v90
	v_sub_f32_e32 v92, v86, v92
	v_sub_f32_e32 v90, v87, v90
	v_cvt_pk_bf16_f32 v90, v92, v90
	v_lshlrev_b32_e32 v92, 16, v91
	v_and_b32_e32 v91, 0xffff0000, v91
	v_sub_f32_e32 v91, v89, v91
	v_sub_f32_e32 v92, v88, v92
	v_cvt_pk_bf16_f32 v91, v92, v91
	global_store_dwordx2 v[94:95], v[90:91], off offset:256
	v_add_f32_e32 v90, v86, v87
	v_mul_f32_e32 v87, v87, v87
	v_fmac_f32_e32 v87, v86, v86
	v_mul_f32_e32 v86, v89, v89
	v_fmac_f32_e32 v86, v88, v88
	v_add_f32_e32 v86, v87, v86
	v_add_f32_e32 v91, v88, v89
	v_add_f32_e32 v124, v140, v86
	v_lshlrev_b32_e32 v86, 16, v120
	v_and_b32_e32 v87, 0xffff0000, v120
	v_lshlrev_b32_e32 v88, 16, v122
	v_and_b32_e32 v89, 0xffff0000, v122
	v_add_f32_e32 v90, v90, v91
	v_pk_add_f32 v[96:97], v[86:87], v[88:89]
	v_lshlrev_b32_e32 v86, 16, v121
	v_and_b32_e32 v87, 0xffff0000, v121
	v_lshlrev_b32_e32 v88, 16, v123
	v_and_b32_e32 v89, 0xffff0000, v123
	v_add_f32_e32 v99, v99, v90
	v_pk_add_f32 v[120:121], v[86:87], v[88:89]
	ds_read_b128 v[86:89], v179 offset:576
	ds_read_b128 v[90:93], v179 offset:4672
	v_pk_fma_f32 v[96:97], v[96:97], v[144:145], v[142:143] op_sel_hi:[1,0,0]
	v_pk_fma_f32 v[120:121], v[120:121], v[144:145], v[142:143] op_sel_hi:[1,0,0]
	v_or_b32_e32 v0, 0x90, v0
	s_waitcnt lgkmcnt(0)
;     template <int AI, int M0, int NR>
;     __device__ __forceinline__ void batch(const f32x4 (&acc)[2][2][4][2], int row0, int col0, int wr, int wc, int fr, int fq, PG8_LAS float* red, const PG8_LAS float* gl) const {
;     ...
;         for (int mm = 0; mm < NR; ++mm) { const int m = M0 + mm; const int row = row0 + AI * HALF + m * 16;
;             float rs, ms; { f32x2 v = stv[mm]; v.x = xsum_rows(v.x); v.y = xsum_rows(v.y);
;               const float mean = v.x * (1.0f / 1024.0f); const float var = v.y * (1.0f / 1024.0f) - mean * mean; rs = __builtin_amdgcn_rsqf(var + 1e-5f); ms = rs * mean; }
;             const unsigned ro = (unsigned)row * 1024u + (unsigned)col0;
;             float sm = 0.f, sq = 0.f;
; #pragma unroll
;             for (int bj = 0; bj < 2; ++bj)
; #pragma unroll
;                 for (int n = 0; n < 2; ++n) { const unsigned hw0 = __float_as_uint(xh[mm][bj][n].x), hw1 = __float_as_uint(xh[mm][bj][n].y), lw0 = __float_as_uint(xl[mm][bj][n].x), lw1 = __float_as_uint(xl[mm][bj][n].y);
;                     f32x4 x; x[0] = __uint_as_float(hw0 << 16) + __uint_as_float(lw0 << 16); x[1] = __uint_as_float(hw0 & 0xffff0000u) + __uint_as_float(lw0 & 0xffff0000u);
;                     x[2] = __uint_as_float(hw1 << 16) + __uint_as_float(lw1 << 16); x[3] = __uint_as_float(hw1 & 0xffff0000u) + __uint_as_float(lw1 & 0xffff0000u);
;                     const f32x4 gvv = *(const PG8_LAS f32x4*)(gl + bj * HALF + n * 16), bvv = *(const PG8_LAS f32x4*)(gl + 1024 + bj * HALF + n * 16);
;                     const f32x4 xn = (x * rs - ms) * gvv + bvv; const f32x4 y = xn * alpha + acc[AI][bj][m][n] * s;
;                     const unsigned nh0 = cvt_pk_bf16(y[0], y[1]), nh1 = cvt_pk_bf16(y[2], y[3]);
;                     f32x2 w; w.x = __uint_as_float(nh0); w.y = __uint_as_float(nh1); *(f32x2*)(PB + (ro + (unsigned)(bj * HALF + n * 16))) = w;
;                     f32x2 wl; wl.x = __uint_as_float(cvt_pk_bf16(y[0] - __uint_as_float(nh0 << 16), y[1] - __uint_as_float(nh0 & 0xffff0000u))); wl.y = __uint_as_float(cvt_pk_bf16(y[2] - __uint_as_float(nh1 << 16), y[3] - __uint_as_float(nh1 & 0xffff0000u)));
;                     *(f32x2*)((bf16_t*)X + ((unsigned)row * 2048u + 1024u + (unsigned)(col0 + bj * HALF + n * 16))) = wl;
;                     sm += (y[0] + y[1]) + (y[2] + y[3]); sq += (y[0] * y[0] + y[1] * y[1]) + (y[2] * y[2] + y[3] * y[3]); }
	v_pk_fma_f32 v[88:89], v[120:121], v[88:89], v[92:93]
	v_pk_fma_f32 v[86:87], v[96:97], v[86:87], v[90:91]
	v_pk_mul_f32 v[88:89], v[88:89], s[60:61] op_sel_hi:[1,0]
	v_pk_mul_f32 v[86:87], v[86:87], s[60:61] op_sel_hi:[1,0]
	v_pk_fma_f32 v[84:85], s[24:25], v[84:85], v[88:89]
	v_pk_fma_f32 v[82:83], s[10:11], v[82:83], v[86:87]
	v_lshl_add_u64 v[88:89], v[0:1], 1, s[26:27]
	v_cvt_pk_bf16_f32 v86, v82, v83
	v_cvt_pk_bf16_f32 v87, v84, v85
	global_store_dwordx2 v[88:89], v[86:87], off
	v_lshlrev_b32_e32 v0, 16, v86
	v_and_b32_e32 v86, 0xffff0000, v86
	v_sub_f32_e32 v0, v82, v0
	v_sub_f32_e32 v86, v83, v86
	v_cvt_pk_bf16_f32 v86, v0, v86
	v_lshlrev_b32_e32 v0, 16, v87
	v_and_b32_e32 v87, 0xffff0000, v87
	v_sub_f32_e32 v0, v84, v0
	v_sub_f32_e32 v87, v85, v87
	v_cvt_pk_bf16_f32 v87, v0, v87
	v_add_f32_e32 v0, v82, v83
	v_mul_f32_e32 v83, v83, v83
	global_store_dwordx2 v[94:95], v[86:87], off offset:288
	v_add_f32_e32 v86, v84, v85
	v_fmac_f32_e32 v83, v82, v82
	v_mul_f32_e32 v82, v85, v85
	v_add_f32_e32 v0, v0, v86
	v_fmac_f32_e32 v82, v84, v84
	v_add_f32_e32 v0, v99, v0
	v_add_f32_e32 v82, v83, v82
	v_add_f32_e32 v83, v124, v82
	v_mov_b32_e32 v82, v0
	s_nop 1
	v_permlane16_swap_b32_e32 v0, v82
	v_add_f32_e32 v82, v0, v82
	v_mov_b32_e32 v0, v83
	s_nop 1
	v_permlane16_swap_b32_e32 v83, v0
	v_add_f32_e32 v83, v83, v0
	v_mov_b32_e32 v84, v82
	v_mov_b32_e32 v85, v83
	s_nop 0
	v_permlane32_swap_b32_e32 v82, v84
	v_permlane32_swap_b32_e32 v83, v85
	s_and_saveexec_b64 s[50:51], s[2:3]
	v_pk_add_f32 v[82:83], v[82:83], v[84:85]
	ds_write_b64 v160, v[82:83] offset:1024
	s_or_b64 exec, exec, s[50:51]
	v_mov_b32_e32 v0, v112
	s_nop 1
	v_permlane16_swap_b32_e32 v112, v0
	v_add_f32_e32 v83, v112, v0
	v_mov_b32_e32 v0, v113
	s_nop 1
	v_permlane16_swap_b32_e32 v113, v0
	v_add_f32_e32 v82, v113, v0
	v_mov_b32_e32 v85, v83
	v_mov_b32_e32 v84, v82
	s_nop 0
	v_permlane32_swap_b32_e32 v83, v85
	v_permlane32_swap_b32_e32 v82, v84
	v_pk_add_f32 v[82:83], v[82:83], v[84:85]
	v_lshlrev_b32_e32 v84, 16, v114
	v_pk_mul_f32 v[82:83], v[82:83], s[68:69] op_sel_hi:[1,0]
	v_and_b32_e32 v85, 0xffff0000, v114
	v_fma_f32 v0, -v83, v83, v82
	v_add_f32_e32 v0, 0x3727c5ac, v0
	v_lshlrev_b32_e32 v86, 16, v116
	v_and_b32_e32 v87, 0xffff0000, v116
	v_rsq_f32_e32 v82, v0
	v_pk_add_f32 v[94:95], v[84:85], v[86:87]
	v_lshlrev_b32_e32 v84, 16, v115
	v_and_b32_e32 v85, 0xffff0000, v115
	v_lshlrev_b32_e32 v86, 16, v117
	v_and_b32_e32 v87, 0xffff0000, v117
	v_pk_add_f32 v[96:97], v[84:85], v[86:87]
	ds_read_b128 v[86:89], v179
	ds_read_b128 v[90:93], v179 offset:4096
	v_mul_f32_e64 v84, v83, -v82
	v_pk_fma_f32 v[94:95], v[94:95], v[82:83], v[84:85] op_sel_hi:[1,0,0]
	v_pk_fma_f32 v[96:97], v[96:97], v[82:83], v[84:85] op_sel_hi:[1,0,0]
	v_add_u32_e32 v0, v148, v180
	s_waitcnt lgkmcnt(0)
	v_pk_fma_f32 v[86:87], v[86:87], v[94:95], v[90:91]
	v_pk_fma_f32 v[88:89], v[88:89], v[96:97], v[92:93]
	v_pk_mul_f32 v[86:87], v[86:87], s[60:61] op_sel_hi:[1,0]
	v_pk_mul_f32 v[88:89], v[88:89], s[60:61] op_sel_hi:[1,0]
	v_pk_fma_f32 v[86:87], s[10:11], v[78:79], v[86:87]
	v_pk_fma_f32 v[80:81], s[24:25], v[80:81], v[88:89]
	v_cvt_pk_bf16_f32 v78, v86, v87
	s_nop 0
	v_cvt_pk_bf16_f32 v79, v80, v81
	global_store_dwordx2 v[108:109], v[78:79], off
	v_lshlrev_b32_e32 v83, 16, v78
	v_and_b32_e32 v78, 0xffff0000, v78
	v_sub_f32_e32 v78, v87, v78
	v_sub_f32_e32 v83, v86, v83
	v_cvt_pk_bf16_f32 v88, v83, v78
	v_lshlrev_b32_e32 v78, 16, v79
	v_and_b32_e32 v79, 0xffff0000, v79
	v_sub_f32_e32 v78, v80, v78
	v_sub_f32_e32 v79, v81, v79
	v_cvt_pk_bf16_f32 v89, v78, v79
	v_lshl_add_u64 v[78:79], v[0:1], 1, s[12:13]
	v_add_f32_e32 v0, v86, v87
	v_add_f32_e32 v83, v80, v81
	v_add_f32_e32 v0, v0, v83
	v_add_f32_e32 v83, 0, v0
	v_mul_f32_e32 v0, v87, v87
	v_mul_f32_e32 v81, v81, v81
	v_fmac_f32_e32 v0, v86, v86
	v_fmac_f32_e32 v81, v80, v80
	v_add_f32_e32 v85, v0, v81
	v_lshlrev_b32_e32 v80, 16, v106
	v_and_b32_e32 v81, 0xffff0000, v106
	v_lshlrev_b32_e32 v86, 16, v110
	v_and_b32_e32 v87, 0xffff0000, v110
	global_store_dwordx2 v[78:79], v[88:89], off
	v_pk_add_f32 v[80:81], v[80:81], v[86:87]
	v_lshlrev_b32_e32 v86, 16, v107
	v_and_b32_e32 v87, 0xffff0000, v107
	v_lshlrev_b32_e32 v88, 16, v111
	v_and_b32_e32 v89, 0xffff0000, v111
	v_pk_add_f32 v[94:95], v[86:87], v[88:89]
	ds_read_b128 v[86:89], v179 offset:64
	ds_read_b128 v[90:93], v179 offset:4160
	v_pk_fma_f32 v[80:81], v[80:81], v[82:83], v[84:85] op_sel_hi:[1,0,0]
	v_pk_fma_f32 v[94:95], v[94:95], v[82:83], v[84:85] op_sel_hi:[1,0,0]
	v_or_b32_e32 v0, 16, v98
	s_waitcnt lgkmcnt(0)
	v_pk_fma_f32 v[88:89], v[88:89], v[94:95], v[92:93]
	v_pk_fma_f32 v[80:81], v[86:87], v[80:81], v[90:91]
	v_pk_mul_f32 v[86:87], v[88:89], s[60:61] op_sel_hi:[1,0]
	v_pk_mul_f32 v[80:81], v[80:81], s[60:61] op_sel_hi:[1,0]
	v_pk_fma_f32 v[76:77], s[24:25], v[76:77], v[86:87]
	v_pk_fma_f32 v[74:75], s[10:11], v[74:75], v[80:81]
	v_lshl_add_u64 v[86:87], v[0:1], 1, s[26:27]
	v_cvt_pk_bf16_f32 v80, v74, v75
	v_cvt_pk_bf16_f32 v81, v76, v77
	global_store_dwordx2 v[86:87], v[80:81], off
	v_lshlrev_b32_e32 v0, 16, v80
	v_and_b32_e32 v80, 0xffff0000, v80
	v_sub_f32_e32 v0, v74, v0
	v_sub_f32_e32 v80, v75, v80
	v_cvt_pk_bf16_f32 v80, v0, v80
	v_lshlrev_b32_e32 v0, 16, v81
	v_and_b32_e32 v81, 0xffff0000, v81
	v_sub_f32_e32 v0, v76, v0
	v_sub_f32_e32 v81, v77, v81
	v_cvt_pk_bf16_f32 v81, v0, v81
	global_store_dwordx2 v[78:79], v[80:81], off offset:32
	v_add_f32_e32 v0, v74, v75
	v_add_f32_e32 v80, v76, v77
	v_add_f32_e32 v0, v0, v80
	v_add_f32_e32 v83, v0, v83
	v_mul_f32_e32 v0, v75, v75
	v_fmac_f32_e32 v0, v74, v74
	v_mul_f32_e32 v74, v77, v77
	v_fmac_f32_e32 v74, v76, v76
	v_add_f32_e32 v0, v0, v74
	v_lshlrev_b32_e32 v74, 16, v102
	v_and_b32_e32 v75, 0xffff0000, v102
	v_lshlrev_b32_e32 v76, 16, v104
	v_and_b32_e32 v77, 0xffff0000, v104
	v_pk_add_f32 v[80:81], v[74:75], v[76:77]
	v_lshlrev_b32_e32 v74, 16, v103
	v_and_b32_e32 v75, 0xffff0000, v103
	v_lshlrev_b32_e32 v76, 16, v105
	v_and_b32_e32 v77, 0xffff0000, v105
	v_pk_add_f32 v[90:91], v[74:75], v[76:77]
	ds_read_b128 v[74:77], v179 offset:512
	ds_read_b128 v[86:89], v179 offset:4608
	v_add_f32_e32 v85, v85, v0
	v_pk_fma_f32 v[80:81], v[80:81], v[82:83], v[84:85] op_sel_hi:[1,0,0]
	v_pk_fma_f32 v[90:91], v[90:91], v[82:83], v[84:85] op_sel_hi:[1,0,0]
	v_or_b32_e32 v0, 0x80, v98
	s_waitcnt lgkmcnt(0)
;     template <int AI, int M0, int NR>
;     __device__ __forceinline__ void batch(const f32x4 (&acc)[2][2][4][2], int row0, int col0, int wr, int wc, int fr, int fq, PG8_LAS float* red, const PG8_LAS float* gl) const {
;     ...
;         for (int mm = 0; mm < NR; ++mm) { const unsigned rr_ = (unsigned)(row0 + AI * HALF + (M0 + mm) * 16); stv[mm] = *(const f32x2*)(stp + (8u * rr_ + 2u * (unsigned)fq));
; #pragma unroll
;             for (int bj = 0; bj < 2; ++bj)
; #pragma unroll
;                 for (int n = 0; n < 2; ++n) { const unsigned cc_ = (unsigned)(col0 + bj * HALF + n * 16);
;     ...
;                 for (int n = 0; n < 2; ++n) { const unsigned hw0 = __float_as_uint(xh[mm][bj][n].x), hw1 = __float_as_uint(xh[mm][bj][n].y), lw0 = __float_as_uint(xl[mm][bj][n].x), lw1 = __float_as_uint(xl[mm][bj][n].y);
;                     f32x4 x; x[0] = __uint_as_float(hw0 << 16) + __uint_as_float(lw0 << 16); x[1] = __uint_as_float(hw0 & 0xffff0000u) + __uint_as_float(lw0 & 0xffff0000u);
;                     x[2] = __uint_as_float(hw1 << 16) + __uint_as_float(lw1 << 16); x[3] = __uint_as_float(hw1 & 0xffff0000u) + __uint_as_float(lw1 & 0xffff0000u);
;                     const f32x4 gvv = *(const PG8_LAS f32x4*)(gl + bj * HALF + n * 16), bvv = *(const PG8_LAS f32x4*)(gl + 1024 + bj * HALF + n * 16);
;                     const f32x4 xn = (x * rs - ms) * gvv + bvv; const f32x4 y = xn * alpha + acc[AI][bj][m][n] * s;
;                     const unsigned nh0 = cvt_pk_bf16(y[0], y[1]), nh1 = cvt_pk_bf16(y[2], y[3]);
;                     f32x2 w; w.x = __uint_as_float(nh0); w.y = __uint_as_float(nh1); *(f32x2*)(PB + (ro + (unsigned)(bj * HALF + n * 16))) = w;
;                     f32x2 wl; wl.x = __uint_as_float(cvt_pk_bf16(y[0] - __uint_as_float(nh0 << 16), y[1] - __uint_as_float(nh0 & 0xffff0000u))); wl.y = __uint_as_float(cvt_pk_bf16(y[2] - __uint_as_float(nh1 << 16), y[3] - __uint_as_float(nh1 & 0xffff0000u)));
;                     *(f32x2*)((bf16_t*)X + ((unsigned)row * 2048u + 1024u + (unsigned)(col0 + bj * HALF + n * 16))) = wl;
;                     sm += (y[0] + y[1]) + (y[2] + y[3]); sq += (y[0] * y[0] + y[1] * y[1]) + (y[2] * y[2] + y[3] * y[3]); }
;             sm = xsum_rows(sm); sq = xsum_rows(sq);
;             if (fq == 0) { f32x2 pr; pr.x = sm; pr.y = sq; *(PG8_LAS f32x2*)(red + ((AI * HALF + wr * 64 + m * 16 + fr) * 4 + wc) * 2) = pr; }
	v_pk_fma_f32 v[76:77], v[90:91], v[76:77], v[88:89]
	v_pk_fma_f32 v[74:75], v[80:81], v[74:75], v[86:87]
	v_pk_mul_f32 v[76:77], v[76:77], s[60:61] op_sel_hi:[1,0]
	v_pk_mul_f32 v[74:75], v[74:75], s[60:61] op_sel_hi:[1,0]
	v_pk_fma_f32 v[72:73], s[24:25], v[72:73], v[76:77]
	v_pk_fma_f32 v[70:71], s[10:11], v[70:71], v[74:75]
	v_lshl_add_u64 v[76:77], v[0:1], 1, s[26:27]
	v_cvt_pk_bf16_f32 v74, v70, v71
	v_cvt_pk_bf16_f32 v75, v72, v73
	global_store_dwordx2 v[76:77], v[74:75], off
	v_lshlrev_b32_e32 v0, 16, v74
	v_and_b32_e32 v74, 0xffff0000, v74
	v_sub_f32_e32 v0, v70, v0
	v_sub_f32_e32 v74, v71, v74
	v_cvt_pk_bf16_f32 v74, v0, v74
	v_lshlrev_b32_e32 v0, 16, v75
	v_and_b32_e32 v75, 0xffff0000, v75
	v_sub_f32_e32 v0, v72, v0
	v_sub_f32_e32 v75, v73, v75
	v_cvt_pk_bf16_f32 v75, v0, v75
	global_store_dwordx2 v[78:79], v[74:75], off offset:256
	v_add_f32_e32 v0, v70, v71
	v_add_f32_e32 v74, v72, v73
	v_add_f32_e32 v0, v0, v74
	v_add_f32_e32 v88, v83, v0
	v_mul_f32_e32 v0, v71, v71
	v_fmac_f32_e32 v0, v70, v70
	v_mul_f32_e32 v70, v73, v73
	v_fmac_f32_e32 v70, v72, v72
	v_add_f32_e32 v0, v0, v70
	v_lshlrev_b32_e32 v70, 16, v100
	v_and_b32_e32 v71, 0xffff0000, v100
	v_lshlrev_b32_e32 v72, 16, v118
	v_and_b32_e32 v73, 0xffff0000, v118
	v_pk_add_f32 v[80:81], v[70:71], v[72:73]
	v_lshlrev_b32_e32 v70, 16, v101
	v_and_b32_e32 v71, 0xffff0000, v101
	v_lshlrev_b32_e32 v72, 16, v119
	v_and_b32_e32 v73, 0xffff0000, v119
	v_pk_add_f32 v[86:87], v[70:71], v[72:73]
	ds_read_b128 v[70:73], v179 offset:576
	ds_read_b128 v[74:77], v179 offset:4672
	v_add_f32_e32 v85, v85, v0
	v_pk_fma_f32 v[80:81], v[80:81], v[82:83], v[84:85] op_sel_hi:[1,0,0]
	v_pk_fma_f32 v[82:83], v[86:87], v[82:83], v[84:85] op_sel_hi:[1,0,0]
	v_or_b32_e32 v0, 0x90, v98
	s_waitcnt lgkmcnt(0)
	v_pk_fma_f32 v[72:73], v[82:83], v[72:73], v[76:77]
	v_pk_fma_f32 v[70:71], v[80:81], v[70:71], v[74:75]
	v_pk_mul_f32 v[72:73], v[72:73], s[60:61] op_sel_hi:[1,0]
	v_pk_mul_f32 v[70:71], v[70:71], s[60:61] op_sel_hi:[1,0]
	v_pk_fma_f32 v[68:69], s[24:25], v[68:69], v[72:73]
	v_pk_fma_f32 v[66:67], s[10:11], v[66:67], v[70:71]
	v_lshl_add_u64 v[72:73], v[0:1], 1, s[26:27]
	v_cvt_pk_bf16_f32 v70, v66, v67
	v_cvt_pk_bf16_f32 v71, v68, v69
	global_store_dwordx2 v[72:73], v[70:71], off
	v_lshlrev_b32_e32 v0, 16, v70
	v_and_b32_e32 v70, 0xffff0000, v70
	v_sub_f32_e32 v0, v66, v0
	v_sub_f32_e32 v70, v67, v70
	v_cvt_pk_bf16_f32 v70, v0, v70
	v_lshlrev_b32_e32 v0, 16, v71
	v_and_b32_e32 v71, 0xffff0000, v71
	v_sub_f32_e32 v0, v68, v0
	v_sub_f32_e32 v71, v69, v71
	v_cvt_pk_bf16_f32 v71, v0, v71
	v_add_f32_e32 v0, v66, v67
	v_mul_f32_e32 v67, v67, v67
	global_store_dwordx2 v[78:79], v[70:71], off offset:288
	v_add_f32_e32 v70, v68, v69
	v_fmac_f32_e32 v67, v66, v66
	v_mul_f32_e32 v66, v69, v69
	v_add_f32_e32 v0, v0, v70
	v_fmac_f32_e32 v66, v68, v68
	v_add_f32_e32 v0, v88, v0
	v_add_f32_e32 v66, v67, v66
	v_add_f32_e32 v67, v85, v66
	v_mov_b32_e32 v66, v0
	s_nop 1
	v_permlane16_swap_b32_e32 v0, v66
	v_add_f32_e32 v66, v0, v66
	v_mov_b32_e32 v0, v67
	s_nop 1
	v_permlane16_swap_b32_e32 v67, v0
	v_add_f32_e32 v67, v67, v0
	v_mov_b32_e32 v68, v66
	v_mov_b32_e32 v69, v67
	s_nop 0
	v_permlane32_swap_b32_e32 v66, v68
	v_permlane32_swap_b32_e32 v67, v69
	s_and_saveexec_b64 s[50:51], s[2:3]
	v_pk_add_f32 v[66:67], v[66:67], v[68:69]
	ds_write_b64 v160, v[66:67] offset:1536
	s_or_b64 exec, exec, s[50:51]
	v_add_u32_e32 v68, 0x80, v183
	v_lshl_or_b32 v0, v68, 3, v173
	v_lshl_add_u64 v[66:67], v[0:1], 2, s[28:29]
	global_load_dwordx2 v[156:157], v[66:67], off
	v_lshlrev_b32_e32 v69, 10, v68
	v_lshlrev_b32_e32 v164, 11, v68
	v_add_u32_e32 v0, v69, v182
	v_or_b32_e32 v68, 0x400, v164
	v_lshl_add_u64 v[154:155], v[0:1], 1, s[26:27]
	global_load_dwordx2 v[158:159], v[154:155], off
	v_add_u32_e32 v66, v68, v182
	v_mov_b32_e32 v67, v1
	v_lshl_add_u64 v[66:67], v[66:67], 1, s[12:13]
	global_load_dwordx2 v[160:161], v[66:67], off
	v_add_u32_e32 v66, v69, v184
	v_mov_b32_e32 v67, v1
	v_lshl_add_u64 v[66:67], v[66:67], 1, s[26:27]
	global_load_dwordx2 v[148:149], v[66:67], off
	v_add_u32_e32 v66, v68, v184
	v_mov_b32_e32 v67, v1
	v_lshl_add_u64 v[66:67], v[66:67], 1, s[12:13]
	global_load_dwordx2 v[150:151], v[66:67], off
	v_add_u32_e32 v66, v69, v181
	v_mov_b32_e32 v67, v1
	v_lshl_add_u64 v[66:67], v[66:67], 1, s[26:27]
	global_load_dwordx2 v[144:145], v[66:67], off
	v_add_u32_e32 v66, v68, v181
	v_mov_b32_e32 v67, v1
	v_lshl_add_u64 v[66:67], v[66:67], 1, s[12:13]
	global_load_dwordx2 v[146:147], v[66:67], off
	v_add_u32_e32 v66, v69, v185
	v_mov_b32_e32 v67, v1
	v_lshl_add_u64 v[66:67], v[66:67], 1, s[26:27]
	global_load_dwordx2 v[140:141], v[66:67], off
	v_add_u32_e32 v66, v68, v185
	v_mov_b32_e32 v67, v1
	v_add_u32_e32 v68, 0x90, v183
	v_lshl_add_u64 v[66:67], v[66:67], 1, s[12:13]
	v_lshlrev_b32_e32 v69, 10, v68
	global_load_dwordx2 v[142:143], v[66:67], off
	v_lshl_or_b32 v66, v68, 3, v173
	v_mov_b32_e32 v67, v1
	v_lshlrev_b32_e32 v153, 11, v68
	v_add_u32_e32 v110, v69, v182
	v_mov_b32_e32 v111, v1
	v_lshl_add_u64 v[66:67], v[66:67], 2, s[28:29]
	v_or_b32_e32 v68, 0x400, v153
	v_lshl_add_u64 v[124:125], v[110:111], 1, s[26:27]
	global_load_dwordx2 v[138:139], v[66:67], off
	global_load_dwordx2 v[126:127], v[124:125], off
	v_add_u32_e32 v66, v68, v182
	v_mov_b32_e32 v67, v1
	v_lshl_add_u64 v[66:67], v[66:67], 1, s[12:13]
	global_load_dwordx2 v[128:129], v[66:67], off
	v_add_u32_e32 v66, v69, v184
	v_mov_b32_e32 v67, v1
	v_lshl_add_u64 v[66:67], v[66:67], 1, s[26:27]
	global_load_dwordx2 v[120:121], v[66:67], off
	v_add_u32_e32 v66, v68, v184
	v_mov_b32_e32 v67, v1
	v_lshl_add_u64 v[66:67], v[66:67], 1, s[12:13]
; __device__ __forceinline__ float xsum_rows(float v) { return xsum32(xsum16(v)); }
; #define PG8_LAS __attribute__((address_space(3)))
;     template <int AI, int M0, int NR>
;     __device__ __forceinline__ void batch(const f32x4 (&acc)[2][2][4][2], int row0, int col0, int wr, int wc, int fr, int fq, PG8_LAS float* red, const PG8_LAS float* gl) const {
;     ...
;         for (int mm = 0; mm < NR; ++mm) { const unsigned rr_ = (unsigned)(row0 + AI * HALF + (M0 + mm) * 16); stv[mm] = *(const f32x2*)(stp + (8u * rr_ + 2u * (unsigned)fq));
; #pragma unroll
;             for (int bj = 0; bj < 2; ++bj)
; #pragma unroll
;                 for (int n = 0; n < 2; ++n) { const unsigned cc_ = (unsigned)(col0 + bj * HALF + n * 16);
;                     xh[mm][bj][n] = *(const f32x2*)(PB + (rr_ * 1024u + cc_)); xl[mm][bj][n] = *(const f32x2*)((const bf16_t*)X + (rr_ * 2048u + 1024u + cc_)); } }
; #pragma unroll
;         for (int mm = 0; mm < NR; ++mm) { const int m = M0 + mm; const int row = row0 + AI * HALF + m * 16;
;             float rs, ms; { f32x2 v = stv[mm]; v.x = xsum_rows(v.x); v.y = xsum_rows(v.y);
;               const float mean = v.x * (1.0f / 1024.0f); const float var = v.y * (1.0f / 1024.0f) - mean * mean; rs = __builtin_amdgcn_rsqf(var + 1e-5f); ms = rs * mean; }
;             const unsigned ro = (unsigned)row * 1024u + (unsigned)col0;
;             float sm = 0.f, sq = 0.f;
; #pragma unroll
;             for (int bj = 0; bj < 2; ++bj)
; #pragma unroll
;                 for (int n = 0; n < 2; ++n) { const unsigned hw0 = __float_as_uint(xh[mm][bj][n].x), hw1 = __float_as_uint(xh[mm][bj][n].y), lw0 = __float_as_uint(xl[mm][bj][n].x), lw1 = __float_as_uint(xl[mm][bj][n].y);
;                     f32x4 x; x[0] = __uint_as_float(hw0 << 16) + __uint_as_float(lw0 << 16); x[1] = __uint_as_float(hw0 & 0xffff0000u) + __uint_as_float(lw0 & 0xffff0000u);
;                     x[2] = __uint_as_float(hw1 << 16) + __uint_as_float(lw1 << 16); x[3] = __uint_as_float(hw1 & 0xffff0000u) + __uint_as_float(lw1 & 0xffff0000u);
;                     const f32x4 gvv = *(const PG8_LAS f32x4*)(gl + bj * HALF + n * 16), bvv = *(const PG8_LAS f32x4*)(gl + 1024 + bj * HALF + n * 16);
;                     const f32x4 xn = (x * rs - ms) * gvv + bvv; const f32x4 y = xn * alpha + acc[AI][bj][m][n] * s;
	global_load_dwordx2 v[122:123], v[66:67], off
	v_add_u32_e32 v66, v69, v181
	v_mov_b32_e32 v67, v1
	v_lshl_add_u64 v[66:67], v[66:67], 1, s[26:27]
	global_load_dwordx2 v[116:117], v[66:67], off
	v_add_u32_e32 v66, v68, v181
	v_mov_b32_e32 v67, v1
	v_lshl_add_u64 v[66:67], v[66:67], 1, s[12:13]
	global_load_dwordx2 v[118:119], v[66:67], off
	v_add_u32_e32 v66, v69, v185
	v_mov_b32_e32 v67, v1
	v_lshl_add_u64 v[66:67], v[66:67], 1, s[26:27]
	global_load_dwordx2 v[112:113], v[66:67], off
	v_add_u32_e32 v66, v68, v185
	v_mov_b32_e32 v67, v1
	v_add_u32_e32 v68, 0xa0, v183
	v_lshl_add_u64 v[66:67], v[66:67], 1, s[12:13]
	v_lshlrev_b32_e32 v69, 10, v68
	global_load_dwordx2 v[114:115], v[66:67], off
	v_lshl_or_b32 v66, v68, 3, v173
	v_mov_b32_e32 v67, v1
	v_lshlrev_b32_e32 v111, 11, v68
	v_add_u32_e32 v88, v69, v182
	v_mov_b32_e32 v89, v1
	v_lshl_add_u64 v[66:67], v[66:67], 2, s[28:29]
	v_or_b32_e32 v68, 0x400, v111
	v_lshl_add_u64 v[102:103], v[88:89], 1, s[26:27]
	global_load_dwordx2 v[108:109], v[66:67], off
	global_load_dwordx2 v[104:105], v[102:103], off
	v_add_u32_e32 v66, v68, v182
	v_mov_b32_e32 v67, v1
	v_lshl_add_u64 v[66:67], v[66:67], 1, s[12:13]
	global_load_dwordx2 v[106:107], v[66:67], off
	v_add_u32_e32 v66, v69, v184
	v_mov_b32_e32 v67, v1
	v_lshl_add_u64 v[66:67], v[66:67], 1, s[26:27]
	global_load_dwordx2 v[98:99], v[66:67], off
	v_add_u32_e32 v66, v68, v184
	v_mov_b32_e32 v67, v1
	v_lshl_add_u64 v[66:67], v[66:67], 1, s[12:13]
	global_load_dwordx2 v[100:101], v[66:67], off
	v_add_u32_e32 v66, v69, v181
	v_mov_b32_e32 v67, v1
	v_lshl_add_u64 v[66:67], v[66:67], 1, s[26:27]
	global_load_dwordx2 v[94:95], v[66:67], off
	v_add_u32_e32 v66, v68, v181
	v_mov_b32_e32 v67, v1
	v_lshl_add_u64 v[66:67], v[66:67], 1, s[12:13]
	global_load_dwordx2 v[96:97], v[66:67], off
	v_add_u32_e32 v66, v69, v185
	v_mov_b32_e32 v67, v1
	v_lshl_add_u64 v[66:67], v[66:67], 1, s[26:27]
	global_load_dwordx2 v[90:91], v[66:67], off
	v_add_u32_e32 v66, v68, v185
	v_add_u32_e32 v68, 0xb0, v183
	v_mov_b32_e32 v67, v1
	v_lshlrev_b32_e32 v89, 11, v68
	v_lshl_add_u64 v[66:67], v[66:67], 1, s[12:13]
	v_or_b32_e32 v71, 0x400, v89
	global_load_dwordx2 v[92:93], v[66:67], off
	v_lshl_or_b32 v66, v68, 3, v173
	v_mov_b32_e32 v67, v1
	v_lshlrev_b32_e32 v70, 10, v68
	v_add_u32_e32 v68, v71, v182
	v_mov_b32_e32 v69, v1
	v_lshl_add_u64 v[66:67], v[66:67], 2, s[28:29]
	v_lshl_add_u64 v[68:69], v[68:69], 1, s[12:13]
	global_load_dwordx2 v[86:87], v[66:67], off
	v_add_u32_e32 v66, v70, v182
	v_mov_b32_e32 v67, v1
	global_load_dwordx2 v[84:85], v[68:69], off
	v_add_u32_e32 v68, v70, v184
	v_mov_b32_e32 v69, v1
	v_lshl_add_u64 v[80:81], v[66:67], 1, s[26:27]
	v_lshl_add_u64 v[68:69], v[68:69], 1, s[26:27]
	s_waitcnt vmcnt(0) lgkmcnt(0)
	v_mov_b32_e32 v67, v156
	global_load_dwordx2 v[82:83], v[80:81], off
	global_load_dwordx2 v[76:77], v[68:69], off
	v_add_u32_e32 v68, v71, v184
	v_mov_b32_e32 v69, v1
	v_permlane16_swap_b32_e32 v156, v67
	v_lshl_add_u64 v[68:69], v[68:69], 1, s[12:13]
	v_add_f32_e32 v163, v156, v67
	v_mov_b32_e32 v67, v157
	global_load_dwordx2 v[78:79], v[68:69], off
	v_add_u32_e32 v68, v70, v181
	v_mov_b32_e32 v69, v1
	v_permlane16_swap_b32_e32 v157, v67
	v_lshl_add_u64 v[68:69], v[68:69], 1, s[26:27]
	v_add_f32_e32 v162, v157, v67
	global_load_dwordx2 v[72:73], v[68:69], off
	v_add_u32_e32 v68, v71, v181
	v_mov_b32_e32 v69, v1
	v_mov_b32_e32 v167, v163
	v_mov_b32_e32 v166, v162
	v_lshl_add_u64 v[68:69], v[68:69], 1, s[12:13]
	v_permlane32_swap_b32_e32 v163, v167
	v_permlane32_swap_b32_e32 v162, v166
	global_load_dwordx2 v[74:75], v[68:69], off
	v_add_u32_e32 v68, v70, v185
	v_mov_b32_e32 v69, v1
	v_add_u32_e32 v70, v71, v185
	v_mov_b32_e32 v71, v1
	v_pk_add_f32 v[156:157], v[162:163], v[166:167]
	v_lshl_add_u64 v[68:69], v[68:69], 1, s[26:27]
	v_lshl_add_u64 v[70:71], v[70:71], 1, s[12:13]
	v_pk_mul_f32 v[156:157], v[156:157], s[68:69] op_sel_hi:[1,0]
	global_load_dwordx2 v[68:69], v[68:69], off
	v_fma_f32 v67, -v157, v157, v156
	global_load_dwordx2 v[70:71], v[70:71], off
	v_add_f32_e32 v67, 0x3727c5ac, v67
	v_rsq_f32_e32 v152, v67
	v_lshlrev_b32_e32 v166, 16, v158
	v_and_b32_e32 v167, 0xffff0000, v158
	v_lshlrev_b32_e32 v168, 16, v160
	v_and_b32_e32 v169, 0xffff0000, v160
	v_lshlrev_b32_e32 v158, 16, v159
	v_and_b32_e32 v159, 0xffff0000, v159
	v_lshlrev_b32_e32 v160, 16, v161
	v_and_b32_e32 v161, 0xffff0000, v161
	v_pk_add_f32 v[182:183], v[166:167], v[168:169]
	v_pk_add_f32 v[184:185], v[158:159], v[160:161]
	ds_read_b128 v[158:161], v179
	ds_read_b128 v[166:169], v179 offset:4096
	v_mul_f32_e64 v156, v157, -v152
	v_pk_fma_f32 v[182:183], v[182:183], v[152:153], v[156:157] op_sel_hi:[1,0,0]
	v_pk_fma_f32 v[184:185], v[184:185], v[152:153], v[156:157] op_sel_hi:[1,0,0]
	v_add_u32_e32 v162, v164, v180
	s_waitcnt lgkmcnt(0)
; #define PG8_LAS __attribute__((address_space(3)))
; __device__ __forceinline__ unsigned cvt_pk_bf16(float lo, float hi) { unsigned r; asm volatile("v_cvt_pk_bf16_f32 %0, %1, %2" : "=v"(r) : "v"(lo), "v"(hi)); return r; }
;     template <int AI, int M0, int NR>
;     __device__ __forceinline__ void batch(const f32x4 (&acc)[2][2][4][2], int row0, int col0, int wr, int wc, int fr, int fq, PG8_LAS float* red, const PG8_LAS float* gl) const {
;     ...
;             const unsigned ro = (unsigned)row * 1024u + (unsigned)col0;
;             float sm = 0.f, sq = 0.f;
; #pragma unroll
;             for (int bj = 0; bj < 2; ++bj)
; #pragma unroll
;                 for (int n = 0; n < 2; ++n) { const unsigned hw0 = __float_as_uint(xh[mm][bj][n].x), hw1 = __float_as_uint(xh[mm][bj][n].y), lw0 = __float_as_uint(xl[mm][bj][n].x), lw1 = __float_as_uint(xl[mm][bj][n].y);
;                     f32x4 x; x[0] = __uint_as_float(hw0 << 16) + __uint_as_float(lw0 << 16); x[1] = __uint_as_float(hw0 & 0xffff0000u) + __uint_as_float(lw0 & 0xffff0000u);
;                     x[2] = __uint_as_float(hw1 << 16) + __uint_as_float(lw1 << 16); x[3] = __uint_as_float(hw1 & 0xffff0000u) + __uint_as_float(lw1 & 0xffff0000u);
;                     const f32x4 gvv = *(const PG8_LAS f32x4*)(gl + bj * HALF + n * 16), bvv = *(const PG8_LAS f32x4*)(gl + 1024 + bj * HALF + n * 16);
;                     const f32x4 xn = (x * rs - ms) * gvv + bvv; const f32x4 y = xn * alpha + acc[AI][bj][m][n] * s;
;                     const unsigned nh0 = cvt_pk_bf16(y[0], y[1]), nh1 = cvt_pk_bf16(y[2], y[3]);
;                     f32x2 w; w.x = __uint_as_float(nh0); w.y = __uint_as_float(nh1); *(f32x2*)(PB + (ro + (unsigned)(bj * HALF + n * 16))) = w;
;                     f32x2 wl; wl.x = __uint_as_float(cvt_pk_bf16(y[0] - __uint_as_float(nh0 << 16), y[1] - __uint_as_float(nh0 & 0xffff0000u))); wl.y = __uint_as_float(cvt_pk_bf16(y[2] - __uint_as_float(nh1 << 16), y[3] - __uint_as_float(nh1 & 0xffff0000u)));
;                     *(f32x2*)((bf16_t*)X + ((unsigned)row * 2048u + 1024u + (unsigned)(col0 + bj * HALF + n * 16))) = wl;
;                     sm += (y[0] + y[1]) + (y[2] + y[3]); sq += (y[0] * y[0] + y[1] * y[1]) + (y[2] * y[2] + y[3] * y[3]); }
	v_pk_fma_f32 v[158:159], v[158:159], v[182:183], v[166:167]
	v_pk_fma_f32 v[160:161], v[160:161], v[184:185], v[168:169]
	v_pk_mul_f32 v[158:159], v[158:159], s[60:61] op_sel_hi:[1,0]
	v_pk_mul_f32 v[160:161], v[160:161], s[60:61] op_sel_hi:[1,0]
	v_pk_fma_f32 v[158:159], s[10:11], v[62:63], v[158:159]
	v_pk_fma_f32 v[64:65], s[24:25], v[64:65], v[160:161]
	v_cvt_pk_bf16_f32 v62, v158, v159
	v_mov_b32_e32 v163, v1
	v_cvt_pk_bf16_f32 v63, v64, v65
	global_store_dwordx2 v[154:155], v[62:63], off
	v_lshlrev_b32_e32 v67, 16, v62
	v_and_b32_e32 v62, 0xffff0000, v62
	v_sub_f32_e32 v62, v159, v62
	v_sub_f32_e32 v67, v158, v67
	v_cvt_pk_bf16_f32 v154, v67, v62
	v_lshlrev_b32_e32 v62, 16, v63
	v_and_b32_e32 v63, 0xffff0000, v63
	v_sub_f32_e32 v62, v64, v62
	v_sub_f32_e32 v63, v65, v63
	v_cvt_pk_bf16_f32 v155, v62, v63
	v_lshl_add_u64 v[62:63], v[162:163], 1, s[12:13]
	global_store_dwordx2 v[62:63], v[154:155], off
	v_add_f32_e32 v67, v158, v159
	v_add_f32_e32 v154, v64, v65
	v_add_f32_e32 v67, v67, v154
	v_mul_f32_e32 v154, v159, v159
	v_mul_f32_e32 v65, v65, v65
	v_fmac_f32_e32 v154, v158, v158
	v_fmac_f32_e32 v65, v64, v64
	v_add_f32_e32 v157, v154, v65
	v_lshlrev_b32_e32 v64, 16, v148
	v_and_b32_e32 v65, 0xffff0000, v148
	v_lshlrev_b32_e32 v154, 16, v150
	v_and_b32_e32 v155, 0xffff0000, v150
	v_lshlrev_b32_e32 v148, 16, v149
	v_and_b32_e32 v149, 0xffff0000, v149
	v_lshlrev_b32_e32 v150, 16, v151
	v_and_b32_e32 v151, 0xffff0000, v151
	v_pk_add_f32 v[64:65], v[64:65], v[154:155]
	v_pk_add_f32 v[154:155], v[148:149], v[150:151]
	ds_read_b128 v[148:151], v179 offset:64
	ds_read_b128 v[158:161], v179 offset:4160
	v_pk_fma_f32 v[154:155], v[154:155], v[152:153], v[156:157] op_sel_hi:[1,0,0]
	v_pk_fma_f32 v[64:65], v[64:65], v[152:153], v[156:157] op_sel_hi:[1,0,0]
	v_add_f32_e32 v67, 0, v67
	s_waitcnt lgkmcnt(0)
	v_pk_fma_f32 v[150:151], v[150:151], v[154:155], v[160:161]
	v_pk_fma_f32 v[64:65], v[148:149], v[64:65], v[158:159]
	v_pk_mul_f32 v[148:149], v[150:151], s[60:61] op_sel_hi:[1,0]
	v_pk_mul_f32 v[64:65], v[64:65], s[60:61] op_sel_hi:[1,0]
	v_pk_fma_f32 v[60:61], s[24:25], v[60:61], v[148:149]
	v_or_b32_e32 v148, 16, v0
	v_mov_b32_e32 v149, v1
	v_pk_fma_f32 v[58:59], s[10:11], v[58:59], v[64:65]
	v_lshl_add_u64 v[148:149], v[148:149], 1, s[26:27]
	v_cvt_pk_bf16_f32 v64, v58, v59
	v_cvt_pk_bf16_f32 v65, v60, v61
	global_store_dwordx2 v[148:149], v[64:65], off
	v_lshlrev_b32_e32 v148, 16, v64
	v_and_b32_e32 v64, 0xffff0000, v64
	v_sub_f32_e32 v148, v58, v148
	v_sub_f32_e32 v64, v59, v64
	v_cvt_pk_bf16_f32 v64, v148, v64
	v_lshlrev_b32_e32 v148, 16, v65
	v_and_b32_e32 v65, 0xffff0000, v65
	v_sub_f32_e32 v65, v61, v65
	v_sub_f32_e32 v148, v60, v148
	v_cvt_pk_bf16_f32 v65, v148, v65
	global_store_dwordx2 v[62:63], v[64:65], off offset:32
	v_add_f32_e32 v64, v58, v59
	v_mul_f32_e32 v59, v59, v59
	v_fmac_f32_e32 v59, v58, v58
	v_mul_f32_e32 v58, v61, v61
	v_fmac_f32_e32 v58, v60, v60
	v_add_f32_e32 v58, v59, v58
	v_add_f32_e32 v65, v60, v61
	v_add_f32_e32 v154, v157, v58
	v_lshlrev_b32_e32 v58, 16, v144
	v_and_b32_e32 v59, 0xffff0000, v144
	v_lshlrev_b32_e32 v60, 16, v146
	v_and_b32_e32 v61, 0xffff0000, v146
	v_pk_add_f32 v[148:149], v[58:59], v[60:61]
	v_lshlrev_b32_e32 v58, 16, v145
	v_and_b32_e32 v59, 0xffff0000, v145
	v_lshlrev_b32_e32 v60, 16, v147
	v_and_b32_e32 v61, 0xffff0000, v147
	v_pk_add_f32 v[150:151], v[58:59], v[60:61]
	ds_read_b128 v[58:61], v179 offset:512
	ds_read_b128 v[144:147], v179 offset:4608
	v_pk_fma_f32 v[148:149], v[148:149], v[152:153], v[156:157] op_sel_hi:[1,0,0]
	v_pk_fma_f32 v[150:151], v[150:151], v[152:153], v[156:157] op_sel_hi:[1,0,0]
	v_add_f32_e32 v64, v64, v65
	v_add_f32_e32 v67, v64, v67
	s_waitcnt lgkmcnt(0)
	v_pk_fma_f32 v[60:61], v[150:151], v[60:61], v[146:147]
	v_pk_fma_f32 v[58:59], v[148:149], v[58:59], v[144:145]
	v_or_b32_e32 v64, 0x80, v0
	v_pk_mul_f32 v[58:59], v[58:59], s[60:61] op_sel_hi:[1,0]
	v_pk_mul_f32 v[60:61], v[60:61], s[60:61] op_sel_hi:[1,0]
	v_mov_b32_e32 v65, v1
	v_pk_fma_f32 v[56:57], s[24:25], v[56:57], v[60:61]
	v_pk_fma_f32 v[54:55], s[10:11], v[54:55], v[58:59]
	v_lshl_add_u64 v[60:61], v[64:65], 1, s[26:27]
	v_cvt_pk_bf16_f32 v58, v54, v55
	v_cvt_pk_bf16_f32 v59, v56, v57
	global_store_dwordx2 v[60:61], v[58:59], off
	v_lshlrev_b32_e32 v60, 16, v58
	v_and_b32_e32 v58, 0xffff0000, v58
	v_sub_f32_e32 v60, v54, v60
	v_sub_f32_e32 v58, v55, v58
	v_cvt_pk_bf16_f32 v58, v60, v58
	v_lshlrev_b32_e32 v60, 16, v59
	v_and_b32_e32 v59, 0xffff0000, v59
	v_sub_f32_e32 v59, v57, v59
	v_sub_f32_e32 v60, v56, v60
	v_cvt_pk_bf16_f32 v59, v60, v59
	global_store_dwordx2 v[62:63], v[58:59], off offset:256
	v_add_f32_e32 v58, v54, v55
	v_mul_f32_e32 v55, v55, v55
	v_fmac_f32_e32 v55, v54, v54
	v_mul_f32_e32 v54, v57, v57
	v_fmac_f32_e32 v54, v56, v56
	v_add_f32_e32 v54, v55, v54
	v_add_f32_e32 v59, v56, v57
	v_add_f32_e32 v144, v154, v54
	v_lshlrev_b32_e32 v54, 16, v140
	v_and_b32_e32 v55, 0xffff0000, v140
	v_lshlrev_b32_e32 v56, 16, v142
	v_and_b32_e32 v57, 0xffff0000, v142
	v_add_f32_e32 v58, v58, v59
	v_pk_add_f32 v[64:65], v[54:55], v[56:57]
	v_lshlrev_b32_e32 v54, 16, v141
	v_and_b32_e32 v55, 0xffff0000, v141
	v_lshlrev_b32_e32 v56, 16, v143
	v_and_b32_e32 v57, 0xffff0000, v143
	v_add_f32_e32 v67, v67, v58
	v_pk_add_f32 v[140:141], v[54:55], v[56:57]
	ds_read_b128 v[54:57], v179 offset:576
	ds_read_b128 v[58:61], v179 offset:4672
	v_pk_fma_f32 v[64:65], v[64:65], v[152:153], v[156:157] op_sel_hi:[1,0,0]
	v_pk_fma_f32 v[140:141], v[140:141], v[152:153], v[156:157] op_sel_hi:[1,0,0]
	v_or_b32_e32 v0, 0x90, v0
	s_waitcnt lgkmcnt(0)
;     template <int AI, int M0, int NR>
;     __device__ __forceinline__ void batch(const f32x4 (&acc)[2][2][4][2], int row0, int col0, int wr, int wc, int fr, int fq, PG8_LAS float* red, const PG8_LAS float* gl) const {
;     ...
;         for (int mm = 0; mm < NR; ++mm) { const int m = M0 + mm; const int row = row0 + AI * HALF + m * 16;
;             float rs, ms; { f32x2 v = stv[mm]; v.x = xsum_rows(v.x); v.y = xsum_rows(v.y);
;               const float mean = v.x * (1.0f / 1024.0f); const float var = v.y * (1.0f / 1024.0f) - mean * mean; rs = __builtin_amdgcn_rsqf(var + 1e-5f); ms = rs * mean; }
;             const unsigned ro = (unsigned)row * 1024u + (unsigned)col0;
;             float sm = 0.f, sq = 0.f;
; #pragma unroll
;             for (int bj = 0; bj < 2; ++bj)
; #pragma unroll
;                 for (int n = 0; n < 2; ++n) { const unsigned hw0 = __float_as_uint(xh[mm][bj][n].x), hw1 = __float_as_uint(xh[mm][bj][n].y), lw0 = __float_as_uint(xl[mm][bj][n].x), lw1 = __float_as_uint(xl[mm][bj][n].y);
;                     f32x4 x; x[0] = __uint_as_float(hw0 << 16) + __uint_as_float(lw0 << 16); x[1] = __uint_as_float(hw0 & 0xffff0000u) + __uint_as_float(lw0 & 0xffff0000u);
;                     x[2] = __uint_as_float(hw1 << 16) + __uint_as_float(lw1 << 16); x[3] = __uint_as_float(hw1 & 0xffff0000u) + __uint_as_float(lw1 & 0xffff0000u);
;                     const f32x4 gvv = *(const PG8_LAS f32x4*)(gl + bj * HALF + n * 16), bvv = *(const PG8_LAS f32x4*)(gl + 1024 + bj * HALF + n * 16);
;                     const f32x4 xn = (x * rs - ms) * gvv + bvv; const f32x4 y = xn * alpha + acc[AI][bj][m][n] * s;
;                     const unsigned nh0 = cvt_pk_bf16(y[0], y[1]), nh1 = cvt_pk_bf16(y[2], y[3]);
;                     f32x2 w; w.x = __uint_as_float(nh0); w.y = __uint_as_float(nh1); *(f32x2*)(PB + (ro + (unsigned)(bj * HALF + n * 16))) = w;
;                     f32x2 wl; wl.x = __uint_as_float(cvt_pk_bf16(y[0] - __uint_as_float(nh0 << 16), y[1] - __uint_as_float(nh0 & 0xffff0000u))); wl.y = __uint_as_float(cvt_pk_bf16(y[2] - __uint_as_float(nh1 << 16), y[3] - __uint_as_float(nh1 & 0xffff0000u)));
;                     *(f32x2*)((bf16_t*)X + ((unsigned)row * 2048u + 1024u + (unsigned)(col0 + bj * HALF + n * 16))) = wl;
;                     sm += (y[0] + y[1]) + (y[2] + y[3]); sq += (y[0] * y[0] + y[1] * y[1]) + (y[2] * y[2] + y[3] * y[3]); }
	v_pk_fma_f32 v[56:57], v[140:141], v[56:57], v[60:61]
	v_pk_fma_f32 v[54:55], v[64:65], v[54:55], v[58:59]
	v_pk_mul_f32 v[56:57], v[56:57], s[60:61] op_sel_hi:[1,0]
	v_pk_mul_f32 v[54:55], v[54:55], s[60:61] op_sel_hi:[1,0]
	v_pk_fma_f32 v[52:53], s[24:25], v[52:53], v[56:57]
	v_pk_fma_f32 v[50:51], s[10:11], v[50:51], v[54:55]
	v_lshl_add_u64 v[56:57], v[0:1], 1, s[26:27]
	v_cvt_pk_bf16_f32 v54, v50, v51
	v_cvt_pk_bf16_f32 v55, v52, v53
	global_store_dwordx2 v[56:57], v[54:55], off
	v_lshlrev_b32_e32 v0, 16, v54
	v_and_b32_e32 v54, 0xffff0000, v54
	v_sub_f32_e32 v0, v50, v0
	v_sub_f32_e32 v54, v51, v54
	v_cvt_pk_bf16_f32 v54, v0, v54
	v_lshlrev_b32_e32 v0, 16, v55
	v_and_b32_e32 v55, 0xffff0000, v55
	v_sub_f32_e32 v0, v52, v0
	v_sub_f32_e32 v55, v53, v55
	v_cvt_pk_bf16_f32 v55, v0, v55
	v_add_f32_e32 v0, v50, v51
	v_mul_f32_e32 v51, v51, v51
	global_store_dwordx2 v[62:63], v[54:55], off offset:288
	v_add_f32_e32 v54, v52, v53
	v_fmac_f32_e32 v51, v50, v50
	v_mul_f32_e32 v50, v53, v53
	v_add_f32_e32 v0, v0, v54
	v_fmac_f32_e32 v50, v52, v52
	v_add_f32_e32 v0, v67, v0
	v_add_f32_e32 v50, v51, v50
	v_add_f32_e32 v51, v144, v50
	v_mov_b32_e32 v50, v0
	s_nop 1
	v_permlane16_swap_b32_e32 v0, v50
	v_add_f32_e32 v50, v0, v50
	v_mov_b32_e32 v0, v51
	s_nop 1
	v_permlane16_swap_b32_e32 v51, v0
	v_add_f32_e32 v51, v51, v0
	v_mov_b32_e32 v52, v50
	v_mov_b32_e32 v53, v51
	s_nop 0
	v_permlane32_swap_b32_e32 v50, v52
	v_permlane32_swap_b32_e32 v51, v53
	s_and_saveexec_b64 s[50:51], s[2:3]
	v_pk_add_f32 v[50:51], v[50:51], v[52:53]
	ds_write_b64 v178, v[50:51]
	s_or_b64 exec, exec, s[50:51]
	v_mov_b32_e32 v0, v138
	s_nop 1
	v_permlane16_swap_b32_e32 v138, v0
	v_add_f32_e32 v51, v138, v0
	v_mov_b32_e32 v0, v139
	s_nop 1
	v_permlane16_swap_b32_e32 v139, v0
	v_add_f32_e32 v50, v139, v0
	v_mov_b32_e32 v53, v51
	v_mov_b32_e32 v52, v50
	s_nop 0
	v_permlane32_swap_b32_e32 v51, v53
	v_permlane32_swap_b32_e32 v50, v52
	v_pk_add_f32 v[50:51], v[50:51], v[52:53]
	v_lshlrev_b32_e32 v52, 16, v126
	v_pk_mul_f32 v[50:51], v[50:51], s[68:69] op_sel_hi:[1,0]
	v_and_b32_e32 v53, 0xffff0000, v126
	v_fma_f32 v0, -v51, v51, v50
	v_add_f32_e32 v0, 0x3727c5ac, v0
	v_lshlrev_b32_e32 v54, 16, v128
	v_and_b32_e32 v55, 0xffff0000, v128
	v_rsq_f32_e32 v50, v0
	v_pk_add_f32 v[62:63], v[52:53], v[54:55]
	v_lshlrev_b32_e32 v52, 16, v127
	v_and_b32_e32 v53, 0xffff0000, v127
	v_lshlrev_b32_e32 v54, 16, v129
	v_and_b32_e32 v55, 0xffff0000, v129
	v_pk_add_f32 v[64:65], v[52:53], v[54:55]
	ds_read_b128 v[54:57], v179
	ds_read_b128 v[58:61], v179 offset:4096
	v_mul_f32_e64 v52, v51, -v50
	v_pk_fma_f32 v[62:63], v[62:63], v[50:51], v[52:53] op_sel_hi:[1,0,0]
	v_pk_fma_f32 v[64:65], v[64:65], v[50:51], v[52:53] op_sel_hi:[1,0,0]
	v_add_u32_e32 v0, v153, v180
	s_waitcnt lgkmcnt(0)
	v_pk_fma_f32 v[54:55], v[54:55], v[62:63], v[58:59]
	v_pk_fma_f32 v[56:57], v[56:57], v[64:65], v[60:61]
	v_pk_mul_f32 v[54:55], v[54:55], s[60:61] op_sel_hi:[1,0]
	v_pk_mul_f32 v[56:57], v[56:57], s[60:61] op_sel_hi:[1,0]
	v_pk_fma_f32 v[54:55], s[10:11], v[46:47], v[54:55]
	v_pk_fma_f32 v[48:49], s[24:25], v[48:49], v[56:57]
	v_cvt_pk_bf16_f32 v46, v54, v55
	s_nop 0
	v_cvt_pk_bf16_f32 v47, v48, v49
	global_store_dwordx2 v[124:125], v[46:47], off
	v_lshlrev_b32_e32 v51, 16, v46
	v_and_b32_e32 v46, 0xffff0000, v46
	v_sub_f32_e32 v46, v55, v46
	v_sub_f32_e32 v51, v54, v51
	v_cvt_pk_bf16_f32 v56, v51, v46
	v_lshlrev_b32_e32 v46, 16, v47
	v_and_b32_e32 v47, 0xffff0000, v47
	v_sub_f32_e32 v46, v48, v46
	v_sub_f32_e32 v47, v49, v47
	v_cvt_pk_bf16_f32 v57, v46, v47
	v_lshl_add_u64 v[46:47], v[0:1], 1, s[12:13]
	v_add_f32_e32 v0, v54, v55
	v_add_f32_e32 v51, v48, v49
	v_add_f32_e32 v0, v0, v51
	v_add_f32_e32 v51, 0, v0
	v_mul_f32_e32 v0, v55, v55
	v_mul_f32_e32 v49, v49, v49
	v_fmac_f32_e32 v0, v54, v54
	v_fmac_f32_e32 v49, v48, v48
	v_add_f32_e32 v53, v0, v49
	v_lshlrev_b32_e32 v48, 16, v120
	v_and_b32_e32 v49, 0xffff0000, v120
	v_lshlrev_b32_e32 v54, 16, v122
	v_and_b32_e32 v55, 0xffff0000, v122
	global_store_dwordx2 v[46:47], v[56:57], off
	v_pk_add_f32 v[48:49], v[48:49], v[54:55]
	v_lshlrev_b32_e32 v54, 16, v121
	v_and_b32_e32 v55, 0xffff0000, v121
	v_lshlrev_b32_e32 v56, 16, v123
	v_and_b32_e32 v57, 0xffff0000, v123
	v_pk_add_f32 v[62:63], v[54:55], v[56:57]
	ds_read_b128 v[54:57], v179 offset:64
	ds_read_b128 v[58:61], v179 offset:4160
	v_pk_fma_f32 v[48:49], v[48:49], v[50:51], v[52:53] op_sel_hi:[1,0,0]
	v_pk_fma_f32 v[62:63], v[62:63], v[50:51], v[52:53] op_sel_hi:[1,0,0]
	v_or_b32_e32 v0, 16, v110
	s_waitcnt lgkmcnt(0)
	v_pk_fma_f32 v[56:57], v[56:57], v[62:63], v[60:61]
	v_pk_fma_f32 v[48:49], v[54:55], v[48:49], v[58:59]
	v_pk_mul_f32 v[54:55], v[56:57], s[60:61] op_sel_hi:[1,0]
	v_pk_mul_f32 v[48:49], v[48:49], s[60:61] op_sel_hi:[1,0]
	v_pk_fma_f32 v[44:45], s[24:25], v[44:45], v[54:55]
	v_pk_fma_f32 v[42:43], s[10:11], v[42:43], v[48:49]
	v_lshl_add_u64 v[54:55], v[0:1], 1, s[26:27]
	v_cvt_pk_bf16_f32 v48, v42, v43
	v_cvt_pk_bf16_f32 v49, v44, v45
	global_store_dwordx2 v[54:55], v[48:49], off
	v_lshlrev_b32_e32 v0, 16, v48
	v_and_b32_e32 v48, 0xffff0000, v48
	v_sub_f32_e32 v0, v42, v0
	v_sub_f32_e32 v48, v43, v48
	v_cvt_pk_bf16_f32 v48, v0, v48
	v_lshlrev_b32_e32 v0, 16, v49
	v_and_b32_e32 v49, 0xffff0000, v49
	v_sub_f32_e32 v0, v44, v0
	v_sub_f32_e32 v49, v45, v49
	v_cvt_pk_bf16_f32 v49, v0, v49
	global_store_dwordx2 v[46:47], v[48:49], off offset:32
	v_add_f32_e32 v0, v42, v43
	v_add_f32_e32 v48, v44, v45
	v_add_f32_e32 v0, v0, v48
	v_add_f32_e32 v51, v0, v51
	v_mul_f32_e32 v0, v43, v43
	v_fmac_f32_e32 v0, v42, v42
	v_mul_f32_e32 v42, v45, v45
	v_fmac_f32_e32 v42, v44, v44
	v_add_f32_e32 v0, v0, v42
	v_lshlrev_b32_e32 v42, 16, v116
	v_and_b32_e32 v43, 0xffff0000, v116
	v_lshlrev_b32_e32 v44, 16, v118
	v_and_b32_e32 v45, 0xffff0000, v118
	v_pk_add_f32 v[48:49], v[42:43], v[44:45]
	v_lshlrev_b32_e32 v42, 16, v117
	v_and_b32_e32 v43, 0xffff0000, v117
	v_lshlrev_b32_e32 v44, 16, v119
	v_and_b32_e32 v45, 0xffff0000, v119
	v_pk_add_f32 v[58:59], v[42:43], v[44:45]
	ds_read_b128 v[42:45], v179 offset:512
	ds_read_b128 v[54:57], v179 offset:4608
	v_add_f32_e32 v53, v53, v0
	v_pk_fma_f32 v[48:49], v[48:49], v[50:51], v[52:53] op_sel_hi:[1,0,0]
	v_pk_fma_f32 v[58:59], v[58:59], v[50:51], v[52:53] op_sel_hi:[1,0,0]
	v_or_b32_e32 v0, 0x80, v110
	s_waitcnt lgkmcnt(0)
;     template <int AI, int M0, int NR>
;     __device__ __forceinline__ void batch(const f32x4 (&acc)[2][2][4][2], int row0, int col0, int wr, int wc, int fr, int fq, PG8_LAS float* red, const PG8_LAS float* gl) const {
;     ...
;         for (int mm = 0; mm < NR; ++mm) { const int m = M0 + mm; const int row = row0 + AI * HALF + m * 16;
;             float rs, ms; { f32x2 v = stv[mm]; v.x = xsum_rows(v.x); v.y = xsum_rows(v.y);
;               const float mean = v.x * (1.0f / 1024.0f); const float var = v.y * (1.0f / 1024.0f) - mean * mean; rs = __builtin_amdgcn_rsqf(var + 1e-5f); ms = rs * mean; }
;             const unsigned ro = (unsigned)row * 1024u + (unsigned)col0;
;             float sm = 0.f, sq = 0.f;
; #pragma unroll
;             for (int bj = 0; bj < 2; ++bj)
; #pragma unroll
;                 for (int n = 0; n < 2; ++n) { const unsigned hw0 = __float_as_uint(xh[mm][bj][n].x), hw1 = __float_as_uint(xh[mm][bj][n].y), lw0 = __float_as_uint(xl[mm][bj][n].x), lw1 = __float_as_uint(xl[mm][bj][n].y);
;                     f32x4 x; x[0] = __uint_as_float(hw0 << 16) + __uint_as_float(lw0 << 16); x[1] = __uint_as_float(hw0 & 0xffff0000u) + __uint_as_float(lw0 & 0xffff0000u);
;                     x[2] = __uint_as_float(hw1 << 16) + __uint_as_float(lw1 << 16); x[3] = __uint_as_float(hw1 & 0xffff0000u) + __uint_as_float(lw1 & 0xffff0000u);
;                     const f32x4 gvv = *(const PG8_LAS f32x4*)(gl + bj * HALF + n * 16), bvv = *(const PG8_LAS f32x4*)(gl + 1024 + bj * HALF + n * 16);
;                     const f32x4 xn = (x * rs - ms) * gvv + bvv; const f32x4 y = xn * alpha + acc[AI][bj][m][n] * s;
;                     const unsigned nh0 = cvt_pk_bf16(y[0], y[1]), nh1 = cvt_pk_bf16(y[2], y[3]);
;                     f32x2 w; w.x = __uint_as_float(nh0); w.y = __uint_as_float(nh1); *(f32x2*)(PB + (ro + (unsigned)(bj * HALF + n * 16))) = w;
;                     f32x2 wl; wl.x = __uint_as_float(cvt_pk_bf16(y[0] - __uint_as_float(nh0 << 16), y[1] - __uint_as_float(nh0 & 0xffff0000u))); wl.y = __uint_as_float(cvt_pk_bf16(y[2] - __uint_as_float(nh1 << 16), y[3] - __uint_as_float(nh1 & 0xffff0000u)));
;                     *(f32x2*)((bf16_t*)X + ((unsigned)row * 2048u + 1024u + (unsigned)(col0 + bj * HALF + n * 16))) = wl;
;                     sm += (y[0] + y[1]) + (y[2] + y[3]); sq += (y[0] * y[0] + y[1] * y[1]) + (y[2] * y[2] + y[3] * y[3]); }
	v_pk_fma_f32 v[44:45], v[58:59], v[44:45], v[56:57]
	v_pk_fma_f32 v[42:43], v[48:49], v[42:43], v[54:55]
	v_pk_mul_f32 v[44:45], v[44:45], s[60:61] op_sel_hi:[1,0]
	v_pk_mul_f32 v[42:43], v[42:43], s[60:61] op_sel_hi:[1,0]
	v_pk_fma_f32 v[40:41], s[24:25], v[40:41], v[44:45]
	v_pk_fma_f32 v[38:39], s[10:11], v[38:39], v[42:43]
	v_lshl_add_u64 v[44:45], v[0:1], 1, s[26:27]
	v_cvt_pk_bf16_f32 v42, v38, v39
	v_cvt_pk_bf16_f32 v43, v40, v41
	global_store_dwordx2 v[44:45], v[42:43], off
	v_lshlrev_b32_e32 v0, 16, v42
	v_and_b32_e32 v42, 0xffff0000, v42
	v_sub_f32_e32 v0, v38, v0
	v_sub_f32_e32 v42, v39, v42
	v_cvt_pk_bf16_f32 v42, v0, v42
	v_lshlrev_b32_e32 v0, 16, v43
	v_and_b32_e32 v43, 0xffff0000, v43
	v_sub_f32_e32 v0, v40, v0
	v_sub_f32_e32 v43, v41, v43
	v_cvt_pk_bf16_f32 v43, v0, v43
	global_store_dwordx2 v[46:47], v[42:43], off offset:256
	v_add_f32_e32 v0, v38, v39
	v_add_f32_e32 v42, v40, v41
	v_add_f32_e32 v0, v0, v42
	v_add_f32_e32 v56, v51, v0
	v_mul_f32_e32 v0, v39, v39
	v_fmac_f32_e32 v0, v38, v38
	v_mul_f32_e32 v38, v41, v41
	v_fmac_f32_e32 v38, v40, v40
	v_add_f32_e32 v0, v0, v38
	v_lshlrev_b32_e32 v38, 16, v112
	v_and_b32_e32 v39, 0xffff0000, v112
	v_lshlrev_b32_e32 v40, 16, v114
	v_and_b32_e32 v41, 0xffff0000, v114
	v_pk_add_f32 v[48:49], v[38:39], v[40:41]
	v_lshlrev_b32_e32 v38, 16, v113
	v_and_b32_e32 v39, 0xffff0000, v113
	v_lshlrev_b32_e32 v40, 16, v115
	v_and_b32_e32 v41, 0xffff0000, v115
	v_pk_add_f32 v[54:55], v[38:39], v[40:41]
	ds_read_b128 v[38:41], v179 offset:576
	ds_read_b128 v[42:45], v179 offset:4672
	v_add_f32_e32 v53, v53, v0
	v_pk_fma_f32 v[48:49], v[48:49], v[50:51], v[52:53] op_sel_hi:[1,0,0]
	v_pk_fma_f32 v[50:51], v[54:55], v[50:51], v[52:53] op_sel_hi:[1,0,0]
	v_or_b32_e32 v0, 0x90, v110
	s_waitcnt lgkmcnt(0)
	v_pk_fma_f32 v[40:41], v[50:51], v[40:41], v[44:45]
	v_pk_fma_f32 v[38:39], v[48:49], v[38:39], v[42:43]
	v_pk_mul_f32 v[40:41], v[40:41], s[60:61] op_sel_hi:[1,0]
	v_pk_mul_f32 v[38:39], v[38:39], s[60:61] op_sel_hi:[1,0]
	v_pk_fma_f32 v[36:37], s[24:25], v[36:37], v[40:41]
	v_pk_fma_f32 v[34:35], s[10:11], v[34:35], v[38:39]
	v_lshl_add_u64 v[40:41], v[0:1], 1, s[26:27]
	v_cvt_pk_bf16_f32 v38, v34, v35
	v_cvt_pk_bf16_f32 v39, v36, v37
	global_store_dwordx2 v[40:41], v[38:39], off
	v_lshlrev_b32_e32 v0, 16, v38
	v_and_b32_e32 v38, 0xffff0000, v38
	v_sub_f32_e32 v0, v34, v0
	v_sub_f32_e32 v38, v35, v38
	v_cvt_pk_bf16_f32 v38, v0, v38
	v_lshlrev_b32_e32 v0, 16, v39
	v_and_b32_e32 v39, 0xffff0000, v39
	v_sub_f32_e32 v0, v36, v0
	v_sub_f32_e32 v39, v37, v39
	v_cvt_pk_bf16_f32 v39, v0, v39
	v_add_f32_e32 v0, v34, v35
	v_mul_f32_e32 v35, v35, v35
	global_store_dwordx2 v[46:47], v[38:39], off offset:288
	v_add_f32_e32 v38, v36, v37
	v_fmac_f32_e32 v35, v34, v34
	v_mul_f32_e32 v34, v37, v37
	v_add_f32_e32 v0, v0, v38
	v_fmac_f32_e32 v34, v36, v36
	v_add_f32_e32 v0, v56, v0
	v_add_f32_e32 v34, v35, v34
	v_add_f32_e32 v35, v53, v34
	v_mov_b32_e32 v34, v0
	s_nop 1
	v_permlane16_swap_b32_e32 v0, v34
	v_add_f32_e32 v34, v0, v34
	v_mov_b32_e32 v0, v35
	s_nop 1
	v_permlane16_swap_b32_e32 v35, v0
	v_add_f32_e32 v35, v35, v0
	v_mov_b32_e32 v36, v34
	v_mov_b32_e32 v37, v35
	s_nop 0
	v_permlane32_swap_b32_e32 v34, v36
	v_permlane32_swap_b32_e32 v35, v37
	s_and_saveexec_b64 s[50:51], s[2:3]
	v_pk_add_f32 v[34:35], v[34:35], v[36:37]
	ds_write_b64 v178, v[34:35] offset:512
	s_or_b64 exec, exec, s[50:51]
	v_mov_b32_e32 v0, v108
	s_nop 1
	v_permlane16_swap_b32_e32 v108, v0
	v_add_f32_e32 v35, v108, v0
	v_mov_b32_e32 v0, v109
	s_nop 1
	v_permlane16_swap_b32_e32 v109, v0
	v_add_f32_e32 v34, v109, v0
	v_mov_b32_e32 v37, v35
	v_mov_b32_e32 v36, v34
	s_nop 0
	v_permlane32_swap_b32_e32 v35, v37
	v_permlane32_swap_b32_e32 v34, v36
	v_pk_add_f32 v[34:35], v[34:35], v[36:37]
	v_lshlrev_b32_e32 v36, 16, v104
	v_pk_mul_f32 v[34:35], v[34:35], s[68:69] op_sel_hi:[1,0]
	v_and_b32_e32 v37, 0xffff0000, v104
	v_fma_f32 v0, -v35, v35, v34
	v_add_f32_e32 v0, 0x3727c5ac, v0
	v_lshlrev_b32_e32 v38, 16, v106
	v_and_b32_e32 v39, 0xffff0000, v106
	v_rsq_f32_e32 v34, v0
	v_pk_add_f32 v[46:47], v[36:37], v[38:39]
	v_lshlrev_b32_e32 v36, 16, v105
	v_and_b32_e32 v37, 0xffff0000, v105
	v_lshlrev_b32_e32 v38, 16, v107
	v_and_b32_e32 v39, 0xffff0000, v107
	v_pk_add_f32 v[48:49], v[36:37], v[38:39]
	ds_read_b128 v[38:41], v179
	ds_read_b128 v[42:45], v179 offset:4096
	v_mul_f32_e64 v36, v35, -v34
	v_pk_fma_f32 v[46:47], v[46:47], v[34:35], v[36:37] op_sel_hi:[1,0,0]
	v_pk_fma_f32 v[48:49], v[48:49], v[34:35], v[36:37] op_sel_hi:[1,0,0]
	v_add_u32_e32 v0, v111, v180
	s_waitcnt lgkmcnt(0)
	v_pk_fma_f32 v[38:39], v[38:39], v[46:47], v[42:43]
	v_pk_fma_f32 v[40:41], v[40:41], v[48:49], v[44:45]
	v_pk_mul_f32 v[38:39], v[38:39], s[60:61] op_sel_hi:[1,0]
	v_pk_mul_f32 v[40:41], v[40:41], s[60:61] op_sel_hi:[1,0]
	v_pk_fma_f32 v[38:39], s[10:11], v[30:31], v[38:39]
	v_pk_fma_f32 v[32:33], s[24:25], v[32:33], v[40:41]
	v_cvt_pk_bf16_f32 v30, v38, v39
	s_nop 0
	v_cvt_pk_bf16_f32 v31, v32, v33
	global_store_dwordx2 v[102:103], v[30:31], off
	v_lshlrev_b32_e32 v35, 16, v30
	v_and_b32_e32 v30, 0xffff0000, v30
	v_sub_f32_e32 v30, v39, v30
	v_sub_f32_e32 v35, v38, v35
	v_cvt_pk_bf16_f32 v40, v35, v30
	v_lshlrev_b32_e32 v30, 16, v31
	v_and_b32_e32 v31, 0xffff0000, v31
	v_sub_f32_e32 v30, v32, v30
	v_sub_f32_e32 v31, v33, v31
	v_cvt_pk_bf16_f32 v41, v30, v31
	v_lshl_add_u64 v[30:31], v[0:1], 1, s[12:13]
	v_add_f32_e32 v0, v38, v39
	v_add_f32_e32 v35, v32, v33
	v_add_f32_e32 v0, v0, v35
	v_add_f32_e32 v35, 0, v0
	v_mul_f32_e32 v0, v39, v39
	v_mul_f32_e32 v33, v33, v33
	v_fmac_f32_e32 v0, v38, v38
	v_fmac_f32_e32 v33, v32, v32
	v_add_f32_e32 v37, v0, v33
	v_lshlrev_b32_e32 v32, 16, v98
	v_and_b32_e32 v33, 0xffff0000, v98
	v_lshlrev_b32_e32 v38, 16, v100
	v_and_b32_e32 v39, 0xffff0000, v100
	global_store_dwordx2 v[30:31], v[40:41], off
	v_pk_add_f32 v[32:33], v[32:33], v[38:39]
	v_lshlrev_b32_e32 v38, 16, v99
	v_and_b32_e32 v39, 0xffff0000, v99
	v_lshlrev_b32_e32 v40, 16, v101
	v_and_b32_e32 v41, 0xffff0000, v101
	v_pk_add_f32 v[46:47], v[38:39], v[40:41]
	ds_read_b128 v[38:41], v179 offset:64
	ds_read_b128 v[42:45], v179 offset:4160
	v_pk_fma_f32 v[32:33], v[32:33], v[34:35], v[36:37] op_sel_hi:[1,0,0]
	v_pk_fma_f32 v[46:47], v[46:47], v[34:35], v[36:37] op_sel_hi:[1,0,0]
	v_or_b32_e32 v0, 16, v88
	s_waitcnt lgkmcnt(0)
;     template <int AI, int M0, int NR>
;     __device__ __forceinline__ void batch(const f32x4 (&acc)[2][2][4][2], int row0, int col0, int wr, int wc, int fr, int fq, PG8_LAS float* red, const PG8_LAS float* gl) const {
;     ...
;         for (int mm = 0; mm < NR; ++mm) { const int m = M0 + mm; const int row = row0 + AI * HALF + m * 16;
;             float rs, ms; { f32x2 v = stv[mm]; v.x = xsum_rows(v.x); v.y = xsum_rows(v.y);
;               const float mean = v.x * (1.0f / 1024.0f); const float var = v.y * (1.0f / 1024.0f) - mean * mean; rs = __builtin_amdgcn_rsqf(var + 1e-5f); ms = rs * mean; }
;             const unsigned ro = (unsigned)row * 1024u + (unsigned)col0;
;             float sm = 0.f, sq = 0.f;
; #pragma unroll
;             for (int bj = 0; bj < 2; ++bj)
; #pragma unroll
;                 for (int n = 0; n < 2; ++n) { const unsigned hw0 = __float_as_uint(xh[mm][bj][n].x), hw1 = __float_as_uint(xh[mm][bj][n].y), lw0 = __float_as_uint(xl[mm][bj][n].x), lw1 = __float_as_uint(xl[mm][bj][n].y);
;                     f32x4 x; x[0] = __uint_as_float(hw0 << 16) + __uint_as_float(lw0 << 16); x[1] = __uint_as_float(hw0 & 0xffff0000u) + __uint_as_float(lw0 & 0xffff0000u);
;                     x[2] = __uint_as_float(hw1 << 16) + __uint_as_float(lw1 << 16); x[3] = __uint_as_float(hw1 & 0xffff0000u) + __uint_as_float(lw1 & 0xffff0000u);
;                     const f32x4 gvv = *(const PG8_LAS f32x4*)(gl + bj * HALF + n * 16), bvv = *(const PG8_LAS f32x4*)(gl + 1024 + bj * HALF + n * 16);
;                     const f32x4 xn = (x * rs - ms) * gvv + bvv; const f32x4 y = xn * alpha + acc[AI][bj][m][n] * s;
;                     const unsigned nh0 = cvt_pk_bf16(y[0], y[1]), nh1 = cvt_pk_bf16(y[2], y[3]);
;                     f32x2 w; w.x = __uint_as_float(nh0); w.y = __uint_as_float(nh1); *(f32x2*)(PB + (ro + (unsigned)(bj * HALF + n * 16))) = w;
;                     f32x2 wl; wl.x = __uint_as_float(cvt_pk_bf16(y[0] - __uint_as_float(nh0 << 16), y[1] - __uint_as_float(nh0 & 0xffff0000u))); wl.y = __uint_as_float(cvt_pk_bf16(y[2] - __uint_as_float(nh1 << 16), y[3] - __uint_as_float(nh1 & 0xffff0000u)));
;                     *(f32x2*)((bf16_t*)X + ((unsigned)row * 2048u + 1024u + (unsigned)(col0 + bj * HALF + n * 16))) = wl;
;                     sm += (y[0] + y[1]) + (y[2] + y[3]); sq += (y[0] * y[0] + y[1] * y[1]) + (y[2] * y[2] + y[3] * y[3]); }
	v_pk_fma_f32 v[40:41], v[40:41], v[46:47], v[44:45]
	v_pk_fma_f32 v[32:33], v[38:39], v[32:33], v[42:43]
	v_pk_mul_f32 v[38:39], v[40:41], s[60:61] op_sel_hi:[1,0]
	v_pk_mul_f32 v[32:33], v[32:33], s[60:61] op_sel_hi:[1,0]
	v_pk_fma_f32 v[28:29], s[24:25], v[28:29], v[38:39]
	v_pk_fma_f32 v[26:27], s[10:11], v[26:27], v[32:33]
	v_lshl_add_u64 v[38:39], v[0:1], 1, s[26:27]
	v_cvt_pk_bf16_f32 v32, v26, v27
	v_cvt_pk_bf16_f32 v33, v28, v29
	global_store_dwordx2 v[38:39], v[32:33], off
	v_lshlrev_b32_e32 v0, 16, v32
	v_and_b32_e32 v32, 0xffff0000, v32
	v_sub_f32_e32 v0, v26, v0
	v_sub_f32_e32 v32, v27, v32
	v_cvt_pk_bf16_f32 v32, v0, v32
	v_lshlrev_b32_e32 v0, 16, v33
	v_and_b32_e32 v33, 0xffff0000, v33
	v_sub_f32_e32 v0, v28, v0
	v_sub_f32_e32 v33, v29, v33
	v_cvt_pk_bf16_f32 v33, v0, v33
	global_store_dwordx2 v[30:31], v[32:33], off offset:32
	v_add_f32_e32 v0, v26, v27
	v_add_f32_e32 v32, v28, v29
	v_add_f32_e32 v0, v0, v32
	v_add_f32_e32 v35, v0, v35
	v_mul_f32_e32 v0, v27, v27
	v_fmac_f32_e32 v0, v26, v26
	v_mul_f32_e32 v26, v29, v29
	v_fmac_f32_e32 v26, v28, v28
	v_add_f32_e32 v0, v0, v26
	v_lshlrev_b32_e32 v26, 16, v94
	v_and_b32_e32 v27, 0xffff0000, v94
	v_lshlrev_b32_e32 v28, 16, v96
	v_and_b32_e32 v29, 0xffff0000, v96
	v_pk_add_f32 v[32:33], v[26:27], v[28:29]
	v_lshlrev_b32_e32 v26, 16, v95
	v_and_b32_e32 v27, 0xffff0000, v95
	v_lshlrev_b32_e32 v28, 16, v97
	v_and_b32_e32 v29, 0xffff0000, v97
	v_pk_add_f32 v[42:43], v[26:27], v[28:29]
	ds_read_b128 v[26:29], v179 offset:512
	ds_read_b128 v[38:41], v179 offset:4608
	v_add_f32_e32 v37, v37, v0
	v_pk_fma_f32 v[32:33], v[32:33], v[34:35], v[36:37] op_sel_hi:[1,0,0]
	v_pk_fma_f32 v[42:43], v[42:43], v[34:35], v[36:37] op_sel_hi:[1,0,0]
	v_or_b32_e32 v0, 0x80, v88
	s_waitcnt lgkmcnt(0)
	v_pk_fma_f32 v[28:29], v[42:43], v[28:29], v[40:41]
	v_pk_fma_f32 v[26:27], v[32:33], v[26:27], v[38:39]
	v_pk_mul_f32 v[28:29], v[28:29], s[60:61] op_sel_hi:[1,0]
	v_pk_mul_f32 v[26:27], v[26:27], s[60:61] op_sel_hi:[1,0]
	v_pk_fma_f32 v[24:25], s[24:25], v[24:25], v[28:29]
	v_pk_fma_f32 v[22:23], s[10:11], v[22:23], v[26:27]
	v_lshl_add_u64 v[28:29], v[0:1], 1, s[26:27]
	v_cvt_pk_bf16_f32 v26, v22, v23
	v_cvt_pk_bf16_f32 v27, v24, v25
	global_store_dwordx2 v[28:29], v[26:27], off
	v_lshlrev_b32_e32 v0, 16, v26
	v_and_b32_e32 v26, 0xffff0000, v26
	v_sub_f32_e32 v0, v22, v0
	v_sub_f32_e32 v26, v23, v26
	v_cvt_pk_bf16_f32 v26, v0, v26
	v_lshlrev_b32_e32 v0, 16, v27
	v_and_b32_e32 v27, 0xffff0000, v27
	v_sub_f32_e32 v0, v24, v0
	v_sub_f32_e32 v27, v25, v27
	v_cvt_pk_bf16_f32 v27, v0, v27
	global_store_dwordx2 v[30:31], v[26:27], off offset:256
	v_add_f32_e32 v0, v22, v23
	v_add_f32_e32 v26, v24, v25
	v_add_f32_e32 v0, v0, v26
	v_add_f32_e32 v40, v35, v0
	v_mul_f32_e32 v0, v23, v23
	v_fmac_f32_e32 v0, v22, v22
	v_mul_f32_e32 v22, v25, v25
	v_fmac_f32_e32 v22, v24, v24
	v_add_f32_e32 v0, v0, v22
	v_lshlrev_b32_e32 v22, 16, v90
	v_and_b32_e32 v23, 0xffff0000, v90
	v_lshlrev_b32_e32 v24, 16, v92
	v_and_b32_e32 v25, 0xffff0000, v92
	v_pk_add_f32 v[32:33], v[22:23], v[24:25]
	v_lshlrev_b32_e32 v22, 16, v91
	v_and_b32_e32 v23, 0xffff0000, v91
	v_lshlrev_b32_e32 v24, 16, v93
	v_and_b32_e32 v25, 0xffff0000, v93
	v_pk_add_f32 v[38:39], v[22:23], v[24:25]
	ds_read_b128 v[22:25], v179 offset:576
	ds_read_b128 v[26:29], v179 offset:4672
	v_add_f32_e32 v37, v37, v0
	v_pk_fma_f32 v[32:33], v[32:33], v[34:35], v[36:37] op_sel_hi:[1,0,0]
	v_pk_fma_f32 v[34:35], v[38:39], v[34:35], v[36:37] op_sel_hi:[1,0,0]
	v_or_b32_e32 v0, 0x90, v88
	s_waitcnt lgkmcnt(0)
	v_pk_fma_f32 v[24:25], v[34:35], v[24:25], v[28:29]
	v_pk_fma_f32 v[22:23], v[32:33], v[22:23], v[26:27]
	v_pk_mul_f32 v[24:25], v[24:25], s[60:61] op_sel_hi:[1,0]
	v_pk_mul_f32 v[22:23], v[22:23], s[60:61] op_sel_hi:[1,0]
	v_pk_fma_f32 v[20:21], s[24:25], v[20:21], v[24:25]
	v_pk_fma_f32 v[18:19], s[10:11], v[18:19], v[22:23]
	v_lshl_add_u64 v[24:25], v[0:1], 1, s[26:27]
	v_cvt_pk_bf16_f32 v22, v18, v19
	v_cvt_pk_bf16_f32 v23, v20, v21
	global_store_dwordx2 v[24:25], v[22:23], off
	v_lshlrev_b32_e32 v0, 16, v22
	v_and_b32_e32 v22, 0xffff0000, v22
	v_sub_f32_e32 v0, v18, v0
	v_sub_f32_e32 v22, v19, v22
	v_cvt_pk_bf16_f32 v22, v0, v22
	v_lshlrev_b32_e32 v0, 16, v23
	v_and_b32_e32 v23, 0xffff0000, v23
	v_sub_f32_e32 v0, v20, v0
	v_sub_f32_e32 v23, v21, v23
	v_cvt_pk_bf16_f32 v23, v0, v23
	v_add_f32_e32 v0, v18, v19
	v_mul_f32_e32 v19, v19, v19
	global_store_dwordx2 v[30:31], v[22:23], off offset:288
	v_add_f32_e32 v22, v20, v21
	v_fmac_f32_e32 v19, v18, v18
	v_mul_f32_e32 v18, v21, v21
	v_add_f32_e32 v0, v0, v22
	v_fmac_f32_e32 v18, v20, v20
	v_add_f32_e32 v0, v40, v0
	v_add_f32_e32 v18, v19, v18
	v_add_f32_e32 v19, v37, v18
	v_mov_b32_e32 v18, v0
	s_nop 1
	v_permlane16_swap_b32_e32 v0, v18
	v_add_f32_e32 v18, v0, v18
	v_mov_b32_e32 v0, v19
	s_nop 1
	v_permlane16_swap_b32_e32 v19, v0
	v_add_f32_e32 v19, v19, v0
	v_mov_b32_e32 v20, v18
	v_mov_b32_e32 v21, v19
	s_nop 0
	v_permlane32_swap_b32_e32 v18, v20
	v_permlane32_swap_b32_e32 v19, v21
	s_and_saveexec_b64 s[50:51], s[2:3]
	v_pk_add_f32 v[18:19], v[18:19], v[20:21]
	ds_write_b64 v178, v[18:19] offset:1024
	s_or_b64 exec, exec, s[50:51]
	v_mov_b32_e32 v0, v86
	s_nop 1
	v_permlane16_swap_b32_e32 v86, v0
	v_add_f32_e32 v19, v86, v0
	v_mov_b32_e32 v0, v87
	s_nop 1
	v_permlane16_swap_b32_e32 v87, v0
	v_add_f32_e32 v18, v87, v0
	v_mov_b32_e32 v21, v19
	v_mov_b32_e32 v20, v18
	s_nop 0
	v_permlane32_swap_b32_e32 v19, v21
	v_permlane32_swap_b32_e32 v18, v20
	v_pk_add_f32 v[18:19], v[18:19], v[20:21]
	s_waitcnt vmcnt(0)
;     template <int AI, int M0, int NR>
;     __device__ __forceinline__ void batch(const f32x4 (&acc)[2][2][4][2], int row0, int col0, int wr, int wc, int fr, int fq, PG8_LAS float* red, const PG8_LAS float* gl) const {
;     ...
;         for (int mm = 0; mm < NR; ++mm) { const int m = M0 + mm; const int row = row0 + AI * HALF + m * 16;
;             float rs, ms; { f32x2 v = stv[mm]; v.x = xsum_rows(v.x); v.y = xsum_rows(v.y);
;               const float mean = v.x * (1.0f / 1024.0f); const float var = v.y * (1.0f / 1024.0f) - mean * mean; rs = __builtin_amdgcn_rsqf(var + 1e-5f); ms = rs * mean; }
;             const unsigned ro = (unsigned)row * 1024u + (unsigned)col0;
;             float sm = 0.f, sq = 0.f;
; #pragma unroll
;             for (int bj = 0; bj < 2; ++bj)
; #pragma unroll
;                 for (int n = 0; n < 2; ++n) { const unsigned hw0 = __float_as_uint(xh[mm][bj][n].x), hw1 = __float_as_uint(xh[mm][bj][n].y), lw0 = __float_as_uint(xl[mm][bj][n].x), lw1 = __float_as_uint(xl[mm][bj][n].y);
;                     f32x4 x; x[0] = __uint_as_float(hw0 << 16) + __uint_as_float(lw0 << 16); x[1] = __uint_as_float(hw0 & 0xffff0000u) + __uint_as_float(lw0 & 0xffff0000u);
;                     x[2] = __uint_as_float(hw1 << 16) + __uint_as_float(lw1 << 16); x[3] = __uint_as_float(hw1 & 0xffff0000u) + __uint_as_float(lw1 & 0xffff0000u);
;                     const f32x4 gvv = *(const PG8_LAS f32x4*)(gl + bj * HALF + n * 16), bvv = *(const PG8_LAS f32x4*)(gl + 1024 + bj * HALF + n * 16);
;                     const f32x4 xn = (x * rs - ms) * gvv + bvv; const f32x4 y = xn * alpha + acc[AI][bj][m][n] * s;
;                     const unsigned nh0 = cvt_pk_bf16(y[0], y[1]), nh1 = cvt_pk_bf16(y[2], y[3]);
;                     f32x2 w; w.x = __uint_as_float(nh0); w.y = __uint_as_float(nh1); *(f32x2*)(PB + (ro + (unsigned)(bj * HALF + n * 16))) = w;
;                     f32x2 wl; wl.x = __uint_as_float(cvt_pk_bf16(y[0] - __uint_as_float(nh0 << 16), y[1] - __uint_as_float(nh0 & 0xffff0000u))); wl.y = __uint_as_float(cvt_pk_bf16(y[2] - __uint_as_float(nh1 << 16), y[3] - __uint_as_float(nh1 & 0xffff0000u)));
;                     *(f32x2*)((bf16_t*)X + ((unsigned)row * 2048u + 1024u + (unsigned)(col0 + bj * HALF + n * 16))) = wl;
;                     sm += (y[0] + y[1]) + (y[2] + y[3]); sq += (y[0] * y[0] + y[1] * y[1]) + (y[2] * y[2] + y[3] * y[3]); }
	v_lshlrev_b32_e32 v20, 16, v82
	v_pk_mul_f32 v[18:19], v[18:19], s[68:69] op_sel_hi:[1,0]
	v_and_b32_e32 v21, 0xffff0000, v82
	v_fma_f32 v0, -v19, v19, v18
	v_add_f32_e32 v0, 0x3727c5ac, v0
	v_lshlrev_b32_e32 v22, 16, v84
	v_and_b32_e32 v23, 0xffff0000, v84
	v_rsq_f32_e32 v18, v0
	v_pk_add_f32 v[30:31], v[20:21], v[22:23]
	v_lshlrev_b32_e32 v20, 16, v83
	v_and_b32_e32 v21, 0xffff0000, v83
	v_lshlrev_b32_e32 v22, 16, v85
	v_and_b32_e32 v23, 0xffff0000, v85
	v_pk_add_f32 v[32:33], v[20:21], v[22:23]
	ds_read_b128 v[22:25], v179
	ds_read_b128 v[26:29], v179 offset:4096
	v_mul_f32_e64 v20, v19, -v18
	v_pk_fma_f32 v[30:31], v[30:31], v[18:19], v[20:21] op_sel_hi:[1,0,0]
	v_pk_fma_f32 v[32:33], v[32:33], v[18:19], v[20:21] op_sel_hi:[1,0,0]
	v_add_u32_e32 v0, v89, v180
	s_waitcnt lgkmcnt(0)
	v_pk_fma_f32 v[22:23], v[22:23], v[30:31], v[26:27]
	v_pk_fma_f32 v[24:25], v[24:25], v[32:33], v[28:29]
	v_pk_mul_f32 v[22:23], v[22:23], s[60:61] op_sel_hi:[1,0]
	v_pk_mul_f32 v[24:25], v[24:25], s[60:61] op_sel_hi:[1,0]
	v_pk_fma_f32 v[22:23], s[10:11], v[14:15], v[22:23]
	v_pk_fma_f32 v[16:17], s[24:25], v[16:17], v[24:25]
	v_cvt_pk_bf16_f32 v14, v22, v23
	s_nop 0
	v_cvt_pk_bf16_f32 v15, v16, v17
	global_store_dwordx2 v[80:81], v[14:15], off
	v_lshlrev_b32_e32 v19, 16, v14
	v_and_b32_e32 v14, 0xffff0000, v14
	v_sub_f32_e32 v14, v23, v14
	v_sub_f32_e32 v19, v22, v19
	v_cvt_pk_bf16_f32 v24, v19, v14
	v_lshlrev_b32_e32 v14, 16, v15
	v_and_b32_e32 v15, 0xffff0000, v15
	v_sub_f32_e32 v14, v16, v14
	v_sub_f32_e32 v15, v17, v15
	v_cvt_pk_bf16_f32 v25, v14, v15
	v_lshl_add_u64 v[14:15], v[0:1], 1, s[12:13]
	v_add_f32_e32 v0, v22, v23
	v_add_f32_e32 v19, v16, v17
	v_add_f32_e32 v0, v0, v19
	v_add_f32_e32 v19, 0, v0
	v_mul_f32_e32 v0, v23, v23
	v_mul_f32_e32 v17, v17, v17
	v_fmac_f32_e32 v0, v22, v22
	v_fmac_f32_e32 v17, v16, v16
	v_add_f32_e32 v21, v0, v17
	v_lshlrev_b32_e32 v16, 16, v76
	v_and_b32_e32 v17, 0xffff0000, v76
	v_lshlrev_b32_e32 v22, 16, v78
	v_and_b32_e32 v23, 0xffff0000, v78
	global_store_dwordx2 v[14:15], v[24:25], off
	v_pk_add_f32 v[16:17], v[16:17], v[22:23]
	v_lshlrev_b32_e32 v22, 16, v77
	v_and_b32_e32 v23, 0xffff0000, v77
	v_lshlrev_b32_e32 v24, 16, v79
	v_and_b32_e32 v25, 0xffff0000, v79
	v_pk_add_f32 v[30:31], v[22:23], v[24:25]
	ds_read_b128 v[22:25], v179 offset:64
	ds_read_b128 v[26:29], v179 offset:4160
	v_pk_fma_f32 v[16:17], v[16:17], v[18:19], v[20:21] op_sel_hi:[1,0,0]
	v_pk_fma_f32 v[30:31], v[30:31], v[18:19], v[20:21] op_sel_hi:[1,0,0]
	v_or_b32_e32 v0, 16, v66
	s_waitcnt lgkmcnt(0)
	v_pk_fma_f32 v[24:25], v[24:25], v[30:31], v[28:29]
	v_pk_fma_f32 v[16:17], v[22:23], v[16:17], v[26:27]
	v_pk_mul_f32 v[22:23], v[24:25], s[60:61] op_sel_hi:[1,0]
	v_pk_mul_f32 v[16:17], v[16:17], s[60:61] op_sel_hi:[1,0]
	v_pk_fma_f32 v[12:13], s[24:25], v[12:13], v[22:23]
	v_pk_fma_f32 v[10:11], s[10:11], v[10:11], v[16:17]
	v_lshl_add_u64 v[22:23], v[0:1], 1, s[26:27]
	v_cvt_pk_bf16_f32 v16, v10, v11
	v_cvt_pk_bf16_f32 v17, v12, v13
	global_store_dwordx2 v[22:23], v[16:17], off
	v_lshlrev_b32_e32 v0, 16, v16
	v_and_b32_e32 v16, 0xffff0000, v16
	v_sub_f32_e32 v0, v10, v0
	v_sub_f32_e32 v16, v11, v16
	v_cvt_pk_bf16_f32 v16, v0, v16
	v_lshlrev_b32_e32 v0, 16, v17
	v_and_b32_e32 v17, 0xffff0000, v17
	v_sub_f32_e32 v0, v12, v0
	v_sub_f32_e32 v17, v13, v17
	v_cvt_pk_bf16_f32 v17, v0, v17
	global_store_dwordx2 v[14:15], v[16:17], off offset:32
	v_add_f32_e32 v0, v10, v11
	v_add_f32_e32 v16, v12, v13
	v_add_f32_e32 v0, v0, v16
	v_add_f32_e32 v19, v0, v19
	v_mul_f32_e32 v0, v11, v11
	v_fmac_f32_e32 v0, v10, v10
	v_mul_f32_e32 v10, v13, v13
	v_fmac_f32_e32 v10, v12, v12
	v_add_f32_e32 v0, v0, v10
	v_lshlrev_b32_e32 v10, 16, v72
	v_and_b32_e32 v11, 0xffff0000, v72
	v_lshlrev_b32_e32 v12, 16, v74
	v_and_b32_e32 v13, 0xffff0000, v74
	v_pk_add_f32 v[16:17], v[10:11], v[12:13]
	v_lshlrev_b32_e32 v10, 16, v73
	v_and_b32_e32 v11, 0xffff0000, v73
	v_lshlrev_b32_e32 v12, 16, v75
	v_and_b32_e32 v13, 0xffff0000, v75
	v_pk_add_f32 v[26:27], v[10:11], v[12:13]
	ds_read_b128 v[10:13], v179 offset:512
	ds_read_b128 v[22:25], v179 offset:4608
	v_add_f32_e32 v21, v21, v0
	v_pk_fma_f32 v[16:17], v[16:17], v[18:19], v[20:21] op_sel_hi:[1,0,0]
	v_pk_fma_f32 v[26:27], v[26:27], v[18:19], v[20:21] op_sel_hi:[1,0,0]
	v_or_b32_e32 v0, 0x80, v66
	s_waitcnt lgkmcnt(0)
; #define PG8_LAS __attribute__((address_space(3)))
;     template <int AI, int M0, int NR>
;     __device__ __forceinline__ void batch(const f32x4 (&acc)[2][2][4][2], int row0, int col0, int wr, int wc, int fr, int fq, PG8_LAS float* red, const PG8_LAS float* gl) const {
;     ...
;                 for (int n = 0; n < 2; ++n) { const unsigned hw0 = __float_as_uint(xh[mm][bj][n].x), hw1 = __float_as_uint(xh[mm][bj][n].y), lw0 = __float_as_uint(xl[mm][bj][n].x), lw1 = __float_as_uint(xl[mm][bj][n].y);
;                     f32x4 x; x[0] = __uint_as_float(hw0 << 16) + __uint_as_float(lw0 << 16); x[1] = __uint_as_float(hw0 & 0xffff0000u) + __uint_as_float(lw0 & 0xffff0000u);
;                     x[2] = __uint_as_float(hw1 << 16) + __uint_as_float(lw1 << 16); x[3] = __uint_as_float(hw1 & 0xffff0000u) + __uint_as_float(lw1 & 0xffff0000u);
;                     const f32x4 gvv = *(const PG8_LAS f32x4*)(gl + bj * HALF + n * 16), bvv = *(const PG8_LAS f32x4*)(gl + 1024 + bj * HALF + n * 16);
;                     const f32x4 xn = (x * rs - ms) * gvv + bvv; const f32x4 y = xn * alpha + acc[AI][bj][m][n] * s;
;                     const unsigned nh0 = cvt_pk_bf16(y[0], y[1]), nh1 = cvt_pk_bf16(y[2], y[3]);
;                     f32x2 w; w.x = __uint_as_float(nh0); w.y = __uint_as_float(nh1); *(f32x2*)(PB + (ro + (unsigned)(bj * HALF + n * 16))) = w;
;                     f32x2 wl; wl.x = __uint_as_float(cvt_pk_bf16(y[0] - __uint_as_float(nh0 << 16), y[1] - __uint_as_float(nh0 & 0xffff0000u))); wl.y = __uint_as_float(cvt_pk_bf16(y[2] - __uint_as_float(nh1 << 16), y[3] - __uint_as_float(nh1 & 0xffff0000u)));
;                     *(f32x2*)((bf16_t*)X + ((unsigned)row * 2048u + 1024u + (unsigned)(col0 + bj * HALF + n * 16))) = wl;
;                     sm += (y[0] + y[1]) + (y[2] + y[3]); sq += (y[0] * y[0] + y[1] * y[1]) + (y[2] * y[2] + y[3] * y[3]); }
;             sm = xsum_rows(sm); sq = xsum_rows(sq);
;             if (fq == 0) { f32x2 pr; pr.x = sm; pr.y = sq; *(PG8_LAS f32x2*)(red + ((AI * HALF + wr * 64 + m * 16 + fr) * 4 + wc) * 2) = pr; }
;         }
;         asm volatile("" ::: "memory");
;     }
;     __device__ __forceinline__ void operator()(const f32x4 (&acc)[2][2][4][2], const Unit& u, int wr, int wc, int fr, int fq, PG8_LAS unsigned char* ldsb) const {
;         const int row0 = u.pm * BM + wr * 64 + fr; const int col0 = u.pn * BM + wc * 32 + 4 * fq;
	v_pk_fma_f32 v[12:13], v[26:27], v[12:13], v[24:25]
	v_pk_fma_f32 v[10:11], v[16:17], v[10:11], v[22:23]
	v_pk_mul_f32 v[12:13], v[12:13], s[60:61] op_sel_hi:[1,0]
	v_pk_mul_f32 v[10:11], v[10:11], s[60:61] op_sel_hi:[1,0]
	v_pk_fma_f32 v[8:9], s[24:25], v[8:9], v[12:13]
	v_pk_fma_f32 v[6:7], s[10:11], v[6:7], v[10:11]
	v_lshl_add_u64 v[12:13], v[0:1], 1, s[26:27]
	v_cvt_pk_bf16_f32 v10, v6, v7
	v_cvt_pk_bf16_f32 v11, v8, v9
	global_store_dwordx2 v[12:13], v[10:11], off
	v_lshlrev_b32_e32 v0, 16, v10
	v_and_b32_e32 v10, 0xffff0000, v10
	v_sub_f32_e32 v0, v6, v0
	v_sub_f32_e32 v10, v7, v10
	v_cvt_pk_bf16_f32 v10, v0, v10
	v_lshlrev_b32_e32 v0, 16, v11
	v_and_b32_e32 v11, 0xffff0000, v11
	v_sub_f32_e32 v0, v8, v0
	v_sub_f32_e32 v11, v9, v11
	v_cvt_pk_bf16_f32 v11, v0, v11
	global_store_dwordx2 v[14:15], v[10:11], off offset:256
	v_add_f32_e32 v0, v6, v7
	v_add_f32_e32 v10, v8, v9
	v_add_f32_e32 v0, v0, v10
	v_add_f32_e32 v24, v19, v0
	v_mul_f32_e32 v0, v7, v7
	v_fmac_f32_e32 v0, v6, v6
	v_mul_f32_e32 v6, v9, v9
	v_fmac_f32_e32 v6, v8, v8
	v_add_f32_e32 v0, v0, v6
	v_lshlrev_b32_e32 v6, 16, v68
	v_and_b32_e32 v7, 0xffff0000, v68
	v_lshlrev_b32_e32 v8, 16, v70
	v_and_b32_e32 v9, 0xffff0000, v70
	v_pk_add_f32 v[16:17], v[6:7], v[8:9]
	v_lshlrev_b32_e32 v6, 16, v69
	v_and_b32_e32 v7, 0xffff0000, v69
	v_lshlrev_b32_e32 v8, 16, v71
	v_and_b32_e32 v9, 0xffff0000, v71
	v_pk_add_f32 v[22:23], v[6:7], v[8:9]
	ds_read_b128 v[6:9], v179 offset:576
	ds_read_b128 v[10:13], v179 offset:4672
	v_add_f32_e32 v21, v21, v0
	v_pk_fma_f32 v[16:17], v[16:17], v[18:19], v[20:21] op_sel_hi:[1,0,0]
	v_pk_fma_f32 v[18:19], v[22:23], v[18:19], v[20:21] op_sel_hi:[1,0,0]
	v_or_b32_e32 v0, 0x90, v66
	s_waitcnt lgkmcnt(0)
	v_pk_fma_f32 v[8:9], v[18:19], v[8:9], v[12:13]
	v_pk_fma_f32 v[6:7], v[16:17], v[6:7], v[10:11]
	v_pk_mul_f32 v[8:9], v[8:9], s[60:61] op_sel_hi:[1,0]
	v_pk_mul_f32 v[6:7], v[6:7], s[60:61] op_sel_hi:[1,0]
	v_pk_fma_f32 v[4:5], s[24:25], v[4:5], v[8:9]
	v_pk_fma_f32 v[2:3], s[10:11], v[2:3], v[6:7]
	v_lshl_add_u64 v[8:9], v[0:1], 1, s[26:27]
	v_cvt_pk_bf16_f32 v6, v2, v3
	v_cvt_pk_bf16_f32 v7, v4, v5
	global_store_dwordx2 v[8:9], v[6:7], off
	v_lshlrev_b32_e32 v0, 16, v6
	v_and_b32_e32 v6, 0xffff0000, v6
	v_sub_f32_e32 v0, v2, v0
	v_sub_f32_e32 v6, v3, v6
	v_cvt_pk_bf16_f32 v6, v0, v6
	v_lshlrev_b32_e32 v0, 16, v7
	v_and_b32_e32 v7, 0xffff0000, v7
	v_sub_f32_e32 v0, v4, v0
	v_sub_f32_e32 v7, v5, v7
	v_cvt_pk_bf16_f32 v7, v0, v7
	v_add_f32_e32 v0, v2, v3
	v_mul_f32_e32 v3, v3, v3
	global_store_dwordx2 v[14:15], v[6:7], off offset:288
	v_add_f32_e32 v6, v4, v5
	v_fmac_f32_e32 v3, v2, v2
	v_mul_f32_e32 v2, v5, v5
	v_add_f32_e32 v0, v0, v6
	v_fmac_f32_e32 v2, v4, v4
	v_add_f32_e32 v0, v24, v0
	v_add_f32_e32 v2, v3, v2
	v_add_f32_e32 v3, v21, v2
	v_mov_b32_e32 v2, v0
	s_nop 1
	v_permlane16_swap_b32_e32 v0, v2
	v_add_f32_e32 v2, v0, v2
	v_mov_b32_e32 v0, v3
	s_nop 1
	v_permlane16_swap_b32_e32 v3, v0
	v_add_f32_e32 v3, v3, v0
	v_mov_b32_e32 v4, v2
	v_mov_b32_e32 v5, v3
	s_nop 0
	v_permlane32_swap_b32_e32 v2, v4
	v_permlane32_swap_b32_e32 v3, v5
	s_and_saveexec_b64 s[50:51], s[2:3]
	v_pk_add_f32 v[2:3], v[2:3], v[4:5]
	ds_write_b64 v178, v[2:3] offset:1536
	s_or_b64 exec, exec, s[50:51]
	s_waitcnt lgkmcnt(0)
	s_barrier
	s_and_saveexec_b64 s[50:51], s[4:5]
	s_cbranch_execz .LBB0_1213
	ds_read_b128 v[2:5], v177
	ds_read_b128 v[6:9], v177 offset:16
	s_waitcnt lgkmcnt(0)
	v_pk_add_f32 v[2:3], v[2:3], v[4:5]
	v_pk_add_f32 v[4:5], v[6:7], v[8:9]
	s_nop 0
	v_pk_add_f32 v[2:3], v[2:3], v[4:5]
	v_add_u32_e32 v4, s52, v175
	v_ashrrev_i32_e32 v5, 31, v4
	v_lshlrev_b64 v[4:5], 5, v[4:5]
	s_lshl_b32 s52, s40, 1
	v_lshl_add_u64 v[4:5], s[30:31], 0, v[4:5]
	s_ashr_i32 s53, s52, 31
	v_lshl_add_u64 v[4:5], s[52:53], 2, v[4:5]
	global_store_dwordx2 v[4:5], v[2:3], off

; __device__ __forceinline__ float bflo(unsigned w) { return __uint_as_float(w << 16); }
; __device__ __forceinline__ float bfhi(unsigned w) { return __uint_as_float(w & 0xffff0000u); }
; __global__ void __launch_bounds__(512, 2) mega_fwd(Params P) {
;     ...
;                 for (int mrow0 = gw; mrow0 < T_TOK; mrow0 += 2 * NGW) {
;                     f32x4 v[2][4];
; #pragma unroll
;                     for (int q = 0; q < 2; ++q) { const int mrow = (mrow0 + q * NGW < T_TOK) ? mrow0 + q * NGW : mrow0;
; #pragma unroll
;                         for (int j = 0; j < 4; ++j) { const unsigned long long hw = ((const unsigned long long*)(XB + (size_t)mrow * 1024))[lane + 64 * j], lw = ((const unsigned long long*)(X + (size_t)mrow * 1024))[256 + lane + 64 * j];
;                             const unsigned h0 = (unsigned)hw, h1 = (unsigned)(hw >> 32), l0 = (unsigned)lw, l1 = (unsigned)(lw >> 32);
;                             v[q][j][0] = bflo(h0) + bflo(l0); v[q][j][1] = bfhi(h0) + bfhi(l0); v[q][j][2] = bflo(h1) + bflo(l1); v[q][j][3] = bfhi(h1) + bfhi(l1); } }
; #pragma unroll
;                     for (int q = 0; q < 2; ++q) { const int mrow = mrow0 + q * NGW; if (mrow < T_TOK) {
;                         f32x4* xr = (f32x4*)(X + (size_t)mrow * 1024) + lane; float s = 0.f;
; #pragma unroll
;                         for (int j = 0; j < 4; ++j) s += (v[q][j][0] + v[q][j][1]) + (v[q][j][2] + v[q][j][3]);
;                         const float mean = wave_sum(s) * (1.0f / 1024.0f); float s2 = 0.f;
; #pragma unroll
;                         for (int j = 0; j < 4; ++j) { v[q][j] = v[q][j] - mean; s2 += (v[q][j][0] * v[q][j][0] + v[q][j][1] * v[q][j][1]) + (v[q][j][2] * v[q][j][2] + v[q][j][3] * v[q][j][3]); }
;                         const float rstd = rsqrtf(wave_sum(s2) * (1.0f / 1024.0f) + LN_EPS);
.LBB0_1260:
	s_add_i32 s3, s1, s2
	s_cmp_lt_i32 s3, 0x10000
	s_cselect_b32 s14, s3, s2
	s_ashr_i32 s15, s14, 31
	s_lshl_b64 s[16:17], s[14:15], 11
	s_lshl_b64 s[14:15], s[14:15], 12
	s_cmp_gt_i32 s3, 0xffff
	v_lshl_add_u64 v[58:59], s[10:11], 0, v[34:35]
	s_mov_b32 s3, 0xd800000
	v_add_co_u32_e32 v70, vcc, s3, v58
	v_lshl_add_u64 v[54:55], v[36:37], 0, s[16:17]
	v_lshl_add_u64 v[56:57], v[38:39], 0, s[14:15]
	v_addc_co_u32_e32 v71, vcc, 0, v59, vcc
	v_lshl_add_u64 v[72:73], s[8:9], 0, v[34:35]
	global_load_dwordx2 v[42:43], v[54:55], off
	global_load_dwordx2 v[44:45], v[56:57], off offset:2048
	global_load_dwordx2 v[46:47], v[54:55], off offset:512
	global_load_dwordx2 v[48:49], v[56:57], off offset:2560
	global_load_dwordx2 v[50:51], v[54:55], off offset:1024
	global_load_dwordx2 v[52:53], v[56:57], off offset:3072
	s_nop 0
	global_load_dwordx2 v[54:55], v[54:55], off offset:1536
	s_nop 0
	global_load_dwordx2 v[56:57], v[56:57], off offset:3584
	s_nop 0
	global_load_dwordx2 v[60:61], v[70:71], off offset:1536
	global_load_dwordx2 v[64:65], v[70:71], off offset:1024
	global_load_dwordx2 v[68:69], v[70:71], off offset:512
	global_load_dwordx2 v[62:63], v[72:73], off offset:3584
	global_load_dwordx2 v[66:67], v[72:73], off offset:3072
	global_load_dwordx2 v[74:75], v[72:73], off offset:2560
	s_waitcnt vmcnt(0) lgkmcnt(0)
	v_lshlrev_b32_e32 v58, 16, v60
	global_load_dwordx2 v[72:73], v[72:73], off offset:2048
	v_lshlrev_b32_e32 v59, 16, v62
	v_add_f32_e32 v58, v58, v59
	v_and_b32_e32 v59, 0xffff0000, v60
	v_and_b32_e32 v60, 0xffff0000, v62
	v_add_f32_e32 v59, v59, v60
	v_lshlrev_b32_e32 v60, 16, v61
	v_lshlrev_b32_e32 v62, 16, v63
	v_add_f32_e32 v60, v60, v62
	v_and_b32_e32 v61, 0xffff0000, v61
	v_and_b32_e32 v62, 0xffff0000, v63
	v_add_f32_e32 v61, v61, v62
	v_lshlrev_b32_e32 v62, 16, v64
	v_lshlrev_b32_e32 v63, 16, v66
	v_add_f32_e32 v62, v62, v63
	v_and_b32_e32 v63, 0xffff0000, v64
	v_and_b32_e32 v64, 0xffff0000, v66
	v_add_f32_e32 v63, v63, v64
	v_lshlrev_b32_e32 v64, 16, v65
	v_lshlrev_b32_e32 v66, 16, v67
	v_add_f32_e32 v64, v64, v66
	v_and_b32_e32 v65, 0xffff0000, v65
	v_and_b32_e32 v66, 0xffff0000, v67
	v_add_f32_e32 v65, v65, v66
	v_lshlrev_b32_e32 v66, 16, v68
	v_lshlrev_b32_e32 v67, 16, v74
	v_add_f32_e32 v66, v66, v67
	v_and_b32_e32 v67, 0xffff0000, v68
	v_and_b32_e32 v68, 0xffff0000, v74
	v_add_f32_e32 v67, v67, v68
	v_lshlrev_b32_e32 v68, 16, v69
	v_lshlrev_b32_e32 v74, 16, v75
	v_add_f32_e32 v68, v68, v74
	v_and_b32_e32 v69, 0xffff0000, v69
	v_and_b32_e32 v74, 0xffff0000, v75
	v_add_f32_e32 v69, v69, v74
	global_load_dwordx2 v[74:75], v[70:71], off
	v_add_f32_e32 v76, v68, v69
	s_waitcnt vmcnt(0) lgkmcnt(0)
	v_lshlrev_b32_e32 v71, 16, v72
	v_and_b32_e32 v72, 0xffff0000, v72
	v_lshlrev_b32_e32 v70, 16, v74
	v_add_f32_e32 v70, v70, v71
	v_and_b32_e32 v71, 0xffff0000, v74
	v_add_f32_e32 v71, v71, v72
	v_lshlrev_b32_e32 v72, 16, v75
	v_lshlrev_b32_e32 v74, 16, v73
	v_add_f32_e32 v72, v72, v74
	v_and_b32_e32 v74, 0xffff0000, v75
	v_and_b32_e32 v73, 0xffff0000, v73
	v_add_f32_e32 v73, v74, v73
	v_add_f32_e32 v74, v70, v71
	v_add_f32_e32 v75, v72, v73
	v_add_f32_e32 v74, v74, v75
	v_add_f32_e32 v75, v66, v67
	v_add_f32_e32 v74, 0, v74
	v_add_f32_e32 v75, v75, v76
	v_add_f32_e32 v74, v74, v75
	v_add_f32_e32 v75, v62, v63
	v_add_f32_e32 v76, v64, v65
	v_add_f32_e32 v75, v75, v76
	v_add_f32_e32 v74, v74, v75
	v_add_f32_e32 v75, v58, v59
	v_add_f32_e32 v76, v60, v61
	v_add_f32_e32 v75, v75, v76
	v_add_f32_e32 v74, v74, v75
	v_mov_b32_e32 v75, v224
	s_nop 0
	v_lshlrev_b32_e32 v75, 2, v75
	v_xor_b32_e32 v76, 4, v75
	ds_bpermute_b32 v76, v76, v74
	s_waitcnt lgkmcnt(0)
	v_add_f32_e32 v74, v74, v76
	v_xor_b32_e32 v76, 8, v75
	ds_bpermute_b32 v76, v76, v74
	s_waitcnt lgkmcnt(0)
	v_add_f32_e32 v74, v74, v76
	v_xor_b32_e32 v76, 16, v75
	ds_bpermute_b32 v76, v76, v74
	v_xor_b32_e32 v75, 32, v75
	s_waitcnt lgkmcnt(0)
	v_add_f32_e32 v74, v74, v76
	ds_bpermute_b32 v75, v75, v74
	s_waitcnt lgkmcnt(0)
	v_add_f32_e32 v74, v74, v75
	v_mov_b32_e32 v75, v74
	s_nop 1
	v_permlane16_swap_b32_e32 v74, v75
	v_add_f32_e32 v74, v74, v75
	v_mov_b32_e32 v75, v74
	s_nop 1
	v_permlane32_swap_b32_e32 v74, v75
	v_add_f32_e32 v74, v74, v75
	v_fmac_f32_e32 v73, 0xba800000, v74
	v_fmac_f32_e32 v71, 0xba800000, v74
	v_fmac_f32_e32 v72, 0xba800000, v74
	v_fmac_f32_e32 v70, 0xba800000, v74
	v_mul_f32_e32 v75, v71, v71
	v_mul_f32_e32 v76, v73, v73
	v_fmac_f32_e32 v75, v70, v70
	v_fmac_f32_e32 v76, v72, v72
	v_fmac_f32_e32 v69, 0xba800000, v74
	v_fmac_f32_e32 v67, 0xba800000, v74
	v_add_f32_e32 v75, v75, v76
	v_fmac_f32_e32 v68, 0xba800000, v74
	v_fmac_f32_e32 v66, 0xba800000, v74
	v_mul_f32_e32 v76, v67, v67
	v_mul_f32_e32 v77, v69, v69
	v_fmac_f32_e32 v76, v66, v66
	v_fmac_f32_e32 v77, v68, v68
	v_add_f32_e32 v76, v76, v77
	v_fmac_f32_e32 v65, 0xba800000, v74
	v_fmac_f32_e32 v63, 0xba800000, v74
	v_add_f32_e32 v75, v75, v76
	v_fmac_f32_e32 v64, 0xba800000, v74
	v_fmac_f32_e32 v62, 0xba800000, v74
	v_mul_f32_e32 v76, v63, v63
	v_mul_f32_e32 v77, v65, v65
	v_fmac_f32_e32 v76, v62, v62
	v_fmac_f32_e32 v77, v64, v64
	v_add_f32_e32 v76, v76, v77
	v_fmac_f32_e32 v61, 0xba800000, v74
	v_fmac_f32_e32 v59, 0xba800000, v74
	v_add_f32_e32 v75, v75, v76
	v_fmac_f32_e32 v60, 0xba800000, v74
	v_fmac_f32_e32 v58, 0xba800000, v74
	v_mul_f32_e32 v74, v59, v59
	v_mul_f32_e32 v76, v61, v61
	v_mov_b32_e32 v77, v224
	v_fmac_f32_e32 v74, v58, v58
	v_fmac_f32_e32 v76, v60, v60
	v_add_f32_e32 v74, v74, v76
	v_lshlrev_b32_e32 v77, 2, v77
	v_add_f32_e32 v76, v75, v74
	v_xor_b32_e32 v78, 4, v77
	ds_bpermute_b32 v78, v78, v76
	v_lshl_add_u64 v[74:75], s[8:9], 0, v[0:1]
	s_waitcnt lgkmcnt(0)
; __global__ void __launch_bounds__(512, 2) mega_fwd(Params P) {
;     ...
;                         const float mean = wave_sum(s) * (1.0f / 1024.0f); float s2 = 0.f;
; #pragma unroll
;                         for (int j = 0; j < 4; ++j) { v[q][j] = v[q][j] - mean; s2 += (v[q][j][0] * v[q][j][0] + v[q][j][1] * v[q][j][1]) + (v[q][j][2] * v[q][j][2] + v[q][j][3] * v[q][j][3]); }
;                         const float rstd = rsqrtf(wave_sum(s2) * (1.0f / 1024.0f) + LN_EPS);
; #pragma unroll
;                         for (int j = 0; j < 4; ++j) { const f32x4 y = v[q][j] * rstd * gv[j] + bv[j]; xr[64 * j] = y; } } }
	v_add_f32_e32 v76, v76, v78
	v_xor_b32_e32 v78, 8, v77
	ds_bpermute_b32 v78, v78, v76
	s_waitcnt lgkmcnt(0)
	v_add_f32_e32 v76, v76, v78
	v_xor_b32_e32 v78, 16, v77
	ds_bpermute_b32 v78, v78, v76
	v_xor_b32_e32 v77, 32, v77
	s_waitcnt lgkmcnt(0)
	v_add_f32_e32 v76, v76, v78
	ds_bpermute_b32 v77, v77, v76
	s_waitcnt lgkmcnt(0)
	v_add_f32_e32 v76, v76, v77
	v_mov_b32_e32 v77, v76
	s_nop 1
	v_permlane16_swap_b32_e32 v76, v77
	v_add_f32_e32 v76, v76, v77
	v_mov_b32_e32 v77, v76
	s_nop 1
	v_permlane32_swap_b32_e32 v76, v77
	v_add_f32_e32 v76, v76, v77
	v_fmamk_f32 v76, v76, 0x3a800000, v220
	v_cmp_gt_f32_e32 vcc, s50, v76
	v_mul_f32_e32 v77, 0x4b800000, v76
	s_nop 0
	v_cndmask_b32_e32 v76, v76, v77, vcc
	v_rsq_f32_e32 v76, v76
	s_nop 0
	v_mul_f32_e32 v77, 0x45800000, v76
	v_cndmask_b32_e32 v76, v76, v77, vcc
	v_pk_mul_f32 v[70:71], v[76:77], v[70:71] op_sel_hi:[0,1]
	v_pk_mul_f32 v[72:73], v[76:77], v[72:73] op_sel_hi:[0,1]
	v_pk_mul_f32 v[66:67], v[76:77], v[66:67] op_sel_hi:[0,1]
	v_pk_mul_f32 v[68:69], v[76:77], v[68:69] op_sel_hi:[0,1]
	v_pk_mul_f32 v[62:63], v[76:77], v[62:63] op_sel_hi:[0,1]
	v_pk_mul_f32 v[64:65], v[76:77], v[64:65] op_sel_hi:[0,1]
	v_pk_mul_f32 v[58:59], v[76:77], v[58:59] op_sel_hi:[0,1]
	v_pk_mul_f32 v[60:61], v[76:77], v[60:61] op_sel_hi:[0,1]
	v_pk_fma_f32 v[72:73], v[72:73], v[4:5], v[8:9]
	v_pk_fma_f32 v[70:71], v[70:71], v[2:3], v[6:7]
	v_pk_fma_f32 v[68:69], v[68:69], v[12:13], v[16:17]
	v_pk_fma_f32 v[66:67], v[66:67], v[10:11], v[14:15]
	v_pk_fma_f32 v[64:65], v[64:65], v[20:21], v[24:25]
	v_pk_fma_f32 v[62:63], v[62:63], v[18:19], v[22:23]
	v_pk_fma_f32 v[60:61], v[60:61], v[28:29], v[32:33]
	v_pk_fma_f32 v[58:59], v[58:59], v[26:27], v[30:31]
	global_store_dwordx4 v[74:75], v[70:73], off
	global_store_dwordx4 v[74:75], v[66:69], off offset:1024
	global_store_dwordx4 v[74:75], v[62:65], off offset:2048
	global_store_dwordx4 v[74:75], v[58:61], off offset:3072
	s_cbranch_scc1 .LBB0_1259
; __device__ __forceinline__ float bflo(unsigned w) { return __uint_as_float(w << 16); }
; __device__ __forceinline__ float bfhi(unsigned w) { return __uint_as_float(w & 0xffff0000u); }
; __global__ void __launch_bounds__(512, 2) mega_fwd(Params P) {
;     ...
;                     for (int q = 0; q < 2; ++q) { const int mrow = (mrow0 + q * NGW < T_TOK) ? mrow0 + q * NGW : mrow0;
; #pragma unroll
;                         for (int j = 0; j < 4; ++j) { const unsigned long long hw = ((const unsigned long long*)(XB + (size_t)mrow * 1024))[lane + 64 * j], lw = ((const unsigned long long*)(X + (size_t)mrow * 1024))[256 + lane + 64 * j];
;                             const unsigned h0 = (unsigned)hw, h1 = (unsigned)(hw >> 32), l0 = (unsigned)lw, l1 = (unsigned)(lw >> 32);
;                             v[q][j][0] = bflo(h0) + bflo(l0); v[q][j][1] = bfhi(h0) + bfhi(l0); v[q][j][2] = bflo(h1) + bflo(l1); v[q][j][3] = bfhi(h1) + bfhi(l1); } }
; #pragma unroll
;                     for (int q = 0; q < 2; ++q) { const int mrow = mrow0 + q * NGW; if (mrow < T_TOK) {
;                         f32x4* xr = (f32x4*)(X + (size_t)mrow * 1024) + lane; float s = 0.f;
; #pragma unroll
;                         for (int j = 0; j < 4; ++j) s += (v[q][j][0] + v[q][j][1]) + (v[q][j][2] + v[q][j][3]);
;                         const float mean = wave_sum(s) * (1.0f / 1024.0f); float s2 = 0.f;
; #pragma unroll
;                         for (int j = 0; j < 4; ++j) { v[q][j] = v[q][j] - mean; s2 += (v[q][j][0] * v[q][j][0] + v[q][j][1] * v[q][j][1]) + (v[q][j][2] * v[q][j][2] + v[q][j][3] * v[q][j][3]); }
;                         const float rstd = rsqrtf(wave_sum(s2) * (1.0f / 1024.0f) + LN_EPS);
; #pragma unroll
;                         for (int j = 0; j < 4; ++j) { const f32x4 y = v[q][j] * rstd * gv[j] + bv[j]; xr[64 * j] = y; } } }
	s_nop 0
	v_lshlrev_b32_e32 v58, 16, v54
	v_lshlrev_b32_e32 v60, 16, v56
	v_and_b32_e32 v59, 0xffff0000, v54
	v_and_b32_e32 v61, 0xffff0000, v56
	v_lshlrev_b32_e32 v54, 16, v55
	v_lshlrev_b32_e32 v56, 16, v57
	v_and_b32_e32 v55, 0xffff0000, v55
	v_and_b32_e32 v57, 0xffff0000, v57
	v_pk_add_f32 v[58:59], v[58:59], v[60:61]
	v_pk_add_f32 v[54:55], v[54:55], v[56:57]
	v_lshlrev_b32_e32 v56, 16, v50
	v_lshlrev_b32_e32 v60, 16, v52
	v_and_b32_e32 v57, 0xffff0000, v50
	v_and_b32_e32 v61, 0xffff0000, v52
	v_lshlrev_b32_e32 v50, 16, v51
	v_lshlrev_b32_e32 v52, 16, v53
	v_and_b32_e32 v51, 0xffff0000, v51
	v_and_b32_e32 v53, 0xffff0000, v53
	v_pk_add_f32 v[56:57], v[56:57], v[60:61]
	v_pk_add_f32 v[50:51], v[50:51], v[52:53]
	v_lshlrev_b32_e32 v52, 16, v46
	v_lshlrev_b32_e32 v60, 16, v48
	v_and_b32_e32 v53, 0xffff0000, v46
	v_and_b32_e32 v61, 0xffff0000, v48
	v_lshlrev_b32_e32 v46, 16, v47
	v_lshlrev_b32_e32 v48, 16, v49
	v_and_b32_e32 v47, 0xffff0000, v47
	v_and_b32_e32 v49, 0xffff0000, v49
	v_pk_add_f32 v[52:53], v[52:53], v[60:61]
	v_pk_add_f32 v[46:47], v[46:47], v[48:49]
	v_lshlrev_b32_e32 v48, 16, v42
	v_lshlrev_b32_e32 v60, 16, v44
	v_and_b32_e32 v49, 0xffff0000, v42
	v_and_b32_e32 v61, 0xffff0000, v44
	v_lshlrev_b32_e32 v42, 16, v43
	v_lshlrev_b32_e32 v44, 16, v45
	v_and_b32_e32 v43, 0xffff0000, v43
	v_and_b32_e32 v45, 0xffff0000, v45
	v_pk_add_f32 v[48:49], v[48:49], v[60:61]
	v_pk_add_f32 v[42:43], v[42:43], v[44:45]
	v_add_f32_e32 v45, v48, v49
	v_add_f32_e32 v44, v42, v43
	v_add_f32_e32 v44, v45, v44
	v_add_f32_e32 v45, v46, v47
	v_add_f32_e32 v60, v52, v53
	v_add_f32_e32 v44, 0, v44
	v_add_f32_e32 v45, v60, v45
	v_add_f32_e32 v44, v44, v45
	v_add_f32_e32 v45, v50, v51
	v_add_f32_e32 v60, v56, v57
	v_add_f32_e32 v45, v60, v45
	v_add_f32_e32 v44, v44, v45
	v_add_f32_e32 v45, v54, v55
	v_add_f32_e32 v60, v58, v59
	v_add_f32_e32 v45, v60, v45
	v_add_f32_e32 v44, v44, v45
	v_mov_b32_e32 v45, v224
	s_nop 0
	v_lshlrev_b32_e32 v45, 2, v45
	v_xor_b32_e32 v60, 4, v45
	ds_bpermute_b32 v60, v60, v44
	s_waitcnt lgkmcnt(0)
	v_add_f32_e32 v44, v44, v60
	v_xor_b32_e32 v60, 8, v45
	ds_bpermute_b32 v60, v60, v44
	s_waitcnt lgkmcnt(0)
	v_add_f32_e32 v44, v44, v60
	v_xor_b32_e32 v60, 16, v45
	ds_bpermute_b32 v60, v60, v44
	v_xor_b32_e32 v45, 32, v45
	s_waitcnt lgkmcnt(0)
	v_add_f32_e32 v44, v44, v60
	ds_bpermute_b32 v45, v45, v44
	s_waitcnt lgkmcnt(0)
	v_add_f32_e32 v44, v44, v45
	v_mov_b32_e32 v45, v44
	s_nop 1
	v_permlane16_swap_b32_e32 v44, v45
	v_add_f32_e32 v44, v44, v45
	v_mov_b32_e32 v45, v44
	s_nop 1
	v_permlane32_swap_b32_e32 v44, v45
	v_add_f32_e32 v44, v44, v45
	v_fmac_f32_e32 v43, 0xba800000, v44
	v_fmac_f32_e32 v49, 0xba800000, v44
	v_fmamk_f32 v42, v44, 0xba800000, v42
	v_fmamk_f32 v48, v44, 0xba800000, v48
	v_mul_f32_e32 v45, v49, v49
	v_mul_f32_e32 v60, v43, v43
	v_fmac_f32_e32 v45, v48, v48
	v_fmac_f32_e32 v60, v42, v42
	v_fmac_f32_e32 v47, 0xba800000, v44
	v_fmac_f32_e32 v53, 0xba800000, v44
	v_add_f32_e32 v45, v45, v60
	v_fmamk_f32 v46, v44, 0xba800000, v46
	v_fmamk_f32 v52, v44, 0xba800000, v52
	v_mul_f32_e32 v60, v53, v53
	v_mul_f32_e32 v61, v47, v47
	v_fmac_f32_e32 v60, v52, v52
	v_fmac_f32_e32 v61, v46, v46
	v_add_f32_e32 v60, v60, v61
	v_fmac_f32_e32 v51, 0xba800000, v44
	v_fmac_f32_e32 v57, 0xba800000, v44
	v_add_f32_e32 v45, v45, v60
	v_fmamk_f32 v50, v44, 0xba800000, v50
	v_fmamk_f32 v56, v44, 0xba800000, v56
	v_mul_f32_e32 v60, v57, v57
	v_mul_f32_e32 v61, v51, v51
	v_fmac_f32_e32 v60, v56, v56
	v_fmac_f32_e32 v61, v50, v50
	v_add_f32_e32 v60, v60, v61
	v_fmac_f32_e32 v55, 0xba800000, v44
	v_fmac_f32_e32 v59, 0xba800000, v44
	v_add_f32_e32 v45, v45, v60
	v_fmamk_f32 v54, v44, 0xba800000, v54
	v_fmamk_f32 v58, v44, 0xba800000, v58
	v_mul_f32_e32 v44, v59, v59
	v_mul_f32_e32 v60, v55, v55
	v_fmac_f32_e32 v44, v58, v58
	v_fmac_f32_e32 v60, v54, v54
	v_add_f32_e32 v44, v44, v60
	v_add_f32_e32 v44, v45, v44
	v_mov_b32_e32 v45, v224
	s_nop 0
	v_lshlrev_b32_e32 v45, 2, v45
	v_xor_b32_e32 v60, 4, v45
	ds_bpermute_b32 v60, v60, v44
	s_waitcnt lgkmcnt(0)
	v_add_f32_e32 v44, v44, v60
	v_xor_b32_e32 v60, 8, v45
	ds_bpermute_b32 v60, v60, v44
	s_waitcnt lgkmcnt(0)
	v_add_f32_e32 v44, v44, v60
	v_xor_b32_e32 v60, 16, v45
	ds_bpermute_b32 v60, v60, v44
	v_xor_b32_e32 v45, 32, v45
	s_waitcnt lgkmcnt(0)
	v_add_f32_e32 v44, v44, v60
	ds_bpermute_b32 v45, v45, v44
	s_waitcnt lgkmcnt(0)
	v_add_f32_e32 v44, v44, v45
	v_mov_b32_e32 v45, v44
	s_nop 1
	v_permlane16_swap_b32_e32 v44, v45
	v_add_f32_e32 v44, v44, v45
	v_mov_b32_e32 v45, v44
	s_nop 1
	v_permlane32_swap_b32_e32 v44, v45
	v_add_f32_e32 v44, v44, v45
	v_fmamk_f32 v44, v44, 0x3a800000, v220
	v_mul_f32_e32 v45, 0x4b800000, v44
	v_cmp_gt_f32_e32 vcc, s50, v44
	s_nop 1
	v_cndmask_b32_e32 v44, v44, v45, vcc
	v_rsq_f32_e32 v44, v44
	s_nop 0
	v_mul_f32_e32 v45, 0x45800000, v44
	v_cndmask_b32_e32 v60, v44, v45, vcc
	v_pk_mul_f32 v[48:49], v[60:61], v[48:49] op_sel_hi:[0,1]
	v_pk_mul_f32 v[42:43], v[60:61], v[42:43] op_sel_hi:[0,1]
	v_pk_fma_f32 v[44:45], v[42:43], v[4:5], v[8:9]
	v_pk_fma_f32 v[42:43], v[48:49], v[2:3], v[6:7]
	global_store_dwordx4 v[40:41], v[42:45], off
	s_nop 1
	v_pk_mul_f32 v[42:43], v[60:61], v[52:53] op_sel_hi:[0,1]
	v_pk_mul_f32 v[44:45], v[60:61], v[46:47] op_sel_hi:[0,1]
	v_pk_fma_f32 v[44:45], v[44:45], v[12:13], v[16:17]
	v_pk_fma_f32 v[42:43], v[42:43], v[10:11], v[14:15]
	global_store_dwordx4 v[40:41], v[42:45], off offset:1024
	s_nop 1
	v_pk_mul_f32 v[42:43], v[60:61], v[56:57] op_sel_hi:[0,1]
	v_pk_mul_f32 v[44:45], v[60:61], v[50:51] op_sel_hi:[0,1]
	v_pk_fma_f32 v[44:45], v[44:45], v[20:21], v[24:25]
	v_pk_fma_f32 v[42:43], v[42:43], v[18:19], v[22:23]
	global_store_dwordx4 v[40:41], v[42:45], off offset:2048
	s_nop 1
	v_pk_mul_f32 v[42:43], v[60:61], v[58:59] op_sel_hi:[0,1]
	v_pk_mul_f32 v[44:45], v[60:61], v[54:55] op_sel_hi:[0,1]
	v_pk_fma_f32 v[44:45], v[44:45], v[28:29], v[32:33]
	v_pk_fma_f32 v[42:43], v[42:43], v[26:27], v[30:31]
	global_store_dwordx4 v[40:41], v[42:45], off offset:3072
	s_branch .LBB0_1259
